# all global stores write-through (sc1) so the grid barriers' L2 write-back finds little dirty data
# baseline (speedup 1.0000x reference)
.LBB0_5:
	v_add_co_u32_e32 v1, vcc, 0x200, v1
	s_xor_b64 s[0:1], vcc, -1
	s_and_b64 s[0:1], exec, s[0:1]
	global_store_dwordx4 v[6:7], v[2:5], off sc1
	s_or_b64 s[4:5], s[0:1], s[4:5]
	v_lshl_add_u64 v[6:7], v[6:7], 0, s[6:7]
	s_andn2_b64 exec, exec, s[4:5]
	s_cbranch_execnz .LBB0_5
	s_or_b64 exec, exec, s[4:5]
	s_lshl_b32 s3, s68, 1
	s_lshl_b32 s63, s69, 1
	s_cmp_ge_i32 s3, s63
	s_cbranch_scc0 .LBB0_7
	s_getpc_b64 s[98:99]

.LBB0_35:
	s_add_i32 s24, s24, s88
	s_lshl_b32 s0, s0, 8
	s_add_i32 s48, s24, -8
	s_or_b32 s0, s0, s82
	s_lshr_b32 s2, s48, 4
	v_mov_b32_e32 v148, v185
	v_mov_b32_e32 v68, v187
	s_cmp_gt_i32 s24, 7
	s_mov_b64 s[4:5], -1
	v_lshl_add_u32 v172, v68, 2, s0
	s_cselect_b64 s[0:1], -1, 0
	s_and_b64 vcc, s[0:1], exec
	s_cselect_b32 s0, s2, 8
	s_mul_hi_u32 s1, s0, 0x6000
	s_mulk_i32 s0, 0x6000
	s_add_u32 s0, s61, s0
	s_addc_u32 s1, s65, s1
	v_ashrrev_i32_e32 v173, 31, v172
	v_lshl_add_u64 v[68:69], v[172:173], 2, s[0:1]
	global_load_dwordx4 v[80:83], v[68:69], off
	global_load_dwordx4 v[76:79], v[68:69], off offset:64
	global_load_dwordx4 v[72:75], v[68:69], off offset:512
	s_nop 0
	global_load_dwordx4 v[68:71], v[68:69], off offset:576
	v_add_u32_e32 v160, s76, v148
	v_ashrrev_i32_e32 v161, 31, v160
	v_add_u32_e32 v174, 16, v160
	v_add_u32_e32 v170, 32, v160
	v_add_u32_e32 v168, 48, v160
	v_add_u32_e32 v166, 0x80, v160
	v_add_u32_e32 v164, 0x90, v160
	v_add_u32_e32 v162, 0xa0, v160
	s_cbranch_vccz .LBB0_42
	s_lshl_b64 s[26:27], s[48:49], 20
	s_and_b64 vcc, exec, s[14:15]
	v_lshlrev_b64 v[176:177], 1, v[172:173]
	v_ashrrev_i32_e32 v175, 31, v174
	v_ashrrev_i32_e32 v171, 31, v170
	v_ashrrev_i32_e32 v169, 31, v168
	v_ashrrev_i32_e32 v167, 31, v166
	v_ashrrev_i32_e32 v165, 31, v164
	v_ashrrev_i32_e32 v163, 31, v162
	s_cbranch_vccz .LBB0_38
	s_add_u32 s28, s8, s26
	s_addc_u32 s29, s9, s27
	v_lshl_add_u64 v[148:149], s[28:29], 0, v[176:177]
	v_lshlrev_b64 v[216:217], 12, v[160:161]
	v_lshl_add_u64 v[150:151], v[148:149], 0, v[216:217]
	global_load_dwordx2 v[218:219], v[150:151], off
	global_load_dwordx2 v[220:221], v[150:151], off offset:32
	global_load_dwordx2 v[222:223], v[150:151], off offset:256
	global_load_dwordx2 v[224:225], v[150:151], off offset:288
	v_lshlrev_b64 v[212:213], 12, v[174:175]
	v_lshl_add_u64 v[150:151], v[148:149], 0, v[212:213]
	global_load_dwordx2 v[210:211], v[150:151], off
	global_load_dwordx2 v[208:209], v[150:151], off offset:32
	global_load_dwordx2 v[206:207], v[150:151], off offset:256
	global_load_dwordx2 v[204:205], v[150:151], off offset:288
	v_lshlrev_b64 v[202:203], 12, v[170:171]
	v_lshl_add_u64 v[150:151], v[148:149], 0, v[202:203]
	global_load_dwordx2 v[200:201], v[150:151], off
	global_load_dwordx2 v[198:199], v[150:151], off offset:32
	global_load_dwordx2 v[196:197], v[150:151], off offset:256
	global_load_dwordx2 v[190:191], v[150:151], off offset:288
	v_lshlrev_b64 v[194:195], 12, v[168:169]
	v_lshl_add_u64 v[150:151], v[148:149], 0, v[194:195]
	global_load_dwordx2 v[192:193], v[150:151], off
	global_load_dwordx2 v[188:189], v[150:151], off offset:32
	global_load_dwordx2 v[178:179], v[150:151], off offset:256
	s_nop 0
	global_load_dwordx2 v[150:151], v[150:151], off offset:288
	v_lshl_add_u64 v[216:217], s[28:29], 0, v[216:217]
	v_lshl_add_u64 v[216:217], v[216:217], 0, v[176:177]
	v_lshl_add_u64 v[212:213], s[28:29], 0, v[212:213]
	v_lshl_add_u64 v[202:203], s[28:29], 0, v[202:203]
	s_mov_b64 s[4:5], 0
	s_waitcnt vmcnt(0)
	v_lshlrev_b32_e32 v226, 16, v218
	v_and_b32_e32 v227, 0xffff0000, v218
	v_lshlrev_b32_e32 v218, 16, v219
	v_and_b32_e32 v219, 0xffff0000, v219
	v_pk_fma_f32 v[218:219], v[146:147], v[82:83], v[218:219]
	v_pk_fma_f32 v[226:227], v[144:145], v[80:81], v[226:227]
	s_nop 0
	v_cvt_pk_bf16_f32 v226, v226, v227
	v_cvt_pk_bf16_f32 v227, v218, v219
	v_lshlrev_b32_e32 v218, 16, v220
	v_and_b32_e32 v219, 0xffff0000, v220
	v_lshlrev_b32_e32 v220, 16, v221
	v_and_b32_e32 v221, 0xffff0000, v221
	v_pk_fma_f32 v[220:221], v[142:143], v[78:79], v[220:221]
	v_pk_fma_f32 v[218:219], v[140:141], v[76:77], v[218:219]
	global_store_dwordx2 v[216:217], v[226:227], off sc1
	v_cvt_pk_bf16_f32 v218, v218, v219
	v_cvt_pk_bf16_f32 v219, v220, v221
	global_store_dwordx2 v[216:217], v[218:219], off offset:32 sc1
	v_lshlrev_b32_e32 v218, 16, v222
	v_and_b32_e32 v219, 0xffff0000, v222
	v_lshlrev_b32_e32 v220, 16, v223
	v_and_b32_e32 v221, 0xffff0000, v223
	v_pk_fma_f32 v[220:221], v[130:131], v[74:75], v[220:221]
	v_pk_fma_f32 v[218:219], v[128:129], v[72:73], v[218:219]
	s_nop 0
	v_cvt_pk_bf16_f32 v218, v218, v219
	v_cvt_pk_bf16_f32 v219, v220, v221
	global_store_dwordx2 v[216:217], v[218:219], off offset:256 sc1
	v_lshlrev_b32_e32 v218, 16, v224
	v_and_b32_e32 v219, 0xffff0000, v224
	v_lshlrev_b32_e32 v220, 16, v225
	v_and_b32_e32 v221, 0xffff0000, v225
	v_pk_fma_f32 v[220:221], v[126:127], v[70:71], v[220:221]
	v_pk_fma_f32 v[218:219], v[124:125], v[68:69], v[218:219]
	s_nop 0
	v_cvt_pk_bf16_f32 v218, v218, v219
	v_cvt_pk_bf16_f32 v219, v220, v221
	global_store_dwordx2 v[216:217], v[218:219], off offset:288 sc1
	v_lshlrev_b32_e32 v216, 16, v210
	v_and_b32_e32 v217, 0xffff0000, v210
	v_lshlrev_b32_e32 v210, 16, v211
	v_and_b32_e32 v211, 0xffff0000, v211
	v_pk_fma_f32 v[210:211], v[138:139], v[82:83], v[210:211]
	v_pk_fma_f32 v[216:217], v[136:137], v[80:81], v[216:217]
	s_nop 0
	v_cvt_pk_bf16_f32 v216, v216, v217
	v_cvt_pk_bf16_f32 v217, v210, v211
	v_lshl_add_u64 v[210:211], v[212:213], 0, v[176:177]
	v_lshlrev_b32_e32 v212, 16, v208
	v_and_b32_e32 v213, 0xffff0000, v208
	v_lshlrev_b32_e32 v208, 16, v209
	v_and_b32_e32 v209, 0xffff0000, v209
	v_pk_fma_f32 v[208:209], v[134:135], v[78:79], v[208:209]
	v_pk_fma_f32 v[212:213], v[132:133], v[76:77], v[212:213]
	global_store_dwordx2 v[210:211], v[216:217], off sc1
	v_cvt_pk_bf16_f32 v212, v212, v213
	v_cvt_pk_bf16_f32 v213, v208, v209
	v_lshlrev_b32_e32 v208, 16, v206
	v_and_b32_e32 v209, 0xffff0000, v206
	v_lshlrev_b32_e32 v206, 16, v207
	v_and_b32_e32 v207, 0xffff0000, v207
	v_pk_fma_f32 v[206:207], v[122:123], v[74:75], v[206:207]
	v_pk_fma_f32 v[208:209], v[120:121], v[72:73], v[208:209]
	global_store_dwordx2 v[210:211], v[212:213], off offset:32 sc1
	v_cvt_pk_bf16_f32 v208, v208, v209
	v_cvt_pk_bf16_f32 v209, v206, v207
	v_lshlrev_b32_e32 v206, 16, v204
	v_and_b32_e32 v207, 0xffff0000, v204
	v_lshlrev_b32_e32 v204, 16, v205
	v_and_b32_e32 v205, 0xffff0000, v205
	v_pk_fma_f32 v[204:205], v[118:119], v[70:71], v[204:205]
	v_pk_fma_f32 v[206:207], v[116:117], v[68:69], v[206:207]
	global_store_dwordx2 v[210:211], v[208:209], off offset:256 sc1
	v_cvt_pk_bf16_f32 v206, v206, v207
	v_cvt_pk_bf16_f32 v207, v204, v205
	v_lshlrev_b32_e32 v204, 16, v200
	v_and_b32_e32 v205, 0xffff0000, v200
	v_lshlrev_b32_e32 v200, 16, v201
	v_and_b32_e32 v201, 0xffff0000, v201
	v_pk_fma_f32 v[200:201], v[114:115], v[82:83], v[200:201]
	v_pk_fma_f32 v[204:205], v[112:113], v[80:81], v[204:205]
	global_store_dwordx2 v[210:211], v[206:207], off offset:288 sc1
	v_cvt_pk_bf16_f32 v204, v204, v205
	v_cvt_pk_bf16_f32 v205, v200, v201
	v_lshl_add_u64 v[200:201], v[202:203], 0, v[176:177]
	v_lshlrev_b32_e32 v202, 16, v198
	v_and_b32_e32 v203, 0xffff0000, v198
	v_lshlrev_b32_e32 v198, 16, v199
	v_and_b32_e32 v199, 0xffff0000, v199
	v_pk_fma_f32 v[198:199], v[110:111], v[78:79], v[198:199]
	v_pk_fma_f32 v[202:203], v[108:109], v[76:77], v[202:203]
	global_store_dwordx2 v[200:201], v[204:205], off sc1
	v_cvt_pk_bf16_f32 v202, v202, v203
	v_cvt_pk_bf16_f32 v203, v198, v199
	v_lshlrev_b32_e32 v198, 16, v196
	v_and_b32_e32 v199, 0xffff0000, v196
	v_lshlrev_b32_e32 v196, 16, v197
	v_and_b32_e32 v197, 0xffff0000, v197
	v_pk_fma_f32 v[196:197], v[98:99], v[74:75], v[196:197]
	v_pk_fma_f32 v[198:199], v[96:97], v[72:73], v[198:199]
	global_store_dwordx2 v[200:201], v[202:203], off offset:32 sc1
	v_cvt_pk_bf16_f32 v198, v198, v199
	v_cvt_pk_bf16_f32 v199, v196, v197
	v_lshlrev_b32_e32 v196, 16, v190
	v_and_b32_e32 v197, 0xffff0000, v190
	v_lshlrev_b32_e32 v190, 16, v191
	v_and_b32_e32 v191, 0xffff0000, v191
	v_pk_fma_f32 v[190:191], v[94:95], v[70:71], v[190:191]
	v_pk_fma_f32 v[196:197], v[92:93], v[68:69], v[196:197]
	global_store_dwordx2 v[200:201], v[198:199], off offset:256 sc1
	v_cvt_pk_bf16_f32 v196, v196, v197
	v_cvt_pk_bf16_f32 v197, v190, v191
	v_lshl_add_u64 v[190:191], s[28:29], 0, v[194:195]
	v_lshlrev_b32_e32 v194, 16, v192
	v_and_b32_e32 v195, 0xffff0000, v192
	v_lshlrev_b32_e32 v192, 16, v193
	v_and_b32_e32 v193, 0xffff0000, v193
	v_pk_fma_f32 v[192:193], v[106:107], v[82:83], v[192:193]
	v_pk_fma_f32 v[194:195], v[104:105], v[80:81], v[194:195]
	v_lshl_add_u64 v[190:191], v[190:191], 0, v[176:177]
	v_cvt_pk_bf16_f32 v194, v194, v195
	v_cvt_pk_bf16_f32 v195, v192, v193
	v_lshlrev_b32_e32 v192, 16, v188
	v_and_b32_e32 v193, 0xffff0000, v188
	v_lshlrev_b32_e32 v188, 16, v189
	v_and_b32_e32 v189, 0xffff0000, v189
	v_pk_fma_f32 v[188:189], v[102:103], v[78:79], v[188:189]
	v_pk_fma_f32 v[192:193], v[100:101], v[76:77], v[192:193]
	global_store_dwordx2 v[200:201], v[196:197], off offset:288 sc1
	v_cvt_pk_bf16_f32 v192, v192, v193
	v_cvt_pk_bf16_f32 v193, v188, v189
	v_lshlrev_b32_e32 v188, 16, v178
	v_and_b32_e32 v189, 0xffff0000, v178
	v_lshlrev_b32_e32 v178, 16, v179
	v_and_b32_e32 v179, 0xffff0000, v179
	v_pk_fma_f32 v[178:179], v[90:91], v[74:75], v[178:179]
	v_pk_fma_f32 v[188:189], v[88:89], v[72:73], v[188:189]
	global_store_dwordx2 v[190:191], v[194:195], off sc1
	v_cvt_pk_bf16_f32 v188, v188, v189
	v_cvt_pk_bf16_f32 v189, v178, v179
	v_lshlrev_b32_e32 v178, 16, v150
	v_and_b32_e32 v179, 0xffff0000, v150
	v_lshlrev_b32_e32 v150, 16, v151
	v_and_b32_e32 v151, 0xffff0000, v151
	v_pk_fma_f32 v[150:151], v[86:87], v[70:71], v[150:151]
	v_pk_fma_f32 v[178:179], v[84:85], v[68:69], v[178:179]
	global_store_dwordx2 v[190:191], v[192:193], off offset:32 sc1
	v_cvt_pk_bf16_f32 v178, v178, v179
	v_cvt_pk_bf16_f32 v179, v150, v151
	global_store_dwordx2 v[190:191], v[188:189], off offset:256 sc1
	global_store_dwordx2 v[190:191], v[178:179], off offset:288 sc1
	v_lshlrev_b64 v[150:151], 12, v[166:167]
	v_lshl_add_u64 v[178:179], v[148:149], 0, v[150:151]
	global_load_dwordx2 v[188:189], v[178:179], off
	global_load_dwordx2 v[190:191], v[178:179], off offset:32
	global_load_dwordx2 v[192:193], v[178:179], off offset:256
	s_nop 0
	global_load_dwordx2 v[178:179], v[178:179], off offset:288
	v_lshlrev_b64 v[194:195], 12, v[164:165]
	v_lshl_add_u64 v[196:197], v[148:149], 0, v[194:195]
	global_load_dwordx2 v[198:199], v[196:197], off
	global_load_dwordx2 v[200:201], v[196:197], off offset:32
	global_load_dwordx2 v[202:203], v[196:197], off offset:256
	s_nop 0
	global_load_dwordx2 v[196:197], v[196:197], off offset:288
	v_lshlrev_b64 v[204:205], 12, v[162:163]
	v_lshl_add_u64 v[206:207], v[148:149], 0, v[204:205]
	global_load_dwordx2 v[208:209], v[206:207], off
	global_load_dwordx2 v[210:211], v[206:207], off offset:32
	global_load_dwordx2 v[212:213], v[206:207], off offset:256
	s_nop 0
	global_load_dwordx2 v[206:207], v[206:207], off offset:288
	v_add_u32_e32 v216, 0xb0, v160
	v_ashrrev_i32_e32 v217, 31, v216
	v_lshlrev_b64 v[216:217], 12, v[216:217]
	v_lshl_add_u64 v[148:149], v[148:149], 0, v[216:217]
	global_load_dwordx2 v[218:219], v[148:149], off
	global_load_dwordx2 v[220:221], v[148:149], off offset:32
	global_load_dwordx2 v[222:223], v[148:149], off offset:256
	s_nop 0
	global_load_dwordx2 v[148:149], v[148:149], off offset:288
	v_lshl_add_u64 v[150:151], s[28:29], 0, v[150:151]
	v_lshl_add_u64 v[150:151], v[150:151], 0, v[176:177]
	s_waitcnt vmcnt(15)
	v_lshlrev_b32_e32 v224, 16, v188
	v_and_b32_e32 v225, 0xffff0000, v188
	v_lshlrev_b32_e32 v188, 16, v189
	v_and_b32_e32 v189, 0xffff0000, v189
	v_pk_fma_f32 v[188:189], v[66:67], v[82:83], v[188:189]
	v_pk_fma_f32 v[224:225], v[64:65], v[80:81], v[224:225]
	s_nop 0
	v_cvt_pk_bf16_f32 v224, v224, v225
	v_cvt_pk_bf16_f32 v225, v188, v189
	s_waitcnt vmcnt(14)
	v_lshlrev_b32_e32 v188, 16, v190
	v_and_b32_e32 v189, 0xffff0000, v190
	v_lshlrev_b32_e32 v190, 16, v191
	v_and_b32_e32 v191, 0xffff0000, v191
	v_pk_fma_f32 v[190:191], v[62:63], v[78:79], v[190:191]
	v_pk_fma_f32 v[188:189], v[60:61], v[76:77], v[188:189]
	global_store_dwordx2 v[150:151], v[224:225], off sc1
	v_cvt_pk_bf16_f32 v188, v188, v189
	v_cvt_pk_bf16_f32 v189, v190, v191
	global_store_dwordx2 v[150:151], v[188:189], off offset:32 sc1
	s_waitcnt vmcnt(15)
	v_lshlrev_b32_e32 v188, 16, v192
	v_and_b32_e32 v189, 0xffff0000, v192
	v_lshlrev_b32_e32 v190, 16, v193
	v_and_b32_e32 v191, 0xffff0000, v193
	v_pk_fma_f32 v[190:191], v[50:51], v[74:75], v[190:191]
	v_pk_fma_f32 v[188:189], v[48:49], v[72:73], v[188:189]
	s_nop 0
	v_cvt_pk_bf16_f32 v188, v188, v189
	v_cvt_pk_bf16_f32 v189, v190, v191
	global_store_dwordx2 v[150:151], v[188:189], off offset:256 sc1
	s_waitcnt vmcnt(15)
	v_lshlrev_b32_e32 v188, 16, v178
	v_and_b32_e32 v189, 0xffff0000, v178
	v_lshlrev_b32_e32 v178, 16, v179
	v_and_b32_e32 v179, 0xffff0000, v179
	v_pk_fma_f32 v[178:179], v[46:47], v[70:71], v[178:179]
	v_pk_fma_f32 v[188:189], v[44:45], v[68:69], v[188:189]
	s_nop 0
	v_cvt_pk_bf16_f32 v188, v188, v189
	v_cvt_pk_bf16_f32 v189, v178, v179
	global_store_dwordx2 v[150:151], v[188:189], off offset:288 sc1
	s_waitcnt vmcnt(15)
	v_lshlrev_b32_e32 v178, 16, v198
	v_and_b32_e32 v179, 0xffff0000, v198
	v_lshlrev_b32_e32 v188, 16, v199
	v_and_b32_e32 v189, 0xffff0000, v199
	v_lshl_add_u64 v[150:151], s[28:29], 0, v[194:195]
	v_pk_fma_f32 v[188:189], v[58:59], v[82:83], v[188:189]
	v_pk_fma_f32 v[178:179], v[56:57], v[80:81], v[178:179]
	v_lshl_add_u64 v[150:151], v[150:151], 0, v[176:177]
	v_cvt_pk_bf16_f32 v178, v178, v179
	v_cvt_pk_bf16_f32 v179, v188, v189
	global_store_dwordx2 v[150:151], v[178:179], off sc1
	s_waitcnt vmcnt(15)
	v_lshlrev_b32_e32 v178, 16, v200
	v_and_b32_e32 v179, 0xffff0000, v200
	v_lshlrev_b32_e32 v188, 16, v201
	v_and_b32_e32 v189, 0xffff0000, v201
	v_pk_fma_f32 v[188:189], v[54:55], v[78:79], v[188:189]
	v_pk_fma_f32 v[178:179], v[52:53], v[76:77], v[178:179]
	s_nop 0
	v_cvt_pk_bf16_f32 v178, v178, v179
	v_cvt_pk_bf16_f32 v179, v188, v189
	global_store_dwordx2 v[150:151], v[178:179], off offset:32 sc1
	s_waitcnt vmcnt(15)
	v_lshlrev_b32_e32 v178, 16, v202
	v_and_b32_e32 v179, 0xffff0000, v202
	v_lshlrev_b32_e32 v188, 16, v203
	v_and_b32_e32 v189, 0xffff0000, v203
	v_pk_fma_f32 v[188:189], v[42:43], v[74:75], v[188:189]
	v_pk_fma_f32 v[178:179], v[40:41], v[72:73], v[178:179]
	s_nop 0
	v_cvt_pk_bf16_f32 v178, v178, v179
	v_cvt_pk_bf16_f32 v179, v188, v189
	global_store_dwordx2 v[150:151], v[178:179], off offset:256 sc1
	s_waitcnt vmcnt(15)
	v_lshlrev_b32_e32 v178, 16, v196
	v_and_b32_e32 v179, 0xffff0000, v196
	v_lshlrev_b32_e32 v188, 16, v197
	v_and_b32_e32 v189, 0xffff0000, v197
	v_pk_fma_f32 v[188:189], v[38:39], v[70:71], v[188:189]
	v_pk_fma_f32 v[178:179], v[36:37], v[68:69], v[178:179]
	s_nop 0
	v_cvt_pk_bf16_f32 v178, v178, v179
	v_cvt_pk_bf16_f32 v179, v188, v189
	global_store_dwordx2 v[150:151], v[178:179], off offset:288 sc1
	s_waitcnt vmcnt(15)
	v_lshlrev_b32_e32 v178, 16, v208
	v_and_b32_e32 v179, 0xffff0000, v208
	v_lshlrev_b32_e32 v188, 16, v209
	v_and_b32_e32 v189, 0xffff0000, v209
	v_lshl_add_u64 v[150:151], s[28:29], 0, v[204:205]
	v_pk_fma_f32 v[188:189], v[34:35], v[82:83], v[188:189]
	v_pk_fma_f32 v[178:179], v[32:33], v[80:81], v[178:179]
	v_lshl_add_u64 v[150:151], v[150:151], 0, v[176:177]
	v_cvt_pk_bf16_f32 v178, v178, v179
	v_cvt_pk_bf16_f32 v179, v188, v189
	global_store_dwordx2 v[150:151], v[178:179], off sc1
	s_waitcnt vmcnt(15)
	v_lshlrev_b32_e32 v178, 16, v210
	v_and_b32_e32 v179, 0xffff0000, v210
	v_lshlrev_b32_e32 v188, 16, v211
	v_and_b32_e32 v189, 0xffff0000, v211
	v_pk_fma_f32 v[188:189], v[30:31], v[78:79], v[188:189]
	v_pk_fma_f32 v[178:179], v[28:29], v[76:77], v[178:179]
	s_nop 0
	v_cvt_pk_bf16_f32 v178, v178, v179
	v_cvt_pk_bf16_f32 v179, v188, v189
	global_store_dwordx2 v[150:151], v[178:179], off offset:32 sc1
	s_waitcnt vmcnt(15)
	v_lshlrev_b32_e32 v178, 16, v212
	v_and_b32_e32 v179, 0xffff0000, v212
	v_lshlrev_b32_e32 v188, 16, v213
	v_and_b32_e32 v189, 0xffff0000, v213
	v_pk_fma_f32 v[188:189], v[26:27], v[74:75], v[188:189]
	v_pk_fma_f32 v[178:179], v[24:25], v[72:73], v[178:179]
	s_nop 0
	v_cvt_pk_bf16_f32 v178, v178, v179
	v_cvt_pk_bf16_f32 v179, v188, v189
	global_store_dwordx2 v[150:151], v[178:179], off offset:256 sc1
	s_waitcnt vmcnt(15)
	v_lshlrev_b32_e32 v178, 16, v206
	v_and_b32_e32 v179, 0xffff0000, v206
	v_lshlrev_b32_e32 v188, 16, v207
	v_and_b32_e32 v189, 0xffff0000, v207
	v_pk_fma_f32 v[188:189], v[22:23], v[70:71], v[188:189]
	v_pk_fma_f32 v[178:179], v[20:21], v[68:69], v[178:179]
	s_nop 0
	v_cvt_pk_bf16_f32 v178, v178, v179
	v_cvt_pk_bf16_f32 v179, v188, v189
	global_store_dwordx2 v[150:151], v[178:179], off offset:288 sc1
	s_waitcnt vmcnt(15)
	v_lshlrev_b32_e32 v178, 16, v218
	v_and_b32_e32 v179, 0xffff0000, v218
	v_lshlrev_b32_e32 v188, 16, v219
	v_and_b32_e32 v189, 0xffff0000, v219
	v_lshl_add_u64 v[150:151], s[28:29], 0, v[216:217]
	v_pk_fma_f32 v[188:189], v[18:19], v[82:83], v[188:189]
	v_pk_fma_f32 v[178:179], v[16:17], v[80:81], v[178:179]
	v_lshl_add_u64 v[150:151], v[150:151], 0, v[176:177]
	v_cvt_pk_bf16_f32 v178, v178, v179
	v_cvt_pk_bf16_f32 v179, v188, v189
	global_store_dwordx2 v[150:151], v[178:179], off sc1
	s_waitcnt vmcnt(15)
	v_lshlrev_b32_e32 v178, 16, v220
	v_and_b32_e32 v179, 0xffff0000, v220
	v_lshlrev_b32_e32 v188, 16, v221
	v_and_b32_e32 v189, 0xffff0000, v221
	v_pk_fma_f32 v[188:189], v[14:15], v[78:79], v[188:189]
	v_pk_fma_f32 v[178:179], v[12:13], v[76:77], v[178:179]
	s_nop 0
	v_cvt_pk_bf16_f32 v178, v178, v179
	v_cvt_pk_bf16_f32 v179, v188, v189
	global_store_dwordx2 v[150:151], v[178:179], off offset:32 sc1
	s_waitcnt vmcnt(15)
	v_lshlrev_b32_e32 v178, 16, v222
	v_and_b32_e32 v179, 0xffff0000, v222
	v_lshlrev_b32_e32 v188, 16, v223
	v_and_b32_e32 v189, 0xffff0000, v223
	v_pk_fma_f32 v[188:189], v[10:11], v[74:75], v[188:189]
	v_pk_fma_f32 v[178:179], v[8:9], v[72:73], v[178:179]
	s_nop 0
	v_cvt_pk_bf16_f32 v178, v178, v179
	v_cvt_pk_bf16_f32 v179, v188, v189
	global_store_dwordx2 v[150:151], v[178:179], off offset:256 sc1
	s_waitcnt vmcnt(15)
	v_lshlrev_b32_e32 v178, 16, v148
	v_and_b32_e32 v179, 0xffff0000, v148
	v_lshlrev_b32_e32 v148, 16, v149
	v_and_b32_e32 v149, 0xffff0000, v149
	v_pk_fma_f32 v[148:149], v[6:7], v[70:71], v[148:149]
	v_pk_fma_f32 v[178:179], v[4:5], v[68:69], v[178:179]
	s_nop 0
	v_cvt_pk_bf16_f32 v178, v178, v179
	v_cvt_pk_bf16_f32 v179, v148, v149
	global_store_dwordx2 v[150:151], v[178:179], off offset:288 sc1
.LBB0_38:
	s_andn2_b64 vcc, exec, s[4:5]
	s_cbranch_vccnz .LBB0_40
	v_lshl_add_u64 v[148:149], v[172:173], 2, s[26:27]
	v_lshlrev_b64 v[150:151], 12, v[160:161]
	v_lshl_add_u64 v[178:179], v[148:149], 0, v[150:151]
	global_load_dwordx4 v[188:191], v[178:179], off
	global_load_dwordx4 v[192:195], v[178:179], off offset:64
	global_load_dwordx4 v[196:199], v[178:179], off offset:512
	global_load_dwordx4 v[200:203], v[178:179], off offset:576
	v_lshlrev_b64 v[178:179], 12, v[174:175]
	v_lshl_add_u64 v[212:213], v[148:149], 0, v[178:179]
	global_load_dwordx4 v[204:207], v[212:213], off
	global_load_dwordx4 v[208:211], v[212:213], off offset:64
	global_load_dwordx4 v[216:219], v[212:213], off offset:512
	global_load_dwordx4 v[220:223], v[212:213], off offset:576
	v_lshl_add_u64 v[150:151], s[26:27], 0, v[150:151]
	v_lshl_add_u64 v[150:151], v[150:151], 0, v[176:177]
	s_waitcnt vmcnt(0)
	v_pk_fma_f32 v[190:191], v[146:147], v[82:83], v[190:191]
	v_pk_fma_f32 v[188:189], v[144:145], v[80:81], v[188:189]
	s_nop 0
	v_cvt_pk_bf16_f32 v188, v188, v189
	v_cvt_pk_bf16_f32 v189, v190, v191
	global_store_dwordx2 v[150:151], v[188:189], off sc1
	v_pk_fma_f32 v[188:189], v[142:143], v[78:79], v[194:195]
	v_pk_fma_f32 v[190:191], v[140:141], v[76:77], v[192:193]
	s_nop 0
	v_cvt_pk_bf16_f32 v190, v190, v191
	v_cvt_pk_bf16_f32 v191, v188, v189
	global_store_dwordx2 v[150:151], v[190:191], off offset:32 sc1
	v_pk_fma_f32 v[188:189], v[130:131], v[74:75], v[198:199]
	v_pk_fma_f32 v[190:191], v[128:129], v[72:73], v[196:197]
	s_nop 0
	v_cvt_pk_bf16_f32 v190, v190, v191
	v_cvt_pk_bf16_f32 v191, v188, v189
	global_store_dwordx2 v[150:151], v[190:191], off offset:256 sc1
	v_pk_fma_f32 v[188:189], v[126:127], v[70:71], v[202:203]
	v_pk_fma_f32 v[190:191], v[124:125], v[68:69], v[200:201]
	s_nop 0
	v_cvt_pk_bf16_f32 v190, v190, v191
	v_cvt_pk_bf16_f32 v191, v188, v189
	global_store_dwordx2 v[150:151], v[190:191], off offset:288 sc1
	v_lshl_add_u64 v[150:151], s[26:27], 0, v[178:179]
	v_pk_fma_f32 v[178:179], v[138:139], v[82:83], v[206:207]
	v_pk_fma_f32 v[188:189], v[136:137], v[80:81], v[204:205]
	v_lshl_add_u64 v[150:151], v[150:151], 0, v[176:177]
	v_cvt_pk_bf16_f32 v188, v188, v189
	v_cvt_pk_bf16_f32 v189, v178, v179
	global_store_dwordx2 v[150:151], v[188:189], off sc1
	v_pk_fma_f32 v[178:179], v[134:135], v[78:79], v[210:211]
	v_pk_fma_f32 v[188:189], v[132:133], v[76:77], v[208:209]
	s_nop 0
	v_cvt_pk_bf16_f32 v188, v188, v189
	v_cvt_pk_bf16_f32 v189, v178, v179
	global_store_dwordx2 v[150:151], v[188:189], off offset:32 sc1
	v_pk_fma_f32 v[178:179], v[122:123], v[74:75], v[218:219]
	v_pk_fma_f32 v[188:189], v[120:121], v[72:73], v[216:217]
	s_nop 0
	v_cvt_pk_bf16_f32 v188, v188, v189
	v_cvt_pk_bf16_f32 v189, v178, v179
	global_store_dwordx2 v[150:151], v[188:189], off offset:256 sc1
	v_pk_fma_f32 v[178:179], v[118:119], v[70:71], v[222:223]
	v_pk_fma_f32 v[188:189], v[116:117], v[68:69], v[220:221]
	s_nop 0
	v_cvt_pk_bf16_f32 v188, v188, v189
	v_cvt_pk_bf16_f32 v189, v178, v179
	global_store_dwordx2 v[150:151], v[188:189], off offset:288 sc1
	v_lshlrev_b64 v[150:151], 12, v[170:171]
	v_lshl_add_u64 v[178:179], v[148:149], 0, v[150:151]
	global_load_dwordx4 v[188:191], v[178:179], off
	global_load_dwordx4 v[192:195], v[178:179], off offset:64
	global_load_dwordx4 v[196:199], v[178:179], off offset:512
	global_load_dwordx4 v[200:203], v[178:179], off offset:576
	v_lshlrev_b64 v[178:179], 12, v[168:169]
	v_lshl_add_u64 v[212:213], v[148:149], 0, v[178:179]
	global_load_dwordx4 v[204:207], v[212:213], off
	global_load_dwordx4 v[208:211], v[212:213], off offset:64
	global_load_dwordx4 v[216:219], v[212:213], off offset:512
	global_load_dwordx4 v[220:223], v[212:213], off offset:576
	v_lshl_add_u64 v[150:151], s[26:27], 0, v[150:151]
	v_lshl_add_u64 v[150:151], v[150:151], 0, v[176:177]
	s_waitcnt vmcnt(7)
	v_pk_fma_f32 v[190:191], v[114:115], v[82:83], v[190:191]
	v_pk_fma_f32 v[188:189], v[112:113], v[80:81], v[188:189]
	s_nop 0
	v_cvt_pk_bf16_f32 v188, v188, v189
	v_cvt_pk_bf16_f32 v189, v190, v191
	global_store_dwordx2 v[150:151], v[188:189], off sc1
	s_waitcnt vmcnt(7)
	v_pk_fma_f32 v[188:189], v[110:111], v[78:79], v[194:195]
	v_pk_fma_f32 v[190:191], v[108:109], v[76:77], v[192:193]
	s_nop 0
	v_cvt_pk_bf16_f32 v190, v190, v191
	v_cvt_pk_bf16_f32 v191, v188, v189
	global_store_dwordx2 v[150:151], v[190:191], off offset:32 sc1
	s_waitcnt vmcnt(7)
	v_pk_fma_f32 v[188:189], v[98:99], v[74:75], v[198:199]
	v_pk_fma_f32 v[190:191], v[96:97], v[72:73], v[196:197]
	s_nop 0
	v_cvt_pk_bf16_f32 v190, v190, v191
	v_cvt_pk_bf16_f32 v191, v188, v189
	global_store_dwordx2 v[150:151], v[190:191], off offset:256 sc1
	s_waitcnt vmcnt(7)
	v_pk_fma_f32 v[188:189], v[94:95], v[70:71], v[202:203]
	v_pk_fma_f32 v[190:191], v[92:93], v[68:69], v[200:201]
	s_nop 0
	v_cvt_pk_bf16_f32 v190, v190, v191
	v_cvt_pk_bf16_f32 v191, v188, v189
	global_store_dwordx2 v[150:151], v[190:191], off offset:288 sc1
	v_lshl_add_u64 v[150:151], s[26:27], 0, v[178:179]
	s_waitcnt vmcnt(7)
	v_pk_fma_f32 v[178:179], v[106:107], v[82:83], v[206:207]
	v_pk_fma_f32 v[188:189], v[104:105], v[80:81], v[204:205]
	v_lshl_add_u64 v[150:151], v[150:151], 0, v[176:177]
	v_cvt_pk_bf16_f32 v188, v188, v189
	v_cvt_pk_bf16_f32 v189, v178, v179
	global_store_dwordx2 v[150:151], v[188:189], off sc1
	s_waitcnt vmcnt(7)
	v_pk_fma_f32 v[178:179], v[102:103], v[78:79], v[210:211]
	v_pk_fma_f32 v[188:189], v[100:101], v[76:77], v[208:209]
	s_nop 0
	v_cvt_pk_bf16_f32 v188, v188, v189
	v_cvt_pk_bf16_f32 v189, v178, v179
	global_store_dwordx2 v[150:151], v[188:189], off offset:32 sc1
	s_waitcnt vmcnt(7)
	v_pk_fma_f32 v[178:179], v[90:91], v[74:75], v[218:219]
	v_pk_fma_f32 v[188:189], v[88:89], v[72:73], v[216:217]
	s_nop 0
	v_cvt_pk_bf16_f32 v188, v188, v189
	v_cvt_pk_bf16_f32 v189, v178, v179
	global_store_dwordx2 v[150:151], v[188:189], off offset:256 sc1
	s_waitcnt vmcnt(7)
	v_pk_fma_f32 v[178:179], v[86:87], v[70:71], v[222:223]
	v_pk_fma_f32 v[188:189], v[84:85], v[68:69], v[220:221]
	s_nop 0
	v_cvt_pk_bf16_f32 v188, v188, v189
	v_cvt_pk_bf16_f32 v189, v178, v179
	global_store_dwordx2 v[150:151], v[188:189], off offset:288 sc1
	v_lshlrev_b64 v[150:151], 12, v[166:167]
	v_lshl_add_u64 v[178:179], v[148:149], 0, v[150:151]
	global_load_dwordx4 v[188:191], v[178:179], off
	global_load_dwordx4 v[192:195], v[178:179], off offset:64
	global_load_dwordx4 v[196:199], v[178:179], off offset:512
	global_load_dwordx4 v[200:203], v[178:179], off offset:576
	v_lshlrev_b64 v[178:179], 12, v[164:165]
	v_lshl_add_u64 v[212:213], v[148:149], 0, v[178:179]
	global_load_dwordx4 v[204:207], v[212:213], off
	global_load_dwordx4 v[208:211], v[212:213], off offset:64
	global_load_dwordx4 v[216:219], v[212:213], off offset:512
	global_load_dwordx4 v[220:223], v[212:213], off offset:576
	v_lshl_add_u64 v[150:151], s[26:27], 0, v[150:151]
	v_lshl_add_u64 v[150:151], v[150:151], 0, v[176:177]
	s_waitcnt vmcnt(7)
	v_pk_fma_f32 v[190:191], v[66:67], v[82:83], v[190:191]
	v_pk_fma_f32 v[188:189], v[64:65], v[80:81], v[188:189]
	s_nop 0
	v_cvt_pk_bf16_f32 v188, v188, v189
	v_cvt_pk_bf16_f32 v189, v190, v191
	global_store_dwordx2 v[150:151], v[188:189], off sc1
	s_waitcnt vmcnt(7)
	v_pk_fma_f32 v[188:189], v[62:63], v[78:79], v[194:195]
	v_pk_fma_f32 v[190:191], v[60:61], v[76:77], v[192:193]
	s_nop 0
	v_cvt_pk_bf16_f32 v190, v190, v191
	v_cvt_pk_bf16_f32 v191, v188, v189
	global_store_dwordx2 v[150:151], v[190:191], off offset:32 sc1
	s_waitcnt vmcnt(7)
	v_pk_fma_f32 v[188:189], v[50:51], v[74:75], v[198:199]
	v_pk_fma_f32 v[190:191], v[48:49], v[72:73], v[196:197]
	s_nop 0
	v_cvt_pk_bf16_f32 v190, v190, v191
	v_cvt_pk_bf16_f32 v191, v188, v189
	global_store_dwordx2 v[150:151], v[190:191], off offset:256 sc1
	s_waitcnt vmcnt(7)
	v_pk_fma_f32 v[188:189], v[46:47], v[70:71], v[202:203]
	v_pk_fma_f32 v[190:191], v[44:45], v[68:69], v[200:201]
	s_nop 0
	v_cvt_pk_bf16_f32 v190, v190, v191
	v_cvt_pk_bf16_f32 v191, v188, v189
	global_store_dwordx2 v[150:151], v[190:191], off offset:288 sc1
	v_lshl_add_u64 v[150:151], s[26:27], 0, v[178:179]
	s_waitcnt vmcnt(7)
	v_pk_fma_f32 v[178:179], v[58:59], v[82:83], v[206:207]
	v_pk_fma_f32 v[188:189], v[56:57], v[80:81], v[204:205]
	v_lshl_add_u64 v[150:151], v[150:151], 0, v[176:177]
	v_cvt_pk_bf16_f32 v188, v188, v189
	v_cvt_pk_bf16_f32 v189, v178, v179
	global_store_dwordx2 v[150:151], v[188:189], off sc1
	s_waitcnt vmcnt(7)
	v_pk_fma_f32 v[178:179], v[54:55], v[78:79], v[210:211]
	v_pk_fma_f32 v[188:189], v[52:53], v[76:77], v[208:209]
	s_nop 0
	v_cvt_pk_bf16_f32 v188, v188, v189
	v_cvt_pk_bf16_f32 v189, v178, v179
	global_store_dwordx2 v[150:151], v[188:189], off offset:32 sc1
	s_waitcnt vmcnt(7)
	v_pk_fma_f32 v[178:179], v[42:43], v[74:75], v[218:219]
	v_pk_fma_f32 v[188:189], v[40:41], v[72:73], v[216:217]
	s_nop 0
	v_cvt_pk_bf16_f32 v188, v188, v189
	v_cvt_pk_bf16_f32 v189, v178, v179
	global_store_dwordx2 v[150:151], v[188:189], off offset:256 sc1
	s_waitcnt vmcnt(7)
	v_pk_fma_f32 v[178:179], v[38:39], v[70:71], v[222:223]
	v_pk_fma_f32 v[188:189], v[36:37], v[68:69], v[220:221]
	s_nop 0
	v_cvt_pk_bf16_f32 v188, v188, v189
	v_cvt_pk_bf16_f32 v189, v178, v179
	global_store_dwordx2 v[150:151], v[188:189], off offset:288 sc1
	v_lshlrev_b64 v[178:179], 12, v[162:163]
	v_lshl_add_u64 v[150:151], v[148:149], 0, v[178:179]
	global_load_dwordx4 v[188:191], v[150:151], off
	global_load_dwordx4 v[192:195], v[150:151], off offset:64
	global_load_dwordx4 v[196:199], v[150:151], off offset:512
	global_load_dwordx4 v[200:203], v[150:151], off offset:576
	v_add_u32_e32 v150, 0xb0, v160
	v_ashrrev_i32_e32 v151, 31, v150
	v_lshlrev_b64 v[212:213], 12, v[150:151]
	v_lshl_add_u64 v[148:149], v[148:149], 0, v[212:213]
	global_load_dwordx4 v[204:207], v[148:149], off
	global_load_dwordx4 v[208:211], v[148:149], off offset:64
	global_load_dwordx4 v[216:219], v[148:149], off offset:512
	s_nop 0
	global_load_dwordx4 v[148:151], v[148:149], off offset:576
	v_lshl_add_u64 v[178:179], s[26:27], 0, v[178:179]
	v_lshl_add_u64 v[178:179], v[178:179], 0, v[176:177]
	s_waitcnt vmcnt(7)
	v_pk_fma_f32 v[190:191], v[34:35], v[82:83], v[190:191]
	v_pk_fma_f32 v[188:189], v[32:33], v[80:81], v[188:189]
	s_waitcnt vmcnt(0)
	v_pk_fma_f32 v[150:151], v[6:7], v[70:71], v[150:151]
	v_cvt_pk_bf16_f32 v188, v188, v189
	v_cvt_pk_bf16_f32 v189, v190, v191
	global_store_dwordx2 v[178:179], v[188:189], off sc1
	v_pk_fma_f32 v[188:189], v[30:31], v[78:79], v[194:195]
	v_pk_fma_f32 v[190:191], v[28:29], v[76:77], v[192:193]
	v_pk_fma_f32 v[148:149], v[4:5], v[68:69], v[148:149]
	v_cvt_pk_bf16_f32 v190, v190, v191
	v_cvt_pk_bf16_f32 v191, v188, v189
	global_store_dwordx2 v[178:179], v[190:191], off offset:32 sc1
	v_pk_fma_f32 v[188:189], v[26:27], v[74:75], v[198:199]
	v_pk_fma_f32 v[190:191], v[24:25], v[72:73], v[196:197]
	v_cvt_pk_bf16_f32 v148, v148, v149
	v_cvt_pk_bf16_f32 v190, v190, v191
	v_cvt_pk_bf16_f32 v191, v188, v189
	global_store_dwordx2 v[178:179], v[190:191], off offset:256 sc1
	v_pk_fma_f32 v[188:189], v[22:23], v[70:71], v[202:203]
	v_pk_fma_f32 v[190:191], v[20:21], v[68:69], v[200:201]
	v_cvt_pk_bf16_f32 v149, v150, v151
	v_cvt_pk_bf16_f32 v190, v190, v191
	v_cvt_pk_bf16_f32 v191, v188, v189
	global_store_dwordx2 v[178:179], v[190:191], off offset:288 sc1
	v_lshl_add_u64 v[178:179], s[26:27], 0, v[212:213]
	v_pk_fma_f32 v[188:189], v[18:19], v[82:83], v[206:207]
	v_pk_fma_f32 v[190:191], v[16:17], v[80:81], v[204:205]
	v_lshl_add_u64 v[176:177], v[178:179], 0, v[176:177]
	v_cvt_pk_bf16_f32 v190, v190, v191
	v_cvt_pk_bf16_f32 v191, v188, v189
	v_pk_fma_f32 v[178:179], v[14:15], v[78:79], v[210:211]
	v_pk_fma_f32 v[188:189], v[12:13], v[76:77], v[208:209]
	global_store_dwordx2 v[176:177], v[190:191], off sc1
	v_cvt_pk_bf16_f32 v188, v188, v189
	v_cvt_pk_bf16_f32 v189, v178, v179
	global_store_dwordx2 v[176:177], v[188:189], off offset:32 sc1
	v_pk_fma_f32 v[178:179], v[10:11], v[74:75], v[218:219]
	v_pk_fma_f32 v[188:189], v[8:9], v[72:73], v[216:217]
	global_store_dwordx2 v[176:177], v[148:149], off offset:288 sc1
	v_cvt_pk_bf16_f32 v188, v188, v189
	v_cvt_pk_bf16_f32 v189, v178, v179
	global_store_dwordx2 v[176:177], v[188:189], off offset:256 sc1

.LBB0_43:
	s_ashr_i32 s25, s24, 31
	s_lshl_b64 s[0:1], s[24:25], 20
	s_add_u32 s24, s59, s0
	s_addc_u32 s25, s60, s1
	v_lshlrev_b64 v[148:149], 2, v[172:173]
	v_lshl_add_u64 v[150:151], s[24:25], 0, v[148:149]
	v_lshlrev_b64 v[212:213], 12, v[160:161]
	v_lshl_add_u64 v[172:173], v[150:151], 0, v[212:213]
	v_ashrrev_i32_e32 v175, 31, v174
	global_load_dwordx4 v[176:179], v[172:173], off
	global_load_dwordx4 v[188:191], v[172:173], off offset:64
	global_load_dwordx4 v[192:195], v[172:173], off offset:512
	global_load_dwordx4 v[196:199], v[172:173], off offset:576
	v_lshlrev_b64 v[216:217], 12, v[174:175]
	v_lshl_add_u64 v[208:209], v[150:151], 0, v[216:217]
	global_load_dwordx4 v[172:175], v[208:209], off
	global_load_dwordx4 v[200:203], v[208:209], off offset:64
	global_load_dwordx4 v[204:207], v[208:209], off offset:512
	s_nop 0
	global_load_dwordx4 v[208:211], v[208:209], off offset:576
	v_lshl_add_u64 v[212:213], s[24:25], 0, v[212:213]
	v_ashrrev_i32_e32 v171, 31, v170
	v_lshlrev_b64 v[170:171], 12, v[170:171]
	v_ashrrev_i32_e32 v169, 31, v168
	v_lshlrev_b64 v[168:169], 12, v[168:169]
	v_ashrrev_i32_e32 v167, 31, v166
	v_ashrrev_i32_e32 v165, 31, v164
	v_ashrrev_i32_e32 v163, 31, v162
	s_waitcnt vmcnt(0)
	v_pk_fma_f32 v[144:145], v[144:145], v[80:81], v[176:177]
	v_lshl_add_u64 v[176:177], v[212:213], 0, v[148:149]
	v_pk_fma_f32 v[130:131], v[130:131], v[74:75], v[194:195]
	v_pk_fma_f32 v[128:129], v[128:129], v[72:73], v[192:193]
	global_store_dwordx4 v[176:177], v[128:131], off offset:512 sc1
	v_pk_fma_f32 v[126:127], v[126:127], v[70:71], v[198:199]
	v_pk_fma_f32 v[124:125], v[124:125], v[68:69], v[196:197]
	v_lshl_add_u64 v[128:129], s[24:25], 0, v[216:217]
	global_store_dwordx4 v[176:177], v[124:127], off offset:576 sc1
	v_lshl_add_u64 v[128:129], v[128:129], 0, v[148:149]
	v_pk_fma_f32 v[146:147], v[146:147], v[82:83], v[178:179]
	v_pk_fma_f32 v[126:127], v[138:139], v[82:83], v[174:175]
	v_pk_fma_f32 v[124:125], v[136:137], v[80:81], v[172:173]
	v_pk_fma_f32 v[142:143], v[142:143], v[78:79], v[190:191]
	v_pk_fma_f32 v[140:141], v[140:141], v[76:77], v[188:189]
	global_store_dwordx4 v[128:129], v[124:127], off sc1
	v_pk_fma_f32 v[122:123], v[122:123], v[74:75], v[206:207]
	v_pk_fma_f32 v[120:121], v[120:121], v[72:73], v[204:205]
	v_pk_fma_f32 v[126:127], v[134:135], v[78:79], v[202:203]
	v_pk_fma_f32 v[124:125], v[132:133], v[76:77], v[200:201]
	v_pk_fma_f32 v[118:119], v[118:119], v[70:71], v[210:211]
	v_pk_fma_f32 v[116:117], v[116:117], v[68:69], v[208:209]
	global_store_dwordx4 v[176:177], v[144:147], off sc1
	global_store_dwordx4 v[176:177], v[140:143], off offset:64 sc1
	global_store_dwordx4 v[128:129], v[124:127], off offset:64 sc1
	global_store_dwordx4 v[128:129], v[120:123], off offset:512 sc1
	global_store_dwordx4 v[128:129], v[116:119], off offset:576 sc1
	v_lshl_add_u64 v[128:129], v[150:151], 0, v[170:171]
	global_load_dwordx4 v[116:119], v[128:129], off
	global_load_dwordx4 v[120:123], v[128:129], off offset:64
	global_load_dwordx4 v[124:127], v[128:129], off offset:512
	s_nop 0
	global_load_dwordx4 v[128:131], v[128:129], off offset:576
	v_lshl_add_u64 v[144:145], v[150:151], 0, v[168:169]
	global_load_dwordx4 v[132:135], v[144:145], off
	global_load_dwordx4 v[136:139], v[144:145], off offset:64
	global_load_dwordx4 v[140:143], v[144:145], off offset:512
	s_nop 0
	global_load_dwordx4 v[144:147], v[144:145], off offset:576
	v_lshl_add_u64 v[170:171], s[24:25], 0, v[170:171]
	s_waitcnt vmcnt(7)
	v_pk_fma_f32 v[112:113], v[112:113], v[80:81], v[116:117]
	v_lshl_add_u64 v[116:117], v[170:171], 0, v[148:149]
	s_waitcnt vmcnt(5)
	v_pk_fma_f32 v[98:99], v[98:99], v[74:75], v[126:127]
	v_pk_fma_f32 v[96:97], v[96:97], v[72:73], v[124:125]
	global_store_dwordx4 v[116:117], v[96:99], off offset:512 sc1
	s_waitcnt vmcnt(5)
	v_pk_fma_f32 v[94:95], v[94:95], v[70:71], v[130:131]
	v_pk_fma_f32 v[92:93], v[92:93], v[68:69], v[128:129]
	v_lshl_add_u64 v[96:97], s[24:25], 0, v[168:169]
	global_store_dwordx4 v[116:117], v[92:95], off offset:576 sc1
	v_lshl_add_u64 v[96:97], v[96:97], 0, v[148:149]
	v_pk_fma_f32 v[114:115], v[114:115], v[82:83], v[118:119]
	s_waitcnt vmcnt(5)
	v_pk_fma_f32 v[94:95], v[106:107], v[82:83], v[134:135]
	v_pk_fma_f32 v[92:93], v[104:105], v[80:81], v[132:133]
	v_pk_fma_f32 v[110:111], v[110:111], v[78:79], v[122:123]
	v_pk_fma_f32 v[108:109], v[108:109], v[76:77], v[120:121]
	global_store_dwordx4 v[96:97], v[92:95], off sc1
	s_waitcnt vmcnt(4)
	v_pk_fma_f32 v[90:91], v[90:91], v[74:75], v[142:143]
	v_pk_fma_f32 v[88:89], v[88:89], v[72:73], v[140:141]
	v_pk_fma_f32 v[94:95], v[102:103], v[78:79], v[138:139]
	v_pk_fma_f32 v[92:93], v[100:101], v[76:77], v[136:137]
	s_waitcnt vmcnt(3)
	v_pk_fma_f32 v[86:87], v[86:87], v[70:71], v[146:147]
	v_pk_fma_f32 v[84:85], v[84:85], v[68:69], v[144:145]
	global_store_dwordx4 v[116:117], v[112:115], off sc1
	global_store_dwordx4 v[116:117], v[108:111], off offset:64 sc1
	global_store_dwordx4 v[96:97], v[92:95], off offset:64 sc1
	global_store_dwordx4 v[96:97], v[88:91], off offset:512 sc1
	global_store_dwordx4 v[96:97], v[84:87], off offset:576 sc1
	v_lshlrev_b64 v[116:117], 12, v[166:167]
	v_lshl_add_u64 v[96:97], v[150:151], 0, v[116:117]
	global_load_dwordx4 v[84:87], v[96:97], off
	global_load_dwordx4 v[88:91], v[96:97], off offset:64
	global_load_dwordx4 v[92:95], v[96:97], off offset:512
	s_nop 0
	global_load_dwordx4 v[96:99], v[96:97], off offset:576
	v_lshlrev_b64 v[118:119], 12, v[164:165]
	v_lshl_add_u64 v[112:113], v[150:151], 0, v[118:119]
	global_load_dwordx4 v[100:103], v[112:113], off
	global_load_dwordx4 v[104:107], v[112:113], off offset:64
	global_load_dwordx4 v[108:111], v[112:113], off offset:512
	s_nop 0
	global_load_dwordx4 v[112:115], v[112:113], off offset:576
	v_lshl_add_u64 v[116:117], s[24:25], 0, v[116:117]
	s_waitcnt vmcnt(7)
	v_pk_fma_f32 v[64:65], v[64:65], v[80:81], v[84:85]
	v_lshl_add_u64 v[84:85], v[116:117], 0, v[148:149]
	s_waitcnt vmcnt(5)
	v_pk_fma_f32 v[50:51], v[50:51], v[74:75], v[94:95]
	v_pk_fma_f32 v[48:49], v[48:49], v[72:73], v[92:93]
	global_store_dwordx4 v[84:85], v[48:51], off offset:512 sc1
	s_waitcnt vmcnt(5)
	v_pk_fma_f32 v[46:47], v[46:47], v[70:71], v[98:99]
	v_pk_fma_f32 v[44:45], v[44:45], v[68:69], v[96:97]
	v_lshl_add_u64 v[48:49], s[24:25], 0, v[118:119]
	global_store_dwordx4 v[84:85], v[44:47], off offset:576 sc1
	v_lshl_add_u64 v[48:49], v[48:49], 0, v[148:149]
	v_pk_fma_f32 v[66:67], v[66:67], v[82:83], v[86:87]
	s_waitcnt vmcnt(5)
	v_pk_fma_f32 v[46:47], v[58:59], v[82:83], v[102:103]
	v_pk_fma_f32 v[44:45], v[56:57], v[80:81], v[100:101]
	v_pk_fma_f32 v[62:63], v[62:63], v[78:79], v[90:91]
	v_pk_fma_f32 v[60:61], v[60:61], v[76:77], v[88:89]
	global_store_dwordx4 v[48:49], v[44:47], off sc1
	s_waitcnt vmcnt(4)
	v_pk_fma_f32 v[42:43], v[42:43], v[74:75], v[110:111]
	v_pk_fma_f32 v[40:41], v[40:41], v[72:73], v[108:109]
	v_pk_fma_f32 v[46:47], v[54:55], v[78:79], v[106:107]
	v_pk_fma_f32 v[44:45], v[52:53], v[76:77], v[104:105]
	s_waitcnt vmcnt(3)
	v_pk_fma_f32 v[38:39], v[38:39], v[70:71], v[114:115]
	v_pk_fma_f32 v[36:37], v[36:37], v[68:69], v[112:113]
	global_store_dwordx4 v[84:85], v[64:67], off sc1
	global_store_dwordx4 v[84:85], v[60:63], off offset:64 sc1
	global_store_dwordx4 v[48:49], v[44:47], off offset:64 sc1
	global_store_dwordx4 v[48:49], v[40:43], off offset:512 sc1
	global_store_dwordx4 v[48:49], v[36:39], off offset:576 sc1
	v_lshlrev_b64 v[84:85], 12, v[162:163]
	v_add_u32_e32 v52, 0xb0, v160
	v_lshl_add_u64 v[48:49], v[150:151], 0, v[84:85]
	v_ashrrev_i32_e32 v53, 31, v52
	global_load_dwordx4 v[36:39], v[48:49], off
	global_load_dwordx4 v[40:43], v[48:49], off offset:64
	global_load_dwordx4 v[44:47], v[48:49], off offset:512
	s_nop 0
	global_load_dwordx4 v[48:51], v[48:49], off offset:576
	v_lshlrev_b64 v[86:87], 12, v[52:53]
	v_lshl_add_u64 v[64:65], v[150:151], 0, v[86:87]
	global_load_dwordx4 v[52:55], v[64:65], off
	global_load_dwordx4 v[56:59], v[64:65], off offset:64
	global_load_dwordx4 v[60:63], v[64:65], off offset:512
	s_nop 0
	global_load_dwordx4 v[64:67], v[64:65], off offset:576
	v_lshl_add_u64 v[84:85], s[24:25], 0, v[84:85]
	s_waitcnt vmcnt(7)
	v_pk_fma_f32 v[32:33], v[32:33], v[80:81], v[36:37]
	v_lshl_add_u64 v[36:37], v[84:85], 0, v[148:149]
	v_pk_fma_f32 v[34:35], v[34:35], v[82:83], v[38:39]
	s_waitcnt vmcnt(4)
	v_pk_fma_f32 v[22:23], v[22:23], v[70:71], v[50:51]
	v_pk_fma_f32 v[20:21], v[20:21], v[68:69], v[48:49]
	global_store_dwordx4 v[36:37], v[20:23], off offset:576 sc1
	v_pk_fma_f32 v[30:31], v[30:31], v[78:79], v[42:43]
	v_pk_fma_f32 v[28:29], v[28:29], v[76:77], v[40:41]
	v_lshl_add_u64 v[20:21], s[24:25], 0, v[86:87]
	v_pk_fma_f32 v[26:27], v[26:27], v[74:75], v[46:47]
	v_pk_fma_f32 v[24:25], v[24:25], v[72:73], v[44:45]
	s_waitcnt vmcnt(4)
	v_pk_fma_f32 v[18:19], v[18:19], v[82:83], v[54:55]
	v_pk_fma_f32 v[16:17], v[16:17], v[80:81], v[52:53]
	v_lshl_add_u64 v[20:21], v[20:21], 0, v[148:149]
	s_waitcnt vmcnt(3)
	v_pk_fma_f32 v[14:15], v[14:15], v[78:79], v[58:59]
	v_pk_fma_f32 v[12:13], v[12:13], v[76:77], v[56:57]
	s_waitcnt vmcnt(2)
	v_pk_fma_f32 v[10:11], v[10:11], v[74:75], v[62:63]
	v_pk_fma_f32 v[8:9], v[8:9], v[72:73], v[60:61]
	s_waitcnt vmcnt(1)
	v_pk_fma_f32 v[6:7], v[6:7], v[70:71], v[66:67]
	v_pk_fma_f32 v[4:5], v[4:5], v[68:69], v[64:65]
	global_store_dwordx4 v[36:37], v[32:35], off sc1
	global_store_dwordx4 v[36:37], v[28:31], off offset:64 sc1
	global_store_dwordx4 v[36:37], v[24:27], off offset:512 sc1
	global_store_dwordx4 v[20:21], v[16:19], off sc1
	global_store_dwordx4 v[20:21], v[12:15], off offset:64 sc1
	global_store_dwordx4 v[20:21], v[8:11], off offset:512 sc1
	global_store_dwordx4 v[20:21], v[4:7], off offset:576 sc1
	s_andn2_b64 vcc, exec, s[6:7]
	s_mov_b64 s[4:5], -1
	s_cbranch_vccnz .LBB0_28

.LBB0_79:
	v_mov_b32_e32 v148, v185
	v_mov_b32_e32 v76, v187
	s_cmp_eq_u32 s0, 0
	s_cbranch_scc1 .LBB0_81
	s_add_i32 s48, s0, -1
	s_ashr_i32 s27, s26, 31
	s_lshl_b64 s[0:1], s[48:49], 23
	s_add_u32 s2, s65, s0
	s_addc_u32 s4, s76, s1
	s_lshl_b64 s[0:1], s[26:27], 20
	s_add_u32 s2, s2, s0
	s_addc_u32 s4, s4, s1
	s_lshl_b32 s0, s28, 8
	s_ashr_i32 s1, s0, 31
	s_lshl_b64 s[0:1], s[0:1], 2
	s_add_u32 s0, s2, s0
	s_addc_u32 s1, s4, s1
	v_mov_b32_e32 v77, v148
	s_add_u32 s0, s0, s96
	v_lshlrev_b32_e32 v78, 2, v76
	s_addc_u32 s1, s1, 0
	v_add_u32_e32 v84, s82, v77
	v_ashrrev_i32_e32 v79, 31, v78
	v_ashrrev_i32_e32 v85, 31, v84
	v_lshl_add_u64 v[78:79], v[78:79], 2, s[0:1]
	v_lshlrev_b64 v[84:85], 12, v[84:85]
	v_lshl_add_u64 v[84:85], v[78:79], 0, v[84:85]
	global_store_dwordx4 v[84:85], v[144:147], off sc1
	global_store_dwordx4 v[84:85], v[140:143], off offset:64 sc1
	global_store_dwordx4 v[84:85], v[128:131], off offset:512 sc1
	global_store_dwordx4 v[84:85], v[124:127], off offset:576 sc1
	v_mov_b32_e32 v77, v148
	s_nop 0
	v_add_u32_e32 v84, s86, v77
	v_ashrrev_i32_e32 v85, 31, v84
	v_lshlrev_b64 v[84:85], 12, v[84:85]
	v_lshl_add_u64 v[84:85], v[78:79], 0, v[84:85]
	global_store_dwordx4 v[84:85], v[136:139], off sc1
	global_store_dwordx4 v[84:85], v[132:135], off offset:64 sc1
	global_store_dwordx4 v[84:85], v[120:123], off offset:512 sc1
	global_store_dwordx4 v[84:85], v[116:119], off offset:576 sc1
	v_mov_b32_e32 v77, v148
	s_nop 0
	v_add_u32_e32 v84, s87, v77
	v_ashrrev_i32_e32 v85, 31, v84
	v_lshlrev_b64 v[84:85], 12, v[84:85]
	v_lshl_add_u64 v[84:85], v[78:79], 0, v[84:85]
	global_store_dwordx4 v[84:85], v[108:111], off sc1
	global_store_dwordx4 v[84:85], v[104:107], off offset:64 sc1
	global_store_dwordx4 v[84:85], v[88:91], off offset:512 sc1
	global_store_dwordx4 v[84:85], v[80:83], off offset:576 sc1
	v_mov_b32_e32 v77, v148
	s_nop 0
	v_add_u32_e32 v84, s88, v77
	v_ashrrev_i32_e32 v85, 31, v84
	v_lshlrev_b64 v[84:85], 12, v[84:85]
	v_lshl_add_u64 v[84:85], v[78:79], 0, v[84:85]
	global_store_dwordx4 v[84:85], v[100:103], off sc1
	global_store_dwordx4 v[84:85], v[92:95], off offset:64 sc1
	global_store_dwordx4 v[84:85], v[72:75], off offset:512 sc1
	global_store_dwordx4 v[84:85], v[68:71], off offset:576 sc1
	v_mov_b32_e32 v77, v148
	s_nop 0
	v_add_u32_e32 v84, s89, v77
	v_ashrrev_i32_e32 v85, 31, v84
	v_lshlrev_b64 v[84:85], 12, v[84:85]
	v_lshl_add_u64 v[84:85], v[78:79], 0, v[84:85]
	global_store_dwordx4 v[84:85], v[64:67], off sc1
	global_store_dwordx4 v[84:85], v[60:63], off offset:64 sc1
	global_store_dwordx4 v[84:85], v[48:51], off offset:512 sc1
	global_store_dwordx4 v[84:85], v[44:47], off offset:576 sc1
	v_mov_b32_e32 v77, v148
	s_nop 0
	v_add_u32_e32 v84, s90, v77
	v_ashrrev_i32_e32 v85, 31, v84
	v_lshlrev_b64 v[84:85], 12, v[84:85]
	v_lshl_add_u64 v[84:85], v[78:79], 0, v[84:85]
	global_store_dwordx4 v[84:85], v[56:59], off sc1
	global_store_dwordx4 v[84:85], v[52:55], off offset:64 sc1
	global_store_dwordx4 v[84:85], v[40:43], off offset:512 sc1
	global_store_dwordx4 v[84:85], v[36:39], off offset:576 sc1
	v_mov_b32_e32 v77, v148
	s_nop 0
	v_add_u32_e32 v84, s91, v77
	v_ashrrev_i32_e32 v85, 31, v84
	v_lshlrev_b64 v[84:85], 12, v[84:85]
	v_lshl_add_u64 v[84:85], v[78:79], 0, v[84:85]
	global_store_dwordx4 v[84:85], v[32:35], off sc1
	global_store_dwordx4 v[84:85], v[28:31], off offset:64 sc1
	global_store_dwordx4 v[84:85], v[24:27], off offset:512 sc1
	global_store_dwordx4 v[84:85], v[20:23], off offset:576 sc1
	v_mov_b32_e32 v77, v148
	s_nop 0
	v_add_u32_e32 v84, s92, v77
	v_ashrrev_i32_e32 v85, 31, v84
	v_lshlrev_b64 v[84:85], 12, v[84:85]
	v_lshl_add_u64 v[78:79], v[78:79], 0, v[84:85]
	global_store_dwordx4 v[78:79], v[16:19], off sc1
	global_store_dwordx4 v[78:79], v[12:15], off offset:64 sc1
	global_store_dwordx4 v[78:79], v[8:11], off offset:512 sc1
	global_store_dwordx4 v[78:79], v[4:7], off offset:576 sc1
	s_cbranch_execz .LBB0_82
	s_branch .LBB0_90
.LBB0_81:
.LBB0_82:
	s_lshl_b32 s0, s28, 8
	s_add_i32 s48, s26, -8
	s_or_b32 s0, s0, s83
	s_lshr_b32 s2, s48, 4
	s_cmp_gt_i32 s26, 7
	v_lshl_add_u32 v170, v76, 2, s0
	s_cselect_b64 s[0:1], -1, 0
	s_and_b64 vcc, s[0:1], exec
	s_cselect_b32 s0, s2, 8
	s_mul_hi_u32 s1, s0, 0x6000
	s_mulk_i32 s0, 0x6000
	s_add_u32 s0, s60, s0
	s_addc_u32 s1, s61, s1
	v_ashrrev_i32_e32 v171, 31, v170
	v_lshl_add_u64 v[76:77], v[170:171], 2, s[0:1]
	global_load_dwordx4 v[112:115], v[76:77], off
	global_load_dwordx4 v[96:99], v[76:77], off offset:64
	global_load_dwordx4 v[84:87], v[76:77], off offset:512
	s_nop 0
	global_load_dwordx4 v[76:79], v[76:77], off offset:576
	v_add_u32_e32 v158, s82, v148
	s_mov_b64 s[4:5], -1
	v_ashrrev_i32_e32 v159, 31, v158
	v_add_u32_e32 v172, 16, v158
	v_add_u32_e32 v168, 32, v158
	v_add_u32_e32 v166, 48, v158
	v_add_u32_e32 v164, 0x80, v158
	v_add_u32_e32 v162, 0x90, v158
	v_add_u32_e32 v160, 0xa0, v158
	s_cbranch_vccz .LBB0_88
	s_lshl_b64 s[28:29], s[48:49], 20
	s_and_b64 vcc, exec, s[12:13]
	v_lshlrev_b64 v[174:175], 1, v[170:171]
	v_ashrrev_i32_e32 v173, 31, v172
	v_ashrrev_i32_e32 v169, 31, v168
	v_ashrrev_i32_e32 v167, 31, v166
	v_ashrrev_i32_e32 v165, 31, v164
	v_ashrrev_i32_e32 v163, 31, v162
	v_ashrrev_i32_e32 v161, 31, v160
	s_cbranch_vccz .LBB0_85
	s_add_u32 s30, s66, s28
	s_addc_u32 s31, s67, s29
	v_lshl_add_u64 v[148:149], s[30:31], 0, v[174:175]
	v_lshlrev_b64 v[214:215], 12, v[158:159]
	v_lshl_add_u64 v[150:151], v[148:149], 0, v[214:215]
	global_load_dwordx2 v[216:217], v[150:151], off
	global_load_dwordx2 v[218:219], v[150:151], off offset:32
	global_load_dwordx2 v[220:221], v[150:151], off offset:256
	global_load_dwordx2 v[222:223], v[150:151], off offset:288
	v_lshlrev_b64 v[210:211], 12, v[172:173]
	v_lshl_add_u64 v[150:151], v[148:149], 0, v[210:211]
	global_load_dwordx2 v[208:209], v[150:151], off
	global_load_dwordx2 v[206:207], v[150:151], off offset:32
	global_load_dwordx2 v[204:205], v[150:151], off offset:256
	global_load_dwordx2 v[202:203], v[150:151], off offset:288
	v_lshlrev_b64 v[200:201], 12, v[168:169]
	v_lshl_add_u64 v[150:151], v[148:149], 0, v[200:201]
	global_load_dwordx2 v[198:199], v[150:151], off
	global_load_dwordx2 v[196:197], v[150:151], off offset:32
	global_load_dwordx2 v[194:195], v[150:151], off offset:256
	global_load_dwordx2 v[188:189], v[150:151], off offset:288
	v_lshlrev_b64 v[192:193], 12, v[166:167]
	v_lshl_add_u64 v[150:151], v[148:149], 0, v[192:193]
	global_load_dwordx2 v[190:191], v[150:151], off
	global_load_dwordx2 v[178:179], v[150:151], off offset:32
	global_load_dwordx2 v[176:177], v[150:151], off offset:256
	s_nop 0
	global_load_dwordx2 v[150:151], v[150:151], off offset:288
	v_lshl_add_u64 v[214:215], s[30:31], 0, v[214:215]
	v_lshl_add_u64 v[214:215], v[214:215], 0, v[174:175]
	v_lshl_add_u64 v[210:211], s[30:31], 0, v[210:211]
	v_lshl_add_u64 v[200:201], s[30:31], 0, v[200:201]
	s_mov_b64 s[4:5], 0
	s_waitcnt vmcnt(0)
	v_lshlrev_b32_e32 v224, 16, v216
	v_and_b32_e32 v225, 0xffff0000, v216
	v_lshlrev_b32_e32 v216, 16, v217
	v_and_b32_e32 v217, 0xffff0000, v217
	v_pk_fma_f32 v[216:217], v[146:147], v[114:115], v[216:217]
	v_pk_fma_f32 v[224:225], v[144:145], v[112:113], v[224:225]
	s_nop 0
	v_cvt_pk_bf16_f32 v224, v224, v225
	v_cvt_pk_bf16_f32 v225, v216, v217
	v_lshlrev_b32_e32 v216, 16, v218
	v_and_b32_e32 v217, 0xffff0000, v218
	v_lshlrev_b32_e32 v218, 16, v219
	v_and_b32_e32 v219, 0xffff0000, v219
	v_pk_fma_f32 v[218:219], v[142:143], v[98:99], v[218:219]
	v_pk_fma_f32 v[216:217], v[140:141], v[96:97], v[216:217]
	global_store_dwordx2 v[214:215], v[224:225], off sc1
	v_cvt_pk_bf16_f32 v216, v216, v217
	v_cvt_pk_bf16_f32 v217, v218, v219
	global_store_dwordx2 v[214:215], v[216:217], off offset:32 sc1
	v_lshlrev_b32_e32 v216, 16, v220
	v_and_b32_e32 v217, 0xffff0000, v220
	v_lshlrev_b32_e32 v218, 16, v221
	v_and_b32_e32 v219, 0xffff0000, v221
	v_pk_fma_f32 v[218:219], v[130:131], v[86:87], v[218:219]
	v_pk_fma_f32 v[216:217], v[128:129], v[84:85], v[216:217]
	s_nop 0
	v_cvt_pk_bf16_f32 v216, v216, v217
	v_cvt_pk_bf16_f32 v217, v218, v219
	global_store_dwordx2 v[214:215], v[216:217], off offset:256 sc1
	v_lshlrev_b32_e32 v216, 16, v222
	v_and_b32_e32 v217, 0xffff0000, v222
	v_lshlrev_b32_e32 v218, 16, v223
	v_and_b32_e32 v219, 0xffff0000, v223
	v_pk_fma_f32 v[218:219], v[126:127], v[78:79], v[218:219]
	v_pk_fma_f32 v[216:217], v[124:125], v[76:77], v[216:217]
	s_nop 0
	v_cvt_pk_bf16_f32 v216, v216, v217
	v_cvt_pk_bf16_f32 v217, v218, v219
	global_store_dwordx2 v[214:215], v[216:217], off offset:288 sc1
	v_lshlrev_b32_e32 v214, 16, v208
	v_and_b32_e32 v215, 0xffff0000, v208
	v_lshlrev_b32_e32 v208, 16, v209
	v_and_b32_e32 v209, 0xffff0000, v209
	v_pk_fma_f32 v[208:209], v[138:139], v[114:115], v[208:209]
	v_pk_fma_f32 v[214:215], v[136:137], v[112:113], v[214:215]
	s_nop 0
	v_cvt_pk_bf16_f32 v214, v214, v215
	v_cvt_pk_bf16_f32 v215, v208, v209
	v_lshl_add_u64 v[208:209], v[210:211], 0, v[174:175]
	v_lshlrev_b32_e32 v210, 16, v206
	v_and_b32_e32 v211, 0xffff0000, v206
	v_lshlrev_b32_e32 v206, 16, v207
	v_and_b32_e32 v207, 0xffff0000, v207
	v_pk_fma_f32 v[206:207], v[134:135], v[98:99], v[206:207]
	v_pk_fma_f32 v[210:211], v[132:133], v[96:97], v[210:211]
	global_store_dwordx2 v[208:209], v[214:215], off sc1
	v_cvt_pk_bf16_f32 v210, v210, v211
	v_cvt_pk_bf16_f32 v211, v206, v207
	v_lshlrev_b32_e32 v206, 16, v204
	v_and_b32_e32 v207, 0xffff0000, v204
	v_lshlrev_b32_e32 v204, 16, v205
	v_and_b32_e32 v205, 0xffff0000, v205
	v_pk_fma_f32 v[204:205], v[122:123], v[86:87], v[204:205]
	v_pk_fma_f32 v[206:207], v[120:121], v[84:85], v[206:207]
	global_store_dwordx2 v[208:209], v[210:211], off offset:32 sc1
	v_cvt_pk_bf16_f32 v206, v206, v207
	v_cvt_pk_bf16_f32 v207, v204, v205
	v_lshlrev_b32_e32 v204, 16, v202
	v_and_b32_e32 v205, 0xffff0000, v202
	v_lshlrev_b32_e32 v202, 16, v203
	v_and_b32_e32 v203, 0xffff0000, v203
	v_pk_fma_f32 v[202:203], v[118:119], v[78:79], v[202:203]
	v_pk_fma_f32 v[204:205], v[116:117], v[76:77], v[204:205]
	global_store_dwordx2 v[208:209], v[206:207], off offset:256 sc1
	v_cvt_pk_bf16_f32 v204, v204, v205
	v_cvt_pk_bf16_f32 v205, v202, v203
	v_lshlrev_b32_e32 v202, 16, v198
	v_and_b32_e32 v203, 0xffff0000, v198
	v_lshlrev_b32_e32 v198, 16, v199
	v_and_b32_e32 v199, 0xffff0000, v199
	v_pk_fma_f32 v[198:199], v[110:111], v[114:115], v[198:199]
	v_pk_fma_f32 v[202:203], v[108:109], v[112:113], v[202:203]
	global_store_dwordx2 v[208:209], v[204:205], off offset:288 sc1
	v_cvt_pk_bf16_f32 v202, v202, v203
	v_cvt_pk_bf16_f32 v203, v198, v199
	v_lshl_add_u64 v[198:199], v[200:201], 0, v[174:175]
	v_lshlrev_b32_e32 v200, 16, v196
	v_and_b32_e32 v201, 0xffff0000, v196
	v_lshlrev_b32_e32 v196, 16, v197
	v_and_b32_e32 v197, 0xffff0000, v197
	v_pk_fma_f32 v[196:197], v[106:107], v[98:99], v[196:197]
	v_pk_fma_f32 v[200:201], v[104:105], v[96:97], v[200:201]
	global_store_dwordx2 v[198:199], v[202:203], off sc1
	v_cvt_pk_bf16_f32 v200, v200, v201
	v_cvt_pk_bf16_f32 v201, v196, v197
	v_lshlrev_b32_e32 v196, 16, v194
	v_and_b32_e32 v197, 0xffff0000, v194
	v_lshlrev_b32_e32 v194, 16, v195
	v_and_b32_e32 v195, 0xffff0000, v195
	v_pk_fma_f32 v[194:195], v[90:91], v[86:87], v[194:195]
	v_pk_fma_f32 v[196:197], v[88:89], v[84:85], v[196:197]
	global_store_dwordx2 v[198:199], v[200:201], off offset:32 sc1
	v_cvt_pk_bf16_f32 v196, v196, v197
	v_cvt_pk_bf16_f32 v197, v194, v195
	v_lshlrev_b32_e32 v194, 16, v188
	v_and_b32_e32 v195, 0xffff0000, v188
	v_lshlrev_b32_e32 v188, 16, v189
	v_and_b32_e32 v189, 0xffff0000, v189
	v_pk_fma_f32 v[188:189], v[82:83], v[78:79], v[188:189]
	v_pk_fma_f32 v[194:195], v[80:81], v[76:77], v[194:195]
	global_store_dwordx2 v[198:199], v[196:197], off offset:256 sc1
	v_cvt_pk_bf16_f32 v194, v194, v195
	v_cvt_pk_bf16_f32 v195, v188, v189
	v_lshl_add_u64 v[188:189], s[30:31], 0, v[192:193]
	v_lshlrev_b32_e32 v192, 16, v190
	v_and_b32_e32 v193, 0xffff0000, v190
	v_lshlrev_b32_e32 v190, 16, v191
	v_and_b32_e32 v191, 0xffff0000, v191
	v_pk_fma_f32 v[190:191], v[102:103], v[114:115], v[190:191]
	v_pk_fma_f32 v[192:193], v[100:101], v[112:113], v[192:193]
	v_lshl_add_u64 v[188:189], v[188:189], 0, v[174:175]
	v_cvt_pk_bf16_f32 v192, v192, v193
	v_cvt_pk_bf16_f32 v193, v190, v191
	v_lshlrev_b32_e32 v190, 16, v178
	v_and_b32_e32 v191, 0xffff0000, v178
	v_lshlrev_b32_e32 v178, 16, v179
	v_and_b32_e32 v179, 0xffff0000, v179
	v_pk_fma_f32 v[178:179], v[94:95], v[98:99], v[178:179]
	v_pk_fma_f32 v[190:191], v[92:93], v[96:97], v[190:191]
	global_store_dwordx2 v[198:199], v[194:195], off offset:288 sc1
	v_cvt_pk_bf16_f32 v190, v190, v191
	v_cvt_pk_bf16_f32 v191, v178, v179
	v_lshlrev_b32_e32 v178, 16, v176
	v_and_b32_e32 v179, 0xffff0000, v176
	v_lshlrev_b32_e32 v176, 16, v177
	v_and_b32_e32 v177, 0xffff0000, v177
	v_pk_fma_f32 v[176:177], v[74:75], v[86:87], v[176:177]
	v_pk_fma_f32 v[178:179], v[72:73], v[84:85], v[178:179]
	global_store_dwordx2 v[188:189], v[192:193], off sc1
	v_cvt_pk_bf16_f32 v178, v178, v179
	v_cvt_pk_bf16_f32 v179, v176, v177
	v_lshlrev_b32_e32 v176, 16, v150
	v_and_b32_e32 v177, 0xffff0000, v150
	v_lshlrev_b32_e32 v150, 16, v151
	v_and_b32_e32 v151, 0xffff0000, v151
	v_pk_fma_f32 v[150:151], v[70:71], v[78:79], v[150:151]
	v_pk_fma_f32 v[176:177], v[68:69], v[76:77], v[176:177]
	global_store_dwordx2 v[188:189], v[190:191], off offset:32 sc1
	v_cvt_pk_bf16_f32 v176, v176, v177
	v_cvt_pk_bf16_f32 v177, v150, v151
	global_store_dwordx2 v[188:189], v[178:179], off offset:256 sc1
	global_store_dwordx2 v[188:189], v[176:177], off offset:288 sc1
	v_lshlrev_b64 v[150:151], 12, v[164:165]
	v_lshl_add_u64 v[176:177], v[148:149], 0, v[150:151]
	global_load_dwordx2 v[178:179], v[176:177], off
	global_load_dwordx2 v[188:189], v[176:177], off offset:32
	global_load_dwordx2 v[190:191], v[176:177], off offset:256
	s_nop 0
	global_load_dwordx2 v[176:177], v[176:177], off offset:288
	v_lshlrev_b64 v[192:193], 12, v[162:163]
	v_lshl_add_u64 v[194:195], v[148:149], 0, v[192:193]
	global_load_dwordx2 v[196:197], v[194:195], off
	global_load_dwordx2 v[198:199], v[194:195], off offset:32
	global_load_dwordx2 v[200:201], v[194:195], off offset:256
	s_nop 0
	global_load_dwordx2 v[194:195], v[194:195], off offset:288
	v_lshlrev_b64 v[202:203], 12, v[160:161]
	v_lshl_add_u64 v[204:205], v[148:149], 0, v[202:203]
	global_load_dwordx2 v[206:207], v[204:205], off
	global_load_dwordx2 v[208:209], v[204:205], off offset:32
	global_load_dwordx2 v[210:211], v[204:205], off offset:256
	s_nop 0
	global_load_dwordx2 v[204:205], v[204:205], off offset:288
	v_add_u32_e32 v214, 0xb0, v158
	v_ashrrev_i32_e32 v215, 31, v214
	v_lshlrev_b64 v[214:215], 12, v[214:215]
	v_lshl_add_u64 v[148:149], v[148:149], 0, v[214:215]
	global_load_dwordx2 v[216:217], v[148:149], off
	global_load_dwordx2 v[218:219], v[148:149], off offset:32
	global_load_dwordx2 v[220:221], v[148:149], off offset:256
	s_nop 0
	global_load_dwordx2 v[148:149], v[148:149], off offset:288
	v_lshl_add_u64 v[150:151], s[30:31], 0, v[150:151]
	v_lshl_add_u64 v[150:151], v[150:151], 0, v[174:175]
	s_waitcnt vmcnt(15)
	v_lshlrev_b32_e32 v222, 16, v178
	v_and_b32_e32 v223, 0xffff0000, v178
	v_lshlrev_b32_e32 v178, 16, v179
	v_and_b32_e32 v179, 0xffff0000, v179
	v_pk_fma_f32 v[178:179], v[66:67], v[114:115], v[178:179]
	v_pk_fma_f32 v[222:223], v[64:65], v[112:113], v[222:223]
	s_nop 0
	v_cvt_pk_bf16_f32 v222, v222, v223
	v_cvt_pk_bf16_f32 v223, v178, v179
	s_waitcnt vmcnt(14)
	v_lshlrev_b32_e32 v178, 16, v188
	v_and_b32_e32 v179, 0xffff0000, v188
	v_lshlrev_b32_e32 v188, 16, v189
	v_and_b32_e32 v189, 0xffff0000, v189
	v_pk_fma_f32 v[188:189], v[62:63], v[98:99], v[188:189]
	v_pk_fma_f32 v[178:179], v[60:61], v[96:97], v[178:179]
	global_store_dwordx2 v[150:151], v[222:223], off sc1
	v_cvt_pk_bf16_f32 v178, v178, v179
	v_cvt_pk_bf16_f32 v179, v188, v189
	global_store_dwordx2 v[150:151], v[178:179], off offset:32 sc1
	s_waitcnt vmcnt(15)
	v_lshlrev_b32_e32 v178, 16, v190
	v_and_b32_e32 v179, 0xffff0000, v190
	v_lshlrev_b32_e32 v188, 16, v191
	v_and_b32_e32 v189, 0xffff0000, v191
	v_pk_fma_f32 v[188:189], v[50:51], v[86:87], v[188:189]
	v_pk_fma_f32 v[178:179], v[48:49], v[84:85], v[178:179]
	s_nop 0
	v_cvt_pk_bf16_f32 v178, v178, v179
	v_cvt_pk_bf16_f32 v179, v188, v189
	global_store_dwordx2 v[150:151], v[178:179], off offset:256 sc1
	s_waitcnt vmcnt(15)
	v_lshlrev_b32_e32 v178, 16, v176
	v_and_b32_e32 v179, 0xffff0000, v176
	v_lshlrev_b32_e32 v176, 16, v177
	v_and_b32_e32 v177, 0xffff0000, v177
	v_pk_fma_f32 v[176:177], v[46:47], v[78:79], v[176:177]
	v_pk_fma_f32 v[178:179], v[44:45], v[76:77], v[178:179]
	s_nop 0
	v_cvt_pk_bf16_f32 v178, v178, v179
	v_cvt_pk_bf16_f32 v179, v176, v177
	global_store_dwordx2 v[150:151], v[178:179], off offset:288 sc1
	s_waitcnt vmcnt(15)
	v_lshlrev_b32_e32 v176, 16, v196
	v_and_b32_e32 v177, 0xffff0000, v196
	v_lshlrev_b32_e32 v178, 16, v197
	v_and_b32_e32 v179, 0xffff0000, v197
	v_lshl_add_u64 v[150:151], s[30:31], 0, v[192:193]
	v_pk_fma_f32 v[178:179], v[58:59], v[114:115], v[178:179]
	v_pk_fma_f32 v[176:177], v[56:57], v[112:113], v[176:177]
	v_lshl_add_u64 v[150:151], v[150:151], 0, v[174:175]
	v_cvt_pk_bf16_f32 v176, v176, v177
	v_cvt_pk_bf16_f32 v177, v178, v179
	global_store_dwordx2 v[150:151], v[176:177], off sc1
	s_waitcnt vmcnt(15)
	v_lshlrev_b32_e32 v176, 16, v198
	v_and_b32_e32 v177, 0xffff0000, v198
	v_lshlrev_b32_e32 v178, 16, v199
	v_and_b32_e32 v179, 0xffff0000, v199
	v_pk_fma_f32 v[178:179], v[54:55], v[98:99], v[178:179]
	v_pk_fma_f32 v[176:177], v[52:53], v[96:97], v[176:177]
	s_nop 0
	v_cvt_pk_bf16_f32 v176, v176, v177
	v_cvt_pk_bf16_f32 v177, v178, v179
	global_store_dwordx2 v[150:151], v[176:177], off offset:32 sc1
	s_waitcnt vmcnt(15)
	v_lshlrev_b32_e32 v176, 16, v200
	v_and_b32_e32 v177, 0xffff0000, v200
	v_lshlrev_b32_e32 v178, 16, v201
	v_and_b32_e32 v179, 0xffff0000, v201
	v_pk_fma_f32 v[178:179], v[42:43], v[86:87], v[178:179]
	v_pk_fma_f32 v[176:177], v[40:41], v[84:85], v[176:177]
	s_nop 0
	v_cvt_pk_bf16_f32 v176, v176, v177
	v_cvt_pk_bf16_f32 v177, v178, v179
	global_store_dwordx2 v[150:151], v[176:177], off offset:256 sc1
	s_waitcnt vmcnt(15)
	v_lshlrev_b32_e32 v176, 16, v194
	v_and_b32_e32 v177, 0xffff0000, v194
	v_lshlrev_b32_e32 v178, 16, v195
	v_and_b32_e32 v179, 0xffff0000, v195
	v_pk_fma_f32 v[178:179], v[38:39], v[78:79], v[178:179]
	v_pk_fma_f32 v[176:177], v[36:37], v[76:77], v[176:177]
	s_nop 0
	v_cvt_pk_bf16_f32 v176, v176, v177
	v_cvt_pk_bf16_f32 v177, v178, v179
	global_store_dwordx2 v[150:151], v[176:177], off offset:288 sc1
	s_waitcnt vmcnt(15)
	v_lshlrev_b32_e32 v176, 16, v206
	v_and_b32_e32 v177, 0xffff0000, v206
	v_lshlrev_b32_e32 v178, 16, v207
	v_and_b32_e32 v179, 0xffff0000, v207
	v_lshl_add_u64 v[150:151], s[30:31], 0, v[202:203]
	v_pk_fma_f32 v[178:179], v[34:35], v[114:115], v[178:179]
	v_pk_fma_f32 v[176:177], v[32:33], v[112:113], v[176:177]
	v_lshl_add_u64 v[150:151], v[150:151], 0, v[174:175]
	v_cvt_pk_bf16_f32 v176, v176, v177
	v_cvt_pk_bf16_f32 v177, v178, v179
	global_store_dwordx2 v[150:151], v[176:177], off sc1
	s_waitcnt vmcnt(15)
	v_lshlrev_b32_e32 v176, 16, v208
	v_and_b32_e32 v177, 0xffff0000, v208
	v_lshlrev_b32_e32 v178, 16, v209
	v_and_b32_e32 v179, 0xffff0000, v209
	v_pk_fma_f32 v[178:179], v[30:31], v[98:99], v[178:179]
	v_pk_fma_f32 v[176:177], v[28:29], v[96:97], v[176:177]
	s_nop 0
	v_cvt_pk_bf16_f32 v176, v176, v177
	v_cvt_pk_bf16_f32 v177, v178, v179
	global_store_dwordx2 v[150:151], v[176:177], off offset:32 sc1
	s_waitcnt vmcnt(15)
	v_lshlrev_b32_e32 v176, 16, v210
	v_and_b32_e32 v177, 0xffff0000, v210
	v_lshlrev_b32_e32 v178, 16, v211
	v_and_b32_e32 v179, 0xffff0000, v211
	v_pk_fma_f32 v[178:179], v[26:27], v[86:87], v[178:179]
	v_pk_fma_f32 v[176:177], v[24:25], v[84:85], v[176:177]
	s_nop 0
	v_cvt_pk_bf16_f32 v176, v176, v177
	v_cvt_pk_bf16_f32 v177, v178, v179
	global_store_dwordx2 v[150:151], v[176:177], off offset:256 sc1
	s_waitcnt vmcnt(15)
	v_lshlrev_b32_e32 v176, 16, v204
	v_and_b32_e32 v177, 0xffff0000, v204
	v_lshlrev_b32_e32 v178, 16, v205
	v_and_b32_e32 v179, 0xffff0000, v205
	v_pk_fma_f32 v[178:179], v[22:23], v[78:79], v[178:179]
	v_pk_fma_f32 v[176:177], v[20:21], v[76:77], v[176:177]
	s_nop 0
	v_cvt_pk_bf16_f32 v176, v176, v177
	v_cvt_pk_bf16_f32 v177, v178, v179
	global_store_dwordx2 v[150:151], v[176:177], off offset:288 sc1
	s_waitcnt vmcnt(15)
	v_lshlrev_b32_e32 v176, 16, v216
	v_and_b32_e32 v177, 0xffff0000, v216
	v_lshlrev_b32_e32 v178, 16, v217
	v_and_b32_e32 v179, 0xffff0000, v217
	v_lshl_add_u64 v[150:151], s[30:31], 0, v[214:215]
	v_pk_fma_f32 v[178:179], v[18:19], v[114:115], v[178:179]
	v_pk_fma_f32 v[176:177], v[16:17], v[112:113], v[176:177]
	v_lshl_add_u64 v[150:151], v[150:151], 0, v[174:175]
	v_cvt_pk_bf16_f32 v176, v176, v177
	v_cvt_pk_bf16_f32 v177, v178, v179
	global_store_dwordx2 v[150:151], v[176:177], off sc1
	s_waitcnt vmcnt(15)
	v_lshlrev_b32_e32 v176, 16, v218
	v_and_b32_e32 v177, 0xffff0000, v218
	v_lshlrev_b32_e32 v178, 16, v219
	v_and_b32_e32 v179, 0xffff0000, v219
	v_pk_fma_f32 v[178:179], v[14:15], v[98:99], v[178:179]
	v_pk_fma_f32 v[176:177], v[12:13], v[96:97], v[176:177]
	s_nop 0
	v_cvt_pk_bf16_f32 v176, v176, v177
	v_cvt_pk_bf16_f32 v177, v178, v179
	global_store_dwordx2 v[150:151], v[176:177], off offset:32 sc1
	s_waitcnt vmcnt(15)
	v_lshlrev_b32_e32 v176, 16, v220
	v_and_b32_e32 v177, 0xffff0000, v220
	v_lshlrev_b32_e32 v178, 16, v221
	v_and_b32_e32 v179, 0xffff0000, v221
	v_pk_fma_f32 v[178:179], v[10:11], v[86:87], v[178:179]
	v_pk_fma_f32 v[176:177], v[8:9], v[84:85], v[176:177]
	s_nop 0
	v_cvt_pk_bf16_f32 v176, v176, v177
	v_cvt_pk_bf16_f32 v177, v178, v179
	global_store_dwordx2 v[150:151], v[176:177], off offset:256 sc1
	s_waitcnt vmcnt(15)
	v_lshlrev_b32_e32 v176, 16, v148
	v_and_b32_e32 v177, 0xffff0000, v148
	v_lshlrev_b32_e32 v148, 16, v149
	v_and_b32_e32 v149, 0xffff0000, v149
	v_pk_fma_f32 v[148:149], v[6:7], v[78:79], v[148:149]
	v_pk_fma_f32 v[176:177], v[4:5], v[76:77], v[176:177]
	s_nop 0
	v_cvt_pk_bf16_f32 v176, v176, v177
	v_cvt_pk_bf16_f32 v177, v148, v149
	global_store_dwordx2 v[150:151], v[176:177], off offset:288 sc1
.LBB0_85:
	s_andn2_b64 vcc, exec, s[4:5]
	s_cbranch_vccnz .LBB0_87
	v_lshl_add_u64 v[148:149], v[170:171], 2, s[28:29]
	v_lshlrev_b64 v[150:151], 12, v[158:159]
	v_lshl_add_u64 v[196:197], v[148:149], 0, v[150:151]
	global_load_dwordx4 v[176:179], v[196:197], off
	global_load_dwordx4 v[188:191], v[196:197], off offset:64
	global_load_dwordx4 v[192:195], v[196:197], off offset:512
	s_nop 0
	global_load_dwordx4 v[196:199], v[196:197], off offset:576
	v_lshlrev_b64 v[218:219], 12, v[172:173]
	v_lshl_add_u64 v[214:215], v[148:149], 0, v[218:219]
	global_load_dwordx4 v[200:203], v[214:215], off
	global_load_dwordx4 v[204:207], v[214:215], off offset:64
	global_load_dwordx4 v[208:211], v[214:215], off offset:512
	s_nop 0
	global_load_dwordx4 v[214:217], v[214:215], off offset:576
	v_lshl_add_u64 v[150:151], s[28:29], 0, v[150:151]
	v_lshl_add_u64 v[150:151], v[150:151], 0, v[174:175]
	s_waitcnt vmcnt(0)
	v_pk_fma_f32 v[178:179], v[146:147], v[114:115], v[178:179]
	v_pk_fma_f32 v[176:177], v[144:145], v[112:113], v[176:177]
	s_nop 0
	v_cvt_pk_bf16_f32 v176, v176, v177
	v_cvt_pk_bf16_f32 v177, v178, v179
	global_store_dwordx2 v[150:151], v[176:177], off sc1
	v_pk_fma_f32 v[176:177], v[142:143], v[98:99], v[190:191]
	v_pk_fma_f32 v[178:179], v[140:141], v[96:97], v[188:189]
	s_nop 0
	v_cvt_pk_bf16_f32 v178, v178, v179
	v_cvt_pk_bf16_f32 v179, v176, v177
	global_store_dwordx2 v[150:151], v[178:179], off offset:32 sc1
	v_pk_fma_f32 v[176:177], v[130:131], v[86:87], v[194:195]
	v_pk_fma_f32 v[178:179], v[128:129], v[84:85], v[192:193]
	s_nop 0
	v_cvt_pk_bf16_f32 v178, v178, v179
	v_cvt_pk_bf16_f32 v179, v176, v177
	global_store_dwordx2 v[150:151], v[178:179], off offset:256 sc1
	v_pk_fma_f32 v[176:177], v[126:127], v[78:79], v[198:199]
	v_pk_fma_f32 v[178:179], v[124:125], v[76:77], v[196:197]
	s_nop 0
	v_cvt_pk_bf16_f32 v178, v178, v179
	v_cvt_pk_bf16_f32 v179, v176, v177
	global_store_dwordx2 v[150:151], v[178:179], off offset:288 sc1
	v_lshl_add_u64 v[150:151], s[28:29], 0, v[218:219]
	v_pk_fma_f32 v[176:177], v[138:139], v[114:115], v[202:203]
	v_pk_fma_f32 v[178:179], v[136:137], v[112:113], v[200:201]
	v_lshl_add_u64 v[150:151], v[150:151], 0, v[174:175]
	v_cvt_pk_bf16_f32 v178, v178, v179
	v_cvt_pk_bf16_f32 v179, v176, v177
	global_store_dwordx2 v[150:151], v[178:179], off sc1
	v_pk_fma_f32 v[176:177], v[134:135], v[98:99], v[206:207]
	v_pk_fma_f32 v[178:179], v[132:133], v[96:97], v[204:205]
	v_lshlrev_b64 v[218:219], 12, v[166:167]
	v_cvt_pk_bf16_f32 v178, v178, v179
	v_cvt_pk_bf16_f32 v179, v176, v177
	global_store_dwordx2 v[150:151], v[178:179], off offset:32 sc1
	v_pk_fma_f32 v[176:177], v[122:123], v[86:87], v[210:211]
	v_pk_fma_f32 v[178:179], v[120:121], v[84:85], v[208:209]
	s_nop 0
	v_cvt_pk_bf16_f32 v178, v178, v179
	v_cvt_pk_bf16_f32 v179, v176, v177
	global_store_dwordx2 v[150:151], v[178:179], off offset:256 sc1
	v_pk_fma_f32 v[176:177], v[118:119], v[78:79], v[216:217]
	v_pk_fma_f32 v[178:179], v[116:117], v[76:77], v[214:215]
	v_lshl_add_u64 v[214:215], v[148:149], 0, v[218:219]
	v_cvt_pk_bf16_f32 v178, v178, v179
	v_cvt_pk_bf16_f32 v179, v176, v177
	global_store_dwordx2 v[150:151], v[178:179], off offset:288 sc1
	v_lshlrev_b64 v[150:151], 12, v[168:169]
	v_lshl_add_u64 v[196:197], v[148:149], 0, v[150:151]
	global_load_dwordx4 v[176:179], v[196:197], off
	global_load_dwordx4 v[188:191], v[196:197], off offset:64
	global_load_dwordx4 v[192:195], v[196:197], off offset:512
	s_nop 0
	global_load_dwordx4 v[196:199], v[196:197], off offset:576
	s_nop 0
	global_load_dwordx4 v[200:203], v[214:215], off
	global_load_dwordx4 v[204:207], v[214:215], off offset:64
	global_load_dwordx4 v[208:211], v[214:215], off offset:512
	s_nop 0
	global_load_dwordx4 v[214:217], v[214:215], off offset:576
	v_lshl_add_u64 v[150:151], s[28:29], 0, v[150:151]
	v_lshl_add_u64 v[150:151], v[150:151], 0, v[174:175]
	s_waitcnt vmcnt(7)
	v_pk_fma_f32 v[178:179], v[110:111], v[114:115], v[178:179]
	v_pk_fma_f32 v[176:177], v[108:109], v[112:113], v[176:177]
	s_nop 0
	v_cvt_pk_bf16_f32 v176, v176, v177
	v_cvt_pk_bf16_f32 v177, v178, v179
	global_store_dwordx2 v[150:151], v[176:177], off sc1
	s_waitcnt vmcnt(7)
	v_pk_fma_f32 v[176:177], v[106:107], v[98:99], v[190:191]
	v_pk_fma_f32 v[178:179], v[104:105], v[96:97], v[188:189]
	s_nop 0
	v_cvt_pk_bf16_f32 v178, v178, v179
	v_cvt_pk_bf16_f32 v179, v176, v177
	global_store_dwordx2 v[150:151], v[178:179], off offset:32 sc1
	s_waitcnt vmcnt(7)
	v_pk_fma_f32 v[176:177], v[90:91], v[86:87], v[194:195]
	v_pk_fma_f32 v[178:179], v[88:89], v[84:85], v[192:193]
	s_nop 0
	v_cvt_pk_bf16_f32 v178, v178, v179
	v_cvt_pk_bf16_f32 v179, v176, v177
	global_store_dwordx2 v[150:151], v[178:179], off offset:256 sc1
	s_waitcnt vmcnt(7)
	v_pk_fma_f32 v[176:177], v[82:83], v[78:79], v[198:199]
	v_pk_fma_f32 v[178:179], v[80:81], v[76:77], v[196:197]
	s_nop 0
	v_cvt_pk_bf16_f32 v178, v178, v179
	v_cvt_pk_bf16_f32 v179, v176, v177
	global_store_dwordx2 v[150:151], v[178:179], off offset:288 sc1
	v_lshl_add_u64 v[150:151], s[28:29], 0, v[218:219]
	s_waitcnt vmcnt(7)
	v_pk_fma_f32 v[176:177], v[102:103], v[114:115], v[202:203]
	v_pk_fma_f32 v[178:179], v[100:101], v[112:113], v[200:201]
	v_lshl_add_u64 v[150:151], v[150:151], 0, v[174:175]
	v_cvt_pk_bf16_f32 v178, v178, v179
	v_cvt_pk_bf16_f32 v179, v176, v177
	global_store_dwordx2 v[150:151], v[178:179], off sc1
	s_waitcnt vmcnt(7)
	v_pk_fma_f32 v[176:177], v[94:95], v[98:99], v[206:207]
	v_pk_fma_f32 v[178:179], v[92:93], v[96:97], v[204:205]
	v_lshlrev_b64 v[218:219], 12, v[162:163]
	v_cvt_pk_bf16_f32 v178, v178, v179
	v_cvt_pk_bf16_f32 v179, v176, v177
	global_store_dwordx2 v[150:151], v[178:179], off offset:32 sc1
	s_waitcnt vmcnt(7)
	v_pk_fma_f32 v[176:177], v[74:75], v[86:87], v[210:211]
	v_pk_fma_f32 v[178:179], v[72:73], v[84:85], v[208:209]
	s_nop 0
	v_cvt_pk_bf16_f32 v178, v178, v179
	v_cvt_pk_bf16_f32 v179, v176, v177
	global_store_dwordx2 v[150:151], v[178:179], off offset:256 sc1
	s_waitcnt vmcnt(7)
	v_pk_fma_f32 v[176:177], v[70:71], v[78:79], v[216:217]
	v_pk_fma_f32 v[178:179], v[68:69], v[76:77], v[214:215]
	v_lshl_add_u64 v[214:215], v[148:149], 0, v[218:219]
	v_cvt_pk_bf16_f32 v178, v178, v179
	v_cvt_pk_bf16_f32 v179, v176, v177
	global_store_dwordx2 v[150:151], v[178:179], off offset:288 sc1
	v_lshlrev_b64 v[150:151], 12, v[164:165]
	v_lshl_add_u64 v[196:197], v[148:149], 0, v[150:151]
	global_load_dwordx4 v[176:179], v[196:197], off
	global_load_dwordx4 v[188:191], v[196:197], off offset:64
	global_load_dwordx4 v[192:195], v[196:197], off offset:512
	s_nop 0
	global_load_dwordx4 v[196:199], v[196:197], off offset:576
	s_nop 0
	global_load_dwordx4 v[200:203], v[214:215], off
	global_load_dwordx4 v[204:207], v[214:215], off offset:64
	global_load_dwordx4 v[208:211], v[214:215], off offset:512
	s_nop 0
	global_load_dwordx4 v[214:217], v[214:215], off offset:576
	v_lshl_add_u64 v[150:151], s[28:29], 0, v[150:151]
	v_lshl_add_u64 v[150:151], v[150:151], 0, v[174:175]
	s_waitcnt vmcnt(7)
	v_pk_fma_f32 v[178:179], v[66:67], v[114:115], v[178:179]
	v_pk_fma_f32 v[176:177], v[64:65], v[112:113], v[176:177]
	s_nop 0
	v_cvt_pk_bf16_f32 v176, v176, v177
	v_cvt_pk_bf16_f32 v177, v178, v179
	global_store_dwordx2 v[150:151], v[176:177], off sc1
	s_waitcnt vmcnt(7)
	v_pk_fma_f32 v[176:177], v[62:63], v[98:99], v[190:191]
	v_pk_fma_f32 v[178:179], v[60:61], v[96:97], v[188:189]
	s_nop 0
	v_cvt_pk_bf16_f32 v178, v178, v179
	v_cvt_pk_bf16_f32 v179, v176, v177
	global_store_dwordx2 v[150:151], v[178:179], off offset:32 sc1
	s_waitcnt vmcnt(7)
	v_pk_fma_f32 v[176:177], v[50:51], v[86:87], v[194:195]
	v_pk_fma_f32 v[178:179], v[48:49], v[84:85], v[192:193]
	s_nop 0
	v_cvt_pk_bf16_f32 v178, v178, v179
	v_cvt_pk_bf16_f32 v179, v176, v177
	global_store_dwordx2 v[150:151], v[178:179], off offset:256 sc1
	s_waitcnt vmcnt(7)
	v_pk_fma_f32 v[176:177], v[46:47], v[78:79], v[198:199]
	v_pk_fma_f32 v[178:179], v[44:45], v[76:77], v[196:197]
	s_nop 0
	v_cvt_pk_bf16_f32 v178, v178, v179
	v_cvt_pk_bf16_f32 v179, v176, v177
	global_store_dwordx2 v[150:151], v[178:179], off offset:288 sc1
	v_lshl_add_u64 v[150:151], s[28:29], 0, v[218:219]
	s_waitcnt vmcnt(7)
	v_pk_fma_f32 v[176:177], v[58:59], v[114:115], v[202:203]
	v_pk_fma_f32 v[178:179], v[56:57], v[112:113], v[200:201]
	v_lshl_add_u64 v[150:151], v[150:151], 0, v[174:175]
	v_cvt_pk_bf16_f32 v178, v178, v179
	v_cvt_pk_bf16_f32 v179, v176, v177
	global_store_dwordx2 v[150:151], v[178:179], off sc1
	s_waitcnt vmcnt(7)
	v_pk_fma_f32 v[176:177], v[54:55], v[98:99], v[206:207]
	v_pk_fma_f32 v[178:179], v[52:53], v[96:97], v[204:205]
	s_nop 0
	v_cvt_pk_bf16_f32 v178, v178, v179
	v_cvt_pk_bf16_f32 v179, v176, v177
	global_store_dwordx2 v[150:151], v[178:179], off offset:32 sc1
	s_waitcnt vmcnt(7)
	v_pk_fma_f32 v[176:177], v[42:43], v[86:87], v[210:211]
	v_pk_fma_f32 v[178:179], v[40:41], v[84:85], v[208:209]
	s_nop 0
	v_cvt_pk_bf16_f32 v178, v178, v179
	v_cvt_pk_bf16_f32 v179, v176, v177
	global_store_dwordx2 v[150:151], v[178:179], off offset:256 sc1
	s_waitcnt vmcnt(7)
	v_pk_fma_f32 v[176:177], v[38:39], v[78:79], v[216:217]
	v_pk_fma_f32 v[178:179], v[36:37], v[76:77], v[214:215]
	v_lshlrev_b64 v[214:215], 12, v[160:161]
	v_cvt_pk_bf16_f32 v178, v178, v179
	v_cvt_pk_bf16_f32 v179, v176, v177
	global_store_dwordx2 v[150:151], v[178:179], off offset:288 sc1
	v_lshl_add_u64 v[150:151], v[148:149], 0, v[214:215]
	global_load_dwordx4 v[176:179], v[150:151], off
	global_load_dwordx4 v[188:191], v[150:151], off offset:64
	global_load_dwordx4 v[192:195], v[150:151], off offset:512
	global_load_dwordx4 v[196:199], v[150:151], off offset:576
	v_add_u32_e32 v150, 0xb0, v158
	v_ashrrev_i32_e32 v151, 31, v150
	v_lshlrev_b64 v[216:217], 12, v[150:151]
	v_lshl_add_u64 v[148:149], v[148:149], 0, v[216:217]
	global_load_dwordx4 v[200:203], v[148:149], off
	global_load_dwordx4 v[204:207], v[148:149], off offset:64
	global_load_dwordx4 v[208:211], v[148:149], off offset:512
	s_nop 0
	global_load_dwordx4 v[148:151], v[148:149], off offset:576
	v_lshl_add_u64 v[214:215], s[28:29], 0, v[214:215]
	s_waitcnt vmcnt(7)
	v_pk_fma_f32 v[178:179], v[34:35], v[114:115], v[178:179]
	v_pk_fma_f32 v[176:177], v[32:33], v[112:113], v[176:177]
	s_waitcnt vmcnt(6)
	v_pk_fma_f32 v[188:189], v[28:29], v[96:97], v[188:189]
	v_cvt_pk_bf16_f32 v176, v176, v177
	v_cvt_pk_bf16_f32 v177, v178, v179
	v_lshl_add_u64 v[178:179], v[214:215], 0, v[174:175]
	global_store_dwordx2 v[178:179], v[176:177], off sc1
	v_pk_fma_f32 v[176:177], v[30:31], v[98:99], v[190:191]
	v_cvt_pk_bf16_f32 v188, v188, v189
	v_cvt_pk_bf16_f32 v189, v176, v177
	global_store_dwordx2 v[178:179], v[188:189], off offset:32 sc1
	s_waitcnt vmcnt(7)
	v_pk_fma_f32 v[176:177], v[26:27], v[86:87], v[194:195]
	v_pk_fma_f32 v[188:189], v[24:25], v[84:85], v[192:193]
	s_waitcnt vmcnt(2)
	v_pk_fma_f32 v[150:151], v[6:7], v[78:79], v[150:151]
	v_cvt_pk_bf16_f32 v188, v188, v189
	v_cvt_pk_bf16_f32 v189, v176, v177
	global_store_dwordx2 v[178:179], v[188:189], off offset:256 sc1
	v_pk_fma_f32 v[176:177], v[22:23], v[78:79], v[198:199]
	v_pk_fma_f32 v[188:189], v[20:21], v[76:77], v[196:197]
	v_pk_fma_f32 v[148:149], v[4:5], v[76:77], v[148:149]
	v_cvt_pk_bf16_f32 v188, v188, v189
	v_cvt_pk_bf16_f32 v189, v176, v177
	global_store_dwordx2 v[178:179], v[188:189], off offset:288 sc1
	v_lshl_add_u64 v[176:177], s[28:29], 0, v[216:217]
	v_pk_fma_f32 v[178:179], v[18:19], v[114:115], v[202:203]
	v_pk_fma_f32 v[188:189], v[16:17], v[112:113], v[200:201]
	v_lshl_add_u64 v[174:175], v[176:177], 0, v[174:175]
	v_cvt_pk_bf16_f32 v188, v188, v189
	v_cvt_pk_bf16_f32 v189, v178, v179
	v_pk_fma_f32 v[176:177], v[14:15], v[98:99], v[206:207]
	v_pk_fma_f32 v[178:179], v[12:13], v[96:97], v[204:205]
	v_cvt_pk_bf16_f32 v148, v148, v149
	v_cvt_pk_bf16_f32 v178, v178, v179
	v_cvt_pk_bf16_f32 v179, v176, v177
	global_store_dwordx2 v[174:175], v[178:179], off offset:32 sc1
	v_pk_fma_f32 v[176:177], v[10:11], v[86:87], v[210:211]
	v_pk_fma_f32 v[178:179], v[8:9], v[84:85], v[208:209]
	v_cvt_pk_bf16_f32 v149, v150, v151
	v_cvt_pk_bf16_f32 v178, v178, v179
	v_cvt_pk_bf16_f32 v179, v176, v177
	global_store_dwordx2 v[174:175], v[188:189], off sc1
	global_store_dwordx2 v[174:175], v[178:179], off offset:256 sc1
	global_store_dwordx2 v[174:175], v[148:149], off offset:288 sc1

.LBB0_88:
	s_andn2_b64 vcc, exec, s[4:5]
	s_cbranch_vccnz .LBB0_90
	s_ashr_i32 s27, s26, 31
	s_lshl_b64 s[0:1], s[26:27], 20
	s_add_u32 s26, s58, s0
	s_addc_u32 s27, s59, s1
	v_lshlrev_b64 v[148:149], 2, v[170:171]
	v_lshl_add_u64 v[150:151], s[26:27], 0, v[148:149]
	v_lshlrev_b64 v[178:179], 12, v[158:159]
	v_lshl_add_u64 v[170:171], v[150:151], 0, v[178:179]
	v_ashrrev_i32_e32 v173, 31, v172
	global_load_dwordx4 v[174:177], v[170:171], off
	global_load_dwordx4 v[188:191], v[170:171], off offset:64
	global_load_dwordx4 v[192:195], v[170:171], off offset:512
	global_load_dwordx4 v[196:199], v[170:171], off offset:576
	v_lshlrev_b64 v[214:215], 12, v[172:173]
	v_lshl_add_u64 v[208:209], v[150:151], 0, v[214:215]
	global_load_dwordx4 v[170:173], v[208:209], off
	global_load_dwordx4 v[200:203], v[208:209], off offset:64
	global_load_dwordx4 v[204:207], v[208:209], off offset:512
	s_nop 0
	global_load_dwordx4 v[208:211], v[208:209], off offset:576
	v_lshl_add_u64 v[178:179], s[26:27], 0, v[178:179]
	v_ashrrev_i32_e32 v169, 31, v168
	v_lshlrev_b64 v[168:169], 12, v[168:169]
	v_ashrrev_i32_e32 v167, 31, v166
	v_lshlrev_b64 v[166:167], 12, v[166:167]
	v_ashrrev_i32_e32 v165, 31, v164
	v_ashrrev_i32_e32 v163, 31, v162
	v_ashrrev_i32_e32 v161, 31, v160
	s_waitcnt vmcnt(0)
	v_pk_fma_f32 v[144:145], v[144:145], v[112:113], v[174:175]
	v_lshl_add_u64 v[174:175], v[178:179], 0, v[148:149]
	v_pk_fma_f32 v[130:131], v[130:131], v[86:87], v[194:195]
	v_pk_fma_f32 v[128:129], v[128:129], v[84:85], v[192:193]
	global_store_dwordx4 v[174:175], v[128:131], off offset:512 sc1
	v_pk_fma_f32 v[126:127], v[126:127], v[78:79], v[198:199]
	v_pk_fma_f32 v[124:125], v[124:125], v[76:77], v[196:197]
	v_lshl_add_u64 v[128:129], s[26:27], 0, v[214:215]
	global_store_dwordx4 v[174:175], v[124:127], off offset:576 sc1
	v_lshl_add_u64 v[128:129], v[128:129], 0, v[148:149]
	v_pk_fma_f32 v[146:147], v[146:147], v[114:115], v[176:177]
	v_pk_fma_f32 v[126:127], v[138:139], v[114:115], v[172:173]
	v_pk_fma_f32 v[124:125], v[136:137], v[112:113], v[170:171]
	v_pk_fma_f32 v[142:143], v[142:143], v[98:99], v[190:191]
	v_pk_fma_f32 v[140:141], v[140:141], v[96:97], v[188:189]
	global_store_dwordx4 v[128:129], v[124:127], off sc1
	v_pk_fma_f32 v[122:123], v[122:123], v[86:87], v[206:207]
	v_pk_fma_f32 v[120:121], v[120:121], v[84:85], v[204:205]
	v_pk_fma_f32 v[126:127], v[134:135], v[98:99], v[202:203]
	v_pk_fma_f32 v[124:125], v[132:133], v[96:97], v[200:201]
	v_pk_fma_f32 v[118:119], v[118:119], v[78:79], v[210:211]
	v_pk_fma_f32 v[116:117], v[116:117], v[76:77], v[208:209]
	global_store_dwordx4 v[174:175], v[144:147], off sc1
	global_store_dwordx4 v[174:175], v[140:143], off offset:64 sc1
	global_store_dwordx4 v[128:129], v[124:127], off offset:64 sc1
	global_store_dwordx4 v[128:129], v[120:123], off offset:512 sc1
	global_store_dwordx4 v[128:129], v[116:119], off offset:576 sc1
	v_lshl_add_u64 v[128:129], v[150:151], 0, v[168:169]
	global_load_dwordx4 v[116:119], v[128:129], off
	global_load_dwordx4 v[120:123], v[128:129], off offset:64
	global_load_dwordx4 v[124:127], v[128:129], off offset:512
	s_nop 0
	global_load_dwordx4 v[128:131], v[128:129], off offset:576
	v_lshl_add_u64 v[144:145], v[150:151], 0, v[166:167]
	global_load_dwordx4 v[132:135], v[144:145], off
	global_load_dwordx4 v[136:139], v[144:145], off offset:64
	global_load_dwordx4 v[140:143], v[144:145], off offset:512
	s_nop 0
	global_load_dwordx4 v[144:147], v[144:145], off offset:576
	v_lshl_add_u64 v[168:169], s[26:27], 0, v[168:169]
	s_waitcnt vmcnt(7)
	v_pk_fma_f32 v[108:109], v[108:109], v[112:113], v[116:117]
	v_lshl_add_u64 v[116:117], v[168:169], 0, v[148:149]
	s_waitcnt vmcnt(5)
	v_pk_fma_f32 v[90:91], v[90:91], v[86:87], v[126:127]
	v_pk_fma_f32 v[88:89], v[88:89], v[84:85], v[124:125]
	global_store_dwordx4 v[116:117], v[88:91], off offset:512 sc1
	s_waitcnt vmcnt(5)
	v_pk_fma_f32 v[82:83], v[82:83], v[78:79], v[130:131]
	v_pk_fma_f32 v[80:81], v[80:81], v[76:77], v[128:129]
	v_lshl_add_u64 v[88:89], s[26:27], 0, v[166:167]
	global_store_dwordx4 v[116:117], v[80:83], off offset:576 sc1
	v_lshl_add_u64 v[88:89], v[88:89], 0, v[148:149]
	v_pk_fma_f32 v[110:111], v[110:111], v[114:115], v[118:119]
	s_waitcnt vmcnt(5)
	v_pk_fma_f32 v[82:83], v[102:103], v[114:115], v[134:135]
	v_pk_fma_f32 v[80:81], v[100:101], v[112:113], v[132:133]
	v_pk_fma_f32 v[106:107], v[106:107], v[98:99], v[122:123]
	v_pk_fma_f32 v[104:105], v[104:105], v[96:97], v[120:121]
	global_store_dwordx4 v[88:89], v[80:83], off sc1
	s_waitcnt vmcnt(4)
	v_pk_fma_f32 v[74:75], v[74:75], v[86:87], v[142:143]
	v_pk_fma_f32 v[72:73], v[72:73], v[84:85], v[140:141]
	v_pk_fma_f32 v[82:83], v[94:95], v[98:99], v[138:139]
	v_pk_fma_f32 v[80:81], v[92:93], v[96:97], v[136:137]
	s_waitcnt vmcnt(3)
	v_pk_fma_f32 v[70:71], v[70:71], v[78:79], v[146:147]
	v_pk_fma_f32 v[68:69], v[68:69], v[76:77], v[144:145]
	global_store_dwordx4 v[116:117], v[108:111], off sc1
	global_store_dwordx4 v[116:117], v[104:107], off offset:64 sc1
	global_store_dwordx4 v[88:89], v[80:83], off offset:64 sc1
	global_store_dwordx4 v[88:89], v[72:75], off offset:512 sc1
	global_store_dwordx4 v[88:89], v[68:71], off offset:576 sc1
	v_lshlrev_b64 v[116:117], 12, v[164:165]
	v_lshl_add_u64 v[88:89], v[150:151], 0, v[116:117]
	global_load_dwordx4 v[68:71], v[88:89], off
	global_load_dwordx4 v[72:75], v[88:89], off offset:64
	global_load_dwordx4 v[80:83], v[88:89], off offset:512
	s_nop 0
	global_load_dwordx4 v[88:91], v[88:89], off offset:576
	v_lshlrev_b64 v[118:119], 12, v[162:163]
	v_lshl_add_u64 v[108:109], v[150:151], 0, v[118:119]
	global_load_dwordx4 v[92:95], v[108:109], off
	global_load_dwordx4 v[100:103], v[108:109], off offset:64
	global_load_dwordx4 v[104:107], v[108:109], off offset:512
	s_nop 0
	global_load_dwordx4 v[108:111], v[108:109], off offset:576
	v_lshl_add_u64 v[116:117], s[26:27], 0, v[116:117]
	s_waitcnt vmcnt(7)
	v_pk_fma_f32 v[64:65], v[64:65], v[112:113], v[68:69]
	v_lshl_add_u64 v[68:69], v[116:117], 0, v[148:149]
	s_waitcnt vmcnt(5)
	v_pk_fma_f32 v[50:51], v[50:51], v[86:87], v[82:83]
	v_pk_fma_f32 v[48:49], v[48:49], v[84:85], v[80:81]
	global_store_dwordx4 v[68:69], v[48:51], off offset:512 sc1
	s_waitcnt vmcnt(5)
	v_pk_fma_f32 v[46:47], v[46:47], v[78:79], v[90:91]
	v_pk_fma_f32 v[44:45], v[44:45], v[76:77], v[88:89]
	v_lshl_add_u64 v[48:49], s[26:27], 0, v[118:119]
	global_store_dwordx4 v[68:69], v[44:47], off offset:576 sc1
	v_lshl_add_u64 v[48:49], v[48:49], 0, v[148:149]
	v_pk_fma_f32 v[66:67], v[66:67], v[114:115], v[70:71]
	s_waitcnt vmcnt(5)
	v_pk_fma_f32 v[46:47], v[58:59], v[114:115], v[94:95]
	v_pk_fma_f32 v[44:45], v[56:57], v[112:113], v[92:93]
	v_pk_fma_f32 v[62:63], v[62:63], v[98:99], v[74:75]
	v_pk_fma_f32 v[60:61], v[60:61], v[96:97], v[72:73]
	global_store_dwordx4 v[48:49], v[44:47], off sc1
	s_waitcnt vmcnt(4)
	v_pk_fma_f32 v[42:43], v[42:43], v[86:87], v[106:107]
	v_pk_fma_f32 v[40:41], v[40:41], v[84:85], v[104:105]
	v_pk_fma_f32 v[46:47], v[54:55], v[98:99], v[102:103]
	v_pk_fma_f32 v[44:45], v[52:53], v[96:97], v[100:101]
	s_waitcnt vmcnt(3)
	v_pk_fma_f32 v[38:39], v[38:39], v[78:79], v[110:111]
	v_pk_fma_f32 v[36:37], v[36:37], v[76:77], v[108:109]
	global_store_dwordx4 v[68:69], v[64:67], off sc1
	global_store_dwordx4 v[68:69], v[60:63], off offset:64 sc1
	global_store_dwordx4 v[48:49], v[44:47], off offset:64 sc1
	global_store_dwordx4 v[48:49], v[40:43], off offset:512 sc1
	global_store_dwordx4 v[48:49], v[36:39], off offset:576 sc1
	v_lshlrev_b64 v[68:69], 12, v[160:161]
	v_add_u32_e32 v52, 0xb0, v158
	v_lshl_add_u64 v[48:49], v[150:151], 0, v[68:69]
	v_ashrrev_i32_e32 v53, 31, v52
	global_load_dwordx4 v[36:39], v[48:49], off
	global_load_dwordx4 v[40:43], v[48:49], off offset:64
	global_load_dwordx4 v[44:47], v[48:49], off offset:512
	s_nop 0
	global_load_dwordx4 v[48:51], v[48:49], off offset:576
	v_lshlrev_b64 v[70:71], 12, v[52:53]
	v_lshl_add_u64 v[64:65], v[150:151], 0, v[70:71]
	global_load_dwordx4 v[52:55], v[64:65], off
	global_load_dwordx4 v[56:59], v[64:65], off offset:64
	global_load_dwordx4 v[60:63], v[64:65], off offset:512
	s_nop 0
	global_load_dwordx4 v[64:67], v[64:65], off offset:576
	v_lshl_add_u64 v[68:69], s[26:27], 0, v[68:69]
	s_waitcnt vmcnt(7)
	v_pk_fma_f32 v[32:33], v[32:33], v[112:113], v[36:37]
	v_lshl_add_u64 v[36:37], v[68:69], 0, v[148:149]
	v_pk_fma_f32 v[34:35], v[34:35], v[114:115], v[38:39]
	s_waitcnt vmcnt(4)
	v_pk_fma_f32 v[22:23], v[22:23], v[78:79], v[50:51]
	v_pk_fma_f32 v[20:21], v[20:21], v[76:77], v[48:49]
	global_store_dwordx4 v[36:37], v[20:23], off offset:576 sc1
	v_pk_fma_f32 v[30:31], v[30:31], v[98:99], v[42:43]
	v_pk_fma_f32 v[28:29], v[28:29], v[96:97], v[40:41]
	v_lshl_add_u64 v[20:21], s[26:27], 0, v[70:71]
	v_pk_fma_f32 v[26:27], v[26:27], v[86:87], v[46:47]
	v_pk_fma_f32 v[24:25], v[24:25], v[84:85], v[44:45]
	s_waitcnt vmcnt(4)
	v_pk_fma_f32 v[18:19], v[18:19], v[114:115], v[54:55]
	v_pk_fma_f32 v[16:17], v[16:17], v[112:113], v[52:53]
	v_lshl_add_u64 v[20:21], v[20:21], 0, v[148:149]
	s_waitcnt vmcnt(3)
	v_pk_fma_f32 v[14:15], v[14:15], v[98:99], v[58:59]
	v_pk_fma_f32 v[12:13], v[12:13], v[96:97], v[56:57]
	s_waitcnt vmcnt(2)
	v_pk_fma_f32 v[10:11], v[10:11], v[86:87], v[62:63]
	v_pk_fma_f32 v[8:9], v[8:9], v[84:85], v[60:61]
	s_waitcnt vmcnt(1)
	v_pk_fma_f32 v[6:7], v[6:7], v[78:79], v[66:67]
	v_pk_fma_f32 v[4:5], v[4:5], v[76:77], v[64:65]
	global_store_dwordx4 v[36:37], v[32:35], off sc1
	global_store_dwordx4 v[36:37], v[28:31], off offset:64 sc1
	global_store_dwordx4 v[36:37], v[24:27], off offset:512 sc1
	global_store_dwordx4 v[20:21], v[16:19], off sc1
	global_store_dwordx4 v[20:21], v[12:15], off offset:64 sc1
	global_store_dwordx4 v[20:21], v[8:11], off offset:512 sc1
	global_store_dwordx4 v[20:21], v[4:7], off offset:576 sc1

.LBB0_108:
	v_mov_b32_e32 v142, v144
	v_mov_b32_e32 v143, v145
	s_lshl_b32 s4, s22, 8
	s_add_i32 s4, s4, s40
	v_add_u32_e32 v142, s4, v142
	s_lshl_b32 s4, s47, 8
	s_or_b32 s4, s4, s41
	v_lshl_add_u32 v148, v143, 3, s4
	v_ashrrev_i32_e32 v143, 31, v142
	v_lshlrev_b64 v[142:143], 13, v[142:143]
	v_max_f32_e32 v124, v124, v124
	v_max_f32_e32 v125, v125, v125
	v_ashrrev_i32_e32 v149, 31, v148
	v_lshl_add_u64 v[142:143], s[10:11], 0, v[142:143]
	v_max_f32_e32 v124, 0, v124
	v_max_f32_e32 v125, 0, v125
	v_lshl_add_u64 v[142:143], v[148:149], 1, v[142:143]
	v_pk_mul_f32 v[148:149], v[124:125], v[124:125]
	v_max_f32_e32 v125, v126, v126
	v_max_f32_e32 v128, v128, v128
	v_max_f32_e32 v129, v129, v129
	v_max_f32_e32 v124, v130, v130
	v_max_f32_e32 v126, 0, v125
	v_max_f32_e32 v125, v131, v131
	v_max_f32_e32 v127, v127, v127
	v_max_f32_e32 v128, 0, v128
	v_max_f32_e32 v129, 0, v129
	v_max_f32_e32 v124, 0, v124
	v_max_f32_e32 v125, 0, v125
	v_max_f32_e32 v127, 0, v127
	v_pk_mul_f32 v[128:129], v[128:129], v[128:129]
	v_pk_mul_f32 v[130:131], v[124:125], v[124:125]
	v_pk_mul_f32 v[150:151], v[126:127], v[126:127]
	v_max_f32_e32 v116, v116, v116
	v_max_f32_e32 v117, v117, v117
	v_cvt_pk_bf16_f32 v124, v128, v129
	v_cvt_pk_bf16_f32 v125, v130, v131
	v_cvt_pk_bf16_f32 v126, v148, v149
	v_cvt_pk_bf16_f32 v127, v150, v151
	v_max_f32_e32 v116, 0, v116
	v_max_f32_e32 v117, 0, v117
	global_store_dwordx4 v[142:143], v[124:127], off sc1
	v_max_f32_e32 v120, v120, v120
	v_max_f32_e32 v121, v121, v121
	v_pk_mul_f32 v[124:125], v[116:117], v[116:117]
	v_max_f32_e32 v117, v118, v118
	v_max_f32_e32 v116, v122, v122
	v_max_f32_e32 v118, 0, v117
	v_max_f32_e32 v117, v123, v123
	v_max_f32_e32 v119, v119, v119
	v_max_f32_e32 v120, 0, v120
	v_max_f32_e32 v121, 0, v121
	v_max_f32_e32 v116, 0, v116
	v_max_f32_e32 v117, 0, v117
	v_max_f32_e32 v119, 0, v119
	v_pk_mul_f32 v[120:121], v[120:121], v[120:121]
	v_pk_mul_f32 v[122:123], v[116:117], v[116:117]
	v_pk_mul_f32 v[126:127], v[118:119], v[118:119]
	v_max_f32_e32 v108, v108, v108
	v_max_f32_e32 v109, v109, v109
	v_cvt_pk_bf16_f32 v116, v120, v121
	v_cvt_pk_bf16_f32 v117, v122, v123
	v_cvt_pk_bf16_f32 v118, v124, v125
	v_cvt_pk_bf16_f32 v119, v126, v127
	v_max_f32_e32 v108, 0, v108
	v_max_f32_e32 v109, 0, v109
	global_store_dwordx4 v[142:143], v[116:119], off offset:256 sc1
	v_max_f32_e32 v112, v112, v112
	v_max_f32_e32 v113, v113, v113
	v_pk_mul_f32 v[118:119], v[108:109], v[108:109]
	v_max_f32_e32 v109, v110, v110
	s_mov_b64 s[4:5], 0x20000
	v_max_f32_e32 v112, 0, v112
	v_max_f32_e32 v113, 0, v113
	v_max_f32_e32 v108, v114, v114
	v_max_f32_e32 v110, 0, v109
	v_max_f32_e32 v109, v115, v115
	v_max_f32_e32 v111, v111, v111
	v_lshl_add_u64 v[116:117], v[142:143], 0, s[4:5]
	v_pk_mul_f32 v[112:113], v[112:113], v[112:113]
	v_max_f32_e32 v108, 0, v108
	v_max_f32_e32 v109, 0, v109
	v_max_f32_e32 v111, 0, v111
	s_mov_b32 s4, 0x20000
	v_pk_mul_f32 v[114:115], v[108:109], v[108:109]
	v_pk_mul_f32 v[120:121], v[110:111], v[110:111]
	v_cvt_pk_bf16_f32 v108, v112, v113
	v_add_co_u32_e32 v112, vcc, s4, v142
	v_max_f32_e32 v100, v100, v100
	v_max_f32_e32 v101, v101, v101
	v_cvt_pk_bf16_f32 v109, v114, v115
	v_cvt_pk_bf16_f32 v110, v118, v119
	v_cvt_pk_bf16_f32 v111, v120, v121
	v_addc_co_u32_e32 v113, vcc, 0, v143, vcc
	v_max_f32_e32 v100, 0, v100
	v_max_f32_e32 v101, 0, v101
	global_store_dwordx4 v[112:113], v[108:111], off sc1
	v_max_f32_e32 v104, v104, v104
	v_max_f32_e32 v105, v105, v105
	v_pk_mul_f32 v[108:109], v[100:101], v[100:101]
	v_max_f32_e32 v101, v102, v102
	v_max_f32_e32 v100, v106, v106
	v_max_f32_e32 v102, 0, v101
	v_max_f32_e32 v101, v107, v107
	v_max_f32_e32 v103, v103, v103
	v_max_f32_e32 v104, 0, v104
	v_max_f32_e32 v105, 0, v105
	v_max_f32_e32 v100, 0, v100
	v_max_f32_e32 v101, 0, v101
	v_max_f32_e32 v103, 0, v103
	v_pk_mul_f32 v[104:105], v[104:105], v[104:105]
	v_pk_mul_f32 v[106:107], v[100:101], v[100:101]
	v_pk_mul_f32 v[110:111], v[102:103], v[102:103]
	v_max_f32_e32 v92, v92, v92
	v_max_f32_e32 v93, v93, v93
	v_cvt_pk_bf16_f32 v100, v104, v105
	v_cvt_pk_bf16_f32 v101, v106, v107
	v_cvt_pk_bf16_f32 v102, v108, v109
	v_cvt_pk_bf16_f32 v103, v110, v111
	v_max_f32_e32 v92, 0, v92
	v_max_f32_e32 v93, 0, v93
	global_store_dwordx4 v[116:117], v[100:103], off offset:256 sc1
	v_max_f32_e32 v96, v96, v96
	v_max_f32_e32 v97, v97, v97
	v_pk_mul_f32 v[102:103], v[92:93], v[92:93]
	v_max_f32_e32 v93, v94, v94
	s_mov_b64 s[4:5], 0x40000
	v_max_f32_e32 v96, 0, v96
	v_max_f32_e32 v97, 0, v97
	v_max_f32_e32 v92, v98, v98
	v_max_f32_e32 v94, 0, v93
	v_max_f32_e32 v93, v99, v99
	v_max_f32_e32 v95, v95, v95
	v_lshl_add_u64 v[100:101], v[142:143], 0, s[4:5]
	v_pk_mul_f32 v[96:97], v[96:97], v[96:97]
	v_max_f32_e32 v92, 0, v92
	v_max_f32_e32 v93, 0, v93
	v_max_f32_e32 v95, 0, v95
	s_mov_b32 s4, 0x40000
	v_pk_mul_f32 v[98:99], v[92:93], v[92:93]
	v_pk_mul_f32 v[104:105], v[94:95], v[94:95]
	v_cvt_pk_bf16_f32 v92, v96, v97
	v_add_co_u32_e32 v96, vcc, s4, v142
	v_max_f32_e32 v84, v84, v84
	v_max_f32_e32 v85, v85, v85
	v_cvt_pk_bf16_f32 v93, v98, v99
	v_cvt_pk_bf16_f32 v94, v102, v103
	v_cvt_pk_bf16_f32 v95, v104, v105
	v_addc_co_u32_e32 v97, vcc, 0, v143, vcc
	v_max_f32_e32 v84, 0, v84
	v_max_f32_e32 v85, 0, v85
	global_store_dwordx4 v[96:97], v[92:95], off sc1
	v_max_f32_e32 v88, v88, v88
	v_max_f32_e32 v89, v89, v89
	v_pk_mul_f32 v[92:93], v[84:85], v[84:85]
	v_max_f32_e32 v85, v86, v86
	v_max_f32_e32 v84, v90, v90
	v_max_f32_e32 v86, 0, v85
	v_max_f32_e32 v85, v91, v91
	v_max_f32_e32 v87, v87, v87
	v_max_f32_e32 v88, 0, v88
	v_max_f32_e32 v89, 0, v89
	v_max_f32_e32 v84, 0, v84
	v_max_f32_e32 v85, 0, v85
	v_max_f32_e32 v87, 0, v87
	v_pk_mul_f32 v[88:89], v[88:89], v[88:89]
	v_pk_mul_f32 v[90:91], v[84:85], v[84:85]
	v_pk_mul_f32 v[94:95], v[86:87], v[86:87]
	v_max_f32_e32 v76, v76, v76
	v_max_f32_e32 v77, v77, v77
	v_cvt_pk_bf16_f32 v84, v88, v89
	v_cvt_pk_bf16_f32 v85, v90, v91
	v_cvt_pk_bf16_f32 v86, v92, v93
	v_cvt_pk_bf16_f32 v87, v94, v95
	v_max_f32_e32 v76, 0, v76
	v_max_f32_e32 v77, 0, v77
	global_store_dwordx4 v[100:101], v[84:87], off offset:256 sc1
	v_max_f32_e32 v80, v80, v80
	v_max_f32_e32 v81, v81, v81
	v_pk_mul_f32 v[86:87], v[76:77], v[76:77]
	v_max_f32_e32 v77, v78, v78
	s_mov_b64 s[4:5], 0x60000
	v_max_f32_e32 v80, 0, v80
	v_max_f32_e32 v81, 0, v81
	v_max_f32_e32 v76, v82, v82
	v_max_f32_e32 v78, 0, v77
	v_max_f32_e32 v77, v83, v83
	v_max_f32_e32 v79, v79, v79
	v_lshl_add_u64 v[84:85], v[142:143], 0, s[4:5]
	v_pk_mul_f32 v[80:81], v[80:81], v[80:81]
	v_max_f32_e32 v76, 0, v76
	v_max_f32_e32 v77, 0, v77
	v_max_f32_e32 v79, 0, v79
	s_mov_b32 s4, 0x60000
	v_pk_mul_f32 v[82:83], v[76:77], v[76:77]
	v_pk_mul_f32 v[88:89], v[78:79], v[78:79]
	v_cvt_pk_bf16_f32 v76, v80, v81
	v_add_co_u32_e32 v80, vcc, s4, v142
	v_max_f32_e32 v68, v68, v68
	v_max_f32_e32 v69, v69, v69
	v_cvt_pk_bf16_f32 v77, v82, v83
	v_cvt_pk_bf16_f32 v78, v86, v87
	v_cvt_pk_bf16_f32 v79, v88, v89
	v_addc_co_u32_e32 v81, vcc, 0, v143, vcc
	v_max_f32_e32 v68, 0, v68
	v_max_f32_e32 v69, 0, v69
	global_store_dwordx4 v[80:81], v[76:79], off sc1
	v_max_f32_e32 v72, v72, v72
	v_max_f32_e32 v73, v73, v73
	v_pk_mul_f32 v[76:77], v[68:69], v[68:69]
	v_max_f32_e32 v69, v70, v70
	v_max_f32_e32 v68, v74, v74
	v_max_f32_e32 v70, 0, v69
	v_max_f32_e32 v69, v75, v75
	v_max_f32_e32 v71, v71, v71
	v_max_f32_e32 v72, 0, v72
	v_max_f32_e32 v73, 0, v73
	v_max_f32_e32 v68, 0, v68
	v_max_f32_e32 v69, 0, v69
	v_max_f32_e32 v71, 0, v71
	v_pk_mul_f32 v[72:73], v[72:73], v[72:73]
	v_pk_mul_f32 v[74:75], v[68:69], v[68:69]
	v_pk_mul_f32 v[78:79], v[70:71], v[70:71]
	v_max_f32_e32 v60, v60, v60
	v_max_f32_e32 v61, v61, v61
	v_cvt_pk_bf16_f32 v68, v72, v73
	v_cvt_pk_bf16_f32 v69, v74, v75
	v_cvt_pk_bf16_f32 v70, v76, v77
	v_cvt_pk_bf16_f32 v71, v78, v79
	v_max_f32_e32 v60, 0, v60
	v_max_f32_e32 v61, 0, v61
	global_store_dwordx4 v[84:85], v[68:71], off offset:256 sc1
	v_max_f32_e32 v64, v64, v64
	v_max_f32_e32 v65, v65, v65
	v_pk_mul_f32 v[70:71], v[60:61], v[60:61]
	v_max_f32_e32 v61, v62, v62
	s_mov_b64 s[4:5], 0x100000
	v_max_f32_e32 v64, 0, v64
	v_max_f32_e32 v65, 0, v65
	v_max_f32_e32 v60, v66, v66
	v_max_f32_e32 v62, 0, v61
	v_max_f32_e32 v61, v67, v67
	v_max_f32_e32 v63, v63, v63
	v_lshl_add_u64 v[68:69], v[142:143], 0, s[4:5]
	v_pk_mul_f32 v[64:65], v[64:65], v[64:65]
	v_max_f32_e32 v60, 0, v60
	v_max_f32_e32 v61, 0, v61
	v_max_f32_e32 v63, 0, v63
	s_mov_b32 s4, 0x100000
	v_pk_mul_f32 v[66:67], v[60:61], v[60:61]
	v_pk_mul_f32 v[72:73], v[62:63], v[62:63]
	v_cvt_pk_bf16_f32 v60, v64, v65
	v_add_co_u32_e32 v64, vcc, s4, v142
	v_max_f32_e32 v52, v52, v52
	v_max_f32_e32 v53, v53, v53
	v_cvt_pk_bf16_f32 v61, v66, v67
	v_cvt_pk_bf16_f32 v62, v70, v71
	v_cvt_pk_bf16_f32 v63, v72, v73
	v_addc_co_u32_e32 v65, vcc, 0, v143, vcc
	v_max_f32_e32 v52, 0, v52
	v_max_f32_e32 v53, 0, v53
	global_store_dwordx4 v[64:65], v[60:63], off sc1
	v_max_f32_e32 v56, v56, v56
	v_max_f32_e32 v57, v57, v57
	v_pk_mul_f32 v[60:61], v[52:53], v[52:53]
	v_max_f32_e32 v53, v54, v54
	v_max_f32_e32 v52, v58, v58
	v_max_f32_e32 v54, 0, v53
	v_max_f32_e32 v53, v59, v59
	v_max_f32_e32 v55, v55, v55
	v_max_f32_e32 v56, 0, v56
	v_max_f32_e32 v57, 0, v57
	v_max_f32_e32 v52, 0, v52
	v_max_f32_e32 v53, 0, v53
	v_max_f32_e32 v55, 0, v55
	v_pk_mul_f32 v[56:57], v[56:57], v[56:57]
	v_pk_mul_f32 v[58:59], v[52:53], v[52:53]
	v_pk_mul_f32 v[62:63], v[54:55], v[54:55]
	v_max_f32_e32 v44, v44, v44
	v_max_f32_e32 v45, v45, v45
	v_cvt_pk_bf16_f32 v52, v56, v57
	v_cvt_pk_bf16_f32 v53, v58, v59
	v_cvt_pk_bf16_f32 v54, v60, v61
	v_cvt_pk_bf16_f32 v55, v62, v63
	v_max_f32_e32 v44, 0, v44
	v_max_f32_e32 v45, 0, v45
	global_store_dwordx4 v[68:69], v[52:55], off offset:256 sc1
	v_max_f32_e32 v48, v48, v48
	v_max_f32_e32 v49, v49, v49
	v_pk_mul_f32 v[54:55], v[44:45], v[44:45]
	v_max_f32_e32 v45, v46, v46
	s_mov_b64 s[4:5], 0x120000
	v_max_f32_e32 v48, 0, v48
	v_max_f32_e32 v49, 0, v49
	v_max_f32_e32 v44, v50, v50
	v_max_f32_e32 v46, 0, v45
	v_max_f32_e32 v45, v51, v51
	v_max_f32_e32 v47, v47, v47
	v_lshl_add_u64 v[52:53], v[142:143], 0, s[4:5]
	v_pk_mul_f32 v[48:49], v[48:49], v[48:49]
	v_max_f32_e32 v44, 0, v44
	v_max_f32_e32 v45, 0, v45
	v_max_f32_e32 v47, 0, v47
	s_mov_b32 s4, 0x120000
	v_pk_mul_f32 v[50:51], v[44:45], v[44:45]
	v_pk_mul_f32 v[56:57], v[46:47], v[46:47]
	v_cvt_pk_bf16_f32 v44, v48, v49
	v_add_co_u32_e32 v48, vcc, s4, v142
	v_max_f32_e32 v36, v36, v36
	v_max_f32_e32 v37, v37, v37
	v_cvt_pk_bf16_f32 v45, v50, v51
	v_cvt_pk_bf16_f32 v46, v54, v55
	v_cvt_pk_bf16_f32 v47, v56, v57
	v_addc_co_u32_e32 v49, vcc, 0, v143, vcc
	v_max_f32_e32 v36, 0, v36
	v_max_f32_e32 v37, 0, v37
	global_store_dwordx4 v[48:49], v[44:47], off sc1
	v_max_f32_e32 v40, v40, v40
	v_max_f32_e32 v41, v41, v41
	v_pk_mul_f32 v[44:45], v[36:37], v[36:37]
	v_max_f32_e32 v37, v38, v38
	v_max_f32_e32 v36, v42, v42
	v_max_f32_e32 v38, 0, v37
	v_max_f32_e32 v37, v43, v43
	v_max_f32_e32 v39, v39, v39
	v_max_f32_e32 v40, 0, v40
	v_max_f32_e32 v41, 0, v41
	v_max_f32_e32 v36, 0, v36
	v_max_f32_e32 v37, 0, v37
	v_max_f32_e32 v39, 0, v39
	v_pk_mul_f32 v[40:41], v[40:41], v[40:41]
	v_pk_mul_f32 v[42:43], v[36:37], v[36:37]
	v_pk_mul_f32 v[46:47], v[38:39], v[38:39]
	v_max_f32_e32 v28, v28, v28
	v_max_f32_e32 v29, v29, v29
	v_cvt_pk_bf16_f32 v36, v40, v41
	v_cvt_pk_bf16_f32 v37, v42, v43
	v_cvt_pk_bf16_f32 v38, v44, v45
	v_cvt_pk_bf16_f32 v39, v46, v47
	v_max_f32_e32 v28, 0, v28
	v_max_f32_e32 v29, 0, v29
	global_store_dwordx4 v[52:53], v[36:39], off offset:256 sc1
	v_max_f32_e32 v32, v32, v32
	v_max_f32_e32 v33, v33, v33
	v_pk_mul_f32 v[38:39], v[28:29], v[28:29]
	v_max_f32_e32 v29, v30, v30
	s_mov_b64 s[4:5], 0x140000
	v_max_f32_e32 v32, 0, v32
	v_max_f32_e32 v33, 0, v33
	v_max_f32_e32 v28, v34, v34
	v_max_f32_e32 v30, 0, v29
	v_max_f32_e32 v29, v35, v35
	v_max_f32_e32 v31, v31, v31
	v_lshl_add_u64 v[36:37], v[142:143], 0, s[4:5]
	v_pk_mul_f32 v[32:33], v[32:33], v[32:33]
	v_max_f32_e32 v28, 0, v28
	v_max_f32_e32 v29, 0, v29
	v_max_f32_e32 v31, 0, v31
	s_mov_b32 s4, 0x140000
	v_pk_mul_f32 v[34:35], v[28:29], v[28:29]
	v_pk_mul_f32 v[40:41], v[30:31], v[30:31]
	v_cvt_pk_bf16_f32 v28, v32, v33
	v_add_co_u32_e32 v32, vcc, s4, v142
	v_max_f32_e32 v20, v20, v20
	v_max_f32_e32 v21, v21, v21
	v_cvt_pk_bf16_f32 v29, v34, v35
	v_cvt_pk_bf16_f32 v30, v38, v39
	v_cvt_pk_bf16_f32 v31, v40, v41
	v_addc_co_u32_e32 v33, vcc, 0, v143, vcc
	v_max_f32_e32 v20, 0, v20
	v_max_f32_e32 v21, 0, v21
	global_store_dwordx4 v[32:33], v[28:31], off sc1
	v_max_f32_e32 v24, v24, v24
	v_max_f32_e32 v25, v25, v25
	v_pk_mul_f32 v[28:29], v[20:21], v[20:21]
	v_max_f32_e32 v21, v22, v22
	v_max_f32_e32 v20, v26, v26
	v_max_f32_e32 v22, 0, v21
	v_max_f32_e32 v21, v27, v27
	v_max_f32_e32 v23, v23, v23
	v_max_f32_e32 v24, 0, v24
	v_max_f32_e32 v25, 0, v25
	v_max_f32_e32 v20, 0, v20
	v_max_f32_e32 v21, 0, v21
	v_max_f32_e32 v23, 0, v23
	v_pk_mul_f32 v[24:25], v[24:25], v[24:25]
	v_pk_mul_f32 v[26:27], v[20:21], v[20:21]
	v_pk_mul_f32 v[30:31], v[22:23], v[22:23]
	v_max_f32_e32 v12, v12, v12
	v_max_f32_e32 v13, v13, v13
	v_cvt_pk_bf16_f32 v20, v24, v25
	v_cvt_pk_bf16_f32 v21, v26, v27
	v_cvt_pk_bf16_f32 v22, v28, v29
	v_cvt_pk_bf16_f32 v23, v30, v31
	v_max_f32_e32 v12, 0, v12
	v_max_f32_e32 v13, 0, v13
	global_store_dwordx4 v[36:37], v[20:23], off offset:256 sc1
	v_max_f32_e32 v16, v16, v16
	v_max_f32_e32 v17, v17, v17
	v_pk_mul_f32 v[22:23], v[12:13], v[12:13]
	v_max_f32_e32 v13, v14, v14
	s_mov_b64 s[4:5], 0x160000
	v_max_f32_e32 v16, 0, v16
	v_max_f32_e32 v17, 0, v17
	v_max_f32_e32 v12, v18, v18
	v_max_f32_e32 v14, 0, v13
	v_max_f32_e32 v13, v19, v19
	v_max_f32_e32 v15, v15, v15
	v_lshl_add_u64 v[20:21], v[142:143], 0, s[4:5]
	v_pk_mul_f32 v[16:17], v[16:17], v[16:17]
	v_max_f32_e32 v12, 0, v12
	v_max_f32_e32 v13, 0, v13
	v_max_f32_e32 v15, 0, v15
	s_mov_b32 s4, 0x160000
	v_pk_mul_f32 v[18:19], v[12:13], v[12:13]
	v_pk_mul_f32 v[24:25], v[14:15], v[14:15]
	v_cvt_pk_bf16_f32 v12, v16, v17
	v_add_co_u32_e32 v16, vcc, s4, v142
	v_max_f32_e32 v4, v4, v4
	v_max_f32_e32 v5, v5, v5
	v_cvt_pk_bf16_f32 v13, v18, v19
	v_cvt_pk_bf16_f32 v14, v22, v23
	v_cvt_pk_bf16_f32 v15, v24, v25
	v_addc_co_u32_e32 v17, vcc, 0, v143, vcc
	v_max_f32_e32 v4, 0, v4
	v_max_f32_e32 v5, 0, v5
	global_store_dwordx4 v[16:17], v[12:15], off sc1
	v_max_f32_e32 v8, v8, v8
	v_max_f32_e32 v9, v9, v9
	v_pk_mul_f32 v[12:13], v[4:5], v[4:5]
	v_max_f32_e32 v5, v6, v6
	v_max_f32_e32 v4, v10, v10
	v_max_f32_e32 v6, 0, v5
	v_max_f32_e32 v5, v11, v11
	v_max_f32_e32 v7, v7, v7
	v_max_f32_e32 v8, 0, v8
	v_max_f32_e32 v9, 0, v9
	v_max_f32_e32 v4, 0, v4
	v_max_f32_e32 v5, 0, v5
	v_max_f32_e32 v7, 0, v7
	v_pk_mul_f32 v[8:9], v[8:9], v[8:9]
	v_pk_mul_f32 v[10:11], v[4:5], v[4:5]
	v_pk_mul_f32 v[14:15], v[6:7], v[6:7]
	v_cvt_pk_bf16_f32 v4, v8, v9
	v_cvt_pk_bf16_f32 v5, v10, v11
	v_cvt_pk_bf16_f32 v6, v12, v13
	v_cvt_pk_bf16_f32 v7, v14, v15
	s_andn2_b64 vcc, exec, s[6:7]
	s_mov_b64 s[4:5], -1
	s_mov_b32 s54, 0xe10000
	s_movk_i32 s55, 0x1fff
	global_store_dwordx4 v[20:21], v[4:7], off offset:256 sc1
	s_cbranch_vccnz .LBB0_101
	s_andn2_b64 vcc, exec, s[8:9]
	s_cbranch_vccnz .LBB0_100
	s_barrier
	s_branch .LBB0_100

.LBB0_117:
	v_mul_hi_i32 v8, v5, s77
	v_lshrrev_b32_e32 v9, 31, v8
	v_ashrrev_i32_e32 v8, 5, v8
	v_add_u32_e32 v10, v8, v9
	v_mul_i32_i24_e32 v29, 0xc90, v10
	v_sub_u32_e32 v30, v5, v29
	v_mov_b64_e32 v[8:9], s[78:79]
	v_ashrrev_i32_e32 v11, 31, v10
	v_mad_i64_i32 v[8:9], s[0:1], v10, s65, v[8:9]
	v_cmp_lt_i32_e32 vcc, s87, v30
	s_and_saveexec_b64 s[0:1], vcc
	s_xor_b64 s[10:11], exec, s[0:1]
	s_cbranch_execz .LBB0_135
	v_cmp_lt_u32_e32 vcc, s76, v30
	s_and_saveexec_b64 s[0:1], vcc
	s_xor_b64 s[12:13], exec, s[0:1]
	s_cbranch_execz .LBB0_132
	s_movk_i32 s0, 0x47f
	v_cmp_lt_u32_e32 vcc, s0, v30
	s_and_saveexec_b64 s[0:1], vcc
	s_xor_b64 s[14:15], exec, s[0:1]
	s_cbranch_execz .LBB0_129
	s_movk_i32 s0, 0x87f
	v_cmp_lt_u32_e32 vcc, s0, v30
	s_and_saveexec_b64 s[0:1], vcc
	s_xor_b64 s[16:17], exec, s[0:1]
	s_cbranch_execz .LBB0_126
	s_movk_i32 s0, 0xc7f
	v_cmp_lt_u32_e32 vcc, s0, v30
	v_lshlrev_b32_e32 v30, 6, v29
	v_sub_u32_e32 v30, v26, v30
	s_and_saveexec_b64 s[0:1], vcc
	s_xor_b64 s[18:19], exec, s[0:1]
	s_cbranch_execz .LBB0_123
	s_load_dwordx2 s[0:1], s[80:81], 0xc0
	v_lshlrev_b64 v[10:11], 18, v[10:11]
	s_waitcnt lgkmcnt(0)
	v_lshl_add_u64 v[32:33], s[0:1], 0, v[10:11]
	v_lshlrev_b32_e32 v10, 4, v29
	v_sub_u32_e32 v10, v27, v10
	v_and_b32_e32 v11, 0xfc0, v10
	v_bitop3_b32 v11, v11, v7, s86 bitop3:0xde
	v_bitop3_b32 v29, v10, s86, v182 bitop3:0x6c
	v_and_b32_e32 v10, 0xc0, v30
	v_lshlrev_b32_e32 v180, 10, v11
	v_lshl_add_u64 v[30:31], v[32:33], 0, v[180:181]
	v_lshlrev_b32_e32 v180, 2, v10
	v_lshl_add_u64 v[30:31], v[30:31], 0, v[180:181]
	v_lshlrev_b32_e32 v180, 2, v4
	v_lshl_add_u64 v[90:91], v[30:31], 0, v[180:181]
	s_movk_i32 s0, 0x2000
	v_add_co_u32_e32 v38, vcc, s0, v90
	global_load_dwordx4 v[30:33], v[90:91], off
	s_nop 0
	v_addc_co_u32_e32 v39, vcc, 0, v91, vcc
	global_load_dwordx4 v[34:37], v[38:39], off offset:-4096
	s_nop 0
	global_load_dwordx4 v[38:41], v[38:39], off
	s_movk_i32 s0, 0x4000
	v_add_co_u32_e32 v46, vcc, s0, v90
	s_mov_b32 s0, 0xa000
	s_nop 0
	v_addc_co_u32_e32 v47, vcc, 0, v91, vcc
	global_load_dwordx4 v[42:45], v[46:47], off offset:-4096
	s_nop 0
	global_load_dwordx4 v[46:49], v[46:47], off
	v_add_co_u32_e32 v54, vcc, s46, v90
	v_add_u32_e32 v11, 0x410, v12
	s_nop 0
	v_addc_co_u32_e32 v55, vcc, 0, v91, vcc
	global_load_dwordx4 v[50:53], v[54:55], off offset:-4096
	s_nop 0
	global_load_dwordx4 v[54:57], v[54:55], off
	v_add_co_u32_e32 v62, vcc, s70, v90
	v_lshlrev_b32_e32 v180, 1, v29
	s_nop 0
	v_addc_co_u32_e32 v63, vcc, 0, v91, vcc
	global_load_dwordx4 v[58:61], v[62:63], off offset:-4096
	s_nop 0
	global_load_dwordx4 v[62:65], v[62:63], off
	v_add_co_u32_e32 v70, vcc, s0, v90
	s_mov_b32 s0, 0xc000
	s_nop 0
	v_addc_co_u32_e32 v71, vcc, 0, v91, vcc
	global_load_dwordx4 v[66:69], v[70:71], off offset:-4096
	s_nop 0
	global_load_dwordx4 v[70:73], v[70:71], off
	v_add_co_u32_e32 v78, vcc, s0, v90
	s_mov_b32 s0, 0xf000
	s_nop 0
	v_addc_co_u32_e32 v79, vcc, 0, v91, vcc
	global_load_dwordx4 v[74:77], v[78:79], off offset:-4096
	s_nop 0
	global_load_dwordx4 v[78:81], v[78:79], off
	v_add_co_u32_e32 v86, vcc, s73, v90
	v_lshl_add_u64 v[8:9], v[8:9], 0, v[180:181]
	s_nop 0
	v_addc_co_u32_e32 v87, vcc, 0, v91, vcc
	global_load_dwordx4 v[82:85], v[86:87], off offset:-4096
	s_nop 0
	global_load_dwordx4 v[86:89], v[86:87], off
	v_add_co_u32_e32 v90, vcc, s0, v90
	v_lshlrev_b32_e32 v180, 1, v6
	s_nop 0
	v_addc_co_u32_e32 v91, vcc, 0, v91, vcc
	global_load_dwordx4 v[90:93], v[90:91], off
	v_lshl_add_u64 v[8:9], v[8:9], 0, v[180:181]
	s_mov_b64 s[0:1], 0x1900000
	v_or_b32_e32 v29, v10, v13
	v_lshl_add_u64 v[8:9], v[8:9], 0, s[0:1]
	v_lshlrev_b32_e32 v180, 9, v29
	v_or_b32_e32 v29, v10, v15
	s_waitcnt vmcnt(15)
	ds_write2_b32 v12, v30, v31 offset1:1
	ds_write2_b32 v12, v32, v33 offset0:2 offset1:3
	s_waitcnt vmcnt(14)
	ds_write2_b32 v11, v34, v35 offset1:1
	v_add_u32_e32 v11, 0x418, v12
	ds_write2_b32 v11, v36, v37 offset1:1
	v_add_u32_e32 v11, 0x820, v12
	s_waitcnt vmcnt(13)
	ds_write2_b32 v11, v38, v39 offset1:1
	v_add_u32_e32 v11, 0x828, v12
	ds_write2_b32 v11, v40, v41 offset1:1
	v_add_u32_e32 v11, 0xc30, v12
	s_waitcnt vmcnt(12)
	ds_write2_b32 v11, v42, v43 offset1:1
	v_add_u32_e32 v11, 0xc38, v12
	ds_write2_b32 v11, v44, v45 offset1:1
	v_add_u32_e32 v11, 0x1040, v12
	s_waitcnt vmcnt(11)
	ds_write2_b32 v11, v46, v47 offset1:1
	v_add_u32_e32 v11, 0x1048, v12
	ds_write2_b32 v11, v48, v49 offset1:1
	v_add_u32_e32 v11, 0x1450, v12
	s_waitcnt vmcnt(10)
	ds_write2_b32 v11, v50, v51 offset1:1
	v_add_u32_e32 v11, 0x1458, v12
	ds_write2_b32 v11, v52, v53 offset1:1
	v_add_u32_e32 v11, 0x1860, v12
	s_waitcnt vmcnt(9)
	ds_write2_b32 v11, v54, v55 offset1:1
	v_add_u32_e32 v11, 0x1868, v12
	ds_write2_b32 v11, v56, v57 offset1:1
	v_add_u32_e32 v11, 0x1c70, v12
	s_waitcnt vmcnt(8)
	ds_write2_b32 v11, v58, v59 offset1:1
	v_add_u32_e32 v11, 0x1c78, v12
	ds_write2_b32 v11, v60, v61 offset1:1
	v_add_u32_e32 v11, 0x2080, v12
	s_waitcnt vmcnt(7)
	ds_write2_b32 v11, v62, v63 offset1:1
	v_add_u32_e32 v11, 0x2088, v12
	ds_write2_b32 v11, v64, v65 offset1:1
	v_add_u32_e32 v11, 0x2490, v12
	s_waitcnt vmcnt(6)
	ds_write2_b32 v11, v66, v67 offset1:1
	v_add_u32_e32 v11, 0x2498, v12
	ds_write2_b32 v11, v68, v69 offset1:1
	v_add_u32_e32 v11, 0x28a0, v12
	s_waitcnt vmcnt(5)
	ds_write2_b32 v11, v70, v71 offset1:1
	v_add_u32_e32 v11, 0x28a8, v12
	ds_write2_b32 v11, v72, v73 offset1:1
	v_add_u32_e32 v11, 0x2cb0, v12
	s_waitcnt vmcnt(4)
	ds_write2_b32 v11, v74, v75 offset1:1
	v_add_u32_e32 v11, 0x2cb8, v12
	ds_write2_b32 v11, v76, v77 offset1:1
	v_add_u32_e32 v11, 0x30c0, v12
	s_waitcnt vmcnt(3)
	ds_write2_b32 v11, v78, v79 offset1:1
	v_add_u32_e32 v11, 0x30c8, v12
	ds_write2_b32 v11, v80, v81 offset1:1
	v_add_u32_e32 v11, 0x34d0, v12
	s_waitcnt vmcnt(2)
	ds_write2_b32 v11, v82, v83 offset1:1
	v_add_u32_e32 v11, 0x34d8, v12
	ds_write2_b32 v11, v84, v85 offset1:1
	v_add_u32_e32 v11, 0x38e0, v12
	s_waitcnt vmcnt(1)
	ds_write2_b32 v11, v86, v87 offset1:1
	v_add_u32_e32 v11, 0x38e8, v12
	ds_write2_b32 v11, v88, v89 offset1:1
	v_add_u32_e32 v11, 0x3cf0, v12
	s_waitcnt vmcnt(0)
	ds_write2_b32 v11, v90, v91 offset1:1
	v_add_u32_e32 v11, 0x3cf8, v12
	ds_write2_b32 v11, v92, v93 offset1:1
	s_waitcnt lgkmcnt(0)
	v_add_u32_e32 v11, 0x400, v14
	ds_read2_b32 v[34:35], v14 offset0:65 offset1:73
	ds_read2_b32 v[36:37], v14 offset1:8
	ds_read2_b32 v[38:39], v14 offset0:130 offset1:138
	ds_read2_b32 v[40:41], v14 offset0:195 offset1:203
	ds_read2_b32 v[42:43], v11 offset0:4 offset1:12
	ds_read2_b32 v[44:45], v11 offset0:69 offset1:77
	ds_read2_b32 v[46:47], v11 offset0:134 offset1:142
	ds_read2_b32 v[48:49], v11 offset0:199 offset1:207
	v_lshl_add_u64 v[50:51], v[8:9], 0, v[180:181]
	s_waitcnt lgkmcnt(6)
	v_cvt_pk_bf16_f32 v30, v36, v34
	s_waitcnt lgkmcnt(4)
	v_cvt_pk_bf16_f32 v31, v38, v40
	s_waitcnt lgkmcnt(2)
	v_cvt_pk_bf16_f32 v32, v42, v44
	s_waitcnt lgkmcnt(0)
	v_cvt_pk_bf16_f32 v33, v46, v48
	v_lshlrev_b32_e32 v180, 9, v29
	global_store_dwordx4 v[50:51], v[30:33], off sc1
	v_or_b32_e32 v29, v10, v16
	s_nop 0
	v_cvt_pk_bf16_f32 v30, v37, v35
	v_cvt_pk_bf16_f32 v31, v39, v41
	v_cvt_pk_bf16_f32 v32, v43, v45
	v_cvt_pk_bf16_f32 v33, v47, v49
	v_lshl_add_u64 v[34:35], v[8:9], 0, v[180:181]
	global_store_dwordx4 v[34:35], v[30:33], off sc1
	ds_read2_b32 v[34:35], v14 offset0:81 offset1:89
	ds_read2_b32 v[36:37], v14 offset0:16 offset1:24
	ds_read2_b32 v[38:39], v14 offset0:146 offset1:154
	ds_read2_b32 v[40:41], v14 offset0:211 offset1:219
	ds_read2_b32 v[42:43], v11 offset0:20 offset1:28
	ds_read2_b32 v[44:45], v11 offset0:85 offset1:93
	ds_read2_b32 v[46:47], v11 offset0:150 offset1:158
	ds_read2_b32 v[48:49], v11 offset0:215 offset1:223
	v_lshlrev_b32_e32 v180, 9, v29
	v_or_b32_e32 v29, v10, v17
	s_waitcnt lgkmcnt(6)
	v_cvt_pk_bf16_f32 v30, v36, v34
	s_waitcnt lgkmcnt(4)
	v_cvt_pk_bf16_f32 v31, v38, v40
	s_waitcnt lgkmcnt(2)
	v_cvt_pk_bf16_f32 v32, v42, v44
	s_waitcnt lgkmcnt(0)
	v_cvt_pk_bf16_f32 v33, v46, v48
	v_lshl_add_u64 v[50:51], v[8:9], 0, v[180:181]
	v_lshlrev_b32_e32 v180, 9, v29
	global_store_dwordx4 v[50:51], v[30:33], off sc1
	v_or_b32_e32 v29, v10, v18
	s_nop 0
	v_cvt_pk_bf16_f32 v30, v37, v35
	v_cvt_pk_bf16_f32 v31, v39, v41
	v_cvt_pk_bf16_f32 v32, v43, v45
	v_cvt_pk_bf16_f32 v33, v47, v49
	v_lshl_add_u64 v[34:35], v[8:9], 0, v[180:181]
	global_store_dwordx4 v[34:35], v[30:33], off sc1
	ds_read2_b32 v[34:35], v14 offset0:32 offset1:40
	ds_read2_b32 v[36:37], v14 offset0:97 offset1:105
	ds_read2_b32 v[38:39], v14 offset0:162 offset1:170
	ds_read2_b32 v[40:41], v14 offset0:227 offset1:235
	ds_read2_b32 v[42:43], v11 offset0:36 offset1:44
	ds_read2_b32 v[44:45], v11 offset0:101 offset1:109
	ds_read2_b32 v[46:47], v11 offset0:166 offset1:174
	ds_read2_b32 v[48:49], v11 offset0:231 offset1:239
	v_lshlrev_b32_e32 v180, 9, v29
	v_or_b32_e32 v29, v10, v19
	s_waitcnt lgkmcnt(6)
	v_cvt_pk_bf16_f32 v30, v34, v36
	s_waitcnt lgkmcnt(4)
	v_cvt_pk_bf16_f32 v31, v38, v40
	s_waitcnt lgkmcnt(2)
	v_cvt_pk_bf16_f32 v32, v42, v44
	s_waitcnt lgkmcnt(0)
	v_cvt_pk_bf16_f32 v33, v46, v48
	v_lshl_add_u64 v[50:51], v[8:9], 0, v[180:181]
	v_lshlrev_b32_e32 v180, 9, v29
	global_store_dwordx4 v[50:51], v[30:33], off sc1
	s_nop 1
	v_cvt_pk_bf16_f32 v30, v35, v37
	v_cvt_pk_bf16_f32 v31, v39, v41
	v_cvt_pk_bf16_f32 v32, v43, v45
	v_cvt_pk_bf16_f32 v33, v47, v49
	v_lshl_add_u64 v[34:35], v[8:9], 0, v[180:181]
	global_store_dwordx4 v[34:35], v[30:33], off sc1
	ds_read2_b32 v[34:35], v14 offset0:48 offset1:56
	ds_read2_b32 v[36:37], v14 offset0:113 offset1:121
	ds_read2_b32 v[38:39], v14 offset0:178 offset1:186
	ds_read2_b32 v[40:41], v14 offset0:243 offset1:251
	ds_read2_b32 v[42:43], v11 offset0:52 offset1:60
	ds_read2_b32 v[44:45], v11 offset0:117 offset1:125
	ds_read2_b32 v[46:47], v11 offset0:182 offset1:190
	ds_read2_b32 v[48:49], v11 offset0:247 offset1:255
	v_or_b32_e32 v11, v10, v20
	v_lshlrev_b32_e32 v180, 9, v11
	v_or_b32_e32 v10, v10, v21
	s_waitcnt lgkmcnt(6)
	v_cvt_pk_bf16_f32 v30, v34, v36
	s_waitcnt lgkmcnt(4)
	v_cvt_pk_bf16_f32 v31, v38, v40
	s_waitcnt lgkmcnt(2)
	v_cvt_pk_bf16_f32 v32, v42, v44
	s_waitcnt lgkmcnt(0)
	v_cvt_pk_bf16_f32 v33, v46, v48
	v_lshl_add_u64 v[50:51], v[8:9], 0, v[180:181]
	v_lshlrev_b32_e32 v180, 9, v10
	global_store_dwordx4 v[50:51], v[30:33], off sc1
	v_lshl_add_u64 v[8:9], v[8:9], 0, v[180:181]
	s_nop 0
	v_cvt_pk_bf16_f32 v30, v35, v37
	v_cvt_pk_bf16_f32 v31, v39, v41
	v_cvt_pk_bf16_f32 v32, v43, v45
	v_cvt_pk_bf16_f32 v33, v47, v49
	global_store_dwordx4 v[8:9], v[30:33], off sc1
	s_waitcnt lgkmcnt(0)
.LBB0_123:
	s_andn2_saveexec_b64 s[18:19], s[18:19]
	s_cbranch_execz .LBB0_125
	s_load_dwordx2 s[0:1], s[80:81], 0xe0
	v_lshlrev_b32_e32 v29, 2, v29
	v_sub_u32_e32 v29, v28, v29
	v_add_u32_e32 v29, 0x3de00, v29
	v_and_b32_e32 v29, 0x3ffc0, v29
	v_lshlrev_b64 v[10:11], 24, v[10:11]
	v_and_b32_e32 v94, 0x3c0, v30
	v_or_b32_e32 v30, v29, v7
	s_waitcnt lgkmcnt(0)
	v_lshl_add_u64 v[10:11], s[0:1], 0, v[10:11]
	v_lshlrev_b32_e32 v180, 12, v30
	v_lshl_add_u64 v[10:11], v[10:11], 0, v[180:181]
	v_lshlrev_b32_e32 v180, 2, v94
	v_lshl_add_u64 v[10:11], v[10:11], 0, v[180:181]
	v_lshlrev_b32_e32 v180, 2, v4
	v_lshl_add_u64 v[10:11], v[10:11], 0, v[180:181]
	s_movk_i32 s0, 0x4000
	v_add_co_u32_e32 v34, vcc, s0, v10
	s_mov_b32 s0, 0xc000
	s_nop 0
	v_addc_co_u32_e32 v35, vcc, 0, v11, vcc
	v_add_co_u32_e32 v38, vcc, s70, v10
	global_load_dwordx4 v[30:33], v[10:11], off
	s_nop 0
	global_load_dwordx4 v[34:37], v[34:35], off
	v_addc_co_u32_e32 v39, vcc, 0, v11, vcc
	v_add_co_u32_e32 v42, vcc, s0, v10
	s_mov_b32 s0, 0x10000
	s_nop 0
	v_addc_co_u32_e32 v43, vcc, 0, v11, vcc
	global_load_dwordx4 v[38:41], v[38:39], off
	s_nop 0
	global_load_dwordx4 v[42:45], v[42:43], off
	v_add_co_u32_e32 v46, vcc, s0, v10
	s_mov_b32 s0, 0x14000
	s_nop 0
	v_addc_co_u32_e32 v47, vcc, 0, v11, vcc
	v_add_co_u32_e32 v50, vcc, s0, v10
	s_mov_b32 s0, 0x18000
	s_nop 0
	v_addc_co_u32_e32 v51, vcc, 0, v11, vcc
	global_load_dwordx4 v[46:49], v[46:47], off
	s_nop 0
	global_load_dwordx4 v[50:53], v[50:51], off
	v_add_co_u32_e32 v54, vcc, s0, v10
	s_mov_b32 s0, 0x20000
	s_nop 0
	v_addc_co_u32_e32 v55, vcc, 0, v11, vcc
	v_add_co_u32_e32 v58, vcc, s71, v10
	v_lshlrev_b32_e32 v180, 1, v29
	s_nop 0
	v_addc_co_u32_e32 v59, vcc, 0, v11, vcc
	global_load_dwordx4 v[54:57], v[54:55], off
	s_nop 0
	global_load_dwordx4 v[58:61], v[58:59], off
	v_add_co_u32_e32 v62, vcc, s0, v10
	s_mov_b32 s0, 0x24000
	s_nop 0
	v_addc_co_u32_e32 v63, vcc, 0, v11, vcc
	v_add_co_u32_e32 v66, vcc, s0, v10
	s_mov_b32 s0, 0x28000
	s_nop 0
	v_addc_co_u32_e32 v67, vcc, 0, v11, vcc
	global_load_dwordx4 v[62:65], v[62:63], off
	s_nop 0
	global_load_dwordx4 v[66:69], v[66:67], off
	v_add_co_u32_e32 v70, vcc, s0, v10
	s_mov_b32 s0, 0x2c000
	s_nop 0
	v_addc_co_u32_e32 v71, vcc, 0, v11, vcc
	v_add_co_u32_e32 v74, vcc, s0, v10
	s_mov_b32 s0, 0x30000
	s_nop 0
	v_addc_co_u32_e32 v75, vcc, 0, v11, vcc
	global_load_dwordx4 v[70:73], v[70:71], off
	s_nop 0
	global_load_dwordx4 v[74:77], v[74:75], off
	v_add_co_u32_e32 v78, vcc, s0, v10
	s_mov_b32 s0, 0x34000
	s_nop 0
	v_addc_co_u32_e32 v79, vcc, 0, v11, vcc
	global_load_dwordx4 v[78:81], v[78:79], off
	v_add_co_u32_e32 v82, vcc, s0, v10
	s_mov_b32 s0, 0x3c000
	s_nop 0
	v_addc_co_u32_e32 v83, vcc, 0, v11, vcc
	global_load_dwordx4 v[82:85], v[82:83], off
	v_add_co_u32_e32 v86, vcc, s85, v10
	v_add_u32_e32 v29, 0x400, v14
	s_nop 0
	v_addc_co_u32_e32 v87, vcc, 0, v11, vcc
	global_load_dwordx4 v[86:89], v[86:87], off
	v_add_co_u32_e32 v10, vcc, s0, v10
	v_lshl_add_u64 v[8:9], v[8:9], 0, v[180:181]
	s_nop 0
	v_addc_co_u32_e32 v11, vcc, 0, v11, vcc
	global_load_dwordx4 v[90:93], v[10:11], off
	v_add_u32_e32 v10, 0x410, v12
	s_waitcnt vmcnt(15)
	ds_write2_b32 v12, v30, v31 offset1:1
	ds_write2_b32 v12, v32, v33 offset0:2 offset1:3
	s_waitcnt vmcnt(14)
	ds_write2_b32 v10, v34, v35 offset1:1
	v_add_u32_e32 v10, 0x418, v12
	ds_write2_b32 v10, v36, v37 offset1:1
	v_add_u32_e32 v10, 0x820, v12
	v_lshlrev_b32_e32 v180, 1, v6
	v_lshl_add_u64 v[8:9], v[8:9], 0, v[180:181]
	s_mov_b64 s[0:1], 0x1100000
	s_waitcnt vmcnt(13)
	ds_write2_b32 v10, v38, v39 offset1:1
	v_add_u32_e32 v10, 0x828, v12
	ds_write2_b32 v10, v40, v41 offset1:1
	v_add_u32_e32 v10, 0xc30, v12
	s_waitcnt vmcnt(12)
	ds_write2_b32 v10, v42, v43 offset1:1
	v_add_u32_e32 v10, 0xc38, v12
	ds_write2_b32 v10, v44, v45 offset1:1
	v_add_u32_e32 v10, 0x1040, v12
	s_waitcnt vmcnt(11)
	ds_write2_b32 v10, v46, v47 offset1:1
	v_add_u32_e32 v10, 0x1048, v12
	ds_write2_b32 v10, v48, v49 offset1:1
	v_add_u32_e32 v10, 0x1450, v12
	s_waitcnt vmcnt(10)
	ds_write2_b32 v10, v50, v51 offset1:1
	v_add_u32_e32 v10, 0x1458, v12
	ds_write2_b32 v10, v52, v53 offset1:1
	v_add_u32_e32 v10, 0x1860, v12
	v_lshl_add_u64 v[46:47], v[8:9], 0, s[0:1]
	s_waitcnt vmcnt(9)
	ds_write2_b32 v10, v54, v55 offset1:1
	v_add_u32_e32 v10, 0x1868, v12
	ds_write2_b32 v10, v56, v57 offset1:1
	v_add_u32_e32 v10, 0x1c70, v12
	s_waitcnt vmcnt(8)
	ds_write2_b32 v10, v58, v59 offset1:1
	v_add_u32_e32 v10, 0x1c78, v12
	ds_write2_b32 v10, v60, v61 offset1:1
	v_add_u32_e32 v10, 0x2080, v12
	s_waitcnt vmcnt(7)
	ds_write2_b32 v10, v62, v63 offset1:1
	v_add_u32_e32 v10, 0x2088, v12
	ds_write2_b32 v10, v64, v65 offset1:1
	v_add_u32_e32 v10, 0x2490, v12
	s_waitcnt vmcnt(6)
	ds_write2_b32 v10, v66, v67 offset1:1
	v_add_u32_e32 v10, 0x2498, v12
	ds_write2_b32 v10, v68, v69 offset1:1
	v_add_u32_e32 v10, 0x28a0, v12
	s_waitcnt vmcnt(5)
	ds_write2_b32 v10, v70, v71 offset1:1
	v_add_u32_e32 v10, 0x28a8, v12
	ds_write2_b32 v10, v72, v73 offset1:1
	v_add_u32_e32 v10, 0x2cb0, v12
	s_waitcnt vmcnt(4)
	ds_write2_b32 v10, v74, v75 offset1:1
	v_add_u32_e32 v10, 0x2cb8, v12
	ds_write2_b32 v10, v76, v77 offset1:1
	v_add_u32_e32 v10, 0x30c0, v12
	s_waitcnt vmcnt(3)
	ds_write2_b32 v10, v78, v79 offset1:1
	v_add_u32_e32 v10, 0x30c8, v12
	ds_write2_b32 v10, v80, v81 offset1:1
	v_add_u32_e32 v10, 0x34d0, v12
	s_waitcnt vmcnt(2)
	ds_write2_b32 v10, v82, v83 offset1:1
	v_add_u32_e32 v10, 0x34d8, v12
	ds_write2_b32 v10, v84, v85 offset1:1
	v_add_u32_e32 v10, 0x38e0, v12
	s_waitcnt vmcnt(1)
	ds_write2_b32 v10, v86, v87 offset1:1
	v_add_u32_e32 v10, 0x38e8, v12
	ds_write2_b32 v10, v88, v89 offset1:1
	v_add_u32_e32 v10, 0x3cf0, v12
	s_waitcnt vmcnt(0)
	ds_write2_b32 v10, v90, v91 offset1:1
	v_add_u32_e32 v10, 0x3cf8, v12
	ds_write2_b32 v10, v92, v93 offset1:1
	s_waitcnt lgkmcnt(0)
	ds_read2_b32 v[30:31], v14 offset0:65 offset1:73
	ds_read2_b32 v[32:33], v14 offset1:8
	ds_read2_b32 v[34:35], v14 offset0:130 offset1:138
	ds_read2_b32 v[36:37], v14 offset0:195 offset1:203
	ds_read2_b32 v[38:39], v29 offset0:4 offset1:12
	ds_read2_b32 v[40:41], v29 offset0:69 offset1:77
	ds_read2_b32 v[42:43], v29 offset0:134 offset1:142
	ds_read2_b32 v[44:45], v29 offset0:199 offset1:207
	s_waitcnt lgkmcnt(6)
	v_cvt_pk_bf16_f32 v8, v32, v30
	v_or_b32_e32 v30, v94, v13
	v_lshlrev_b32_e32 v180, 13, v30
	s_waitcnt lgkmcnt(4)
	v_cvt_pk_bf16_f32 v9, v34, v36
	s_waitcnt lgkmcnt(2)
	v_cvt_pk_bf16_f32 v10, v38, v40
	s_waitcnt lgkmcnt(0)
	v_cvt_pk_bf16_f32 v11, v42, v44
	v_lshl_add_u64 v[48:49], v[46:47], 0, v[180:181]
	global_store_dwordx4 v[48:49], v[8:11], off sc1
	v_or_b32_e32 v30, v94, v15
	v_lshlrev_b32_e32 v180, 13, v30
	v_cvt_pk_bf16_f32 v8, v33, v31
	v_cvt_pk_bf16_f32 v9, v35, v37
	v_cvt_pk_bf16_f32 v10, v39, v41
	v_cvt_pk_bf16_f32 v11, v43, v45
	ds_read2_b32 v[32:33], v14 offset0:81 offset1:89
	ds_read2_b32 v[34:35], v14 offset0:16 offset1:24
	ds_read2_b32 v[36:37], v14 offset0:146 offset1:154
	ds_read2_b32 v[38:39], v14 offset0:211 offset1:219
	ds_read2_b32 v[40:41], v29 offset0:20 offset1:28
	ds_read2_b32 v[42:43], v29 offset0:85 offset1:93
	ds_read2_b32 v[44:45], v29 offset0:150 offset1:158
	ds_read2_b32 v[48:49], v29 offset0:215 offset1:223
	v_lshl_add_u64 v[30:31], v[46:47], 0, v[180:181]
	global_store_dwordx4 v[30:31], v[8:11], off sc1
	v_or_b32_e32 v30, v94, v16
	v_lshlrev_b32_e32 v180, 13, v30
	s_waitcnt lgkmcnt(6)
	v_cvt_pk_bf16_f32 v8, v34, v32
	s_waitcnt lgkmcnt(4)
	v_cvt_pk_bf16_f32 v9, v36, v38
	s_waitcnt lgkmcnt(2)
	v_cvt_pk_bf16_f32 v10, v40, v42
	s_waitcnt lgkmcnt(0)
	v_cvt_pk_bf16_f32 v11, v44, v48
	v_lshl_add_u64 v[30:31], v[46:47], 0, v[180:181]
	global_store_dwordx4 v[30:31], v[8:11], off sc1
	v_or_b32_e32 v30, v94, v17
	v_lshlrev_b32_e32 v180, 13, v30
	v_cvt_pk_bf16_f32 v8, v35, v33
	v_cvt_pk_bf16_f32 v9, v37, v39
	v_cvt_pk_bf16_f32 v10, v41, v43
	v_cvt_pk_bf16_f32 v11, v45, v49
	ds_read2_b32 v[32:33], v14 offset0:32 offset1:40
	ds_read2_b32 v[34:35], v14 offset0:97 offset1:105
	ds_read2_b32 v[36:37], v14 offset0:162 offset1:170
	ds_read2_b32 v[38:39], v14 offset0:227 offset1:235
	ds_read2_b32 v[40:41], v29 offset0:36 offset1:44
	ds_read2_b32 v[42:43], v29 offset0:101 offset1:109
	ds_read2_b32 v[44:45], v29 offset0:166 offset1:174
	ds_read2_b32 v[48:49], v29 offset0:231 offset1:239
	v_lshl_add_u64 v[30:31], v[46:47], 0, v[180:181]
	global_store_dwordx4 v[30:31], v[8:11], off sc1
	v_or_b32_e32 v30, v94, v18
	v_lshlrev_b32_e32 v180, 13, v30
	s_waitcnt lgkmcnt(6)
	v_cvt_pk_bf16_f32 v8, v32, v34
	s_waitcnt lgkmcnt(4)
	v_cvt_pk_bf16_f32 v9, v36, v38
	s_waitcnt lgkmcnt(2)
	v_cvt_pk_bf16_f32 v10, v40, v42
	s_waitcnt lgkmcnt(0)
	v_cvt_pk_bf16_f32 v11, v44, v48
	v_lshl_add_u64 v[30:31], v[46:47], 0, v[180:181]
	global_store_dwordx4 v[30:31], v[8:11], off sc1
	v_or_b32_e32 v30, v94, v19
	v_lshlrev_b32_e32 v180, 13, v30
	v_cvt_pk_bf16_f32 v8, v33, v35
	v_cvt_pk_bf16_f32 v9, v37, v39
	v_cvt_pk_bf16_f32 v10, v41, v43
	v_cvt_pk_bf16_f32 v11, v45, v49
	ds_read2_b32 v[32:33], v14 offset0:48 offset1:56
	ds_read2_b32 v[34:35], v14 offset0:113 offset1:121
	ds_read2_b32 v[36:37], v14 offset0:178 offset1:186
	ds_read2_b32 v[38:39], v14 offset0:243 offset1:251
	ds_read2_b32 v[40:41], v29 offset0:52 offset1:60
	ds_read2_b32 v[42:43], v29 offset0:117 offset1:125
	ds_read2_b32 v[44:45], v29 offset0:182 offset1:190
	ds_read2_b32 v[48:49], v29 offset0:247 offset1:255
	v_or_b32_e32 v29, v94, v20
	v_lshl_add_u64 v[30:31], v[46:47], 0, v[180:181]
	v_lshlrev_b32_e32 v180, 13, v29
	v_or_b32_e32 v29, v94, v21
	global_store_dwordx4 v[30:31], v[8:11], off sc1
	v_lshl_add_u64 v[30:31], v[46:47], 0, v[180:181]
	v_lshlrev_b32_e32 v180, 13, v29
	s_waitcnt lgkmcnt(6)
	v_cvt_pk_bf16_f32 v8, v32, v34
	s_waitcnt lgkmcnt(4)
	v_cvt_pk_bf16_f32 v9, v36, v38
	s_waitcnt lgkmcnt(2)
	v_cvt_pk_bf16_f32 v10, v40, v42
	s_waitcnt lgkmcnt(0)
	v_cvt_pk_bf16_f32 v11, v44, v48
	global_store_dwordx4 v[30:31], v[8:11], off sc1
	v_lshl_add_u64 v[30:31], v[46:47], 0, v[180:181]
	s_nop 0
	v_cvt_pk_bf16_f32 v8, v33, v35
	v_cvt_pk_bf16_f32 v9, v37, v39
	v_cvt_pk_bf16_f32 v10, v41, v43
	v_cvt_pk_bf16_f32 v11, v45, v49
	global_store_dwordx4 v[30:31], v[8:11], off sc1
	s_waitcnt lgkmcnt(0)

.LBB0_126:
	s_andn2_saveexec_b64 s[16:17], s[16:17]
	s_cbranch_execz .LBB0_128
	s_load_dwordx2 s[0:1], s[80:81], 0xd8
	v_add_u32_e32 v30, 0xfb80, v30
	v_lshlrev_b32_e32 v29, 6, v29
	v_and_b32_e32 v94, 0xffc0, v30
	v_lshlrev_b64 v[10:11], 24, v[10:11]
	v_sub_u32_e32 v29, v26, v29
	v_or_b32_e32 v30, v94, v7
	s_waitcnt lgkmcnt(0)
	v_lshl_add_u64 v[10:11], s[0:1], 0, v[10:11]
	v_and_b32_e32 v29, 0xfc0, v29
	v_lshlrev_b32_e32 v180, 14, v30
	v_lshl_add_u64 v[10:11], v[10:11], 0, v[180:181]
	v_lshlrev_b32_e32 v180, 2, v29
	v_lshl_add_u64 v[10:11], v[10:11], 0, v[180:181]
	v_lshlrev_b32_e32 v180, 2, v4
	v_lshl_add_u64 v[10:11], v[10:11], 0, v[180:181]
	s_mov_b32 s0, 0x10000
	v_add_co_u32_e32 v34, vcc, s0, v10
	s_mov_b32 s0, 0x20000
	s_nop 0
	v_addc_co_u32_e32 v35, vcc, 0, v11, vcc
	v_add_co_u32_e32 v38, vcc, s0, v10
	global_load_dwordx4 v[30:33], v[10:11], off
	s_nop 0
	global_load_dwordx4 v[34:37], v[34:35], off
	v_addc_co_u32_e32 v39, vcc, 0, v11, vcc
	s_mov_b32 s0, 0x30000
	v_add_co_u32_e32 v42, vcc, s0, v10
	s_mov_b32 s0, 0x40000
	s_nop 0
	v_addc_co_u32_e32 v43, vcc, 0, v11, vcc
	global_load_dwordx4 v[38:41], v[38:39], off
	s_nop 0
	global_load_dwordx4 v[42:45], v[42:43], off
	v_add_co_u32_e32 v46, vcc, s0, v10
	s_mov_b32 s0, 0x50000
	s_nop 0
	v_addc_co_u32_e32 v47, vcc, 0, v11, vcc
	v_add_co_u32_e32 v50, vcc, s0, v10
	s_mov_b32 s0, 0x60000
	s_nop 0
	v_addc_co_u32_e32 v51, vcc, 0, v11, vcc
	global_load_dwordx4 v[46:49], v[46:47], off
	s_nop 0
	global_load_dwordx4 v[50:53], v[50:51], off
	v_add_co_u32_e32 v54, vcc, s0, v10
	s_mov_b32 s0, 0x80000
	s_nop 0
	v_addc_co_u32_e32 v55, vcc, 0, v11, vcc
	v_add_co_u32_e32 v58, vcc, s82, v10
	v_lshlrev_b32_e32 v180, 1, v94
	s_nop 0
	v_addc_co_u32_e32 v59, vcc, 0, v11, vcc
	global_load_dwordx4 v[54:57], v[54:55], off
	s_nop 0
	global_load_dwordx4 v[58:61], v[58:59], off
	v_add_co_u32_e32 v62, vcc, s0, v10
	s_mov_b32 s0, 0x90000
	s_nop 0
	v_addc_co_u32_e32 v63, vcc, 0, v11, vcc
	v_add_co_u32_e32 v66, vcc, s0, v10
	s_mov_b32 s0, 0xa0000
	s_nop 0
	v_addc_co_u32_e32 v67, vcc, 0, v11, vcc
	global_load_dwordx4 v[62:65], v[62:63], off
	s_nop 0
	global_load_dwordx4 v[66:69], v[66:67], off
	v_add_co_u32_e32 v70, vcc, s0, v10
	s_mov_b32 s0, 0xb0000
	s_nop 0
	v_addc_co_u32_e32 v71, vcc, 0, v11, vcc
	v_add_co_u32_e32 v74, vcc, s0, v10
	s_mov_b32 s0, 0xc0000
	s_nop 0
	v_addc_co_u32_e32 v75, vcc, 0, v11, vcc
	global_load_dwordx4 v[70:73], v[70:71], off
	s_nop 0
	global_load_dwordx4 v[74:77], v[74:75], off
	v_add_co_u32_e32 v78, vcc, s0, v10
	s_mov_b32 s0, 0xd0000
	s_nop 0
	v_addc_co_u32_e32 v79, vcc, 0, v11, vcc
	global_load_dwordx4 v[78:81], v[78:79], off
	v_add_co_u32_e32 v82, vcc, s0, v10
	s_mov_b32 s0, 0xe0000
	s_nop 0
	v_addc_co_u32_e32 v83, vcc, 0, v11, vcc
	global_load_dwordx4 v[82:85], v[82:83], off
	v_add_co_u32_e32 v86, vcc, s0, v10
	s_mov_b32 s0, 0xf0000
	s_nop 0
	v_addc_co_u32_e32 v87, vcc, 0, v11, vcc
	global_load_dwordx4 v[86:89], v[86:87], off
	v_add_co_u32_e32 v10, vcc, s0, v10
	v_lshl_add_u64 v[8:9], v[8:9], 0, v[180:181]
	s_nop 0
	v_addc_co_u32_e32 v11, vcc, 0, v11, vcc
	global_load_dwordx4 v[90:93], v[10:11], off
	v_add_u32_e32 v10, 0x410, v12
	s_waitcnt vmcnt(15)
	ds_write2_b32 v12, v30, v31 offset1:1
	ds_write2_b32 v12, v32, v33 offset0:2 offset1:3
	s_waitcnt vmcnt(14)
	ds_write2_b32 v10, v34, v35 offset1:1
	v_add_u32_e32 v10, 0x418, v12
	ds_write2_b32 v10, v36, v37 offset1:1
	v_add_u32_e32 v10, 0x820, v12
	v_lshlrev_b32_e32 v180, 1, v6
	v_lshl_add_u64 v[8:9], v[8:9], 0, v[180:181]
	s_mov_b64 s[0:1], 0x900000
	s_waitcnt vmcnt(13)
	ds_write2_b32 v10, v38, v39 offset1:1
	v_add_u32_e32 v10, 0x828, v12
	ds_write2_b32 v10, v40, v41 offset1:1
	v_add_u32_e32 v10, 0xc30, v12
	s_waitcnt vmcnt(12)
	ds_write2_b32 v10, v42, v43 offset1:1
	v_add_u32_e32 v10, 0xc38, v12
	ds_write2_b32 v10, v44, v45 offset1:1
	v_add_u32_e32 v10, 0x1040, v12
	s_waitcnt vmcnt(11)
	ds_write2_b32 v10, v46, v47 offset1:1
	v_add_u32_e32 v10, 0x1048, v12
	ds_write2_b32 v10, v48, v49 offset1:1
	v_add_u32_e32 v10, 0x1450, v12
	s_waitcnt vmcnt(10)
	ds_write2_b32 v10, v50, v51 offset1:1
	v_add_u32_e32 v10, 0x1458, v12
	ds_write2_b32 v10, v52, v53 offset1:1
	v_add_u32_e32 v10, 0x1860, v12
	v_add_u32_e32 v50, 0x400, v14
	v_lshl_add_u64 v[46:47], v[8:9], 0, s[0:1]
	s_waitcnt vmcnt(9)
	ds_write2_b32 v10, v54, v55 offset1:1
	v_add_u32_e32 v10, 0x1868, v12
	ds_write2_b32 v10, v56, v57 offset1:1
	v_add_u32_e32 v10, 0x1c70, v12
	s_waitcnt vmcnt(8)
	ds_write2_b32 v10, v58, v59 offset1:1
	v_add_u32_e32 v10, 0x1c78, v12
	ds_write2_b32 v10, v60, v61 offset1:1
	v_add_u32_e32 v10, 0x2080, v12
	s_waitcnt vmcnt(7)
	ds_write2_b32 v10, v62, v63 offset1:1
	v_add_u32_e32 v10, 0x2088, v12
	ds_write2_b32 v10, v64, v65 offset1:1
	v_add_u32_e32 v10, 0x2490, v12
	s_waitcnt vmcnt(6)
	ds_write2_b32 v10, v66, v67 offset1:1
	v_add_u32_e32 v10, 0x2498, v12
	ds_write2_b32 v10, v68, v69 offset1:1
	v_add_u32_e32 v10, 0x28a0, v12
	s_waitcnt vmcnt(5)
	ds_write2_b32 v10, v70, v71 offset1:1
	v_add_u32_e32 v10, 0x28a8, v12
	ds_write2_b32 v10, v72, v73 offset1:1
	v_add_u32_e32 v10, 0x2cb0, v12
	s_waitcnt vmcnt(4)
	ds_write2_b32 v10, v74, v75 offset1:1
	v_add_u32_e32 v10, 0x2cb8, v12
	ds_write2_b32 v10, v76, v77 offset1:1
	v_add_u32_e32 v10, 0x30c0, v12
	s_waitcnt vmcnt(3)
	ds_write2_b32 v10, v78, v79 offset1:1
	v_add_u32_e32 v10, 0x30c8, v12
	ds_write2_b32 v10, v80, v81 offset1:1
	v_add_u32_e32 v10, 0x34d0, v12
	s_waitcnt vmcnt(2)
	ds_write2_b32 v10, v82, v83 offset1:1
	v_add_u32_e32 v10, 0x34d8, v12
	ds_write2_b32 v10, v84, v85 offset1:1
	v_add_u32_e32 v10, 0x38e0, v12
	s_waitcnt vmcnt(1)
	ds_write2_b32 v10, v86, v87 offset1:1
	v_add_u32_e32 v10, 0x38e8, v12
	ds_write2_b32 v10, v88, v89 offset1:1
	v_add_u32_e32 v10, 0x3cf0, v12
	s_waitcnt vmcnt(0)
	ds_write2_b32 v10, v90, v91 offset1:1
	v_add_u32_e32 v10, 0x3cf8, v12
	ds_write2_b32 v10, v92, v93 offset1:1
	s_waitcnt lgkmcnt(0)
	ds_read2_b32 v[30:31], v14 offset0:65 offset1:73
	ds_read2_b32 v[32:33], v14 offset1:8
	ds_read2_b32 v[34:35], v14 offset0:130 offset1:138
	ds_read2_b32 v[36:37], v14 offset0:195 offset1:203
	ds_read2_b32 v[38:39], v50 offset0:4 offset1:12
	ds_read2_b32 v[40:41], v50 offset0:69 offset1:77
	ds_read2_b32 v[42:43], v50 offset0:134 offset1:142
	ds_read2_b32 v[44:45], v50 offset0:199 offset1:207
	s_waitcnt lgkmcnt(6)
	v_cvt_pk_bf16_f32 v8, v32, v30
	v_or_b32_e32 v30, v29, v13
	v_lshlrev_b32_e32 v180, 11, v30
	s_waitcnt lgkmcnt(4)
	v_cvt_pk_bf16_f32 v9, v34, v36
	s_waitcnt lgkmcnt(2)
	v_cvt_pk_bf16_f32 v10, v38, v40
	s_waitcnt lgkmcnt(0)
	v_cvt_pk_bf16_f32 v11, v42, v44
	v_lshl_add_u64 v[48:49], v[46:47], 0, v[180:181]
	global_store_dwordx4 v[48:49], v[8:11], off sc1
	v_or_b32_e32 v30, v29, v15
	v_lshlrev_b32_e32 v180, 11, v30
	v_cvt_pk_bf16_f32 v8, v33, v31
	v_cvt_pk_bf16_f32 v9, v35, v37
	v_cvt_pk_bf16_f32 v10, v39, v41
	v_cvt_pk_bf16_f32 v11, v43, v45
	ds_read2_b32 v[32:33], v14 offset0:81 offset1:89
	ds_read2_b32 v[34:35], v14 offset0:16 offset1:24
	ds_read2_b32 v[36:37], v14 offset0:146 offset1:154
	ds_read2_b32 v[38:39], v14 offset0:211 offset1:219
	ds_read2_b32 v[40:41], v50 offset0:20 offset1:28
	ds_read2_b32 v[42:43], v50 offset0:85 offset1:93
	ds_read2_b32 v[44:45], v50 offset0:150 offset1:158
	ds_read2_b32 v[48:49], v50 offset0:215 offset1:223
	v_lshl_add_u64 v[30:31], v[46:47], 0, v[180:181]
	global_store_dwordx4 v[30:31], v[8:11], off sc1
	v_or_b32_e32 v30, v29, v16
	v_lshlrev_b32_e32 v180, 11, v30
	s_waitcnt lgkmcnt(6)
	v_cvt_pk_bf16_f32 v8, v34, v32
	s_waitcnt lgkmcnt(4)
	v_cvt_pk_bf16_f32 v9, v36, v38
	s_waitcnt lgkmcnt(2)
	v_cvt_pk_bf16_f32 v10, v40, v42
	s_waitcnt lgkmcnt(0)
	v_cvt_pk_bf16_f32 v11, v44, v48
	v_lshl_add_u64 v[30:31], v[46:47], 0, v[180:181]
	global_store_dwordx4 v[30:31], v[8:11], off sc1
	v_or_b32_e32 v30, v29, v17
	v_lshlrev_b32_e32 v180, 11, v30
	v_cvt_pk_bf16_f32 v8, v35, v33
	v_cvt_pk_bf16_f32 v9, v37, v39
	v_cvt_pk_bf16_f32 v10, v41, v43
	v_cvt_pk_bf16_f32 v11, v45, v49
	ds_read2_b32 v[32:33], v14 offset0:32 offset1:40
	ds_read2_b32 v[34:35], v14 offset0:97 offset1:105
	ds_read2_b32 v[36:37], v14 offset0:162 offset1:170
	ds_read2_b32 v[38:39], v14 offset0:227 offset1:235
	ds_read2_b32 v[40:41], v50 offset0:36 offset1:44
	ds_read2_b32 v[42:43], v50 offset0:101 offset1:109
	ds_read2_b32 v[44:45], v50 offset0:166 offset1:174
	ds_read2_b32 v[48:49], v50 offset0:231 offset1:239
	v_lshl_add_u64 v[30:31], v[46:47], 0, v[180:181]
	global_store_dwordx4 v[30:31], v[8:11], off sc1
	v_or_b32_e32 v30, v29, v18
	v_lshlrev_b32_e32 v180, 11, v30
	s_waitcnt lgkmcnt(6)
	v_cvt_pk_bf16_f32 v8, v32, v34
	s_waitcnt lgkmcnt(4)
	v_cvt_pk_bf16_f32 v9, v36, v38
	s_waitcnt lgkmcnt(2)
	v_cvt_pk_bf16_f32 v10, v40, v42
	s_waitcnt lgkmcnt(0)
	v_cvt_pk_bf16_f32 v11, v44, v48
	v_lshl_add_u64 v[30:31], v[46:47], 0, v[180:181]
	global_store_dwordx4 v[30:31], v[8:11], off sc1
	v_or_b32_e32 v30, v29, v19
	v_lshlrev_b32_e32 v180, 11, v30
	v_cvt_pk_bf16_f32 v8, v33, v35
	v_cvt_pk_bf16_f32 v9, v37, v39
	v_cvt_pk_bf16_f32 v10, v41, v43
	v_cvt_pk_bf16_f32 v11, v45, v49
	ds_read2_b32 v[32:33], v14 offset0:48 offset1:56
	ds_read2_b32 v[34:35], v14 offset0:113 offset1:121
	ds_read2_b32 v[36:37], v14 offset0:178 offset1:186
	ds_read2_b32 v[38:39], v14 offset0:243 offset1:251
	ds_read2_b32 v[40:41], v50 offset0:52 offset1:60
	ds_read2_b32 v[42:43], v50 offset0:117 offset1:125
	ds_read2_b32 v[44:45], v50 offset0:182 offset1:190
	ds_read2_b32 v[48:49], v50 offset0:247 offset1:255
	v_lshl_add_u64 v[30:31], v[46:47], 0, v[180:181]
	global_store_dwordx4 v[30:31], v[8:11], off sc1
	v_or_b32_e32 v30, v29, v20
	v_lshlrev_b32_e32 v180, 11, v30
	v_or_b32_e32 v29, v29, v21
	s_waitcnt lgkmcnt(6)
	v_cvt_pk_bf16_f32 v8, v32, v34
	s_waitcnt lgkmcnt(4)
	v_cvt_pk_bf16_f32 v9, v36, v38
	s_waitcnt lgkmcnt(2)
	v_cvt_pk_bf16_f32 v10, v40, v42
	s_waitcnt lgkmcnt(0)
	v_cvt_pk_bf16_f32 v11, v44, v48
	v_lshl_add_u64 v[30:31], v[46:47], 0, v[180:181]
	v_lshlrev_b32_e32 v180, 11, v29
	global_store_dwordx4 v[30:31], v[8:11], off sc1
	v_lshl_add_u64 v[30:31], v[46:47], 0, v[180:181]
	s_nop 0
	v_cvt_pk_bf16_f32 v8, v33, v35
	v_cvt_pk_bf16_f32 v9, v37, v39
	v_cvt_pk_bf16_f32 v10, v41, v43
	v_cvt_pk_bf16_f32 v11, v45, v49
	global_store_dwordx4 v[30:31], v[8:11], off sc1
	s_waitcnt lgkmcnt(0)

.LBB0_129:
	s_andn2_saveexec_b64 s[14:15], s[14:15]
	s_cbranch_execz .LBB0_131
	s_load_dwordx2 s[0:1], s[80:81], 0xd0
	v_lshlrev_b32_e32 v30, 2, v29
	v_sub_u32_e32 v94, v28, v30
	v_and_b32_e32 v30, 0x3c0, v94
	v_lshlrev_b32_e32 v29, 6, v29
	v_lshlrev_b64 v[10:11], 22, v[10:11]
	v_sub_u32_e32 v29, v26, v29
	v_bitop3_b32 v30, v30, v7, s74 bitop3:0xde
	s_waitcnt lgkmcnt(0)
	v_lshl_add_u64 v[10:11], s[0:1], 0, v[10:11]
	v_and_b32_e32 v29, 0x3c0, v29
	v_lshlrev_b32_e32 v180, 12, v30
	v_lshl_add_u64 v[10:11], v[10:11], 0, v[180:181]
	v_lshlrev_b32_e32 v180, 2, v29
	v_lshl_add_u64 v[10:11], v[10:11], 0, v[180:181]
	v_lshlrev_b32_e32 v180, 2, v4
	v_lshl_add_u64 v[10:11], v[10:11], 0, v[180:181]
	s_movk_i32 s0, 0x4000
	v_add_co_u32_e32 v34, vcc, s0, v10
	s_mov_b32 s0, 0xc000
	s_nop 0
	v_addc_co_u32_e32 v35, vcc, 0, v11, vcc
	v_add_co_u32_e32 v38, vcc, s70, v10
	global_load_dwordx4 v[30:33], v[10:11], off
	s_nop 0
	global_load_dwordx4 v[34:37], v[34:35], off
	v_addc_co_u32_e32 v39, vcc, 0, v11, vcc
	v_add_co_u32_e32 v42, vcc, s0, v10
	s_mov_b32 s0, 0x10000
	s_nop 0
	v_addc_co_u32_e32 v43, vcc, 0, v11, vcc
	global_load_dwordx4 v[38:41], v[38:39], off
	s_nop 0
	global_load_dwordx4 v[42:45], v[42:43], off
	v_add_co_u32_e32 v46, vcc, s0, v10
	s_mov_b32 s0, 0x14000
	s_nop 0
	v_addc_co_u32_e32 v47, vcc, 0, v11, vcc
	v_add_co_u32_e32 v50, vcc, s0, v10
	s_mov_b32 s0, 0x18000
	s_nop 0
	v_addc_co_u32_e32 v51, vcc, 0, v11, vcc
	global_load_dwordx4 v[46:49], v[46:47], off
	s_nop 0
	global_load_dwordx4 v[50:53], v[50:51], off
	v_add_co_u32_e32 v54, vcc, s0, v10
	s_mov_b32 s0, 0x20000
	s_nop 0
	v_addc_co_u32_e32 v55, vcc, 0, v11, vcc
	v_add_co_u32_e32 v58, vcc, s71, v10
	s_nop 1
	v_addc_co_u32_e32 v59, vcc, 0, v11, vcc
	global_load_dwordx4 v[54:57], v[54:55], off
	s_nop 0
	global_load_dwordx4 v[58:61], v[58:59], off
	v_add_co_u32_e32 v62, vcc, s0, v10
	s_mov_b32 s0, 0x24000
	s_nop 0
	v_addc_co_u32_e32 v63, vcc, 0, v11, vcc
	v_add_co_u32_e32 v66, vcc, s0, v10
	s_mov_b32 s0, 0x28000
	s_nop 0
	v_addc_co_u32_e32 v67, vcc, 0, v11, vcc
	global_load_dwordx4 v[62:65], v[62:63], off
	s_nop 0
	global_load_dwordx4 v[66:69], v[66:67], off
	v_add_co_u32_e32 v70, vcc, s0, v10
	s_mov_b32 s0, 0x2c000
	s_nop 0
	v_addc_co_u32_e32 v71, vcc, 0, v11, vcc
	v_add_co_u32_e32 v74, vcc, s0, v10
	s_mov_b32 s0, 0x30000
	s_nop 0
	v_addc_co_u32_e32 v75, vcc, 0, v11, vcc
	global_load_dwordx4 v[70:73], v[70:71], off
	s_nop 0
	global_load_dwordx4 v[74:77], v[74:75], off
	v_add_co_u32_e32 v78, vcc, s0, v10
	s_mov_b32 s0, 0x34000
	s_nop 0
	v_addc_co_u32_e32 v79, vcc, 0, v11, vcc
	global_load_dwordx4 v[78:81], v[78:79], off
	v_add_co_u32_e32 v82, vcc, s0, v10
	s_mov_b32 s0, 0x3c000
	s_nop 0
	v_addc_co_u32_e32 v83, vcc, 0, v11, vcc
	global_load_dwordx4 v[82:85], v[82:83], off
	v_add_co_u32_e32 v86, vcc, s85, v10
	s_nop 1
	v_addc_co_u32_e32 v87, vcc, 0, v11, vcc
	global_load_dwordx4 v[86:89], v[86:87], off
	v_add_co_u32_e32 v10, vcc, s0, v10
	s_mov_b64 s[0:1], 0x700000
	s_nop 0
	v_addc_co_u32_e32 v11, vcc, 0, v11, vcc
	global_load_dwordx4 v[90:93], v[10:11], off
	v_add_u32_e32 v11, 0x410, v12
	s_waitcnt vmcnt(15)
	ds_write2_b32 v12, v30, v31 offset1:1
	ds_write2_b32 v12, v32, v33 offset0:2 offset1:3
	s_waitcnt vmcnt(14)
	ds_write2_b32 v11, v34, v35 offset1:1
	v_add_u32_e32 v11, 0x418, v12
	ds_write2_b32 v11, v36, v37 offset1:1
	v_add_u32_e32 v11, 0x820, v12
	v_bitop3_b32 v10, v94, s74, v250 bitop3:0x6c
	v_lshlrev_b32_e32 v180, 1, v10
	v_lshl_add_u64 v[8:9], v[8:9], 0, v[180:181]
	s_waitcnt vmcnt(13)
	ds_write2_b32 v11, v38, v39 offset1:1
	v_add_u32_e32 v11, 0x828, v12
	ds_write2_b32 v11, v40, v41 offset1:1
	v_add_u32_e32 v11, 0xc30, v12
	s_waitcnt vmcnt(12)
	ds_write2_b32 v11, v42, v43 offset1:1
	v_add_u32_e32 v11, 0xc38, v12
	ds_write2_b32 v11, v44, v45 offset1:1
	v_add_u32_e32 v11, 0x1040, v12
	v_lshlrev_b32_e32 v180, 1, v6
	v_lshl_add_u64 v[8:9], v[8:9], 0, v[180:181]
	s_waitcnt vmcnt(11)
	ds_write2_b32 v11, v46, v47 offset1:1
	v_add_u32_e32 v11, 0x1048, v12
	ds_write2_b32 v11, v48, v49 offset1:1
	v_add_u32_e32 v11, 0x1450, v12
	s_waitcnt vmcnt(10)
	ds_write2_b32 v11, v50, v51 offset1:1
	v_add_u32_e32 v11, 0x1458, v12
	ds_write2_b32 v11, v52, v53 offset1:1
	v_add_u32_e32 v11, 0x1860, v12
	v_add_u32_e32 v50, 0x400, v14
	v_lshl_add_u64 v[46:47], v[8:9], 0, s[0:1]
	s_waitcnt vmcnt(9)
	ds_write2_b32 v11, v54, v55 offset1:1
	v_add_u32_e32 v11, 0x1868, v12
	ds_write2_b32 v11, v56, v57 offset1:1
	v_add_u32_e32 v11, 0x1c70, v12
	s_waitcnt vmcnt(8)
	ds_write2_b32 v11, v58, v59 offset1:1
	v_add_u32_e32 v11, 0x1c78, v12
	ds_write2_b32 v11, v60, v61 offset1:1
	v_add_u32_e32 v11, 0x2080, v12
	s_waitcnt vmcnt(7)
	ds_write2_b32 v11, v62, v63 offset1:1
	v_add_u32_e32 v11, 0x2088, v12
	ds_write2_b32 v11, v64, v65 offset1:1
	v_add_u32_e32 v11, 0x2490, v12
	s_waitcnt vmcnt(6)
	ds_write2_b32 v11, v66, v67 offset1:1
	v_add_u32_e32 v11, 0x2498, v12
	ds_write2_b32 v11, v68, v69 offset1:1
	v_add_u32_e32 v11, 0x28a0, v12
	s_waitcnt vmcnt(5)
	ds_write2_b32 v11, v70, v71 offset1:1
	v_add_u32_e32 v11, 0x28a8, v12
	ds_write2_b32 v11, v72, v73 offset1:1
	v_add_u32_e32 v11, 0x2cb0, v12
	s_waitcnt vmcnt(4)
	ds_write2_b32 v11, v74, v75 offset1:1
	v_add_u32_e32 v11, 0x2cb8, v12
	ds_write2_b32 v11, v76, v77 offset1:1
	v_add_u32_e32 v11, 0x30c0, v12
	s_waitcnt vmcnt(3)
	ds_write2_b32 v11, v78, v79 offset1:1
	v_add_u32_e32 v11, 0x30c8, v12
	ds_write2_b32 v11, v80, v81 offset1:1
	v_add_u32_e32 v11, 0x34d0, v12
	s_waitcnt vmcnt(2)
	ds_write2_b32 v11, v82, v83 offset1:1
	v_add_u32_e32 v11, 0x34d8, v12
	ds_write2_b32 v11, v84, v85 offset1:1
	v_add_u32_e32 v11, 0x38e0, v12
	s_waitcnt vmcnt(1)
	ds_write2_b32 v11, v86, v87 offset1:1
	v_add_u32_e32 v11, 0x38e8, v12
	ds_write2_b32 v11, v88, v89 offset1:1
	v_add_u32_e32 v11, 0x3cf0, v12
	s_waitcnt vmcnt(0)
	ds_write2_b32 v11, v90, v91 offset1:1
	v_add_u32_e32 v11, 0x3cf8, v12
	ds_write2_b32 v11, v92, v93 offset1:1
	s_waitcnt lgkmcnt(0)
	ds_read2_b32 v[30:31], v14 offset0:65 offset1:73
	ds_read2_b32 v[32:33], v14 offset1:8
	ds_read2_b32 v[34:35], v14 offset0:130 offset1:138
	ds_read2_b32 v[36:37], v14 offset0:195 offset1:203
	ds_read2_b32 v[38:39], v50 offset0:4 offset1:12
	ds_read2_b32 v[40:41], v50 offset0:69 offset1:77
	ds_read2_b32 v[42:43], v50 offset0:134 offset1:142
	ds_read2_b32 v[44:45], v50 offset0:199 offset1:207
	s_waitcnt lgkmcnt(6)
	v_cvt_pk_bf16_f32 v8, v32, v30
	v_or_b32_e32 v30, v29, v13
	v_lshlrev_b32_e32 v180, 11, v30
	s_waitcnt lgkmcnt(4)
	v_cvt_pk_bf16_f32 v9, v34, v36
	s_waitcnt lgkmcnt(2)
	v_cvt_pk_bf16_f32 v10, v38, v40
	s_waitcnt lgkmcnt(0)
	v_cvt_pk_bf16_f32 v11, v42, v44
	v_lshl_add_u64 v[48:49], v[46:47], 0, v[180:181]
	global_store_dwordx4 v[48:49], v[8:11], off sc1
	v_or_b32_e32 v30, v29, v15
	v_lshlrev_b32_e32 v180, 11, v30
	v_cvt_pk_bf16_f32 v8, v33, v31
	v_cvt_pk_bf16_f32 v9, v35, v37
	v_cvt_pk_bf16_f32 v10, v39, v41
	v_cvt_pk_bf16_f32 v11, v43, v45
	ds_read2_b32 v[32:33], v14 offset0:81 offset1:89
	ds_read2_b32 v[34:35], v14 offset0:16 offset1:24
	ds_read2_b32 v[36:37], v14 offset0:146 offset1:154
	ds_read2_b32 v[38:39], v14 offset0:211 offset1:219
	ds_read2_b32 v[40:41], v50 offset0:20 offset1:28
	ds_read2_b32 v[42:43], v50 offset0:85 offset1:93
	ds_read2_b32 v[44:45], v50 offset0:150 offset1:158
	ds_read2_b32 v[48:49], v50 offset0:215 offset1:223
	v_lshl_add_u64 v[30:31], v[46:47], 0, v[180:181]
	global_store_dwordx4 v[30:31], v[8:11], off sc1
	v_or_b32_e32 v30, v29, v16
	v_lshlrev_b32_e32 v180, 11, v30
	s_waitcnt lgkmcnt(6)
	v_cvt_pk_bf16_f32 v8, v34, v32
	s_waitcnt lgkmcnt(4)
	v_cvt_pk_bf16_f32 v9, v36, v38
	s_waitcnt lgkmcnt(2)
	v_cvt_pk_bf16_f32 v10, v40, v42
	s_waitcnt lgkmcnt(0)
	v_cvt_pk_bf16_f32 v11, v44, v48
	v_lshl_add_u64 v[30:31], v[46:47], 0, v[180:181]
	global_store_dwordx4 v[30:31], v[8:11], off sc1
	v_or_b32_e32 v30, v29, v17
	v_lshlrev_b32_e32 v180, 11, v30
	v_cvt_pk_bf16_f32 v8, v35, v33
	v_cvt_pk_bf16_f32 v9, v37, v39
	v_cvt_pk_bf16_f32 v10, v41, v43
	v_cvt_pk_bf16_f32 v11, v45, v49
	ds_read2_b32 v[32:33], v14 offset0:32 offset1:40
	ds_read2_b32 v[34:35], v14 offset0:97 offset1:105
	ds_read2_b32 v[36:37], v14 offset0:162 offset1:170
	ds_read2_b32 v[38:39], v14 offset0:227 offset1:235
	ds_read2_b32 v[40:41], v50 offset0:36 offset1:44
	ds_read2_b32 v[42:43], v50 offset0:101 offset1:109
	ds_read2_b32 v[44:45], v50 offset0:166 offset1:174
	ds_read2_b32 v[48:49], v50 offset0:231 offset1:239
	v_lshl_add_u64 v[30:31], v[46:47], 0, v[180:181]
	global_store_dwordx4 v[30:31], v[8:11], off sc1
	v_or_b32_e32 v30, v29, v18
	v_lshlrev_b32_e32 v180, 11, v30
	s_waitcnt lgkmcnt(6)
	v_cvt_pk_bf16_f32 v8, v32, v34
	s_waitcnt lgkmcnt(4)
	v_cvt_pk_bf16_f32 v9, v36, v38
	s_waitcnt lgkmcnt(2)
	v_cvt_pk_bf16_f32 v10, v40, v42
	s_waitcnt lgkmcnt(0)
	v_cvt_pk_bf16_f32 v11, v44, v48
	v_lshl_add_u64 v[30:31], v[46:47], 0, v[180:181]
	global_store_dwordx4 v[30:31], v[8:11], off sc1
	v_or_b32_e32 v30, v29, v19
	v_lshlrev_b32_e32 v180, 11, v30
	v_cvt_pk_bf16_f32 v8, v33, v35
	v_cvt_pk_bf16_f32 v9, v37, v39
	v_cvt_pk_bf16_f32 v10, v41, v43
	v_cvt_pk_bf16_f32 v11, v45, v49
	ds_read2_b32 v[32:33], v14 offset0:48 offset1:56
	ds_read2_b32 v[34:35], v14 offset0:113 offset1:121
	ds_read2_b32 v[36:37], v14 offset0:178 offset1:186
	ds_read2_b32 v[38:39], v14 offset0:243 offset1:251
	ds_read2_b32 v[40:41], v50 offset0:52 offset1:60
	ds_read2_b32 v[42:43], v50 offset0:117 offset1:125
	ds_read2_b32 v[44:45], v50 offset0:182 offset1:190
	ds_read2_b32 v[48:49], v50 offset0:247 offset1:255
	v_lshl_add_u64 v[30:31], v[46:47], 0, v[180:181]
	global_store_dwordx4 v[30:31], v[8:11], off sc1
	v_or_b32_e32 v30, v29, v20
	v_lshlrev_b32_e32 v180, 11, v30
	v_or_b32_e32 v29, v29, v21
	s_waitcnt lgkmcnt(6)
	v_cvt_pk_bf16_f32 v8, v32, v34
	s_waitcnt lgkmcnt(4)
	v_cvt_pk_bf16_f32 v9, v36, v38
	s_waitcnt lgkmcnt(2)
	v_cvt_pk_bf16_f32 v10, v40, v42
	s_waitcnt lgkmcnt(0)
	v_cvt_pk_bf16_f32 v11, v44, v48
	v_lshl_add_u64 v[30:31], v[46:47], 0, v[180:181]
	v_lshlrev_b32_e32 v180, 11, v29
	global_store_dwordx4 v[30:31], v[8:11], off sc1
	v_lshl_add_u64 v[30:31], v[46:47], 0, v[180:181]
	s_nop 0
	v_cvt_pk_bf16_f32 v8, v33, v35
	v_cvt_pk_bf16_f32 v9, v37, v39
	v_cvt_pk_bf16_f32 v10, v41, v43
	v_cvt_pk_bf16_f32 v11, v45, v49
	global_store_dwordx4 v[30:31], v[8:11], off sc1
	s_waitcnt lgkmcnt(0)

.LBB0_132:
	s_andn2_saveexec_b64 s[12:13], s[12:13]
	s_cbranch_execz .LBB0_134
	s_load_dwordx2 s[0:1], s[80:81], 0x40
	v_lshlrev_b32_e32 v11, 4, v29
	v_sub_u32_e32 v11, v27, v11
	v_add_u32_e32 v32, 0xc00, v11
	v_and_b32_e32 v94, 0xfc0, v32
	s_waitcnt lgkmcnt(0)
	v_mov_b64_e32 v[30:31], s[0:1]
	v_mad_i64_i32 v[10:11], s[0:1], v10, s54, v[30:31]
	v_lshlrev_b32_e32 v29, 6, v29
	v_or_b32_e32 v30, v94, v7
	v_sub_u32_e32 v29, v26, v29
	v_mul_u32_u24_e32 v30, 0xe10, v30
	v_and_b32_e32 v29, 0xc0, v29
	v_lshlrev_b32_e32 v180, 2, v30
	v_lshl_add_u64 v[10:11], v[10:11], 0, v[180:181]
	v_lshlrev_b32_e32 v180, 2, v29
	v_lshl_add_u64 v[10:11], v[10:11], 0, v[180:181]
	v_lshlrev_b32_e32 v180, 2, v4
	v_lshl_add_u64 v[10:11], v[10:11], 0, v[180:181]
	v_add_co_u32_e32 v30, vcc, s84, v10
	s_mov_b32 s0, 0x11000
	s_nop 0
	v_addc_co_u32_e32 v31, vcc, 0, v11, vcc
	v_add_co_u32_e32 v34, vcc, s0, v10
	s_mov_b32 s0, 0x1f000
	s_nop 0
	v_addc_co_u32_e32 v35, vcc, 0, v11, vcc
	v_add_co_u32_e32 v38, vcc, s0, v10
	global_load_dwordx4 v[30:33], v[30:31], off offset:1088
	s_nop 0
	global_load_dwordx4 v[34:37], v[34:35], off offset:1344
	v_addc_co_u32_e32 v39, vcc, 0, v11, vcc
	s_mov_b32 s0, 0x2d000
	v_add_co_u32_e32 v42, vcc, s0, v10
	s_mov_b32 s0, 0x3b000
	s_nop 0
	v_addc_co_u32_e32 v43, vcc, 0, v11, vcc
	global_load_dwordx4 v[38:41], v[38:39], off offset:1600
	s_nop 0
	global_load_dwordx4 v[42:45], v[42:43], off offset:1856
	v_add_co_u32_e32 v46, vcc, s0, v10
	s_mov_b32 s0, 0x49000
	s_nop 0
	v_addc_co_u32_e32 v47, vcc, 0, v11, vcc
	v_add_co_u32_e32 v50, vcc, s0, v10
	s_mov_b32 s0, 0x57000
	s_nop 0
	v_addc_co_u32_e32 v51, vcc, 0, v11, vcc
	global_load_dwordx4 v[46:49], v[46:47], off offset:2112
	s_nop 0
	global_load_dwordx4 v[50:53], v[50:51], off offset:2368
	v_add_co_u32_e32 v54, vcc, s0, v10
	s_mov_b32 s0, 0x65000
	s_nop 0
	v_addc_co_u32_e32 v55, vcc, 0, v11, vcc
	v_add_co_u32_e32 v58, vcc, s0, v10
	s_mov_b32 s0, 0x73000
	s_nop 0
	v_addc_co_u32_e32 v59, vcc, 0, v11, vcc
	global_load_dwordx4 v[54:57], v[54:55], off offset:2624
	s_nop 0
	global_load_dwordx4 v[58:61], v[58:59], off offset:2880
	v_add_co_u32_e32 v62, vcc, s0, v10
	s_mov_b32 s0, 0x81000
	s_nop 0
	v_addc_co_u32_e32 v63, vcc, 0, v11, vcc
	v_add_co_u32_e32 v66, vcc, s0, v10
	s_mov_b32 s0, 0x8f000
	s_nop 0
	v_addc_co_u32_e32 v67, vcc, 0, v11, vcc
	global_load_dwordx4 v[62:65], v[62:63], off offset:3136
	s_nop 0
	global_load_dwordx4 v[66:69], v[66:67], off offset:3392
	v_add_co_u32_e32 v70, vcc, s0, v10
	s_mov_b32 s0, 0x9d000
	s_nop 0
	v_addc_co_u32_e32 v71, vcc, 0, v11, vcc
	v_add_co_u32_e32 v74, vcc, s0, v10
	s_mov_b32 s0, 0xac000
	s_nop 0
	v_addc_co_u32_e32 v75, vcc, 0, v11, vcc
	global_load_dwordx4 v[70:73], v[70:71], off offset:3648
	s_nop 0
	global_load_dwordx4 v[74:77], v[74:75], off offset:3904
	v_add_co_u32_e32 v78, vcc, s0, v10
	s_mov_b32 s0, 0xba000
	s_nop 0
	v_addc_co_u32_e32 v79, vcc, 0, v11, vcc
	global_load_dwordx4 v[78:81], v[78:79], off offset:64
	v_add_co_u32_e32 v82, vcc, s0, v10
	s_mov_b32 s0, 0xc8000
	s_nop 0
	v_addc_co_u32_e32 v83, vcc, 0, v11, vcc
	global_load_dwordx4 v[82:85], v[82:83], off offset:320
	v_add_co_u32_e32 v86, vcc, s0, v10
	s_mov_b32 s0, 0xd6000
	s_nop 0
	v_addc_co_u32_e32 v87, vcc, 0, v11, vcc
	global_load_dwordx4 v[86:89], v[86:87], off offset:576
	v_add_co_u32_e32 v10, vcc, s0, v10
	v_lshlrev_b32_e32 v180, 1, v94
	s_nop 0
	v_addc_co_u32_e32 v11, vcc, 0, v11, vcc
	global_load_dwordx4 v[90:93], v[10:11], off offset:832
	v_add_u32_e32 v10, 0x410, v12
	s_waitcnt vmcnt(15)
	ds_write2_b32 v12, v30, v31 offset1:1
	ds_write2_b32 v12, v32, v33 offset0:2 offset1:3
	s_waitcnt vmcnt(14)
	ds_write2_b32 v10, v34, v35 offset1:1
	v_add_u32_e32 v10, 0x418, v12
	ds_write2_b32 v10, v36, v37 offset1:1
	v_add_u32_e32 v10, 0x820, v12
	v_lshl_add_u64 v[8:9], v[8:9], 0, v[180:181]
	v_lshlrev_b32_e32 v180, 1, v6
	v_lshl_add_u64 v[8:9], v[8:9], 0, v[180:181]
	s_mov_b64 s[0:1], 0x680000
	s_waitcnt vmcnt(13)
	ds_write2_b32 v10, v38, v39 offset1:1
	v_add_u32_e32 v10, 0x828, v12
	ds_write2_b32 v10, v40, v41 offset1:1
	v_add_u32_e32 v10, 0xc30, v12
	s_waitcnt vmcnt(12)
	ds_write2_b32 v10, v42, v43 offset1:1
	v_add_u32_e32 v10, 0xc38, v12
	ds_write2_b32 v10, v44, v45 offset1:1
	v_add_u32_e32 v10, 0x1040, v12
	s_waitcnt vmcnt(11)
	ds_write2_b32 v10, v46, v47 offset1:1
	v_add_u32_e32 v10, 0x1048, v12
	ds_write2_b32 v10, v48, v49 offset1:1
	v_add_u32_e32 v10, 0x1450, v12
	s_waitcnt vmcnt(10)
	ds_write2_b32 v10, v50, v51 offset1:1
	v_add_u32_e32 v10, 0x1458, v12
	ds_write2_b32 v10, v52, v53 offset1:1
	v_add_u32_e32 v10, 0x1860, v12
	v_add_u32_e32 v50, 0x400, v14
	v_lshl_add_u64 v[46:47], v[8:9], 0, s[0:1]
	s_waitcnt vmcnt(9)
	ds_write2_b32 v10, v54, v55 offset1:1
	v_add_u32_e32 v10, 0x1868, v12
	ds_write2_b32 v10, v56, v57 offset1:1
	v_add_u32_e32 v10, 0x1c70, v12
	s_waitcnt vmcnt(8)
	ds_write2_b32 v10, v58, v59 offset1:1
	v_add_u32_e32 v10, 0x1c78, v12
	ds_write2_b32 v10, v60, v61 offset1:1
	v_add_u32_e32 v10, 0x2080, v12
	s_waitcnt vmcnt(7)
	ds_write2_b32 v10, v62, v63 offset1:1
	v_add_u32_e32 v10, 0x2088, v12
	ds_write2_b32 v10, v64, v65 offset1:1
	v_add_u32_e32 v10, 0x2490, v12
	s_waitcnt vmcnt(6)
	ds_write2_b32 v10, v66, v67 offset1:1
	v_add_u32_e32 v10, 0x2498, v12
	ds_write2_b32 v10, v68, v69 offset1:1
	v_add_u32_e32 v10, 0x28a0, v12
	s_waitcnt vmcnt(5)
	ds_write2_b32 v10, v70, v71 offset1:1
	v_add_u32_e32 v10, 0x28a8, v12
	ds_write2_b32 v10, v72, v73 offset1:1
	v_add_u32_e32 v10, 0x2cb0, v12
	s_waitcnt vmcnt(4)
	ds_write2_b32 v10, v74, v75 offset1:1
	v_add_u32_e32 v10, 0x2cb8, v12
	ds_write2_b32 v10, v76, v77 offset1:1
	v_add_u32_e32 v10, 0x30c0, v12
	s_waitcnt vmcnt(3)
	ds_write2_b32 v10, v78, v79 offset1:1
	v_add_u32_e32 v10, 0x30c8, v12
	ds_write2_b32 v10, v80, v81 offset1:1
	v_add_u32_e32 v10, 0x34d0, v12
	s_waitcnt vmcnt(2)
	ds_write2_b32 v10, v82, v83 offset1:1
	v_add_u32_e32 v10, 0x34d8, v12
	ds_write2_b32 v10, v84, v85 offset1:1
	v_add_u32_e32 v10, 0x38e0, v12
	s_waitcnt vmcnt(1)
	ds_write2_b32 v10, v86, v87 offset1:1
	v_add_u32_e32 v10, 0x38e8, v12
	ds_write2_b32 v10, v88, v89 offset1:1
	v_add_u32_e32 v10, 0x3cf0, v12
	s_waitcnt vmcnt(0)
	ds_write2_b32 v10, v90, v91 offset1:1
	v_add_u32_e32 v10, 0x3cf8, v12
	ds_write2_b32 v10, v92, v93 offset1:1
	s_waitcnt lgkmcnt(0)
	ds_read2_b32 v[30:31], v14 offset0:65 offset1:73
	ds_read2_b32 v[32:33], v14 offset1:8
	ds_read2_b32 v[34:35], v14 offset0:130 offset1:138
	ds_read2_b32 v[36:37], v14 offset0:195 offset1:203
	ds_read2_b32 v[38:39], v50 offset0:4 offset1:12
	ds_read2_b32 v[40:41], v50 offset0:69 offset1:77
	ds_read2_b32 v[42:43], v50 offset0:134 offset1:142
	ds_read2_b32 v[44:45], v50 offset0:199 offset1:207
	s_waitcnt lgkmcnt(6)
	v_cvt_pk_bf16_f32 v8, v32, v30
	v_or_b32_e32 v30, v29, v13
	v_lshlrev_b32_e32 v180, 11, v30
	s_waitcnt lgkmcnt(4)
	v_cvt_pk_bf16_f32 v9, v34, v36
	s_waitcnt lgkmcnt(2)
	v_cvt_pk_bf16_f32 v10, v38, v40
	s_waitcnt lgkmcnt(0)
	v_cvt_pk_bf16_f32 v11, v42, v44
	v_lshl_add_u64 v[48:49], v[46:47], 0, v[180:181]
	global_store_dwordx4 v[48:49], v[8:11], off sc1
	v_or_b32_e32 v30, v29, v15
	v_lshlrev_b32_e32 v180, 11, v30
	v_cvt_pk_bf16_f32 v8, v33, v31
	v_cvt_pk_bf16_f32 v9, v35, v37
	v_cvt_pk_bf16_f32 v10, v39, v41
	v_cvt_pk_bf16_f32 v11, v43, v45
	ds_read2_b32 v[32:33], v14 offset0:81 offset1:89
	ds_read2_b32 v[34:35], v14 offset0:16 offset1:24
	ds_read2_b32 v[36:37], v14 offset0:146 offset1:154
	ds_read2_b32 v[38:39], v14 offset0:211 offset1:219
	ds_read2_b32 v[40:41], v50 offset0:20 offset1:28
	ds_read2_b32 v[42:43], v50 offset0:85 offset1:93
	ds_read2_b32 v[44:45], v50 offset0:150 offset1:158
	ds_read2_b32 v[48:49], v50 offset0:215 offset1:223
	v_lshl_add_u64 v[30:31], v[46:47], 0, v[180:181]
	global_store_dwordx4 v[30:31], v[8:11], off sc1
	v_or_b32_e32 v30, v29, v16
	v_lshlrev_b32_e32 v180, 11, v30
	s_waitcnt lgkmcnt(6)
	v_cvt_pk_bf16_f32 v8, v34, v32
	s_waitcnt lgkmcnt(4)
	v_cvt_pk_bf16_f32 v9, v36, v38
	s_waitcnt lgkmcnt(2)
	v_cvt_pk_bf16_f32 v10, v40, v42
	s_waitcnt lgkmcnt(0)
	v_cvt_pk_bf16_f32 v11, v44, v48
	v_lshl_add_u64 v[30:31], v[46:47], 0, v[180:181]
	global_store_dwordx4 v[30:31], v[8:11], off sc1
	v_or_b32_e32 v30, v29, v17
	v_lshlrev_b32_e32 v180, 11, v30
	v_cvt_pk_bf16_f32 v8, v35, v33
	v_cvt_pk_bf16_f32 v9, v37, v39
	v_cvt_pk_bf16_f32 v10, v41, v43
	v_cvt_pk_bf16_f32 v11, v45, v49
	ds_read2_b32 v[32:33], v14 offset0:32 offset1:40
	ds_read2_b32 v[34:35], v14 offset0:97 offset1:105
	ds_read2_b32 v[36:37], v14 offset0:162 offset1:170
	ds_read2_b32 v[38:39], v14 offset0:227 offset1:235
	ds_read2_b32 v[40:41], v50 offset0:36 offset1:44
	ds_read2_b32 v[42:43], v50 offset0:101 offset1:109
	ds_read2_b32 v[44:45], v50 offset0:166 offset1:174
	ds_read2_b32 v[48:49], v50 offset0:231 offset1:239
	v_lshl_add_u64 v[30:31], v[46:47], 0, v[180:181]
	global_store_dwordx4 v[30:31], v[8:11], off sc1
	v_or_b32_e32 v30, v29, v18
	v_lshlrev_b32_e32 v180, 11, v30
	s_waitcnt lgkmcnt(6)
	v_cvt_pk_bf16_f32 v8, v32, v34
	s_waitcnt lgkmcnt(4)
	v_cvt_pk_bf16_f32 v9, v36, v38
	s_waitcnt lgkmcnt(2)
	v_cvt_pk_bf16_f32 v10, v40, v42
	s_waitcnt lgkmcnt(0)
	v_cvt_pk_bf16_f32 v11, v44, v48
	v_lshl_add_u64 v[30:31], v[46:47], 0, v[180:181]
	global_store_dwordx4 v[30:31], v[8:11], off sc1
	v_or_b32_e32 v30, v29, v19
	v_lshlrev_b32_e32 v180, 11, v30
	v_cvt_pk_bf16_f32 v8, v33, v35
	v_cvt_pk_bf16_f32 v9, v37, v39
	v_cvt_pk_bf16_f32 v10, v41, v43
	v_cvt_pk_bf16_f32 v11, v45, v49
	ds_read2_b32 v[32:33], v14 offset0:48 offset1:56
	ds_read2_b32 v[34:35], v14 offset0:113 offset1:121
	ds_read2_b32 v[36:37], v14 offset0:178 offset1:186
	ds_read2_b32 v[38:39], v14 offset0:243 offset1:251
	ds_read2_b32 v[40:41], v50 offset0:52 offset1:60
	ds_read2_b32 v[42:43], v50 offset0:117 offset1:125
	ds_read2_b32 v[44:45], v50 offset0:182 offset1:190
	ds_read2_b32 v[48:49], v50 offset0:247 offset1:255
	v_lshl_add_u64 v[30:31], v[46:47], 0, v[180:181]
	global_store_dwordx4 v[30:31], v[8:11], off sc1
	v_or_b32_e32 v30, v29, v20
	v_lshlrev_b32_e32 v180, 11, v30
	v_or_b32_e32 v29, v29, v21
	s_waitcnt lgkmcnt(6)
	v_cvt_pk_bf16_f32 v8, v32, v34
	s_waitcnt lgkmcnt(4)
	v_cvt_pk_bf16_f32 v9, v36, v38
	s_waitcnt lgkmcnt(2)
	v_cvt_pk_bf16_f32 v10, v40, v42
	s_waitcnt lgkmcnt(0)
	v_cvt_pk_bf16_f32 v11, v44, v48
	v_lshl_add_u64 v[30:31], v[46:47], 0, v[180:181]
	v_lshlrev_b32_e32 v180, 11, v29
	global_store_dwordx4 v[30:31], v[8:11], off sc1
	v_lshl_add_u64 v[30:31], v[46:47], 0, v[180:181]
	s_nop 0
	v_cvt_pk_bf16_f32 v8, v33, v35
	v_cvt_pk_bf16_f32 v9, v37, v39
	v_cvt_pk_bf16_f32 v10, v41, v43
	v_cvt_pk_bf16_f32 v11, v45, v49
	global_store_dwordx4 v[30:31], v[8:11], off sc1
	s_waitcnt lgkmcnt(0)

.LBB0_135:
	s_andn2_saveexec_b64 s[10:11], s[10:11]
	s_cbranch_execz .LBB0_116
	s_load_dwordx2 s[0:1], s[80:81], 0x40
	v_mul_i32_i24_e32 v11, 0x4ec5, v30
	v_lshrrev_b32_e32 v29, 31, v11
	v_ashrrev_i32_e32 v11, 20, v11
	v_lshlrev_b32_e32 v180, 2, v4
	s_waitcnt lgkmcnt(0)
	v_mov_b64_e32 v[32:33], s[0:1]
	v_mad_i64_i32 v[32:33], s[0:1], v10, s54, v[32:33]
	v_add_u16_e32 v10, v11, v29
	v_mul_lo_u16_e32 v11, 52, v10
	v_sub_u16_e32 v11, v30, v11
	v_lshlrev_b32_sdwa v94, v246, sext(v10) dst_sel:DWORD dst_unused:UNUSED_PAD src0_sel:DWORD src1_sel:WORD_0
	v_lshlrev_b32_sdwa v10, v246, sext(v11) dst_sel:DWORD dst_unused:UNUSED_PAD src0_sel:DWORD src1_sel:WORD_0
	v_or_b32_e32 v11, v94, v7
	v_mul_i32_i24_e32 v30, 0xe10, v11
	v_ashrrev_i32_e32 v31, 31, v30
	v_lshl_add_u64 v[30:31], v[30:31], 2, v[32:33]
	v_ashrrev_i32_e32 v11, 31, v10
	v_lshl_add_u64 v[30:31], v[10:11], 2, v[30:31]
	v_lshl_add_u64 v[90:91], v[30:31], 0, v[180:181]
	v_add_co_u32_e32 v34, vcc, s73, v90
	s_mov_b32 s0, 0x2a000
	s_nop 0
	v_addc_co_u32_e32 v35, vcc, 0, v91, vcc
	v_add_co_u32_e32 v38, vcc, s71, v90
	global_load_dwordx4 v[30:33], v[90:91], off
	s_nop 0
	global_load_dwordx4 v[34:37], v[34:35], off offset:256
	v_addc_co_u32_e32 v39, vcc, 0, v91, vcc
	v_add_co_u32_e32 v42, vcc, s0, v90
	s_mov_b32 s0, 0x46000
	s_nop 0
	v_addc_co_u32_e32 v43, vcc, 0, v91, vcc
	global_load_dwordx4 v[38:41], v[38:39], off offset:512
	s_nop 0
	global_load_dwordx4 v[42:45], v[42:43], off offset:768
	v_add_co_u32_e32 v46, vcc, s85, v90
	v_add_u32_e32 v11, 0x410, v12
	s_nop 0
	v_addc_co_u32_e32 v47, vcc, 0, v91, vcc
	v_add_co_u32_e32 v50, vcc, s0, v90
	s_mov_b32 s0, 0x54000
	s_nop 0
	v_addc_co_u32_e32 v51, vcc, 0, v91, vcc
	global_load_dwordx4 v[46:49], v[46:47], off offset:1024
	s_nop 0
	global_load_dwordx4 v[50:53], v[50:51], off offset:1280
	v_add_co_u32_e32 v54, vcc, s0, v90
	s_mov_b32 s0, 0x62000
	s_nop 0
	v_addc_co_u32_e32 v55, vcc, 0, v91, vcc
	v_add_co_u32_e32 v58, vcc, s0, v90
	s_mov_b32 s0, 0x7e000
	s_nop 0
	v_addc_co_u32_e32 v59, vcc, 0, v91, vcc
	global_load_dwordx4 v[54:57], v[54:55], off offset:1536
	s_nop 0
	global_load_dwordx4 v[58:61], v[58:59], off offset:1792
	v_add_co_u32_e32 v62, vcc, s82, v90
	v_or_b32_e32 v29, v10, v13
	s_nop 0
	v_addc_co_u32_e32 v63, vcc, 0, v91, vcc
	v_add_co_u32_e32 v66, vcc, s0, v90
	s_mov_b32 s0, 0x8c000
	s_nop 0
	v_addc_co_u32_e32 v67, vcc, 0, v91, vcc
	global_load_dwordx4 v[62:65], v[62:63], off offset:2048
	s_nop 0
	global_load_dwordx4 v[66:69], v[66:67], off offset:2304
	v_add_co_u32_e32 v70, vcc, s0, v90
	s_mov_b32 s0, 0x9a000
	s_nop 0
	v_addc_co_u32_e32 v71, vcc, 0, v91, vcc
	v_add_co_u32_e32 v74, vcc, s0, v90
	s_mov_b32 s0, 0xa8000
	s_nop 0
	v_addc_co_u32_e32 v75, vcc, 0, v91, vcc
	global_load_dwordx4 v[70:73], v[70:71], off offset:2560
	s_nop 0
	global_load_dwordx4 v[74:77], v[74:75], off offset:2816
	v_add_co_u32_e32 v78, vcc, s0, v90
	s_mov_b32 s0, 0xb6000
	s_nop 0
	v_addc_co_u32_e32 v79, vcc, 0, v91, vcc
	global_load_dwordx4 v[78:81], v[78:79], off offset:3072
	v_add_co_u32_e32 v82, vcc, s0, v90
	s_mov_b32 s0, 0xc4000
	s_nop 0
	v_addc_co_u32_e32 v83, vcc, 0, v91, vcc
	global_load_dwordx4 v[82:85], v[82:83], off offset:3328
	v_add_co_u32_e32 v86, vcc, s0, v90
	s_mov_b32 s0, 0xd2000
	s_nop 0
	v_addc_co_u32_e32 v87, vcc, 0, v91, vcc
	global_load_dwordx4 v[86:89], v[86:87], off offset:3584
	v_add_co_u32_e32 v90, vcc, s0, v90
	v_ashrrev_i32_e32 v95, 31, v94
	s_nop 0
	v_addc_co_u32_e32 v91, vcc, 0, v91, vcc
	global_load_dwordx4 v[90:93], v[90:91], off offset:3840
	s_waitcnt vmcnt(15)
	ds_write2_b32 v12, v30, v31 offset1:1
	ds_write2_b32 v12, v32, v33 offset0:2 offset1:3
	s_waitcnt vmcnt(14)
	ds_write2_b32 v11, v34, v35 offset1:1
	v_add_u32_e32 v11, 0x418, v12
	ds_write2_b32 v11, v36, v37 offset1:1
	v_add_u32_e32 v11, 0x820, v12
	v_lshl_add_u64 v[8:9], v[94:95], 1, v[8:9]
	v_lshlrev_b32_e32 v180, 1, v6
	v_lshl_add_u64 v[8:9], v[8:9], 0, v[180:181]
	s_waitcnt vmcnt(13)
	ds_write2_b32 v11, v38, v39 offset1:1
	v_add_u32_e32 v11, 0x828, v12
	ds_write2_b32 v11, v40, v41 offset1:1
	v_add_u32_e32 v11, 0xc30, v12
	s_waitcnt vmcnt(12)
	ds_write2_b32 v11, v42, v43 offset1:1
	v_add_u32_e32 v11, 0xc38, v12
	ds_write2_b32 v11, v44, v45 offset1:1
	v_add_u32_e32 v11, 0x1040, v12
	s_waitcnt vmcnt(11)
	ds_write2_b32 v11, v46, v47 offset1:1
	v_add_u32_e32 v11, 0x1048, v12
	ds_write2_b32 v11, v48, v49 offset1:1
	v_add_u32_e32 v11, 0x1450, v12
	s_waitcnt vmcnt(10)
	ds_write2_b32 v11, v50, v51 offset1:1
	v_add_u32_e32 v11, 0x1458, v12
	ds_write2_b32 v11, v52, v53 offset1:1
	v_add_u32_e32 v11, 0x1860, v12
	v_or_b32_e32 v52, v10, v22
	s_waitcnt vmcnt(9)
	ds_write2_b32 v11, v54, v55 offset1:1
	v_add_u32_e32 v11, 0x1868, v12
	ds_write2_b32 v11, v56, v57 offset1:1
	v_add_u32_e32 v11, 0x1c70, v12
	s_waitcnt vmcnt(8)
	ds_write2_b32 v11, v58, v59 offset1:1
	v_add_u32_e32 v11, 0x1c78, v12
	ds_write2_b32 v11, v60, v61 offset1:1
	v_add_u32_e32 v11, 0x2080, v12
	s_waitcnt vmcnt(7)
	ds_write2_b32 v11, v62, v63 offset1:1
	v_add_u32_e32 v11, 0x2088, v12
	ds_write2_b32 v11, v64, v65 offset1:1
	v_add_u32_e32 v11, 0x2490, v12
	s_waitcnt vmcnt(6)
	ds_write2_b32 v11, v66, v67 offset1:1
	v_add_u32_e32 v11, 0x2498, v12
	ds_write2_b32 v11, v68, v69 offset1:1
	v_add_u32_e32 v11, 0x28a0, v12
	s_waitcnt vmcnt(5)
	ds_write2_b32 v11, v70, v71 offset1:1
	v_add_u32_e32 v11, 0x28a8, v12
	ds_write2_b32 v11, v72, v73 offset1:1
	v_add_u32_e32 v11, 0x2cb0, v12
	s_waitcnt vmcnt(4)
	ds_write2_b32 v11, v74, v75 offset1:1
	v_add_u32_e32 v11, 0x2cb8, v12
	ds_write2_b32 v11, v76, v77 offset1:1
	v_add_u32_e32 v11, 0x30c0, v12
	s_waitcnt vmcnt(3)
	ds_write2_b32 v11, v78, v79 offset1:1
	v_add_u32_e32 v11, 0x30c8, v12
	ds_write2_b32 v11, v80, v81 offset1:1
	v_add_u32_e32 v11, 0x34d0, v12
	s_waitcnt vmcnt(2)
	ds_write2_b32 v11, v82, v83 offset1:1
	v_add_u32_e32 v11, 0x34d8, v12
	ds_write2_b32 v11, v84, v85 offset1:1
	v_add_u32_e32 v11, 0x38e0, v12
	s_waitcnt vmcnt(1)
	ds_write2_b32 v11, v86, v87 offset1:1
	v_add_u32_e32 v11, 0x38e8, v12
	ds_write2_b32 v11, v88, v89 offset1:1
	v_add_u32_e32 v11, 0x3cf0, v12
	s_waitcnt vmcnt(0)
	ds_write2_b32 v11, v90, v91 offset1:1
	v_add_u32_e32 v11, 0x3cf8, v12
	ds_write2_b32 v11, v92, v93 offset1:1
	s_waitcnt lgkmcnt(0)
	ds_read2_b32 v[34:35], v14 offset0:65 offset1:73
	ds_read2_b32 v[36:37], v14 offset1:8
	ds_read2_b32 v[38:39], v14 offset0:130 offset1:138
	ds_read2_b32 v[40:41], v14 offset0:195 offset1:203
	v_add_u32_e32 v11, 0x400, v14
	ds_read2_b32 v[42:43], v11 offset0:4 offset1:12
	ds_read2_b32 v[44:45], v11 offset0:69 offset1:77
	ds_read2_b32 v[46:47], v11 offset0:134 offset1:142
	ds_read2_b32 v[48:49], v11 offset0:199 offset1:207
	s_waitcnt lgkmcnt(6)
	v_cvt_pk_bf16_f32 v30, v36, v34
	v_add_u32_e32 v34, 0xfffffb00, v10
	v_cmp_gt_u32_e32 vcc, s74, v34
	s_waitcnt lgkmcnt(4)
	v_cvt_pk_bf16_f32 v31, v38, v40
	s_waitcnt lgkmcnt(2)
	v_cvt_pk_bf16_f32 v32, v42, v44
	v_cndmask_b32_e32 v50, v29, v52, vcc
	v_ashrrev_i32_e32 v51, 31, v50
	v_lshlrev_b64 v[50:51], 11, v[50:51]
	v_cndmask_b32_e64 v29, 0, 1, vcc
	s_waitcnt lgkmcnt(0)
	v_cvt_pk_bf16_f32 v33, v46, v48
	v_lshl_add_u64 v[50:51], v[8:9], 0, v[50:51]
	v_lshl_or_b32 v34, v15, v29, v10
	global_store_dwordx4 v[50:51], v[30:33], off sc1
	s_nop 1
	v_cvt_pk_bf16_f32 v30, v37, v35
	v_ashrrev_i32_e32 v35, 31, v34
	v_cvt_pk_bf16_f32 v31, v39, v41
	v_cvt_pk_bf16_f32 v32, v43, v45
	v_cvt_pk_bf16_f32 v33, v47, v49
	v_lshlrev_b64 v[34:35], 11, v[34:35]
	ds_read2_b32 v[36:37], v14 offset0:81 offset1:89
	ds_read2_b32 v[38:39], v14 offset0:16 offset1:24
	ds_read2_b32 v[40:41], v14 offset0:146 offset1:154
	ds_read2_b32 v[42:43], v14 offset0:211 offset1:219
	ds_read2_b32 v[44:45], v11 offset0:20 offset1:28
	ds_read2_b32 v[46:47], v11 offset0:85 offset1:93
	ds_read2_b32 v[48:49], v11 offset0:150 offset1:158
	ds_read2_b32 v[50:51], v11 offset0:215 offset1:223
	v_lshl_add_u64 v[34:35], v[8:9], 0, v[34:35]
	global_store_dwordx4 v[34:35], v[30:33], off sc1
	v_lshl_or_b32 v34, v16, v29, v10
	v_ashrrev_i32_e32 v35, 31, v34
	v_lshlrev_b64 v[34:35], 11, v[34:35]
	s_waitcnt lgkmcnt(6)
	v_cvt_pk_bf16_f32 v30, v38, v36
	s_waitcnt lgkmcnt(4)
	v_cvt_pk_bf16_f32 v31, v40, v42
	s_waitcnt lgkmcnt(2)
	v_cvt_pk_bf16_f32 v32, v44, v46
	s_waitcnt lgkmcnt(0)
	v_cvt_pk_bf16_f32 v33, v48, v50
	v_lshl_add_u64 v[34:35], v[8:9], 0, v[34:35]
	global_store_dwordx4 v[34:35], v[30:33], off sc1
	v_lshl_or_b32 v34, v17, v29, v10
	v_ashrrev_i32_e32 v35, 31, v34
	v_lshlrev_b64 v[34:35], 11, v[34:35]
	v_cvt_pk_bf16_f32 v30, v39, v37
	v_cvt_pk_bf16_f32 v31, v41, v43
	v_cvt_pk_bf16_f32 v32, v45, v47
	v_cvt_pk_bf16_f32 v33, v49, v51
	v_lshl_add_u64 v[34:35], v[8:9], 0, v[34:35]
	ds_read2_b32 v[36:37], v14 offset0:32 offset1:40
	ds_read2_b32 v[38:39], v14 offset0:97 offset1:105
	ds_read2_b32 v[40:41], v14 offset0:162 offset1:170
	ds_read2_b32 v[42:43], v14 offset0:227 offset1:235
	ds_read2_b32 v[44:45], v11 offset0:36 offset1:44
	ds_read2_b32 v[46:47], v11 offset0:101 offset1:109
	ds_read2_b32 v[48:49], v11 offset0:166 offset1:174
	ds_read2_b32 v[50:51], v11 offset0:231 offset1:239
	global_store_dwordx4 v[34:35], v[30:33], off sc1
	v_or_b32_e32 v29, v10, v18
	v_or_b32_e32 v34, 1, v52
	v_cndmask_b32_e32 v34, v29, v34, vcc
	v_ashrrev_i32_e32 v35, 31, v34
	v_lshlrev_b64 v[34:35], 11, v[34:35]
	s_waitcnt lgkmcnt(6)
	v_cvt_pk_bf16_f32 v30, v36, v38
	s_waitcnt lgkmcnt(4)
	v_cvt_pk_bf16_f32 v31, v40, v42
	s_waitcnt lgkmcnt(2)
	v_cvt_pk_bf16_f32 v32, v44, v46
	s_waitcnt lgkmcnt(0)
	v_cvt_pk_bf16_f32 v33, v48, v50
	v_lshl_add_u64 v[34:35], v[8:9], 0, v[34:35]
	v_cndmask_b32_e32 v29, v19, v23, vcc
	global_store_dwordx4 v[34:35], v[30:33], off sc1
	v_or_b32_e32 v34, v29, v10
	v_ashrrev_i32_e32 v35, 31, v34
	v_cvt_pk_bf16_f32 v30, v37, v39
	v_cvt_pk_bf16_f32 v31, v41, v43
	v_cvt_pk_bf16_f32 v32, v45, v47
	v_cvt_pk_bf16_f32 v33, v49, v51
	v_lshlrev_b64 v[34:35], 11, v[34:35]
	ds_read2_b32 v[36:37], v14 offset0:48 offset1:56
	ds_read2_b32 v[38:39], v14 offset0:113 offset1:121
	ds_read2_b32 v[40:41], v14 offset0:178 offset1:186
	ds_read2_b32 v[42:43], v14 offset0:243 offset1:251
	ds_read2_b32 v[44:45], v11 offset0:52 offset1:60
	ds_read2_b32 v[46:47], v11 offset0:117 offset1:125
	ds_read2_b32 v[48:49], v11 offset0:182 offset1:190
	ds_read2_b32 v[50:51], v11 offset0:247 offset1:255
	v_lshl_add_u64 v[34:35], v[8:9], 0, v[34:35]
	v_cndmask_b32_e32 v11, v20, v24, vcc
	global_store_dwordx4 v[34:35], v[30:33], off sc1
	v_or_b32_e32 v34, v11, v10
	v_cndmask_b32_e32 v11, v21, v25, vcc
	v_ashrrev_i32_e32 v35, 31, v34
	v_or_b32_e32 v10, v11, v10
	v_lshlrev_b64 v[34:35], 11, v[34:35]
	v_ashrrev_i32_e32 v11, 31, v10
	s_waitcnt lgkmcnt(6)
	v_cvt_pk_bf16_f32 v30, v36, v38
	s_waitcnt lgkmcnt(4)
	v_cvt_pk_bf16_f32 v31, v40, v42
	s_waitcnt lgkmcnt(2)
	v_cvt_pk_bf16_f32 v32, v44, v46
	s_waitcnt lgkmcnt(0)
	v_cvt_pk_bf16_f32 v33, v48, v50
	v_lshl_add_u64 v[34:35], v[8:9], 0, v[34:35]
	v_lshlrev_b64 v[10:11], 11, v[10:11]
	global_store_dwordx4 v[34:35], v[30:33], off sc1
	v_lshl_add_u64 v[8:9], v[8:9], 0, v[10:11]
	s_nop 0
	v_cvt_pk_bf16_f32 v30, v37, v39
	v_cvt_pk_bf16_f32 v31, v41, v43
	v_cvt_pk_bf16_f32 v32, v45, v47
	v_cvt_pk_bf16_f32 v33, v49, v51
	global_store_dwordx4 v[8:9], v[30:33], off sc1
	s_waitcnt lgkmcnt(0)
	s_branch .LBB0_116

.LBB0_151:
	ds_read2st64_b32 v[10:11], v8 offset0:144 offset1:153
	v_cmp_lt_i32_e32 vcc, 63, v9
	s_or_b64 s[12:13], vcc, s[12:13]
	s_waitcnt lgkmcnt(0)
	v_add_f32_e32 v10, 0, v10
	v_add_f32_e32 v12, v10, v11
	ds_read2st64_b32 v[10:11], v8 offset0:162 offset1:171
	s_waitcnt lgkmcnt(0)
	v_add_f32_e32 v10, v12, v10
	v_add_f32_e32 v12, v10, v11
	ds_read2st64_b32 v[10:11], v8 offset0:180 offset1:189
	s_waitcnt lgkmcnt(0)
	v_add_f32_e32 v10, v12, v10
	v_add_f32_e32 v12, v10, v11
	ds_read2st64_b32 v[10:11], v8 offset0:198 offset1:207
	s_waitcnt lgkmcnt(0)
	v_add_f32_e32 v10, v12, v10
	v_add_f32_e32 v12, v10, v11
	ds_read2st64_b32 v[10:11], v8 offset0:216 offset1:225
	s_waitcnt lgkmcnt(0)
	v_add_f32_e32 v10, v12, v10
	v_add_f32_e32 v12, v10, v11
	ds_read2st64_b32 v[10:11], v8 offset0:234 offset1:243
	s_waitcnt lgkmcnt(0)
	v_add_f32_e32 v10, v12, v10
	v_add_f32_e32 v10, v10, v11
	ds_read_b32 v11, v8 offset:64512
	global_load_dword v12, v[4:5], off
	s_waitcnt lgkmcnt(0)
	v_add_f32_e32 v10, v10, v11
	v_add_u32_e32 v11, 0x10500, v8
	ds_read_b32 v11, v11
	s_waitcnt lgkmcnt(0)
	v_add_f32_e32 v10, v10, v11
	v_add_u32_e32 v11, 0x10e00, v8
	ds_read_b32 v11, v11
	s_waitcnt lgkmcnt(0)
	v_add_f32_e32 v10, v10, v11
	v_add_u32_e32 v11, 0x11700, v8
	ds_read_b32 v11, v11
	s_waitcnt lgkmcnt(0)
	v_add_f32_e32 v10, v10, v11
	v_add_u32_e32 v11, 0x12000, v8
	ds_read_b32 v11, v11
	s_waitcnt lgkmcnt(0)
	v_add_f32_e32 v10, v10, v11
	v_add_u32_e32 v11, 0x12900, v8
	ds_read_b32 v11, v11
	s_waitcnt lgkmcnt(0)
	v_add_f32_e32 v10, v10, v11
	v_add_u32_e32 v11, 0x13200, v8
	ds_read_b32 v11, v11
	s_waitcnt lgkmcnt(0)
	v_add_f32_e32 v10, v10, v11
	v_add_u32_e32 v11, 0x13b00, v8
	ds_read_b32 v11, v11
	s_waitcnt lgkmcnt(0)
	v_add_f32_e32 v10, v10, v11
	v_add_u32_e32 v11, 0x14400, v8
	ds_read_b32 v11, v11
	s_waitcnt lgkmcnt(0)
	v_add_f32_e32 v10, v10, v11
	v_add_u32_e32 v11, 0x14d00, v8
	ds_read_b32 v11, v11
	s_waitcnt lgkmcnt(0)
	v_add_f32_e32 v10, v10, v11
	v_add_u32_e32 v11, 0x15600, v8
	ds_read_b32 v11, v11
	s_waitcnt lgkmcnt(0)
	v_add_f32_e32 v10, v10, v11
	v_add_u32_e32 v11, 0x15f00, v8
	ds_read_b32 v11, v11
	s_waitcnt lgkmcnt(0)
	v_add_f32_e32 v10, v10, v11
	v_add_u32_e32 v11, 0x16800, v8
	ds_read_b32 v11, v11
	s_waitcnt lgkmcnt(0)
	v_add_f32_e32 v10, v10, v11
	v_add_u32_e32 v11, 0x17100, v8
	ds_read_b32 v11, v11
	s_waitcnt lgkmcnt(0)
	v_add_f32_e32 v10, v10, v11
	v_add_u32_e32 v11, 0x17a00, v8
	ds_read_b32 v11, v11
	s_waitcnt lgkmcnt(0)
	v_add_f32_e32 v10, v10, v11
	v_add_u32_e32 v11, 0x18300, v8
	ds_read_b32 v11, v11
	s_waitcnt lgkmcnt(0)
	v_add_f32_e32 v10, v10, v11
	v_add_u32_e32 v11, 0x18c00, v8
	ds_read_b32 v11, v11
	s_waitcnt lgkmcnt(0)
	v_add_f32_e32 v10, v10, v11
	v_add_u32_e32 v11, 0x19500, v8
	ds_read_b32 v11, v11
	s_waitcnt lgkmcnt(0)
	v_add_f32_e32 v10, v10, v11
	v_add_u32_e32 v11, 0x19e00, v8
	ds_read_b32 v11, v11
	s_waitcnt lgkmcnt(0)
	v_add_f32_e32 v10, v10, v11
	v_add_u32_e32 v11, 0x1a700, v8
	ds_read_b32 v11, v11
	v_add_u32_e32 v8, 0x800, v8
	s_waitcnt lgkmcnt(0)
	v_add_f32_e32 v11, v10, v11
	v_ashrrev_i32_e32 v10, 6, v9
	s_waitcnt vmcnt(0)
	v_add_f32_e32 v14, v11, v12
	v_ashrrev_i32_e32 v11, 31, v10
	v_lshl_add_u64 v[10:11], s[16:17], 0, v[10:11]
	v_mad_u64_u32 v[12:13], s[0:1], v10, s46, v[6:7]
	v_mov_b32_e32 v10, v13
	v_mad_u64_u32 v[10:11], s[0:1], v11, s46, v[10:11]
	v_mov_b32_e32 v13, v10
	v_add_u32_e32 v10, 0x200, v9
	v_mov_b32_e32 v9, v10
	global_store_dword v[12:13], v14, off sc1
	s_andn2_b64 exec, exec, s[12:13]
	s_cbranch_execnz .LBB0_151
	s_branch .LBB0_146

.LBB0_161:
	s_or_b64 exec, exec, s[8:9]
	v_pk_mul_f32 v[68:69], v[58:59], v[58:59]
	v_pk_mul_f32 v[70:71], v[56:57], v[56:57]
	v_mov_b32_e32 v67, v181
	v_pk_mov_b32 v[76:77], v[70:71], v[68:69] op_sel:[1,0]
	v_mov_b32_e32 v71, v69
	v_pk_add_f32 v[68:69], v[76:77], v[70:71]
	v_pk_mul_f32 v[70:71], v[52:53], v[52:53]
	v_pk_add_f32 v[68:69], v[68:69], v[68:69] op_sel_hi:[0,1]
	v_pk_mul_f32 v[76:77], v[54:55], v[54:55]
	v_mul_f32_e32 v68, v48, v48
	v_pk_mov_b32 v[78:79], v[76:77], v[70:71] op_sel:[1,0]
	v_mov_b32_e32 v77, v71
	v_pk_add_f32 v[70:71], v[78:79], v[76:77]
	v_pk_fma_f32 v[76:77], v[48:49], v[48:49], v[68:69] op_sel_hi:[1,1,0]
	v_mul_f32_e32 v68, v50, v50
	v_pk_add_f32 v[70:71], v[70:71], v[70:71] op_sel_hi:[0,1]
	v_pk_fma_f32 v[78:79], v[50:51], v[50:51], v[68:69] op_sel_hi:[1,1,0]
	v_mul_f32_e32 v76, v44, v44
	v_mul_f32_e32 v78, v45, v45
	v_mul_f32_e32 v68, v46, v46
	v_mul_f32_e32 v70, v47, v47
	v_pk_add_f32 v[76:77], v[76:77], v[78:79]
	v_pk_add_f32 v[68:69], v[68:69], v[70:71]
	v_lshlrev_b32_e32 v180, 3, v60
	v_pk_add_f32 v[68:69], v[76:77], v[68:69]
	v_lshl_add_u64 v[70:71], s[22:23], 0, v[30:31]
	v_add_f32_e32 v43, v68, v69
	s_nop 1
	v_add_f32_dpp v43, v43, v43 row_shr:1 row_mask:0xf bank_mask:0xf bound_ctrl:1
	s_nop 1
	v_add_f32_dpp v43, v43, v43 row_shr:2 row_mask:0xf bank_mask:0xf bound_ctrl:1
	s_nop 1
	v_add_f32_dpp v43, v43, v43 row_shr:4 row_mask:0xf bank_mask:0xf bound_ctrl:1
	s_nop 1
	v_add_f32_dpp v43, v43, v43 row_shr:8 row_mask:0xf bank_mask:0xf bound_ctrl:1
	s_nop 1
	v_mov_b32_dpp v67, v43 row_bcast:15 row_mask:0xa bank_mask:0xf
	v_add_f32_e32 v43, v43, v67
	v_mov_b32_e32 v67, v181
	s_nop 1
	v_mov_b32_dpp v67, v43 row_bcast:31 row_mask:0xc bank_mask:0xf
	v_add_f32_e32 v43, v43, v67
	s_nop 0
	v_readlane_b32 s0, v43, 63
	s_nop 1
	v_fma_f32 v43, s0, v247, v237
	v_rsq_f32_e32 v68, v43
	s_nop 0
	v_pk_mul_f32 v[56:57], v[68:69], v[56:57] op_sel_hi:[0,1]
	v_pk_mul_f32 v[58:59], v[68:69], v[58:59] op_sel_hi:[0,1]
	s_waitcnt lgkmcnt(0)
	v_pk_fma_f32 v[6:7], v[6:7], v[58:59], v[10:11]
	v_pk_fma_f32 v[4:5], v[4:5], v[56:57], v[8:9]
	v_pk_mul_f32 v[76:77], v[54:55], v[68:69] op_sel_hi:[1,0]
	v_cvt_pk_bf16_f32 v4, v4, v5
	v_cvt_pk_bf16_f32 v5, v6, v7
	v_lshl_add_u64 v[6:7], v[70:71], 0, v[180:181]
	global_store_dwordx2 v[6:7], v[4:5], off sc1
	v_lshl_add_u32 v4, v42, 4, v73
	ds_read_b128 v[4:7], v4 offset:40960
	ds_read_b128 v[8:11], v66 offset:46080
	v_pk_mul_f32 v[78:79], v[52:53], v[68:69] op_sel_hi:[1,0]
	v_lshl_add_u32 v42, v40, 4, v73
	ds_read_b128 v[52:55], v42 offset:40960
	s_waitcnt lgkmcnt(1)
	v_pk_fma_f32 v[6:7], v[6:7], v[78:79], v[10:11]
	v_pk_fma_f32 v[4:5], v[4:5], v[76:77], v[8:9]
	v_cvt_pk_bf16_f32 v9, v6, v7
	v_cvt_pk_bf16_f32 v8, v4, v5
	ds_read_b128 v[4:7], v66 offset:47104
	v_lshl_add_u32 v42, v62, 4, v73
	v_lshl_add_u64 v[10:11], v[64:65], 3, v[70:71]
	ds_read_b128 v[56:59], v42 offset:40960
	global_store_dwordx2 v[10:11], v[8:9], off sc1
	ds_read_b128 v[8:11], v66 offset:48128
	v_pk_mul_f32 v[42:43], v[48:49], v[68:69] op_sel_hi:[1,0]
	v_pk_mul_f32 v[48:49], v[50:51], v[68:69] op_sel_hi:[1,0]
	s_waitcnt lgkmcnt(2)
	v_pk_fma_f32 v[4:5], v[52:53], v[42:43], v[4:5]
	v_pk_fma_f32 v[6:7], v[54:55], v[48:49], v[6:7]
	v_cvt_pk_bf16_f32 v4, v4, v5
	v_cvt_pk_bf16_f32 v5, v6, v7
	v_lshl_add_u64 v[6:7], v[40:41], 3, v[70:71]
	global_store_dwordx2 v[6:7], v[4:5], off sc1
	v_pk_mul_f32 v[4:5], v[44:45], v[68:69] op_sel_hi:[1,0]
	v_pk_mul_f32 v[6:7], v[46:47], v[68:69] op_sel_hi:[1,0]
	s_waitcnt lgkmcnt(0)
	v_pk_fma_f32 v[4:5], v[4:5], v[56:57], v[8:9]
	v_pk_fma_f32 v[6:7], v[6:7], v[58:59], v[10:11]
	v_cvt_pk_bf16_f32 v4, v4, v5
	v_cvt_pk_bf16_f32 v5, v6, v7
	v_lshl_add_u64 v[6:7], v[62:63], 3, v[70:71]
	v_mov_b32_e32 v43, v61
	global_store_dwordx2 v[6:7], v[4:5], off sc1

.LBB0_169:
	s_or_b64 exec, exec, s[6:7]
	s_waitcnt vmcnt(3)
	v_and_b32_e32 v57, 0xffff0000, v13
	v_and_b32_e32 v56, 0xffff0000, v12
	v_lshlrev_b32_e32 v55, 16, v13
	v_lshlrev_b32_e32 v54, 16, v12
	v_pk_mul_f32 v[70:71], v[56:57], v[56:57]
	s_waitcnt vmcnt(2)
	v_and_b32_e32 v61, 0xffff0000, v15
	v_and_b32_e32 v60, 0xffff0000, v14
	v_pk_fma_f32 v[70:71], v[54:55], v[54:55], v[70:71]
	v_lshlrev_b32_e32 v59, 16, v15
	v_lshlrev_b32_e32 v58, 16, v14
	s_waitcnt vmcnt(1)
	v_lshlrev_b32_e32 v62, 16, v16
	v_and_b32_e32 v63, 0xffff0000, v16
	v_lshlrev_b32_e32 v64, 16, v17
	s_waitcnt vmcnt(0)
	v_lshlrev_b32_e32 v66, 16, v18
	v_pk_add_f32 v[70:71], v[70:71], v[70:71] op_sel_hi:[0,1]
	v_pk_mul_f32 v[74:75], v[60:61], v[60:61]
	v_and_b32_e32 v65, 0xffff0000, v17
	v_pk_fma_f32 v[74:75], v[58:59], v[58:59], v[74:75]
	v_mul_f32_e32 v67, v62, v62
	v_mul_f32_e32 v77, v63, v63
	v_mul_f32_e32 v70, v64, v64
	v_mov_b32_e32 v76, v66
	v_and_b32_e32 v82, 0xffff0000, v18
	v_lshlrev_b32_e32 v68, 16, v19
	v_and_b32_e32 v69, 0xffff0000, v19
	v_pk_add_f32 v[74:75], v[74:75], v[74:75] op_sel_hi:[0,1]
	v_pk_fma_f32 v[78:79], v[64:65], v[64:65], v[70:71] op_sel_hi:[1,1,0]
	v_pk_add_f32 v[76:77], v[66:67], v[76:77]
	v_mul_f32_e32 v78, v82, v82
	v_mul_f32_e32 v74, v68, v68
	v_mul_f32_e32 v70, v69, v69
	v_mul_f32_e32 v80, v66, v66
	v_mov_b32_e32 v81, v77
	v_pk_add_f32 v[76:77], v[80:81], v[78:79]
	v_pk_add_f32 v[70:71], v[74:75], v[70:71]
	v_mov_b32_e32 v49, v181
	v_pk_add_f32 v[70:71], v[76:77], v[70:71]
	v_mov_b32_e32 v74, v54
	v_add_f32_e32 v45, v70, v71
	v_mov_b32_e32 v75, v56
	v_mov_b32_e32 v56, v55
	v_add_f32_dpp v45, v45, v45 row_shr:1 row_mask:0xf bank_mask:0xf bound_ctrl:1
	v_lshlrev_b32_e32 v180, 3, v44
	v_mov_b32_e32 v67, v82
	v_add_f32_dpp v45, v45, v45 row_shr:2 row_mask:0xf bank_mask:0xf bound_ctrl:1
	s_nop 1
	v_add_f32_dpp v45, v45, v45 row_shr:4 row_mask:0xf bank_mask:0xf bound_ctrl:1
	s_nop 1
	v_add_f32_dpp v45, v45, v45 row_shr:8 row_mask:0xf bank_mask:0xf bound_ctrl:1
	s_nop 1
	v_mov_b32_dpp v49, v45 row_bcast:15 row_mask:0xa bank_mask:0xf
	v_add_f32_e32 v45, v45, v49
	v_mov_b32_e32 v49, v181
	s_nop 1
	v_mov_b32_dpp v49, v45 row_bcast:31 row_mask:0xc bank_mask:0xf
	v_add_f32_e32 v45, v45, v49
	s_nop 0
	v_readlane_b32 s0, v45, 63
	s_nop 1
	v_fma_f32 v45, s0, v247, v237
	v_rsq_f32_e32 v70, v45
	v_lshl_add_u64 v[44:45], s[22:23], 0, v[28:29]
	v_pk_mul_f32 v[74:75], v[70:71], v[74:75] op_sel_hi:[0,1]
	v_pk_mul_f32 v[54:55], v[70:71], v[56:57] op_sel_hi:[0,1]
	s_waitcnt lgkmcnt(0)
	v_pk_fma_f32 v[6:7], v[6:7], v[54:55], v[10:11]
	v_pk_fma_f32 v[4:5], v[4:5], v[74:75], v[8:9]
	s_nop 0
	v_cvt_pk_bf16_f32 v4, v4, v5
	v_cvt_pk_bf16_f32 v5, v6, v7
	v_lshl_add_u64 v[6:7], v[44:45], 0, v[180:181]
	global_store_dwordx2 v[6:7], v[4:5], off sc1
	v_mov_b32_e32 v4, v58
	v_mov_b32_e32 v5, v60
	v_pk_mul_f32 v[74:75], v[70:71], v[4:5] op_sel_hi:[0,1]
	v_lshl_add_u32 v4, v48, 4, v73
	ds_read_b128 v[4:7], v4 offset:40960
	ds_read_b128 v[8:11], v41 offset:46080
	v_mov_b32_e32 v60, v59
	v_pk_mul_f32 v[76:77], v[70:71], v[60:61] op_sel_hi:[0,1]
	v_lshl_add_u32 v48, v46, 4, v73
	ds_read_b128 v[54:57], v48 offset:40960
	s_waitcnt lgkmcnt(1)
	v_pk_fma_f32 v[6:7], v[6:7], v[76:77], v[10:11]
	v_pk_fma_f32 v[4:5], v[4:5], v[74:75], v[8:9]
	v_cvt_pk_bf16_f32 v9, v6, v7
	v_cvt_pk_bf16_f32 v8, v4, v5
	ds_read_b128 v[4:7], v41 offset:47104
	v_lshl_add_u32 v48, v50, 4, v73
	v_lshl_add_u64 v[10:11], v[52:53], 3, v[44:45]
	ds_read_b128 v[58:61], v48 offset:40960
	global_store_dwordx2 v[10:11], v[8:9], off sc1
	ds_read_b128 v[8:11], v41 offset:48128
	v_pk_mul_f32 v[48:49], v[70:71], v[62:63] op_sel_hi:[0,1]
	v_pk_mul_f32 v[52:53], v[70:71], v[64:65] op_sel_hi:[0,1]
	s_waitcnt lgkmcnt(2)
	v_pk_fma_f32 v[6:7], v[56:57], v[52:53], v[6:7]
	v_pk_fma_f32 v[4:5], v[54:55], v[48:49], v[4:5]
	v_add_u32_e32 v74, 3, v40
	v_cvt_pk_bf16_f32 v4, v4, v5
	v_cvt_pk_bf16_f32 v5, v6, v7
	v_lshl_add_u64 v[6:7], v[46:47], 3, v[44:45]
	global_store_dwordx2 v[6:7], v[4:5], off sc1
	v_pk_mul_f32 v[4:5], v[70:71], v[66:67] op_sel_hi:[0,1]
	v_pk_mul_f32 v[6:7], v[70:71], v[68:69] op_sel_hi:[0,1]
	s_waitcnt lgkmcnt(0)
	v_pk_fma_f32 v[6:7], v[6:7], v[60:61], v[10:11]
	v_pk_fma_f32 v[4:5], v[4:5], v[58:59], v[8:9]
	v_cmp_lt_i32_e64 s[8:9], v74, v72
	v_cvt_pk_bf16_f32 v4, v4, v5
	v_cvt_pk_bf16_f32 v5, v6, v7
	v_lshl_add_u64 v[6:7], v[50:51], 3, v[44:45]
	v_cmp_ge_i32_e64 s[6:7], v74, v72
	global_store_dwordx2 v[6:7], v[4:5], off sc1
	s_and_saveexec_b64 s[4:5], s[8:9]
	s_cbranch_execz .LBB0_171
	v_mov_b32_e32 v4, v186
	s_nop 0
	v_and_b32_e32 v6, 63, v4
	v_add_u32_e32 v4, 0xfffff803, v40
	v_ashrrev_i32_e32 v5, 31, v4
	v_lshlrev_b64 v[4:5], 12, v[4:5]
	v_lshl_add_u64 v[4:5], s[10:11], 0, v[4:5]
	v_lshlrev_b32_e32 v180, 3, v6
	v_lshl_add_u64 v[4:5], v[4:5], 0, v[180:181]
	global_load_dwordx2 v[12:13], v[4:5], off
	global_load_dwordx2 v[14:15], v[4:5], off offset:512
	global_load_dwordx2 v[16:17], v[4:5], off offset:1024
	global_load_dwordx2 v[18:19], v[4:5], off offset:1536

.LBB0_176:
	s_or_b64 exec, exec, s[8:9]
	v_pk_mul_f32 v[76:77], v[60:61], v[60:61]
	v_pk_mul_f32 v[78:79], v[58:59], v[58:59]
	v_mov_b32_e32 v57, v181
	v_pk_mov_b32 v[80:81], v[78:79], v[76:77] op_sel:[1,0]
	v_mov_b32_e32 v79, v77
	v_pk_add_f32 v[76:77], v[80:81], v[78:79]
	v_pk_mul_f32 v[78:79], v[52:53], v[52:53]
	v_pk_add_f32 v[76:77], v[76:77], v[76:77] op_sel_hi:[0,1]
	v_pk_mul_f32 v[80:81], v[54:55], v[54:55]
	v_mul_f32_e32 v76, v48, v48
	v_pk_mov_b32 v[82:83], v[80:81], v[78:79] op_sel:[1,0]
	v_mov_b32_e32 v81, v79
	v_pk_add_f32 v[78:79], v[82:83], v[80:81]
	v_pk_fma_f32 v[80:81], v[48:49], v[48:49], v[76:77] op_sel_hi:[1,1,0]
	v_mul_f32_e32 v76, v50, v50
	v_pk_add_f32 v[78:79], v[78:79], v[78:79] op_sel_hi:[0,1]
	v_pk_fma_f32 v[82:83], v[50:51], v[50:51], v[76:77] op_sel_hi:[1,1,0]
	v_mul_f32_e32 v80, v44, v44
	v_mul_f32_e32 v82, v45, v45
	v_mul_f32_e32 v76, v46, v46
	v_mul_f32_e32 v78, v47, v47
	v_pk_add_f32 v[80:81], v[80:81], v[82:83]
	v_pk_add_f32 v[76:77], v[76:77], v[78:79]
	v_lshlrev_b32_e32 v180, 3, v62
	v_pk_add_f32 v[76:77], v[80:81], v[76:77]
	s_nop 0
	v_add_f32_e32 v43, v76, v77
	s_nop 1
	v_add_f32_dpp v43, v43, v43 row_shr:1 row_mask:0xf bank_mask:0xf bound_ctrl:1
	s_nop 1
	v_add_f32_dpp v43, v43, v43 row_shr:2 row_mask:0xf bank_mask:0xf bound_ctrl:1
	s_nop 1
	v_add_f32_dpp v43, v43, v43 row_shr:4 row_mask:0xf bank_mask:0xf bound_ctrl:1
	s_nop 1
	v_add_f32_dpp v43, v43, v43 row_shr:8 row_mask:0xf bank_mask:0xf bound_ctrl:1
	s_nop 1
	v_mov_b32_dpp v57, v43 row_bcast:15 row_mask:0xa bank_mask:0xf
	v_add_f32_e32 v43, v43, v57
	v_mov_b32_e32 v57, v181
	s_nop 1
	v_mov_b32_dpp v57, v43 row_bcast:31 row_mask:0xc bank_mask:0xf
	v_add_f32_e32 v43, v43, v57
	v_ashrrev_i32_e32 v57, 31, v56
	v_readlane_b32 s0, v43, 63
	v_lshlrev_b64 v[56:57], 11, v[56:57]
	s_nop 0
	v_fma_f32 v43, s0, v247, v237
	v_rsq_f32_e32 v76, v43
	v_lshl_add_u32 v43, v64, 4, v73
	v_pk_mul_f32 v[58:59], v[76:77], v[58:59] op_sel_hi:[0,1]
	v_pk_mul_f32 v[60:61], v[76:77], v[60:61] op_sel_hi:[0,1]
	s_waitcnt lgkmcnt(0)
	v_pk_fma_f32 v[6:7], v[6:7], v[60:61], v[10:11]
	v_pk_fma_f32 v[4:5], v[4:5], v[58:59], v[8:9]
	v_lshl_add_u64 v[60:61], s[18:19], 0, v[56:57]
	v_cvt_pk_bf16_f32 v4, v4, v5
	v_cvt_pk_bf16_f32 v5, v6, v7
	v_lshl_add_u64 v[6:7], v[60:61], 0, v[180:181]
	global_store_dwordx2 v[6:7], v[4:5], off sc1
	v_lshl_add_u32 v4, v66, 4, v73
	ds_read_b128 v[4:7], v4 offset:40960
	ds_read_b128 v[8:11], v63 offset:46080
	v_pk_mul_f32 v[78:79], v[54:55], v[76:77] op_sel_hi:[1,0]
	v_pk_mul_f32 v[80:81], v[52:53], v[76:77] op_sel_hi:[1,0]
	ds_read_b128 v[52:55], v43 offset:40960
	v_pk_mul_f32 v[48:49], v[48:49], v[76:77] op_sel_hi:[1,0]
	s_waitcnt lgkmcnt(1)
	v_pk_fma_f32 v[6:7], v[6:7], v[80:81], v[10:11]
	v_pk_fma_f32 v[4:5], v[4:5], v[78:79], v[8:9]
	v_cvt_pk_bf16_f32 v9, v6, v7
	v_cvt_pk_bf16_f32 v8, v4, v5
	ds_read_b128 v[4:7], v63 offset:47104
	v_lshl_add_u32 v43, v68, 4, v73
	v_lshl_add_u64 v[10:11], v[70:71], 3, v[60:61]
	ds_read_b128 v[56:59], v43 offset:40960
	global_store_dwordx2 v[10:11], v[8:9], off sc1
	ds_read_b128 v[8:11], v63 offset:48128
	v_pk_mul_f32 v[50:51], v[50:51], v[76:77] op_sel_hi:[1,0]
	s_waitcnt lgkmcnt(2)
	v_pk_fma_f32 v[4:5], v[52:53], v[48:49], v[4:5]
	v_pk_fma_f32 v[6:7], v[54:55], v[50:51], v[6:7]
	v_cvt_pk_bf16_f32 v4, v4, v5
	v_cvt_pk_bf16_f32 v5, v6, v7
	v_lshl_add_u64 v[6:7], v[64:65], 3, v[60:61]
	global_store_dwordx2 v[6:7], v[4:5], off sc1
	v_pk_mul_f32 v[4:5], v[44:45], v[76:77] op_sel_hi:[1,0]
	v_pk_mul_f32 v[6:7], v[46:47], v[76:77] op_sel_hi:[1,0]
	s_waitcnt lgkmcnt(0)
	v_pk_fma_f32 v[4:5], v[4:5], v[56:57], v[8:9]
	v_pk_fma_f32 v[6:7], v[6:7], v[58:59], v[10:11]
	v_cvt_pk_bf16_f32 v4, v4, v5
	v_cvt_pk_bf16_f32 v5, v6, v7
	v_lshl_add_u64 v[6:7], v[68:69], 3, v[60:61]
	v_mov_b32_e32 v43, v41
	global_store_dwordx2 v[6:7], v[4:5], off sc1

.LBB0_196:
	s_or_b64 exec, exec, s[16:17]
	v_pk_mul_f32 v[62:63], v[52:53], v[52:53]
	v_pk_mul_f32 v[64:65], v[50:51], v[50:51]
	v_lshlrev_b32_e32 v180, 3, v54
	v_pk_mov_b32 v[68:69], v[64:65], v[62:63] op_sel:[1,0]
	v_mov_b32_e32 v65, v63
	v_pk_add_f32 v[62:63], v[68:69], v[64:65]
	v_pk_mul_f32 v[64:65], v[46:47], v[46:47]
	v_pk_add_f32 v[62:63], v[62:63], v[62:63] op_sel_hi:[0,1]
	v_pk_mul_f32 v[68:69], v[48:49], v[48:49]
	v_mul_f32_e32 v62, v42, v42
	v_pk_mov_b32 v[70:71], v[68:69], v[64:65] op_sel:[1,0]
	v_mov_b32_e32 v69, v65
	v_pk_add_f32 v[64:65], v[70:71], v[68:69]
	v_pk_fma_f32 v[68:69], v[42:43], v[42:43], v[62:63] op_sel_hi:[1,1,0]
	v_mul_f32_e32 v62, v44, v44
	v_pk_add_f32 v[64:65], v[64:65], v[64:65] op_sel_hi:[0,1]
	v_pk_fma_f32 v[70:71], v[44:45], v[44:45], v[62:63] op_sel_hi:[1,1,0]
	v_mul_f32_e32 v68, v38, v38
	v_mul_f32_e32 v70, v39, v39
	v_mul_f32_e32 v62, v40, v40
	v_mul_f32_e32 v64, v41, v41
	v_pk_add_f32 v[68:69], v[68:69], v[70:71]
	v_pk_add_f32 v[62:63], v[62:63], v[64:65]
	v_lshl_add_u64 v[64:65], s[84:85], 0, v[96:97]
	v_pk_add_f32 v[62:63], v[68:69], v[62:63]
	v_mov_b32_e32 v67, v55
	v_add_f32_e32 v62, v62, v63
	v_mov_b32_e32 v63, v181
	s_nop 0
	v_add_f32_dpp v62, v62, v62 row_shr:1 row_mask:0xf bank_mask:0xf bound_ctrl:1
	s_nop 1
	v_add_f32_dpp v62, v62, v62 row_shr:2 row_mask:0xf bank_mask:0xf bound_ctrl:1
	s_nop 1
	v_add_f32_dpp v62, v62, v62 row_shr:4 row_mask:0xf bank_mask:0xf bound_ctrl:1
	s_nop 1
	v_add_f32_dpp v62, v62, v62 row_shr:8 row_mask:0xf bank_mask:0xf bound_ctrl:1
	s_nop 1
	v_mov_b32_dpp v63, v62 row_bcast:15 row_mask:0xa bank_mask:0xf
	v_add_f32_e32 v62, v62, v63
	v_mov_b32_e32 v63, v181
	s_nop 1
	v_mov_b32_dpp v63, v62 row_bcast:31 row_mask:0xc bank_mask:0xf
	v_add_f32_e32 v62, v62, v63
	s_nop 0
	v_readlane_b32 s0, v62, 63
	s_nop 1
	v_fma_f32 v62, s0, v247, v237
	v_rsq_f32_e32 v62, v62
	s_nop 0
	v_pk_mul_f32 v[50:51], v[62:63], v[50:51] op_sel_hi:[0,1]
	v_pk_mul_f32 v[52:53], v[62:63], v[52:53] op_sel_hi:[0,1]
	s_waitcnt lgkmcnt(0)
	v_pk_fma_f32 v[6:7], v[6:7], v[52:53], v[10:11]
	v_pk_fma_f32 v[4:5], v[4:5], v[50:51], v[8:9]
	v_pk_mul_f32 v[68:69], v[48:49], v[62:63] op_sel_hi:[1,0]
	v_cvt_pk_bf16_f32 v4, v4, v5
	v_cvt_pk_bf16_f32 v5, v6, v7
	v_lshl_add_u64 v[6:7], v[64:65], 0, v[180:181]
	global_store_dwordx2 v[6:7], v[4:5], off sc1
	v_lshl_add_u32 v4, v56, 4, v114
	ds_read_b128 v[4:7], v4 offset:40960
	ds_read_b128 v[8:11], v57 offset:46080
	v_pk_mul_f32 v[70:71], v[46:47], v[62:63] op_sel_hi:[1,0]
	v_lshl_add_u32 v46, v36, 4, v114
	ds_read_b128 v[46:49], v46 offset:40960
	v_lshl_add_u32 v50, v58, 4, v114
	s_waitcnt lgkmcnt(1)
	v_pk_fma_f32 v[6:7], v[6:7], v[70:71], v[10:11]
	v_pk_fma_f32 v[4:5], v[4:5], v[68:69], v[8:9]
	v_cvt_pk_bf16_f32 v9, v6, v7
	v_cvt_pk_bf16_f32 v8, v4, v5
	ds_read_b128 v[4:7], v57 offset:47104
	v_lshl_add_u64 v[10:11], v[60:61], 3, v[64:65]
	ds_read_b128 v[50:53], v50 offset:40960
	global_store_dwordx2 v[10:11], v[8:9], off sc1
	ds_read_b128 v[8:11], v57 offset:48128
	v_pk_mul_f32 v[42:43], v[42:43], v[62:63] op_sel_hi:[1,0]
	v_pk_mul_f32 v[44:45], v[44:45], v[62:63] op_sel_hi:[1,0]
	s_waitcnt lgkmcnt(2)
	v_pk_fma_f32 v[4:5], v[46:47], v[42:43], v[4:5]
	v_pk_fma_f32 v[6:7], v[48:49], v[44:45], v[6:7]
	v_cvt_pk_bf16_f32 v4, v4, v5
	v_cvt_pk_bf16_f32 v5, v6, v7
	v_lshl_add_u64 v[6:7], v[36:37], 3, v[64:65]
	global_store_dwordx2 v[6:7], v[4:5], off sc1
	v_pk_mul_f32 v[4:5], v[38:39], v[62:63] op_sel_hi:[1,0]
	v_pk_mul_f32 v[6:7], v[40:41], v[62:63] op_sel_hi:[1,0]
	s_waitcnt lgkmcnt(0)
	v_pk_fma_f32 v[4:5], v[4:5], v[50:51], v[8:9]
	v_pk_fma_f32 v[6:7], v[6:7], v[52:53], v[10:11]
	v_cvt_pk_bf16_f32 v4, v4, v5
	v_cvt_pk_bf16_f32 v5, v6, v7
	v_lshl_add_u64 v[6:7], v[58:59], 3, v[64:65]
	global_store_dwordx2 v[6:7], v[4:5], off sc1

.LBB0_204:
	s_or_b64 exec, exec, s[14:15]
	s_waitcnt vmcnt(1)
	v_and_b32_e32 v51, 0xffff0000, v13
	v_and_b32_e32 v50, 0xffff0000, v12
	s_waitcnt vmcnt(2)
	v_and_b32_e32 v55, 0xffff0000, v15
	v_and_b32_e32 v54, 0xffff0000, v14
	v_lshlrev_b32_e32 v49, 16, v13
	v_lshlrev_b32_e32 v48, 16, v12
	v_lshlrev_b32_e32 v53, 16, v15
	v_lshlrev_b32_e32 v52, 16, v14
	s_waitcnt vmcnt(0)
	v_lshlrev_b32_e32 v58, 16, v16
	v_and_b32_e32 v59, 0xffff0000, v16
	v_lshlrev_b32_e32 v60, 16, v17
	s_waitcnt vmcnt(0)
	v_lshlrev_b32_e32 v62, 16, v18
	v_pk_mul_f32 v[68:69], v[50:51], v[50:51]
	v_pk_mul_f32 v[70:71], v[54:55], v[54:55]
	v_and_b32_e32 v61, 0xffff0000, v17
	v_pk_fma_f32 v[68:69], v[48:49], v[48:49], v[68:69]
	v_pk_fma_f32 v[70:71], v[52:53], v[52:53], v[70:71]
	v_mul_f32_e32 v63, v58, v58
	v_mul_f32_e32 v73, v59, v59
	v_mul_f32_e32 v56, v60, v60
	v_mov_b32_e32 v72, v62
	v_and_b32_e32 v66, 0xffff0000, v18
	v_lshlrev_b32_e32 v64, 16, v19
	v_and_b32_e32 v65, 0xffff0000, v19
	v_pk_add_f32 v[68:69], v[68:69], v[68:69] op_sel_hi:[0,1]
	v_pk_add_f32 v[70:71], v[70:71], v[70:71] op_sel_hi:[0,1]
	v_pk_fma_f32 v[74:75], v[60:61], v[60:61], v[56:57] op_sel_hi:[1,1,0]
	v_pk_add_f32 v[72:73], v[62:63], v[72:73]
	v_mul_f32_e32 v74, v66, v66
	v_mul_f32_e32 v70, v64, v64
	v_mul_f32_e32 v68, v65, v65
	v_mul_f32_e32 v76, v62, v62
	v_mov_b32_e32 v77, v73
	v_pk_add_f32 v[72:73], v[76:77], v[74:75]
	v_pk_add_f32 v[68:69], v[70:71], v[68:69]
	v_mov_b32_e32 v43, v181
	v_pk_add_f32 v[68:69], v[72:73], v[68:69]
	v_lshlrev_b32_e32 v180, 3, v38
	v_add_f32_e32 v39, v68, v69
	v_mov_b32_e32 v68, v48
	v_mov_b32_e32 v69, v50
	v_add_f32_dpp v39, v39, v39 row_shr:1 row_mask:0xf bank_mask:0xf bound_ctrl:1
	v_mov_b32_e32 v50, v49
	v_mov_b32_e32 v63, v66
	v_add_f32_dpp v39, v39, v39 row_shr:2 row_mask:0xf bank_mask:0xf bound_ctrl:1
	v_add_u32_e32 v66, 3, v57
	v_cmp_lt_i32_e64 s[16:17], v66, v115
	v_add_f32_dpp v39, v39, v39 row_shr:4 row_mask:0xf bank_mask:0xf bound_ctrl:1
	v_cmp_ge_i32_e64 s[14:15], v66, v115
	s_nop 0
	v_add_f32_dpp v39, v39, v39 row_shr:8 row_mask:0xf bank_mask:0xf bound_ctrl:1
	s_nop 1
	v_mov_b32_dpp v43, v39 row_bcast:15 row_mask:0xa bank_mask:0xf
	v_add_f32_e32 v39, v39, v43
	v_mov_b32_e32 v43, v181
	s_nop 1
	v_mov_b32_dpp v43, v39 row_bcast:31 row_mask:0xc bank_mask:0xf
	v_add_f32_e32 v39, v39, v43
	s_nop 0
	v_readlane_b32 s0, v39, 63
	s_nop 1
	v_fma_f32 v39, s0, v247, v237
	v_rsq_f32_e32 v56, v39
	v_lshl_add_u64 v[38:39], s[84:85], 0, v[94:95]
	v_pk_mul_f32 v[68:69], v[56:57], v[68:69] op_sel_hi:[0,1]
	v_pk_mul_f32 v[48:49], v[56:57], v[50:51] op_sel_hi:[0,1]
	s_waitcnt lgkmcnt(0)
	v_pk_fma_f32 v[6:7], v[6:7], v[48:49], v[10:11]
	v_pk_fma_f32 v[4:5], v[4:5], v[68:69], v[8:9]
	s_nop 0
	v_cvt_pk_bf16_f32 v4, v4, v5
	v_cvt_pk_bf16_f32 v5, v6, v7
	v_lshl_add_u64 v[6:7], v[38:39], 0, v[180:181]
	global_store_dwordx2 v[6:7], v[4:5], off sc1
	v_mov_b32_e32 v4, v52
	v_mov_b32_e32 v5, v54
	v_pk_mul_f32 v[68:69], v[56:57], v[4:5] op_sel_hi:[0,1]
	v_lshl_add_u32 v4, v42, 4, v114
	ds_read_b128 v[4:7], v4 offset:40960
	ds_read_b128 v[8:11], v37 offset:46080
	v_mov_b32_e32 v54, v53
	v_pk_mul_f32 v[70:71], v[56:57], v[54:55] op_sel_hi:[0,1]
	v_lshl_add_u32 v42, v40, 4, v114
	ds_read_b128 v[48:51], v42 offset:40960
	s_waitcnt lgkmcnt(1)
	v_pk_fma_f32 v[6:7], v[6:7], v[70:71], v[10:11]
	v_pk_fma_f32 v[4:5], v[4:5], v[68:69], v[8:9]
	v_cvt_pk_bf16_f32 v9, v6, v7
	v_cvt_pk_bf16_f32 v8, v4, v5
	ds_read_b128 v[4:7], v37 offset:47104
	v_lshl_add_u32 v42, v44, 4, v114
	v_lshl_add_u64 v[10:11], v[46:47], 3, v[38:39]
	ds_read_b128 v[52:55], v42 offset:40960
	global_store_dwordx2 v[10:11], v[8:9], off sc1
	ds_read_b128 v[8:11], v37 offset:48128
	v_pk_mul_f32 v[42:43], v[56:57], v[58:59] op_sel_hi:[0,1]
	v_pk_mul_f32 v[46:47], v[56:57], v[60:61] op_sel_hi:[0,1]
	s_waitcnt lgkmcnt(2)
	v_pk_fma_f32 v[6:7], v[50:51], v[46:47], v[6:7]
	v_pk_fma_f32 v[4:5], v[48:49], v[42:43], v[4:5]
	s_nop 0
	v_cvt_pk_bf16_f32 v4, v4, v5
	v_cvt_pk_bf16_f32 v5, v6, v7
	v_lshl_add_u64 v[6:7], v[40:41], 3, v[38:39]
	global_store_dwordx2 v[6:7], v[4:5], off sc1
	v_pk_mul_f32 v[4:5], v[56:57], v[62:63] op_sel_hi:[0,1]
	v_pk_mul_f32 v[6:7], v[56:57], v[64:65] op_sel_hi:[0,1]
	s_waitcnt lgkmcnt(0)
	v_pk_fma_f32 v[6:7], v[6:7], v[54:55], v[10:11]
	v_pk_fma_f32 v[4:5], v[4:5], v[52:53], v[8:9]
	s_nop 0
	v_cvt_pk_bf16_f32 v4, v4, v5
	v_cvt_pk_bf16_f32 v5, v6, v7
	v_lshl_add_u64 v[6:7], v[44:45], 3, v[38:39]
	global_store_dwordx2 v[6:7], v[4:5], off sc1
	s_and_saveexec_b64 s[4:5], s[16:17]
	s_cbranch_execz .LBB0_206
	v_mov_b32_e32 v4, v186
	s_nop 0
	v_and_b32_e32 v6, 63, v4
	v_add_u32_e32 v4, 0xfffff803, v57
	v_ashrrev_i32_e32 v5, 31, v4
	v_lshlrev_b64 v[4:5], 12, v[4:5]
	v_lshl_add_u64 v[4:5], s[38:39], 0, v[4:5]
	v_lshlrev_b32_e32 v180, 3, v6
	v_lshl_add_u64 v[4:5], v[4:5], 0, v[180:181]
	global_load_dwordx2 v[12:13], v[4:5], off
	global_load_dwordx2 v[14:15], v[4:5], off offset:512
	global_load_dwordx2 v[16:17], v[4:5], off offset:1024
	global_load_dwordx2 v[18:19], v[4:5], off offset:1536

.LBB0_211:
	s_or_b64 exec, exec, s[16:17]
	v_pk_mul_f32 v[68:69], v[54:55], v[54:55]
	v_pk_mul_f32 v[70:71], v[52:53], v[52:53]
	v_mov_b32_e32 v67, v181
	v_pk_mov_b32 v[72:73], v[70:71], v[68:69] op_sel:[1,0]
	v_mov_b32_e32 v71, v69
	v_pk_add_f32 v[68:69], v[72:73], v[70:71]
	v_pk_mul_f32 v[70:71], v[46:47], v[46:47]
	v_pk_add_f32 v[68:69], v[68:69], v[68:69] op_sel_hi:[0,1]
	v_pk_mul_f32 v[72:73], v[48:49], v[48:49]
	v_mul_f32_e32 v68, v42, v42
	v_pk_mov_b32 v[74:75], v[72:73], v[70:71] op_sel:[1,0]
	v_mov_b32_e32 v73, v71
	v_pk_add_f32 v[70:71], v[74:75], v[72:73]
	v_pk_fma_f32 v[72:73], v[42:43], v[42:43], v[68:69] op_sel_hi:[1,1,0]
	v_mul_f32_e32 v68, v44, v44
	v_pk_add_f32 v[70:71], v[70:71], v[70:71] op_sel_hi:[0,1]
	v_pk_fma_f32 v[74:75], v[44:45], v[44:45], v[68:69] op_sel_hi:[1,1,0]
	v_mul_f32_e32 v72, v38, v38
	v_mul_f32_e32 v74, v39, v39
	v_mul_f32_e32 v68, v40, v40
	v_mul_f32_e32 v70, v41, v41
	v_pk_add_f32 v[72:73], v[72:73], v[74:75]
	v_pk_add_f32 v[68:69], v[68:69], v[70:71]
	v_lshlrev_b32_e32 v180, 3, v56
	v_pk_add_f32 v[68:69], v[72:73], v[68:69]
	s_nop 0
	v_add_f32_e32 v51, v68, v69
	s_nop 1
	v_add_f32_dpp v51, v51, v51 row_shr:1 row_mask:0xf bank_mask:0xf bound_ctrl:1
	s_nop 1
	v_add_f32_dpp v51, v51, v51 row_shr:2 row_mask:0xf bank_mask:0xf bound_ctrl:1
	s_nop 1
	v_add_f32_dpp v51, v51, v51 row_shr:4 row_mask:0xf bank_mask:0xf bound_ctrl:1
	s_nop 1
	v_add_f32_dpp v51, v51, v51 row_shr:8 row_mask:0xf bank_mask:0xf bound_ctrl:1
	s_nop 1
	v_mov_b32_dpp v67, v51 row_bcast:15 row_mask:0xa bank_mask:0xf
	v_add_f32_e32 v51, v51, v67
	v_mov_b32_e32 v67, v181
	s_nop 1
	v_mov_b32_dpp v67, v51 row_bcast:31 row_mask:0xc bank_mask:0xf
	v_add_f32_e32 v51, v51, v67
	v_mov_b32_e32 v67, v37
	v_readlane_b32 s0, v51, 63
	s_nop 1
	v_fma_f32 v51, s0, v247, v237
	v_rsq_f32_e32 v68, v51
	v_ashrrev_i32_e32 v51, 31, v50
	v_lshlrev_b64 v[50:51], 11, v[50:51]
	v_pk_mul_f32 v[52:53], v[68:69], v[52:53] op_sel_hi:[0,1]
	v_pk_mul_f32 v[54:55], v[68:69], v[54:55] op_sel_hi:[0,1]
	s_waitcnt lgkmcnt(0)
	v_pk_fma_f32 v[6:7], v[6:7], v[54:55], v[10:11]
	v_pk_fma_f32 v[4:5], v[4:5], v[52:53], v[8:9]
	v_lshl_add_u64 v[54:55], s[20:21], 0, v[50:51]
	v_cvt_pk_bf16_f32 v4, v4, v5
	v_cvt_pk_bf16_f32 v5, v6, v7
	v_lshl_add_u64 v[6:7], v[54:55], 0, v[180:181]
	global_store_dwordx2 v[6:7], v[4:5], off sc1
	v_lshl_add_u32 v4, v60, 4, v114
	ds_read_b128 v[4:7], v4 offset:40960
	ds_read_b128 v[8:11], v61 offset:46080
	v_pk_mul_f32 v[70:71], v[48:49], v[68:69] op_sel_hi:[1,0]
	v_pk_mul_f32 v[72:73], v[46:47], v[68:69] op_sel_hi:[1,0]
	v_lshl_add_u32 v46, v58, 4, v114
	ds_read_b128 v[46:49], v46 offset:40960
	s_waitcnt lgkmcnt(1)
	v_pk_fma_f32 v[6:7], v[6:7], v[72:73], v[10:11]
	v_pk_fma_f32 v[4:5], v[4:5], v[70:71], v[8:9]
	v_cvt_pk_bf16_f32 v9, v6, v7
	v_cvt_pk_bf16_f32 v8, v4, v5
	ds_read_b128 v[4:7], v61 offset:47104
	v_lshl_add_u32 v50, v62, 4, v114
	v_lshl_add_u64 v[10:11], v[64:65], 3, v[54:55]
	ds_read_b128 v[50:53], v50 offset:40960
	global_store_dwordx2 v[10:11], v[8:9], off sc1
	ds_read_b128 v[8:11], v61 offset:48128
	v_pk_mul_f32 v[42:43], v[42:43], v[68:69] op_sel_hi:[1,0]
	v_pk_mul_f32 v[44:45], v[44:45], v[68:69] op_sel_hi:[1,0]
	s_waitcnt lgkmcnt(2)
	v_pk_fma_f32 v[4:5], v[46:47], v[42:43], v[4:5]
	v_pk_fma_f32 v[6:7], v[48:49], v[44:45], v[6:7]
	v_cvt_pk_bf16_f32 v4, v4, v5
	v_cvt_pk_bf16_f32 v5, v6, v7
	v_lshl_add_u64 v[6:7], v[58:59], 3, v[54:55]
	global_store_dwordx2 v[6:7], v[4:5], off sc1
	v_pk_mul_f32 v[4:5], v[38:39], v[68:69] op_sel_hi:[1,0]
	v_pk_mul_f32 v[6:7], v[40:41], v[68:69] op_sel_hi:[1,0]
	s_waitcnt lgkmcnt(0)
	v_pk_fma_f32 v[4:5], v[4:5], v[50:51], v[8:9]
	v_pk_fma_f32 v[6:7], v[6:7], v[52:53], v[10:11]
	v_cvt_pk_bf16_f32 v4, v4, v5
	v_cvt_pk_bf16_f32 v5, v6, v7
	v_lshl_add_u64 v[6:7], v[62:63], 3, v[54:55]
	global_store_dwordx2 v[6:7], v[4:5], off sc1

.LBB0_230:
	s_or_b64 exec, exec, s[4:5]
	v_mov_b32_e32 v52, v186
	s_mov_b32 s0, 0x1b485000
	v_and_b32_e32 v113, 63, v52
	v_or_b32_e32 v56, 64, v113
	v_lshlrev_b32_e32 v119, 4, v56
	v_or_b32_e32 v56, 0x80, v113
	v_lshlrev_b32_e32 v180, 4, v113
	v_lshlrev_b32_e32 v118, 4, v56
	v_or_b32_e32 v56, 0xc0, v113
	v_lshlrev_b32_e32 v117, 4, v56
	v_lshl_add_u64 v[56:57], v[110:111], 0, v[180:181]
	v_lshl_add_u64 v[136:137], s[78:79], 0, v[56:57]
	v_add_co_u32_e32 v138, vcc, s0, v136
	s_mov_b32 s0, 0x1bc85000
	s_nop 0
	v_addc_co_u32_e32 v139, vcc, 0, v137, vcc
	v_add_co_u32_e32 v140, vcc, s0, v136
	s_mov_b32 s0, 0x1c485000
	s_nop 0
	v_addc_co_u32_e32 v141, vcc, 0, v137, vcc
	v_add_co_u32_e32 v142, vcc, s0, v136
	s_mov_b32 s0, 0x1cc85000
	s_nop 0
	v_addc_co_u32_e32 v143, vcc, 0, v137, vcc
	global_load_dwordx4 v[56:59], v[138:139], off
	global_load_dwordx4 v[72:75], v[140:141], off
	global_load_dwordx4 v[76:79], v[142:143], off
	v_add_co_u32_e32 v144, vcc, s0, v136
	global_load_dwordx4 v[52:55], v180, s[24:25]
	global_load_dwordx4 v[60:63], v119, s[24:25]
	v_addc_co_u32_e32 v145, vcc, 0, v137, vcc
	global_load_dwordx4 v[64:67], v118, s[24:25]
	global_load_dwordx4 v[68:71], v117, s[24:25]
	global_load_dwordx4 v[80:83], v[144:145], off
	global_load_dwordx4 v[120:123], v[138:139], off offset:1024
	global_load_dwordx4 v[124:127], v[140:141], off offset:1024
	global_load_dwordx4 v[128:131], v[142:143], off offset:1024
	global_load_dwordx4 v[132:135], v[144:145], off offset:1024
	s_xor_b64 s[42:43], s[42:43], -1
	s_mov_b64 s[50:51], -1
	s_waitcnt vmcnt(10)
	v_pk_add_f32 v[58:59], v[58:59], v[74:75]
	v_pk_add_f32 v[56:57], v[56:57], v[72:73]
	s_waitcnt vmcnt(4)
	v_pk_add_f32 v[72:73], v[78:79], v[82:83]
	v_pk_add_f32 v[74:75], v[76:77], v[80:81]
	v_pk_add_f32 v[58:59], v[58:59], v[72:73]
	v_pk_add_f32 v[56:57], v[56:57], v[74:75]
	v_pk_fma_f32 v[58:59], v[54:55], v[58:59], v[6:7]
	v_pk_fma_f32 v[56:57], v[52:53], v[56:57], v[4:5]
	s_waitcnt vmcnt(2)
	v_pk_add_f32 v[52:53], v[122:123], v[126:127]
	v_pk_add_f32 v[54:55], v[120:121], v[124:125]
	s_waitcnt vmcnt(0)
	v_pk_add_f32 v[72:73], v[130:131], v[134:135]
	v_pk_add_f32 v[74:75], v[128:129], v[132:133]
	v_pk_add_f32 v[52:53], v[52:53], v[72:73]
	v_pk_add_f32 v[72:73], v[54:55], v[74:75]
	v_pk_fma_f32 v[54:55], v[62:63], v[52:53], v[10:11]
	v_pk_fma_f32 v[52:53], v[60:61], v[72:73], v[8:9]
	global_load_dwordx4 v[60:63], v[138:139], off offset:2048
	global_load_dwordx4 v[72:75], v[140:141], off offset:2048
	global_load_dwordx4 v[76:79], v[142:143], off offset:2048
	global_load_dwordx4 v[80:83], v[144:145], off offset:2048
	global_load_dwordx4 v[120:123], v[138:139], off offset:3072
	global_load_dwordx4 v[124:127], v[140:141], off offset:3072
	global_load_dwordx4 v[128:131], v[142:143], off offset:3072
	global_load_dwordx4 v[132:135], v[144:145], off offset:3072
	s_waitcnt vmcnt(6)
	v_pk_add_f32 v[62:63], v[62:63], v[74:75]
	v_pk_add_f32 v[60:61], v[60:61], v[72:73]
	s_waitcnt vmcnt(4)
	v_pk_add_f32 v[72:73], v[78:79], v[82:83]
	v_pk_add_f32 v[74:75], v[76:77], v[80:81]
	v_pk_add_f32 v[62:63], v[62:63], v[72:73]
	v_pk_add_f32 v[60:61], v[60:61], v[74:75]
	v_pk_fma_f32 v[66:67], v[66:67], v[62:63], v[14:15]
	v_pk_fma_f32 v[64:65], v[64:65], v[60:61], v[12:13]
	s_waitcnt vmcnt(2)
	v_pk_add_f32 v[60:61], v[122:123], v[126:127]
	v_pk_add_f32 v[62:63], v[120:121], v[124:125]
	s_waitcnt vmcnt(0)
	v_pk_add_f32 v[72:73], v[130:131], v[134:135]
	v_pk_add_f32 v[74:75], v[128:129], v[132:133]
	v_pk_add_f32 v[60:61], v[60:61], v[72:73]
	v_pk_add_f32 v[72:73], v[62:63], v[74:75]
	v_pk_fma_f32 v[62:63], v[70:71], v[60:61], v[18:19]
	v_pk_fma_f32 v[60:61], v[68:69], v[72:73], v[16:17]
	v_add_co_u32_e32 v68, vcc, 0x3465000, v136
	v_add_u32_e32 v120, v114, v180
	s_nop 0
	v_addc_co_u32_e32 v69, vcc, 0, v137, vcc
	s_and_b64 vcc, exec, s[42:43]
	global_store_dwordx4 v[68:69], v[56:59], off sc1
	global_store_dwordx4 v[68:69], v[52:55], off offset:1024 sc1
	global_store_dwordx4 v[68:69], v[64:67], off offset:2048 sc1
	global_store_dwordx4 v[68:69], v[60:63], off offset:3072 sc1
	s_cbranch_vccz .LBB0_232
	global_load_dwordx4 v[68:71], v180, s[34:35]
	global_load_dwordx4 v[72:75], v180, s[30:31]
	global_load_dwordx4 v[76:79], v180, s[28:29]
	s_mov_b64 s[50:51], 0
	s_waitcnt vmcnt(1)
	v_pk_add_f32 v[74:75], v[74:75], 1.0 op_sel_hi:[1,0]
	v_pk_add_f32 v[72:73], v[72:73], 1.0 op_sel_hi:[1,0]
	v_pk_mul_f32 v[70:71], v[70:71], v[74:75]
	v_pk_mul_f32 v[68:69], v[68:69], v[72:73]
	ds_write_b128 v120, v[68:71] offset:40960
	s_waitcnt vmcnt(0)
	ds_write_b128 v120, v[76:79] offset:45056
	global_load_dwordx4 v[72:75], v180, s[34:35] offset:1024
	global_load_dwordx4 v[80:83], v119, s[30:31]
	s_waitcnt vmcnt(0)
	v_pk_add_f32 v[82:83], v[82:83], 1.0 op_sel_hi:[1,0]
	v_pk_add_f32 v[80:81], v[80:81], 1.0 op_sel_hi:[1,0]
	v_pk_mul_f32 v[74:75], v[74:75], v[82:83]
	v_pk_mul_f32 v[72:73], v[72:73], v[80:81]
	global_load_dwordx4 v[80:83], v119, s[28:29]
	ds_write_b128 v120, v[72:75] offset:41984
	s_waitcnt vmcnt(0)
	ds_write_b128 v120, v[80:83] offset:46080
	global_load_dwordx4 v[122:125], v180, s[34:35] offset:2048
	global_load_dwordx4 v[126:129], v118, s[30:31]
	s_waitcnt vmcnt(0)
	v_pk_add_f32 v[128:129], v[128:129], 1.0 op_sel_hi:[1,0]
	v_pk_add_f32 v[126:127], v[126:127], 1.0 op_sel_hi:[1,0]
	v_pk_mul_f32 v[124:125], v[124:125], v[128:129]
	v_pk_mul_f32 v[122:123], v[122:123], v[126:127]
	ds_write_b128 v120, v[122:125] offset:43008
	global_load_dwordx4 v[122:125], v118, s[28:29]
	s_waitcnt vmcnt(0)
	ds_write_b128 v120, v[122:125] offset:47104
	global_load_dwordx4 v[122:125], v180, s[34:35] offset:3072
	global_load_dwordx4 v[126:129], v117, s[30:31]
	s_waitcnt vmcnt(0)
	v_pk_add_f32 v[118:119], v[128:129], 1.0 op_sel_hi:[1,0]
	v_pk_add_f32 v[126:127], v[126:127], 1.0 op_sel_hi:[1,0]
	v_pk_mul_f32 v[124:125], v[124:125], v[118:119]
	v_pk_mul_f32 v[122:123], v[122:123], v[126:127]
	ds_write_b128 v120, v[122:125] offset:44032
	global_load_dwordx4 v[122:125], v117, s[28:29]
	s_waitcnt vmcnt(0)
	ds_write_b128 v120, v[122:125] offset:48128

.LBB0_234:
	v_pk_mul_f32 v[118:119], v[58:59], v[58:59]
	v_pk_mul_f32 v[122:123], v[56:57], v[56:57]
	v_mul_f32_e32 v117, v60, v60
	v_pk_mov_b32 v[124:125], v[122:123], v[118:119] op_sel:[1,0]
	v_mov_b32_e32 v123, v119
	v_pk_add_f32 v[118:119], v[124:125], v[122:123]
	v_pk_mul_f32 v[122:123], v[54:55], v[54:55]
	v_pk_mul_f32 v[124:125], v[52:53], v[52:53]
	v_mul_f32_e32 v121, v61, v61
	v_pk_mov_b32 v[126:127], v[124:125], v[122:123] op_sel:[1,0]
	v_mov_b32_e32 v125, v123
	v_pk_add_f32 v[122:123], v[126:127], v[124:125]
	v_pk_add_f32 v[118:119], v[118:119], v[118:119] op_sel:[0,1] op_sel_hi:[1,0]
	v_pk_add_f32 v[122:123], v[122:123], v[122:123] op_sel:[0,1] op_sel_hi:[1,0]
	v_mov_b32_e32 v119, v117
	v_mov_b32_e32 v123, v121
	v_pk_add_f32 v[118:119], v[118:119], v[122:123]
	v_mul_f32_e32 v122, v65, v65
	v_mul_f32_e32 v124, v62, v62
	v_pk_fma_f32 v[122:123], v[64:65], v[64:65], v[122:123] op_sel_hi:[1,1,0]
	v_mul_f32_e32 v126, v63, v63
	v_mov_b32_e32 v123, v124
	v_mul_f32_e32 v124, v67, v67
	v_pk_fma_f32 v[124:125], v[66:67], v[66:67], v[124:125] op_sel_hi:[1,1,0]
	v_lshlrev_b32_e32 v180, 3, v113
	v_mov_b32_e32 v125, v126
	v_pk_add_f32 v[122:123], v[122:123], v[124:125]
	s_nop 0
	v_pk_add_f32 v[118:119], v[118:119], v[122:123]
	s_nop 0
	v_add_f32_e32 v117, v118, v119
	v_mov_b32_e32 v118, v181
	s_nop 0
	v_add_f32_dpp v117, v117, v117 row_shr:1 row_mask:0xf bank_mask:0xf bound_ctrl:1
	s_nop 1
	v_add_f32_dpp v117, v117, v117 row_shr:2 row_mask:0xf bank_mask:0xf bound_ctrl:1
	s_nop 1
	v_add_f32_dpp v117, v117, v117 row_shr:4 row_mask:0xf bank_mask:0xf bound_ctrl:1
	s_nop 1
	v_add_f32_dpp v117, v117, v117 row_shr:8 row_mask:0xf bank_mask:0xf bound_ctrl:1
	s_nop 1
	v_mov_b32_dpp v118, v117 row_bcast:15 row_mask:0xa bank_mask:0xf
	v_add_f32_e32 v117, v117, v118
	v_mov_b32_e32 v118, v181
	s_nop 1
	v_mov_b32_dpp v118, v117 row_bcast:31 row_mask:0xc bank_mask:0xf
	v_add_f32_e32 v117, v117, v118
	s_nop 0
	v_readlane_b32 s0, v117, 63
	s_nop 1
	v_fma_f32 v117, s0, v247, v237
	v_rsq_f32_e32 v118, v117
	s_mov_b32 s0, 0x3e85000
	v_pk_mul_f32 v[56:57], v[56:57], v[118:119] op_sel_hi:[1,0]
	v_pk_mul_f32 v[58:59], v[58:59], v[118:119] op_sel_hi:[1,0]
	s_waitcnt lgkmcnt(1)
	v_pk_fma_f32 v[56:57], v[68:69], v[56:57], v[76:77]
	v_pk_fma_f32 v[58:59], v[70:71], v[58:59], v[78:79]
	v_cvt_pk_bf16_f32 v56, v56, v57
	v_cvt_pk_bf16_f32 v57, v58, v59
	v_lshl_add_u64 v[58:59], v[108:109], 0, v[180:181]
	v_lshl_add_u64 v[58:59], s[78:79], 0, v[58:59]
	v_pk_mul_f32 v[52:53], v[52:53], v[118:119] op_sel_hi:[1,0]
	v_pk_mul_f32 v[54:55], v[54:55], v[118:119] op_sel_hi:[1,0]
	v_add_co_u32_e32 v76, vcc, s0, v58
	s_waitcnt lgkmcnt(0)
	v_pk_fma_f32 v[54:55], v[74:75], v[54:55], v[82:83]
	v_pk_fma_f32 v[52:53], v[72:73], v[52:53], v[80:81]
	v_addc_co_u32_e32 v77, vcc, 0, v59, vcc
	v_cvt_pk_bf16_f32 v52, v52, v53
	v_cvt_pk_bf16_f32 v53, v54, v55
	global_store_dwordx2 v[76:77], v[56:57], off sc1
	global_store_dwordx2 v[76:77], v[52:53], off offset:512 sc1
	ds_read_b128 v[52:55], v120 offset:43008
	ds_read_b128 v[56:59], v120 offset:47104
	v_pk_mul_f32 v[72:73], v[64:65], v[118:119] op_sel_hi:[1,0]
	v_pk_mul_f32 v[74:75], v[66:67], v[118:119] op_sel_hi:[1,0]
	ds_read_b128 v[64:67], v120 offset:44032
	ds_read_b128 v[68:71], v120 offset:48128
	s_waitcnt lgkmcnt(2)
	v_pk_fma_f32 v[54:55], v[54:55], v[74:75], v[58:59]
	v_pk_fma_f32 v[52:53], v[52:53], v[72:73], v[56:57]
	v_add_u32_e32 v72, -1, v112
	v_cvt_pk_bf16_f32 v52, v52, v53
	v_cvt_pk_bf16_f32 v53, v54, v55
	global_store_dwordx2 v[76:77], v[52:53], off offset:1024 sc1
	v_pk_mul_f32 v[52:53], v[60:61], v[118:119] op_sel_hi:[1,0]
	v_pk_mul_f32 v[54:55], v[62:63], v[118:119] op_sel_hi:[1,0]
	s_waitcnt lgkmcnt(0)
	v_pk_fma_f32 v[52:53], v[52:53], v[64:65], v[68:69]
	v_pk_fma_f32 v[54:55], v[54:55], v[66:67], v[70:71]
	v_cvt_pk_bf16_f32 v52, v52, v53
	v_cvt_pk_bf16_f32 v53, v54, v55
	v_cmp_lt_i32_e32 vcc, v72, v116
	global_store_dwordx2 v[76:77], v[52:53], off offset:1536 sc1
	s_and_saveexec_b64 s[4:5], vcc
	s_cbranch_execz .LBB0_236
	v_mov_b32_e32 v4, v186
	s_nop 0
	v_and_b32_e32 v4, 63, v4
	v_lshlrev_b32_e32 v180, 4, v4
	v_lshl_add_u64 v[4:5], v[110:111], 0, v[180:181]
	v_lshl_add_u64 v[4:5], s[16:17], 0, v[4:5]
	v_add_co_u32_e32 v16, vcc, 0x3000, v4
	s_nop 1
	v_addc_co_u32_e32 v17, vcc, 0, v5, vcc
	global_load_dwordx4 v[4:7], v[16:17], off
	global_load_dwordx4 v[8:11], v[16:17], off offset:1024
	global_load_dwordx4 v[12:15], v[16:17], off offset:2048
	s_nop 0
	global_load_dwordx4 v[16:19], v[16:17], off offset:3072
.LBB0_236:
	s_or_b64 exec, exec, s[4:5]
	v_add_u32_e32 v68, -3, v112
	v_cmp_lt_i32_e32 vcc, v68, v116
	s_and_saveexec_b64 s[42:43], vcc
	s_cbranch_execz .LBB0_239
	v_mov_b32_e32 v52, v186
	v_ashrrev_i32_e32 v69, 31, v68
	v_and_b32_e32 v73, 63, v52
	v_lshlrev_b32_e32 v180, 4, v73
	v_or_b32_e32 v64, 0xc00, v180
	v_lshlrev_b64 v[70:71], 12, v[68:69]
	global_load_dwordx4 v[52:55], v180, s[24:25]
	global_load_dwordx4 v[74:77], v64, s[24:25]
	v_lshl_add_u64 v[64:65], s[22:23], 0, v[70:71]
	v_lshl_add_u64 v[82:83], v[64:65], 0, v[180:181]
	s_mov_b32 s0, 0x800000
	v_add_co_u32_e32 v142, vcc, s0, v82
	s_mov_b32 s0, 0x1000000
	s_nop 0
	v_addc_co_u32_e32 v143, vcc, 0, v83, vcc
	v_add_co_u32_e32 v144, vcc, s0, v82
	s_mov_b32 s0, 0x1800000
	s_nop 0
	v_addc_co_u32_e32 v145, vcc, 0, v83, vcc
	global_load_dwordx4 v[64:67], v[82:83], off
	global_load_dwordx4 v[78:81], v[142:143], off
	global_load_dwordx4 v[118:121], v[144:145], off
	v_add_co_u32_e32 v146, vcc, s0, v82
	v_or_b32_e32 v56, 0x400, v180
	v_or_b32_e32 v60, 0x800, v180
	v_addc_co_u32_e32 v147, vcc, 0, v83, vcc
	global_load_dwordx4 v[56:59], v56, s[24:25]
	v_lshl_add_u64 v[70:71], s[26:27], 0, v[70:71]
	global_load_dwordx4 v[60:63], v60, s[24:25]
	s_nop 0
	global_load_dwordx4 v[122:125], v[146:147], off
	global_load_dwordx4 v[126:129], v[82:83], off offset:1024
	global_load_dwordx4 v[130:133], v[142:143], off offset:1024
	global_load_dwordx4 v[134:137], v[144:145], off offset:1024
	global_load_dwordx4 v[138:141], v[146:147], off offset:1024
	v_lshl_add_u64 v[70:71], v[70:71], 0, v[180:181]
	s_waitcnt vmcnt(8)
	v_pk_add_f32 v[66:67], v[66:67], v[80:81]
	v_pk_add_f32 v[64:65], v[64:65], v[78:79]
	s_waitcnt vmcnt(4)
	v_pk_add_f32 v[78:79], v[120:121], v[124:125]
	v_pk_add_f32 v[80:81], v[118:119], v[122:123]
	v_pk_add_f32 v[66:67], v[66:67], v[78:79]
	v_pk_add_f32 v[64:65], v[64:65], v[80:81]
	v_pk_fma_f32 v[66:67], v[54:55], v[66:67], v[22:23]
	v_pk_fma_f32 v[64:65], v[52:53], v[64:65], v[20:21]
	s_waitcnt vmcnt(2)
	v_pk_add_f32 v[52:53], v[128:129], v[132:133]
	v_pk_add_f32 v[54:55], v[126:127], v[130:131]
	s_waitcnt vmcnt(0)
	v_pk_add_f32 v[78:79], v[136:137], v[140:141]
	v_pk_add_f32 v[80:81], v[134:135], v[138:139]
	v_pk_add_f32 v[52:53], v[52:53], v[78:79]
	v_pk_add_f32 v[54:55], v[54:55], v[80:81]
	v_pk_fma_f32 v[58:59], v[58:59], v[52:53], v[26:27]
	v_pk_fma_f32 v[56:57], v[56:57], v[54:55], v[24:25]
	global_load_dwordx4 v[52:55], v[82:83], off offset:2048
	global_load_dwordx4 v[78:81], v[142:143], off offset:2048
	global_load_dwordx4 v[118:121], v[144:145], off offset:2048
	global_load_dwordx4 v[122:125], v[146:147], off offset:2048
	global_load_dwordx4 v[126:129], v[82:83], off offset:3072
	global_load_dwordx4 v[130:133], v[142:143], off offset:3072
	global_load_dwordx4 v[134:137], v[144:145], off offset:3072
	global_load_dwordx4 v[138:141], v[146:147], off offset:3072
	s_waitcnt vmcnt(6)
	v_pk_add_f32 v[54:55], v[54:55], v[80:81]
	v_pk_add_f32 v[52:53], v[52:53], v[78:79]
	s_waitcnt vmcnt(4)
	v_pk_add_f32 v[78:79], v[120:121], v[124:125]
	v_pk_add_f32 v[80:81], v[118:119], v[122:123]
	v_pk_add_f32 v[54:55], v[54:55], v[78:79]
	v_pk_add_f32 v[52:53], v[52:53], v[80:81]
	v_pk_fma_f32 v[62:63], v[62:63], v[54:55], v[30:31]
	v_pk_fma_f32 v[60:61], v[60:61], v[52:53], v[28:29]
	s_waitcnt vmcnt(2)
	v_pk_add_f32 v[52:53], v[128:129], v[132:133]
	v_pk_add_f32 v[54:55], v[126:127], v[130:131]
	s_waitcnt vmcnt(0)
	v_pk_add_f32 v[78:79], v[136:137], v[140:141]
	v_pk_add_f32 v[80:81], v[134:135], v[138:139]
	v_pk_add_f32 v[52:53], v[52:53], v[78:79]
	v_pk_add_f32 v[78:79], v[54:55], v[80:81]
	v_pk_fma_f32 v[54:55], v[76:77], v[52:53], v[34:35]
	v_pk_fma_f32 v[52:53], v[74:75], v[78:79], v[32:33]
	global_store_dwordx4 v[70:71], v[64:67], off sc1
	global_store_dwordx4 v[70:71], v[56:59], off offset:1024 sc1
	global_store_dwordx4 v[70:71], v[60:63], off offset:2048 sc1
	global_store_dwordx4 v[70:71], v[52:55], off offset:3072 sc1
	v_pk_mul_f32 v[70:71], v[66:67], v[66:67]
	v_pk_mul_f32 v[74:75], v[64:65], v[64:65]
	s_nop 0
	v_pk_mov_b32 v[76:77], v[74:75], v[70:71] op_sel:[1,0]
	v_mov_b32_e32 v75, v71
	v_pk_add_f32 v[70:71], v[76:77], v[74:75]
	v_pk_mul_f32 v[74:75], v[58:59], v[58:59]
	v_pk_mul_f32 v[76:77], v[56:57], v[56:57]
	v_pk_add_f32 v[70:71], v[70:71], v[70:71] op_sel:[0,1] op_sel_hi:[1,0]
	v_pk_mov_b32 v[78:79], v[76:77], v[74:75] op_sel:[1,0]
	v_mov_b32_e32 v77, v75
	v_pk_add_f32 v[74:75], v[78:79], v[76:77]
	v_mul_f32_e32 v76, v52, v52
	v_mul_f32_e32 v77, v53, v53
	v_pk_add_f32 v[74:75], v[74:75], v[74:75] op_sel:[0,1] op_sel_hi:[1,0]
	v_mov_b32_e32 v71, v76
	v_mov_b32_e32 v75, v77
	v_pk_add_f32 v[70:71], v[70:71], v[74:75]
	v_mul_f32_e32 v74, v61, v61
	v_mul_f32_e32 v76, v63, v63
	v_mul_f32_e32 v78, v54, v54
	v_mul_f32_e32 v79, v55, v55
	v_pk_fma_f32 v[74:75], v[60:61], v[60:61], v[74:75] op_sel_hi:[1,1,0]
	v_pk_fma_f32 v[76:77], v[62:63], v[62:63], v[76:77] op_sel_hi:[1,1,0]
	v_mov_b32_e32 v75, v78
	v_mov_b32_e32 v77, v79
	v_pk_add_f32 v[74:75], v[74:75], v[76:77]
	v_lshlrev_b64 v[76:77], 11, v[68:69]
	v_pk_add_f32 v[70:71], v[70:71], v[74:75]
	s_nop 0
	v_add_f32_e32 v70, v70, v71
	v_mov_b32_e32 v71, v181
	s_nop 0
	v_add_f32_dpp v70, v70, v70 row_shr:1 row_mask:0xf bank_mask:0xf bound_ctrl:1
	s_nop 1
	v_add_f32_dpp v70, v70, v70 row_shr:2 row_mask:0xf bank_mask:0xf bound_ctrl:1
	s_nop 1
	v_add_f32_dpp v70, v70, v70 row_shr:4 row_mask:0xf bank_mask:0xf bound_ctrl:1
	s_nop 1
	v_add_f32_dpp v70, v70, v70 row_shr:8 row_mask:0xf bank_mask:0xf bound_ctrl:1
	s_nop 1
	v_mov_b32_dpp v71, v70 row_bcast:15 row_mask:0xa bank_mask:0xf
	v_add_f32_e32 v70, v70, v71
	v_mov_b32_e32 v71, v181
	s_nop 1
	v_mov_b32_dpp v71, v70 row_bcast:31 row_mask:0xc bank_mask:0xf
	v_add_f32_e32 v70, v70, v71
	s_nop 0
	v_readlane_b32 s0, v70, 63
	s_nop 1
	v_fma_f32 v70, s0, v247, v237
	v_rsq_f32_e32 v74, v70
	s_nop 0
	v_pk_mul_f32 v[78:79], v[64:65], v[74:75] op_sel_hi:[1,0]
	v_pk_mul_f32 v[80:81], v[66:67], v[74:75] op_sel_hi:[1,0]
	v_add_u32_e32 v75, v114, v180
	ds_read_b128 v[64:67], v75 offset:40960
	ds_read_b128 v[68:71], v75 offset:45056
	v_lshlrev_b32_e32 v180, 3, v73
	s_waitcnt lgkmcnt(0)
	v_pk_fma_f32 v[66:67], v[66:67], v[80:81], v[70:71]
	v_pk_fma_f32 v[64:65], v[64:65], v[78:79], v[68:69]
	v_pk_mul_f32 v[70:71], v[56:57], v[74:75] op_sel_hi:[1,0]
	v_cvt_pk_bf16_f32 v64, v64, v65
	v_cvt_pk_bf16_f32 v65, v66, v67
	v_lshl_add_u64 v[66:67], s[20:21], 0, v[76:77]
	v_lshl_add_u64 v[68:69], v[66:67], 0, v[180:181]
	global_store_dwordx2 v[68:69], v[64:65], off sc1
	v_pk_mul_f32 v[76:77], v[58:59], v[74:75] op_sel_hi:[1,0]
	ds_read_b128 v[56:59], v75 offset:41984
	ds_read_b128 v[64:67], v75 offset:46080
	s_waitcnt lgkmcnt(0)
	v_pk_fma_f32 v[58:59], v[58:59], v[76:77], v[66:67]
	v_pk_fma_f32 v[56:57], v[56:57], v[70:71], v[64:65]
	v_pk_mul_f32 v[64:65], v[60:61], v[74:75] op_sel_hi:[1,0]
	v_cvt_pk_bf16_f32 v56, v56, v57
	v_cvt_pk_bf16_f32 v57, v58, v59
	global_store_dwordx2 v[68:69], v[56:57], off offset:512 sc1
	v_pk_mul_f32 v[66:67], v[62:63], v[74:75] op_sel_hi:[1,0]
	ds_read_b128 v[56:59], v75 offset:43008
	ds_read_b128 v[60:63], v75 offset:47104
	s_waitcnt lgkmcnt(0)
	v_pk_fma_f32 v[58:59], v[66:67], v[58:59], v[62:63]
	v_pk_fma_f32 v[56:57], v[64:65], v[56:57], v[60:61]
	v_pk_mul_f32 v[60:61], v[52:53], v[74:75] op_sel_hi:[1,0]
	v_cvt_pk_bf16_f32 v56, v56, v57
	v_cvt_pk_bf16_f32 v57, v58, v59
	global_store_dwordx2 v[68:69], v[56:57], off offset:1024 sc1
	v_pk_mul_f32 v[62:63], v[54:55], v[74:75] op_sel_hi:[1,0]
	ds_read_b128 v[52:55], v75 offset:44032
	ds_read_b128 v[56:59], v75 offset:48128
	s_waitcnt lgkmcnt(0)
	v_pk_fma_f32 v[54:55], v[62:63], v[54:55], v[58:59]
	v_pk_fma_f32 v[52:53], v[60:61], v[52:53], v[56:57]
	s_nop 0
	v_cvt_pk_bf16_f32 v52, v52, v53
	v_cvt_pk_bf16_f32 v53, v54, v55
	global_store_dwordx2 v[68:69], v[52:53], off offset:1536 sc1
	s_or_b64 exec, exec, s[42:43]
	v_cmp_lt_i32_e32 vcc, v112, v116
	s_and_saveexec_b64 s[4:5], vcc
	s_cbranch_execnz .LBB0_240

.LBB0_241:
	v_mov_b32_e32 v52, v186
	s_mov_b32 s0, 0x3465000
	v_and_b32_e32 v70, 63, v52
	v_lshlrev_b32_e32 v180, 4, v70
	v_or_b32_e32 v56, 0x400, v180
	v_or_b32_e32 v60, 0x800, v180
	global_load_dwordx4 v[56:59], v56, s[24:25]
	s_nop 0
	global_load_dwordx4 v[74:77], v60, s[24:25]
	v_or_b32_e32 v60, 0xc00, v180
	global_load_dwordx4 v[52:55], v180, s[24:25]
	global_load_dwordx4 v[78:81], v60, s[24:25]
	v_lshl_add_u64 v[60:61], v[104:105], 0, v[180:181]
	v_lshl_add_u64 v[68:69], s[78:79], 0, v[60:61]
	v_add_co_u32_e32 v82, vcc, 0x1b485000, v68
	s_nop 1
	v_addc_co_u32_e32 v83, vcc, 0, v69, vcc
	v_add_co_u32_e32 v142, vcc, 0x1bc85000, v68
	global_load_dwordx4 v[60:63], v[82:83], off
	s_nop 0
	v_addc_co_u32_e32 v143, vcc, 0, v69, vcc
	v_add_co_u32_e32 v144, vcc, 0x1c485000, v68
	global_load_dwordx4 v[64:67], v[142:143], off
	s_nop 0
	v_addc_co_u32_e32 v145, vcc, 0, v69, vcc
	global_load_dwordx4 v[118:121], v[144:145], off
	v_add_co_u32_e32 v146, vcc, 0x1cc85000, v68
	s_waitcnt vmcnt(1)
	v_pk_add_f32 v[62:63], v[62:63], v[66:67]
	v_addc_co_u32_e32 v147, vcc, 0, v69, vcc
	global_load_dwordx4 v[122:125], v[146:147], off
	global_load_dwordx4 v[126:129], v[82:83], off offset:1024
	global_load_dwordx4 v[130:133], v[142:143], off offset:1024
	global_load_dwordx4 v[134:137], v[144:145], off offset:1024
	global_load_dwordx4 v[138:141], v[146:147], off offset:1024
	v_pk_add_f32 v[60:61], v[60:61], v[64:65]
	v_add_co_u32_e32 v68, vcc, s0, v68
	s_waitcnt vmcnt(4)
	v_pk_add_f32 v[64:65], v[120:121], v[124:125]
	v_pk_add_f32 v[66:67], v[118:119], v[122:123]
	v_pk_add_f32 v[62:63], v[62:63], v[64:65]
	v_pk_add_f32 v[60:61], v[60:61], v[66:67]
	v_pk_fma_f32 v[66:67], v[54:55], v[62:63], v[38:39]
	v_pk_fma_f32 v[64:65], v[52:53], v[60:61], v[36:37]
	s_waitcnt vmcnt(2)
	v_pk_add_f32 v[52:53], v[128:129], v[132:133]
	v_pk_add_f32 v[54:55], v[126:127], v[130:131]
	s_waitcnt vmcnt(0)
	v_pk_add_f32 v[60:61], v[136:137], v[140:141]
	v_pk_add_f32 v[62:63], v[134:135], v[138:139]
	v_pk_add_f32 v[52:53], v[52:53], v[60:61]
	v_pk_add_f32 v[54:55], v[54:55], v[62:63]
	v_pk_fma_f32 v[62:63], v[58:59], v[52:53], v[50:51]
	v_pk_fma_f32 v[60:61], v[56:57], v[54:55], v[48:49]
	global_load_dwordx4 v[52:55], v[82:83], off offset:2048
	global_load_dwordx4 v[56:59], v[142:143], off offset:2048
	global_load_dwordx4 v[118:121], v[144:145], off offset:2048
	global_load_dwordx4 v[122:125], v[146:147], off offset:2048
	global_load_dwordx4 v[126:129], v[82:83], off offset:3072
	global_load_dwordx4 v[130:133], v[142:143], off offset:3072
	global_load_dwordx4 v[134:137], v[144:145], off offset:3072
	global_load_dwordx4 v[138:141], v[146:147], off offset:3072
	v_addc_co_u32_e32 v69, vcc, 0, v69, vcc
	s_waitcnt vmcnt(6)
	v_pk_add_f32 v[54:55], v[54:55], v[58:59]
	v_pk_add_f32 v[52:53], v[52:53], v[56:57]
	s_waitcnt vmcnt(4)
	v_pk_add_f32 v[56:57], v[120:121], v[124:125]
	v_pk_add_f32 v[58:59], v[118:119], v[122:123]
	v_pk_add_f32 v[54:55], v[54:55], v[56:57]
	v_pk_add_f32 v[52:53], v[52:53], v[58:59]
	v_pk_fma_f32 v[58:59], v[76:77], v[54:55], v[46:47]
	v_pk_fma_f32 v[56:57], v[74:75], v[52:53], v[44:45]
	s_waitcnt vmcnt(2)
	v_pk_add_f32 v[52:53], v[128:129], v[132:133]
	v_pk_add_f32 v[54:55], v[126:127], v[130:131]
	s_waitcnt vmcnt(0)
	v_pk_add_f32 v[74:75], v[136:137], v[140:141]
	v_pk_add_f32 v[76:77], v[134:135], v[138:139]
	v_pk_add_f32 v[52:53], v[52:53], v[74:75]
	v_pk_add_f32 v[74:75], v[54:55], v[76:77]
	v_pk_fma_f32 v[54:55], v[80:81], v[52:53], v[42:43]
	v_pk_fma_f32 v[52:53], v[78:79], v[74:75], v[40:41]
	global_store_dwordx4 v[68:69], v[64:67], off sc1
	global_store_dwordx4 v[68:69], v[60:63], off offset:1024 sc1
	global_store_dwordx4 v[68:69], v[56:59], off offset:2048 sc1
	global_store_dwordx4 v[68:69], v[52:55], off offset:3072 sc1
	v_pk_mul_f32 v[68:69], v[66:67], v[66:67]
	v_pk_mul_f32 v[74:75], v[64:65], v[64:65]
	v_mul_f32_e32 v71, v52, v52
	v_pk_mov_b32 v[76:77], v[74:75], v[68:69] op_sel:[1,0]
	v_mov_b32_e32 v75, v69
	v_pk_add_f32 v[68:69], v[76:77], v[74:75]
	v_pk_mul_f32 v[74:75], v[62:63], v[62:63]
	v_pk_mul_f32 v[76:77], v[60:61], v[60:61]
	v_mul_f32_e32 v73, v53, v53
	v_pk_mov_b32 v[78:79], v[76:77], v[74:75] op_sel:[1,0]
	v_mov_b32_e32 v77, v75
	v_pk_add_f32 v[74:75], v[78:79], v[76:77]
	v_pk_add_f32 v[68:69], v[68:69], v[68:69] op_sel:[0,1] op_sel_hi:[1,0]
	v_pk_add_f32 v[74:75], v[74:75], v[74:75] op_sel:[0,1] op_sel_hi:[1,0]
	v_mov_b32_e32 v69, v71
	v_mov_b32_e32 v75, v73
	v_pk_add_f32 v[68:69], v[68:69], v[74:75]
	v_mul_f32_e32 v74, v57, v57
	v_mul_f32_e32 v76, v54, v54
	v_pk_fma_f32 v[74:75], v[56:57], v[56:57], v[74:75] op_sel_hi:[1,1,0]
	v_mul_f32_e32 v78, v55, v55
	v_mov_b32_e32 v75, v76
	v_mul_f32_e32 v76, v59, v59
	v_pk_fma_f32 v[76:77], v[58:59], v[58:59], v[76:77] op_sel_hi:[1,1,0]
	s_nop 0
	v_mov_b32_e32 v77, v78
	v_pk_add_f32 v[74:75], v[74:75], v[76:77]
	s_nop 0
	v_pk_add_f32 v[68:69], v[68:69], v[74:75]
	s_nop 0
	v_add_f32_e32 v68, v68, v69
	v_mov_b32_e32 v69, v181
	s_nop 0
	v_add_f32_dpp v68, v68, v68 row_shr:1 row_mask:0xf bank_mask:0xf bound_ctrl:1
	s_nop 1
	v_add_f32_dpp v68, v68, v68 row_shr:2 row_mask:0xf bank_mask:0xf bound_ctrl:1
	s_nop 1
	v_add_f32_dpp v68, v68, v68 row_shr:4 row_mask:0xf bank_mask:0xf bound_ctrl:1
	s_nop 1
	v_add_f32_dpp v68, v68, v68 row_shr:8 row_mask:0xf bank_mask:0xf bound_ctrl:1
	s_nop 1
	v_mov_b32_dpp v69, v68 row_bcast:15 row_mask:0xa bank_mask:0xf
	v_add_f32_e32 v68, v68, v69
	v_mov_b32_e32 v69, v181
	s_nop 1
	v_mov_b32_dpp v69, v68 row_bcast:31 row_mask:0xc bank_mask:0xf
	v_add_f32_e32 v68, v68, v69
	s_nop 0
	v_readlane_b32 s0, v68, 63
	s_nop 1
	v_fma_f32 v68, s0, v247, v237
	v_rsq_f32_e32 v68, v68
	s_mov_b32 s0, 0x3e85000
	v_pk_mul_f32 v[78:79], v[64:65], v[68:69] op_sel_hi:[1,0]
	v_pk_mul_f32 v[80:81], v[66:67], v[68:69] op_sel_hi:[1,0]
	v_add_u32_e32 v69, v114, v180
	ds_read_b128 v[64:67], v69 offset:40960
	ds_read_b128 v[74:77], v69 offset:45056
	v_lshlrev_b32_e32 v180, 3, v70
	s_waitcnt lgkmcnt(0)
	v_pk_fma_f32 v[66:67], v[66:67], v[80:81], v[76:77]
	v_pk_fma_f32 v[64:65], v[64:65], v[78:79], v[74:75]
	v_pk_mul_f32 v[74:75], v[60:61], v[68:69] op_sel_hi:[1,0]
	v_cvt_pk_bf16_f32 v64, v64, v65
	v_cvt_pk_bf16_f32 v65, v66, v67
	v_lshl_add_u64 v[66:67], v[106:107], 0, v[180:181]
	v_lshl_add_u64 v[66:67], s[78:79], 0, v[66:67]
	v_add_co_u32_e32 v70, vcc, s0, v66
	v_pk_mul_f32 v[76:77], v[62:63], v[68:69] op_sel_hi:[1,0]
	s_nop 0
	v_addc_co_u32_e32 v71, vcc, 0, v67, vcc
	global_store_dwordx2 v[70:71], v[64:65], off sc1
	ds_read_b128 v[60:63], v69 offset:41984
	ds_read_b128 v[64:67], v69 offset:46080
	s_waitcnt lgkmcnt(0)
	v_pk_fma_f32 v[62:63], v[62:63], v[76:77], v[66:67]
	v_pk_fma_f32 v[60:61], v[60:61], v[74:75], v[64:65]
	v_pk_mul_f32 v[64:65], v[56:57], v[68:69] op_sel_hi:[1,0]
	v_cvt_pk_bf16_f32 v60, v60, v61
	v_cvt_pk_bf16_f32 v61, v62, v63
	global_store_dwordx2 v[70:71], v[60:61], off offset:512 sc1
	v_pk_mul_f32 v[66:67], v[58:59], v[68:69] op_sel_hi:[1,0]
	ds_read_b128 v[56:59], v69 offset:43008
	ds_read_b128 v[60:63], v69 offset:47104
	s_waitcnt lgkmcnt(0)
	v_pk_fma_f32 v[58:59], v[66:67], v[58:59], v[62:63]
	v_pk_fma_f32 v[56:57], v[64:65], v[56:57], v[60:61]
	v_pk_mul_f32 v[60:61], v[52:53], v[68:69] op_sel_hi:[1,0]
	v_cvt_pk_bf16_f32 v56, v56, v57
	v_cvt_pk_bf16_f32 v57, v58, v59
	global_store_dwordx2 v[70:71], v[56:57], off offset:1024 sc1
	v_pk_mul_f32 v[62:63], v[54:55], v[68:69] op_sel_hi:[1,0]
	ds_read_b128 v[52:55], v69 offset:44032
	ds_read_b128 v[56:59], v69 offset:48128
	s_waitcnt lgkmcnt(0)
	v_pk_fma_f32 v[54:55], v[62:63], v[54:55], v[58:59]
	v_pk_fma_f32 v[52:53], v[60:61], v[52:53], v[56:57]
	s_nop 0
	v_cvt_pk_bf16_f32 v52, v52, v53
	v_cvt_pk_bf16_f32 v53, v54, v55
	global_store_dwordx2 v[70:71], v[52:53], off offset:1536 sc1
	s_branch .LBB0_227

.LBB0_258:
	s_add_i32 s26, s26, s88
	s_lshl_b32 s0, s0, 8
	s_add_i32 s48, s26, -8
	s_or_b32 s0, s0, s83
	s_lshr_b32 s2, s48, 4
	v_mov_b32_e32 v148, v185
	v_mov_b32_e32 v68, v187
	s_cmp_gt_i32 s26, 7
	s_mov_b64 s[4:5], -1
	v_lshl_add_u32 v170, v68, 2, s0
	s_cselect_b64 s[0:1], -1, 0
	s_and_b64 vcc, s[0:1], exec
	s_cselect_b32 s0, s2, 8
	s_mul_hi_u32 s1, s0, 0x6000
	s_mulk_i32 s0, 0x6000
	s_add_u32 s0, s65, s0
	s_addc_u32 s1, s76, s1
	v_ashrrev_i32_e32 v171, 31, v170
	v_lshl_add_u64 v[68:69], v[170:171], 2, s[0:1]
	global_load_dwordx4 v[80:83], v[68:69], off
	global_load_dwordx4 v[76:79], v[68:69], off offset:64
	global_load_dwordx4 v[72:75], v[68:69], off offset:512
	s_nop 0
	global_load_dwordx4 v[68:71], v[68:69], off offset:576
	v_add_u32_e32 v158, s82, v148
	v_ashrrev_i32_e32 v159, 31, v158
	v_add_u32_e32 v172, 16, v158
	v_add_u32_e32 v168, 32, v158
	v_add_u32_e32 v166, 48, v158
	v_add_u32_e32 v164, 0x80, v158
	v_add_u32_e32 v162, 0x90, v158
	v_add_u32_e32 v160, 0xa0, v158
	s_cbranch_vccz .LBB0_265
	s_lshl_b64 s[28:29], s[48:49], 20
	s_and_b64 vcc, exec, s[16:17]
	v_lshlrev_b64 v[174:175], 1, v[170:171]
	v_ashrrev_i32_e32 v173, 31, v172
	v_ashrrev_i32_e32 v169, 31, v168
	v_ashrrev_i32_e32 v167, 31, v166
	v_ashrrev_i32_e32 v165, 31, v164
	v_ashrrev_i32_e32 v163, 31, v162
	v_ashrrev_i32_e32 v161, 31, v160
	s_cbranch_vccz .LBB0_261
	s_add_u32 s30, s10, s28
	s_addc_u32 s31, s11, s29
	v_lshl_add_u64 v[148:149], s[30:31], 0, v[174:175]
	v_lshlrev_b64 v[214:215], 12, v[158:159]
	v_lshl_add_u64 v[150:151], v[148:149], 0, v[214:215]
	global_load_dwordx2 v[216:217], v[150:151], off
	global_load_dwordx2 v[218:219], v[150:151], off offset:32
	global_load_dwordx2 v[220:221], v[150:151], off offset:256
	global_load_dwordx2 v[222:223], v[150:151], off offset:288
	v_lshlrev_b64 v[210:211], 12, v[172:173]
	v_lshl_add_u64 v[150:151], v[148:149], 0, v[210:211]
	global_load_dwordx2 v[208:209], v[150:151], off
	global_load_dwordx2 v[206:207], v[150:151], off offset:32
	global_load_dwordx2 v[204:205], v[150:151], off offset:256
	global_load_dwordx2 v[202:203], v[150:151], off offset:288
	v_lshlrev_b64 v[200:201], 12, v[168:169]
	v_lshl_add_u64 v[150:151], v[148:149], 0, v[200:201]
	global_load_dwordx2 v[198:199], v[150:151], off
	global_load_dwordx2 v[196:197], v[150:151], off offset:32
	global_load_dwordx2 v[194:195], v[150:151], off offset:256
	global_load_dwordx2 v[188:189], v[150:151], off offset:288
	v_lshlrev_b64 v[192:193], 12, v[166:167]
	v_lshl_add_u64 v[150:151], v[148:149], 0, v[192:193]
	global_load_dwordx2 v[190:191], v[150:151], off
	global_load_dwordx2 v[178:179], v[150:151], off offset:32
	global_load_dwordx2 v[176:177], v[150:151], off offset:256
	s_nop 0
	global_load_dwordx2 v[150:151], v[150:151], off offset:288
	v_lshl_add_u64 v[214:215], s[30:31], 0, v[214:215]
	v_lshl_add_u64 v[214:215], v[214:215], 0, v[174:175]
	v_lshl_add_u64 v[210:211], s[30:31], 0, v[210:211]
	v_lshl_add_u64 v[200:201], s[30:31], 0, v[200:201]
	s_mov_b64 s[4:5], 0
	s_waitcnt vmcnt(0)
	v_lshlrev_b32_e32 v224, 16, v216
	v_and_b32_e32 v225, 0xffff0000, v216
	v_lshlrev_b32_e32 v216, 16, v217
	v_and_b32_e32 v217, 0xffff0000, v217
	v_pk_fma_f32 v[216:217], v[146:147], v[82:83], v[216:217]
	v_pk_fma_f32 v[224:225], v[144:145], v[80:81], v[224:225]
	s_nop 0
	v_cvt_pk_bf16_f32 v224, v224, v225
	v_cvt_pk_bf16_f32 v225, v216, v217
	v_lshlrev_b32_e32 v216, 16, v218
	v_and_b32_e32 v217, 0xffff0000, v218
	v_lshlrev_b32_e32 v218, 16, v219
	v_and_b32_e32 v219, 0xffff0000, v219
	v_pk_fma_f32 v[218:219], v[142:143], v[78:79], v[218:219]
	v_pk_fma_f32 v[216:217], v[140:141], v[76:77], v[216:217]
	global_store_dwordx2 v[214:215], v[224:225], off sc1
	v_cvt_pk_bf16_f32 v216, v216, v217
	v_cvt_pk_bf16_f32 v217, v218, v219
	global_store_dwordx2 v[214:215], v[216:217], off offset:32 sc1
	v_lshlrev_b32_e32 v216, 16, v220
	v_and_b32_e32 v217, 0xffff0000, v220
	v_lshlrev_b32_e32 v218, 16, v221
	v_and_b32_e32 v219, 0xffff0000, v221
	v_pk_fma_f32 v[218:219], v[130:131], v[74:75], v[218:219]
	v_pk_fma_f32 v[216:217], v[128:129], v[72:73], v[216:217]
	s_nop 0
	v_cvt_pk_bf16_f32 v216, v216, v217
	v_cvt_pk_bf16_f32 v217, v218, v219
	global_store_dwordx2 v[214:215], v[216:217], off offset:256 sc1
	v_lshlrev_b32_e32 v216, 16, v222
	v_and_b32_e32 v217, 0xffff0000, v222
	v_lshlrev_b32_e32 v218, 16, v223
	v_and_b32_e32 v219, 0xffff0000, v223
	v_pk_fma_f32 v[218:219], v[126:127], v[70:71], v[218:219]
	v_pk_fma_f32 v[216:217], v[124:125], v[68:69], v[216:217]
	s_nop 0
	v_cvt_pk_bf16_f32 v216, v216, v217
	v_cvt_pk_bf16_f32 v217, v218, v219
	global_store_dwordx2 v[214:215], v[216:217], off offset:288 sc1
	v_lshlrev_b32_e32 v214, 16, v208
	v_and_b32_e32 v215, 0xffff0000, v208
	v_lshlrev_b32_e32 v208, 16, v209
	v_and_b32_e32 v209, 0xffff0000, v209
	v_pk_fma_f32 v[208:209], v[138:139], v[82:83], v[208:209]
	v_pk_fma_f32 v[214:215], v[136:137], v[80:81], v[214:215]
	s_nop 0
	v_cvt_pk_bf16_f32 v214, v214, v215
	v_cvt_pk_bf16_f32 v215, v208, v209
	v_lshl_add_u64 v[208:209], v[210:211], 0, v[174:175]
	v_lshlrev_b32_e32 v210, 16, v206
	v_and_b32_e32 v211, 0xffff0000, v206
	v_lshlrev_b32_e32 v206, 16, v207
	v_and_b32_e32 v207, 0xffff0000, v207
	v_pk_fma_f32 v[206:207], v[134:135], v[78:79], v[206:207]
	v_pk_fma_f32 v[210:211], v[132:133], v[76:77], v[210:211]
	global_store_dwordx2 v[208:209], v[214:215], off sc1
	v_cvt_pk_bf16_f32 v210, v210, v211
	v_cvt_pk_bf16_f32 v211, v206, v207
	v_lshlrev_b32_e32 v206, 16, v204
	v_and_b32_e32 v207, 0xffff0000, v204
	v_lshlrev_b32_e32 v204, 16, v205
	v_and_b32_e32 v205, 0xffff0000, v205
	v_pk_fma_f32 v[204:205], v[122:123], v[74:75], v[204:205]
	v_pk_fma_f32 v[206:207], v[120:121], v[72:73], v[206:207]
	global_store_dwordx2 v[208:209], v[210:211], off offset:32 sc1
	v_cvt_pk_bf16_f32 v206, v206, v207
	v_cvt_pk_bf16_f32 v207, v204, v205
	v_lshlrev_b32_e32 v204, 16, v202
	v_and_b32_e32 v205, 0xffff0000, v202
	v_lshlrev_b32_e32 v202, 16, v203
	v_and_b32_e32 v203, 0xffff0000, v203
	v_pk_fma_f32 v[202:203], v[118:119], v[70:71], v[202:203]
	v_pk_fma_f32 v[204:205], v[116:117], v[68:69], v[204:205]
	global_store_dwordx2 v[208:209], v[206:207], off offset:256 sc1
	v_cvt_pk_bf16_f32 v204, v204, v205
	v_cvt_pk_bf16_f32 v205, v202, v203
	v_lshlrev_b32_e32 v202, 16, v198
	v_and_b32_e32 v203, 0xffff0000, v198
	v_lshlrev_b32_e32 v198, 16, v199
	v_and_b32_e32 v199, 0xffff0000, v199
	v_pk_fma_f32 v[198:199], v[114:115], v[82:83], v[198:199]
	v_pk_fma_f32 v[202:203], v[112:113], v[80:81], v[202:203]
	global_store_dwordx2 v[208:209], v[204:205], off offset:288 sc1
	v_cvt_pk_bf16_f32 v202, v202, v203
	v_cvt_pk_bf16_f32 v203, v198, v199
	v_lshl_add_u64 v[198:199], v[200:201], 0, v[174:175]
	v_lshlrev_b32_e32 v200, 16, v196
	v_and_b32_e32 v201, 0xffff0000, v196
	v_lshlrev_b32_e32 v196, 16, v197
	v_and_b32_e32 v197, 0xffff0000, v197
	v_pk_fma_f32 v[196:197], v[110:111], v[78:79], v[196:197]
	v_pk_fma_f32 v[200:201], v[108:109], v[76:77], v[200:201]
	global_store_dwordx2 v[198:199], v[202:203], off sc1
	v_cvt_pk_bf16_f32 v200, v200, v201
	v_cvt_pk_bf16_f32 v201, v196, v197
	v_lshlrev_b32_e32 v196, 16, v194
	v_and_b32_e32 v197, 0xffff0000, v194
	v_lshlrev_b32_e32 v194, 16, v195
	v_and_b32_e32 v195, 0xffff0000, v195
	v_pk_fma_f32 v[194:195], v[98:99], v[74:75], v[194:195]
	v_pk_fma_f32 v[196:197], v[96:97], v[72:73], v[196:197]
	global_store_dwordx2 v[198:199], v[200:201], off offset:32 sc1
	v_cvt_pk_bf16_f32 v196, v196, v197
	v_cvt_pk_bf16_f32 v197, v194, v195
	v_lshlrev_b32_e32 v194, 16, v188
	v_and_b32_e32 v195, 0xffff0000, v188
	v_lshlrev_b32_e32 v188, 16, v189
	v_and_b32_e32 v189, 0xffff0000, v189
	v_pk_fma_f32 v[188:189], v[94:95], v[70:71], v[188:189]
	v_pk_fma_f32 v[194:195], v[92:93], v[68:69], v[194:195]
	global_store_dwordx2 v[198:199], v[196:197], off offset:256 sc1
	v_cvt_pk_bf16_f32 v194, v194, v195
	v_cvt_pk_bf16_f32 v195, v188, v189
	v_lshl_add_u64 v[188:189], s[30:31], 0, v[192:193]
	v_lshlrev_b32_e32 v192, 16, v190
	v_and_b32_e32 v193, 0xffff0000, v190
	v_lshlrev_b32_e32 v190, 16, v191
	v_and_b32_e32 v191, 0xffff0000, v191
	v_pk_fma_f32 v[190:191], v[106:107], v[82:83], v[190:191]
	v_pk_fma_f32 v[192:193], v[104:105], v[80:81], v[192:193]
	v_lshl_add_u64 v[188:189], v[188:189], 0, v[174:175]
	v_cvt_pk_bf16_f32 v192, v192, v193
	v_cvt_pk_bf16_f32 v193, v190, v191
	v_lshlrev_b32_e32 v190, 16, v178
	v_and_b32_e32 v191, 0xffff0000, v178
	v_lshlrev_b32_e32 v178, 16, v179
	v_and_b32_e32 v179, 0xffff0000, v179
	v_pk_fma_f32 v[178:179], v[102:103], v[78:79], v[178:179]
	v_pk_fma_f32 v[190:191], v[100:101], v[76:77], v[190:191]
	global_store_dwordx2 v[198:199], v[194:195], off offset:288 sc1
	v_cvt_pk_bf16_f32 v190, v190, v191
	v_cvt_pk_bf16_f32 v191, v178, v179
	v_lshlrev_b32_e32 v178, 16, v176
	v_and_b32_e32 v179, 0xffff0000, v176
	v_lshlrev_b32_e32 v176, 16, v177
	v_and_b32_e32 v177, 0xffff0000, v177
	v_pk_fma_f32 v[176:177], v[90:91], v[74:75], v[176:177]
	v_pk_fma_f32 v[178:179], v[88:89], v[72:73], v[178:179]
	global_store_dwordx2 v[188:189], v[192:193], off sc1
	v_cvt_pk_bf16_f32 v178, v178, v179
	v_cvt_pk_bf16_f32 v179, v176, v177
	v_lshlrev_b32_e32 v176, 16, v150
	v_and_b32_e32 v177, 0xffff0000, v150
	v_lshlrev_b32_e32 v150, 16, v151
	v_and_b32_e32 v151, 0xffff0000, v151
	v_pk_fma_f32 v[150:151], v[86:87], v[70:71], v[150:151]
	v_pk_fma_f32 v[176:177], v[84:85], v[68:69], v[176:177]
	global_store_dwordx2 v[188:189], v[190:191], off offset:32 sc1
	v_cvt_pk_bf16_f32 v176, v176, v177
	v_cvt_pk_bf16_f32 v177, v150, v151
	global_store_dwordx2 v[188:189], v[178:179], off offset:256 sc1
	global_store_dwordx2 v[188:189], v[176:177], off offset:288 sc1
	v_lshlrev_b64 v[150:151], 12, v[164:165]
	v_lshl_add_u64 v[176:177], v[148:149], 0, v[150:151]
	global_load_dwordx2 v[178:179], v[176:177], off
	global_load_dwordx2 v[188:189], v[176:177], off offset:32
	global_load_dwordx2 v[190:191], v[176:177], off offset:256
	s_nop 0
	global_load_dwordx2 v[176:177], v[176:177], off offset:288
	v_lshlrev_b64 v[192:193], 12, v[162:163]
	v_lshl_add_u64 v[194:195], v[148:149], 0, v[192:193]
	global_load_dwordx2 v[196:197], v[194:195], off
	global_load_dwordx2 v[198:199], v[194:195], off offset:32
	global_load_dwordx2 v[200:201], v[194:195], off offset:256
	s_nop 0
	global_load_dwordx2 v[194:195], v[194:195], off offset:288
	v_lshlrev_b64 v[202:203], 12, v[160:161]
	v_lshl_add_u64 v[204:205], v[148:149], 0, v[202:203]
	global_load_dwordx2 v[206:207], v[204:205], off
	global_load_dwordx2 v[208:209], v[204:205], off offset:32
	global_load_dwordx2 v[210:211], v[204:205], off offset:256
	s_nop 0
	global_load_dwordx2 v[204:205], v[204:205], off offset:288
	v_add_u32_e32 v214, 0xb0, v158
	v_ashrrev_i32_e32 v215, 31, v214
	v_lshlrev_b64 v[214:215], 12, v[214:215]
	v_lshl_add_u64 v[148:149], v[148:149], 0, v[214:215]
	global_load_dwordx2 v[216:217], v[148:149], off
	global_load_dwordx2 v[218:219], v[148:149], off offset:32
	global_load_dwordx2 v[220:221], v[148:149], off offset:256
	s_nop 0
	global_load_dwordx2 v[148:149], v[148:149], off offset:288
	v_lshl_add_u64 v[150:151], s[30:31], 0, v[150:151]
	v_lshl_add_u64 v[150:151], v[150:151], 0, v[174:175]
	s_waitcnt vmcnt(15)
	v_lshlrev_b32_e32 v222, 16, v178
	v_and_b32_e32 v223, 0xffff0000, v178
	v_lshlrev_b32_e32 v178, 16, v179
	v_and_b32_e32 v179, 0xffff0000, v179
	v_pk_fma_f32 v[178:179], v[66:67], v[82:83], v[178:179]
	v_pk_fma_f32 v[222:223], v[64:65], v[80:81], v[222:223]
	s_nop 0
	v_cvt_pk_bf16_f32 v222, v222, v223
	v_cvt_pk_bf16_f32 v223, v178, v179
	s_waitcnt vmcnt(14)
	v_lshlrev_b32_e32 v178, 16, v188
	v_and_b32_e32 v179, 0xffff0000, v188
	v_lshlrev_b32_e32 v188, 16, v189
	v_and_b32_e32 v189, 0xffff0000, v189
	v_pk_fma_f32 v[188:189], v[62:63], v[78:79], v[188:189]
	v_pk_fma_f32 v[178:179], v[60:61], v[76:77], v[178:179]
	global_store_dwordx2 v[150:151], v[222:223], off sc1
	v_cvt_pk_bf16_f32 v178, v178, v179
	v_cvt_pk_bf16_f32 v179, v188, v189
	global_store_dwordx2 v[150:151], v[178:179], off offset:32 sc1
	s_waitcnt vmcnt(15)
	v_lshlrev_b32_e32 v178, 16, v190
	v_and_b32_e32 v179, 0xffff0000, v190
	v_lshlrev_b32_e32 v188, 16, v191
	v_and_b32_e32 v189, 0xffff0000, v191
	v_pk_fma_f32 v[188:189], v[50:51], v[74:75], v[188:189]
	v_pk_fma_f32 v[178:179], v[48:49], v[72:73], v[178:179]
	s_nop 0
	v_cvt_pk_bf16_f32 v178, v178, v179
	v_cvt_pk_bf16_f32 v179, v188, v189
	global_store_dwordx2 v[150:151], v[178:179], off offset:256 sc1
	s_waitcnt vmcnt(15)
	v_lshlrev_b32_e32 v178, 16, v176
	v_and_b32_e32 v179, 0xffff0000, v176
	v_lshlrev_b32_e32 v176, 16, v177
	v_and_b32_e32 v177, 0xffff0000, v177
	v_pk_fma_f32 v[176:177], v[46:47], v[70:71], v[176:177]
	v_pk_fma_f32 v[178:179], v[44:45], v[68:69], v[178:179]
	s_nop 0
	v_cvt_pk_bf16_f32 v178, v178, v179
	v_cvt_pk_bf16_f32 v179, v176, v177
	global_store_dwordx2 v[150:151], v[178:179], off offset:288 sc1
	s_waitcnt vmcnt(15)
	v_lshlrev_b32_e32 v176, 16, v196
	v_and_b32_e32 v177, 0xffff0000, v196
	v_lshlrev_b32_e32 v178, 16, v197
	v_and_b32_e32 v179, 0xffff0000, v197
	v_lshl_add_u64 v[150:151], s[30:31], 0, v[192:193]
	v_pk_fma_f32 v[178:179], v[58:59], v[82:83], v[178:179]
	v_pk_fma_f32 v[176:177], v[56:57], v[80:81], v[176:177]
	v_lshl_add_u64 v[150:151], v[150:151], 0, v[174:175]
	v_cvt_pk_bf16_f32 v176, v176, v177
	v_cvt_pk_bf16_f32 v177, v178, v179
	global_store_dwordx2 v[150:151], v[176:177], off sc1
	s_waitcnt vmcnt(15)
	v_lshlrev_b32_e32 v176, 16, v198
	v_and_b32_e32 v177, 0xffff0000, v198
	v_lshlrev_b32_e32 v178, 16, v199
	v_and_b32_e32 v179, 0xffff0000, v199
	v_pk_fma_f32 v[178:179], v[54:55], v[78:79], v[178:179]
	v_pk_fma_f32 v[176:177], v[52:53], v[76:77], v[176:177]
	s_nop 0
	v_cvt_pk_bf16_f32 v176, v176, v177
	v_cvt_pk_bf16_f32 v177, v178, v179
	global_store_dwordx2 v[150:151], v[176:177], off offset:32 sc1
	s_waitcnt vmcnt(15)
	v_lshlrev_b32_e32 v176, 16, v200
	v_and_b32_e32 v177, 0xffff0000, v200
	v_lshlrev_b32_e32 v178, 16, v201
	v_and_b32_e32 v179, 0xffff0000, v201
	v_pk_fma_f32 v[178:179], v[42:43], v[74:75], v[178:179]
	v_pk_fma_f32 v[176:177], v[40:41], v[72:73], v[176:177]
	s_nop 0
	v_cvt_pk_bf16_f32 v176, v176, v177
	v_cvt_pk_bf16_f32 v177, v178, v179
	global_store_dwordx2 v[150:151], v[176:177], off offset:256 sc1
	s_waitcnt vmcnt(15)
	v_lshlrev_b32_e32 v176, 16, v194
	v_and_b32_e32 v177, 0xffff0000, v194
	v_lshlrev_b32_e32 v178, 16, v195
	v_and_b32_e32 v179, 0xffff0000, v195
	v_pk_fma_f32 v[178:179], v[38:39], v[70:71], v[178:179]
	v_pk_fma_f32 v[176:177], v[36:37], v[68:69], v[176:177]
	s_nop 0
	v_cvt_pk_bf16_f32 v176, v176, v177
	v_cvt_pk_bf16_f32 v177, v178, v179
	global_store_dwordx2 v[150:151], v[176:177], off offset:288 sc1
	s_waitcnt vmcnt(15)
	v_lshlrev_b32_e32 v176, 16, v206
	v_and_b32_e32 v177, 0xffff0000, v206
	v_lshlrev_b32_e32 v178, 16, v207
	v_and_b32_e32 v179, 0xffff0000, v207
	v_lshl_add_u64 v[150:151], s[30:31], 0, v[202:203]
	v_pk_fma_f32 v[178:179], v[34:35], v[82:83], v[178:179]
	v_pk_fma_f32 v[176:177], v[32:33], v[80:81], v[176:177]
	v_lshl_add_u64 v[150:151], v[150:151], 0, v[174:175]
	v_cvt_pk_bf16_f32 v176, v176, v177
	v_cvt_pk_bf16_f32 v177, v178, v179
	global_store_dwordx2 v[150:151], v[176:177], off sc1
	s_waitcnt vmcnt(15)
	v_lshlrev_b32_e32 v176, 16, v208
	v_and_b32_e32 v177, 0xffff0000, v208
	v_lshlrev_b32_e32 v178, 16, v209
	v_and_b32_e32 v179, 0xffff0000, v209
	v_pk_fma_f32 v[178:179], v[30:31], v[78:79], v[178:179]
	v_pk_fma_f32 v[176:177], v[28:29], v[76:77], v[176:177]
	s_nop 0
	v_cvt_pk_bf16_f32 v176, v176, v177
	v_cvt_pk_bf16_f32 v177, v178, v179
	global_store_dwordx2 v[150:151], v[176:177], off offset:32 sc1
	s_waitcnt vmcnt(15)
	v_lshlrev_b32_e32 v176, 16, v210
	v_and_b32_e32 v177, 0xffff0000, v210
	v_lshlrev_b32_e32 v178, 16, v211
	v_and_b32_e32 v179, 0xffff0000, v211
	v_pk_fma_f32 v[178:179], v[26:27], v[74:75], v[178:179]
	v_pk_fma_f32 v[176:177], v[24:25], v[72:73], v[176:177]
	s_nop 0
	v_cvt_pk_bf16_f32 v176, v176, v177
	v_cvt_pk_bf16_f32 v177, v178, v179
	global_store_dwordx2 v[150:151], v[176:177], off offset:256 sc1
	s_waitcnt vmcnt(15)
	v_lshlrev_b32_e32 v176, 16, v204
	v_and_b32_e32 v177, 0xffff0000, v204
	v_lshlrev_b32_e32 v178, 16, v205
	v_and_b32_e32 v179, 0xffff0000, v205
	v_pk_fma_f32 v[178:179], v[22:23], v[70:71], v[178:179]
	v_pk_fma_f32 v[176:177], v[20:21], v[68:69], v[176:177]
	s_nop 0
	v_cvt_pk_bf16_f32 v176, v176, v177
	v_cvt_pk_bf16_f32 v177, v178, v179
	global_store_dwordx2 v[150:151], v[176:177], off offset:288 sc1
	s_waitcnt vmcnt(15)
	v_lshlrev_b32_e32 v176, 16, v216
	v_and_b32_e32 v177, 0xffff0000, v216
	v_lshlrev_b32_e32 v178, 16, v217
	v_and_b32_e32 v179, 0xffff0000, v217
	v_lshl_add_u64 v[150:151], s[30:31], 0, v[214:215]
	v_pk_fma_f32 v[178:179], v[18:19], v[82:83], v[178:179]
	v_pk_fma_f32 v[176:177], v[16:17], v[80:81], v[176:177]
	v_lshl_add_u64 v[150:151], v[150:151], 0, v[174:175]
	v_cvt_pk_bf16_f32 v176, v176, v177
	v_cvt_pk_bf16_f32 v177, v178, v179
	global_store_dwordx2 v[150:151], v[176:177], off sc1
	s_waitcnt vmcnt(15)
	v_lshlrev_b32_e32 v176, 16, v218
	v_and_b32_e32 v177, 0xffff0000, v218
	v_lshlrev_b32_e32 v178, 16, v219
	v_and_b32_e32 v179, 0xffff0000, v219
	v_pk_fma_f32 v[178:179], v[14:15], v[78:79], v[178:179]
	v_pk_fma_f32 v[176:177], v[12:13], v[76:77], v[176:177]
	s_nop 0
	v_cvt_pk_bf16_f32 v176, v176, v177
	v_cvt_pk_bf16_f32 v177, v178, v179
	global_store_dwordx2 v[150:151], v[176:177], off offset:32 sc1
	s_waitcnt vmcnt(15)
	v_lshlrev_b32_e32 v176, 16, v220
	v_and_b32_e32 v177, 0xffff0000, v220
	v_lshlrev_b32_e32 v178, 16, v221
	v_and_b32_e32 v179, 0xffff0000, v221
	v_pk_fma_f32 v[178:179], v[10:11], v[74:75], v[178:179]
	v_pk_fma_f32 v[176:177], v[8:9], v[72:73], v[176:177]
	s_nop 0
	v_cvt_pk_bf16_f32 v176, v176, v177
	v_cvt_pk_bf16_f32 v177, v178, v179
	global_store_dwordx2 v[150:151], v[176:177], off offset:256 sc1
	s_waitcnt vmcnt(15)
	v_lshlrev_b32_e32 v176, 16, v148
	v_and_b32_e32 v177, 0xffff0000, v148
	v_lshlrev_b32_e32 v148, 16, v149
	v_and_b32_e32 v149, 0xffff0000, v149
	v_pk_fma_f32 v[148:149], v[6:7], v[70:71], v[148:149]
	v_pk_fma_f32 v[176:177], v[4:5], v[68:69], v[176:177]
	s_nop 0
	v_cvt_pk_bf16_f32 v176, v176, v177
	v_cvt_pk_bf16_f32 v177, v148, v149
	global_store_dwordx2 v[150:151], v[176:177], off offset:288 sc1
.LBB0_261:
	s_andn2_b64 vcc, exec, s[4:5]
	s_cbranch_vccnz .LBB0_263
	v_lshl_add_u64 v[148:149], v[170:171], 2, s[28:29]
	v_lshlrev_b64 v[150:151], 12, v[158:159]
	v_lshl_add_u64 v[196:197], v[148:149], 0, v[150:151]
	global_load_dwordx4 v[176:179], v[196:197], off
	global_load_dwordx4 v[188:191], v[196:197], off offset:64
	global_load_dwordx4 v[192:195], v[196:197], off offset:512
	s_nop 0
	global_load_dwordx4 v[196:199], v[196:197], off offset:576
	v_lshlrev_b64 v[218:219], 12, v[172:173]
	v_lshl_add_u64 v[214:215], v[148:149], 0, v[218:219]
	global_load_dwordx4 v[200:203], v[214:215], off
	global_load_dwordx4 v[204:207], v[214:215], off offset:64
	global_load_dwordx4 v[208:211], v[214:215], off offset:512
	s_nop 0
	global_load_dwordx4 v[214:217], v[214:215], off offset:576
	v_lshl_add_u64 v[150:151], s[28:29], 0, v[150:151]
	v_lshl_add_u64 v[150:151], v[150:151], 0, v[174:175]
	s_waitcnt vmcnt(0)
	v_pk_fma_f32 v[178:179], v[146:147], v[82:83], v[178:179]
	v_pk_fma_f32 v[176:177], v[144:145], v[80:81], v[176:177]
	s_nop 0
	v_cvt_pk_bf16_f32 v176, v176, v177
	v_cvt_pk_bf16_f32 v177, v178, v179
	global_store_dwordx2 v[150:151], v[176:177], off sc1
	v_pk_fma_f32 v[176:177], v[142:143], v[78:79], v[190:191]
	v_pk_fma_f32 v[178:179], v[140:141], v[76:77], v[188:189]
	s_nop 0
	v_cvt_pk_bf16_f32 v178, v178, v179
	v_cvt_pk_bf16_f32 v179, v176, v177
	global_store_dwordx2 v[150:151], v[178:179], off offset:32 sc1
	v_pk_fma_f32 v[176:177], v[130:131], v[74:75], v[194:195]
	v_pk_fma_f32 v[178:179], v[128:129], v[72:73], v[192:193]
	s_nop 0
	v_cvt_pk_bf16_f32 v178, v178, v179
	v_cvt_pk_bf16_f32 v179, v176, v177
	global_store_dwordx2 v[150:151], v[178:179], off offset:256 sc1
	v_pk_fma_f32 v[176:177], v[126:127], v[70:71], v[198:199]
	v_pk_fma_f32 v[178:179], v[124:125], v[68:69], v[196:197]
	s_nop 0
	v_cvt_pk_bf16_f32 v178, v178, v179
	v_cvt_pk_bf16_f32 v179, v176, v177
	global_store_dwordx2 v[150:151], v[178:179], off offset:288 sc1
	v_lshl_add_u64 v[150:151], s[28:29], 0, v[218:219]
	v_pk_fma_f32 v[176:177], v[138:139], v[82:83], v[202:203]
	v_pk_fma_f32 v[178:179], v[136:137], v[80:81], v[200:201]
	v_lshl_add_u64 v[150:151], v[150:151], 0, v[174:175]
	v_cvt_pk_bf16_f32 v178, v178, v179
	v_cvt_pk_bf16_f32 v179, v176, v177
	global_store_dwordx2 v[150:151], v[178:179], off sc1
	v_pk_fma_f32 v[176:177], v[134:135], v[78:79], v[206:207]
	v_pk_fma_f32 v[178:179], v[132:133], v[76:77], v[204:205]
	v_lshlrev_b64 v[218:219], 12, v[166:167]
	v_cvt_pk_bf16_f32 v178, v178, v179
	v_cvt_pk_bf16_f32 v179, v176, v177
	global_store_dwordx2 v[150:151], v[178:179], off offset:32 sc1
	v_pk_fma_f32 v[176:177], v[122:123], v[74:75], v[210:211]
	v_pk_fma_f32 v[178:179], v[120:121], v[72:73], v[208:209]
	s_nop 0
	v_cvt_pk_bf16_f32 v178, v178, v179
	v_cvt_pk_bf16_f32 v179, v176, v177
	global_store_dwordx2 v[150:151], v[178:179], off offset:256 sc1
	v_pk_fma_f32 v[176:177], v[118:119], v[70:71], v[216:217]
	v_pk_fma_f32 v[178:179], v[116:117], v[68:69], v[214:215]
	v_lshl_add_u64 v[214:215], v[148:149], 0, v[218:219]
	v_cvt_pk_bf16_f32 v178, v178, v179
	v_cvt_pk_bf16_f32 v179, v176, v177
	global_store_dwordx2 v[150:151], v[178:179], off offset:288 sc1
	v_lshlrev_b64 v[150:151], 12, v[168:169]
	v_lshl_add_u64 v[196:197], v[148:149], 0, v[150:151]
	global_load_dwordx4 v[176:179], v[196:197], off
	global_load_dwordx4 v[188:191], v[196:197], off offset:64
	global_load_dwordx4 v[192:195], v[196:197], off offset:512
	s_nop 0
	global_load_dwordx4 v[196:199], v[196:197], off offset:576
	s_nop 0
	global_load_dwordx4 v[200:203], v[214:215], off
	global_load_dwordx4 v[204:207], v[214:215], off offset:64
	global_load_dwordx4 v[208:211], v[214:215], off offset:512
	s_nop 0
	global_load_dwordx4 v[214:217], v[214:215], off offset:576
	v_lshl_add_u64 v[150:151], s[28:29], 0, v[150:151]
	v_lshl_add_u64 v[150:151], v[150:151], 0, v[174:175]
	s_waitcnt vmcnt(7)
	v_pk_fma_f32 v[178:179], v[114:115], v[82:83], v[178:179]
	v_pk_fma_f32 v[176:177], v[112:113], v[80:81], v[176:177]
	s_nop 0
	v_cvt_pk_bf16_f32 v176, v176, v177
	v_cvt_pk_bf16_f32 v177, v178, v179
	global_store_dwordx2 v[150:151], v[176:177], off sc1
	s_waitcnt vmcnt(7)
	v_pk_fma_f32 v[176:177], v[110:111], v[78:79], v[190:191]
	v_pk_fma_f32 v[178:179], v[108:109], v[76:77], v[188:189]
	s_nop 0
	v_cvt_pk_bf16_f32 v178, v178, v179
	v_cvt_pk_bf16_f32 v179, v176, v177
	global_store_dwordx2 v[150:151], v[178:179], off offset:32 sc1
	s_waitcnt vmcnt(7)
	v_pk_fma_f32 v[176:177], v[98:99], v[74:75], v[194:195]
	v_pk_fma_f32 v[178:179], v[96:97], v[72:73], v[192:193]
	s_nop 0
	v_cvt_pk_bf16_f32 v178, v178, v179
	v_cvt_pk_bf16_f32 v179, v176, v177
	global_store_dwordx2 v[150:151], v[178:179], off offset:256 sc1
	s_waitcnt vmcnt(7)
	v_pk_fma_f32 v[176:177], v[94:95], v[70:71], v[198:199]
	v_pk_fma_f32 v[178:179], v[92:93], v[68:69], v[196:197]
	s_nop 0
	v_cvt_pk_bf16_f32 v178, v178, v179
	v_cvt_pk_bf16_f32 v179, v176, v177
	global_store_dwordx2 v[150:151], v[178:179], off offset:288 sc1
	v_lshl_add_u64 v[150:151], s[28:29], 0, v[218:219]
	s_waitcnt vmcnt(7)
	v_pk_fma_f32 v[176:177], v[106:107], v[82:83], v[202:203]
	v_pk_fma_f32 v[178:179], v[104:105], v[80:81], v[200:201]
	v_lshl_add_u64 v[150:151], v[150:151], 0, v[174:175]
	v_cvt_pk_bf16_f32 v178, v178, v179
	v_cvt_pk_bf16_f32 v179, v176, v177
	global_store_dwordx2 v[150:151], v[178:179], off sc1
	s_waitcnt vmcnt(7)
	v_pk_fma_f32 v[176:177], v[102:103], v[78:79], v[206:207]
	v_pk_fma_f32 v[178:179], v[100:101], v[76:77], v[204:205]
	v_lshlrev_b64 v[218:219], 12, v[162:163]
	v_cvt_pk_bf16_f32 v178, v178, v179
	v_cvt_pk_bf16_f32 v179, v176, v177
	global_store_dwordx2 v[150:151], v[178:179], off offset:32 sc1
	s_waitcnt vmcnt(7)
	v_pk_fma_f32 v[176:177], v[90:91], v[74:75], v[210:211]
	v_pk_fma_f32 v[178:179], v[88:89], v[72:73], v[208:209]
	s_nop 0
	v_cvt_pk_bf16_f32 v178, v178, v179
	v_cvt_pk_bf16_f32 v179, v176, v177
	global_store_dwordx2 v[150:151], v[178:179], off offset:256 sc1
	s_waitcnt vmcnt(7)
	v_pk_fma_f32 v[176:177], v[86:87], v[70:71], v[216:217]
	v_pk_fma_f32 v[178:179], v[84:85], v[68:69], v[214:215]
	v_lshl_add_u64 v[214:215], v[148:149], 0, v[218:219]
	v_cvt_pk_bf16_f32 v178, v178, v179
	v_cvt_pk_bf16_f32 v179, v176, v177
	global_store_dwordx2 v[150:151], v[178:179], off offset:288 sc1
	v_lshlrev_b64 v[150:151], 12, v[164:165]
	v_lshl_add_u64 v[196:197], v[148:149], 0, v[150:151]
	global_load_dwordx4 v[176:179], v[196:197], off
	global_load_dwordx4 v[188:191], v[196:197], off offset:64
	global_load_dwordx4 v[192:195], v[196:197], off offset:512
	s_nop 0
	global_load_dwordx4 v[196:199], v[196:197], off offset:576
	s_nop 0
	global_load_dwordx4 v[200:203], v[214:215], off
	global_load_dwordx4 v[204:207], v[214:215], off offset:64
	global_load_dwordx4 v[208:211], v[214:215], off offset:512
	s_nop 0
	global_load_dwordx4 v[214:217], v[214:215], off offset:576
	v_lshl_add_u64 v[150:151], s[28:29], 0, v[150:151]
	v_lshl_add_u64 v[150:151], v[150:151], 0, v[174:175]
	s_waitcnt vmcnt(7)
	v_pk_fma_f32 v[178:179], v[66:67], v[82:83], v[178:179]
	v_pk_fma_f32 v[176:177], v[64:65], v[80:81], v[176:177]
	s_nop 0
	v_cvt_pk_bf16_f32 v176, v176, v177
	v_cvt_pk_bf16_f32 v177, v178, v179
	global_store_dwordx2 v[150:151], v[176:177], off sc1
	s_waitcnt vmcnt(7)
	v_pk_fma_f32 v[176:177], v[62:63], v[78:79], v[190:191]
	v_pk_fma_f32 v[178:179], v[60:61], v[76:77], v[188:189]
	s_nop 0
	v_cvt_pk_bf16_f32 v178, v178, v179
	v_cvt_pk_bf16_f32 v179, v176, v177
	global_store_dwordx2 v[150:151], v[178:179], off offset:32 sc1
	s_waitcnt vmcnt(7)
	v_pk_fma_f32 v[176:177], v[50:51], v[74:75], v[194:195]
	v_pk_fma_f32 v[178:179], v[48:49], v[72:73], v[192:193]
	s_nop 0
	v_cvt_pk_bf16_f32 v178, v178, v179
	v_cvt_pk_bf16_f32 v179, v176, v177
	global_store_dwordx2 v[150:151], v[178:179], off offset:256 sc1
	s_waitcnt vmcnt(7)
	v_pk_fma_f32 v[176:177], v[46:47], v[70:71], v[198:199]
	v_pk_fma_f32 v[178:179], v[44:45], v[68:69], v[196:197]
	s_nop 0
	v_cvt_pk_bf16_f32 v178, v178, v179
	v_cvt_pk_bf16_f32 v179, v176, v177
	global_store_dwordx2 v[150:151], v[178:179], off offset:288 sc1
	v_lshl_add_u64 v[150:151], s[28:29], 0, v[218:219]
	s_waitcnt vmcnt(7)
	v_pk_fma_f32 v[176:177], v[58:59], v[82:83], v[202:203]
	v_pk_fma_f32 v[178:179], v[56:57], v[80:81], v[200:201]
	v_lshl_add_u64 v[150:151], v[150:151], 0, v[174:175]
	v_cvt_pk_bf16_f32 v178, v178, v179
	v_cvt_pk_bf16_f32 v179, v176, v177
	global_store_dwordx2 v[150:151], v[178:179], off sc1
	s_waitcnt vmcnt(7)
	v_pk_fma_f32 v[176:177], v[54:55], v[78:79], v[206:207]
	v_pk_fma_f32 v[178:179], v[52:53], v[76:77], v[204:205]
	s_nop 0
	v_cvt_pk_bf16_f32 v178, v178, v179
	v_cvt_pk_bf16_f32 v179, v176, v177
	global_store_dwordx2 v[150:151], v[178:179], off offset:32 sc1
	s_waitcnt vmcnt(7)
	v_pk_fma_f32 v[176:177], v[42:43], v[74:75], v[210:211]
	v_pk_fma_f32 v[178:179], v[40:41], v[72:73], v[208:209]
	s_nop 0
	v_cvt_pk_bf16_f32 v178, v178, v179
	v_cvt_pk_bf16_f32 v179, v176, v177
	global_store_dwordx2 v[150:151], v[178:179], off offset:256 sc1
	s_waitcnt vmcnt(7)
	v_pk_fma_f32 v[176:177], v[38:39], v[70:71], v[216:217]
	v_pk_fma_f32 v[178:179], v[36:37], v[68:69], v[214:215]
	v_lshlrev_b64 v[214:215], 12, v[160:161]
	v_cvt_pk_bf16_f32 v178, v178, v179
	v_cvt_pk_bf16_f32 v179, v176, v177
	global_store_dwordx2 v[150:151], v[178:179], off offset:288 sc1
	v_lshl_add_u64 v[150:151], v[148:149], 0, v[214:215]
	global_load_dwordx4 v[176:179], v[150:151], off
	global_load_dwordx4 v[188:191], v[150:151], off offset:64
	global_load_dwordx4 v[192:195], v[150:151], off offset:512
	global_load_dwordx4 v[196:199], v[150:151], off offset:576
	v_add_u32_e32 v150, 0xb0, v158
	v_ashrrev_i32_e32 v151, 31, v150
	v_lshlrev_b64 v[216:217], 12, v[150:151]
	v_lshl_add_u64 v[148:149], v[148:149], 0, v[216:217]
	global_load_dwordx4 v[200:203], v[148:149], off
	global_load_dwordx4 v[204:207], v[148:149], off offset:64
	global_load_dwordx4 v[208:211], v[148:149], off offset:512
	s_nop 0
	global_load_dwordx4 v[148:151], v[148:149], off offset:576
	v_lshl_add_u64 v[214:215], s[28:29], 0, v[214:215]
	s_waitcnt vmcnt(7)
	v_pk_fma_f32 v[178:179], v[34:35], v[82:83], v[178:179]
	v_pk_fma_f32 v[176:177], v[32:33], v[80:81], v[176:177]
	s_waitcnt vmcnt(6)
	v_pk_fma_f32 v[188:189], v[28:29], v[76:77], v[188:189]
	v_cvt_pk_bf16_f32 v176, v176, v177
	v_cvt_pk_bf16_f32 v177, v178, v179
	v_lshl_add_u64 v[178:179], v[214:215], 0, v[174:175]
	global_store_dwordx2 v[178:179], v[176:177], off sc1
	v_pk_fma_f32 v[176:177], v[30:31], v[78:79], v[190:191]
	v_cvt_pk_bf16_f32 v188, v188, v189
	v_cvt_pk_bf16_f32 v189, v176, v177
	global_store_dwordx2 v[178:179], v[188:189], off offset:32 sc1
	s_waitcnt vmcnt(7)
	v_pk_fma_f32 v[176:177], v[26:27], v[74:75], v[194:195]
	v_pk_fma_f32 v[188:189], v[24:25], v[72:73], v[192:193]
	s_waitcnt vmcnt(2)
	v_pk_fma_f32 v[150:151], v[6:7], v[70:71], v[150:151]
	v_cvt_pk_bf16_f32 v188, v188, v189
	v_cvt_pk_bf16_f32 v189, v176, v177
	global_store_dwordx2 v[178:179], v[188:189], off offset:256 sc1
	v_pk_fma_f32 v[176:177], v[22:23], v[70:71], v[198:199]
	v_pk_fma_f32 v[188:189], v[20:21], v[68:69], v[196:197]
	v_pk_fma_f32 v[148:149], v[4:5], v[68:69], v[148:149]
	v_cvt_pk_bf16_f32 v188, v188, v189
	v_cvt_pk_bf16_f32 v189, v176, v177
	global_store_dwordx2 v[178:179], v[188:189], off offset:288 sc1
	v_lshl_add_u64 v[176:177], s[28:29], 0, v[216:217]
	v_pk_fma_f32 v[178:179], v[18:19], v[82:83], v[202:203]
	v_pk_fma_f32 v[188:189], v[16:17], v[80:81], v[200:201]
	v_lshl_add_u64 v[174:175], v[176:177], 0, v[174:175]
	v_cvt_pk_bf16_f32 v188, v188, v189
	v_cvt_pk_bf16_f32 v189, v178, v179
	v_pk_fma_f32 v[176:177], v[14:15], v[78:79], v[206:207]
	v_pk_fma_f32 v[178:179], v[12:13], v[76:77], v[204:205]
	v_cvt_pk_bf16_f32 v148, v148, v149
	v_cvt_pk_bf16_f32 v178, v178, v179
	v_cvt_pk_bf16_f32 v179, v176, v177
	global_store_dwordx2 v[174:175], v[178:179], off offset:32 sc1
	v_pk_fma_f32 v[176:177], v[10:11], v[74:75], v[210:211]
	v_pk_fma_f32 v[178:179], v[8:9], v[72:73], v[208:209]
	v_cvt_pk_bf16_f32 v149, v150, v151
	v_cvt_pk_bf16_f32 v178, v178, v179
	v_cvt_pk_bf16_f32 v179, v176, v177
	global_store_dwordx2 v[174:175], v[188:189], off sc1
	global_store_dwordx2 v[174:175], v[178:179], off offset:256 sc1
	global_store_dwordx2 v[174:175], v[148:149], off offset:288 sc1

.LBB0_266:
	s_ashr_i32 s27, s26, 31
	s_lshl_b64 s[0:1], s[26:27], 20
	s_add_u32 s26, s60, s0
	s_addc_u32 s27, s61, s1
	v_lshlrev_b64 v[148:149], 2, v[170:171]
	v_lshl_add_u64 v[150:151], s[26:27], 0, v[148:149]
	v_lshlrev_b64 v[178:179], 12, v[158:159]
	v_lshl_add_u64 v[170:171], v[150:151], 0, v[178:179]
	v_ashrrev_i32_e32 v173, 31, v172
	global_load_dwordx4 v[174:177], v[170:171], off
	global_load_dwordx4 v[188:191], v[170:171], off offset:64
	global_load_dwordx4 v[192:195], v[170:171], off offset:512
	global_load_dwordx4 v[196:199], v[170:171], off offset:576
	v_lshlrev_b64 v[214:215], 12, v[172:173]
	v_lshl_add_u64 v[208:209], v[150:151], 0, v[214:215]
	global_load_dwordx4 v[170:173], v[208:209], off
	global_load_dwordx4 v[200:203], v[208:209], off offset:64
	global_load_dwordx4 v[204:207], v[208:209], off offset:512
	s_nop 0
	global_load_dwordx4 v[208:211], v[208:209], off offset:576
	v_lshl_add_u64 v[178:179], s[26:27], 0, v[178:179]
	v_ashrrev_i32_e32 v169, 31, v168
	v_lshlrev_b64 v[168:169], 12, v[168:169]
	v_ashrrev_i32_e32 v167, 31, v166
	v_lshlrev_b64 v[166:167], 12, v[166:167]
	v_ashrrev_i32_e32 v165, 31, v164
	v_ashrrev_i32_e32 v163, 31, v162
	v_ashrrev_i32_e32 v161, 31, v160
	s_waitcnt vmcnt(0)
	v_pk_fma_f32 v[144:145], v[144:145], v[80:81], v[174:175]
	v_lshl_add_u64 v[174:175], v[178:179], 0, v[148:149]
	v_pk_fma_f32 v[130:131], v[130:131], v[74:75], v[194:195]
	v_pk_fma_f32 v[128:129], v[128:129], v[72:73], v[192:193]
	global_store_dwordx4 v[174:175], v[128:131], off offset:512 sc1
	v_pk_fma_f32 v[126:127], v[126:127], v[70:71], v[198:199]
	v_pk_fma_f32 v[124:125], v[124:125], v[68:69], v[196:197]
	v_lshl_add_u64 v[128:129], s[26:27], 0, v[214:215]
	global_store_dwordx4 v[174:175], v[124:127], off offset:576 sc1
	v_lshl_add_u64 v[128:129], v[128:129], 0, v[148:149]
	v_pk_fma_f32 v[146:147], v[146:147], v[82:83], v[176:177]
	v_pk_fma_f32 v[126:127], v[138:139], v[82:83], v[172:173]
	v_pk_fma_f32 v[124:125], v[136:137], v[80:81], v[170:171]
	v_pk_fma_f32 v[142:143], v[142:143], v[78:79], v[190:191]
	v_pk_fma_f32 v[140:141], v[140:141], v[76:77], v[188:189]
	global_store_dwordx4 v[128:129], v[124:127], off sc1
	v_pk_fma_f32 v[122:123], v[122:123], v[74:75], v[206:207]
	v_pk_fma_f32 v[120:121], v[120:121], v[72:73], v[204:205]
	v_pk_fma_f32 v[126:127], v[134:135], v[78:79], v[202:203]
	v_pk_fma_f32 v[124:125], v[132:133], v[76:77], v[200:201]
	v_pk_fma_f32 v[118:119], v[118:119], v[70:71], v[210:211]
	v_pk_fma_f32 v[116:117], v[116:117], v[68:69], v[208:209]
	global_store_dwordx4 v[174:175], v[144:147], off sc1
	global_store_dwordx4 v[174:175], v[140:143], off offset:64 sc1
	global_store_dwordx4 v[128:129], v[124:127], off offset:64 sc1
	global_store_dwordx4 v[128:129], v[120:123], off offset:512 sc1
	global_store_dwordx4 v[128:129], v[116:119], off offset:576 sc1
	v_lshl_add_u64 v[128:129], v[150:151], 0, v[168:169]
	global_load_dwordx4 v[116:119], v[128:129], off
	global_load_dwordx4 v[120:123], v[128:129], off offset:64
	global_load_dwordx4 v[124:127], v[128:129], off offset:512
	s_nop 0
	global_load_dwordx4 v[128:131], v[128:129], off offset:576
	v_lshl_add_u64 v[144:145], v[150:151], 0, v[166:167]
	global_load_dwordx4 v[132:135], v[144:145], off
	global_load_dwordx4 v[136:139], v[144:145], off offset:64
	global_load_dwordx4 v[140:143], v[144:145], off offset:512
	s_nop 0
	global_load_dwordx4 v[144:147], v[144:145], off offset:576
	v_lshl_add_u64 v[168:169], s[26:27], 0, v[168:169]
	s_waitcnt vmcnt(7)
	v_pk_fma_f32 v[112:113], v[112:113], v[80:81], v[116:117]
	v_lshl_add_u64 v[116:117], v[168:169], 0, v[148:149]
	s_waitcnt vmcnt(5)
	v_pk_fma_f32 v[98:99], v[98:99], v[74:75], v[126:127]
	v_pk_fma_f32 v[96:97], v[96:97], v[72:73], v[124:125]
	global_store_dwordx4 v[116:117], v[96:99], off offset:512 sc1
	s_waitcnt vmcnt(5)
	v_pk_fma_f32 v[94:95], v[94:95], v[70:71], v[130:131]
	v_pk_fma_f32 v[92:93], v[92:93], v[68:69], v[128:129]
	v_lshl_add_u64 v[96:97], s[26:27], 0, v[166:167]
	global_store_dwordx4 v[116:117], v[92:95], off offset:576 sc1
	v_lshl_add_u64 v[96:97], v[96:97], 0, v[148:149]
	v_pk_fma_f32 v[114:115], v[114:115], v[82:83], v[118:119]
	s_waitcnt vmcnt(5)
	v_pk_fma_f32 v[94:95], v[106:107], v[82:83], v[134:135]
	v_pk_fma_f32 v[92:93], v[104:105], v[80:81], v[132:133]
	v_pk_fma_f32 v[110:111], v[110:111], v[78:79], v[122:123]
	v_pk_fma_f32 v[108:109], v[108:109], v[76:77], v[120:121]
	global_store_dwordx4 v[96:97], v[92:95], off sc1
	s_waitcnt vmcnt(4)
	v_pk_fma_f32 v[90:91], v[90:91], v[74:75], v[142:143]
	v_pk_fma_f32 v[88:89], v[88:89], v[72:73], v[140:141]
	v_pk_fma_f32 v[94:95], v[102:103], v[78:79], v[138:139]
	v_pk_fma_f32 v[92:93], v[100:101], v[76:77], v[136:137]
	s_waitcnt vmcnt(3)
	v_pk_fma_f32 v[86:87], v[86:87], v[70:71], v[146:147]
	v_pk_fma_f32 v[84:85], v[84:85], v[68:69], v[144:145]
	global_store_dwordx4 v[116:117], v[112:115], off sc1
	global_store_dwordx4 v[116:117], v[108:111], off offset:64 sc1
	global_store_dwordx4 v[96:97], v[92:95], off offset:64 sc1
	global_store_dwordx4 v[96:97], v[88:91], off offset:512 sc1
	global_store_dwordx4 v[96:97], v[84:87], off offset:576 sc1
	v_lshlrev_b64 v[116:117], 12, v[164:165]
	v_lshl_add_u64 v[96:97], v[150:151], 0, v[116:117]
	global_load_dwordx4 v[84:87], v[96:97], off
	global_load_dwordx4 v[88:91], v[96:97], off offset:64
	global_load_dwordx4 v[92:95], v[96:97], off offset:512
	s_nop 0
	global_load_dwordx4 v[96:99], v[96:97], off offset:576
	v_lshlrev_b64 v[118:119], 12, v[162:163]
	v_lshl_add_u64 v[112:113], v[150:151], 0, v[118:119]
	global_load_dwordx4 v[100:103], v[112:113], off
	global_load_dwordx4 v[104:107], v[112:113], off offset:64
	global_load_dwordx4 v[108:111], v[112:113], off offset:512
	s_nop 0
	global_load_dwordx4 v[112:115], v[112:113], off offset:576
	v_lshl_add_u64 v[116:117], s[26:27], 0, v[116:117]
	s_waitcnt vmcnt(7)
	v_pk_fma_f32 v[64:65], v[64:65], v[80:81], v[84:85]
	v_lshl_add_u64 v[84:85], v[116:117], 0, v[148:149]
	s_waitcnt vmcnt(5)
	v_pk_fma_f32 v[50:51], v[50:51], v[74:75], v[94:95]
	v_pk_fma_f32 v[48:49], v[48:49], v[72:73], v[92:93]
	global_store_dwordx4 v[84:85], v[48:51], off offset:512 sc1
	s_waitcnt vmcnt(5)
	v_pk_fma_f32 v[46:47], v[46:47], v[70:71], v[98:99]
	v_pk_fma_f32 v[44:45], v[44:45], v[68:69], v[96:97]
	v_lshl_add_u64 v[48:49], s[26:27], 0, v[118:119]
	global_store_dwordx4 v[84:85], v[44:47], off offset:576 sc1
	v_lshl_add_u64 v[48:49], v[48:49], 0, v[148:149]
	v_pk_fma_f32 v[66:67], v[66:67], v[82:83], v[86:87]
	s_waitcnt vmcnt(5)
	v_pk_fma_f32 v[46:47], v[58:59], v[82:83], v[102:103]
	v_pk_fma_f32 v[44:45], v[56:57], v[80:81], v[100:101]
	v_pk_fma_f32 v[62:63], v[62:63], v[78:79], v[90:91]
	v_pk_fma_f32 v[60:61], v[60:61], v[76:77], v[88:89]
	global_store_dwordx4 v[48:49], v[44:47], off sc1
	s_waitcnt vmcnt(4)
	v_pk_fma_f32 v[42:43], v[42:43], v[74:75], v[110:111]
	v_pk_fma_f32 v[40:41], v[40:41], v[72:73], v[108:109]
	v_pk_fma_f32 v[46:47], v[54:55], v[78:79], v[106:107]
	v_pk_fma_f32 v[44:45], v[52:53], v[76:77], v[104:105]
	s_waitcnt vmcnt(3)
	v_pk_fma_f32 v[38:39], v[38:39], v[70:71], v[114:115]
	v_pk_fma_f32 v[36:37], v[36:37], v[68:69], v[112:113]
	global_store_dwordx4 v[84:85], v[64:67], off sc1
	global_store_dwordx4 v[84:85], v[60:63], off offset:64 sc1
	global_store_dwordx4 v[48:49], v[44:47], off offset:64 sc1
	global_store_dwordx4 v[48:49], v[40:43], off offset:512 sc1
	global_store_dwordx4 v[48:49], v[36:39], off offset:576 sc1
	v_lshlrev_b64 v[84:85], 12, v[160:161]
	v_add_u32_e32 v52, 0xb0, v158
	v_lshl_add_u64 v[48:49], v[150:151], 0, v[84:85]
	v_ashrrev_i32_e32 v53, 31, v52
	global_load_dwordx4 v[36:39], v[48:49], off
	global_load_dwordx4 v[40:43], v[48:49], off offset:64
	global_load_dwordx4 v[44:47], v[48:49], off offset:512
	s_nop 0
	global_load_dwordx4 v[48:51], v[48:49], off offset:576
	v_lshlrev_b64 v[86:87], 12, v[52:53]
	v_lshl_add_u64 v[64:65], v[150:151], 0, v[86:87]
	global_load_dwordx4 v[52:55], v[64:65], off
	global_load_dwordx4 v[56:59], v[64:65], off offset:64
	global_load_dwordx4 v[60:63], v[64:65], off offset:512
	s_nop 0
	global_load_dwordx4 v[64:67], v[64:65], off offset:576
	v_lshl_add_u64 v[84:85], s[26:27], 0, v[84:85]
	s_waitcnt vmcnt(7)
	v_pk_fma_f32 v[32:33], v[32:33], v[80:81], v[36:37]
	v_lshl_add_u64 v[36:37], v[84:85], 0, v[148:149]
	v_pk_fma_f32 v[34:35], v[34:35], v[82:83], v[38:39]
	s_waitcnt vmcnt(4)
	v_pk_fma_f32 v[22:23], v[22:23], v[70:71], v[50:51]
	v_pk_fma_f32 v[20:21], v[20:21], v[68:69], v[48:49]
	global_store_dwordx4 v[36:37], v[20:23], off offset:576 sc1
	v_pk_fma_f32 v[30:31], v[30:31], v[78:79], v[42:43]
	v_pk_fma_f32 v[28:29], v[28:29], v[76:77], v[40:41]
	v_lshl_add_u64 v[20:21], s[26:27], 0, v[86:87]
	v_pk_fma_f32 v[26:27], v[26:27], v[74:75], v[46:47]
	v_pk_fma_f32 v[24:25], v[24:25], v[72:73], v[44:45]
	s_waitcnt vmcnt(4)
	v_pk_fma_f32 v[18:19], v[18:19], v[82:83], v[54:55]
	v_pk_fma_f32 v[16:17], v[16:17], v[80:81], v[52:53]
	v_lshl_add_u64 v[20:21], v[20:21], 0, v[148:149]
	s_waitcnt vmcnt(3)
	v_pk_fma_f32 v[14:15], v[14:15], v[78:79], v[58:59]
	v_pk_fma_f32 v[12:13], v[12:13], v[76:77], v[56:57]
	s_waitcnt vmcnt(2)
	v_pk_fma_f32 v[10:11], v[10:11], v[74:75], v[62:63]
	v_pk_fma_f32 v[8:9], v[8:9], v[72:73], v[60:61]
	s_waitcnt vmcnt(1)
	v_pk_fma_f32 v[6:7], v[6:7], v[70:71], v[66:67]
	v_pk_fma_f32 v[4:5], v[4:5], v[68:69], v[64:65]
	global_store_dwordx4 v[36:37], v[32:35], off sc1
	global_store_dwordx4 v[36:37], v[28:31], off offset:64 sc1
	global_store_dwordx4 v[36:37], v[24:27], off offset:512 sc1
	global_store_dwordx4 v[20:21], v[16:19], off sc1
	global_store_dwordx4 v[20:21], v[12:15], off offset:64 sc1
	global_store_dwordx4 v[20:21], v[8:11], off offset:512 sc1
	global_store_dwordx4 v[20:21], v[4:7], off offset:576 sc1
	s_andn2_b64 vcc, exec, s[6:7]
	s_mov_b64 s[4:5], -1
	s_cbranch_vccnz .LBB0_251

.LBB0_303:
	v_mov_b32_e32 v148, v185
	v_mov_b32_e32 v100, v187
	s_cmp_eq_u32 s0, 0
	s_cbranch_scc1 .LBB0_305
	s_add_i32 s48, s0, -1
	s_ashr_i32 s29, s28, 31
	s_lshl_b64 s[0:1], s[48:49], 23
	s_add_u32 s2, s76, s0
	s_addc_u32 s4, s82, s1
	s_lshl_b64 s[0:1], s[28:29], 20
	s_add_u32 s2, s2, s0
	s_addc_u32 s4, s4, s1
	s_lshl_b32 s0, s30, 8
	s_ashr_i32 s1, s0, 31
	s_lshl_b64 s[0:1], s[0:1], 2
	s_add_u32 s0, s2, s0
	s_addc_u32 s1, s4, s1
	v_mov_b32_e32 v101, v148
	s_add_u32 s0, s0, s97
	v_lshlrev_b32_e32 v102, 2, v100
	s_addc_u32 s1, s1, 0
	v_add_u32_e32 v104, s83, v101
	v_ashrrev_i32_e32 v103, 31, v102
	v_ashrrev_i32_e32 v105, 31, v104
	v_lshl_add_u64 v[102:103], v[102:103], 2, s[0:1]
	v_lshlrev_b64 v[104:105], 12, v[104:105]
	v_lshl_add_u64 v[104:105], v[102:103], 0, v[104:105]
	global_store_dwordx4 v[104:105], v[144:147], off sc1
	global_store_dwordx4 v[104:105], v[140:143], off offset:64 sc1
	global_store_dwordx4 v[104:105], v[124:127], off offset:512 sc1
	global_store_dwordx4 v[104:105], v[120:123], off offset:576 sc1
	v_mov_b32_e32 v101, v148
	s_nop 0
	v_add_u32_e32 v104, s87, v101
	v_ashrrev_i32_e32 v105, 31, v104
	v_lshlrev_b64 v[104:105], 12, v[104:105]
	v_lshl_add_u64 v[104:105], v[102:103], 0, v[104:105]
	global_store_dwordx4 v[104:105], v[136:139], off sc1
	global_store_dwordx4 v[104:105], v[132:135], off offset:64 sc1
	global_store_dwordx4 v[104:105], v[116:119], off offset:512 sc1
	global_store_dwordx4 v[104:105], v[112:115], off offset:576 sc1
	v_mov_b32_e32 v101, v148
	s_nop 0
	v_add_u32_e32 v104, s88, v101
	v_ashrrev_i32_e32 v105, 31, v104
	v_lshlrev_b64 v[104:105], 12, v[104:105]
	v_lshl_add_u64 v[104:105], v[102:103], 0, v[104:105]
	global_store_dwordx4 v[104:105], v[96:99], off sc1
	global_store_dwordx4 v[104:105], v[92:95], off offset:64 sc1
	global_store_dwordx4 v[104:105], v[80:83], off offset:512 sc1
	global_store_dwordx4 v[104:105], v[76:79], off offset:576 sc1
	v_mov_b32_e32 v101, v148
	s_nop 0
	v_add_u32_e32 v104, s89, v101
	v_ashrrev_i32_e32 v105, 31, v104
	v_lshlrev_b64 v[104:105], 12, v[104:105]
	v_lshl_add_u64 v[104:105], v[102:103], 0, v[104:105]
	global_store_dwordx4 v[104:105], v[88:91], off sc1
	global_store_dwordx4 v[104:105], v[84:87], off offset:64 sc1
	global_store_dwordx4 v[104:105], v[72:75], off offset:512 sc1
	global_store_dwordx4 v[104:105], v[68:71], off offset:576 sc1
	v_mov_b32_e32 v101, v148
	s_nop 0
	v_add_u32_e32 v104, s90, v101
	v_ashrrev_i32_e32 v105, 31, v104
	v_lshlrev_b64 v[104:105], 12, v[104:105]
	v_lshl_add_u64 v[104:105], v[102:103], 0, v[104:105]
	global_store_dwordx4 v[104:105], v[64:67], off sc1
	global_store_dwordx4 v[104:105], v[60:63], off offset:64 sc1
	global_store_dwordx4 v[104:105], v[48:51], off offset:512 sc1
	global_store_dwordx4 v[104:105], v[44:47], off offset:576 sc1
	v_mov_b32_e32 v101, v148
	s_nop 0
	v_add_u32_e32 v104, s91, v101
	v_ashrrev_i32_e32 v105, 31, v104
	v_lshlrev_b64 v[104:105], 12, v[104:105]
	v_lshl_add_u64 v[104:105], v[102:103], 0, v[104:105]
	global_store_dwordx4 v[104:105], v[56:59], off sc1
	global_store_dwordx4 v[104:105], v[52:55], off offset:64 sc1
	global_store_dwordx4 v[104:105], v[40:43], off offset:512 sc1
	global_store_dwordx4 v[104:105], v[36:39], off offset:576 sc1
	v_mov_b32_e32 v101, v148
	s_nop 0
	v_add_u32_e32 v104, s92, v101
	v_ashrrev_i32_e32 v105, 31, v104
	v_lshlrev_b64 v[104:105], 12, v[104:105]
	v_lshl_add_u64 v[104:105], v[102:103], 0, v[104:105]
	global_store_dwordx4 v[104:105], v[32:35], off sc1
	global_store_dwordx4 v[104:105], v[28:31], off offset:64 sc1
	global_store_dwordx4 v[104:105], v[20:23], off offset:512 sc1
	global_store_dwordx4 v[104:105], v[16:19], off offset:576 sc1
	v_mov_b32_e32 v101, v148
	s_nop 0
	v_add_u32_e32 v104, s93, v101
	v_ashrrev_i32_e32 v105, 31, v104
	v_lshlrev_b64 v[104:105], 12, v[104:105]
	v_lshl_add_u64 v[102:103], v[102:103], 0, v[104:105]
	global_store_dwordx4 v[102:103], v[24:27], off sc1
	global_store_dwordx4 v[102:103], v[12:15], off offset:64 sc1
	global_store_dwordx4 v[102:103], v[8:11], off offset:512 sc1
	global_store_dwordx4 v[102:103], v[4:7], off offset:576 sc1
	s_cbranch_execz .LBB0_306
	s_branch .LBB0_310
.LBB0_305:
.LBB0_306:
	s_lshl_b32 s0, s30, 8
	s_add_i32 s48, s28, -8
	s_or_b32 s0, s0, s84
	s_lshr_b32 s2, s48, 4
	s_cmp_gt_i32 s28, 7
	v_lshl_add_u32 v210, v100, 2, s0
	s_cselect_b64 s[0:1], -1, 0
	s_and_b64 vcc, s[0:1], exec
	s_cselect_b32 s0, s2, 8
	s_mul_hi_u32 s1, s0, 0x6000
	s_mulk_i32 s0, 0x6000
	s_add_u32 s0, s61, s0
	s_addc_u32 s1, s65, s1
	v_ashrrev_i32_e32 v211, 31, v210
	v_lshl_add_u64 v[100:101], v[210:211], 2, s[0:1]
	global_load_dwordx4 v[128:131], v[100:101], off
	global_load_dwordx4 v[108:111], v[100:101], off offset:64
	global_load_dwordx4 v[104:107], v[100:101], off offset:512
	s_nop 0
	global_load_dwordx4 v[100:103], v[100:101], off offset:576
	v_add_u32_e32 v148, s83, v148
	v_add_u32_e32 v150, 16, v148
	v_ashrrev_i32_e32 v149, 31, v148
	v_ashrrev_i32_e32 v151, 31, v150
	v_add_u32_e32 v208, 32, v148
	v_add_u32_e32 v202, 48, v148
	v_add_u32_e32 v200, 0x80, v148
	v_add_u32_e32 v198, 0x90, v148
	v_lshlrev_b64 v[204:205], 12, v[148:149]
	v_lshlrev_b64 v[206:207], 12, v[150:151]
	s_mov_b64 s[4:5], -1
	v_ashrrev_i32_e32 v209, 31, v208
	v_ashrrev_i32_e32 v203, 31, v202
	v_ashrrev_i32_e32 v201, 31, v200
	v_ashrrev_i32_e32 v199, 31, v198
	v_add_u32_e32 v196, 0xa0, v148
	v_add_u32_e32 v194, 0xb0, v148
	s_cbranch_vccz .LBB0_308
	s_lshl_b64 s[30:31], s[48:49], 20
	s_add_u32 s0, s6, s30
	s_addc_u32 s1, s7, s31
	v_lshl_add_u64 v[214:215], v[210:211], 2, s[0:1]
	v_lshl_add_u64 v[148:149], v[214:215], 0, v[204:205]
	global_load_dwordx4 v[176:179], v[148:149], off
	global_load_dwordx4 v[172:175], v[148:149], off offset:64
	global_load_dwordx4 v[168:171], v[148:149], off offset:512
	global_load_dwordx4 v[160:163], v[148:149], off offset:576
	v_lshl_add_u64 v[148:149], v[214:215], 0, v[206:207]
	global_load_dwordx4 v[164:167], v[148:149], off
	global_load_dwordx4 v[156:159], v[148:149], off offset:64
	global_load_dwordx4 v[152:155], v[148:149], off offset:512
	s_nop 0
	global_load_dwordx4 v[148:151], v[148:149], off offset:576
	s_add_u32 s30, s10, s30
	s_addc_u32 s31, s11, s31
	v_lshlrev_b64 v[212:213], 1, v[210:211]
	v_lshl_add_u64 v[222:223], s[30:31], 0, v[204:205]
	v_lshl_add_u64 v[224:225], s[30:31], 0, v[206:207]
	v_lshl_add_u64 v[222:223], v[222:223], 0, v[212:213]
	v_lshlrev_b64 v[216:217], 12, v[208:209]
	v_lshl_add_u64 v[224:225], v[224:225], 0, v[212:213]
	v_lshl_add_u64 v[218:219], v[214:215], 0, v[216:217]
	v_lshl_add_u64 v[216:217], s[30:31], 0, v[216:217]
	v_lshl_add_u64 v[216:217], v[216:217], 0, v[212:213]
	v_ashrrev_i32_e32 v197, 31, v196
	v_ashrrev_i32_e32 v195, 31, v194
	s_mov_b64 s[4:5], 0
	s_waitcnt vmcnt(0)
	v_pk_fma_f32 v[178:179], v[146:147], v[130:131], v[178:179]
	v_pk_fma_f32 v[176:177], v[144:145], v[128:129], v[176:177]
	v_pk_fma_f32 v[174:175], v[142:143], v[110:111], v[174:175]
	v_pk_fma_f32 v[172:173], v[140:141], v[108:109], v[172:173]
	v_pk_fma_f32 v[170:171], v[126:127], v[106:107], v[170:171]
	v_pk_fma_f32 v[168:169], v[124:125], v[104:105], v[168:169]
	v_pk_fma_f32 v[162:163], v[122:123], v[102:103], v[162:163]
	v_pk_fma_f32 v[160:161], v[120:121], v[100:101], v[160:161]
	v_pk_fma_f32 v[166:167], v[138:139], v[130:131], v[166:167]
	v_pk_fma_f32 v[164:165], v[136:137], v[128:129], v[164:165]
	v_pk_fma_f32 v[158:159], v[134:135], v[110:111], v[158:159]
	v_pk_fma_f32 v[156:157], v[132:133], v[108:109], v[156:157]
	v_pk_fma_f32 v[154:155], v[118:119], v[106:107], v[154:155]
	v_pk_fma_f32 v[152:153], v[116:117], v[104:105], v[152:153]
	v_pk_fma_f32 v[150:151], v[114:115], v[102:103], v[150:151]
	v_pk_fma_f32 v[148:149], v[112:113], v[100:101], v[148:149]
	v_cvt_pk_bf16_f32 v176, v176, v177
	v_cvt_pk_bf16_f32 v177, v178, v179
	v_cvt_pk_bf16_f32 v172, v172, v173
	v_cvt_pk_bf16_f32 v173, v174, v175
	v_cvt_pk_bf16_f32 v168, v168, v169
	v_cvt_pk_bf16_f32 v169, v170, v171
	v_cvt_pk_bf16_f32 v160, v160, v161
	v_cvt_pk_bf16_f32 v161, v162, v163
	v_cvt_pk_bf16_f32 v162, v164, v165
	v_cvt_pk_bf16_f32 v163, v166, v167
	v_cvt_pk_bf16_f32 v156, v156, v157
	v_cvt_pk_bf16_f32 v157, v158, v159
	v_cvt_pk_bf16_f32 v152, v152, v153
	v_cvt_pk_bf16_f32 v153, v154, v155
	v_cvt_pk_bf16_f32 v148, v148, v149
	v_cvt_pk_bf16_f32 v149, v150, v151
	global_store_dwordx2 v[222:223], v[176:177], off sc1
	global_store_dwordx2 v[222:223], v[172:173], off offset:32 sc1
	global_store_dwordx2 v[222:223], v[168:169], off offset:256 sc1
	global_store_dwordx2 v[222:223], v[160:161], off offset:288 sc1
	global_store_dwordx2 v[224:225], v[162:163], off sc1
	global_store_dwordx2 v[224:225], v[156:157], off offset:32 sc1
	global_store_dwordx2 v[224:225], v[152:153], off offset:256 sc1
	global_store_dwordx2 v[224:225], v[148:149], off offset:288 sc1
	v_lshlrev_b64 v[222:223], 12, v[202:203]
	v_lshl_add_u64 v[164:165], v[214:215], 0, v[222:223]
	global_load_dwordx4 v[156:159], v[218:219], off
	global_load_dwordx4 v[152:155], v[218:219], off offset:64
	global_load_dwordx4 v[148:151], v[218:219], off offset:512
	global_load_dwordx4 v[160:163], v[218:219], off offset:576
	global_load_dwordx4 v[176:179], v[164:165], off
	global_load_dwordx4 v[172:175], v[164:165], off offset:64
	global_load_dwordx4 v[168:171], v[164:165], off offset:512
	s_nop 0
	global_load_dwordx4 v[164:167], v[164:165], off offset:576
	v_lshl_add_u64 v[222:223], s[30:31], 0, v[222:223]
	v_lshlrev_b64 v[218:219], 12, v[200:201]
	v_lshl_add_u64 v[222:223], v[222:223], 0, v[212:213]
	v_lshl_add_u64 v[224:225], v[214:215], 0, v[218:219]
	v_lshl_add_u64 v[218:219], s[30:31], 0, v[218:219]
	v_lshl_add_u64 v[218:219], v[218:219], 0, v[212:213]
	s_waitcnt vmcnt(7)
	v_pk_fma_f32 v[158:159], v[98:99], v[130:131], v[158:159]
	v_pk_fma_f32 v[156:157], v[96:97], v[128:129], v[156:157]
	s_waitcnt vmcnt(6)
	v_pk_fma_f32 v[154:155], v[94:95], v[110:111], v[154:155]
	v_pk_fma_f32 v[152:153], v[92:93], v[108:109], v[152:153]
	s_waitcnt vmcnt(5)
	v_pk_fma_f32 v[150:151], v[82:83], v[106:107], v[150:151]
	v_pk_fma_f32 v[148:149], v[80:81], v[104:105], v[148:149]
	s_waitcnt vmcnt(4)
	v_pk_fma_f32 v[162:163], v[78:79], v[102:103], v[162:163]
	v_pk_fma_f32 v[160:161], v[76:77], v[100:101], v[160:161]
	s_waitcnt vmcnt(3)
	v_pk_fma_f32 v[178:179], v[90:91], v[130:131], v[178:179]
	v_pk_fma_f32 v[176:177], v[88:89], v[128:129], v[176:177]
	s_waitcnt vmcnt(2)
	v_pk_fma_f32 v[174:175], v[86:87], v[110:111], v[174:175]
	v_pk_fma_f32 v[172:173], v[84:85], v[108:109], v[172:173]
	s_waitcnt vmcnt(1)
	v_pk_fma_f32 v[170:171], v[74:75], v[106:107], v[170:171]
	v_pk_fma_f32 v[168:169], v[72:73], v[104:105], v[168:169]
	s_waitcnt vmcnt(0)
	v_pk_fma_f32 v[166:167], v[70:71], v[102:103], v[166:167]
	v_pk_fma_f32 v[164:165], v[68:69], v[100:101], v[164:165]
	v_cvt_pk_bf16_f32 v156, v156, v157
	v_cvt_pk_bf16_f32 v157, v158, v159
	v_cvt_pk_bf16_f32 v152, v152, v153
	v_cvt_pk_bf16_f32 v153, v154, v155
	v_cvt_pk_bf16_f32 v148, v148, v149
	v_cvt_pk_bf16_f32 v149, v150, v151
	v_cvt_pk_bf16_f32 v150, v160, v161
	v_cvt_pk_bf16_f32 v151, v162, v163
	v_cvt_pk_bf16_f32 v154, v176, v177
	v_cvt_pk_bf16_f32 v155, v178, v179
	v_cvt_pk_bf16_f32 v158, v172, v173
	v_cvt_pk_bf16_f32 v159, v174, v175
	v_cvt_pk_bf16_f32 v160, v168, v169
	v_cvt_pk_bf16_f32 v161, v170, v171
	v_cvt_pk_bf16_f32 v162, v164, v165
	v_cvt_pk_bf16_f32 v163, v166, v167
	global_store_dwordx2 v[216:217], v[156:157], off sc1
	global_store_dwordx2 v[216:217], v[152:153], off offset:32 sc1
	global_store_dwordx2 v[216:217], v[148:149], off offset:256 sc1
	global_store_dwordx2 v[216:217], v[150:151], off offset:288 sc1
	global_store_dwordx2 v[222:223], v[154:155], off sc1
	global_store_dwordx2 v[222:223], v[158:159], off offset:32 sc1
	global_store_dwordx2 v[222:223], v[160:161], off offset:256 sc1
	global_store_dwordx2 v[222:223], v[162:163], off offset:288 sc1
	v_lshlrev_b64 v[216:217], 12, v[198:199]
	v_lshl_add_u64 v[164:165], v[214:215], 0, v[216:217]
	global_load_dwordx4 v[156:159], v[224:225], off
	global_load_dwordx4 v[152:155], v[224:225], off offset:64
	global_load_dwordx4 v[148:151], v[224:225], off offset:512
	global_load_dwordx4 v[160:163], v[224:225], off offset:576
	global_load_dwordx4 v[176:179], v[164:165], off
	global_load_dwordx4 v[172:175], v[164:165], off offset:64
	global_load_dwordx4 v[168:171], v[164:165], off offset:512
	s_nop 0
	global_load_dwordx4 v[164:167], v[164:165], off offset:576
	v_lshl_add_u64 v[216:217], s[30:31], 0, v[216:217]
	v_lshl_add_u64 v[216:217], v[216:217], 0, v[212:213]
	v_lshlrev_b64 v[222:223], 12, v[196:197]
	v_lshl_add_u64 v[224:225], v[214:215], 0, v[222:223]
	s_waitcnt vmcnt(7)
	v_pk_fma_f32 v[158:159], v[66:67], v[130:131], v[158:159]
	v_pk_fma_f32 v[156:157], v[64:65], v[128:129], v[156:157]
	s_waitcnt vmcnt(6)
	v_pk_fma_f32 v[154:155], v[62:63], v[110:111], v[154:155]
	v_pk_fma_f32 v[152:153], v[60:61], v[108:109], v[152:153]
	s_waitcnt vmcnt(5)
	v_pk_fma_f32 v[150:151], v[50:51], v[106:107], v[150:151]
	v_pk_fma_f32 v[148:149], v[48:49], v[104:105], v[148:149]
	s_waitcnt vmcnt(4)
	v_pk_fma_f32 v[162:163], v[46:47], v[102:103], v[162:163]
	v_pk_fma_f32 v[160:161], v[44:45], v[100:101], v[160:161]
	s_waitcnt vmcnt(3)
	v_pk_fma_f32 v[178:179], v[58:59], v[130:131], v[178:179]
	v_pk_fma_f32 v[176:177], v[56:57], v[128:129], v[176:177]
	s_waitcnt vmcnt(2)
	v_pk_fma_f32 v[174:175], v[54:55], v[110:111], v[174:175]
	v_pk_fma_f32 v[172:173], v[52:53], v[108:109], v[172:173]
	s_waitcnt vmcnt(1)
	v_pk_fma_f32 v[170:171], v[42:43], v[106:107], v[170:171]
	v_pk_fma_f32 v[168:169], v[40:41], v[104:105], v[168:169]
	s_waitcnt vmcnt(0)
	v_pk_fma_f32 v[166:167], v[38:39], v[102:103], v[166:167]
	v_pk_fma_f32 v[164:165], v[36:37], v[100:101], v[164:165]
	v_cvt_pk_bf16_f32 v156, v156, v157
	v_cvt_pk_bf16_f32 v157, v158, v159
	v_cvt_pk_bf16_f32 v152, v152, v153
	v_cvt_pk_bf16_f32 v153, v154, v155
	v_cvt_pk_bf16_f32 v148, v148, v149
	v_cvt_pk_bf16_f32 v149, v150, v151
	v_cvt_pk_bf16_f32 v150, v160, v161
	v_cvt_pk_bf16_f32 v151, v162, v163
	v_cvt_pk_bf16_f32 v154, v176, v177
	v_cvt_pk_bf16_f32 v155, v178, v179
	v_cvt_pk_bf16_f32 v158, v172, v173
	v_cvt_pk_bf16_f32 v159, v174, v175
	v_cvt_pk_bf16_f32 v160, v168, v169
	v_cvt_pk_bf16_f32 v161, v170, v171
	v_cvt_pk_bf16_f32 v162, v164, v165
	v_cvt_pk_bf16_f32 v163, v166, v167
	global_store_dwordx2 v[218:219], v[156:157], off sc1
	global_store_dwordx2 v[218:219], v[152:153], off offset:32 sc1
	global_store_dwordx2 v[218:219], v[148:149], off offset:256 sc1
	global_store_dwordx2 v[218:219], v[150:151], off offset:288 sc1
	global_store_dwordx2 v[216:217], v[154:155], off sc1
	global_store_dwordx2 v[216:217], v[158:159], off offset:32 sc1
	global_store_dwordx2 v[216:217], v[160:161], off offset:256 sc1
	global_store_dwordx2 v[216:217], v[162:163], off offset:288 sc1
	v_lshlrev_b64 v[216:217], 12, v[194:195]
	v_lshl_add_u64 v[176:177], v[214:215], 0, v[216:217]
	global_load_dwordx4 v[148:151], v[224:225], off
	global_load_dwordx4 v[152:155], v[224:225], off offset:64
	global_load_dwordx4 v[156:159], v[224:225], off offset:512
	global_load_dwordx4 v[160:163], v[224:225], off offset:576
	global_load_dwordx4 v[164:167], v[176:177], off
	global_load_dwordx4 v[168:171], v[176:177], off offset:64
	global_load_dwordx4 v[172:175], v[176:177], off offset:512
	s_nop 0
	global_load_dwordx4 v[176:179], v[176:177], off offset:576
	v_lshl_add_u64 v[214:215], s[30:31], 0, v[222:223]
	v_lshl_add_u64 v[216:217], s[30:31], 0, v[216:217]
	v_lshl_add_u64 v[214:215], v[214:215], 0, v[212:213]
	v_lshl_add_u64 v[212:213], v[216:217], 0, v[212:213]
	s_waitcnt vmcnt(7)
	v_pk_fma_f32 v[150:151], v[34:35], v[130:131], v[150:151]
	v_pk_fma_f32 v[148:149], v[32:33], v[128:129], v[148:149]
	s_waitcnt vmcnt(6)
	v_pk_fma_f32 v[154:155], v[30:31], v[110:111], v[154:155]
	v_pk_fma_f32 v[152:153], v[28:29], v[108:109], v[152:153]
	s_waitcnt vmcnt(5)
	v_pk_fma_f32 v[158:159], v[22:23], v[106:107], v[158:159]
	v_pk_fma_f32 v[156:157], v[20:21], v[104:105], v[156:157]
	s_waitcnt vmcnt(4)
	v_pk_fma_f32 v[162:163], v[18:19], v[102:103], v[162:163]
	v_pk_fma_f32 v[160:161], v[16:17], v[100:101], v[160:161]
	s_waitcnt vmcnt(3)
	v_pk_fma_f32 v[166:167], v[26:27], v[130:131], v[166:167]
	v_pk_fma_f32 v[164:165], v[24:25], v[128:129], v[164:165]
	s_waitcnt vmcnt(2)
	v_pk_fma_f32 v[170:171], v[14:15], v[110:111], v[170:171]
	v_pk_fma_f32 v[168:169], v[12:13], v[108:109], v[168:169]
	s_waitcnt vmcnt(1)
	v_pk_fma_f32 v[174:175], v[10:11], v[106:107], v[174:175]
	v_pk_fma_f32 v[172:173], v[8:9], v[104:105], v[172:173]
	s_waitcnt vmcnt(0)
	v_pk_fma_f32 v[178:179], v[6:7], v[102:103], v[178:179]
	v_pk_fma_f32 v[176:177], v[4:5], v[100:101], v[176:177]
	v_cvt_pk_bf16_f32 v148, v148, v149
	v_cvt_pk_bf16_f32 v149, v150, v151
	v_cvt_pk_bf16_f32 v150, v152, v153
	v_cvt_pk_bf16_f32 v151, v154, v155
	v_cvt_pk_bf16_f32 v152, v156, v157
	v_cvt_pk_bf16_f32 v153, v158, v159
	v_cvt_pk_bf16_f32 v154, v160, v161
	v_cvt_pk_bf16_f32 v155, v162, v163
	v_cvt_pk_bf16_f32 v156, v164, v165
	v_cvt_pk_bf16_f32 v157, v166, v167
	v_cvt_pk_bf16_f32 v158, v168, v169
	v_cvt_pk_bf16_f32 v159, v170, v171
	v_cvt_pk_bf16_f32 v160, v172, v173
	v_cvt_pk_bf16_f32 v161, v174, v175
	v_cvt_pk_bf16_f32 v162, v176, v177
	v_cvt_pk_bf16_f32 v163, v178, v179
	global_store_dwordx2 v[214:215], v[148:149], off sc1
	global_store_dwordx2 v[214:215], v[150:151], off offset:32 sc1
	global_store_dwordx2 v[214:215], v[152:153], off offset:256 sc1
	global_store_dwordx2 v[214:215], v[154:155], off offset:288 sc1
	global_store_dwordx2 v[212:213], v[156:157], off sc1
	global_store_dwordx2 v[212:213], v[158:159], off offset:32 sc1
	global_store_dwordx2 v[212:213], v[160:161], off offset:256 sc1
	global_store_dwordx2 v[212:213], v[162:163], off offset:288 sc1
.LBB0_308:
	s_andn2_b64 vcc, exec, s[4:5]
	s_cbranch_vccnz .LBB0_310
	s_ashr_i32 s29, s28, 31
	s_lshl_b64 s[28:29], s[28:29], 20
	s_add_u32 s0, s8, s28
	s_addc_u32 s1, s9, s29
	v_lshlrev_b64 v[148:149], 2, v[210:211]
	v_lshl_add_u64 v[150:151], s[0:1], 0, v[148:149]
	v_lshl_add_u64 v[152:153], v[150:151], 0, v[204:205]
	global_load_dwordx4 v[154:157], v[152:153], off
	global_load_dwordx4 v[158:161], v[152:153], off offset:64
	global_load_dwordx4 v[162:165], v[152:153], off offset:512
	global_load_dwordx4 v[166:169], v[152:153], off offset:576
	v_lshl_add_u64 v[152:153], v[150:151], 0, v[206:207]
	global_load_dwordx4 v[170:173], v[152:153], off
	global_load_dwordx4 v[174:177], v[152:153], off offset:64
	global_load_dwordx4 v[210:213], v[152:153], off offset:512
	global_load_dwordx4 v[214:217], v[152:153], off offset:576
	s_add_u32 s28, s59, s28
	s_addc_u32 s29, s60, s29
	v_lshl_add_u64 v[204:205], s[28:29], 0, v[204:205]
	v_lshl_add_u64 v[206:207], s[28:29], 0, v[206:207]
	v_lshl_add_u64 v[204:205], v[204:205], 0, v[148:149]
	v_lshlrev_b64 v[152:153], 12, v[208:209]
	v_lshl_add_u64 v[206:207], v[206:207], 0, v[148:149]
	v_lshl_add_u64 v[178:179], v[150:151], 0, v[152:153]
	v_lshl_add_u64 v[152:153], s[28:29], 0, v[152:153]
	v_lshl_add_u64 v[152:153], v[152:153], 0, v[148:149]
	v_ashrrev_i32_e32 v197, 31, v196
	v_ashrrev_i32_e32 v195, 31, v194
	s_waitcnt vmcnt(0)
	v_pk_fma_f32 v[146:147], v[146:147], v[130:131], v[156:157]
	v_pk_fma_f32 v[144:145], v[144:145], v[128:129], v[154:155]
	v_pk_fma_f32 v[126:127], v[126:127], v[106:107], v[164:165]
	v_pk_fma_f32 v[142:143], v[142:143], v[110:111], v[160:161]
	v_pk_fma_f32 v[140:141], v[140:141], v[108:109], v[158:159]
	v_pk_fma_f32 v[124:125], v[124:125], v[104:105], v[162:163]
	v_pk_fma_f32 v[122:123], v[122:123], v[102:103], v[168:169]
	v_pk_fma_f32 v[120:121], v[120:121], v[100:101], v[166:167]
	v_pk_fma_f32 v[138:139], v[138:139], v[130:131], v[172:173]
	v_pk_fma_f32 v[136:137], v[136:137], v[128:129], v[170:171]
	v_pk_fma_f32 v[134:135], v[134:135], v[110:111], v[176:177]
	v_pk_fma_f32 v[132:133], v[132:133], v[108:109], v[174:175]
	v_pk_fma_f32 v[118:119], v[118:119], v[106:107], v[212:213]
	v_pk_fma_f32 v[116:117], v[116:117], v[104:105], v[210:211]
	v_pk_fma_f32 v[114:115], v[114:115], v[102:103], v[216:217]
	v_pk_fma_f32 v[112:113], v[112:113], v[100:101], v[214:215]
	global_store_dwordx4 v[204:205], v[144:147], off sc1
	global_store_dwordx4 v[204:205], v[140:143], off offset:64 sc1
	global_store_dwordx4 v[204:205], v[124:127], off offset:512 sc1
	global_store_dwordx4 v[204:205], v[120:123], off offset:576 sc1
	global_store_dwordx4 v[206:207], v[136:139], off sc1
	global_store_dwordx4 v[206:207], v[132:135], off offset:64 sc1
	global_store_dwordx4 v[206:207], v[116:119], off offset:512 sc1
	global_store_dwordx4 v[206:207], v[112:115], off offset:576 sc1
	v_lshlrev_b64 v[126:127], 12, v[202:203]
	global_load_dwordx4 v[114:117], v[178:179], off
	global_load_dwordx4 v[118:121], v[178:179], off offset:64
	global_load_dwordx4 v[122:125], v[178:179], off offset:512
	v_lshl_add_u64 v[112:113], v[150:151], 0, v[126:127]
	global_load_dwordx4 v[132:135], v[178:179], off offset:576
	global_load_dwordx4 v[136:139], v[112:113], off
	global_load_dwordx4 v[140:143], v[112:113], off offset:64
	global_load_dwordx4 v[144:147], v[112:113], off offset:512
	global_load_dwordx4 v[154:157], v[112:113], off offset:576
	v_lshl_add_u64 v[126:127], s[28:29], 0, v[126:127]
	v_lshlrev_b64 v[112:113], 12, v[200:201]
	v_lshl_add_u64 v[126:127], v[126:127], 0, v[148:149]
	v_lshl_add_u64 v[158:159], v[150:151], 0, v[112:113]
	v_lshl_add_u64 v[112:113], s[28:29], 0, v[112:113]
	v_lshl_add_u64 v[112:113], v[112:113], 0, v[148:149]
	s_waitcnt vmcnt(7)
	v_pk_fma_f32 v[98:99], v[98:99], v[130:131], v[116:117]
	v_pk_fma_f32 v[96:97], v[96:97], v[128:129], v[114:115]
	s_waitcnt vmcnt(6)
	v_pk_fma_f32 v[94:95], v[94:95], v[110:111], v[120:121]
	v_pk_fma_f32 v[92:93], v[92:93], v[108:109], v[118:119]
	s_waitcnt vmcnt(5)
	v_pk_fma_f32 v[82:83], v[82:83], v[106:107], v[124:125]
	v_pk_fma_f32 v[80:81], v[80:81], v[104:105], v[122:123]
	s_waitcnt vmcnt(4)
	v_pk_fma_f32 v[78:79], v[78:79], v[102:103], v[134:135]
	v_pk_fma_f32 v[76:77], v[76:77], v[100:101], v[132:133]
	s_waitcnt vmcnt(3)
	v_pk_fma_f32 v[90:91], v[90:91], v[130:131], v[138:139]
	v_pk_fma_f32 v[88:89], v[88:89], v[128:129], v[136:137]
	s_waitcnt vmcnt(2)
	v_pk_fma_f32 v[86:87], v[86:87], v[110:111], v[142:143]
	v_pk_fma_f32 v[84:85], v[84:85], v[108:109], v[140:141]
	s_waitcnt vmcnt(1)
	v_pk_fma_f32 v[74:75], v[74:75], v[106:107], v[146:147]
	v_pk_fma_f32 v[72:73], v[72:73], v[104:105], v[144:145]
	s_waitcnt vmcnt(0)
	v_pk_fma_f32 v[70:71], v[70:71], v[102:103], v[156:157]
	v_pk_fma_f32 v[68:69], v[68:69], v[100:101], v[154:155]
	global_store_dwordx4 v[152:153], v[96:99], off sc1
	global_store_dwordx4 v[152:153], v[92:95], off offset:64 sc1
	global_store_dwordx4 v[152:153], v[80:83], off offset:512 sc1
	global_store_dwordx4 v[152:153], v[76:79], off offset:576 sc1
	global_store_dwordx4 v[126:127], v[88:91], off sc1
	global_store_dwordx4 v[126:127], v[84:87], off offset:64 sc1
	global_store_dwordx4 v[126:127], v[72:75], off offset:512 sc1
	global_store_dwordx4 v[126:127], v[68:71], off offset:576 sc1
	v_lshlrev_b64 v[114:115], 12, v[198:199]
	v_lshl_add_u64 v[96:97], v[150:151], 0, v[114:115]
	global_load_dwordx4 v[68:71], v[158:159], off
	global_load_dwordx4 v[72:75], v[158:159], off offset:64
	global_load_dwordx4 v[76:79], v[158:159], off offset:512
	global_load_dwordx4 v[80:83], v[158:159], off offset:576
	global_load_dwordx4 v[84:87], v[96:97], off
	global_load_dwordx4 v[88:91], v[96:97], off offset:64
	global_load_dwordx4 v[92:95], v[96:97], off offset:512
	s_nop 0
	global_load_dwordx4 v[96:99], v[96:97], off offset:576
	v_lshl_add_u64 v[114:115], s[28:29], 0, v[114:115]
	v_lshlrev_b64 v[116:117], 12, v[196:197]
	v_lshl_add_u64 v[114:115], v[114:115], 0, v[148:149]
	v_lshl_add_u64 v[118:119], v[150:151], 0, v[116:117]
	s_waitcnt vmcnt(7)
	v_pk_fma_f32 v[66:67], v[66:67], v[130:131], v[70:71]
	v_pk_fma_f32 v[64:65], v[64:65], v[128:129], v[68:69]
	s_waitcnt vmcnt(6)
	v_pk_fma_f32 v[62:63], v[62:63], v[110:111], v[74:75]
	v_pk_fma_f32 v[60:61], v[60:61], v[108:109], v[72:73]
	s_waitcnt vmcnt(5)
	v_pk_fma_f32 v[50:51], v[50:51], v[106:107], v[78:79]
	v_pk_fma_f32 v[48:49], v[48:49], v[104:105], v[76:77]
	s_waitcnt vmcnt(4)
	v_pk_fma_f32 v[46:47], v[46:47], v[102:103], v[82:83]
	v_pk_fma_f32 v[44:45], v[44:45], v[100:101], v[80:81]
	s_waitcnt vmcnt(3)
	v_pk_fma_f32 v[58:59], v[58:59], v[130:131], v[86:87]
	v_pk_fma_f32 v[56:57], v[56:57], v[128:129], v[84:85]
	s_waitcnt vmcnt(2)
	v_pk_fma_f32 v[54:55], v[54:55], v[110:111], v[90:91]
	v_pk_fma_f32 v[52:53], v[52:53], v[108:109], v[88:89]
	s_waitcnt vmcnt(1)
	v_pk_fma_f32 v[42:43], v[42:43], v[106:107], v[94:95]
	v_pk_fma_f32 v[40:41], v[40:41], v[104:105], v[92:93]
	s_waitcnt vmcnt(0)
	v_pk_fma_f32 v[38:39], v[38:39], v[102:103], v[98:99]
	v_pk_fma_f32 v[36:37], v[36:37], v[100:101], v[96:97]
	global_store_dwordx4 v[112:113], v[64:67], off sc1
	global_store_dwordx4 v[112:113], v[60:63], off offset:64 sc1
	global_store_dwordx4 v[112:113], v[48:51], off offset:512 sc1
	global_store_dwordx4 v[112:113], v[44:47], off offset:576 sc1
	global_store_dwordx4 v[114:115], v[56:59], off sc1
	global_store_dwordx4 v[114:115], v[52:55], off offset:64 sc1
	global_store_dwordx4 v[114:115], v[40:43], off offset:512 sc1
	global_store_dwordx4 v[114:115], v[36:39], off offset:576 sc1
	v_lshlrev_b64 v[68:69], 12, v[194:195]
	v_lshl_add_u64 v[64:65], v[150:151], 0, v[68:69]
	global_load_dwordx4 v[36:39], v[118:119], off
	global_load_dwordx4 v[40:43], v[118:119], off offset:64
	global_load_dwordx4 v[44:47], v[118:119], off offset:512
	global_load_dwordx4 v[48:51], v[118:119], off offset:576
	global_load_dwordx4 v[52:55], v[64:65], off
	global_load_dwordx4 v[56:59], v[64:65], off offset:64
	global_load_dwordx4 v[60:63], v[64:65], off offset:512
	s_nop 0
	global_load_dwordx4 v[64:67], v[64:65], off offset:576
	v_lshl_add_u64 v[70:71], s[28:29], 0, v[116:117]
	v_lshl_add_u64 v[68:69], s[28:29], 0, v[68:69]
	v_lshl_add_u64 v[70:71], v[70:71], 0, v[148:149]
	v_lshl_add_u64 v[68:69], v[68:69], 0, v[148:149]
	s_waitcnt vmcnt(7)
	v_pk_fma_f32 v[34:35], v[34:35], v[130:131], v[38:39]
	v_pk_fma_f32 v[32:33], v[32:33], v[128:129], v[36:37]
	s_waitcnt vmcnt(6)
	v_pk_fma_f32 v[30:31], v[30:31], v[110:111], v[42:43]
	v_pk_fma_f32 v[28:29], v[28:29], v[108:109], v[40:41]
	s_waitcnt vmcnt(5)
	v_pk_fma_f32 v[22:23], v[22:23], v[106:107], v[46:47]
	v_pk_fma_f32 v[20:21], v[20:21], v[104:105], v[44:45]
	s_waitcnt vmcnt(4)
	v_pk_fma_f32 v[18:19], v[18:19], v[102:103], v[50:51]
	v_pk_fma_f32 v[16:17], v[16:17], v[100:101], v[48:49]
	s_waitcnt vmcnt(3)
	v_pk_fma_f32 v[26:27], v[26:27], v[130:131], v[54:55]
	v_pk_fma_f32 v[24:25], v[24:25], v[128:129], v[52:53]
	s_waitcnt vmcnt(2)
	v_pk_fma_f32 v[14:15], v[14:15], v[110:111], v[58:59]
	v_pk_fma_f32 v[12:13], v[12:13], v[108:109], v[56:57]
	s_waitcnt vmcnt(1)
	v_pk_fma_f32 v[10:11], v[10:11], v[106:107], v[62:63]
	v_pk_fma_f32 v[8:9], v[8:9], v[104:105], v[60:61]
	s_waitcnt vmcnt(0)
	v_pk_fma_f32 v[6:7], v[6:7], v[102:103], v[66:67]
	v_pk_fma_f32 v[4:5], v[4:5], v[100:101], v[64:65]
	global_store_dwordx4 v[70:71], v[32:35], off sc1
	global_store_dwordx4 v[70:71], v[28:31], off offset:64 sc1
	global_store_dwordx4 v[70:71], v[20:23], off offset:512 sc1
	global_store_dwordx4 v[70:71], v[16:19], off offset:576 sc1
	global_store_dwordx4 v[68:69], v[24:27], off sc1
	global_store_dwordx4 v[68:69], v[12:15], off offset:64 sc1
	global_store_dwordx4 v[68:69], v[8:11], off offset:512 sc1
	global_store_dwordx4 v[68:69], v[4:7], off offset:576 sc1

.LBB0_326:
	s_or_b64 exec, exec, s[8:9]
	v_lshlrev_b32_e32 v74, 16, v64
	v_and_b32_e32 v75, 0xffff0000, v64
	v_lshlrev_b32_e32 v76, 16, v66
	v_and_b32_e32 v77, 0xffff0000, v66
	v_lshlrev_b32_e32 v64, 16, v65
	v_and_b32_e32 v65, 0xffff0000, v65
	v_lshlrev_b32_e32 v66, 16, v67
	v_and_b32_e32 v67, 0xffff0000, v67
	v_pk_add_f32 v[74:75], v[76:77], v[74:75]
	v_pk_add_f32 v[64:65], v[66:67], v[64:65]
	v_mov_b32_e32 v76, v75
	v_mov_b32_e32 v77, v65
	v_mov_b32_e32 v66, v74
	v_mov_b32_e32 v67, v64
	v_pk_mul_f32 v[76:77], v[76:77], v[76:77]
	s_mov_b32 s0, 0x3e85000
	v_pk_fma_f32 v[66:67], v[66:67], v[66:67], v[76:77]
	s_nop 0
	v_add_f32_e32 v66, v66, v67
	s_nop 1
	v_add_f32_dpp v66, v66, v66 quad_perm:[1,0,3,2] row_mask:0xf bank_mask:0xf bound_ctrl:1
	s_nop 1
	v_add_f32_dpp v66, v66, v66 quad_perm:[2,3,0,1] row_mask:0xf bank_mask:0xf bound_ctrl:1
	s_nop 1
	v_add_f32_dpp v66, v66, v66 row_half_mirror row_mask:0xf bank_mask:0xf bound_ctrl:1
	s_nop 1
	v_add_f32_dpp v66, v66, v66 row_mirror row_mask:0xf bank_mask:0xf bound_ctrl:1
	v_fmamk_f32 v66, v66, 0x3c800000, v237
	v_rsq_f32_e32 v66, v66
	s_nop 0
	v_pk_mul_f32 v[74:75], v[74:75], v[66:67] op_sel_hi:[1,0]
	v_pk_mul_f32 v[64:65], v[64:65], v[66:67] op_sel_hi:[1,0]
	v_pk_mul_f32 v[66:67], v[4:5], v[74:75]
	v_lshlrev_b32_e32 v74, 16, v62
	v_and_b32_e32 v75, 0xffff0000, v62
	v_mul_f32_e32 v62, 0xbfb8aa3b, v74
	v_exp_f32_e32 v62, v62
	v_pk_mul_f32 v[64:65], v[6:7], v[64:65]
	v_add_f32_e32 v62, 1.0, v62
	v_rcp_f32_e32 v76, v62
	v_mul_f32_e32 v62, 0xbfb8aa3b, v75
	v_exp_f32_e32 v62, v62
	s_nop 0
	v_add_f32_e32 v62, 1.0, v62
	v_rcp_f32_e32 v77, v62
	v_lshlrev_b32_e32 v62, 16, v63
	v_and_b32_e32 v63, 0xffff0000, v63
	v_pk_mul_f32 v[74:75], v[76:77], v[74:75]
	s_nop 0
	v_pk_mul_f32 v[66:67], v[74:75], v[66:67]
	s_nop 0
	v_cvt_pk_bf16_f32 v66, v66, v67
	v_mul_f32_e32 v67, 0xbfb8aa3b, v62
	v_exp_f32_e32 v67, v67
	s_nop 0
	v_add_f32_e32 v67, 1.0, v67
	v_rcp_f32_e32 v74, v67
	v_mul_f32_e32 v67, 0xbfb8aa3b, v63
	v_exp_f32_e32 v67, v67
	s_nop 0
	v_add_f32_e32 v67, 1.0, v67
	v_rcp_f32_e32 v75, v67
	s_nop 0
	v_pk_mul_f32 v[62:63], v[74:75], v[62:63]
	s_nop 0
	v_pk_mul_f32 v[62:63], v[62:63], v[64:65]
	v_lshlrev_b32_e32 v64, 16, v60
	v_cvt_pk_bf16_f32 v67, v62, v63
	v_add_co_u32_e32 v62, vcc, s0, v70
	v_and_b32_e32 v65, 0xffff0000, v60
	s_nop 0
	v_addc_co_u32_e32 v63, vcc, 0, v71, vcc
	global_store_dwordx2 v[62:63], v[66:67], off sc1
	v_lshlrev_b32_e32 v66, 16, v58
	v_and_b32_e32 v67, 0xffff0000, v58
	v_lshlrev_b32_e32 v60, 16, v61
	v_and_b32_e32 v61, 0xffff0000, v61
	v_lshlrev_b32_e32 v58, 16, v59
	v_and_b32_e32 v59, 0xffff0000, v59
	v_pk_add_f32 v[64:65], v[66:67], v[64:65]
	v_pk_add_f32 v[58:59], v[58:59], v[60:61]
	v_mov_b32_e32 v66, v65
	v_mov_b32_e32 v67, v59
	v_mov_b32_e32 v60, v64
	v_mov_b32_e32 v61, v58
	v_pk_mul_f32 v[66:67], v[66:67], v[66:67]
	s_mov_b64 s[0:1], 0x800
	v_pk_fma_f32 v[60:61], v[60:61], v[60:61], v[66:67]
	v_lshl_add_u64 v[20:21], v[20:21], 0, s[0:1]
	v_add_f32_e32 v60, v60, v61
	s_mov_b64 s[0:1], 0x1c00
	v_lshl_add_u64 v[24:25], v[24:25], 0, s[0:1]
	v_add_f32_dpp v60, v60, v60 quad_perm:[1,0,3,2] row_mask:0xf bank_mask:0xf bound_ctrl:1
	s_nop 1
	v_add_f32_dpp v60, v60, v60 quad_perm:[2,3,0,1] row_mask:0xf bank_mask:0xf bound_ctrl:1
	s_nop 1
	v_add_f32_dpp v60, v60, v60 row_half_mirror row_mask:0xf bank_mask:0xf bound_ctrl:1
	s_nop 1
	v_add_f32_dpp v60, v60, v60 row_mirror row_mask:0xf bank_mask:0xf bound_ctrl:1
	v_fmamk_f32 v60, v60, 0x3c800000, v237
	v_rsq_f32_e32 v60, v60
	s_nop 0
	v_pk_mul_f32 v[58:59], v[58:59], v[60:61] op_sel_hi:[1,0]
	v_pk_mul_f32 v[60:61], v[64:65], v[60:61] op_sel_hi:[1,0]
	v_lshlrev_b32_e32 v64, 16, v56
	v_and_b32_e32 v65, 0xffff0000, v56
	v_mul_f32_e32 v56, 0xbfb8aa3b, v64
	v_exp_f32_e32 v56, v56
	s_nop 0
	v_add_f32_e32 v56, 1.0, v56
	v_rcp_f32_e32 v66, v56
	v_mul_f32_e32 v56, 0xbfb8aa3b, v65
	v_exp_f32_e32 v56, v56
	s_nop 0
	v_add_f32_e32 v56, 1.0, v56
	v_rcp_f32_e32 v67, v56
	s_nop 0
	v_pk_mul_f32 v[64:65], v[66:67], v[64:65]
	s_nop 0
	v_pk_mul_f32 v[60:61], v[64:65], v[60:61]
	s_waitcnt vmcnt(8)
	v_mov_b64_e32 v[66:67], v[26:27]
	v_cvt_pk_bf16_f32 v56, v60, v61
	v_lshlrev_b32_e32 v60, 16, v57
	v_and_b32_e32 v61, 0xffff0000, v57
	v_mul_f32_e32 v57, 0xbfb8aa3b, v60
	v_exp_f32_e32 v57, v57
	s_nop 0
	v_add_f32_e32 v57, 1.0, v57
	v_rcp_f32_e32 v64, v57
	v_mul_f32_e32 v57, 0xbfb8aa3b, v61
	v_exp_f32_e32 v57, v57
	s_nop 0
	v_add_f32_e32 v57, 1.0, v57
	v_rcp_f32_e32 v65, v57
	s_nop 0
	v_pk_mul_f32 v[60:61], v[64:65], v[60:61]
	s_nop 0
	v_pk_mul_f32 v[58:59], v[60:61], v[58:59]
	v_mov_b64_e32 v[64:65], v[32:33]
	v_cvt_pk_bf16_f32 v57, v58, v59
	global_store_dwordx2 v[62:63], v[56:57], off offset:512 sc1
	v_lshlrev_b32_e32 v56, 16, v54
	v_and_b32_e32 v57, 0xffff0000, v54
	v_lshlrev_b32_e32 v58, 16, v52
	v_and_b32_e32 v59, 0xffff0000, v52
	v_lshlrev_b32_e32 v54, 16, v55
	v_and_b32_e32 v55, 0xffff0000, v55
	v_lshlrev_b32_e32 v52, 16, v53
	v_and_b32_e32 v53, 0xffff0000, v53
	v_pk_add_f32 v[56:57], v[58:59], v[56:57]
	v_pk_add_f32 v[52:53], v[52:53], v[54:55]
	v_mov_b32_e32 v58, v57
	v_mov_b32_e32 v59, v53
	v_mov_b32_e32 v54, v56
	v_mov_b32_e32 v55, v52
	v_pk_mul_f32 v[58:59], v[58:59], v[58:59]
	v_mov_b64_e32 v[60:61], v[38:39]
	v_pk_fma_f32 v[54:55], v[54:55], v[54:55], v[58:59]
	s_nop 0
	v_add_f32_e32 v54, v54, v55
	s_nop 1
	v_add_f32_dpp v54, v54, v54 quad_perm:[1,0,3,2] row_mask:0xf bank_mask:0xf bound_ctrl:1
	s_nop 1
	v_add_f32_dpp v54, v54, v54 quad_perm:[2,3,0,1] row_mask:0xf bank_mask:0xf bound_ctrl:1
	s_nop 1
	v_add_f32_dpp v54, v54, v54 row_half_mirror row_mask:0xf bank_mask:0xf bound_ctrl:1
	s_nop 1
	v_add_f32_dpp v54, v54, v54 row_mirror row_mask:0xf bank_mask:0xf bound_ctrl:1
	v_fmamk_f32 v54, v54, 0x3c800000, v237
	v_rsq_f32_e32 v54, v54
	s_nop 0
	v_pk_mul_f32 v[56:57], v[56:57], v[54:55] op_sel_hi:[1,0]
	v_pk_mul_f32 v[52:53], v[52:53], v[54:55] op_sel_hi:[1,0]
	v_pk_mul_f32 v[54:55], v[8:9], v[56:57]
	v_lshlrev_b32_e32 v56, 16, v50
	v_and_b32_e32 v57, 0xffff0000, v50
	v_mul_f32_e32 v50, 0xbfb8aa3b, v56
	v_exp_f32_e32 v50, v50
	v_pk_mul_f32 v[52:53], v[10:11], v[52:53]
	v_add_f32_e32 v50, 1.0, v50
	v_rcp_f32_e32 v58, v50
	v_mul_f32_e32 v50, 0xbfb8aa3b, v57
	v_exp_f32_e32 v50, v50
	s_nop 0
	v_add_f32_e32 v50, 1.0, v50
	v_rcp_f32_e32 v59, v50
	s_nop 0
	v_pk_mul_f32 v[56:57], v[58:59], v[56:57]
	s_nop 0
	v_pk_mul_f32 v[54:55], v[56:57], v[54:55]
	s_waitcnt vmcnt(8)
	v_mov_b64_e32 v[58:59], v[40:41]
	v_cvt_pk_bf16_f32 v50, v54, v55
	v_lshlrev_b32_e32 v54, 16, v51
	v_and_b32_e32 v55, 0xffff0000, v51
	v_mul_f32_e32 v51, 0xbfb8aa3b, v54
	v_exp_f32_e32 v51, v51
	s_nop 0
	v_add_f32_e32 v51, 1.0, v51
	v_rcp_f32_e32 v56, v51
	v_mul_f32_e32 v51, 0xbfb8aa3b, v55
	v_exp_f32_e32 v51, v51
	s_nop 0
	v_add_f32_e32 v51, 1.0, v51
	v_rcp_f32_e32 v57, v51
	s_nop 0
	v_pk_mul_f32 v[54:55], v[56:57], v[54:55]
	s_nop 0
	v_pk_mul_f32 v[52:53], v[54:55], v[52:53]
	s_waitcnt vmcnt(4)
	v_mov_b64_e32 v[56:57], v[30:31]
	v_cvt_pk_bf16_f32 v51, v52, v53
	global_store_dwordx2 v[62:63], v[50:51], off offset:1024 sc1
	v_lshlrev_b32_e32 v50, 16, v18
	v_and_b32_e32 v51, 0xffff0000, v18
	v_lshlrev_b32_e32 v52, 16, v16
	v_and_b32_e32 v53, 0xffff0000, v16
	v_pk_add_f32 v[50:51], v[52:53], v[50:51]
	v_lshlrev_b32_e32 v52, 16, v22
	v_and_b32_e32 v53, 0xffff0000, v22
	v_pk_fma_f32 v[50:51], v[12:13], v[52:53], v[50:51]
	v_lshlrev_b32_e32 v18, 16, v19
	v_mul_f32_e32 v16, 0x3d372713, v50
	v_mul_f32_e32 v16, v50, v16
	v_fma_f32 v16, v50, v16, v50
	v_mul_f32_e32 v16, 0x3f4c422a, v16
	v_mul_f32_e32 v16, 0xc038aa3b, v16
	v_exp_f32_e32 v16, v16
	v_and_b32_e32 v19, 0xffff0000, v19
	v_lshlrev_b32_e32 v22, 16, v23
	v_and_b32_e32 v23, 0xffff0000, v23
	v_add_f32_e32 v16, 1.0, v16
	v_rcp_f32_e32 v52, v16
	v_mul_f32_e32 v16, 0x3d372713, v51
	v_mul_f32_e32 v16, v51, v16
	v_fma_f32 v16, v51, v16, v51
	v_mul_f32_e32 v16, 0x3f4c422a, v16
	v_mul_f32_e32 v16, 0xc038aa3b, v16
	v_exp_f32_e32 v16, v16
	v_mov_b64_e32 v[54:55], v[44:45]
	v_add_f32_e32 v16, 1.0, v16
	v_rcp_f32_e32 v53, v16
	s_nop 0
	v_pk_mul_f32 v[50:51], v[50:51], v[52:53]
	s_nop 0
	v_cvt_pk_bf16_f32 v16, v50, v51
	v_lshlrev_b32_e32 v50, 16, v17
	v_and_b32_e32 v51, 0xffff0000, v17
	v_pk_add_f32 v[18:19], v[50:51], v[18:19]
	s_waitcnt vmcnt(4)
	v_mov_b64_e32 v[50:51], v[34:35]
	v_pk_fma_f32 v[18:19], v[14:15], v[22:23], v[18:19]
	v_mov_b64_e32 v[52:53], v[42:43]
	v_mul_f32_e32 v17, 0x3d372713, v18
	v_mul_f32_e32 v17, v18, v17
	v_fma_f32 v17, v18, v17, v18
	v_mul_f32_e32 v17, 0x3f4c422a, v17
	v_mul_f32_e32 v17, 0xc038aa3b, v17
	v_exp_f32_e32 v17, v17
	s_nop 0
	v_add_f32_e32 v17, 1.0, v17
	v_rcp_f32_e32 v22, v17
	v_mul_f32_e32 v17, 0x3d372713, v19
	v_mul_f32_e32 v17, v19, v17
	v_fma_f32 v17, v19, v17, v19
	v_mul_f32_e32 v17, 0x3f4c422a, v17
	v_mul_f32_e32 v17, 0xc038aa3b, v17
	v_exp_f32_e32 v17, v17
	s_nop 0
	v_add_f32_e32 v17, 1.0, v17
	v_rcp_f32_e32 v23, v17
	s_nop 0
	v_pk_mul_f32 v[18:19], v[18:19], v[22:23]
	s_nop 0
	v_cvt_pk_bf16_f32 v17, v18, v19
	global_store_dwordx2 v[62:63], v[16:17], off offset:1536 sc1
	v_mov_b64_e32 v[62:63], v[28:29]
	s_waitcnt vmcnt(4)
	v_mov_b64_e32 v[22:23], v[36:37]
	v_mov_b64_e32 v[16:17], v[46:47]
	v_mov_b64_e32 v[18:19], v[48:49]
	s_andn2_b64 exec, exec, s[12:13]
	s_cbranch_execz .LBB0_329

.LBB0_332:
	v_add_u32_e32 v133, v69, v68
	v_min_i32_e32 v4, v133, v107
	v_ashrrev_i32_e32 v5, 31, v4
	v_lshlrev_b64 v[4:5], 11, v[4:5]
	v_lshl_add_u64 v[36:37], s[6:7], 0, v[4:5]
	v_lshl_add_u64 v[4:5], v[36:37], 0, v[180:181]
	global_load_dwordx4 v[32:35], v[4:5], off offset:1536
	global_load_dwordx4 v[28:31], v[4:5], off offset:1600
	global_load_dwordx4 v[24:27], v[4:5], off offset:1664
	global_load_dwordx4 v[20:23], v[4:5], off offset:1728
	global_load_dwordx4 v[16:19], v[4:5], off offset:1792
	global_load_dwordx4 v[12:15], v[4:5], off offset:1856
	global_load_dwordx4 v[8:11], v[4:5], off offset:1920
	s_nop 0
	global_load_dwordx4 v[4:7], v[4:5], off offset:1984
	v_mov_b32_e32 v71, v181
	v_lshl_add_u64 v[72:73], v[36:37], 0, v[70:71]
	global_load_dwordx2 v[104:105], v[72:73], off offset:1536
	global_load_dwordx2 v[102:103], v[72:73], off offset:1568
	global_load_dwordx2 v[100:101], v[72:73], off offset:1600
	global_load_dwordx2 v[98:99], v[72:73], off offset:1632
	global_load_dwordx2 v[96:97], v[72:73], off offset:1664
	global_load_dwordx2 v[94:95], v[72:73], off offset:1696
	global_load_dwordx2 v[92:93], v[72:73], off offset:1728
	global_load_dwordx2 v[90:91], v[72:73], off offset:1760
	global_load_dwordx2 v[88:89], v[72:73], off offset:1792
	global_load_dwordx2 v[86:87], v[72:73], off offset:1824
	global_load_dwordx2 v[84:85], v[72:73], off offset:1856
	global_load_dwordx2 v[82:83], v[72:73], off offset:1888
	global_load_dwordx2 v[80:81], v[72:73], off offset:1920
	global_load_dwordx2 v[78:79], v[72:73], off offset:1952
	global_load_dwordx2 v[76:77], v[72:73], off offset:1984
	global_load_dwordx2 v[74:75], v[72:73], off offset:2016
	ds_read_b128 v[36:39], v109
	v_cmp_lt_i32_e32 vcc, v133, v106
	s_waitcnt vmcnt(23) lgkmcnt(0)
	v_mfma_f32_16x16x32_bf16 v[44:47], v[36:39], v[32:35], 0
	ds_read_b128 v[36:39], v109 offset:8448
	s_waitcnt lgkmcnt(0)
	v_mfma_f32_16x16x32_bf16 v[48:51], v[36:39], v[32:35], 0
	ds_read_b128 v[36:39], v109 offset:16896
	s_waitcnt lgkmcnt(0)
	v_mfma_f32_16x16x32_bf16 v[52:55], v[36:39], v[32:35], 0
	ds_read_b128 v[36:39], v109 offset:25344
	s_waitcnt lgkmcnt(0)
	v_mfma_f32_16x16x32_bf16 v[56:59], v[36:39], v[32:35], 0
	ds_read_b128 v[36:39], v109 offset:33792
	s_waitcnt lgkmcnt(0)
	v_mfma_f32_16x16x32_bf16 v[60:63], v[36:39], v[32:35], 0
	ds_read_b128 v[36:39], v109 offset:42240
	s_waitcnt lgkmcnt(0)
	v_mfma_f32_16x16x32_bf16 v[64:67], v[36:39], v[32:35], 0
	ds_read_b128 v[36:39], v109 offset:50688
	s_waitcnt lgkmcnt(0)
	v_mfma_f32_16x16x32_bf16 v[40:43], v[36:39], v[32:35], 0
	ds_read_b128 v[36:39], v109 offset:59136
	ds_read_b128 v[134:137], v125
	ds_read_b128 v[138:141], v126
	ds_read_b128 v[142:145], v127
	ds_read_b128 v[146:149], v128
	ds_read_b128 v[150:153], v129
	ds_read_b128 v[154:157], v130
	ds_read_b128 v[158:161], v131
	ds_read_b128 v[162:165], v132
	s_waitcnt lgkmcnt(8)
	v_mfma_f32_16x16x32_bf16 v[36:39], v[36:39], v[32:35], 0
	s_waitcnt lgkmcnt(7)
	v_mfma_f32_16x16x32_bf16 v[134:137], v[134:137], v[32:35], 0
	s_waitcnt lgkmcnt(6)
	v_mfma_f32_16x16x32_bf16 v[138:141], v[138:141], v[32:35], 0
	s_waitcnt lgkmcnt(5)
	v_mfma_f32_16x16x32_bf16 v[142:145], v[142:145], v[32:35], 0
	s_waitcnt lgkmcnt(4)
	v_mfma_f32_16x16x32_bf16 v[146:149], v[146:149], v[32:35], 0
	s_waitcnt lgkmcnt(3)
	v_mfma_f32_16x16x32_bf16 v[150:153], v[150:153], v[32:35], 0
	s_waitcnt lgkmcnt(2)
	v_mfma_f32_16x16x32_bf16 v[154:157], v[154:157], v[32:35], 0
	s_waitcnt lgkmcnt(1)
	v_mfma_f32_16x16x32_bf16 v[158:161], v[158:161], v[32:35], 0
	s_waitcnt lgkmcnt(0)
	v_mfma_f32_16x16x32_bf16 v[32:35], v[162:165], v[32:35], 0
	ds_read_b128 v[162:165], v109 offset:64
	s_waitcnt vmcnt(22) lgkmcnt(0)
	v_mfma_f32_16x16x32_bf16 v[44:47], v[162:165], v[28:31], v[44:47]
	ds_read_b128 v[162:165], v109 offset:8512
	s_waitcnt lgkmcnt(0)
	v_mfma_f32_16x16x32_bf16 v[48:51], v[162:165], v[28:31], v[48:51]
	ds_read_b128 v[162:165], v109 offset:16960
	s_waitcnt lgkmcnt(0)
	v_mfma_f32_16x16x32_bf16 v[52:55], v[162:165], v[28:31], v[52:55]
	ds_read_b128 v[162:165], v109 offset:25408
	s_waitcnt lgkmcnt(0)
	v_mfma_f32_16x16x32_bf16 v[56:59], v[162:165], v[28:31], v[56:59]
	ds_read_b128 v[162:165], v109 offset:33856
	s_waitcnt lgkmcnt(0)
	v_mfma_f32_16x16x32_bf16 v[60:63], v[162:165], v[28:31], v[60:63]
	ds_read_b128 v[162:165], v109 offset:42304
	s_waitcnt lgkmcnt(0)
	v_mfma_f32_16x16x32_bf16 v[64:67], v[162:165], v[28:31], v[64:67]
	ds_read_b128 v[162:165], v109 offset:50752
	s_waitcnt lgkmcnt(0)
	v_mfma_f32_16x16x32_bf16 v[40:43], v[162:165], v[28:31], v[40:43]
	ds_read_b128 v[162:165], v109 offset:59200
	s_waitcnt lgkmcnt(0)
	v_mfma_f32_16x16x32_bf16 v[36:39], v[162:165], v[28:31], v[36:39]
	ds_read_b128 v[162:165], v125 offset:64
	s_waitcnt lgkmcnt(0)
	v_mfma_f32_16x16x32_bf16 v[134:137], v[162:165], v[28:31], v[134:137]
	ds_read_b128 v[162:165], v126 offset:64
	s_waitcnt lgkmcnt(0)
	v_mfma_f32_16x16x32_bf16 v[138:141], v[162:165], v[28:31], v[138:141]
	ds_read_b128 v[162:165], v127 offset:64
	s_waitcnt lgkmcnt(0)
	v_mfma_f32_16x16x32_bf16 v[142:145], v[162:165], v[28:31], v[142:145]
	ds_read_b128 v[162:165], v128 offset:64
	s_waitcnt lgkmcnt(0)
	v_mfma_f32_16x16x32_bf16 v[146:149], v[162:165], v[28:31], v[146:149]
	ds_read_b128 v[162:165], v129 offset:64
	s_waitcnt lgkmcnt(0)
	v_mfma_f32_16x16x32_bf16 v[150:153], v[162:165], v[28:31], v[150:153]
	ds_read_b128 v[162:165], v130 offset:64
	s_waitcnt lgkmcnt(0)
	v_mfma_f32_16x16x32_bf16 v[154:157], v[162:165], v[28:31], v[154:157]
	ds_read_b128 v[162:165], v131 offset:64
	s_waitcnt lgkmcnt(0)
	v_mfma_f32_16x16x32_bf16 v[158:161], v[162:165], v[28:31], v[158:161]
	ds_read_b128 v[162:165], v132 offset:64
	s_waitcnt lgkmcnt(0)
	v_mfma_f32_16x16x32_bf16 v[28:31], v[162:165], v[28:31], v[32:35]
	s_nop 2
	ds_read_b128 v[32:35], v109 offset:128
	s_waitcnt vmcnt(21) lgkmcnt(0)
	v_mfma_f32_16x16x32_bf16 v[32:35], v[32:35], v[24:27], v[44:47]
	s_nop 2
	ds_read_b128 v[44:47], v109 offset:8576
	s_waitcnt lgkmcnt(0)
	v_mfma_f32_16x16x32_bf16 v[44:47], v[44:47], v[24:27], v[48:51]
	s_nop 2
	ds_read_b128 v[48:51], v109 offset:17024
	s_waitcnt lgkmcnt(0)
	v_mfma_f32_16x16x32_bf16 v[48:51], v[48:51], v[24:27], v[52:55]
	s_nop 2
	ds_read_b128 v[52:55], v109 offset:25472
	s_waitcnt lgkmcnt(0)
	v_mfma_f32_16x16x32_bf16 v[52:55], v[52:55], v[24:27], v[56:59]
	s_nop 2
	ds_read_b128 v[56:59], v109 offset:33920
	s_waitcnt lgkmcnt(0)
	v_mfma_f32_16x16x32_bf16 v[56:59], v[56:59], v[24:27], v[60:63]
	s_nop 2
	ds_read_b128 v[60:63], v109 offset:42368
	s_waitcnt lgkmcnt(0)
	v_mfma_f32_16x16x32_bf16 v[60:63], v[60:63], v[24:27], v[64:67]
	s_nop 2
	ds_read_b128 v[64:67], v109 offset:50816
	s_waitcnt lgkmcnt(0)
	v_mfma_f32_16x16x32_bf16 v[40:43], v[64:67], v[24:27], v[40:43]
	ds_read_b128 v[64:67], v109 offset:59264
	s_waitcnt lgkmcnt(0)
	v_mfma_f32_16x16x32_bf16 v[36:39], v[64:67], v[24:27], v[36:39]
	ds_read_b128 v[64:67], v125 offset:128
	s_waitcnt lgkmcnt(0)
	v_mfma_f32_16x16x32_bf16 v[64:67], v[64:67], v[24:27], v[134:137]
	s_nop 2
	ds_read_b128 v[134:137], v126 offset:128
	s_waitcnt lgkmcnt(0)
	v_mfma_f32_16x16x32_bf16 v[134:137], v[134:137], v[24:27], v[138:141]
	s_nop 2
	ds_read_b128 v[138:141], v127 offset:128
	s_waitcnt lgkmcnt(0)
	v_mfma_f32_16x16x32_bf16 v[138:141], v[138:141], v[24:27], v[142:145]
	s_nop 2
	ds_read_b128 v[142:145], v128 offset:128
	s_waitcnt lgkmcnt(0)
	v_mfma_f32_16x16x32_bf16 v[142:145], v[142:145], v[24:27], v[146:149]
	s_nop 2
	ds_read_b128 v[146:149], v129 offset:128
	s_waitcnt lgkmcnt(0)
	v_mfma_f32_16x16x32_bf16 v[146:149], v[146:149], v[24:27], v[150:153]
	s_nop 2
	ds_read_b128 v[150:153], v130 offset:128
	s_waitcnt lgkmcnt(0)
	v_mfma_f32_16x16x32_bf16 v[150:153], v[150:153], v[24:27], v[154:157]
	s_nop 2
	ds_read_b128 v[154:157], v131 offset:128
	s_waitcnt lgkmcnt(0)
	v_mfma_f32_16x16x32_bf16 v[154:157], v[154:157], v[24:27], v[158:161]
	s_nop 2
	ds_read_b128 v[158:161], v132 offset:128
	s_waitcnt lgkmcnt(0)
	v_mfma_f32_16x16x32_bf16 v[24:27], v[158:161], v[24:27], v[28:31]
	s_nop 2
	ds_read_b128 v[28:31], v109 offset:192
	s_waitcnt vmcnt(20) lgkmcnt(0)
	v_mfma_f32_16x16x32_bf16 v[28:31], v[28:31], v[20:23], v[32:35]
	s_nop 2
	ds_read_b128 v[32:35], v109 offset:8640
	s_waitcnt lgkmcnt(0)
	v_mfma_f32_16x16x32_bf16 v[32:35], v[32:35], v[20:23], v[44:47]
	s_nop 2
	ds_read_b128 v[44:47], v109 offset:17088
	s_waitcnt lgkmcnt(0)
	v_mfma_f32_16x16x32_bf16 v[44:47], v[44:47], v[20:23], v[48:51]
	s_nop 2
	ds_read_b128 v[48:51], v109 offset:25536
	s_waitcnt lgkmcnt(0)
	v_mfma_f32_16x16x32_bf16 v[48:51], v[48:51], v[20:23], v[52:55]
	s_nop 2
	ds_read_b128 v[52:55], v109 offset:33984
	s_waitcnt lgkmcnt(0)
	v_mfma_f32_16x16x32_bf16 v[52:55], v[52:55], v[20:23], v[56:59]
	s_nop 2
	ds_read_b128 v[56:59], v109 offset:42432
	s_waitcnt lgkmcnt(0)
	v_mfma_f32_16x16x32_bf16 v[56:59], v[56:59], v[20:23], v[60:63]
	s_nop 2
	ds_read_b128 v[60:63], v109 offset:50880
	s_waitcnt lgkmcnt(0)
	v_mfma_f32_16x16x32_bf16 v[40:43], v[60:63], v[20:23], v[40:43]
	ds_read_b128 v[60:63], v109 offset:59328
	s_waitcnt lgkmcnt(0)
	v_mfma_f32_16x16x32_bf16 v[36:39], v[60:63], v[20:23], v[36:39]
	ds_read_b128 v[60:63], v125 offset:192
	s_waitcnt lgkmcnt(0)
	v_mfma_f32_16x16x32_bf16 v[60:63], v[60:63], v[20:23], v[64:67]
	s_nop 2
	ds_read_b128 v[64:67], v126 offset:192
	s_waitcnt lgkmcnt(0)
	v_mfma_f32_16x16x32_bf16 v[64:67], v[64:67], v[20:23], v[134:137]
	s_nop 2
	ds_read_b128 v[134:137], v127 offset:192
	s_waitcnt lgkmcnt(0)
	v_mfma_f32_16x16x32_bf16 v[134:137], v[134:137], v[20:23], v[138:141]
	s_nop 2
	ds_read_b128 v[138:141], v128 offset:192
	s_waitcnt lgkmcnt(0)
	v_mfma_f32_16x16x32_bf16 v[138:141], v[138:141], v[20:23], v[142:145]
	s_nop 2
	ds_read_b128 v[142:145], v129 offset:192
	s_waitcnt lgkmcnt(0)
	v_mfma_f32_16x16x32_bf16 v[142:145], v[142:145], v[20:23], v[146:149]
	s_nop 2
	ds_read_b128 v[146:149], v130 offset:192
	s_waitcnt lgkmcnt(0)
	v_mfma_f32_16x16x32_bf16 v[146:149], v[146:149], v[20:23], v[150:153]
	s_nop 2
	ds_read_b128 v[150:153], v131 offset:192
	s_waitcnt lgkmcnt(0)
	v_mfma_f32_16x16x32_bf16 v[150:153], v[150:153], v[20:23], v[154:157]
	s_nop 2
	ds_read_b128 v[154:157], v132 offset:192
	s_waitcnt lgkmcnt(0)
	v_mfma_f32_16x16x32_bf16 v[20:23], v[154:157], v[20:23], v[24:27]
	s_nop 2
	ds_read_b128 v[24:27], v109 offset:256
	s_waitcnt vmcnt(19) lgkmcnt(0)
	v_mfma_f32_16x16x32_bf16 v[24:27], v[24:27], v[16:19], v[28:31]
	s_nop 2
	ds_read_b128 v[28:31], v109 offset:8704
	s_waitcnt lgkmcnt(0)
	v_mfma_f32_16x16x32_bf16 v[28:31], v[28:31], v[16:19], v[32:35]
	s_nop 2
	ds_read_b128 v[32:35], v109 offset:17152
	s_waitcnt lgkmcnt(0)
	v_mfma_f32_16x16x32_bf16 v[32:35], v[32:35], v[16:19], v[44:47]
	s_nop 2
	ds_read_b128 v[44:47], v109 offset:25600
	s_waitcnt lgkmcnt(0)
	v_mfma_f32_16x16x32_bf16 v[44:47], v[44:47], v[16:19], v[48:51]
	s_nop 2
	ds_read_b128 v[48:51], v109 offset:34048
	s_waitcnt lgkmcnt(0)
	v_mfma_f32_16x16x32_bf16 v[48:51], v[48:51], v[16:19], v[52:55]
	s_nop 2
	ds_read_b128 v[52:55], v109 offset:42496
	s_waitcnt lgkmcnt(0)
	v_mfma_f32_16x16x32_bf16 v[52:55], v[52:55], v[16:19], v[56:59]
	s_nop 2
	ds_read_b128 v[56:59], v109 offset:50944
	s_waitcnt lgkmcnt(0)
	v_mfma_f32_16x16x32_bf16 v[40:43], v[56:59], v[16:19], v[40:43]
	ds_read_b128 v[56:59], v109 offset:59392
	s_waitcnt lgkmcnt(0)
	v_mfma_f32_16x16x32_bf16 v[36:39], v[56:59], v[16:19], v[36:39]
	ds_read_b128 v[56:59], v125 offset:256
	s_waitcnt lgkmcnt(0)
	v_mfma_f32_16x16x32_bf16 v[56:59], v[56:59], v[16:19], v[60:63]
	s_nop 2
	ds_read_b128 v[60:63], v126 offset:256
	s_waitcnt lgkmcnt(0)
	v_mfma_f32_16x16x32_bf16 v[60:63], v[60:63], v[16:19], v[64:67]
	s_nop 2
	ds_read_b128 v[64:67], v127 offset:256
	s_waitcnt lgkmcnt(0)
	v_mfma_f32_16x16x32_bf16 v[64:67], v[64:67], v[16:19], v[134:137]
	s_nop 2
	ds_read_b128 v[134:137], v128 offset:256
	s_waitcnt lgkmcnt(0)
	v_mfma_f32_16x16x32_bf16 v[134:137], v[134:137], v[16:19], v[138:141]
	s_nop 2
	ds_read_b128 v[138:141], v129 offset:256
	s_waitcnt lgkmcnt(0)
	v_mfma_f32_16x16x32_bf16 v[138:141], v[138:141], v[16:19], v[142:145]
	s_nop 2
	ds_read_b128 v[142:145], v130 offset:256
	s_waitcnt lgkmcnt(0)
	v_mfma_f32_16x16x32_bf16 v[142:145], v[142:145], v[16:19], v[146:149]
	s_nop 2
	ds_read_b128 v[146:149], v131 offset:256
	s_waitcnt lgkmcnt(0)
	v_mfma_f32_16x16x32_bf16 v[146:149], v[146:149], v[16:19], v[150:153]
	s_nop 2
	ds_read_b128 v[150:153], v132 offset:256
	s_waitcnt lgkmcnt(0)
	v_mfma_f32_16x16x32_bf16 v[16:19], v[150:153], v[16:19], v[20:23]
	s_nop 2
	ds_read_b128 v[20:23], v109 offset:320
	s_waitcnt vmcnt(18) lgkmcnt(0)
	v_mfma_f32_16x16x32_bf16 v[20:23], v[20:23], v[12:15], v[24:27]
	s_nop 2
	ds_read_b128 v[24:27], v109 offset:8768
	s_waitcnt lgkmcnt(0)
	v_mfma_f32_16x16x32_bf16 v[24:27], v[24:27], v[12:15], v[28:31]
	s_nop 2
	ds_read_b128 v[28:31], v109 offset:17216
	s_waitcnt lgkmcnt(0)
	v_mfma_f32_16x16x32_bf16 v[28:31], v[28:31], v[12:15], v[32:35]
	s_nop 2
	ds_read_b128 v[32:35], v109 offset:25664
	s_waitcnt lgkmcnt(0)
	v_mfma_f32_16x16x32_bf16 v[32:35], v[32:35], v[12:15], v[44:47]
	s_nop 2
	ds_read_b128 v[44:47], v109 offset:34112
	s_waitcnt lgkmcnt(0)
	v_mfma_f32_16x16x32_bf16 v[44:47], v[44:47], v[12:15], v[48:51]
	s_nop 2
	ds_read_b128 v[48:51], v109 offset:42560
	s_waitcnt lgkmcnt(0)
	v_mfma_f32_16x16x32_bf16 v[48:51], v[48:51], v[12:15], v[52:55]
	s_nop 2
	ds_read_b128 v[52:55], v109 offset:51008
	s_waitcnt lgkmcnt(0)
	v_mfma_f32_16x16x32_bf16 v[40:43], v[52:55], v[12:15], v[40:43]
	ds_read_b128 v[52:55], v109 offset:59456
	s_waitcnt lgkmcnt(0)
	v_mfma_f32_16x16x32_bf16 v[36:39], v[52:55], v[12:15], v[36:39]
	ds_read_b128 v[52:55], v125 offset:320
	s_waitcnt lgkmcnt(0)
	v_mfma_f32_16x16x32_bf16 v[52:55], v[52:55], v[12:15], v[56:59]
	s_nop 2
	ds_read_b128 v[56:59], v126 offset:320
	s_waitcnt lgkmcnt(0)
	v_mfma_f32_16x16x32_bf16 v[56:59], v[56:59], v[12:15], v[60:63]
	s_nop 2
	ds_read_b128 v[60:63], v127 offset:320
	s_waitcnt lgkmcnt(0)
	v_mfma_f32_16x16x32_bf16 v[60:63], v[60:63], v[12:15], v[64:67]
	s_nop 2
	ds_read_b128 v[64:67], v128 offset:320
	s_waitcnt lgkmcnt(0)
	v_mfma_f32_16x16x32_bf16 v[64:67], v[64:67], v[12:15], v[134:137]
	s_nop 2
	ds_read_b128 v[134:137], v129 offset:320
	s_waitcnt lgkmcnt(0)
	v_mfma_f32_16x16x32_bf16 v[134:137], v[134:137], v[12:15], v[138:141]
	s_nop 2
	ds_read_b128 v[138:141], v130 offset:320
	s_waitcnt lgkmcnt(0)
	v_mfma_f32_16x16x32_bf16 v[138:141], v[138:141], v[12:15], v[142:145]
	s_nop 2
	ds_read_b128 v[142:145], v131 offset:320
	s_waitcnt lgkmcnt(0)
	v_mfma_f32_16x16x32_bf16 v[142:145], v[142:145], v[12:15], v[146:149]
	s_nop 2
	ds_read_b128 v[146:149], v132 offset:320
	s_waitcnt lgkmcnt(0)
	v_mfma_f32_16x16x32_bf16 v[12:15], v[146:149], v[12:15], v[16:19]
	s_nop 2
	ds_read_b128 v[16:19], v109 offset:384
	s_waitcnt vmcnt(17) lgkmcnt(0)
	v_mfma_f32_16x16x32_bf16 v[16:19], v[16:19], v[8:11], v[20:23]
	s_nop 2
	ds_read_b128 v[20:23], v109 offset:8832
	s_waitcnt lgkmcnt(0)
	v_mfma_f32_16x16x32_bf16 v[20:23], v[20:23], v[8:11], v[24:27]
	s_nop 2
	ds_read_b128 v[24:27], v109 offset:17280
	s_waitcnt lgkmcnt(0)
	v_mfma_f32_16x16x32_bf16 v[24:27], v[24:27], v[8:11], v[28:31]
	s_nop 2
	ds_read_b128 v[28:31], v109 offset:25728
	s_waitcnt lgkmcnt(0)
	v_mfma_f32_16x16x32_bf16 v[28:31], v[28:31], v[8:11], v[32:35]
	s_nop 2
	ds_read_b128 v[32:35], v109 offset:34176
	s_waitcnt lgkmcnt(0)
	v_mfma_f32_16x16x32_bf16 v[32:35], v[32:35], v[8:11], v[44:47]
	s_nop 2
	ds_read_b128 v[44:47], v109 offset:42624
	s_waitcnt lgkmcnt(0)
	v_mfma_f32_16x16x32_bf16 v[44:47], v[44:47], v[8:11], v[48:51]
	s_nop 2
	ds_read_b128 v[48:51], v109 offset:51072
	s_waitcnt lgkmcnt(0)
	v_mfma_f32_16x16x32_bf16 v[40:43], v[48:51], v[8:11], v[40:43]
	ds_read_b128 v[48:51], v109 offset:59520
	s_waitcnt lgkmcnt(0)
	v_mfma_f32_16x16x32_bf16 v[36:39], v[48:51], v[8:11], v[36:39]
	ds_read_b128 v[48:51], v125 offset:384
	s_waitcnt lgkmcnt(0)
	v_mfma_f32_16x16x32_bf16 v[146:149], v[48:51], v[8:11], v[52:55]
	ds_read_b128 v[48:51], v126 offset:384
	s_waitcnt lgkmcnt(0)
	v_mfma_f32_16x16x32_bf16 v[150:153], v[48:51], v[8:11], v[56:59]
	ds_read_b128 v[48:51], v127 offset:384
	s_waitcnt lgkmcnt(0)
	v_mfma_f32_16x16x32_bf16 v[154:157], v[48:51], v[8:11], v[60:63]
	ds_read_b128 v[48:51], v128 offset:384
	s_waitcnt lgkmcnt(0)
	v_mfma_f32_16x16x32_bf16 v[158:161], v[48:51], v[8:11], v[64:67]
	ds_read_b128 v[48:51], v129 offset:384
	s_waitcnt lgkmcnt(0)
	v_mfma_f32_16x16x32_bf16 v[134:137], v[48:51], v[8:11], v[134:137]
	ds_read_b128 v[48:51], v130 offset:384
	s_waitcnt lgkmcnt(0)
	v_mfma_f32_16x16x32_bf16 v[138:141], v[48:51], v[8:11], v[138:141]
	ds_read_b128 v[48:51], v131 offset:384
	s_waitcnt lgkmcnt(0)
	v_mfma_f32_16x16x32_bf16 v[142:145], v[48:51], v[8:11], v[142:145]
	ds_read_b128 v[48:51], v132 offset:384
	s_waitcnt lgkmcnt(0)
	v_mfma_f32_16x16x32_bf16 v[162:165], v[48:51], v[8:11], v[12:15]
	ds_read_b128 v[8:11], v109 offset:448
	s_waitcnt vmcnt(16) lgkmcnt(0)
	v_mfma_f32_16x16x32_bf16 v[64:67], v[8:11], v[4:7], v[16:19]
	ds_read_b128 v[8:11], v109 offset:8896
	s_waitcnt lgkmcnt(0)
	v_mfma_f32_16x16x32_bf16 v[60:63], v[8:11], v[4:7], v[20:23]
	ds_read_b128 v[8:11], v109 offset:17344
	s_waitcnt lgkmcnt(0)
	v_mfma_f32_16x16x32_bf16 v[56:59], v[8:11], v[4:7], v[24:27]
	ds_read_b128 v[8:11], v109 offset:25792
	s_waitcnt lgkmcnt(0)
	v_mfma_f32_16x16x32_bf16 v[52:55], v[8:11], v[4:7], v[28:31]
	ds_read_b128 v[8:11], v109 offset:34240
	s_waitcnt lgkmcnt(0)
	v_mfma_f32_16x16x32_bf16 v[48:51], v[8:11], v[4:7], v[32:35]
	ds_read_b128 v[8:11], v109 offset:42688
	s_waitcnt lgkmcnt(0)
	v_mfma_f32_16x16x32_bf16 v[44:47], v[8:11], v[4:7], v[44:47]
	ds_read_b128 v[8:11], v109 offset:51136
	s_waitcnt lgkmcnt(0)
	v_mfma_f32_16x16x32_bf16 v[40:43], v[8:11], v[4:7], v[40:43]
	ds_read_b128 v[8:11], v109 offset:59584
	s_waitcnt lgkmcnt(0)
	v_mfma_f32_16x16x32_bf16 v[36:39], v[8:11], v[4:7], v[36:39]
	ds_read_b128 v[8:11], v125 offset:448
	s_waitcnt lgkmcnt(0)
	v_mfma_f32_16x16x32_bf16 v[32:35], v[8:11], v[4:7], v[146:149]
	ds_read_b128 v[8:11], v126 offset:448
	s_waitcnt lgkmcnt(0)
	v_mfma_f32_16x16x32_bf16 v[28:31], v[8:11], v[4:7], v[150:153]
	ds_read_b128 v[8:11], v127 offset:448
	s_waitcnt lgkmcnt(0)
	v_mfma_f32_16x16x32_bf16 v[24:27], v[8:11], v[4:7], v[154:157]
	ds_read_b128 v[8:11], v128 offset:448
	s_waitcnt lgkmcnt(0)
	v_mfma_f32_16x16x32_bf16 v[20:23], v[8:11], v[4:7], v[158:161]
	ds_read_b128 v[8:11], v129 offset:448
	s_waitcnt lgkmcnt(0)
	v_mfma_f32_16x16x32_bf16 v[16:19], v[8:11], v[4:7], v[134:137]
	ds_read_b128 v[8:11], v130 offset:448
	s_nop 1
	ds_read_b128 v[134:137], v132 offset:448
	s_waitcnt lgkmcnt(1)
	v_mfma_f32_16x16x32_bf16 v[12:15], v[8:11], v[4:7], v[138:141]
	ds_read_b128 v[8:11], v131 offset:448
	s_waitcnt lgkmcnt(0)
	v_mfma_f32_16x16x32_bf16 v[8:11], v[8:11], v[4:7], v[142:145]
	v_mfma_f32_16x16x32_bf16 v[4:7], v[134:137], v[4:7], v[162:165]
	s_and_saveexec_b64 s[12:13], vcc
	s_cbranch_execz .LBB0_331
	s_add_i32 s4, 0, 0x21000
	v_add_u32_e32 v71, s4, v108
	ds_read_b128 v[134:137], v71
	s_waitcnt lgkmcnt(0)
	v_add_f32_e32 v64, v64, v134
	v_add_f32_e32 v65, v65, v135
	v_mul_f32_e32 v64, 0xbfb8aa3b, v64
	v_mul_f32_e32 v65, 0xbfb8aa3b, v65
	v_exp_f32_e32 v64, v64
	v_exp_f32_e32 v65, v65
	s_waitcnt vmcnt(15)
	v_lshlrev_b32_e32 v134, 16, v104
	v_and_b32_e32 v135, 0xffff0000, v104
	v_add_f32_e32 v64, 1.0, v64
	v_add_f32_e32 v65, 1.0, v65
	v_rcp_f32_e32 v64, v64
	v_rcp_f32_e32 v65, v65
	v_lshlrev_b32_e32 v104, 16, v105
	v_and_b32_e32 v105, 0xffff0000, v105
	v_pk_mul_f32 v[64:65], v[64:65], v[134:135]
	s_nop 0
	v_cvt_pk_bf16_f32 v64, v64, v65
	v_add_f32_e32 v65, v66, v136
	v_mul_f32_e32 v65, 0xbfb8aa3b, v65
	v_exp_f32_e32 v65, v65
	s_nop 0
	v_add_f32_e32 v65, 1.0, v65
	v_rcp_f32_e32 v66, v65
	v_add_f32_e32 v65, v67, v137
	v_mul_f32_e32 v65, 0xbfb8aa3b, v65
	v_exp_f32_e32 v65, v65
	s_nop 0
	v_add_f32_e32 v65, 1.0, v65
	v_rcp_f32_e32 v67, v65
	s_nop 0
	v_pk_mul_f32 v[66:67], v[66:67], v[104:105]
	s_nop 0
	v_cvt_pk_bf16_f32 v65, v66, v67
	global_store_dwordx2 v[72:73], v[64:65], off offset:1536 sc1
	v_add_u32_e32 v64, s4, v110
	ds_read_b128 v[64:67], v64
	s_waitcnt lgkmcnt(0)
	v_add_f32_e32 v60, v60, v64
	v_add_f32_e32 v61, v61, v65
	v_mul_f32_e32 v60, 0xbfb8aa3b, v60
	v_mul_f32_e32 v61, 0xbfb8aa3b, v61
	v_exp_f32_e32 v60, v60
	v_exp_f32_e32 v61, v61
	s_waitcnt vmcnt(15)
	v_lshlrev_b32_e32 v64, 16, v102
	v_and_b32_e32 v65, 0xffff0000, v102
	v_add_f32_e32 v60, 1.0, v60
	v_add_f32_e32 v61, 1.0, v61
	v_rcp_f32_e32 v60, v60
	v_rcp_f32_e32 v61, v61
	s_nop 0
	v_pk_mul_f32 v[60:61], v[60:61], v[64:65]
	s_nop 0
	v_cvt_pk_bf16_f32 v60, v60, v61
	v_add_f32_e32 v61, v62, v66
	v_mul_f32_e32 v61, 0xbfb8aa3b, v61
	v_exp_f32_e32 v61, v61
	v_lshlrev_b32_e32 v64, 16, v103
	v_and_b32_e32 v65, 0xffff0000, v103
	v_add_f32_e32 v61, 1.0, v61
	v_rcp_f32_e32 v62, v61
	v_add_f32_e32 v61, v63, v67
	v_mul_f32_e32 v61, 0xbfb8aa3b, v61
	v_exp_f32_e32 v61, v61
	s_nop 0
	v_add_f32_e32 v61, 1.0, v61
	v_rcp_f32_e32 v63, v61
	s_nop 0
	v_pk_mul_f32 v[62:63], v[62:63], v[64:65]
	s_nop 0
	v_cvt_pk_bf16_f32 v61, v62, v63
	global_store_dwordx2 v[72:73], v[60:61], off offset:1568 sc1
	v_add_u32_e32 v60, s4, v111
	ds_read_b128 v[60:63], v60
	s_waitcnt lgkmcnt(0)
	v_add_f32_e32 v56, v56, v60
	v_add_f32_e32 v57, v57, v61
	v_mul_f32_e32 v56, 0xbfb8aa3b, v56
	v_mul_f32_e32 v57, 0xbfb8aa3b, v57
	v_exp_f32_e32 v56, v56
	v_exp_f32_e32 v57, v57
	s_waitcnt vmcnt(15)
	v_lshlrev_b32_e32 v60, 16, v100
	v_and_b32_e32 v61, 0xffff0000, v100
	v_add_f32_e32 v56, 1.0, v56
	v_add_f32_e32 v57, 1.0, v57
	v_rcp_f32_e32 v56, v56
	v_rcp_f32_e32 v57, v57
	s_nop 0
	v_pk_mul_f32 v[56:57], v[56:57], v[60:61]
	s_nop 0
	v_cvt_pk_bf16_f32 v56, v56, v57
	v_add_f32_e32 v57, v58, v62
	v_mul_f32_e32 v57, 0xbfb8aa3b, v57
	v_exp_f32_e32 v57, v57
	v_lshlrev_b32_e32 v60, 16, v101
	v_and_b32_e32 v61, 0xffff0000, v101
	v_add_f32_e32 v57, 1.0, v57
	v_rcp_f32_e32 v58, v57
	v_add_f32_e32 v57, v59, v63
	v_mul_f32_e32 v57, 0xbfb8aa3b, v57
	v_exp_f32_e32 v57, v57
	s_nop 0
	v_add_f32_e32 v57, 1.0, v57
	v_rcp_f32_e32 v59, v57
	s_nop 0
	v_pk_mul_f32 v[58:59], v[58:59], v[60:61]
	s_nop 0
	v_cvt_pk_bf16_f32 v57, v58, v59
	global_store_dwordx2 v[72:73], v[56:57], off offset:1600 sc1
	v_add_u32_e32 v56, s4, v112
	ds_read_b128 v[56:59], v56
	s_waitcnt lgkmcnt(0)
	v_add_f32_e32 v52, v52, v56
	v_add_f32_e32 v53, v53, v57
	v_mul_f32_e32 v52, 0xbfb8aa3b, v52
	v_mul_f32_e32 v53, 0xbfb8aa3b, v53
	v_exp_f32_e32 v52, v52
	v_exp_f32_e32 v53, v53
	s_waitcnt vmcnt(15)
	v_lshlrev_b32_e32 v56, 16, v98
	v_and_b32_e32 v57, 0xffff0000, v98
	v_add_f32_e32 v52, 1.0, v52
	v_add_f32_e32 v53, 1.0, v53
	v_rcp_f32_e32 v52, v52
	v_rcp_f32_e32 v53, v53
	s_nop 0
	v_pk_mul_f32 v[52:53], v[52:53], v[56:57]
	s_nop 0
	v_cvt_pk_bf16_f32 v52, v52, v53
	v_add_f32_e32 v53, v54, v58
	v_mul_f32_e32 v53, 0xbfb8aa3b, v53
	v_exp_f32_e32 v53, v53
	v_lshlrev_b32_e32 v56, 16, v99
	v_and_b32_e32 v57, 0xffff0000, v99
	v_add_f32_e32 v53, 1.0, v53
	v_rcp_f32_e32 v54, v53
	v_add_f32_e32 v53, v55, v59
	v_mul_f32_e32 v53, 0xbfb8aa3b, v53
	v_exp_f32_e32 v53, v53
	s_nop 0
	v_add_f32_e32 v53, 1.0, v53
	v_rcp_f32_e32 v55, v53
	s_nop 0
	v_pk_mul_f32 v[54:55], v[54:55], v[56:57]
	s_nop 0
	v_cvt_pk_bf16_f32 v53, v54, v55
	global_store_dwordx2 v[72:73], v[52:53], off offset:1632 sc1
	v_add_u32_e32 v52, s4, v113
	ds_read_b128 v[52:55], v52
	s_waitcnt lgkmcnt(0)
	v_add_f32_e32 v48, v48, v52
	v_add_f32_e32 v49, v49, v53
	v_mul_f32_e32 v48, 0xbfb8aa3b, v48
	v_mul_f32_e32 v49, 0xbfb8aa3b, v49
	v_exp_f32_e32 v48, v48
	v_exp_f32_e32 v49, v49
	s_waitcnt vmcnt(15)
	v_lshlrev_b32_e32 v52, 16, v96
	v_and_b32_e32 v53, 0xffff0000, v96
	v_add_f32_e32 v48, 1.0, v48
	v_add_f32_e32 v49, 1.0, v49
	v_rcp_f32_e32 v48, v48
	v_rcp_f32_e32 v49, v49
	s_nop 0
	v_pk_mul_f32 v[48:49], v[48:49], v[52:53]
	s_nop 0
	v_cvt_pk_bf16_f32 v48, v48, v49
	v_add_f32_e32 v49, v50, v54
	v_mul_f32_e32 v49, 0xbfb8aa3b, v49
	v_exp_f32_e32 v49, v49
	v_lshlrev_b32_e32 v52, 16, v97
	v_and_b32_e32 v53, 0xffff0000, v97
	v_add_f32_e32 v49, 1.0, v49
	v_rcp_f32_e32 v50, v49
	v_add_f32_e32 v49, v51, v55
	v_mul_f32_e32 v49, 0xbfb8aa3b, v49
	v_exp_f32_e32 v49, v49
	s_nop 0
	v_add_f32_e32 v49, 1.0, v49
	v_rcp_f32_e32 v51, v49
	s_nop 0
	v_pk_mul_f32 v[50:51], v[50:51], v[52:53]
	s_nop 0
	v_cvt_pk_bf16_f32 v49, v50, v51
	global_store_dwordx2 v[72:73], v[48:49], off offset:1664 sc1
	v_add_u32_e32 v48, s4, v114
	ds_read_b128 v[48:51], v48
	s_waitcnt lgkmcnt(0)
	v_add_f32_e32 v44, v44, v48
	v_add_f32_e32 v45, v45, v49
	v_mul_f32_e32 v44, 0xbfb8aa3b, v44
	v_mul_f32_e32 v45, 0xbfb8aa3b, v45
	v_exp_f32_e32 v44, v44
	v_exp_f32_e32 v45, v45
	s_waitcnt vmcnt(15)
	v_lshlrev_b32_e32 v48, 16, v94
	v_and_b32_e32 v49, 0xffff0000, v94
	v_add_f32_e32 v44, 1.0, v44
	v_add_f32_e32 v45, 1.0, v45
	v_rcp_f32_e32 v44, v44
	v_rcp_f32_e32 v45, v45
	s_nop 0
	v_pk_mul_f32 v[44:45], v[44:45], v[48:49]
	s_nop 0
	v_cvt_pk_bf16_f32 v44, v44, v45
	v_add_f32_e32 v45, v46, v50
	v_mul_f32_e32 v45, 0xbfb8aa3b, v45
	v_exp_f32_e32 v45, v45
	v_lshlrev_b32_e32 v48, 16, v95
	v_and_b32_e32 v49, 0xffff0000, v95
	v_add_f32_e32 v45, 1.0, v45
	v_rcp_f32_e32 v46, v45
	v_add_f32_e32 v45, v47, v51
	v_mul_f32_e32 v45, 0xbfb8aa3b, v45
	v_exp_f32_e32 v45, v45
	s_nop 0
	v_add_f32_e32 v45, 1.0, v45
	v_rcp_f32_e32 v47, v45
	s_nop 0
	v_pk_mul_f32 v[46:47], v[46:47], v[48:49]
	s_nop 0
	v_cvt_pk_bf16_f32 v45, v46, v47
	global_store_dwordx2 v[72:73], v[44:45], off offset:1696 sc1
	v_add_u32_e32 v44, s4, v115
	ds_read_b128 v[44:47], v44
	s_waitcnt lgkmcnt(0)
	v_add_f32_e32 v40, v40, v44
	v_add_f32_e32 v41, v41, v45
	v_mul_f32_e32 v40, 0xbfb8aa3b, v40
	v_mul_f32_e32 v41, 0xbfb8aa3b, v41
	v_exp_f32_e32 v40, v40
	v_exp_f32_e32 v41, v41
	s_waitcnt vmcnt(15)
	v_lshlrev_b32_e32 v44, 16, v92
	v_and_b32_e32 v45, 0xffff0000, v92
	v_add_f32_e32 v40, 1.0, v40
	v_add_f32_e32 v41, 1.0, v41
	v_rcp_f32_e32 v40, v40
	v_rcp_f32_e32 v41, v41
	s_nop 0
	v_pk_mul_f32 v[40:41], v[40:41], v[44:45]
	s_nop 0
	v_cvt_pk_bf16_f32 v40, v40, v41
	v_add_f32_e32 v41, v42, v46
	v_mul_f32_e32 v41, 0xbfb8aa3b, v41
	v_exp_f32_e32 v41, v41
	v_lshlrev_b32_e32 v44, 16, v93
	v_and_b32_e32 v45, 0xffff0000, v93
	v_add_f32_e32 v41, 1.0, v41
	v_rcp_f32_e32 v42, v41
	v_add_f32_e32 v41, v43, v47
	v_mul_f32_e32 v41, 0xbfb8aa3b, v41
	v_exp_f32_e32 v41, v41
	s_nop 0
	v_add_f32_e32 v41, 1.0, v41
	v_rcp_f32_e32 v43, v41
	s_nop 0
	v_pk_mul_f32 v[42:43], v[42:43], v[44:45]
	s_nop 0
	v_cvt_pk_bf16_f32 v41, v42, v43
	global_store_dwordx2 v[72:73], v[40:41], off offset:1728 sc1
	v_add_u32_e32 v40, s4, v116
	ds_read_b128 v[40:43], v40
	s_waitcnt lgkmcnt(0)
	v_add_f32_e32 v36, v36, v40
	v_add_f32_e32 v37, v37, v41
	v_mul_f32_e32 v36, 0xbfb8aa3b, v36
	v_mul_f32_e32 v37, 0xbfb8aa3b, v37
	v_exp_f32_e32 v36, v36
	v_exp_f32_e32 v37, v37
	s_waitcnt vmcnt(15)
	v_lshlrev_b32_e32 v40, 16, v90
	v_and_b32_e32 v41, 0xffff0000, v90
	v_add_f32_e32 v36, 1.0, v36
	v_add_f32_e32 v37, 1.0, v37
	v_rcp_f32_e32 v36, v36
	v_rcp_f32_e32 v37, v37
	s_nop 0
	v_pk_mul_f32 v[36:37], v[36:37], v[40:41]
	s_nop 0
	v_cvt_pk_bf16_f32 v36, v36, v37
	v_add_f32_e32 v37, v38, v42
	v_mul_f32_e32 v37, 0xbfb8aa3b, v37
	v_exp_f32_e32 v37, v37
	v_lshlrev_b32_e32 v40, 16, v91
	v_and_b32_e32 v41, 0xffff0000, v91
	v_add_f32_e32 v37, 1.0, v37
	v_rcp_f32_e32 v38, v37
	v_add_f32_e32 v37, v39, v43
	v_mul_f32_e32 v37, 0xbfb8aa3b, v37
	v_exp_f32_e32 v37, v37
	s_nop 0
	v_add_f32_e32 v37, 1.0, v37
	v_rcp_f32_e32 v39, v37
	s_nop 0
	v_pk_mul_f32 v[38:39], v[38:39], v[40:41]
	s_nop 0
	v_cvt_pk_bf16_f32 v37, v38, v39
	global_store_dwordx2 v[72:73], v[36:37], off offset:1760 sc1
	v_add_u32_e32 v36, s4, v117
	ds_read_b128 v[36:39], v36
	s_waitcnt lgkmcnt(0)
	v_add_f32_e32 v32, v32, v36
	v_add_f32_e32 v33, v33, v37
	v_mul_f32_e32 v32, 0xbfb8aa3b, v32
	v_mul_f32_e32 v33, 0xbfb8aa3b, v33
	v_exp_f32_e32 v32, v32
	v_exp_f32_e32 v33, v33
	s_waitcnt vmcnt(15)
	v_lshlrev_b32_e32 v36, 16, v88
	v_and_b32_e32 v37, 0xffff0000, v88
	v_add_f32_e32 v32, 1.0, v32
	v_add_f32_e32 v33, 1.0, v33
	v_rcp_f32_e32 v32, v32
	v_rcp_f32_e32 v33, v33
	s_nop 0
	v_pk_mul_f32 v[32:33], v[32:33], v[36:37]
	s_nop 0
	v_cvt_pk_bf16_f32 v32, v32, v33
	v_add_f32_e32 v33, v34, v38
	v_mul_f32_e32 v33, 0xbfb8aa3b, v33
	v_exp_f32_e32 v33, v33
	v_lshlrev_b32_e32 v36, 16, v89
	v_and_b32_e32 v37, 0xffff0000, v89
	v_add_f32_e32 v33, 1.0, v33
	v_rcp_f32_e32 v34, v33
	v_add_f32_e32 v33, v35, v39
	v_mul_f32_e32 v33, 0xbfb8aa3b, v33
	v_exp_f32_e32 v33, v33
	s_nop 0
	v_add_f32_e32 v33, 1.0, v33
	v_rcp_f32_e32 v35, v33
	s_nop 0
	v_pk_mul_f32 v[34:35], v[34:35], v[36:37]
	s_nop 0
	v_cvt_pk_bf16_f32 v33, v34, v35
	global_store_dwordx2 v[72:73], v[32:33], off offset:1792 sc1
	v_add_u32_e32 v32, s4, v118
	ds_read_b128 v[32:35], v32
	s_waitcnt lgkmcnt(0)
	v_add_f32_e32 v28, v28, v32
	v_add_f32_e32 v29, v29, v33
	v_mul_f32_e32 v28, 0xbfb8aa3b, v28
	v_mul_f32_e32 v29, 0xbfb8aa3b, v29
	v_exp_f32_e32 v28, v28
	v_exp_f32_e32 v29, v29
	s_waitcnt vmcnt(15)
	v_lshlrev_b32_e32 v32, 16, v86
	v_and_b32_e32 v33, 0xffff0000, v86
	v_add_f32_e32 v28, 1.0, v28
	v_add_f32_e32 v29, 1.0, v29
	v_rcp_f32_e32 v28, v28
	v_rcp_f32_e32 v29, v29
	s_nop 0
	v_pk_mul_f32 v[28:29], v[28:29], v[32:33]
	s_nop 0
	v_cvt_pk_bf16_f32 v28, v28, v29
	v_add_f32_e32 v29, v30, v34
	v_mul_f32_e32 v29, 0xbfb8aa3b, v29
	v_exp_f32_e32 v29, v29
	v_lshlrev_b32_e32 v32, 16, v87
	v_and_b32_e32 v33, 0xffff0000, v87
	v_add_f32_e32 v29, 1.0, v29
	v_rcp_f32_e32 v30, v29
	v_add_f32_e32 v29, v31, v35
	v_mul_f32_e32 v29, 0xbfb8aa3b, v29
	v_exp_f32_e32 v29, v29
	s_nop 0
	v_add_f32_e32 v29, 1.0, v29
	v_rcp_f32_e32 v31, v29
	s_nop 0
	v_pk_mul_f32 v[30:31], v[30:31], v[32:33]
	s_nop 0
	v_cvt_pk_bf16_f32 v29, v30, v31
	global_store_dwordx2 v[72:73], v[28:29], off offset:1824 sc1
	v_add_u32_e32 v28, s4, v119
	ds_read_b128 v[28:31], v28
	s_waitcnt lgkmcnt(0)
	v_add_f32_e32 v24, v24, v28
	v_add_f32_e32 v25, v25, v29
	v_mul_f32_e32 v24, 0xbfb8aa3b, v24
	v_mul_f32_e32 v25, 0xbfb8aa3b, v25
	v_exp_f32_e32 v24, v24
	v_exp_f32_e32 v25, v25
	s_waitcnt vmcnt(15)
	v_lshlrev_b32_e32 v28, 16, v84
	v_and_b32_e32 v29, 0xffff0000, v84
	v_add_f32_e32 v24, 1.0, v24
	v_add_f32_e32 v25, 1.0, v25
	v_rcp_f32_e32 v24, v24
	v_rcp_f32_e32 v25, v25
	s_nop 0
	v_pk_mul_f32 v[24:25], v[24:25], v[28:29]
	s_nop 0
	v_cvt_pk_bf16_f32 v24, v24, v25
	v_add_f32_e32 v25, v26, v30
	v_mul_f32_e32 v25, 0xbfb8aa3b, v25
	v_exp_f32_e32 v25, v25
	v_lshlrev_b32_e32 v28, 16, v85
	v_and_b32_e32 v29, 0xffff0000, v85
	v_add_f32_e32 v25, 1.0, v25
	v_rcp_f32_e32 v26, v25
	v_add_f32_e32 v25, v27, v31
	v_mul_f32_e32 v25, 0xbfb8aa3b, v25
	v_exp_f32_e32 v25, v25
	s_nop 0
	v_add_f32_e32 v25, 1.0, v25
	v_rcp_f32_e32 v27, v25
	s_nop 0
	v_pk_mul_f32 v[26:27], v[26:27], v[28:29]
	s_nop 0
	v_cvt_pk_bf16_f32 v25, v26, v27
	global_store_dwordx2 v[72:73], v[24:25], off offset:1856 sc1
	v_add_u32_e32 v24, s4, v120
	ds_read_b128 v[24:27], v24
	s_waitcnt lgkmcnt(0)
	v_add_f32_e32 v20, v20, v24
	v_add_f32_e32 v21, v21, v25
	v_mul_f32_e32 v20, 0xbfb8aa3b, v20
	v_mul_f32_e32 v21, 0xbfb8aa3b, v21
	v_exp_f32_e32 v20, v20
	v_exp_f32_e32 v21, v21
	s_waitcnt vmcnt(15)
	v_lshlrev_b32_e32 v24, 16, v82
	v_and_b32_e32 v25, 0xffff0000, v82
	v_add_f32_e32 v20, 1.0, v20
	v_add_f32_e32 v21, 1.0, v21
	v_rcp_f32_e32 v20, v20
	v_rcp_f32_e32 v21, v21
	s_nop 0
	v_pk_mul_f32 v[20:21], v[20:21], v[24:25]
	s_nop 0
	v_cvt_pk_bf16_f32 v20, v20, v21
	v_add_f32_e32 v21, v22, v26
	v_mul_f32_e32 v21, 0xbfb8aa3b, v21
	v_exp_f32_e32 v21, v21
	v_lshlrev_b32_e32 v24, 16, v83
	v_and_b32_e32 v25, 0xffff0000, v83
	v_add_f32_e32 v21, 1.0, v21
	v_rcp_f32_e32 v22, v21
	v_add_f32_e32 v21, v23, v27
	v_mul_f32_e32 v21, 0xbfb8aa3b, v21
	v_exp_f32_e32 v21, v21
	s_nop 0
	v_add_f32_e32 v21, 1.0, v21
	v_rcp_f32_e32 v23, v21
	s_nop 0
	v_pk_mul_f32 v[22:23], v[22:23], v[24:25]
	s_nop 0
	v_cvt_pk_bf16_f32 v21, v22, v23
	global_store_dwordx2 v[72:73], v[20:21], off offset:1888 sc1
	v_add_u32_e32 v20, s4, v121
	ds_read_b128 v[20:23], v20
	s_waitcnt lgkmcnt(0)
	v_add_f32_e32 v16, v16, v20
	v_add_f32_e32 v17, v17, v21
	v_mul_f32_e32 v16, 0xbfb8aa3b, v16
	v_mul_f32_e32 v17, 0xbfb8aa3b, v17
	v_exp_f32_e32 v16, v16
	v_exp_f32_e32 v17, v17
	s_waitcnt vmcnt(15)
	v_lshlrev_b32_e32 v20, 16, v80
	v_and_b32_e32 v21, 0xffff0000, v80
	v_add_f32_e32 v16, 1.0, v16
	v_add_f32_e32 v17, 1.0, v17
	v_rcp_f32_e32 v16, v16
	v_rcp_f32_e32 v17, v17
	s_nop 0
	v_pk_mul_f32 v[16:17], v[16:17], v[20:21]
	s_nop 0
	v_cvt_pk_bf16_f32 v16, v16, v17
	v_add_f32_e32 v17, v18, v22
	v_mul_f32_e32 v17, 0xbfb8aa3b, v17
	v_exp_f32_e32 v17, v17
	v_lshlrev_b32_e32 v20, 16, v81
	v_and_b32_e32 v21, 0xffff0000, v81
	v_add_f32_e32 v17, 1.0, v17
	v_rcp_f32_e32 v18, v17
	v_add_f32_e32 v17, v19, v23
	v_mul_f32_e32 v17, 0xbfb8aa3b, v17
	v_exp_f32_e32 v17, v17
	s_nop 0
	v_add_f32_e32 v17, 1.0, v17
	v_rcp_f32_e32 v19, v17
	s_nop 0
	v_pk_mul_f32 v[18:19], v[18:19], v[20:21]
	s_nop 0
	v_cvt_pk_bf16_f32 v17, v18, v19
	global_store_dwordx2 v[72:73], v[16:17], off offset:1920 sc1
	v_add_u32_e32 v16, s4, v122
	ds_read_b128 v[16:19], v16
	s_waitcnt lgkmcnt(0)
	v_add_f32_e32 v12, v12, v16
	v_add_f32_e32 v13, v13, v17
	v_mul_f32_e32 v12, 0xbfb8aa3b, v12
	v_mul_f32_e32 v13, 0xbfb8aa3b, v13
	v_exp_f32_e32 v12, v12
	v_exp_f32_e32 v13, v13
	s_waitcnt vmcnt(15)
	v_lshlrev_b32_e32 v16, 16, v78
	v_and_b32_e32 v17, 0xffff0000, v78
	v_add_f32_e32 v12, 1.0, v12
	v_add_f32_e32 v13, 1.0, v13
	v_rcp_f32_e32 v12, v12
	v_rcp_f32_e32 v13, v13
	s_nop 0
	v_pk_mul_f32 v[12:13], v[12:13], v[16:17]
	s_nop 0
	v_cvt_pk_bf16_f32 v12, v12, v13
	v_add_f32_e32 v13, v14, v18
	v_mul_f32_e32 v13, 0xbfb8aa3b, v13
	v_exp_f32_e32 v13, v13
	v_lshlrev_b32_e32 v16, 16, v79
	v_and_b32_e32 v17, 0xffff0000, v79
	v_add_f32_e32 v13, 1.0, v13
	v_rcp_f32_e32 v14, v13
	v_add_f32_e32 v13, v15, v19
	v_mul_f32_e32 v13, 0xbfb8aa3b, v13
	v_exp_f32_e32 v13, v13
	s_nop 0
	v_add_f32_e32 v13, 1.0, v13
	v_rcp_f32_e32 v15, v13
	s_nop 0
	v_pk_mul_f32 v[14:15], v[14:15], v[16:17]
	s_nop 0
	v_cvt_pk_bf16_f32 v13, v14, v15
	global_store_dwordx2 v[72:73], v[12:13], off offset:1952 sc1
	v_add_u32_e32 v12, s4, v123
	ds_read_b128 v[12:15], v12
	s_waitcnt lgkmcnt(0)
	v_add_f32_e32 v8, v8, v12
	v_add_f32_e32 v9, v9, v13
	v_mul_f32_e32 v8, 0xbfb8aa3b, v8
	v_mul_f32_e32 v9, 0xbfb8aa3b, v9
	v_exp_f32_e32 v8, v8
	v_exp_f32_e32 v9, v9
	s_waitcnt vmcnt(15)
	v_lshlrev_b32_e32 v12, 16, v76
	v_and_b32_e32 v13, 0xffff0000, v76
	v_add_f32_e32 v8, 1.0, v8
	v_add_f32_e32 v9, 1.0, v9
	v_rcp_f32_e32 v8, v8
	v_rcp_f32_e32 v9, v9
	s_nop 0
	v_pk_mul_f32 v[8:9], v[8:9], v[12:13]
	s_nop 0
	v_cvt_pk_bf16_f32 v8, v8, v9
	v_add_f32_e32 v9, v10, v14
	v_mul_f32_e32 v9, 0xbfb8aa3b, v9
	v_exp_f32_e32 v9, v9
	v_lshlrev_b32_e32 v12, 16, v77
	v_and_b32_e32 v13, 0xffff0000, v77
	v_add_f32_e32 v9, 1.0, v9
	v_rcp_f32_e32 v10, v9
	v_add_f32_e32 v9, v11, v15
	v_mul_f32_e32 v9, 0xbfb8aa3b, v9
	v_exp_f32_e32 v9, v9
	s_nop 0
	v_add_f32_e32 v9, 1.0, v9
	v_rcp_f32_e32 v11, v9
	s_nop 0
	v_pk_mul_f32 v[10:11], v[10:11], v[12:13]
	s_nop 0
	v_cvt_pk_bf16_f32 v9, v10, v11
	global_store_dwordx2 v[72:73], v[8:9], off offset:1984 sc1
	v_add_u32_e32 v8, s4, v124
	ds_read_b128 v[8:11], v8
	s_waitcnt lgkmcnt(0)
	v_add_f32_e32 v4, v4, v8
	v_add_f32_e32 v5, v5, v9
	v_mul_f32_e32 v4, 0xbfb8aa3b, v4
	v_mul_f32_e32 v5, 0xbfb8aa3b, v5
	v_exp_f32_e32 v4, v4
	v_exp_f32_e32 v5, v5
	s_waitcnt vmcnt(15)
	v_lshlrev_b32_e32 v8, 16, v74
	v_and_b32_e32 v9, 0xffff0000, v74
	v_add_f32_e32 v4, 1.0, v4
	v_add_f32_e32 v5, 1.0, v5
	v_rcp_f32_e32 v4, v4
	v_rcp_f32_e32 v5, v5
	s_nop 0
	v_pk_mul_f32 v[4:5], v[4:5], v[8:9]
	s_nop 0
	v_cvt_pk_bf16_f32 v4, v4, v5
	v_add_f32_e32 v5, v6, v10
	v_mul_f32_e32 v5, 0xbfb8aa3b, v5
	v_exp_f32_e32 v5, v5
	v_lshlrev_b32_e32 v8, 16, v75
	v_and_b32_e32 v9, 0xffff0000, v75
	v_add_f32_e32 v5, 1.0, v5
	v_rcp_f32_e32 v6, v5
	v_add_f32_e32 v5, v7, v11
	v_mul_f32_e32 v5, 0xbfb8aa3b, v5
	v_exp_f32_e32 v5, v5
	s_nop 0
	v_add_f32_e32 v5, 1.0, v5
	v_rcp_f32_e32 v7, v5
	s_nop 0
	v_pk_mul_f32 v[6:7], v[6:7], v[8:9]
	s_nop 0
	v_cvt_pk_bf16_f32 v5, v6, v7
	global_store_dwordx2 v[72:73], v[4:5], off offset:2016 sc1
	s_branch .LBB0_331

.LBB0_388:
	v_add_u32_e32 v60, s14, v74
	v_lshl_or_b32 v180, v60, 10, v58
	s_nop 2
	v_cvt_pk_bf16_f32 v52, v52, v53
	v_cvt_pk_bf16_f32 v53, v54, v55
	v_lshl_add_u64 v[54:55], v[180:181], 1, s[10:11]
	global_store_dwordx2 v[54:55], v[52:53], off offset:1536 sc1

.LBB0_417:
	v_mul_u32_u24_e32 v98, 0x90, v36
	v_add_u32_e32 v41, s4, v98
	v_lshrrev_b32_e32 v36, 1, v68
	v_readlane_b32 s4, v255, 2
	v_and_or_b32 v99, v36, 24, v37
	s_add_i32 s43, s34, 0
	v_mov_b32_e32 v36, s4
	s_waitcnt lgkmcnt(0)
	s_barrier
	ds_read_b32 v42, v36
	ds_read_b128 v[88:91], v77 offset:9216
	v_mov_b32_e32 v36, s43
	v_mad_u32_u24 v43, v99, s61, v36
	ds_read_b128 v[36:39], v62 offset:64512
	v_add_u32_e32 v84, v43, v50
	ds_read_b64_tr_b16 v[92:93], v84 offset:36864
	ds_read_b64_tr_b16 v[94:95], v84 offset:37440
	ds_read_b128 v[100:103], v78 offset:9216
	v_add_u32_e32 v83, v41, v47
	s_waitcnt lgkmcnt(5)
	v_mul_f32_e32 v41, 0x3fb8aa3b, v42
	v_exp_f32_e32 v41, v41
	s_waitcnt lgkmcnt(3)
	v_mfma_f32_16x16x32_bf16 v[88:91], v[36:39], v[88:91], 0
	ds_read_b128 v[104:107], v62 offset:64576
	ds_read_b128 v[108:111], v77 offset:64512
	v_mul_f32_e32 v112, 0, v41
	v_mov_b32_e32 v113, v112
	s_waitcnt lgkmcnt(2)
	v_mfma_f32_16x16x32_bf16 v[36:39], v[36:39], v[100:103], 0
	ds_read_b128 v[100:103], v78 offset:64512
	v_mov_b32_e32 v114, v112
	v_mov_b32_e32 v115, v112
	ds_read_b128 v[116:119], v83
	ds_read_b64_tr_b16 v[120:121], v84 offset:41472
	ds_read_b128 v[124:127], v77 offset:9280
	s_waitcnt lgkmcnt(4)
	v_mfma_f32_16x16x32_bf16 v[108:111], v[92:95], v[108:111], v[112:115]
	v_mul_lo_u32 v85, v40, s39
	s_add_i32 s44, 0, 0x14400
	s_and_b64 s[4:5], s[26:27], exec
	s_waitcnt lgkmcnt(3)
	v_mfma_f32_16x16x32_bf16 v[100:103], v[92:95], v[100:103], v[112:115]
	ds_read_b64_tr_b16 v[122:123], v84 offset:42048
	ds_read_b128 v[92:95], v78 offset:9280
	s_nop 0
	ds_read_b128 v[112:115], v77 offset:64576
	ds_read_b128 v[128:131], v78 offset:64576
	ds_read_b128 v[132:135], v83 offset:64
	s_cselect_b32 s4, 0xc0, 63
	s_waitcnt lgkmcnt(5)
	v_mfma_f32_16x16x32_bf16 v[124:127], v[104:107], v[124:127], v[88:91]
	s_or_b32 s45, s4, s38
	s_add_i32 s35, s25, 0x900
	s_and_b64 s[4:5], s[26:27], exec
	s_waitcnt lgkmcnt(3)
	v_mfma_f32_16x16x32_bf16 v[104:107], v[104:107], v[92:95], v[36:39]
	v_add_u32_e32 v91, s44, v49
	v_add_u32_e32 v87, s34, v91
	v_add_u32_e32 v93, s44, v48
	s_waitcnt lgkmcnt(2)
	v_mfma_f32_16x16x32_bf16 v[36:39], v[120:123], v[112:115], v[108:111]
	v_add_u32_e32 v87, v87, v46
	v_add_u32_e32 v90, s34, v93
	s_cselect_b32 s4, s92, 0x1b485000
	ds_read_b128 v[108:111], v77 offset:27648
	s_waitcnt lgkmcnt(2)
	v_mfma_f32_16x16x32_bf16 v[40:43], v[120:123], v[128:131], v[100:103]
	s_nop 2
	ds_read_b128 v[100:103], v77 offset:27712
	ds_read_b128 v[112:115], v78 offset:27648
	ds_read_b128 v[120:123], v78 offset:27712
	v_cvt_pk_bf16_f32 v88, v36, v37
	s_waitcnt lgkmcnt(3)
	v_mfma_f32_16x16x32_bf16 v[108:111], v[116:119], v[108:111], v[124:127]
	v_cvt_pk_bf16_f32 v89, v38, v39
	ds_write_b64 v87, v[88:89]
	v_add_u32_e32 v89, s24, v85
	s_waitcnt lgkmcnt(3)
	v_mfma_f32_16x16x32_bf16 v[100:103], v[132:135], v[100:103], v[108:111]
	v_cvt_pk_bf16_f32 v94, v40, v41
	v_cvt_pk_bf16_f32 v95, v42, v43
	v_add_u32_e32 v88, v90, v46
	s_waitcnt lgkmcnt(2)
	v_mfma_f32_16x16x32_bf16 v[104:107], v[116:119], v[112:115], v[104:107]
	v_lshl_or_b32 v89, v89, 10, s33
	v_mul_lo_u32 v86, v86, s39
	s_add_u32 s28, s78, s4
	ds_write_b64 v88, v[94:95]
	v_cvt_pk_bf16_f32 v94, v100, v101
	v_add_u32_e32 v100, s37, v89
	v_mov_b32_e32 v101, v181
	s_addc_u32 s29, s79, 0
	s_waitcnt lgkmcnt(2)
	v_mfma_f32_16x16x32_bf16 v[104:107], v[132:135], v[120:123], v[104:107]
	v_lshl_add_u64 v[100:101], v[100:101], 0, v[180:181]
	v_add_u32_e32 v89, s24, v86
	v_cvt_pk_bf16_f32 v95, v102, v103
	v_lshl_add_u64 v[100:101], v[100:101], 1, s[28:29]
	v_lshl_or_b32 v89, v89, 10, s33
	global_store_dwordx2 v[100:101], v[94:95], off offset:1024 sc1
	v_add_u32_e32 v100, s37, v89
	v_mov_b32_e32 v101, v181
	v_lshl_add_u64 v[100:101], v[100:101], 0, v[180:181]
	v_cvt_pk_bf16_f32 v94, v104, v105
	v_cvt_pk_bf16_f32 v95, v106, v107
	v_lshl_add_u64 v[100:101], v[100:101], 1, s[28:29]
	v_mov_b32_e32 v89, v68
	global_store_dwordx2 v[100:101], v[94:95], off offset:1024 sc1
	s_waitcnt vmcnt(7)
	v_lshlrev_b32_e32 v94, 16, v4
	v_ashrrev_i32_e32 v90, 3, v89
	v_lshlrev_b32_e32 v89, 4, v89
	v_mul_lo_u32 v92, v90, s61
	v_and_b32_e32 v89, 0x70, v89
	v_add3_u32 v97, 0, v92, v89
	ds_write_b128 v97, v[16:19]
	v_lshl_add_u32 v16, v90, 2, 0
	v_add_u32_e32 v16, 0x1fa00, v16
	ds_read_b32 v112, v16
	v_and_b32_e32 v95, 0xffff0000, v4
	v_and_b32_e32 v17, 0xffff0000, v12
	v_lshlrev_b32_e32 v104, 16, v5
	v_and_b32_e32 v105, 0xffff0000, v5
	s_waitcnt lgkmcnt(0)
	v_mul_f32_e32 v16, 0x3fb8aa3b, v112
	v_exp_f32_e32 v90, v16
	v_lshlrev_b32_e32 v16, 16, v12
	v_lshlrev_b32_e32 v108, 16, v15
	v_and_b32_e32 v109, 0xffff0000, v15
	v_pk_mul_f32 v[18:19], v[90:91], v[94:95] op_sel_hi:[0,1]
	v_cvt_pk_bf16_f32 v100, v18, v19
	v_lshlrev_b32_e32 v18, 16, v13
	v_and_b32_e32 v19, 0xffff0000, v13
	v_pk_mul_f32 v[16:17], v[90:91], v[16:17] op_sel_hi:[0,1]
	v_pk_mul_f32 v[18:19], v[90:91], v[18:19] op_sel_hi:[0,1]
	v_cvt_pk_bf16_f32 v16, v16, v17
	v_cvt_pk_bf16_f32 v17, v18, v19
	v_pk_mul_f32 v[18:19], v[90:91], v[104:105] op_sel_hi:[0,1]
	v_cvt_pk_bf16_f32 v101, v18, v19
	v_lshlrev_b32_e32 v18, 16, v14
	v_and_b32_e32 v19, 0xffff0000, v14
	v_pk_mul_f32 v[18:19], v[90:91], v[18:19] op_sel_hi:[0,1]
	v_pk_mul_f32 v[108:109], v[90:91], v[108:109] op_sel_hi:[0,1]
	v_cvt_pk_bf16_f32 v18, v18, v19
	v_lshlrev_b32_e32 v106, 16, v6
	v_and_b32_e32 v107, 0xffff0000, v6
	v_cvt_pk_bf16_f32 v19, v108, v109
	v_lshlrev_b32_e32 v108, 16, v7
	v_and_b32_e32 v109, 0xffff0000, v7
	v_readlane_b32 s4, v255, 4
	v_pk_mul_f32 v[102:103], v[90:91], v[106:107] op_sel_hi:[0,1]
	v_pk_mul_f32 v[110:111], v[90:91], v[108:109] op_sel_hi:[0,1]
	v_add3_u32 v90, s4, v92, v89
	v_cvt_pk_bf16_f32 v102, v102, v103
	v_cvt_pk_bf16_f32 v103, v110, v111
	ds_write_b128 v90, v[16:19]
	ds_write_b128 v97, v[100:103] offset:18432
	v_add3_u32 v16, s40, v92, v89
	ds_write_b128 v16, v[12:15]
	v_add3_u32 v12, s41, v92, v89
	ds_write_b128 v12, v[4:7]
	s_waitcnt vmcnt(6)
	ds_write_b128 v97, v[8:11] offset:46080
	v_mov_b32_e32 v4, s72
	ds_read_b32 v4, v4
	v_readlane_b32 s4, v255, 6
	s_waitcnt lgkmcnt(0)
	v_sub_f32_e32 v4, v4, v112
	v_mul_f32_e32 v4, 0x3fb8aa3b, v4
	v_exp_f32_e32 v8, v4
	s_nop 0
	v_pk_mul_f32 v[4:5], v[8:9], v[94:95] op_sel_hi:[0,1]
	v_pk_mul_f32 v[6:7], v[8:9], v[104:105] op_sel_hi:[0,1]
	v_cvt_pk_bf16_f32 v4, v4, v5
	v_cvt_pk_bf16_f32 v5, v6, v7
	v_pk_mul_f32 v[6:7], v[8:9], v[106:107] op_sel_hi:[0,1]
	v_pk_mul_f32 v[8:9], v[8:9], v[108:109] op_sel_hi:[0,1]
	v_cvt_pk_bf16_f32 v6, v6, v7
	v_cvt_pk_bf16_f32 v7, v8, v9
	v_add3_u32 v8, s4, v92, v89
	ds_write_b128 v8, v[4:7]
	v_mov_b32_e32 v4, v68
	s_and_b64 s[4:5], s[26:27], exec
	s_waitcnt lgkmcnt(0)
	s_barrier
	s_cselect_b32 s4, 0xc0, 0
	v_ashrrev_i32_e32 v6, 3, v4
	s_or_b32 s24, s4, s38
	v_lshlrev_b32_e32 v4, 3, v4
	v_add_u32_e32 v5, s24, v6
	v_and_b32_e32 v7, 56, v4
	v_mul_lo_u32 v6, v6, s39
	v_or_b32_e32 v4, s35, v7
	v_add_u32_e32 v6, s45, v6
	v_or_b32_e32 v4, s0, v4
	v_mul_u32_u24_e32 v6, 0x300, v6
	v_mad_u32_u24 v4, v5, s63, v4
	v_or3_b32 v6, v6, s37, v7
	v_ashrrev_i32_e32 v5, 31, v4
	v_ashrrev_i32_e32 v7, 31, v6
	v_lshl_add_u64 v[4:5], v[4:5], 1, s[82:83]
	v_lshl_add_u64 v[16:17], v[6:7], 1, s[84:85]
	global_load_dwordx4 v[4:7], v[4:5], off
	s_nop 0
	global_load_dwordx4 v[8:11], v[16:17], off
	global_load_dwordx4 v[12:15], v[16:17], off offset:512
	s_nop 0
	global_load_dwordx4 v[16:19], v[16:17], off offset:1024
	v_or_b32_e32 v89, 8, v59
	s_and_saveexec_b64 s[4:5], s[6:7]
	s_cbranch_execz .LBB0_419
	v_add_u32_e32 v55, s24, v68
	v_lshl_add_u32 v94, v55, 4, v59
	v_mov_b32_e32 v95, v181
	v_lshl_add_u64 v[94:95], v[94:95], 2, s[86:87]
	v_add_u32_e32 v58, s45, v54
	global_load_dword v55, v[94:95], off
	v_lshl_add_u32 v94, v58, 4, v89
	v_mov_b32_e32 v95, v181
	v_lshl_add_u64 v[94:95], v[94:95], 2, s[86:87]
	global_load_dword v58, v[94:95], off

.LBB0_423:
	v_mov_b32_e32 v53, s72
	s_waitcnt lgkmcnt(0)
	s_barrier
	ds_read_b32 v53, v53
	v_mul_u32_u24_e32 v52, 0x90, v99
	v_add_u32_e32 v51, s44, v98
	s_add_i32 s43, s43, 0x1d400
	v_add_u32_e32 v99, s43, v52
	v_add_u32_e32 v98, v51, v47
	v_add_u32_e32 v100, s43, v50
	ds_read_b128 v[104:107], v98
	s_waitcnt lgkmcnt(1)
	v_mul_f32_e32 v51, 0x3fb8aa3b, v53
	v_add_u32_e32 v99, v99, v50
	v_exp_f32_e32 v102, v51
	ds_read_b128 v[108:111], v62 offset:64512
	ds_read_b128 v[112:115], v62 offset:64576
	ds_read_b64_tr_b16 v[50:51], v99
	v_add_u32_e32 v100, v100, v52
	ds_read_b128 v[116:119], v77 offset:9216
	ds_read_b64_tr_b16 v[52:53], v99 offset:576
	ds_read_b64_tr_b16 v[120:121], v100 offset:4608
	ds_read_b64_tr_b16 v[122:123], v100 offset:5184
	ds_read_b128 v[124:127], v77 offset:9280
	ds_read_b128 v[128:131], v78 offset:9216
	s_waitcnt lgkmcnt(5)
	v_mfma_f32_16x16x32_bf16 v[116:119], v[108:111], v[116:119], 0
	ds_read_b128 v[132:135], v78 offset:9280
	ds_read_b128 v[136:139], v77 offset:64512
	ds_read_b128 v[140:143], v77 offset:64576
	v_readlane_b32 s4, v255, 4
	v_pk_mul_f32 v[38:39], v[38:39], v[102:103] op_sel_hi:[1,0]
	s_waitcnt lgkmcnt(3)
	v_mfma_f32_16x16x32_bf16 v[108:111], v[108:111], v[128:131], 0
	ds_read_b128 v[128:131], v78 offset:64512
	v_add_u32_e32 v49, s4, v49
	v_pk_mul_f32 v[36:37], v[36:37], v[102:103] op_sel_hi:[1,0]
	v_pk_mul_f32 v[42:43], v[42:43], v[102:103] op_sel_hi:[1,0]
	v_pk_mul_f32 v[40:41], v[40:41], v[102:103] op_sel_hi:[1,0]
	v_add_u32_e32 v101, v49, v47
	s_waitcnt lgkmcnt(2)
	v_mfma_f32_16x16x32_bf16 v[36:39], v[50:53], v[136:139], v[36:39]
	ds_read_b128 v[136:139], v78 offset:64576
	v_add_u32_e32 v48, s4, v48
	v_add_u32_e32 v102, v48, v47
	s_waitcnt lgkmcnt(1)
	v_mfma_f32_16x16x32_bf16 v[40:43], v[50:53], v[128:131], v[40:43]
	v_add_u32_e32 v47, s34, v44
	v_add_u32_e32 v103, v47, v46
	v_mov_b32_e32 v47, v181
	v_mfma_f32_16x16x32_bf16 v[50:53], v[112:115], v[124:127], v[116:119]
	v_mfma_f32_16x16x32_bf16 v[108:111], v[112:115], v[132:135], v[108:111]
	ds_read_b128 v[112:115], v101
	s_nop 0
	ds_read_b128 v[116:119], v101 offset:64
	v_mfma_f32_16x16x32_bf16 v[36:39], v[120:123], v[140:143], v[36:39]
	s_waitcnt lgkmcnt(2)
	v_mfma_f32_16x16x32_bf16 v[40:43], v[120:123], v[136:139], v[40:43]
	s_waitcnt lgkmcnt(1)
	v_mfma_f32_16x16x32_bf16 v[48:51], v[104:107], v[112:115], v[50:53]
	ds_read_b128 v[112:115], v102
	ds_read_b128 v[120:123], v102 offset:64
	s_nop 1
	v_cvt_pk_bf16_f32 v44, v36, v37
	v_add_u32_e32 v52, s34, v45
	s_waitcnt lgkmcnt(1)
	v_mfma_f32_16x16x32_bf16 v[104:107], v[104:107], v[112:115], v[108:111]
	v_cvt_pk_bf16_f32 v45, v38, v39
	s_waitcnt vmcnt(7)
	v_and_b32_e32 v53, 0xffff0000, v21
	ds_read_b128 v[108:111], v98 offset:64
	s_waitcnt lgkmcnt(0)
	v_mfma_f32_16x16x32_bf16 v[48:51], v[108:111], v[116:119], v[48:51]
	ds_write_b64 v103, v[44:45]
	v_cvt_pk_bf16_f32 v44, v40, v41
	v_cvt_pk_bf16_f32 v45, v42, v43
	v_mfma_f32_16x16x32_bf16 v[106:109], v[108:111], v[120:123], v[104:107]
	s_nop 2
	v_add_u32_e32 v104, v52, v46
	ds_write_b64 v104, v[44:45]
	v_add_u32_e32 v44, s2, v85
	v_lshl_or_b32 v46, v44, 10, s33
	v_add_u32_e32 v46, s37, v46
	v_lshl_add_u64 v[46:47], v[46:47], 0, v[180:181]
	v_cvt_pk_bf16_f32 v44, v48, v49
	v_cvt_pk_bf16_f32 v45, v50, v51
	v_lshl_add_u64 v[46:47], v[46:47], 1, s[28:29]
	global_store_dwordx2 v[46:47], v[44:45], off offset:1024 sc1
	v_add_u32_e32 v44, s2, v86
	v_lshl_or_b32 v46, v44, 10, s33
	v_add_u32_e32 v46, s37, v46
	v_mov_b32_e32 v47, v181
	v_lshl_add_u64 v[46:47], v[46:47], 0, v[180:181]
	v_cvt_pk_bf16_f32 v44, v106, v107
	v_cvt_pk_bf16_f32 v45, v108, v109
	v_lshl_add_u64 v[46:47], v[46:47], 1, s[28:29]
	global_store_dwordx2 v[46:47], v[44:45], off offset:1024 sc1
	v_mov_b32_e32 v44, v68
	v_lshlrev_b32_e32 v50, 16, v20
	v_ashrrev_i32_e32 v45, 3, v44
	v_lshlrev_b32_e32 v44, 4, v44
	v_mul_lo_u32 v105, v45, s61
	v_and_b32_e32 v110, 0x70, v44
	v_add3_u32 v111, 0, v105, v110
	ds_write_b128 v111, v[32:35]
	v_lshl_add_u32 v32, v45, 2, 0
	v_add_u32_e32 v32, 0x1f800, v32
	ds_read_b32 v112, v32
	v_and_b32_e32 v51, 0xffff0000, v20
	v_and_b32_e32 v33, 0xffff0000, v28
	v_lshlrev_b32_e32 v52, 16, v21
	v_lshlrev_b32_e32 v108, 16, v31
	s_waitcnt lgkmcnt(0)
	v_mul_f32_e32 v32, 0x3fb8aa3b, v112
	v_exp_f32_e32 v48, v32
	v_lshlrev_b32_e32 v32, 16, v28
	v_and_b32_e32 v109, 0xffff0000, v31
	v_lshlrev_b32_e32 v106, 16, v22
	v_pk_mul_f32 v[34:35], v[48:49], v[50:51] op_sel_hi:[0,1]
	v_cvt_pk_bf16_f32 v44, v34, v35
	v_lshlrev_b32_e32 v34, 16, v29
	v_and_b32_e32 v35, 0xffff0000, v29
	v_pk_mul_f32 v[32:33], v[48:49], v[32:33] op_sel_hi:[0,1]
	v_pk_mul_f32 v[34:35], v[48:49], v[34:35] op_sel_hi:[0,1]
	v_cvt_pk_bf16_f32 v32, v32, v33
	v_cvt_pk_bf16_f32 v33, v34, v35
	v_pk_mul_f32 v[34:35], v[48:49], v[52:53] op_sel_hi:[0,1]
	v_cvt_pk_bf16_f32 v45, v34, v35
	v_lshlrev_b32_e32 v34, 16, v30
	v_and_b32_e32 v35, 0xffff0000, v30
	v_pk_mul_f32 v[34:35], v[48:49], v[34:35] op_sel_hi:[0,1]
	v_pk_mul_f32 v[108:109], v[48:49], v[108:109] op_sel_hi:[0,1]
	v_cvt_pk_bf16_f32 v34, v34, v35
	v_and_b32_e32 v107, 0xffff0000, v22
	v_cvt_pk_bf16_f32 v35, v108, v109
	v_lshlrev_b32_e32 v108, 16, v23
	v_and_b32_e32 v109, 0xffff0000, v23
	v_pk_mul_f32 v[46:47], v[48:49], v[106:107] op_sel_hi:[0,1]
	v_pk_mul_f32 v[48:49], v[48:49], v[108:109] op_sel_hi:[0,1]
	v_cvt_pk_bf16_f32 v46, v46, v47
	v_cvt_pk_bf16_f32 v47, v48, v49
	ds_write_b128 v111, v[32:35] offset:27648
	ds_write_b128 v111, v[44:47] offset:18432
	v_add3_u32 v32, s40, v105, v110
	ds_write_b128 v32, v[28:31]
	v_add3_u32 v28, s41, v105, v110
	v_readlane_b32 s2, v255, 2
	ds_write_b128 v28, v[20:23]
	s_waitcnt vmcnt(8)
	ds_write_b128 v111, v[24:27] offset:46080
	v_mov_b32_e32 v20, s2
	ds_read_b32 v20, v20
	s_lshl_b32 s2, s1, 12
	s_or_b32 s1, s2, 0x800
	s_or_b32 s2, s2, 0x700
	s_and_b64 s[4:5], s[26:27], exec
	s_waitcnt lgkmcnt(0)
	v_sub_f32_e32 v20, v20, v112
	v_mul_f32_e32 v20, 0x3fb8aa3b, v20
	v_exp_f32_e32 v24, v20
	s_movk_i32 s4, 0x10c0
	s_cselect_b32 s4, 0x100, s4
	s_add_i32 s31, s2, s4
	v_pk_mul_f32 v[20:21], v[24:25], v[50:51] op_sel_hi:[0,1]
	v_pk_mul_f32 v[22:23], v[24:25], v[52:53] op_sel_hi:[0,1]
	v_cvt_pk_bf16_f32 v20, v20, v21
	v_cvt_pk_bf16_f32 v21, v22, v23
	v_pk_mul_f32 v[22:23], v[24:25], v[106:107] op_sel_hi:[0,1]
	v_pk_mul_f32 v[24:25], v[24:25], v[108:109] op_sel_hi:[0,1]
	v_cvt_pk_bf16_f32 v22, v22, v23
	v_cvt_pk_bf16_f32 v23, v24, v25
	ds_write_b128 v111, v[20:23] offset:36864
	v_mov_b32_e32 v20, v68
	s_waitcnt lgkmcnt(0)
	s_barrier
	s_and_b64 s[4:5], s[26:27], exec
	v_ashrrev_i32_e32 v22, 3, v20
	s_cselect_b32 s4, 0, 0xfff
	v_lshlrev_b32_e32 v20, 3, v20
	s_add_i32 s30, s1, s4
	v_add_u32_e32 v21, s31, v22
	v_and_b32_e32 v23, 56, v20
	v_mul_lo_u32 v22, v22, s39
	v_or_b32_e32 v20, s35, v23
	v_add_u32_e32 v22, s30, v22
	v_or_b32_e32 v20, s0, v20
	v_mul_u32_u24_e32 v22, 0x300, v22
	v_mad_u32_u24 v20, v21, s63, v20
	v_or3_b32 v22, v22, s37, v23
	v_ashrrev_i32_e32 v21, 31, v20
	v_ashrrev_i32_e32 v23, 31, v22
	v_lshl_add_u64 v[20:21], v[20:21], 1, s[82:83]
	v_lshl_add_u64 v[32:33], v[22:23], 1, s[84:85]
	global_load_dwordx4 v[20:23], v[20:21], off
	s_nop 0
	global_load_dwordx4 v[24:27], v[32:33], off
	global_load_dwordx4 v[28:31], v[32:33], off offset:512
	s_nop 0
	global_load_dwordx4 v[32:35], v[32:33], off offset:1024
	s_and_saveexec_b64 s[4:5], s[6:7]
	s_cbranch_execz .LBB0_425
	v_add_u32_e32 v44, s31, v68
	v_lshl_add_u32 v44, v44, 4, v59
	v_mov_b32_e32 v45, v181
	v_lshl_add_u64 v[44:45], v[44:45], 2, s[86:87]
	global_load_dword v56, v[44:45], off
	v_add_u32_e32 v44, s30, v54
	v_lshl_add_u32 v44, v44, 4, v89
	v_mov_b32_e32 v45, v181
	v_lshl_add_u64 v[44:45], v[44:45], 2, s[86:87]
	global_load_dword v57, v[44:45], off

.LBB0_436:
	v_add_u32_e32 v105, s34, v85
	v_cvt_pk_bf16_f32 v48, v48, v49
	v_cvt_pk_bf16_f32 v49, v50, v51
	v_lshl_or_b32 v50, v105, 10, v52
	v_mov_b32_e32 v51, v53
	v_lshl_add_u64 v[50:51], v[50:51], 1, s[28:29]
	global_store_dwordx2 v[50:51], v[48:49], off offset:1024 sc1
	v_add_u32_e32 v48, s34, v86
	v_cvt_pk_bf16_f32 v44, v44, v45
	v_cvt_pk_bf16_f32 v45, v46, v47
	v_lshl_or_b32 v46, v48, 10, v52
	v_mov_b32_e32 v47, v53
	v_lshl_add_u64 v[46:47], v[46:47], 1, s[28:29]
	global_store_dwordx2 v[46:47], v[44:45], off offset:1024 sc1
	v_mov_b32_e32 v44, v68
	s_waitcnt vmcnt(5)
	v_lshlrev_b32_e32 v108, 16, v12
	v_ashrrev_i32_e32 v45, 3, v44
	v_lshlrev_b32_e32 v44, 4, v44
	v_mul_lo_u32 v105, v45, s61
	v_and_b32_e32 v116, 0x70, v44
	v_add3_u32 v117, 0, v105, v116
	v_lshl_add_u32 v44, v45, 2, 0
	ds_write_b128 v117, v[4:7]
	v_add_u32_e32 v44, 0x1fa00, v44
	ds_read_b32 v118, v44
	v_and_b32_e32 v109, 0xffff0000, v12
	v_and_b32_e32 v45, 0xffff0000, v8
	v_lshlrev_b32_e32 v110, 16, v13
	v_and_b32_e32 v111, 0xffff0000, v13
	s_waitcnt lgkmcnt(0)
	v_mul_f32_e32 v44, 0x3fb8aa3b, v118
	v_exp_f32_e32 v106, v44
	v_lshlrev_b32_e32 v44, 16, v8
	v_lshlrev_b32_e32 v114, 16, v11
	v_and_b32_e32 v115, 0xffff0000, v11
	v_pk_mul_f32 v[46:47], v[106:107], v[108:109] op_sel_hi:[0,1]
	v_cvt_pk_bf16_f32 v48, v46, v47
	v_lshlrev_b32_e32 v46, 16, v9
	v_and_b32_e32 v47, 0xffff0000, v9
	v_pk_mul_f32 v[44:45], v[106:107], v[44:45] op_sel_hi:[0,1]
	v_pk_mul_f32 v[46:47], v[106:107], v[46:47] op_sel_hi:[0,1]
	v_cvt_pk_bf16_f32 v44, v44, v45
	v_cvt_pk_bf16_f32 v45, v46, v47
	v_pk_mul_f32 v[46:47], v[106:107], v[110:111] op_sel_hi:[0,1]
	v_cvt_pk_bf16_f32 v49, v46, v47
	v_lshlrev_b32_e32 v46, 16, v10
	v_and_b32_e32 v47, 0xffff0000, v10
	v_pk_mul_f32 v[46:47], v[106:107], v[46:47] op_sel_hi:[0,1]
	v_pk_mul_f32 v[114:115], v[106:107], v[114:115] op_sel_hi:[0,1]
	v_cvt_pk_bf16_f32 v46, v46, v47
	v_lshlrev_b32_e32 v112, 16, v14
	v_and_b32_e32 v113, 0xffff0000, v14
	v_cvt_pk_bf16_f32 v47, v114, v115
	v_lshlrev_b32_e32 v114, 16, v15
	v_and_b32_e32 v115, 0xffff0000, v15
	v_pk_mul_f32 v[50:51], v[106:107], v[112:113] op_sel_hi:[0,1]
	v_pk_mul_f32 v[106:107], v[106:107], v[114:115] op_sel_hi:[0,1]
	v_readlane_b32 s4, v255, 4
	v_cvt_pk_bf16_f32 v50, v50, v51
	v_cvt_pk_bf16_f32 v51, v106, v107
	v_add3_u32 v106, s4, v105, v116
	ds_write_b128 v106, v[44:47]
	ds_write_b128 v117, v[48:51] offset:18432
	v_add3_u32 v44, s40, v105, v116
	ds_write_b128 v44, v[8:11]
	v_add3_u32 v44, s41, v105, v116
	ds_write_b128 v44, v[12:15]
	s_waitcnt vmcnt(4)
	ds_write_b128 v117, v[16:19] offset:46080
	v_mov_b32_e32 v44, s72
	ds_read_b32 v44, v44
	v_readlane_b32 s4, v255, 6
	s_cmp_gt_u32 s45, 64
	s_waitcnt lgkmcnt(0)
	v_sub_f32_e32 v44, v44, v118
	v_mul_f32_e32 v44, 0x3fb8aa3b, v44
	v_exp_f32_e32 v48, v44
	s_nop 0
	v_pk_mul_f32 v[44:45], v[48:49], v[108:109] op_sel_hi:[0,1]
	v_pk_mul_f32 v[46:47], v[48:49], v[110:111] op_sel_hi:[0,1]
	v_cvt_pk_bf16_f32 v44, v44, v45
	v_cvt_pk_bf16_f32 v45, v46, v47
	v_pk_mul_f32 v[46:47], v[48:49], v[112:113] op_sel_hi:[0,1]
	v_pk_mul_f32 v[48:49], v[48:49], v[114:115] op_sel_hi:[0,1]
	v_cvt_pk_bf16_f32 v46, v46, v47
	v_cvt_pk_bf16_f32 v47, v48, v49
	v_add3_u32 v48, s4, v105, v116
	ds_write_b128 v48, v[44:47]
	s_waitcnt lgkmcnt(0)
	s_barrier
	s_cbranch_scc1 .LBB0_440
	s_and_b64 s[4:5], s[26:27], exec
	s_cselect_b32 s4, s43, s44
	s_lshl_b32 s35, s4, 6
	s_add_i32 s35, s35, s2
	s_add_i32 s34, s33, 64
	v_mov_b32_e32 v4, v68
	s_and_b64 s[4:5], s[26:27], exec
	s_cselect_b32 s34, s42, s34
	v_ashrrev_i32_e32 v6, 3, v4
	s_add_i32 s34, s34, s1
	v_add_u32_e32 v5, s35, v6
	v_lshlrev_b32_e32 v4, 3, v4
	v_mul_lo_u32 v6, v6, s39
	v_and_b32_e32 v7, 56, v4
	v_add_u32_e32 v6, s34, v6
	v_or_b32_e32 v4, s0, v7
	v_mul_u32_u24_e32 v6, 0x300, v6
	v_mad_u32_u24 v4, v5, s63, v4
	v_or3_b32 v6, v6, s37, v7
	v_ashrrev_i32_e32 v5, 31, v4
	v_ashrrev_i32_e32 v7, 31, v6
	v_lshl_add_u64 v[4:5], v[4:5], 1, s[82:83]
	v_lshl_add_u64 v[16:17], v[6:7], 1, s[84:85]
	global_load_dwordx4 v[4:7], v[4:5], off
	s_nop 0
	global_load_dwordx4 v[8:11], v[16:17], off
	global_load_dwordx4 v[12:15], v[16:17], off offset:512
	s_nop 0
	global_load_dwordx4 v[16:19], v[16:17], off offset:1024
	s_and_saveexec_b64 s[4:5], s[6:7]
	s_cbranch_execz .LBB0_439
	v_add_u32_e32 v44, s35, v68
	v_lshl_add_u32 v180, v44, 4, v59
	v_lshl_add_u64 v[44:45], v[180:181], 2, s[86:87]
	global_load_dword v55, v[44:45], off
	v_add_u32_e32 v44, s34, v54
	v_lshl_add_u32 v180, v44, 4, v89
	v_lshl_add_u64 v[44:45], v[180:181], 2, s[86:87]
	global_load_dword v58, v[44:45], off

.LBB0_448:
	v_add_u32_e32 v105, s30, v85
	v_cvt_pk_bf16_f32 v48, v48, v49
	v_cvt_pk_bf16_f32 v49, v50, v51
	v_lshl_or_b32 v50, v105, 10, v52
	v_mov_b32_e32 v51, v53
	v_lshl_add_u64 v[50:51], v[50:51], 1, s[28:29]
	global_store_dwordx2 v[50:51], v[48:49], off offset:1024 sc1
	v_add_u32_e32 v48, s30, v86
	v_cvt_pk_bf16_f32 v44, v44, v45
	v_cvt_pk_bf16_f32 v45, v46, v47
	v_lshl_or_b32 v46, v48, 10, v52
	v_mov_b32_e32 v47, v53
	v_lshl_add_u64 v[46:47], v[46:47], 1, s[28:29]
	s_andn2_b64 vcc, exec, s[34:35]
	global_store_dwordx2 v[46:47], v[44:45], off offset:1024 sc1
	s_cbranch_vccnz .LBB0_450
	v_mov_b32_e32 v44, v68
	s_waitcnt vmcnt(5)
	v_lshlrev_b32_e32 v108, 16, v28
	v_ashrrev_i32_e32 v45, 3, v44
	v_lshlrev_b32_e32 v44, 4, v44
	v_mul_lo_u32 v105, v45, s61
	v_and_b32_e32 v116, 0x70, v44
	v_add3_u32 v117, 0, v105, v116
	v_lshl_add_u32 v44, v45, 2, 0
	ds_write_b128 v117, v[20:23]
	v_add_u32_e32 v44, 0x1f800, v44
	ds_read_b32 v118, v44
	v_and_b32_e32 v109, 0xffff0000, v28
	v_and_b32_e32 v45, 0xffff0000, v24
	v_lshlrev_b32_e32 v110, 16, v29
	v_and_b32_e32 v111, 0xffff0000, v29
	s_waitcnt lgkmcnt(0)
	v_mul_f32_e32 v44, 0x3fb8aa3b, v118
	v_exp_f32_e32 v106, v44
	v_lshlrev_b32_e32 v44, 16, v24
	v_lshlrev_b32_e32 v114, 16, v27
	v_and_b32_e32 v115, 0xffff0000, v27
	v_pk_mul_f32 v[46:47], v[106:107], v[108:109] op_sel_hi:[0,1]
	v_cvt_pk_bf16_f32 v48, v46, v47
	v_lshlrev_b32_e32 v46, 16, v25
	v_and_b32_e32 v47, 0xffff0000, v25
	v_pk_mul_f32 v[44:45], v[106:107], v[44:45] op_sel_hi:[0,1]
	v_pk_mul_f32 v[46:47], v[106:107], v[46:47] op_sel_hi:[0,1]
	v_cvt_pk_bf16_f32 v44, v44, v45
	v_cvt_pk_bf16_f32 v45, v46, v47
	v_pk_mul_f32 v[46:47], v[106:107], v[110:111] op_sel_hi:[0,1]
	v_cvt_pk_bf16_f32 v49, v46, v47
	v_lshlrev_b32_e32 v46, 16, v26
	v_and_b32_e32 v47, 0xffff0000, v26
	v_pk_mul_f32 v[46:47], v[106:107], v[46:47] op_sel_hi:[0,1]
	v_pk_mul_f32 v[114:115], v[106:107], v[114:115] op_sel_hi:[0,1]
	v_cvt_pk_bf16_f32 v46, v46, v47
	v_lshlrev_b32_e32 v112, 16, v30
	v_and_b32_e32 v113, 0xffff0000, v30
	v_cvt_pk_bf16_f32 v47, v114, v115
	v_lshlrev_b32_e32 v114, 16, v31
	v_and_b32_e32 v115, 0xffff0000, v31
	v_pk_mul_f32 v[50:51], v[106:107], v[112:113] op_sel_hi:[0,1]
	v_pk_mul_f32 v[106:107], v[106:107], v[114:115] op_sel_hi:[0,1]
	v_cvt_pk_bf16_f32 v50, v50, v51
	v_cvt_pk_bf16_f32 v51, v106, v107
	ds_write_b128 v117, v[44:47] offset:27648
	ds_write_b128 v117, v[48:51] offset:18432
	v_add3_u32 v44, s40, v105, v116
	ds_write_b128 v44, v[24:27]
	v_add3_u32 v44, s41, v105, v116
	v_readlane_b32 s4, v255, 2
	ds_write_b128 v44, v[28:31]
	s_waitcnt vmcnt(4)
	ds_write_b128 v117, v[32:35] offset:46080
	v_mov_b32_e32 v44, s4
	ds_read_b32 v44, v44
	s_waitcnt lgkmcnt(0)
	v_sub_f32_e32 v44, v44, v118
	v_mul_f32_e32 v44, 0x3fb8aa3b, v44
	v_exp_f32_e32 v48, v44
	s_nop 0
	v_pk_mul_f32 v[44:45], v[48:49], v[108:109] op_sel_hi:[0,1]
	v_pk_mul_f32 v[46:47], v[48:49], v[110:111] op_sel_hi:[0,1]
	v_cvt_pk_bf16_f32 v44, v44, v45
	v_cvt_pk_bf16_f32 v45, v46, v47
	v_pk_mul_f32 v[46:47], v[48:49], v[112:113] op_sel_hi:[0,1]
	v_pk_mul_f32 v[48:49], v[48:49], v[114:115] op_sel_hi:[0,1]
	v_cvt_pk_bf16_f32 v46, v46, v47
	v_cvt_pk_bf16_f32 v47, v48, v49
	ds_write_b128 v117, v[44:47] offset:36864

.LBB0_480:
	ds_read_b64_tr_b16 v[40:41], v104 offset:27648
	ds_read_b64_tr_b16 v[42:43], v104 offset:28224
	v_exp_f32_e32 v60, v36
	ds_read_b128 v[44:47], v109 offset:36864
	v_exp_f32_e32 v61, v37
	v_exp_f32_e32 v62, v38
	v_exp_f32_e32 v63, v39
	ds_read_b128 v[36:39], v108 offset:36864
	s_waitcnt lgkmcnt(1)
	v_mfma_f32_16x16x32_bf16 v[44:47], v[40:43], v[44:47], 0
	ds_read_b64_tr_b16 v[48:49], v104 offset:18432
	ds_read_b64_tr_b16 v[50:51], v104 offset:19008
	ds_read_b64_tr_b16 v[52:53], v104 offset:32256
	v_pk_mul_f32 v[34:35], v[34:35], v[62:63]
	v_pk_mul_f32 v[32:33], v[32:33], v[60:61]
	s_waitcnt lgkmcnt(3)
	v_mfma_f32_16x16x32_bf16 v[36:39], v[40:43], v[36:39], 0
	ds_read_b64_tr_b16 v[40:41], v106 offset:27648
	ds_read_b64_tr_b16 v[42:43], v106 offset:28224
	ds_read_b64_tr_b16 v[56:57], v107 offset:27648
	ds_read_b64_tr_b16 v[58:59], v107 offset:28224
	ds_read_b64_tr_b16 v[54:55], v104 offset:32832
	v_pk_mul_f32 v[30:31], v[30:31], v[62:63]
	v_pk_mul_f32 v[28:29], v[28:29], v[60:61]
	s_waitcnt lgkmcnt(3)
	v_mfma_f32_16x16x32_bf16 v[32:35], v[48:51], v[40:43], v[32:35]
	s_add_i32 s47, s47, 2
	s_and_b64 vcc, exec, s[60:61]
	s_mov_b32 s60, 0xffff0000
	s_waitcnt lgkmcnt(1)
	v_mfma_f32_16x16x32_bf16 v[40:43], v[48:51], v[56:59], v[28:31]
	s_nop 2
	ds_read_b128 v[28:31], v109 offset:36928
	ds_read_b64_tr_b16 v[48:49], v104 offset:23616
	ds_read_b128 v[56:59], v108 offset:36928
	s_movk_i32 s61, 0x90
	s_waitcnt lgkmcnt(2)
	v_mfma_f32_16x16x32_bf16 v[60:63], v[52:55], v[28:31], v[44:47]
	s_nop 2
	ds_read_b64_tr_b16 v[46:47], v104 offset:23040
	ds_read_b64_tr_b16 v[28:29], v106 offset:32256
	s_waitcnt lgkmcnt(2)
	v_mfma_f32_16x16x32_bf16 v[36:39], v[52:55], v[56:59], v[36:39]
	ds_read_b64_tr_b16 v[30:31], v106 offset:32832
	ds_read_b64_tr_b16 v[50:51], v107 offset:32256
	ds_read_b64_tr_b16 v[52:53], v107 offset:32832
	ds_read_b128 v[54:57], v105 offset:55296
	s_waitcnt lgkmcnt(3)
	v_mfma_f32_16x16x32_bf16 v[28:31], v[46:49], v[28:31], v[32:35]
	s_waitcnt lgkmcnt(1)
	v_mfma_f32_16x16x32_bf16 v[32:35], v[46:49], v[50:53], v[40:43]
	s_nop 2
	ds_read_b128 v[40:43], v109 offset:9216
	ds_read_b128 v[44:47], v108 offset:9216
	ds_read_b128 v[48:51], v105 offset:55360
	v_cvt_pk_bf16_f32 v52, v28, v29
	s_waitcnt lgkmcnt(1)
	v_mfma_f32_16x16x32_bf16 v[36:39], v[54:57], v[44:47], v[36:39]
	ds_read_b128 v[44:47], v109 offset:9280
	v_cvt_pk_bf16_f32 v53, v30, v31
	v_mfma_f32_16x16x32_bf16 v[40:43], v[54:57], v[40:43], v[60:63]
	s_waitcnt lgkmcnt(0)
	v_mfma_f32_16x16x32_bf16 v[40:43], v[48:51], v[44:47], v[40:43]
	ds_read_b128 v[44:47], v108 offset:9280
	ds_write_b64 v113, v[52:53] offset:46080
	s_waitcnt lgkmcnt(1)
	v_mfma_f32_16x16x32_bf16 v[36:39], v[48:51], v[44:47], v[36:39]
	v_cvt_pk_bf16_f32 v44, v32, v33
	v_cvt_pk_bf16_f32 v45, v34, v35
	ds_write_b64 v112, v[44:45] offset:46080
	v_add_u32_e32 v44, s34, v75
	v_lshl_or_b32 v180, v44, 10, v76
	v_cvt_pk_bf16_f32 v40, v40, v41
	v_cvt_pk_bf16_f32 v41, v42, v43
	v_lshl_add_u64 v[42:43], v[180:181], 1, s[92:93]
	global_store_dwordx2 v[42:43], v[40:41], off sc1
	v_add_u32_e32 v40, s34, v77
	v_lshl_or_b32 v180, v40, 10, v76
	v_cvt_pk_bf16_f32 v36, v36, v37
	v_cvt_pk_bf16_f32 v37, v38, v39
	v_lshl_add_u64 v[38:39], v[180:181], 1, s[92:93]
	global_store_dwordx2 v[38:39], v[36:37], off sc1
	s_waitcnt lgkmcnt(0)
	s_barrier
	s_cbranch_vccnz .LBB0_541

.LBB0_508:
	v_add_u32_e32 v109, v72, v64
	v_add_u32_e32 v108, v73, v64
	ds_read_b64_tr_b16 v[40:41], v104 offset:27648
	ds_read_b64_tr_b16 v[42:43], v104 offset:28224
	v_exp_f32_e32 v60, v36
	v_exp_f32_e32 v61, v37
	ds_read_b128 v[44:47], v109 offset:36864
	v_exp_f32_e32 v62, v38
	v_exp_f32_e32 v63, v39
	ds_read_b128 v[36:39], v108 offset:36864
	s_waitcnt lgkmcnt(1)
	v_mfma_f32_16x16x32_bf16 v[44:47], v[40:43], v[44:47], 0
	ds_read_b64_tr_b16 v[48:49], v104 offset:18432
	ds_read_b64_tr_b16 v[50:51], v104 offset:19008
	ds_read_b64_tr_b16 v[52:53], v104 offset:32256
	v_pk_mul_f32 v[30:31], v[30:31], v[62:63]
	v_pk_mul_f32 v[28:29], v[28:29], v[60:61]
	s_waitcnt lgkmcnt(3)
	v_mfma_f32_16x16x32_bf16 v[36:39], v[40:43], v[36:39], 0
	ds_read_b64_tr_b16 v[40:41], v106 offset:27648
	ds_read_b64_tr_b16 v[42:43], v106 offset:28224
	ds_read_b64_tr_b16 v[56:57], v107 offset:27648
	ds_read_b64_tr_b16 v[58:59], v107 offset:28224
	ds_read_b64_tr_b16 v[54:55], v104 offset:32832
	v_pk_mul_f32 v[34:35], v[34:35], v[62:63]
	v_pk_mul_f32 v[32:33], v[32:33], v[60:61]
	s_waitcnt lgkmcnt(3)
	v_mfma_f32_16x16x32_bf16 v[28:31], v[48:51], v[40:43], v[28:31]
	v_add_u32_e32 v113, v72, v74
	v_add_u32_e32 v112, v73, v74
	v_readlane_b32 s4, v255, 10
	s_waitcnt lgkmcnt(1)
	v_mfma_f32_16x16x32_bf16 v[40:43], v[48:51], v[56:59], v[32:35]
	s_nop 2
	ds_read_b128 v[32:35], v109 offset:36928
	ds_read_b64_tr_b16 v[48:49], v104 offset:23616
	ds_read_b128 v[56:59], v108 offset:36928
	s_and_b64 vcc, exec, s[34:35]
	s_waitcnt lgkmcnt(2)
	v_mfma_f32_16x16x32_bf16 v[60:63], v[52:55], v[32:35], v[44:47]
	s_nop 2
	ds_read_b64_tr_b16 v[46:47], v104 offset:23040
	ds_read_b64_tr_b16 v[32:33], v106 offset:32256
	s_waitcnt lgkmcnt(2)
	v_mfma_f32_16x16x32_bf16 v[36:39], v[52:55], v[56:59], v[36:39]
	ds_read_b64_tr_b16 v[34:35], v106 offset:32832
	ds_read_b64_tr_b16 v[50:51], v107 offset:32256
	ds_read_b64_tr_b16 v[52:53], v107 offset:32832
	ds_read_b128 v[54:57], v105 offset:46080
	s_waitcnt lgkmcnt(3)
	v_mfma_f32_16x16x32_bf16 v[32:35], v[46:49], v[32:35], v[28:31]
	s_waitcnt lgkmcnt(1)
	v_mfma_f32_16x16x32_bf16 v[28:31], v[46:49], v[50:53], v[40:43]
	s_nop 2
	ds_read_b128 v[40:43], v109 offset:9216
	ds_read_b128 v[44:47], v108 offset:9216
	ds_read_b128 v[48:51], v105 offset:46144
	s_waitcnt lgkmcnt(1)
	v_mfma_f32_16x16x32_bf16 v[36:39], v[54:57], v[44:47], v[36:39]
	ds_read_b128 v[44:47], v109 offset:9280
	v_mfma_f32_16x16x32_bf16 v[40:43], v[54:57], v[40:43], v[60:63]
	s_waitcnt lgkmcnt(0)
	v_mfma_f32_16x16x32_bf16 v[40:43], v[48:51], v[44:47], v[40:43]
	ds_read_b128 v[44:47], v108 offset:9280
	s_waitcnt lgkmcnt(0)
	v_mfma_f32_16x16x32_bf16 v[36:39], v[48:51], v[44:47], v[36:39]
	v_cvt_pk_bf16_f32 v44, v32, v33
	v_cvt_pk_bf16_f32 v45, v34, v35
	ds_write_b64 v113, v[44:45] offset:55296
	v_cvt_pk_bf16_f32 v44, v28, v29
	v_cvt_pk_bf16_f32 v45, v30, v31
	ds_write_b64 v112, v[44:45] offset:55296
	v_add_u32_e32 v44, s48, v75
	v_lshl_or_b32 v180, v44, 10, v76
	v_cvt_pk_bf16_f32 v40, v40, v41
	v_cvt_pk_bf16_f32 v41, v42, v43
	v_lshl_add_u64 v[42:43], v[180:181], 1, s[92:93]
	global_store_dwordx2 v[42:43], v[40:41], off sc1
	v_add_u32_e32 v40, s48, v77
	v_lshl_or_b32 v180, v40, 10, v76
	v_cvt_pk_bf16_f32 v36, v36, v37
	v_cvt_pk_bf16_f32 v37, v38, v39
	v_lshl_add_u64 v[38:39], v[180:181], 1, s[92:93]
	global_store_dwordx2 v[38:39], v[36:37], off sc1
	v_mov_b32_e32 v36, v68
	s_waitcnt lgkmcnt(0)
	s_barrier
	v_mov_b32_e32 v43, 0
	v_lshrrev_b32_e32 v37, 3, v36
	v_and_or_b32 v40, v37, 7, s70
	v_and_b32_e32 v41, 7, v36
	v_lshlrev_b32_e32 v36, 8, v40
	v_lshlrev_b32_e32 v37, 5, v41
	v_add3_u32 v36, s4, v36, v37
	ds_read_b128 v[44:47], v36
	ds_read_b128 v[36:39], v36 offset:16
	v_mul_lo_u32 v116, v40, s72
	v_lshlrev_b32_e32 v117, 4, v41
	v_lshlrev_b32_e32 v115, 3, v41
	v_add3_u32 v114, 0, v116, v117
	v_mov_b32_e32 v42, 0
	v_mov_b32_e32 v41, 0
	v_mov_b32_e32 v40, 0
	v_mov_b32_e32 v51, 0
	v_mov_b32_e32 v50, 0
	v_mov_b32_e32 v49, 0
	v_mov_b32_e32 v48, 0
	ds_write_b128 v114, v[24:27] offset:27648
	s_cbranch_vccnz .LBB0_510
	v_lshl_add_u32 v40, v115, 2, s62
	ds_read_b128 v[48:51], v40
	ds_read_b128 v[40:43], v40 offset:16

.LBB0_548:
	v_mul_u32_u24_e32 v22, 0x90, v22
	v_add_u32_e32 v22, 0, v22
	s_lshl_b32 s4, s4, 2
	v_and_or_b32 v21, s4, -16, v21
	v_add_u32_e32 v69, v22, v79
	s_waitcnt lgkmcnt(0)
	s_barrier
	ds_read_b128 v[22:25], v69 offset:27648
	v_mul_lo_u32 v26, v21, s61
	v_add_u32_e32 v76, 0, v26
	v_add_u32_e32 v110, 0x1200, v76
	v_add_u32_e32 v70, v76, v79
	v_add_u32_e32 v71, v110, v79
	ds_read_b128 v[72:75], v70 offset:46080
	ds_read_b128 v[82:85], v71 offset:46080
	s_waitcnt lgkmcnt(1)
	v_mfma_f32_16x16x32_bf16 v[72:75], v[22:25], v[72:75], 0
	ds_read_b128 v[86:89], v69 offset:36864
	ds_read_b128 v[90:93], v70 offset:27648
	ds_read_b128 v[98:101], v69 offset:27712
	v_mul_f32_e32 v94, 0, v28
	s_waitcnt lgkmcnt(3)
	v_mfma_f32_16x16x32_bf16 v[22:25], v[22:25], v[82:85], 0
	ds_read_b128 v[82:85], v71 offset:27648
	v_mov_b32_e32 v95, v94
	v_mov_b32_e32 v96, v94
	v_mov_b32_e32 v97, v94
	v_or_b32_e32 v20, s12, v20
	v_lshlrev_b32_e32 v111, 1, v20
	s_waitcnt lgkmcnt(2)
	v_mfma_f32_16x16x32_bf16 v[90:93], v[86:89], v[90:93], v[94:97]
	s_and_b64 s[12:13], s[8:9], exec
	s_cselect_b32 s4, 0xc0, 63
	s_or_b32 s2, s4, s2
	s_waitcnt lgkmcnt(0)
	v_mfma_f32_16x16x32_bf16 v[82:85], v[86:89], v[82:85], v[94:97]
	ds_read_b128 v[86:89], v70 offset:46144
	s_nop 1
	ds_read_b128 v[94:97], v69 offset:36928
	ds_read_b128 v[102:105], v71 offset:46144
	s_and_b64 s[12:13], s[8:9], exec
	s_cselect_b32 s4, s92, 0x1b485000
	s_waitcnt lgkmcnt(2)
	v_mfma_f32_16x16x32_bf16 v[86:89], v[98:101], v[86:89], v[72:75]
	s_nop 2
	ds_read_b128 v[72:75], v70 offset:27712
	ds_read_b128 v[106:109], v71 offset:27712
	s_add_u32 s12, s78, s4
	s_addc_u32 s13, s79, 0
	s_waitcnt lgkmcnt(2)
	v_mfma_f32_16x16x32_bf16 v[98:101], v[98:101], v[102:105], v[22:25]
	ds_read_b128 v[102:105], v69 offset:55296
	v_mov_b32_e32 v31, v30
	s_andn2_b64 vcc, exec, s[6:7]
	s_waitcnt lgkmcnt(2)
	v_mfma_f32_16x16x32_bf16 v[24:27], v[94:97], v[72:75], v[90:93]
	v_mul_lo_u32 v72, v21, s19
	v_or_b32_e32 v73, s0, v20
	v_add_u32_e32 v75, v76, v111
	ds_read_b128 v[90:93], v70 offset:18432
	s_waitcnt lgkmcnt(2)
	v_mfma_f32_16x16x32_bf16 v[20:23], v[94:97], v[106:109], v[82:85]
	s_nop 2
	ds_read_b128 v[82:85], v69 offset:55360
	ds_read_b128 v[94:97], v70 offset:18496
	ds_read_b128 v[106:109], v71 offset:18432
	v_cvt_pk_bf16_f32 v58, v24, v25
	v_cvt_pk_bf16_f32 v59, v26, v27
	s_waitcnt lgkmcnt(3)
	v_mfma_f32_16x16x32_bf16 v[86:89], v[102:105], v[90:93], v[86:89]
	ds_read_b128 v[90:93], v71 offset:18496
	ds_write_b64 v75, v[58:59] offset:64512
	v_cvt_pk_bf16_f32 v58, v20, v21
	s_waitcnt lgkmcnt(2)
	v_mfma_f32_16x16x32_bf16 v[98:101], v[102:105], v[106:109], v[98:101]
	v_cvt_pk_bf16_f32 v59, v22, v23
	v_add_u32_e32 v76, v110, v111
	v_lshl_add_u32 v74, s19, 5, v72
	v_mfma_f32_16x16x32_bf16 v[86:89], v[82:85], v[94:97], v[86:89]
	ds_write_b64 v76, v[58:59] offset:64512
	s_waitcnt lgkmcnt(2)
	v_mfma_f32_16x16x32_bf16 v[82:85], v[82:85], v[90:93], v[98:101]
	v_add_u32_e32 v90, s5, v72
	v_lshl_or_b32 v180, v90, 10, v73
	s_nop 2
	v_cvt_pk_bf16_f32 v58, v86, v87
	v_cvt_pk_bf16_f32 v59, v88, v89
	v_lshl_add_u64 v[86:87], v[180:181], 1, s[12:13]
	global_store_dwordx2 v[86:87], v[58:59], off offset:512 sc1
	v_add_u32_e32 v86, s5, v74
	v_lshl_or_b32 v180, v86, 10, v73
	v_cvt_pk_bf16_f32 v58, v82, v83
	v_cvt_pk_bf16_f32 v59, v84, v85
	v_lshl_add_u64 v[82:83], v[180:181], 1, s[12:13]
	global_store_dwordx2 v[82:83], v[58:59], off offset:512 sc1
	s_waitcnt lgkmcnt(0)
	s_barrier
	s_waitcnt vmcnt(13)
	ds_write_b128 v62, v[12:15]
	s_waitcnt vmcnt(12)
	ds_write_b128 v62, v[16:19] offset:9216
	v_lshlrev_b32_e32 v16, 16, v12
	v_and_b32_e32 v17, 0xffff0000, v12
	v_pk_mul_f32 v[16:17], v[30:31], v[16:17]
	s_mov_b64 s[4:5], -1
	v_cvt_pk_bf16_f32 v12, v16, v17
	v_lshlrev_b32_e32 v16, 16, v13
	v_and_b32_e32 v17, 0xffff0000, v13
	v_pk_mul_f32 v[16:17], v[30:31], v[16:17]
	s_nop 0
	v_cvt_pk_bf16_f32 v13, v16, v17
	v_lshlrev_b32_e32 v16, 16, v14
	v_and_b32_e32 v17, 0xffff0000, v14
	v_pk_mul_f32 v[16:17], v[30:31], v[16:17]
	s_nop 0
	v_cvt_pk_bf16_f32 v14, v16, v17
	v_lshlrev_b32_e32 v16, 16, v15
	v_and_b32_e32 v17, 0xffff0000, v15
	v_pk_mul_f32 v[16:17], v[30:31], v[16:17]
	s_nop 0
	v_cvt_pk_bf16_f32 v15, v16, v17
	ds_write_b128 v62, v[12:15] offset:18432
	s_waitcnt vmcnt(11)
	v_and_b32_e32 v12, 0xffff, v42
	s_waitcnt vmcnt(10)
	v_lshl_or_b32 v14, v52, 16, v12
	s_waitcnt vmcnt(9)
	v_lshlrev_b32_e32 v13, 16, v56
	s_waitcnt vmcnt(8)
	v_lshlrev_b32_e32 v12, 16, v54
	v_pk_mul_f32 v[12:13], v[32:33], v[12:13]
	s_nop 0
	v_cvt_pk_bf16_f32 v15, v12, v13
	v_lshrrev_b32_e32 v12, 16, v42
	v_and_or_b32 v12, v52, s60, v12
	ds_write2_b32 v63, v14, v12 offset1:36
	v_and_b32_e32 v13, 0xffff0000, v56
	v_and_b32_e32 v12, 0xffff0000, v54
	v_pk_mul_f32 v[12:13], v[32:33], v[12:13]
	v_add_u32_e32 v42, s2, v67
	v_cvt_pk_bf16_f32 v12, v12, v13
	ds_write2_b32 v64, v15, v12 offset1:36
	v_and_b32_e32 v12, 0xffff, v43
	v_lshl_or_b32 v14, v53, 16, v12
	v_lshlrev_b32_e32 v13, 16, v57
	v_lshlrev_b32_e32 v12, 16, v55
	v_pk_mul_f32 v[12:13], v[32:33], v[12:13]
	v_mad_u32_u24 v42, v42, s63, v61
	v_cvt_pk_bf16_f32 v15, v12, v13
	v_lshrrev_b32_e32 v12, 16, v43
	v_and_or_b32 v12, v53, s60, v12
	ds_write2_b32 v63, v14, v12 offset0:72 offset1:108
	v_and_b32_e32 v13, 0xffff0000, v57
	v_and_b32_e32 v12, 0xffff0000, v55
	v_pk_mul_f32 v[12:13], v[32:33], v[12:13]
	v_ashrrev_i32_e32 v43, 31, v42
	v_cvt_pk_bf16_f32 v12, v12, v13
	ds_write2_b32 v64, v15, v12 offset0:72 offset1:108
	v_add_u32_e32 v12, s2, v60
	v_mul_u32_u24_e32 v12, 0xe00, v12
	v_or3_b32 v12, v12, v77, s0
	v_ashrrev_i32_e32 v13, 31, v12
	v_lshl_add_u64 v[42:43], v[42:43], 1, s[82:83]
	v_lshl_add_u64 v[16:17], v[12:13], 1, s[82:83]
	v_lshl_add_u64 v[52:53], s[10:11], 1, v[42:43]
	s_waitcnt lgkmcnt(0)
	s_barrier
	global_load_dwordx4 v[12:15], v[16:17], off offset:2560
	s_nop 0
	global_load_dwordx4 v[16:19], v[16:17], off offset:3072
	s_nop 0
	global_load_dwordx2 v[56:57], v[42:43], off offset:3584
	global_load_dwordx2 v[58:59], v[52:53], off offset:3584
	global_load_dwordx2 v[54:55], v[52:53], off offset:3072
	s_nop 0
	global_load_dwordx2 v[52:53], v[42:43], off offset:3072
	ds_read_b128 v[82:85], v65 offset:9216
	ds_read_b128 v[86:89], v66
	ds_read_b128 v[90:93], v65 offset:9280
	s_waitcnt lgkmcnt(1)
	v_mfma_f32_16x16x32_bf16 v[82:85], v[82:85], v[86:89], 0
	ds_read_b128 v[86:89], v66 offset:64
	s_waitcnt lgkmcnt(0)
	v_mfma_f32_16x16x32_bf16 v[82:85], v[90:93], v[86:89], v[82:85]
	s_nop 7
	v_pk_mul_f32 v[42:43], v[34:35], v[82:83]
	v_pk_mul_f32 v[82:83], v[38:39], v[84:85]
	v_cvt_pk_bf16_f32 v42, v42, v43
	v_cvt_pk_bf16_f32 v43, v82, v83
	ds_write_b64 v68, v[42:43] offset:46080
	s_cbranch_vccnz .LBB0_550
	s_lshl_b32 s6, s18, 5
	v_mul_u32_u24_e32 v82, 0x90, v81
	s_mov_b64 s[4:5], 0
	v_mov_b32_e32 v83, s6

.LBB0_552:
	s_waitcnt lgkmcnt(0)
	s_barrier
	ds_read_b128 v[84:87], v69 offset:27648
	ds_read_b128 v[88:91], v70 offset:46080
	ds_read_b128 v[92:95], v69 offset:36864
	ds_read_b128 v[96:99], v71 offset:46080
	s_waitcnt lgkmcnt(2)
	v_mfma_f32_16x16x32_bf16 v[88:91], v[84:87], v[88:91], 0
	ds_read_b128 v[100:103], v70 offset:27648
	ds_read_b128 v[104:107], v71 offset:27648
	v_mov_b32_e32 v42, v28
	v_mov_b32_e32 v43, v28
	s_waitcnt lgkmcnt(2)
	v_mfma_f32_16x16x32_bf16 v[84:87], v[84:87], v[96:99], 0
	ds_read_b128 v[96:99], v69 offset:27712
	v_mov_b32_e32 v29, v28
	v_pk_mul_f32 v[26:27], v[28:29], v[26:27]
	v_pk_mul_f32 v[24:25], v[42:43], v[24:25]
	v_pk_mul_f32 v[22:23], v[28:29], v[22:23]
	v_pk_mul_f32 v[20:21], v[42:43], v[20:21]
	s_waitcnt lgkmcnt(2)
	v_mfma_f32_16x16x32_bf16 v[24:27], v[92:95], v[100:103], v[24:27]
	v_add_u32_e32 v81, s17, v72
	v_lshl_or_b32 v180, v81, 10, v73
	v_add_u32_e32 v81, s17, v74
	s_waitcnt lgkmcnt(1)
	v_mfma_f32_16x16x32_bf16 v[20:23], v[92:95], v[104:107], v[20:23]
	ds_read_b128 v[92:95], v70 offset:46144
	ds_read_b128 v[100:103], v71 offset:46144
	s_lshl_b32 s1, s1, 12
	s_bitset1_b32 s1, 11
	s_waitcnt lgkmcnt(1)
	v_mfma_f32_16x16x32_bf16 v[88:91], v[96:99], v[92:95], v[88:91]
	ds_read_b128 v[92:95], v69 offset:36928
	s_and_b64 s[4:5], s[8:9], exec
	s_cselect_b32 s4, 0, 0xfff
	s_waitcnt lgkmcnt(1)
	v_mfma_f32_16x16x32_bf16 v[84:87], v[96:99], v[100:103], v[84:87]
	ds_read_b128 v[96:99], v70 offset:27712
	ds_read_b128 v[100:103], v71 offset:27712
	s_add_i32 s4, s1, s4
	s_andn2_b64 vcc, exec, s[14:15]
	s_waitcnt lgkmcnt(1)
	v_mfma_f32_16x16x32_bf16 v[24:27], v[92:95], v[96:99], v[24:27]
	ds_read_b128 v[96:99], v69 offset:64512
	s_waitcnt lgkmcnt(1)
	v_mfma_f32_16x16x32_bf16 v[20:23], v[92:95], v[100:103], v[20:23]
	ds_read_b128 v[92:95], v70 offset:18432
	ds_read_b128 v[100:103], v69 offset:64576
	ds_read_b128 v[104:107], v71 offset:18432
	ds_read_b128 v[108:111], v71 offset:18496
	s_waitcnt lgkmcnt(3)
	v_mfma_f32_16x16x32_bf16 v[88:91], v[96:99], v[92:95], v[88:91]
	ds_read_b128 v[92:95], v70 offset:18496
	s_waitcnt lgkmcnt(2)
	v_mfma_f32_16x16x32_bf16 v[84:87], v[96:99], v[104:107], v[84:87]
	v_cvt_pk_bf16_f32 v96, v24, v25
	v_cvt_pk_bf16_f32 v97, v26, v27
	ds_write_b64 v75, v[96:97] offset:55296
	s_waitcnt lgkmcnt(1)
	v_mfma_f32_16x16x32_bf16 v[88:91], v[100:103], v[92:95], v[88:91]
	v_cvt_pk_bf16_f32 v92, v20, v21
	v_cvt_pk_bf16_f32 v93, v22, v23
	ds_write_b64 v76, v[92:93] offset:55296
	v_mfma_f32_16x16x32_bf16 v[84:87], v[100:103], v[108:111], v[84:87]
	s_nop 3
	v_cvt_pk_bf16_f32 v88, v88, v89
	v_cvt_pk_bf16_f32 v89, v90, v91
	v_lshl_add_u64 v[90:91], v[180:181], 1, s[12:13]
	v_lshl_or_b32 v180, v81, 10, v73
	v_cvt_pk_bf16_f32 v84, v84, v85
	v_cvt_pk_bf16_f32 v85, v86, v87
	v_lshl_add_u64 v[86:87], v[180:181], 1, s[12:13]
	global_store_dwordx2 v[90:91], v[88:89], off offset:512 sc1
	global_store_dwordx2 v[86:87], v[84:85], off offset:512 sc1
	s_waitcnt lgkmcnt(0)
	s_barrier
	s_waitcnt vmcnt(15)
	ds_write_b128 v62, v[4:7]
	s_waitcnt vmcnt(14)
	ds_write_b128 v62, v[8:11] offset:9216
	v_lshlrev_b32_e32 v8, 16, v4
	v_and_b32_e32 v9, 0xffff0000, v4
	v_pk_mul_f32 v[8:9], v[30:31], v[8:9]
	s_nop 0
	v_cvt_pk_bf16_f32 v4, v8, v9
	v_lshlrev_b32_e32 v8, 16, v5
	v_and_b32_e32 v9, 0xffff0000, v5
	v_pk_mul_f32 v[8:9], v[30:31], v[8:9]
	s_nop 0
	v_cvt_pk_bf16_f32 v5, v8, v9
	v_lshlrev_b32_e32 v8, 16, v6
	v_and_b32_e32 v9, 0xffff0000, v6
	v_pk_mul_f32 v[8:9], v[30:31], v[8:9]
	s_nop 0
	v_cvt_pk_bf16_f32 v6, v8, v9
	v_lshlrev_b32_e32 v8, 16, v7
	v_and_b32_e32 v9, 0xffff0000, v7
	v_pk_mul_f32 v[8:9], v[30:31], v[8:9]
	s_nop 0
	v_cvt_pk_bf16_f32 v7, v8, v9
	ds_write_b128 v62, v[4:7] offset:18432
	s_waitcnt vmcnt(13)
	v_and_b32_e32 v4, 0xffff, v44
	s_waitcnt vmcnt(12)
	v_lshl_or_b32 v6, v46, 16, v4
	s_waitcnt vmcnt(11)
	v_lshlrev_b32_e32 v5, 16, v50
	s_waitcnt vmcnt(10)
	v_lshlrev_b32_e32 v4, 16, v48
	v_pk_mul_f32 v[4:5], v[32:33], v[4:5]
	s_nop 0
	v_cvt_pk_bf16_f32 v7, v4, v5
	v_lshrrev_b32_e32 v4, 16, v44
	v_and_or_b32 v4, v46, s60, v4
	ds_write2_b32 v63, v6, v4 offset1:36
	v_and_b32_e32 v5, 0xffff0000, v50
	v_and_b32_e32 v4, 0xffff0000, v48
	v_pk_mul_f32 v[4:5], v[32:33], v[4:5]
	v_add_u32_e32 v44, s4, v67
	v_cvt_pk_bf16_f32 v4, v4, v5
	ds_write2_b32 v64, v7, v4 offset1:36
	v_and_b32_e32 v4, 0xffff, v45
	v_lshl_or_b32 v6, v47, 16, v4
	v_lshlrev_b32_e32 v5, 16, v51
	v_lshlrev_b32_e32 v4, 16, v49
	v_pk_mul_f32 v[4:5], v[32:33], v[4:5]
	v_mad_u32_u24 v44, v44, s63, v61
	v_cvt_pk_bf16_f32 v7, v4, v5
	v_lshrrev_b32_e32 v4, 16, v45
	v_and_or_b32 v4, v47, s60, v4
	ds_write2_b32 v63, v6, v4 offset0:72 offset1:108
	v_and_b32_e32 v5, 0xffff0000, v51
	v_and_b32_e32 v4, 0xffff0000, v49
	v_pk_mul_f32 v[4:5], v[32:33], v[4:5]
	v_ashrrev_i32_e32 v45, 31, v44
	v_cvt_pk_bf16_f32 v4, v4, v5
	ds_write2_b32 v64, v7, v4 offset0:72 offset1:108
	v_add_u32_e32 v4, s4, v60
	v_mul_u32_u24_e32 v4, 0xe00, v4
	v_or3_b32 v4, v4, v77, s0
	v_ashrrev_i32_e32 v5, 31, v4
	v_lshl_add_u64 v[50:51], v[44:45], 1, s[82:83]
	v_lshl_add_u64 v[8:9], v[4:5], 1, s[82:83]
	v_lshl_add_u64 v[48:49], s[10:11], 1, v[50:51]
	s_waitcnt lgkmcnt(0)
	s_barrier
	global_load_dwordx4 v[4:7], v[8:9], off offset:2560
	s_nop 0
	global_load_dwordx4 v[8:11], v[8:9], off offset:3072
	s_nop 0
	global_load_dwordx2 v[44:45], v[50:51], off offset:3584
	global_load_dwordx2 v[46:47], v[48:49], off offset:3584
	s_nop 0
	global_load_dwordx2 v[48:49], v[48:49], off offset:3072
	s_nop 0
	global_load_dwordx2 v[50:51], v[50:51], off offset:3072
	ds_read_b128 v[84:87], v65 offset:9216
	ds_read_b128 v[88:91], v65 offset:9280
	ds_read_b128 v[92:95], v66
	ds_read_b128 v[96:99], v66 offset:64
	s_waitcnt lgkmcnt(1)
	v_mfma_f32_16x16x32_bf16 v[84:87], v[84:87], v[92:95], 0
	v_add_u32_e32 v92, 0, v80
	v_add_u32_e32 v93, 0, v82
	v_add_u32_e32 v82, v78, v82
	s_waitcnt lgkmcnt(0)
	v_mfma_f32_16x16x32_bf16 v[84:87], v[88:91], v[96:99], v[84:87]
	v_cndmask_b32_e64 v78, 0, 1, s[14:15]
	v_cmp_ne_u32_e64 s[6:7], 1, v78
	v_add_u32_e32 v78, v92, v79
	v_add_u32_e32 v79, v93, v79
	s_nop 3
	v_pk_mul_f32 v[80:81], v[34:35], v[84:85]
	v_pk_mul_f32 v[84:85], v[38:39], v[86:87]
	v_cvt_pk_bf16_f32 v80, v80, v81
	v_cvt_pk_bf16_f32 v81, v84, v85
	ds_write_b64 v68, v[80:81] offset:46080
	v_add_u32_e32 v80, v82, v83
	s_cbranch_vccnz .LBB0_554
	ds_read_b128 v[82:85], v78 offset:9216
	ds_read_b128 v[86:89], v79
	ds_read_b128 v[90:93], v78 offset:9280
	s_waitcnt lgkmcnt(1)
	v_mfma_f32_16x16x32_bf16 v[82:85], v[82:85], v[86:89], 0
	ds_read_b128 v[86:89], v79 offset:64
	s_waitcnt lgkmcnt(0)
	v_mfma_f32_16x16x32_bf16 v[82:85], v[90:93], v[86:89], v[82:85]
	s_nop 7
	v_pk_mul_f32 v[82:83], v[36:37], v[82:83]
	v_pk_mul_f32 v[84:85], v[40:41], v[84:85]
	v_cvt_pk_bf16_f32 v82, v82, v83
	v_cvt_pk_bf16_f32 v83, v84, v85
	ds_write_b64 v80, v[82:83] offset:46080
.LBB0_554:
	s_waitcnt lgkmcnt(0)
	s_barrier
	ds_read_b128 v[82:85], v69 offset:27648
	ds_read_b128 v[86:89], v70 offset:46080
	ds_read_b128 v[90:93], v69 offset:36864
	ds_read_b128 v[94:97], v71 offset:46080
	ds_read_b128 v[98:101], v70 offset:27648
	v_pk_mul_f32 v[26:27], v[28:29], v[26:27]
	v_pk_mul_f32 v[24:25], v[42:43], v[24:25]
	s_waitcnt lgkmcnt(3)
	v_mfma_f32_16x16x32_bf16 v[86:89], v[82:85], v[86:89], 0
	v_mul_f32_e64 v22, v28, v22
	v_mul_f32_e64 v23, v29, v23
	v_pk_mul_f32 v[20:21], v[42:43], v[20:21]
	v_add_u32_e32 v29, s16, v72
	s_waitcnt lgkmcnt(1)
	v_mfma_f32_16x16x32_bf16 v[82:85], v[82:85], v[94:97], 0
	ds_read_b128 v[94:97], v71 offset:27648
	v_lshl_or_b32 v180, v29, 10, v73
	v_add_u32_e32 v29, s16, v74
	s_waitcnt lgkmcnt(1)
	v_mfma_f32_16x16x32_bf16 v[24:27], v[90:93], v[98:101], v[24:27]
	ds_read_b128 v[98:101], v69 offset:27712
	s_and_b64 s[4:5], s[8:9], exec
	s_cselect_b32 s4, 64, 0xfbf
	s_waitcnt lgkmcnt(1)
	v_mfma_f32_16x16x32_bf16 v[20:23], v[90:93], v[94:97], v[20:23]
	ds_read_b128 v[90:93], v70 offset:46144
	ds_read_b128 v[94:97], v71 offset:46144
	s_add_i32 s4, s1, s4
	s_and_b64 vcc, exec, s[6:7]
	s_waitcnt lgkmcnt(1)
	v_mfma_f32_16x16x32_bf16 v[86:89], v[98:101], v[90:93], v[86:89]
	ds_read_b128 v[90:93], v69 offset:36928
	s_waitcnt lgkmcnt(1)
	v_mfma_f32_16x16x32_bf16 v[82:85], v[98:101], v[94:97], v[82:85]
	ds_read_b128 v[94:97], v70 offset:27712
	ds_read_b128 v[98:101], v71 offset:27712
	ds_read_b128 v[102:105], v69 offset:55296
	s_waitcnt lgkmcnt(2)
	v_mfma_f32_16x16x32_bf16 v[24:27], v[90:93], v[94:97], v[24:27]
	ds_read_b128 v[94:97], v69 offset:55360
	ds_read_b128 v[106:109], v70 offset:18432
	ds_read_b128 v[110:113], v70 offset:18496
	s_nop 4
	v_cvt_pk_bf16_f32 v114, v24, v25
	s_waitcnt lgkmcnt(4)
	v_mfma_f32_16x16x32_bf16 v[20:23], v[90:93], v[98:101], v[20:23]
	ds_read_b128 v[90:93], v71 offset:18432
	ds_read_b128 v[98:101], v71 offset:18496
	v_cvt_pk_bf16_f32 v115, v26, v27
	ds_write_b64 v75, v[114:115] offset:64512
	s_waitcnt lgkmcnt(4)
	v_mfma_f32_16x16x32_bf16 v[86:89], v[102:105], v[106:109], v[86:89]
	s_nop 1
	v_cvt_pk_bf16_f32 v106, v20, v21
	v_cvt_pk_bf16_f32 v107, v22, v23
	ds_write_b64 v76, v[106:107] offset:64512
	s_waitcnt lgkmcnt(3)
	v_mfma_f32_16x16x32_bf16 v[82:85], v[102:105], v[90:93], v[82:85]
	v_mfma_f32_16x16x32_bf16 v[86:89], v[94:97], v[110:113], v[86:89]
	s_waitcnt lgkmcnt(2)
	v_mfma_f32_16x16x32_bf16 v[82:85], v[94:97], v[98:101], v[82:85]
	s_nop 5
	v_cvt_pk_bf16_f32 v86, v86, v87
	v_cvt_pk_bf16_f32 v87, v88, v89
	v_lshl_add_u64 v[88:89], v[180:181], 1, s[12:13]
	v_lshl_or_b32 v180, v29, 10, v73
	v_cvt_pk_bf16_f32 v82, v82, v83
	v_cvt_pk_bf16_f32 v83, v84, v85
	v_lshl_add_u64 v[84:85], v[180:181], 1, s[12:13]
	global_store_dwordx2 v[88:89], v[86:87], off offset:512 sc1
	global_store_dwordx2 v[84:85], v[82:83], off offset:512 sc1
	s_waitcnt lgkmcnt(0)
	s_barrier
	s_waitcnt vmcnt(15)
	ds_write_b128 v62, v[12:15]
	s_waitcnt vmcnt(14)
	ds_write_b128 v62, v[16:19] offset:9216
	v_lshlrev_b32_e32 v16, 16, v12
	v_and_b32_e32 v17, 0xffff0000, v12
	v_pk_mul_f32 v[16:17], v[30:31], v[16:17]
	v_add_u32_e32 v29, s4, v67
	v_cvt_pk_bf16_f32 v12, v16, v17
	v_lshlrev_b32_e32 v16, 16, v13
	v_and_b32_e32 v17, 0xffff0000, v13
	v_pk_mul_f32 v[16:17], v[30:31], v[16:17]
	s_nop 0
	v_cvt_pk_bf16_f32 v13, v16, v17
	v_lshlrev_b32_e32 v16, 16, v14
	v_and_b32_e32 v17, 0xffff0000, v14
	v_pk_mul_f32 v[16:17], v[30:31], v[16:17]
	s_nop 0
	v_cvt_pk_bf16_f32 v14, v16, v17
	v_lshlrev_b32_e32 v16, 16, v15
	v_and_b32_e32 v17, 0xffff0000, v15
	v_pk_mul_f32 v[16:17], v[30:31], v[16:17]
	s_nop 0
	v_cvt_pk_bf16_f32 v15, v16, v17
	ds_write_b128 v62, v[12:15] offset:18432
	s_waitcnt vmcnt(13)
	v_and_b32_e32 v12, 0xffff, v56
	s_waitcnt vmcnt(12)
	v_lshl_or_b32 v14, v58, 16, v12
	s_waitcnt vmcnt(11)
	v_lshlrev_b32_e32 v13, 16, v54
	s_waitcnt vmcnt(10)
	v_lshlrev_b32_e32 v12, 16, v52
	v_pk_mul_f32 v[12:13], v[32:33], v[12:13]
	s_nop 0
	v_cvt_pk_bf16_f32 v15, v12, v13
	v_lshrrev_b32_e32 v12, 16, v56
	v_and_or_b32 v12, v58, s60, v12
	ds_write2_b32 v63, v14, v12 offset1:36
	v_and_b32_e32 v13, 0xffff0000, v54
	v_and_b32_e32 v12, 0xffff0000, v52
	v_pk_mul_f32 v[12:13], v[32:33], v[12:13]
	v_mad_u32_u24 v52, v29, s63, v61
	v_cvt_pk_bf16_f32 v12, v12, v13
	ds_write2_b32 v64, v15, v12 offset1:36
	v_and_b32_e32 v12, 0xffff, v57
	v_lshl_or_b32 v14, v59, 16, v12
	v_lshlrev_b32_e32 v13, 16, v55
	v_lshlrev_b32_e32 v12, 16, v53
	v_pk_mul_f32 v[12:13], v[32:33], v[12:13]
	s_nop 0
	v_cvt_pk_bf16_f32 v15, v12, v13
	v_lshrrev_b32_e32 v12, 16, v57
	v_and_or_b32 v12, v59, s60, v12
	ds_write2_b32 v63, v14, v12 offset0:72 offset1:108
	v_and_b32_e32 v13, 0xffff0000, v55
	v_and_b32_e32 v12, 0xffff0000, v53
	v_pk_mul_f32 v[12:13], v[32:33], v[12:13]
	v_ashrrev_i32_e32 v53, 31, v52
	v_cvt_pk_bf16_f32 v12, v12, v13
	ds_write2_b32 v64, v15, v12 offset0:72 offset1:108
	v_add_u32_e32 v12, s4, v60
	v_mul_u32_u24_e32 v12, 0xe00, v12
	v_or3_b32 v12, v12, v77, s0
	v_ashrrev_i32_e32 v13, 31, v12
	v_lshl_add_u64 v[58:59], v[52:53], 1, s[82:83]
	v_lshl_add_u64 v[16:17], v[12:13], 1, s[82:83]
	v_lshl_add_u64 v[56:57], s[10:11], 1, v[58:59]
	s_waitcnt lgkmcnt(0)
	s_barrier
	global_load_dwordx4 v[12:15], v[16:17], off offset:2560
	s_nop 0
	global_load_dwordx4 v[16:19], v[16:17], off offset:3072
	s_nop 0
	global_load_dwordx2 v[52:53], v[58:59], off offset:3584
	global_load_dwordx2 v[54:55], v[56:57], off offset:3584
	s_nop 0
	global_load_dwordx2 v[56:57], v[56:57], off offset:3072
	s_nop 0
	global_load_dwordx2 v[58:59], v[58:59], off offset:3072
	ds_read_b128 v[82:85], v65 offset:9216
	ds_read_b128 v[86:89], v66
	ds_read_b128 v[90:93], v65 offset:9280
	s_waitcnt lgkmcnt(1)
	v_mfma_f32_16x16x32_bf16 v[82:85], v[82:85], v[86:89], 0
	ds_read_b128 v[86:89], v66 offset:64
	s_waitcnt lgkmcnt(0)
	v_mfma_f32_16x16x32_bf16 v[82:85], v[90:93], v[86:89], v[82:85]
	s_nop 7
	v_pk_mul_f32 v[82:83], v[34:35], v[82:83]
	v_pk_mul_f32 v[84:85], v[38:39], v[84:85]
	v_cvt_pk_bf16_f32 v82, v82, v83
	v_cvt_pk_bf16_f32 v83, v84, v85
	ds_write_b64 v68, v[82:83] offset:46080
	s_cbranch_vccnz .LBB0_556
	ds_read_b128 v[82:85], v78 offset:9216
	ds_read_b128 v[86:89], v79
	ds_read_b128 v[90:93], v78 offset:9280
	s_waitcnt lgkmcnt(1)
	v_mfma_f32_16x16x32_bf16 v[82:85], v[82:85], v[86:89], 0
	ds_read_b128 v[86:89], v79 offset:64
	s_waitcnt lgkmcnt(0)
	v_mfma_f32_16x16x32_bf16 v[82:85], v[90:93], v[86:89], v[82:85]
	s_nop 7
	v_pk_mul_f32 v[82:83], v[36:37], v[82:83]
	v_pk_mul_f32 v[84:85], v[40:41], v[84:85]
	v_cvt_pk_bf16_f32 v82, v82, v83
	v_cvt_pk_bf16_f32 v83, v84, v85
	ds_write_b64 v80, v[82:83] offset:46080
.LBB0_556:
	s_waitcnt lgkmcnt(0)
	s_barrier
	ds_read_b128 v[82:85], v69 offset:27648
	ds_read_b128 v[86:89], v70 offset:46080
	ds_read_b128 v[90:93], v69 offset:36864
	ds_read_b128 v[94:97], v71 offset:46080
	ds_read_b128 v[98:101], v70 offset:27648
	ds_read_b128 v[102:105], v71 offset:27648
	s_waitcnt lgkmcnt(4)
	v_mfma_f32_16x16x32_bf16 v[86:89], v[82:85], v[86:89], 0
	v_mov_b32_e32 v29, v28
	v_pk_mul_f32 v[26:27], v[28:29], v[26:27]
	v_pk_mul_f32 v[24:25], v[42:43], v[24:25]
	s_waitcnt lgkmcnt(2)
	v_mfma_f32_16x16x32_bf16 v[82:85], v[82:85], v[94:97], 0
	ds_read_b128 v[94:97], v69 offset:27712
	v_pk_mul_f32 v[22:23], v[28:29], v[22:23]
	v_pk_mul_f32 v[20:21], v[42:43], v[20:21]
	s_waitcnt lgkmcnt(2)
	v_mfma_f32_16x16x32_bf16 v[24:27], v[90:93], v[98:101], v[24:27]
	v_add_u32_e32 v29, s2, v72
	v_lshl_or_b32 v180, v29, 10, v73
	v_add_u32_e32 v29, s2, v74
	s_waitcnt lgkmcnt(1)
	v_mfma_f32_16x16x32_bf16 v[20:23], v[90:93], v[102:105], v[20:23]
	ds_read_b128 v[90:93], v70 offset:46144
	ds_read_b128 v[98:101], v71 offset:46144
	v_or_b32_e32 v77, s0, v77
	s_mov_b32 s0, 4
	s_waitcnt lgkmcnt(1)
	v_mfma_f32_16x16x32_bf16 v[86:89], v[94:97], v[90:93], v[86:89]
	ds_read_b128 v[90:93], v69 offset:36928
	s_movk_i32 s2, 0xfff
	s_movk_i32 s4, 0x80
	s_waitcnt lgkmcnt(1)
	v_mfma_f32_16x16x32_bf16 v[82:85], v[94:97], v[98:101], v[82:85]
	ds_read_b128 v[94:97], v70 offset:27712
	ds_read_b128 v[98:101], v71 offset:27712
	s_waitcnt lgkmcnt(1)
	v_mfma_f32_16x16x32_bf16 v[24:27], v[90:93], v[94:97], v[24:27]
	ds_read_b128 v[94:97], v69 offset:64512
	ds_read_b128 v[102:105], v69 offset:64576
	ds_read_b128 v[106:109], v70 offset:18432
	s_waitcnt lgkmcnt(3)
	v_mfma_f32_16x16x32_bf16 v[20:23], v[90:93], v[98:101], v[20:23]
	ds_read_b128 v[90:93], v70 offset:18496
	ds_read_b128 v[98:101], v71 offset:18432
	ds_read_b128 v[110:113], v71 offset:18496
	s_waitcnt lgkmcnt(3)
	v_mfma_f32_16x16x32_bf16 v[86:89], v[94:97], v[106:109], v[86:89]
	v_cvt_pk_bf16_f32 v106, v24, v25
	v_cvt_pk_bf16_f32 v107, v26, v27
	ds_write_b64 v75, v[106:107] offset:55296
	s_waitcnt lgkmcnt(2)
	v_mfma_f32_16x16x32_bf16 v[82:85], v[94:97], v[98:101], v[82:85]
	v_cvt_pk_bf16_f32 v94, v20, v21
	v_cvt_pk_bf16_f32 v95, v22, v23
	ds_write_b64 v76, v[94:95] offset:55296
	v_mfma_f32_16x16x32_bf16 v[86:89], v[102:105], v[90:93], v[86:89]
	s_waitcnt lgkmcnt(2)
	v_mfma_f32_16x16x32_bf16 v[82:85], v[102:105], v[110:113], v[82:85]
	s_nop 5
	v_cvt_pk_bf16_f32 v86, v86, v87
	v_cvt_pk_bf16_f32 v87, v88, v89
	v_lshl_add_u64 v[88:89], v[180:181], 1, s[12:13]
	v_lshl_or_b32 v180, v29, 10, v73
	v_cvt_pk_bf16_f32 v82, v82, v83
	v_cvt_pk_bf16_f32 v83, v84, v85
	v_lshl_add_u64 v[84:85], v[180:181], 1, s[12:13]
	global_store_dwordx2 v[88:89], v[86:87], off offset:512 sc1
	global_store_dwordx2 v[84:85], v[82:83], off offset:512 sc1
	s_waitcnt lgkmcnt(0)
	s_barrier
	s_branch .LBB0_558
.LBB0_557:
	s_waitcnt lgkmcnt(0)
	s_barrier
	ds_read_b128 v[82:85], v69 offset:27648
	ds_read_b128 v[86:89], v70 offset:46080
	ds_read_b128 v[90:93], v69 offset:36864
	ds_read_b128 v[94:97], v71 offset:46080
	ds_read_b128 v[98:101], v70 offset:27648
	ds_read_b128 v[102:105], v71 offset:27648
	s_waitcnt lgkmcnt(4)
	v_mfma_f32_16x16x32_bf16 v[86:89], v[82:85], v[86:89], 0
	v_mov_b32_e32 v29, v28
	v_pk_mul_f32 v[26:27], v[28:29], v[26:27]
	v_pk_mul_f32 v[24:25], v[42:43], v[24:25]
	s_waitcnt lgkmcnt(2)
	v_mfma_f32_16x16x32_bf16 v[82:85], v[82:85], v[94:97], 0
	ds_read_b128 v[94:97], v69 offset:27712
	v_pk_mul_f32 v[22:23], v[28:29], v[22:23]
	v_pk_mul_f32 v[20:21], v[42:43], v[20:21]
	s_waitcnt lgkmcnt(2)
	v_mfma_f32_16x16x32_bf16 v[24:27], v[90:93], v[98:101], v[24:27]
	s_and_b64 s[16:17], s[8:9], exec
	s_cselect_b32 s5, s4, s2
	s_add_i32 s5, s5, s1
	s_waitcnt lgkmcnt(1)
	v_mfma_f32_16x16x32_bf16 v[20:23], v[90:93], v[102:105], v[20:23]
	ds_read_b128 v[90:93], v70 offset:46144
	ds_read_b128 v[98:101], v71 offset:46144
	s_sub_i32 s5, s5, 64
	v_add_u32_e32 v29, s5, v72
	s_waitcnt lgkmcnt(1)
	v_mfma_f32_16x16x32_bf16 v[86:89], v[94:97], v[90:93], v[86:89]
	ds_read_b128 v[90:93], v69 offset:36928
	v_lshl_or_b32 v180, v29, 10, v73
	v_add_u32_e32 v29, s5, v74
	s_waitcnt lgkmcnt(1)
	v_mfma_f32_16x16x32_bf16 v[82:85], v[94:97], v[98:101], v[82:85]
	ds_read_b128 v[94:97], v70 offset:27712
	ds_read_b128 v[98:101], v71 offset:27712
	ds_read_b128 v[102:105], v70 offset:18432
	s_add_i32 s0, s0, 2
	s_waitcnt lgkmcnt(2)
	v_mfma_f32_16x16x32_bf16 v[24:27], v[90:93], v[94:97], v[24:27]
	ds_read_b128 v[94:97], v69 offset:64512
	s_addk_i32 s2, 0xff80
	s_addk_i32 s4, 0x80
	s_waitcnt lgkmcnt(2)
	v_mfma_f32_16x16x32_bf16 v[20:23], v[90:93], v[98:101], v[20:23]
	ds_read_b128 v[90:93], v69 offset:64576
	ds_read_b128 v[98:101], v70 offset:18496
	ds_read_b128 v[106:109], v71 offset:18432
	s_and_b64 vcc, exec, s[14:15]
	s_waitcnt lgkmcnt(3)
	v_mfma_f32_16x16x32_bf16 v[86:89], v[94:97], v[102:105], v[86:89]
	ds_read_b128 v[102:105], v71 offset:18496
	s_waitcnt lgkmcnt(1)
	v_mfma_f32_16x16x32_bf16 v[82:85], v[94:97], v[106:109], v[82:85]
	v_cvt_pk_bf16_f32 v94, v24, v25
	v_cvt_pk_bf16_f32 v95, v26, v27
	ds_write_b64 v75, v[94:95] offset:55296
	v_mfma_f32_16x16x32_bf16 v[86:89], v[90:93], v[98:101], v[86:89]
	v_cvt_pk_bf16_f32 v94, v20, v21
	v_cvt_pk_bf16_f32 v95, v22, v23
	ds_write_b64 v76, v[94:95] offset:55296
	s_waitcnt lgkmcnt(2)
	v_mfma_f32_16x16x32_bf16 v[82:85], v[90:93], v[102:105], v[82:85]
	s_nop 2
	v_cvt_pk_bf16_f32 v86, v86, v87
	v_cvt_pk_bf16_f32 v87, v88, v89
	v_lshl_add_u64 v[88:89], v[180:181], 1, s[12:13]
	v_lshl_or_b32 v180, v29, 10, v73
	s_nop 0
	v_cvt_pk_bf16_f32 v82, v82, v83
	v_cvt_pk_bf16_f32 v83, v84, v85
	v_lshl_add_u64 v[84:85], v[180:181], 1, s[12:13]
	global_store_dwordx2 v[88:89], v[86:87], off offset:512 sc1
	global_store_dwordx2 v[84:85], v[82:83], off offset:512 sc1
	s_waitcnt lgkmcnt(0)
	s_barrier
	s_cbranch_vccnz .LBB0_342

.LBB0_562:
	s_waitcnt lgkmcnt(0)
	s_barrier
	ds_read_b128 v[82:85], v69 offset:27648
	ds_read_b128 v[86:89], v70 offset:46080
	ds_read_b128 v[90:93], v69 offset:36864
	ds_read_b128 v[94:97], v71 offset:46080
	ds_read_b128 v[98:101], v70 offset:27648
	ds_read_b128 v[102:105], v71 offset:27648
	s_waitcnt lgkmcnt(4)
	v_mfma_f32_16x16x32_bf16 v[86:89], v[82:85], v[86:89], 0
	v_mov_b32_e32 v29, v28
	v_pk_mul_f32 v[26:27], v[28:29], v[26:27]
	v_pk_mul_f32 v[24:25], v[42:43], v[24:25]
	s_waitcnt lgkmcnt(2)
	v_mfma_f32_16x16x32_bf16 v[82:85], v[82:85], v[94:97], 0
	ds_read_b128 v[94:97], v69 offset:27712
	v_pk_mul_f32 v[22:23], v[28:29], v[22:23]
	v_pk_mul_f32 v[20:21], v[42:43], v[20:21]
	s_waitcnt lgkmcnt(2)
	v_mfma_f32_16x16x32_bf16 v[24:27], v[90:93], v[98:101], v[24:27]
	s_add_i32 s5, s4, 0xffffff80
	s_and_b64 s[18:19], s[8:9], exec
	s_cselect_b32 s5, s5, s2
	s_waitcnt lgkmcnt(1)
	v_mfma_f32_16x16x32_bf16 v[20:23], v[90:93], v[102:105], v[20:23]
	ds_read_b128 v[90:93], v70 offset:46144
	ds_read_b128 v[98:101], v71 offset:46144
	s_add_i32 s5, s5, s1
	v_add_u32_e32 v29, s5, v72
	s_waitcnt lgkmcnt(1)
	v_mfma_f32_16x16x32_bf16 v[86:89], v[94:97], v[90:93], v[86:89]
	ds_read_b128 v[90:93], v69 offset:36928
	v_lshl_or_b32 v180, v29, 10, v73
	v_add_u32_e32 v29, s5, v74
	s_waitcnt lgkmcnt(1)
	v_mfma_f32_16x16x32_bf16 v[82:85], v[94:97], v[98:101], v[82:85]
	ds_read_b128 v[94:97], v70 offset:27712
	ds_read_b128 v[98:101], v71 offset:27712
	ds_read_b128 v[102:105], v70 offset:18432
	s_mov_b32 s5, 0xffff
	s_waitcnt lgkmcnt(2)
	v_mfma_f32_16x16x32_bf16 v[24:27], v[90:93], v[94:97], v[24:27]
	ds_read_b128 v[94:97], v69 offset:55296
	s_andn2_b64 vcc, exec, s[16:17]
	s_waitcnt lgkmcnt(2)
	v_mfma_f32_16x16x32_bf16 v[20:23], v[90:93], v[98:101], v[20:23]
	ds_read_b128 v[90:93], v69 offset:55360
	ds_read_b128 v[98:101], v70 offset:18496
	ds_read_b128 v[106:109], v71 offset:18432
	s_waitcnt lgkmcnt(3)
	v_mfma_f32_16x16x32_bf16 v[86:89], v[94:97], v[102:105], v[86:89]
	ds_read_b128 v[102:105], v71 offset:18496
	s_waitcnt lgkmcnt(1)
	v_mfma_f32_16x16x32_bf16 v[82:85], v[94:97], v[106:109], v[82:85]
	v_cvt_pk_bf16_f32 v94, v24, v25
	v_cvt_pk_bf16_f32 v95, v26, v27
	ds_write_b64 v75, v[94:95] offset:64512
	v_mfma_f32_16x16x32_bf16 v[86:89], v[90:93], v[98:101], v[86:89]
	v_cvt_pk_bf16_f32 v94, v20, v21
	v_cvt_pk_bf16_f32 v95, v22, v23
	ds_write_b64 v76, v[94:95] offset:64512
	s_waitcnt lgkmcnt(2)
	v_mfma_f32_16x16x32_bf16 v[82:85], v[90:93], v[102:105], v[82:85]
	s_nop 2
	v_cvt_pk_bf16_f32 v86, v86, v87
	v_cvt_pk_bf16_f32 v87, v88, v89
	v_lshl_add_u64 v[88:89], v[180:181], 1, s[12:13]
	v_lshl_or_b32 v180, v29, 10, v73
	s_nop 0
	v_cvt_pk_bf16_f32 v82, v82, v83
	v_cvt_pk_bf16_f32 v83, v84, v85
	v_lshl_add_u64 v[84:85], v[180:181], 1, s[12:13]
	global_store_dwordx2 v[88:89], v[86:87], off offset:512 sc1
	global_store_dwordx2 v[84:85], v[82:83], off offset:512 sc1
	s_waitcnt vmcnt(9)
	v_lshlrev_b32_e32 v82, 16, v12
	v_and_b32_e32 v83, 0xffff0000, v12
	v_lshlrev_b32_e32 v84, 16, v13
	v_and_b32_e32 v85, 0xffff0000, v13
	v_pk_mul_f32 v[82:83], v[30:31], v[82:83]
	v_pk_mul_f32 v[84:85], v[30:31], v[84:85]
	v_cvt_pk_bf16_f32 v82, v82, v83
	v_cvt_pk_bf16_f32 v83, v84, v85
	v_lshlrev_b32_e32 v84, 16, v14
	v_and_b32_e32 v85, 0xffff0000, v14
	v_lshlrev_b32_e32 v86, 16, v15
	v_and_b32_e32 v87, 0xffff0000, v15
	v_pk_mul_f32 v[84:85], v[30:31], v[84:85]
	v_pk_mul_f32 v[86:87], v[30:31], v[86:87]
	v_cvt_pk_bf16_f32 v84, v84, v85
	v_cvt_pk_bf16_f32 v85, v86, v87
	s_waitcnt lgkmcnt(0)
	s_barrier
	ds_write_b128 v62, v[12:15]
	s_waitcnt vmcnt(8)
	ds_write_b128 v62, v[16:19] offset:9216
	ds_write_b128 v62, v[82:85] offset:18432
	s_waitcnt vmcnt(5)
	v_lshlrev_b32_e32 v83, 16, v56
	s_waitcnt vmcnt(4)
	v_lshlrev_b32_e32 v82, 16, v58
	v_pk_mul_f32 v[82:83], v[32:33], v[82:83]
	v_lshlrev_b32_e32 v29, 16, v54
	v_cvt_pk_bf16_f32 v81, v82, v83
	v_lshrrev_b32_e32 v82, 16, v52
	v_and_or_b32 v29, v52, s5, v29
	v_and_or_b32 v82, v54, s60, v82
	ds_write2_b32 v63, v29, v82 offset1:36
	v_and_b32_e32 v83, 0xffff0000, v56
	v_and_b32_e32 v82, 0xffff0000, v58
	v_pk_mul_f32 v[82:83], v[32:33], v[82:83]
	s_nop 0
	v_cvt_pk_bf16_f32 v29, v82, v83
	v_lshlrev_b32_e32 v83, 16, v57
	v_lshlrev_b32_e32 v82, 16, v59
	v_pk_mul_f32 v[82:83], v[32:33], v[82:83]
	ds_write2_b32 v64, v81, v29 offset1:36
	v_lshlrev_b32_e32 v29, 16, v55
	v_cvt_pk_bf16_f32 v81, v82, v83
	v_lshrrev_b32_e32 v82, 16, v53
	v_and_or_b32 v29, v53, s5, v29
	v_and_or_b32 v82, v55, s60, v82
	ds_write2_b32 v63, v29, v82 offset0:72 offset1:108
	v_and_b32_e32 v83, 0xffff0000, v57
	v_and_b32_e32 v82, 0xffff0000, v59
	v_pk_mul_f32 v[82:83], v[32:33], v[82:83]
	s_nop 0
	v_cvt_pk_bf16_f32 v29, v82, v83
	ds_write2_b32 v64, v81, v29 offset0:72 offset1:108
	s_waitcnt lgkmcnt(0)
	s_barrier
	s_cbranch_vccnz .LBB0_564
	s_add_i32 s5, s4, 64
	s_add_i32 s18, s2, 0xffffff40
	s_and_b64 s[16:17], s[8:9], exec
	s_cselect_b32 s5, s5, s18
	s_add_i32 s5, s5, s1
	v_add_u32_e32 v12, s5, v60
	v_add_u32_e32 v29, s5, v67
	v_mul_u32_u24_e32 v12, 0xe00, v12
	v_mad_u32_u24 v52, v29, s63, v61
	v_or_b32_e32 v12, v12, v77
	v_ashrrev_i32_e32 v53, 31, v52
	v_ashrrev_i32_e32 v13, 31, v12
	v_lshl_add_u64 v[58:59], v[52:53], 1, s[82:83]
	v_lshl_add_u64 v[16:17], v[12:13], 1, s[82:83]
	v_lshl_add_u64 v[56:57], s[10:11], 1, v[58:59]
	global_load_dwordx4 v[12:15], v[16:17], off offset:2560
	s_nop 0
	global_load_dwordx4 v[16:19], v[16:17], off offset:3072
	s_nop 0
	global_load_dwordx2 v[52:53], v[58:59], off offset:3584
	global_load_dwordx2 v[54:55], v[56:57], off offset:3584
	s_nop 0
	global_load_dwordx2 v[56:57], v[56:57], off offset:3072
	s_nop 0
	global_load_dwordx2 v[58:59], v[58:59], off offset:3072

.LBB0_574:
	s_or_b64 exec, exec, s[8:9]
	s_waitcnt lgkmcnt(0)
	v_add_u32_e32 v40, v45, v46
	ds_read_b128 v[36:39], v40 offset:11776
	ds_read_b128 v[44:47], v40 offset:9216
	ds_read_b128 v[48:51], v40 offset:13056
	ds_read_b128 v[52:55], v40 offset:10496
	s_waitcnt lgkmcnt(0)
	s_waitcnt lgkmcnt(2)
	v_mfma_f32_16x16x32_bf16 v[56:59], v[36:39], v[44:47], 0
	s_lshl_b32 s0, s26, 6
	s_and_b32 s0, s0, 0x1c0
	s_addk_i32 s0, 0x900
	s_waitcnt lgkmcnt(0)
	v_mfma_f32_16x16x32_bf16 v[36:39], v[36:39], v[52:55], 0
	s_nop 2
	v_xor_b32_e32 v41, 0x80000000, v56
	v_xor_b32_e32 v40, 0x80000000, v57
	v_cvt_pk_bf16_f32 v40, v41, v40
	v_xor_b32_e32 v41, 0x80000000, v58
	v_xor_b32_e32 v42, 0x80000000, v59
	v_xor_b32_e32 v37, 0x80000000, v37
	v_xor_b32_e32 v36, 0x80000000, v36
	v_cvt_pk_bf16_f32 v56, v36, v37
	v_xor_b32_e32 v36, 0x80000000, v38
	v_xor_b32_e32 v37, 0x80000000, v39
	v_cvt_pk_bf16_f32 v57, v36, v37
	v_mfma_f32_16x16x32_bf16 v[36:39], v[48:51], v[44:47], 0
	v_cvt_pk_bf16_f32 v41, v41, v42
	v_add_u32_e32 v42, v89, v43
	v_add_u32_e32 v43, v88, v43
	s_nop 4
	v_xor_b32_e32 v37, 0x80000000, v37
	v_xor_b32_e32 v36, 0x80000000, v36
	v_cvt_pk_bf16_f32 v36, v36, v37
	v_xor_b32_e32 v37, 0x80000000, v38
	v_xor_b32_e32 v38, 0x80000000, v39
	v_cvt_pk_bf16_f32 v37, v37, v38
	v_add_u32_e32 v38, 0x1000, v42
	ds_write2_b64 v38, v[40:41], v[36:37] offset0:64 offset1:68
	v_mfma_f32_16x16x32_bf16 v[36:39], v[48:51], v[52:55], 0
	v_add_u32_e32 v41, s27, v83
	s_nop 6
	v_xor_b32_e32 v37, 0x80000000, v37
	v_xor_b32_e32 v36, 0x80000000, v36
	v_cvt_pk_bf16_f32 v36, v36, v37
	v_xor_b32_e32 v37, 0x80000000, v38
	v_xor_b32_e32 v38, 0x80000000, v39
	v_cvt_pk_bf16_f32 v37, v37, v38
	v_add_u32_e32 v38, 0x1000, v43
	ds_write2_b64 v38, v[56:57], v[36:37] offset0:64 offset1:68
	v_and_b32_e32 v36, 7, v78
	v_lshlrev_b32_e32 v44, 4, v36
	s_waitcnt lgkmcnt(0)
	v_lshl_or_b32 v40, v36, 3, s0
	v_add_u32_e32 v36, v87, v44
	ds_read_b128 v[36:39], v36
	s_movk_i32 s0, 0xe00
	v_mad_u64_u32 v[40:41], s[0:1], v41, s0, v[40:41]
	v_mov_b32_e32 v41, v181
	v_lshl_add_u64 v[42:43], v[40:41], 1, s[16:17]
	s_waitcnt lgkmcnt(0)
	global_store_dwordx4 v[42:43], v[36:39], off sc1
	v_add_u32_e32 v180, 0x7000, v40
	v_lshl_add_u64 v[42:43], v[180:181], 1, s[16:17]
	v_add_u32_e32 v36, v86, v44
	ds_read_b128 v[36:39], v36
	v_add_u32_e32 v180, 0xe000, v40
	s_waitcnt lgkmcnt(0)
	global_store_dwordx4 v[42:43], v[36:39], off sc1
	s_nop 1
	v_add_u32_e32 v36, v85, v44
	ds_read_b128 v[36:39], v36
	v_lshl_add_u64 v[42:43], v[180:181], 1, s[16:17]
	v_add_u32_e32 v180, 0x15000, v40
	s_waitcnt lgkmcnt(0)
	global_store_dwordx4 v[42:43], v[36:39], off sc1
	s_nop 1
	v_add_u32_e32 v36, v84, v44
	ds_read_b128 v[36:39], v36
	v_lshl_add_u64 v[42:43], v[180:181], 1, s[16:17]
	v_add_u32_e32 v180, 0x1c000, v40
	s_waitcnt lgkmcnt(0)
	global_store_dwordx4 v[42:43], v[36:39], off sc1
	s_nop 1
	v_add_u32_e32 v36, v82, v44
	ds_read_b128 v[36:39], v36
	v_lshl_add_u64 v[42:43], v[180:181], 1, s[16:17]
	v_add_u32_e32 v180, 0x23000, v40
	s_waitcnt lgkmcnt(0)
	global_store_dwordx4 v[42:43], v[36:39], off sc1
	s_nop 1
	v_add_u32_e32 v36, v81, v44
	ds_read_b128 v[36:39], v36
	v_lshl_add_u64 v[42:43], v[180:181], 1, s[16:17]
	v_add_u32_e32 v180, 0x2a000, v40
	s_waitcnt lgkmcnt(0)
	global_store_dwordx4 v[42:43], v[36:39], off sc1
	s_nop 1
	v_add_u32_e32 v36, v80, v44
	ds_read_b128 v[36:39], v36
	v_lshl_add_u64 v[42:43], v[180:181], 1, s[16:17]
	v_add_u32_e32 v180, 0x31000, v40
	v_lshl_add_u64 v[40:41], v[180:181], 1, s[16:17]
	s_waitcnt lgkmcnt(0)
	global_store_dwordx4 v[42:43], v[36:39], off sc1
	s_nop 1
	v_add_u32_e32 v36, v79, v44
	ds_read_b128 v[36:39], v36
	s_waitcnt lgkmcnt(0)
	global_store_dwordx4 v[40:41], v[36:39], off sc1
	s_waitcnt lgkmcnt(0)

.LBB0_584:
	v_and_b32_e32 v69, 64, v238
	v_add_u32_e32 v70, -1, v238
	v_cmp_lt_i32_e32 vcc, v70, v69
	v_bfe_u32 v123, v120, 3, 3
	v_lshlrev_b32_e32 v68, 4, v120
	v_cndmask_b32_e32 v70, v70, v238, vcc
	v_lshlrev_b32_e32 v114, 2, v70
	s_waitcnt vmcnt(19)
	ds_bpermute_b32 v70, v114, v110
	v_mov_b32_e32 v106, s35
	v_and_b32_e32 v68, 0x70, v68
	v_mad_u32_u24 v129, v123, s61, v106
	v_and_b32_e32 v135, 63, v120
	v_add_u32_e32 v71, v129, v68
	s_waitcnt vmcnt(10)
	ds_write_b128 v71, v[20:23]
	s_waitcnt lgkmcnt(0)
	v_add_f32_e32 v70, v110, v70
	v_cmp_eq_u32_e32 vcc, 0, v135
	v_add_u32_e32 v71, -2, v238
	v_add_u32_e32 v128, 0x480, v129
	v_cndmask_b32_e32 v70, v70, v110, vcc
	v_cmp_lt_i32_e32 vcc, v71, v69
	v_add_u32_e32 v72, v128, v68
	v_add_u32_e32 v127, 0x900, v129
	v_cndmask_b32_e32 v71, v71, v238, vcc
	v_lshlrev_b32_e32 v115, 2, v71
	ds_bpermute_b32 v71, v115, v70
	v_cmp_gt_u32_e32 vcc, 2, v135
	ds_write_b128 v72, v[16:19]
	v_add_u32_e32 v72, v127, v68
	v_add_u32_e32 v126, 0xd80, v129
	s_waitcnt lgkmcnt(1)
	v_add_f32_e32 v71, v70, v71
	v_cndmask_b32_e32 v70, v71, v70, vcc
	v_add_u32_e32 v71, -4, v238
	v_cmp_lt_i32_e32 vcc, v71, v69
	ds_write_b128 v72, v[32:35]
	v_add_u32_e32 v72, v126, v68
	v_cndmask_b32_e32 v71, v71, v238, vcc
	v_lshlrev_b32_e32 v116, 2, v71
	ds_bpermute_b32 v71, v116, v70
	v_cmp_gt_u32_e32 vcc, 4, v135
	v_add_u32_e32 v125, 0x1200, v129
	ds_write_b128 v72, v[12:15]
	v_add_u32_e32 v72, v125, v68
	s_waitcnt lgkmcnt(1)
	v_add_f32_e32 v71, v70, v71
	v_cndmask_b32_e32 v70, v71, v70, vcc
	v_add_u32_e32 v71, -8, v238
	v_cmp_lt_i32_e32 vcc, v71, v69
	v_add_u32_e32 v124, 0x1680, v129
	ds_write_b128 v72, v[28:31]
	v_cndmask_b32_e32 v71, v71, v238, vcc
	v_lshlrev_b32_e32 v117, 2, v71
	ds_bpermute_b32 v71, v117, v70
	v_cmp_gt_u32_e32 vcc, 8, v135
	v_add_u32_e32 v72, v124, v68
	v_add_u32_e32 v122, 0x1b00, v129
	v_add_u32_e32 v121, 0x1f80, v129
	s_waitcnt lgkmcnt(0)
	v_add_f32_e32 v71, v70, v71
	v_cndmask_b32_e32 v70, v71, v70, vcc
	v_add_u32_e32 v71, -16, v238
	v_cmp_lt_i32_e32 vcc, v71, v69
	ds_write_b128 v72, v[8:11]
	v_add_u32_e32 v72, v122, v68
	v_cndmask_b32_e32 v71, v71, v238, vcc
	v_lshlrev_b32_e32 v118, 2, v71
	ds_bpermute_b32 v71, v118, v70
	v_cmp_gt_u32_e32 vcc, 16, v135
	v_add_u32_e32 v68, v121, v68
	s_and_b32 s0, s38, 1
	ds_write_b128 v68, v[4:7]
	s_waitcnt lgkmcnt(1)
	v_add_f32_e32 v71, v70, v71
	v_cndmask_b32_e32 v70, v71, v70, vcc
	v_subrev_u32_e32 v71, 32, v238
	v_cmp_lt_i32_e32 vcc, v71, v69
	v_cmp_gt_u32_e64 s[8:9], 32, v135
	s_lshl_b32 s2, s0, 2
	v_cndmask_b32_e32 v69, v71, v238, vcc
	v_lshlrev_b32_e32 v119, 2, v69
	ds_bpermute_b32 v69, v119, v70
	s_lshr_b32 s1, s38, 1
	v_and_b32_e32 v132, 15, v120
	ds_write_b128 v72, v[24:27]
	v_and_b32_e32 v134, 48, v120
	s_waitcnt lgkmcnt(1)
	v_add_f32_e32 v68, v70, v69
	v_cndmask_b32_e64 v70, v68, v70, s[8:9]
	v_add_u32_e32 v68, s39, v135
	v_lshl_or_b32 v68, v68, 4, s2
	v_and_or_b32 v180, s1, 3, v68
	v_lshl_add_u64 v[68:69], v[180:181], 2, s[20:21]
	global_store_dword v[68:69], v70, off sc1
	v_lshl_add_u32 v68, v135, 2, s35
	ds_write2st64_b32 v68, v70, v111 offset0:56 offset1:57
	v_mad_u32_u24 v133, v132, s61, v106
	v_bfe_u32 v131, v120, 4, 2
	s_waitcnt lgkmcnt(0)
	v_add_u32_e32 v68, v133, v134
	ds_read_b128 v[96:99], v68
	ds_read_b128 v[92:95], v68 offset:64
	s_cmp_eq_u32 s0, 0
	v_lshlrev_b32_e32 v151, 2, v131
	v_add_u32_e32 v130, 0x900, v133
	v_bitop3_b32 v100, v120, 63, 15 bitop3:0x6c
	s_cselect_b64 s[10:11], -1, 0
	v_xor_b32_e32 v108, 60, v151
	v_add_u32_e32 v68, v130, v134
	v_cndmask_b32_e64 v107, v100, v132, s[10:11]
	v_cndmask_b32_e64 v136, v108, v151, s[10:11]
	ds_read_b128 v[88:91], v68
	ds_read_b128 v[84:87], v68 offset:64
	ds_read_b128 v[80:83], v68 offset:2304
	ds_read_b128 v[76:79], v68 offset:2368
	ds_read_b128 v[72:75], v68 offset:4608
	ds_read_b128 v[68:71], v68 offset:4672
	s_waitcnt lgkmcnt(0)
	v_lshl_add_u32 v100, v107, 2, s35
	v_lshlrev_b32_e32 v137, 2, v136
	ds_read2st64_b32 v[104:105], v100 offset0:56 offset1:57
	s_waitcnt lgkmcnt(8)
	v_mfma_f32_16x16x32_bf16 v[100:103], v[96:99], v[96:99], 0
	v_add_u32_e32 v139, s35, v137
	ds_read_b128 v[140:143], v139 offset:14336
	v_mad_u32_u24 v152, v107, s61, v106
	s_waitcnt lgkmcnt(8)
	v_mfma_f32_16x16x32_bf16 v[100:103], v[92:95], v[92:95], v[100:103]
	s_waitcnt lgkmcnt(1)
	v_mov_b32_e32 v150, v105
	v_and_b32_e32 v106, 0x70, v137
	s_waitcnt lgkmcnt(0)
	v_sub_f32_e32 v138, v104, v142
	v_sub_f32_e32 v108, v104, v140
	v_sub_f32_e32 v109, v104, v141
	v_mul_f32_e32 v138, 0x3fb8aa3b, v138
	v_mul_f32_e32 v108, 0x3fb8aa3b, v108
	v_mul_f32_e32 v109, 0x3fb8aa3b, v109
	v_exp_f32_e32 v140, v138
	v_sub_f32_e32 v138, v104, v143
	v_pk_mov_b32 v[142:143], v[102:103], v[102:103] op_sel:[1,0]
	v_exp_f32_e32 v108, v108
	v_exp_f32_e32 v109, v109
	v_mul_f32_e32 v138, 0x3fb8aa3b, v138
	v_pk_mov_b32 v[144:145], v[100:101], v[100:101] op_sel:[1,0]
	v_cndmask_b32_e64 v101, v143, v101, s[10:11]
	v_cndmask_b32_e64 v100, v142, v100, s[10:11]
	v_exp_f32_e32 v141, v138
	v_cndmask_b32_e64 v103, v145, v103, s[10:11]
	v_cndmask_b32_e64 v102, v144, v102, s[10:11]
	v_or_b32_e32 v138, 1, v136
	v_pk_mul_f32 v[142:143], v[150:151], v[100:101] op_sel_hi:[0,1]
	v_pk_mul_f32 v[102:103], v[150:151], v[102:103] op_sel_hi:[0,1]
	v_pk_mul_f32 v[108:109], v[108:109], v[142:143]
	v_cmp_lt_u32_e32 vcc, v138, v107
	v_or_b32_e32 v101, 3, v136
	v_pk_mul_f32 v[102:103], v[102:103], v[140:141]
	v_cndmask_b32_e32 v141, 0, v109, vcc
	v_cmp_lt_u32_e32 vcc, v136, v107
	v_or_b32_e32 v100, 2, v136
	s_bitcmp1_b32 s38, 0
	v_cndmask_b32_e32 v140, 0, v108, vcc
	v_cmp_lt_u32_e32 vcc, v101, v107
	s_cselect_b64 s[26:27], -1, 0
	s_xor_b64 s[24:25], s[26:27], -1
	v_cndmask_b32_e32 v143, 0, v103, vcc
	v_cmp_lt_u32_e32 vcc, v100, v107
	v_bitop3_b32 v103, v151, 60, 16 bitop3:0x36
	v_cmp_lt_u32_e64 s[6:7], 31, v135
	v_cndmask_b32_e32 v142, 0, v102, vcc
	v_add_u32_e32 v102, v152, v106
	ds_write_b128 v102, v[140:143]
	v_or_b32_e32 v102, 16, v151
	v_cndmask_b32_e64 v137, v103, v102, s[10:11]
	v_lshlrev_b32_e32 v153, 2, v137
	v_add_u32_e32 v140, s35, v153
	ds_read_b128 v[146:149], v140 offset:14336
	v_mfma_f32_16x16x32_bf16 v[142:145], v[88:91], v[96:99], 0
	v_or_b32_e32 v141, 1, v137
	v_cmp_lt_u32_e32 vcc, v141, v107
	s_movk_i32 s2, 0x50
	s_waitcnt lgkmcnt(0)
	v_sub_f32_e32 v102, v104, v146
	v_mul_f32_e32 v102, 0x3fb8aa3b, v102
	v_exp_f32_e32 v108, v102
	v_sub_f32_e32 v102, v104, v147
	v_mul_f32_e32 v102, 0x3fb8aa3b, v102
	v_mfma_f32_16x16x32_bf16 v[142:145], v[84:87], v[92:95], v[142:145]
	v_exp_f32_e32 v109, v102
	v_sub_f32_e32 v102, v104, v148
	v_mul_f32_e32 v102, 0x3fb8aa3b, v102
	v_exp_f32_e32 v146, v102
	v_sub_f32_e32 v102, v104, v149
	v_mul_f32_e32 v102, 0x3fb8aa3b, v102
	v_exp_f32_e32 v147, v102
	s_nop 0
	v_pk_mov_b32 v[102:103], v[144:145], v[144:145] op_sel:[1,0]
	v_pk_mov_b32 v[148:149], v[142:143], v[142:143] op_sel:[1,0]
	v_cndmask_b32_e64 v103, v103, v143, s[10:11]
	v_cndmask_b32_e64 v102, v102, v142, s[10:11]
	v_pk_mul_f32 v[142:143], v[150:151], v[102:103] op_sel_hi:[0,1]
	v_cndmask_b32_e64 v145, v149, v145, s[10:11]
	v_cndmask_b32_e64 v144, v148, v144, s[10:11]
	v_pk_mul_f32 v[108:109], v[108:109], v[142:143]
	v_or_b32_e32 v103, 3, v137
	v_pk_mul_f32 v[144:145], v[150:151], v[144:145] op_sel_hi:[0,1]
	v_cndmask_b32_e32 v143, 0, v109, vcc
	v_cmp_lt_u32_e32 vcc, v137, v107
	v_or_b32_e32 v102, 2, v137
	v_pk_mul_f32 v[144:145], v[144:145], v[146:147]
	v_cndmask_b32_e32 v142, 0, v108, vcc
	v_cmp_lt_u32_e32 vcc, v103, v107
	v_and_b32_e32 v108, 0x70, v153
	v_add_u32_e32 v109, v152, v108
	v_cndmask_b32_e32 v145, 0, v145, vcc
	v_cmp_lt_u32_e32 vcc, v102, v107
	s_nop 1
	v_cndmask_b32_e32 v144, 0, v144, vcc
	ds_write_b128 v109, v[142:145]
	v_or_b32_e32 v109, 32, v151
	v_or_b32_e32 v142, 48, v151
	s_and_b64 vcc, exec, s[24:25]
	v_sub_u32_e32 v144, 60, v109
	v_sub_u32_e32 v143, 60, v142
	s_cbranch_vccnz .LBB0_586
	v_mfma_f32_16x16x32_bf16 v[146:149], v[80:83], v[96:99], 0
	v_cndmask_b32_e64 v145, v144, v109, s[10:11]
	v_lshl_add_u32 v150, v145, 2, s35
	ds_read_b128 v[150:153], v150 offset:14336
	v_mfma_f32_16x16x32_bf16 v[146:149], v[76:79], v[92:95], v[146:149]
	v_mov_b32_e32 v154, v105
	v_mov_b32_e32 v155, v105
	v_cmp_lt_u32_e32 vcc, v145, v107
	s_waitcnt lgkmcnt(0)
	v_sub_f32_e32 v150, v104, v150
	v_sub_f32_e32 v151, v104, v151
	s_nop 1
	v_pk_mov_b32 v[156:157], v[148:149], v[148:149] op_sel:[1,0]
	v_mul_f32_e32 v150, 0x3fb8aa3b, v150
	v_mul_f32_e32 v151, 0x3fb8aa3b, v151
	v_pk_mov_b32 v[158:159], v[146:147], v[146:147] op_sel:[1,0]
	v_cndmask_b32_e64 v147, v157, v147, s[10:11]
	v_cndmask_b32_e64 v146, v156, v146, s[10:11]
	v_exp_f32_e32 v150, v150
	v_exp_f32_e32 v151, v151
	v_pk_mul_f32 v[146:147], v[154:155], v[146:147]
	v_sub_f32_e32 v152, v104, v152
	v_sub_f32_e32 v153, v104, v153
	v_mul_f32_e32 v152, 0x3fb8aa3b, v152
	v_pk_mul_f32 v[146:147], v[150:151], v[146:147]
	v_mul_f32_e32 v153, 0x3fb8aa3b, v153
	v_cndmask_b32_e64 v149, v159, v149, s[10:11]
	v_cndmask_b32_e64 v148, v158, v148, s[10:11]
	v_or_b32_e32 v156, 1, v145
	v_cvt_pk_bf16_f32 v146, v146, v147
	v_exp_f32_e32 v152, v152
	v_exp_f32_e32 v153, v153
	v_pk_mul_f32 v[148:149], v[154:155], v[148:149]
	v_cndmask_b32_e32 v147, 0, v146, vcc
	v_lshrrev_b32_e32 v146, 16, v146
	v_cmp_lt_u32_e32 vcc, v156, v107
	v_or_b32_e32 v151, 2, v145
	v_pk_mul_f32 v[148:149], v[148:149], v[152:153]
	v_cndmask_b32_e32 v146, 0, v146, vcc
	v_or_b32_e32 v150, 3, v145
	v_perm_b32 v146, v146, v147, s93
	v_cvt_pk_bf16_f32 v147, v148, v149
	v_cmp_lt_u32_e32 vcc, v151, v107
	v_mov_b32_e32 v105, s35
	v_mad_u32_u24 v158, v107, s2, v105
	v_cndmask_b32_e32 v148, 0, v147, vcc
	v_lshrrev_b32_e32 v147, 16, v147
	v_cmp_lt_u32_e32 vcc, v150, v107
	v_lshl_add_u32 v105, v145, 1, v158
	v_cndmask_b32_e64 v145, v143, v142, s[10:11]
	v_cndmask_b32_e32 v147, 0, v147, vcc
	v_perm_b32 v147, v147, v148, s93
	ds_write_b64 v105, v[146:147] offset:6656
	v_lshl_add_u32 v105, v145, 2, s35
	ds_read_b128 v[150:153], v105 offset:14336
	v_mfma_f32_16x16x32_bf16 v[146:149], v[72:75], v[96:99], 0
	v_cmp_lt_u32_e64 s[14:15], v145, v107
	s_waitcnt lgkmcnt(0)
	v_sub_f32_e32 v105, v104, v150
	v_mul_f32_e32 v105, 0x3fb8aa3b, v105
	v_mfma_f32_16x16x32_bf16 v[146:149], v[68:71], v[92:95], v[146:149]
	v_exp_f32_e32 v150, v105
	v_sub_f32_e32 v105, v104, v151
	v_mul_f32_e32 v105, 0x3fb8aa3b, v105
	v_exp_f32_e32 v151, v105
	v_sub_f32_e32 v105, v104, v152
	v_sub_f32_e32 v104, v104, v153
	v_mul_f32_e32 v105, 0x3fb8aa3b, v105
	v_mul_f32_e32 v104, 0x3fb8aa3b, v104
	v_exp_f32_e32 v152, v105
	v_exp_f32_e32 v153, v104
	v_pk_mov_b32 v[104:105], v[148:149], v[148:149] op_sel:[1,0]
	v_pk_mov_b32 v[156:157], v[146:147], v[146:147] op_sel:[1,0]
	v_cndmask_b32_e64 v105, v105, v147, s[10:11]
	v_cndmask_b32_e64 v104, v104, v146, s[10:11]
	v_or_b32_e32 v146, 1, v145
	v_pk_mul_f32 v[104:105], v[154:155], v[104:105]
	v_cndmask_b32_e64 v149, v157, v149, s[10:11]
	v_cndmask_b32_e64 v148, v156, v148, s[10:11]
	v_cmp_lt_u32_e32 vcc, v146, v107
	v_pk_mul_f32 v[104:105], v[150:151], v[104:105]
	v_or_b32_e32 v146, 3, v145
	v_cmp_lt_u32_e64 s[12:13], v146, v107
	v_pk_mul_f32 v[146:147], v[154:155], v[148:149]
	v_cvt_pk_bf16_f32 v104, v104, v105
	v_or_b32_e32 v150, 2, v145
	v_pk_mul_f32 v[146:147], v[146:147], v[152:153]
	v_cndmask_b32_e64 v105, 0, v104, s[14:15]
	v_cndmask_b32_sdwa v104, v181, v104, vcc dst_sel:DWORD dst_unused:UNUSED_PAD src0_sel:DWORD src1_sel:WORD_1
	v_perm_b32 v104, v104, v105, s93
	v_cvt_pk_bf16_f32 v105, v146, v147
	v_cmp_lt_u32_e32 vcc, v150, v107
	s_nop 1
	v_cndmask_b32_e32 v107, 0, v105, vcc
	s_mov_b64 vcc, s[12:13]
	v_cndmask_b32_sdwa v105, v181, v105, vcc dst_sel:DWORD dst_unused:UNUSED_PAD src0_sel:DWORD src1_sel:WORD_1
	v_perm_b32 v105, v105, v107, s93
	v_lshl_add_u32 v107, v145, 1, v158
	ds_write_b64 v107, v[104:105] offset:6656

.LBB0_598:
	s_or_b64 exec, exec, s[8:9]
	s_waitcnt lgkmcnt(0)
	v_add_u32_e32 v72, v77, v78
	ds_read_b128 v[68:71], v72 offset:11776
	ds_read_b128 v[76:79], v72 offset:9216
	ds_read_b128 v[80:83], v72 offset:13056
	ds_read_b128 v[84:87], v72 offset:10496
	s_waitcnt lgkmcnt(0)
	s_waitcnt lgkmcnt(2)
	v_mfma_f32_16x16x32_bf16 v[88:91], v[68:71], v[76:79], 0
	s_lshl_b32 s0, s38, 6
	s_and_b32 s0, s0, 0x1c0
	s_addk_i32 s0, 0x900
	s_waitcnt lgkmcnt(0)
	v_mfma_f32_16x16x32_bf16 v[68:71], v[68:71], v[84:87], 0
	s_nop 2
	v_xor_b32_e32 v73, 0x80000000, v88
	v_xor_b32_e32 v72, 0x80000000, v89
	v_cvt_pk_bf16_f32 v72, v73, v72
	v_xor_b32_e32 v73, 0x80000000, v90
	v_xor_b32_e32 v74, 0x80000000, v91
	v_xor_b32_e32 v69, 0x80000000, v69
	v_xor_b32_e32 v68, 0x80000000, v68
	v_cvt_pk_bf16_f32 v88, v68, v69
	v_xor_b32_e32 v68, 0x80000000, v70
	v_xor_b32_e32 v69, 0x80000000, v71
	v_cvt_pk_bf16_f32 v89, v68, v69
	v_mfma_f32_16x16x32_bf16 v[68:71], v[80:83], v[76:79], 0
	v_cvt_pk_bf16_f32 v73, v73, v74
	v_add_u32_e32 v74, v133, v75
	v_add_u32_e32 v75, v130, v75
	s_andn2_b64 vcc, exec, s[22:23]
	s_nop 3
	v_xor_b32_e32 v69, 0x80000000, v69
	v_xor_b32_e32 v68, 0x80000000, v68
	v_cvt_pk_bf16_f32 v68, v68, v69
	v_xor_b32_e32 v69, 0x80000000, v70
	v_xor_b32_e32 v70, 0x80000000, v71
	v_cvt_pk_bf16_f32 v69, v69, v70
	v_add_u32_e32 v70, 0x1000, v74
	ds_write2_b64 v70, v[72:73], v[68:69] offset0:64 offset1:68
	v_mfma_f32_16x16x32_bf16 v[68:71], v[80:83], v[84:87], 0
	v_add_u32_e32 v73, s39, v123
	s_nop 6
	v_xor_b32_e32 v69, 0x80000000, v69
	v_xor_b32_e32 v68, 0x80000000, v68
	v_cvt_pk_bf16_f32 v68, v68, v69
	v_xor_b32_e32 v69, 0x80000000, v70
	v_xor_b32_e32 v70, 0x80000000, v71
	v_cvt_pk_bf16_f32 v69, v69, v70
	v_add_u32_e32 v70, 0x1000, v75
	ds_write2_b64 v70, v[88:89], v[68:69] offset0:64 offset1:68
	v_and_b32_e32 v68, 7, v120
	v_lshlrev_b32_e32 v76, 4, v68
	s_waitcnt lgkmcnt(0)
	v_lshl_or_b32 v72, v68, 3, s0
	v_add_u32_e32 v68, v129, v76
	ds_read_b128 v[68:71], v68
	s_movk_i32 s0, 0xe00
	v_mad_u64_u32 v[72:73], s[0:1], v73, s0, v[72:73]
	v_mov_b32_e32 v73, v181
	v_lshl_add_u64 v[74:75], v[72:73], 1, s[16:17]
	s_waitcnt lgkmcnt(0)
	global_store_dwordx4 v[74:75], v[68:71], off sc1
	v_add_u32_e32 v180, 0x7000, v72
	v_lshl_add_u64 v[74:75], v[180:181], 1, s[16:17]
	v_add_u32_e32 v68, v128, v76
	ds_read_b128 v[68:71], v68
	v_add_u32_e32 v180, 0xe000, v72
	s_waitcnt lgkmcnt(0)
	global_store_dwordx4 v[74:75], v[68:71], off sc1
	s_nop 1
	v_add_u32_e32 v68, v127, v76
	ds_read_b128 v[68:71], v68
	v_lshl_add_u64 v[74:75], v[180:181], 1, s[16:17]
	v_add_u32_e32 v180, 0x15000, v72
	s_waitcnt lgkmcnt(0)
	global_store_dwordx4 v[74:75], v[68:71], off sc1
	s_nop 1
	v_add_u32_e32 v68, v126, v76
	ds_read_b128 v[68:71], v68
	v_lshl_add_u64 v[74:75], v[180:181], 1, s[16:17]
	v_add_u32_e32 v180, 0x1c000, v72
	s_waitcnt lgkmcnt(0)
	global_store_dwordx4 v[74:75], v[68:71], off sc1
	s_nop 1
	v_add_u32_e32 v68, v125, v76
	ds_read_b128 v[68:71], v68
	v_lshl_add_u64 v[74:75], v[180:181], 1, s[16:17]
	v_add_u32_e32 v180, 0x23000, v72
	s_waitcnt lgkmcnt(0)
	global_store_dwordx4 v[74:75], v[68:71], off sc1
	s_nop 1
	v_add_u32_e32 v68, v124, v76
	ds_read_b128 v[68:71], v68
	v_lshl_add_u64 v[74:75], v[180:181], 1, s[16:17]
	v_add_u32_e32 v180, 0x2a000, v72
	s_waitcnt lgkmcnt(0)
	global_store_dwordx4 v[74:75], v[68:71], off sc1
	s_nop 1
	v_add_u32_e32 v68, v122, v76
	ds_read_b128 v[68:71], v68
	v_lshl_add_u64 v[74:75], v[180:181], 1, s[16:17]
	v_add_u32_e32 v180, 0x31000, v72
	v_lshl_add_u64 v[72:73], v[180:181], 1, s[16:17]
	s_waitcnt lgkmcnt(0)
	global_store_dwordx4 v[74:75], v[68:71], off sc1
	s_nop 1
	v_add_u32_e32 v68, v121, v76
	ds_read_b128 v[68:71], v68
	s_waitcnt lgkmcnt(0)
	global_store_dwordx4 v[72:73], v[68:71], off sc1
	s_waitcnt lgkmcnt(0)
	s_cbranch_vccnz .LBB0_575
	s_cmp_lt_i32 s36, s31
	s_cselect_b32 s0, s36, s37
	s_min_i32 s1, s0, s29
	s_cmp_lt_i32 s0, s29
	s_mul_i32 s1, s1, s28
	s_cselect_b32 s0, s34, s30
	s_add_i32 s1, s0, s1
	s_ashr_i32 s1, s1, 3
	s_mul_hi_i32 s2, s1, 0x78787879
	s_lshr_b32 s4, s2, 31
	s_ashr_i32 s2, s2, 5
	s_add_i32 s2, s2, s4
	s_mul_i32 s4, s2, 0x44
	s_sub_i32 s1, s1, s4
	s_lshl_b32 s6, s1, 6
	v_mov_b32_e32 v68, v186
	s_cmp_gt_i32 s1, 3
	s_mov_b64 s[4:5], -1
	s_cbranch_scc0 .LBB0_601
	s_lshl_b32 s1, s2, 12
	s_add_i32 s1, s6, s1
	s_addk_i32 s1, 0x700
	s_mov_b64 s[4:5], 0

.LBB0_607:
	s_waitcnt vmcnt(20)
	ds_bpermute_b32 v69, v114, v113
	v_bfe_u32 v83, v78, 3, 3
	v_lshlrev_b32_e32 v68, 4, v78
	v_mov_b32_e32 v74, s35
	v_and_b32_e32 v68, 0x70, v68
	v_mad_u32_u24 v87, v83, s61, v74
	v_and_b32_e32 v93, 63, v78
	v_add_u32_e32 v70, v87, v68
	ds_write_b128 v70, v[64:67]
	s_waitcnt lgkmcnt(1)
	v_add_f32_e32 v64, v113, v69
	v_cmp_eq_u32_e32 vcc, 0, v93
	v_add_u32_e32 v86, 0x480, v87
	v_add_u32_e32 v66, v86, v68
	v_cndmask_b32_e32 v64, v64, v113, vcc
	ds_bpermute_b32 v65, v115, v64
	ds_write_b128 v66, v[48:51]
	v_cmp_gt_u32_e32 vcc, 2, v93
	v_add_u32_e32 v85, 0x900, v87
	v_add_u32_e32 v48, v85, v68
	s_waitcnt lgkmcnt(1)
	v_add_f32_e32 v49, v64, v65
	v_cndmask_b32_e32 v49, v49, v64, vcc
	ds_bpermute_b32 v50, v116, v49
	v_add_u32_e32 v84, 0xd80, v87
	ds_write_b128 v48, v[56:59]
	v_add_u32_e32 v48, v84, v68
	ds_write_b128 v48, v[52:55]
	s_waitcnt lgkmcnt(2)
	v_add_f32_e32 v48, v49, v50
	v_cmp_gt_u32_e32 vcc, 4, v93
	v_add_u32_e32 v82, 0x1200, v87
	v_add_u32_e32 v50, v82, v68
	v_cndmask_b32_e32 v48, v48, v49, vcc
	ds_bpermute_b32 v49, v117, v48
	v_cmp_gt_u32_e32 vcc, 8, v93
	v_add_u32_e32 v81, 0x1680, v87
	ds_write_b128 v50, v[60:63]
	v_add_u32_e32 v50, v81, v68
	s_waitcnt lgkmcnt(1)
	v_add_f32_e32 v49, v48, v49
	v_cndmask_b32_e32 v48, v49, v48, vcc
	ds_bpermute_b32 v49, v118, v48
	ds_write_b128 v50, v[36:39]
	v_cmp_gt_u32_e32 vcc, 16, v93
	v_add_u32_e32 v80, 0x1b00, v87
	v_add_u32_e32 v36, v80, v68
	s_waitcnt lgkmcnt(1)
	v_add_f32_e32 v37, v48, v49
	v_cndmask_b32_e32 v37, v37, v48, vcc
	ds_bpermute_b32 v38, v119, v37
	v_add_u32_e32 v79, 0x1f80, v87
	ds_write_b128 v36, v[44:47]
	v_add_u32_e32 v36, v79, v68
	s_and_b32 s0, s26, 1
	ds_write_b128 v36, v[40:43]
	s_waitcnt lgkmcnt(2)
	v_add_f32_e32 v36, v37, v38
	v_cmp_gt_u32_e64 s[8:9], 32, v93
	s_lshl_b32 s2, s0, 2
	s_lshr_b32 s1, s26, 1
	v_cndmask_b32_e64 v38, v36, v37, s[8:9]
	v_add_u32_e32 v36, s27, v93
	v_lshl_or_b32 v36, v36, 4, s2
	v_and_or_b32 v180, s1, 3, v36
	v_lshl_add_u64 v[36:37], v[180:181], 2, s[20:21]
	v_and_b32_e32 v91, 15, v78
	global_store_dword v[36:37], v38, off sc1
	v_lshl_add_u32 v36, v93, 2, s35
	s_waitcnt vmcnt(20)
	ds_write2st64_b32 v36, v38, v112 offset0:56 offset1:57
	v_and_b32_e32 v92, 48, v78
	v_mad_u32_u24 v89, v91, s61, v74
	v_bfe_u32 v90, v78, 4, 2
	s_waitcnt lgkmcnt(0)
	v_add_u32_e32 v36, v89, v92
	ds_read_b128 v[64:67], v36
	ds_read_b128 v[60:63], v36 offset:64
	s_cmp_eq_u32 s0, 0
	v_lshlrev_b32_e32 v109, 2, v90
	v_add_u32_e32 v88, 0x900, v89
	v_bitop3_b32 v68, v78, 63, 15 bitop3:0x6c
	s_cselect_b64 s[10:11], -1, 0
	v_xor_b32_e32 v76, 60, v109
	v_add_u32_e32 v36, v88, v92
	v_cndmask_b32_e64 v75, v68, v91, s[10:11]
	v_cndmask_b32_e64 v94, v76, v109, s[10:11]
	ds_read_b128 v[56:59], v36
	ds_read_b128 v[52:55], v36 offset:64
	ds_read_b128 v[48:51], v36 offset:2304
	ds_read_b128 v[44:47], v36 offset:2368
	ds_read_b128 v[40:43], v36 offset:4608
	ds_read_b128 v[36:39], v36 offset:4672
	s_waitcnt lgkmcnt(0)
	v_lshl_add_u32 v68, v75, 2, s35
	v_lshlrev_b32_e32 v95, 2, v94
	ds_read2st64_b32 v[72:73], v68 offset0:56 offset1:57
	s_waitcnt lgkmcnt(8)
	v_mfma_f32_16x16x32_bf16 v[68:71], v[64:67], v[64:67], 0
	v_add_u32_e32 v97, s35, v95
	ds_read_b128 v[98:101], v97 offset:14336
	v_mad_u32_u24 v112, v75, s61, v74
	s_waitcnt lgkmcnt(8)
	v_mfma_f32_16x16x32_bf16 v[68:71], v[60:63], v[60:63], v[68:71]
	s_waitcnt lgkmcnt(1)
	v_mov_b32_e32 v108, v73
	v_and_b32_e32 v74, 0x70, v95
	s_waitcnt lgkmcnt(0)
	v_sub_f32_e32 v96, v72, v100
	v_sub_f32_e32 v76, v72, v98
	v_sub_f32_e32 v77, v72, v99
	v_mul_f32_e32 v96, 0x3fb8aa3b, v96
	v_mul_f32_e32 v76, 0x3fb8aa3b, v76
	v_mul_f32_e32 v77, 0x3fb8aa3b, v77
	v_exp_f32_e32 v98, v96
	v_sub_f32_e32 v96, v72, v101
	v_pk_mov_b32 v[100:101], v[70:71], v[70:71] op_sel:[1,0]
	v_exp_f32_e32 v76, v76
	v_exp_f32_e32 v77, v77
	v_mul_f32_e32 v96, 0x3fb8aa3b, v96
	v_pk_mov_b32 v[102:103], v[68:69], v[68:69] op_sel:[1,0]
	v_cndmask_b32_e64 v69, v101, v69, s[10:11]
	v_cndmask_b32_e64 v68, v100, v68, s[10:11]
	v_exp_f32_e32 v99, v96
	v_cndmask_b32_e64 v71, v103, v71, s[10:11]
	v_cndmask_b32_e64 v70, v102, v70, s[10:11]
	v_or_b32_e32 v96, 1, v94
	v_pk_mul_f32 v[100:101], v[108:109], v[68:69] op_sel_hi:[0,1]
	v_pk_mul_f32 v[70:71], v[108:109], v[70:71] op_sel_hi:[0,1]
	v_pk_mul_f32 v[76:77], v[76:77], v[100:101]
	v_cmp_lt_u32_e32 vcc, v96, v75
	v_or_b32_e32 v69, 3, v94
	v_pk_mul_f32 v[70:71], v[70:71], v[98:99]
	v_cndmask_b32_e32 v99, 0, v77, vcc
	v_cmp_lt_u32_e32 vcc, v94, v75
	v_or_b32_e32 v68, 2, v94
	s_bitcmp1_b32 s26, 0
	v_cndmask_b32_e32 v98, 0, v76, vcc
	v_cmp_lt_u32_e32 vcc, v69, v75
	s_cselect_b64 s[24:25], -1, 0
	s_xor_b64 s[22:23], s[24:25], -1
	v_cndmask_b32_e32 v101, 0, v71, vcc
	v_cmp_lt_u32_e32 vcc, v68, v75
	v_bitop3_b32 v71, v109, 60, 16 bitop3:0x36
	v_cmp_lt_u32_e64 s[6:7], 31, v93
	v_cndmask_b32_e32 v100, 0, v70, vcc
	v_add_u32_e32 v70, v112, v74
	ds_write_b128 v70, v[98:101]
	v_or_b32_e32 v70, 16, v109
	v_cndmask_b32_e64 v95, v71, v70, s[10:11]
	v_lshlrev_b32_e32 v113, 2, v95
	v_add_u32_e32 v98, s35, v113
	ds_read_b128 v[104:107], v98 offset:14336
	v_mfma_f32_16x16x32_bf16 v[100:103], v[56:59], v[64:67], 0
	v_or_b32_e32 v99, 1, v95
	v_cmp_lt_u32_e32 vcc, v99, v75
	s_movk_i32 s2, 0x50
	s_waitcnt lgkmcnt(0)
	v_sub_f32_e32 v70, v72, v104
	v_mul_f32_e32 v70, 0x3fb8aa3b, v70
	v_exp_f32_e32 v76, v70
	v_sub_f32_e32 v70, v72, v105
	v_mul_f32_e32 v70, 0x3fb8aa3b, v70
	v_mfma_f32_16x16x32_bf16 v[100:103], v[52:55], v[60:63], v[100:103]
	v_exp_f32_e32 v77, v70
	v_sub_f32_e32 v70, v72, v106
	v_mul_f32_e32 v70, 0x3fb8aa3b, v70
	v_exp_f32_e32 v104, v70
	v_sub_f32_e32 v70, v72, v107
	v_mul_f32_e32 v70, 0x3fb8aa3b, v70
	v_exp_f32_e32 v105, v70
	s_nop 0
	v_pk_mov_b32 v[70:71], v[102:103], v[102:103] op_sel:[1,0]
	v_pk_mov_b32 v[106:107], v[100:101], v[100:101] op_sel:[1,0]
	v_cndmask_b32_e64 v71, v71, v101, s[10:11]
	v_cndmask_b32_e64 v70, v70, v100, s[10:11]
	v_pk_mul_f32 v[100:101], v[108:109], v[70:71] op_sel_hi:[0,1]
	v_cndmask_b32_e64 v103, v107, v103, s[10:11]
	v_cndmask_b32_e64 v102, v106, v102, s[10:11]
	v_pk_mul_f32 v[76:77], v[76:77], v[100:101]
	v_or_b32_e32 v71, 3, v95
	v_pk_mul_f32 v[102:103], v[108:109], v[102:103] op_sel_hi:[0,1]
	v_cndmask_b32_e32 v101, 0, v77, vcc
	v_cmp_lt_u32_e32 vcc, v95, v75
	v_or_b32_e32 v70, 2, v95
	v_pk_mul_f32 v[102:103], v[102:103], v[104:105]
	v_cndmask_b32_e32 v100, 0, v76, vcc
	v_cmp_lt_u32_e32 vcc, v71, v75
	v_and_b32_e32 v76, 0x70, v113
	v_add_u32_e32 v77, v112, v76
	v_cndmask_b32_e32 v103, 0, v103, vcc
	v_cmp_lt_u32_e32 vcc, v70, v75
	s_nop 1
	v_cndmask_b32_e32 v102, 0, v102, vcc
	ds_write_b128 v77, v[100:103]
	v_or_b32_e32 v77, 32, v109
	v_or_b32_e32 v100, 48, v109
	s_and_b64 vcc, exec, s[22:23]
	v_sub_u32_e32 v102, 60, v77
	v_sub_u32_e32 v101, 60, v100
	s_cbranch_vccnz .LBB0_609
	v_mfma_f32_16x16x32_bf16 v[104:107], v[48:51], v[64:67], 0
	v_cndmask_b32_e64 v103, v102, v77, s[10:11]
	v_lshl_add_u32 v108, v103, 2, s35
	ds_read_b128 v[112:115], v108 offset:14336
	v_mfma_f32_16x16x32_bf16 v[104:107], v[44:47], v[60:63], v[104:107]
	v_mov_b32_e32 v108, v73
	v_mov_b32_e32 v109, v73
	v_cmp_lt_u32_e32 vcc, v103, v75
	s_waitcnt lgkmcnt(0)
	v_sub_f32_e32 v112, v72, v112
	v_sub_f32_e32 v113, v72, v113
	s_nop 1
	v_pk_mov_b32 v[116:117], v[106:107], v[106:107] op_sel:[1,0]
	v_mul_f32_e32 v112, 0x3fb8aa3b, v112
	v_mul_f32_e32 v113, 0x3fb8aa3b, v113
	v_pk_mov_b32 v[118:119], v[104:105], v[104:105] op_sel:[1,0]
	v_cndmask_b32_e64 v105, v117, v105, s[10:11]
	v_cndmask_b32_e64 v104, v116, v104, s[10:11]
	v_exp_f32_e32 v112, v112
	v_exp_f32_e32 v113, v113
	v_pk_mul_f32 v[104:105], v[108:109], v[104:105]
	v_sub_f32_e32 v114, v72, v114
	v_sub_f32_e32 v115, v72, v115
	v_mul_f32_e32 v114, 0x3fb8aa3b, v114
	v_pk_mul_f32 v[104:105], v[112:113], v[104:105]
	v_mul_f32_e32 v115, 0x3fb8aa3b, v115
	v_cndmask_b32_e64 v107, v119, v107, s[10:11]
	v_cndmask_b32_e64 v106, v118, v106, s[10:11]
	v_or_b32_e32 v116, 1, v103
	v_cvt_pk_bf16_f32 v104, v104, v105
	v_exp_f32_e32 v114, v114
	v_exp_f32_e32 v115, v115
	v_pk_mul_f32 v[106:107], v[108:109], v[106:107]
	v_cndmask_b32_e32 v105, 0, v104, vcc
	v_lshrrev_b32_e32 v104, 16, v104
	v_cmp_lt_u32_e32 vcc, v116, v75
	v_or_b32_e32 v113, 2, v103
	v_pk_mul_f32 v[106:107], v[106:107], v[114:115]
	v_cndmask_b32_e32 v104, 0, v104, vcc
	v_or_b32_e32 v112, 3, v103
	v_perm_b32 v104, v104, v105, s93
	v_cvt_pk_bf16_f32 v105, v106, v107
	v_cmp_lt_u32_e32 vcc, v113, v75
	v_mov_b32_e32 v73, s35
	v_mad_u32_u24 v118, v75, s2, v73
	v_cndmask_b32_e32 v106, 0, v105, vcc
	v_lshrrev_b32_e32 v105, 16, v105
	v_cmp_lt_u32_e32 vcc, v112, v75
	v_lshl_add_u32 v73, v103, 1, v118
	v_cndmask_b32_e64 v103, v101, v100, s[10:11]
	v_cndmask_b32_e32 v105, 0, v105, vcc
	v_perm_b32 v105, v105, v106, s93
	ds_write_b64 v73, v[104:105] offset:6656
	v_lshl_add_u32 v73, v103, 2, s35
	ds_read_b128 v[112:115], v73 offset:14336
	v_mfma_f32_16x16x32_bf16 v[104:107], v[40:43], v[64:67], 0
	v_cmp_lt_u32_e64 s[14:15], v103, v75
	s_waitcnt lgkmcnt(0)
	v_sub_f32_e32 v73, v72, v112
	v_mul_f32_e32 v73, 0x3fb8aa3b, v73
	v_mfma_f32_16x16x32_bf16 v[104:107], v[36:39], v[60:63], v[104:107]
	v_exp_f32_e32 v112, v73
	v_sub_f32_e32 v73, v72, v113
	v_mul_f32_e32 v73, 0x3fb8aa3b, v73
	v_exp_f32_e32 v113, v73
	v_sub_f32_e32 v73, v72, v114
	v_sub_f32_e32 v72, v72, v115
	v_mul_f32_e32 v73, 0x3fb8aa3b, v73
	v_mul_f32_e32 v72, 0x3fb8aa3b, v72
	v_exp_f32_e32 v114, v73
	v_exp_f32_e32 v115, v72
	v_pk_mov_b32 v[72:73], v[106:107], v[106:107] op_sel:[1,0]
	v_pk_mov_b32 v[116:117], v[104:105], v[104:105] op_sel:[1,0]
	v_cndmask_b32_e64 v73, v73, v105, s[10:11]
	v_cndmask_b32_e64 v72, v72, v104, s[10:11]
	v_or_b32_e32 v104, 1, v103
	v_pk_mul_f32 v[72:73], v[108:109], v[72:73]
	v_cndmask_b32_e64 v107, v117, v107, s[10:11]
	v_cndmask_b32_e64 v106, v116, v106, s[10:11]
	v_cmp_lt_u32_e32 vcc, v104, v75
	v_pk_mul_f32 v[72:73], v[112:113], v[72:73]
	v_or_b32_e32 v104, 3, v103
	v_cmp_lt_u32_e64 s[12:13], v104, v75
	v_pk_mul_f32 v[104:105], v[108:109], v[106:107]
	v_cvt_pk_bf16_f32 v72, v72, v73
	v_or_b32_e32 v112, 2, v103
	v_pk_mul_f32 v[104:105], v[104:105], v[114:115]
	v_cndmask_b32_e64 v73, 0, v72, s[14:15]
	v_cndmask_b32_sdwa v72, v181, v72, vcc dst_sel:DWORD dst_unused:UNUSED_PAD src0_sel:DWORD src1_sel:WORD_1
	v_perm_b32 v72, v72, v73, s93
	v_cvt_pk_bf16_f32 v73, v104, v105
	v_cmp_lt_u32_e32 vcc, v112, v75
	s_nop 1
	v_cndmask_b32_e32 v75, 0, v73, vcc
	s_mov_b64 vcc, s[12:13]
	v_cndmask_b32_sdwa v73, v181, v73, vcc dst_sel:DWORD dst_unused:UNUSED_PAD src0_sel:DWORD src1_sel:WORD_1
	v_perm_b32 v73, v73, v75, s93
	v_lshl_add_u32 v75, v103, 1, v118
	ds_write_b64 v75, v[72:73] offset:6656

.LBB0_625:
	s_or_b64 exec, exec, s[8:9]
	v_lshlrev_b32_e32 v148, 16, v177
	v_and_b32_e32 v149, 0xffff0000, v177
	v_pk_fma_f32 v[148:149], v[22:23], v[148:149], v[178:179]
	v_mov_b64_e32 v[230:231], v[130:131]
	v_mul_f32_e32 v150, 0xbfb8aa3b, v149
	v_exp_f32_e32 v150, v150
	v_mov_b64_e32 v[232:233], v[136:137]
	v_mov_b64_e32 v[234:235], v[134:135]
	v_mov_b64_e32 v[194:195], v[142:143]
	v_add_f32_e32 v150, 1.0, v150
	v_rcp_f32_e32 v151, v150
	v_mul_f32_e32 v150, 0xbfb8aa3b, v148
	v_exp_f32_e32 v150, v150
	v_mov_b64_e32 v[218:219], v[132:133]
	v_mov_b64_e32 v[224:225], v[144:145]
	v_mov_b64_e32 v[190:191], v[120:121]
	v_add_f32_e32 v150, 1.0, v150
	v_rcp_f32_e32 v150, v150
	v_mov_b64_e32 v[192:193], v[112:113]
	v_mov_b64_e32 v[178:179], v[114:115]
	v_mov_b64_e32 v[112:113], v[146:147]
	v_pk_mul_f32 v[148:149], v[148:149], v[150:151]
	v_lshlrev_b32_e32 v150, 16, v176
	v_and_b32_e32 v151, 0xffff0000, v176
	v_pk_fma_f32 v[150:151], v[20:21], v[150:151], v[174:175]
	v_mov_b64_e32 v[174:175], v[124:125]
	v_mul_f32_e32 v154, 0xbfb8aa3b, v151
	v_exp_f32_e32 v154, v154
	v_mov_b64_e32 v[176:177], v[118:119]
	v_mov_b64_e32 v[114:115], v[140:141]
	v_add_f32_e32 v154, 1.0, v154
	v_rcp_f32_e32 v155, v154
	v_mul_f32_e32 v154, 0xbfb8aa3b, v150
	v_exp_f32_e32 v154, v154
	s_nop 0
	v_add_f32_e32 v154, 1.0, v154
	v_rcp_f32_e32 v154, v154
	s_nop 0
	v_pk_mul_f32 v[150:151], v[150:151], v[154:155]
	s_nop 0
	v_cvt_pk_bf16_f32 v150, v150, v151
	v_cvt_pk_bf16_f32 v151, v148, v149
	global_store_dwordx2 v[188:189], v[150:151], off offset:1024 sc1
	v_mov_b64_e32 v[148:149], v[128:129]
	v_mov_b64_e32 v[188:189], v[126:127]
	v_mov_b64_e32 v[150:151], v[122:123]
	v_mov_b64_e32 v[154:155], v[116:117]
	v_mov_b64_e32 v[116:117], v[138:139]

.LBB0_633:
	s_or_b64 exec, exec, s[8:9]
	v_lshlrev_b32_e32 v212, 16, v205
	v_and_b32_e32 v213, 0xffff0000, v205
	v_pk_fma_f32 v[202:203], v[10:11], v[212:213], v[202:203]
	v_lshlrev_b32_e32 v214, 16, v180
	v_mul_f32_e32 v205, 0xbfb8aa3b, v203
	v_exp_f32_e32 v205, v205
	v_mul_f32_e32 v212, 0xbfb8aa3b, v202
	v_exp_f32_e32 v212, v212
	v_and_b32_e32 v215, 0xffff0000, v180
	v_pk_fma_f32 v[200:201], v[8:9], v[214:215], v[200:201]
	v_add_f32_e32 v205, 1.0, v205
	v_mul_f32_e32 v180, 0xbfb8aa3b, v201
	v_rcp_f32_e32 v213, v205
	v_add_f32_e32 v205, 1.0, v212
	v_exp_f32_e32 v180, v180
	v_mul_f32_e32 v212, 0xbfb8aa3b, v200
	v_exp_f32_e32 v214, v212
	v_rcp_f32_e32 v212, v205
	v_add_f32_e32 v180, 1.0, v180
	v_rcp_f32_e32 v215, v180
	v_add_f32_e32 v180, 1.0, v214
	v_rcp_f32_e32 v214, v180
	v_pk_mul_f32 v[202:203], v[202:203], v[212:213]
	v_pk_mul_f32 v[200:201], v[200:201], v[214:215]
	v_mov_b32_e32 v212, v202
	v_mov_b32_e32 v213, v200
	v_pk_mul_f32 v[212:213], v[212:213], v[212:213]
	v_mov_b32_e32 v214, v203
	v_mov_b32_e32 v215, v201
	v_pk_fma_f32 v[212:213], v[214:215], v[214:215], v[212:213]
	s_nop 0
	v_add_f32_e32 v180, v212, v213
	s_nop 1
	v_add_f32_dpp v180, v180, v180 quad_perm:[1,0,3,2] row_mask:0xf bank_mask:0xf bound_ctrl:1
	s_nop 1
	v_add_f32_dpp v180, v180, v180 quad_perm:[2,3,0,1] row_mask:0xf bank_mask:0xf bound_ctrl:1
	s_nop 1
	v_add_f32_dpp v180, v180, v180 row_half_mirror row_mask:0xf bank_mask:0xf bound_ctrl:1
	s_nop 1
	v_add_f32_dpp v180, v180, v180 row_mirror row_mask:0xf bank_mask:0xf bound_ctrl:1
	v_add_f32_e32 v180, 0x358637bd, v180
	v_rsq_f32_e32 v180, v180
	s_nop 0
	v_mul_f32_e32 v180, 0x3e000000, v180
	v_pk_mul_f32 v[202:203], v[202:203], v[180:181] op_sel_hi:[1,0]
	v_pk_mul_f32 v[200:201], v[200:201], v[180:181] op_sel_hi:[1,0]
	v_and_b32_e32 v180, 63, v204
	v_lshlrev_b32_e32 v180, 3, v180
	v_cvt_pk_bf16_f32 v212, v200, v201
	v_cvt_pk_bf16_f32 v213, v202, v203
	v_lshl_add_u64 v[200:201], v[152:153], 0, v[180:181]
	global_store_dwordx2 v[200:201], v[212:213], off offset:-1024 sc1
	s_and_saveexec_b64 s[0:1], s[26:27]
	s_xor_b64 s[28:29], exec, s[0:1]
	s_cbranch_execz .LBB0_635
	v_cmp_le_u32_e64 s[10:11], v207, v206
	s_and_b64 s[0:1], vcc, s[10:11]
	v_cmp_le_u32_e64 s[12:13], v210, v209
	s_and_b64 s[8:9], s[0:1], s[12:13]
	v_cndmask_b32_e64 v180, 0, v222, s[8:9]
	v_cmp_eq_u32_e64 s[14:15], 0, v207
	v_cmp_lt_u32_e64 s[16:17], v210, v209
	v_cndmask_b32_e64 v202, 0, v223, s[8:9]
	v_cndmask_b32_e64 v180, v180, 0, s[14:15]
	s_and_b64 s[8:9], s[10:11], s[16:17]
	v_cndmask_b32_e64 v205, v202, 0, s[14:15]
	v_lshlrev_b32_e32 v202, 16, v180
	v_and_b32_e32 v203, 0xffff0000, v180
	v_cndmask_b32_e64 v180, 0, v178, s[8:9]
	v_cndmask_b32_e64 v212, 0, v179, s[8:9]
	v_cmp_le_u32_e64 s[8:9], v211, v209
	s_and_b64 s[10:11], s[10:11], s[8:9]
	v_cndmask_b32_e64 v214, v212, 0, s[14:15]
	v_cndmask_b32_e64 v212, 0, v114, s[10:11]
	v_cndmask_b32_e64 v213, 0, v115, s[10:11]
	v_cmp_lt_u32_e64 s[10:11], v207, v206
	s_and_b64 s[0:1], vcc, s[10:11]
	v_cndmask_b32_e64 v180, v180, 0, s[14:15]
	v_cndmask_b32_e64 v215, v213, 0, s[14:15]
	v_cndmask_b32_e64 v216, v212, 0, s[14:15]
	s_and_b64 s[14:15], s[0:1], s[12:13]
	v_cndmask_b32_e64 v217, 0, v221, s[14:15]
	v_cndmask_b32_e64 v220, 0, v220, s[14:15]
	s_and_b64 s[14:15], s[10:11], s[16:17]
	s_and_b64 s[10:11], s[10:11], s[8:9]
	v_pk_fma_f32 v[202:203], v[100:101], v[202:203], 0 op_sel_hi:[1,1,0]
	v_lshlrev_b32_e32 v212, 16, v180
	v_and_b32_e32 v213, 0xffff0000, v180
	v_cndmask_b32_e64 v223, 0, v119, s[10:11]
	v_cndmask_b32_e64 v224, 0, v118, s[10:11]
	v_cmp_le_u32_e64 s[10:11], v208, v206
	v_pk_fma_f32 v[202:203], v[88:89], v[212:213], v[202:203]
	v_lshlrev_b32_e32 v212, 16, v216
	v_and_b32_e32 v213, 0xffff0000, v216
	v_cndmask_b32_e64 v222, 0, v176, s[14:15]
	s_and_b64 s[0:1], vcc, s[10:11]
	v_pk_fma_f32 v[202:203], v[104:105], v[212:213], v[202:203]
	v_lshlrev_b32_e32 v212, 16, v220
	v_and_b32_e32 v213, 0xffff0000, v220
	s_and_b64 s[12:13], s[0:1], s[12:13]
	v_pk_fma_f32 v[202:203], v[60:61], v[212:213], v[202:203]
	v_lshlrev_b32_e32 v212, 16, v222
	v_and_b32_e32 v213, 0xffff0000, v222
	v_cndmask_b32_e64 v219, 0, v219, s[12:13]
	v_cndmask_b32_e64 v218, 0, v218, s[12:13]
	s_and_b64 s[12:13], s[10:11], s[16:17]
	v_pk_fma_f32 v[202:203], v[48:49], v[212:213], v[202:203]
	v_lshlrev_b32_e32 v212, 16, v224
	v_and_b32_e32 v213, 0xffff0000, v224
	v_cndmask_b32_e64 v226, 0, v174, s[12:13]
	v_pk_fma_f32 v[202:203], v[40:41], v[212:213], v[202:203]
	v_lshlrev_b32_e32 v212, 16, v218
	v_and_b32_e32 v213, 0xffff0000, v218
	v_lshlrev_b32_e32 v204, 16, v205
	v_and_b32_e32 v205, 0xffff0000, v205
	v_pk_fma_f32 v[202:203], v[52:53], v[212:213], v[202:203]
	v_lshlrev_b32_e32 v212, 16, v226
	v_and_b32_e32 v213, 0xffff0000, v226
	v_pk_fma_f32 v[202:203], v[12:13], v[212:213], v[202:203]
	v_pk_fma_f32 v[204:205], v[102:103], v[204:205], 0 op_sel_hi:[1,1,0]
	v_lshlrev_b32_e32 v212, 16, v214
	v_and_b32_e32 v213, 0xffff0000, v214
	v_pk_fma_f32 v[204:205], v[90:91], v[212:213], v[204:205]
	v_lshlrev_b32_e32 v212, 16, v215
	v_and_b32_e32 v213, 0xffff0000, v215
	v_cndmask_b32_e64 v221, 0, v177, s[14:15]
	v_pk_fma_f32 v[204:205], v[106:107], v[212:213], v[204:205]
	v_lshlrev_b32_e32 v212, 16, v217
	v_and_b32_e32 v213, 0xffff0000, v217
	v_pk_fma_f32 v[204:205], v[62:63], v[212:213], v[204:205]
	v_lshlrev_b32_e32 v212, 16, v221
	v_and_b32_e32 v213, 0xffff0000, v221
	v_pk_fma_f32 v[204:205], v[50:51], v[212:213], v[204:205]
	v_lshlrev_b32_e32 v212, 16, v223
	v_and_b32_e32 v213, 0xffff0000, v223
	v_cndmask_b32_e64 v225, 0, v175, s[12:13]
	v_pk_fma_f32 v[204:205], v[42:43], v[212:213], v[204:205]
	v_lshlrev_b32_e32 v212, 16, v219
	v_and_b32_e32 v213, 0xffff0000, v219
	v_pk_fma_f32 v[204:205], v[54:55], v[212:213], v[204:205]
	v_lshlrev_b32_e32 v212, 16, v225
	v_and_b32_e32 v213, 0xffff0000, v225
	s_and_b64 s[8:9], s[10:11], s[8:9]
	v_pk_fma_f32 v[204:205], v[14:15], v[212:213], v[204:205]
	v_cndmask_b32_e64 v180, 0, v124, s[8:9]
	v_cndmask_b32_e64 v212, 0, v125, s[8:9]

.LBB0_637:
	s_or_b64 exec, exec, s[8:9]
	v_lshlrev_b32_e32 v214, 16, v212
	v_and_b32_e32 v215, 0xffff0000, v212
	v_pk_fma_f32 v[204:205], v[6:7], v[214:215], v[204:205]
	v_and_b32_e32 v215, 0xffff0000, v180
	v_mul_f32_e32 v212, 0xbfb8aa3b, v205
	v_exp_f32_e32 v212, v212
	v_mul_f32_e32 v213, 0xbfb8aa3b, v204
	v_exp_f32_e32 v214, v213
	v_add_f32_e32 v212, 1.0, v212
	v_rcp_f32_e32 v213, v212
	v_add_f32_e32 v212, 1.0, v214
	v_lshlrev_b32_e32 v214, 16, v180
	v_pk_fma_f32 v[202:203], v[4:5], v[214:215], v[202:203]
	v_rcp_f32_e32 v212, v212
	v_mul_f32_e32 v180, 0xbfb8aa3b, v203
	v_exp_f32_e32 v180, v180
	v_mul_f32_e32 v214, 0xbfb8aa3b, v202
	v_exp_f32_e32 v214, v214
	v_pk_mul_f32 v[204:205], v[204:205], v[212:213]
	v_add_f32_e32 v180, 1.0, v180
	v_rcp_f32_e32 v215, v180
	v_add_f32_e32 v180, 1.0, v214
	v_rcp_f32_e32 v214, v180
	v_mov_b32_e32 v212, v204
	v_pk_mul_f32 v[202:203], v[202:203], v[214:215]
	s_nop 0
	v_mov_b32_e32 v213, v202
	v_pk_mul_f32 v[212:213], v[212:213], v[212:213]
	v_mov_b32_e32 v214, v205
	v_mov_b32_e32 v215, v203
	v_pk_fma_f32 v[212:213], v[214:215], v[214:215], v[212:213]
	s_nop 0
	v_add_f32_e32 v180, v212, v213
	s_nop 1
	v_add_f32_dpp v180, v180, v180 quad_perm:[1,0,3,2] row_mask:0xf bank_mask:0xf bound_ctrl:1
	s_nop 1
	v_add_f32_dpp v180, v180, v180 quad_perm:[2,3,0,1] row_mask:0xf bank_mask:0xf bound_ctrl:1
	s_nop 1
	v_add_f32_dpp v180, v180, v180 row_half_mirror row_mask:0xf bank_mask:0xf bound_ctrl:1
	s_nop 1
	v_add_f32_dpp v180, v180, v180 row_mirror row_mask:0xf bank_mask:0xf bound_ctrl:1
	v_add_f32_e32 v180, 0x358637bd, v180
	v_rsq_f32_e32 v180, v180
	s_nop 0
	v_pk_mul_f32 v[204:205], v[204:205], v[180:181] op_sel_hi:[1,0]
	v_pk_mul_f32 v[202:203], v[202:203], v[180:181] op_sel_hi:[1,0]
	s_nop 0
	v_cvt_pk_bf16_f32 v202, v202, v203
	v_cvt_pk_bf16_f32 v203, v204, v205
	global_store_dwordx2 v[200:201], v[202:203], off offset:-512 sc1
	s_and_saveexec_b64 s[0:1], s[26:27]
	s_xor_b64 s[26:27], exec, s[0:1]
	s_cbranch_execz .LBB0_639
	v_cmp_le_u32_e64 s[10:11], v207, v206
	s_and_b64 s[0:1], vcc, s[10:11]
	v_cmp_le_u32_e64 s[12:13], v210, v209
	s_and_b64 s[8:9], s[0:1], s[12:13]
	v_cndmask_b32_e64 v180, 0, v198, s[8:9]
	v_cndmask_b32_e64 v198, 0, v199, s[8:9]
	v_cmp_eq_u32_e64 s[14:15], 0, v207
	v_cmp_lt_u32_e64 s[16:17], v210, v209
	s_and_b64 s[8:9], s[10:11], s[16:17]
	v_cndmask_b32_e64 v202, v198, 0, s[14:15]
	v_cndmask_b32_e64 v180, v180, 0, s[14:15]
	v_lshlrev_b32_e32 v198, 16, v180
	v_and_b32_e32 v199, 0xffff0000, v180
	v_lshlrev_b32_e32 v204, 16, v202
	v_and_b32_e32 v205, 0xffff0000, v202
	v_cndmask_b32_e64 v180, 0, v154, s[8:9]
	v_cndmask_b32_e64 v202, 0, v155, s[8:9]
	v_cmp_le_u32_e64 s[8:9], v211, v209
	s_and_b64 s[10:11], s[10:11], s[8:9]
	v_cndmask_b32_e64 v210, v202, 0, s[14:15]
	v_cndmask_b32_e64 v202, 0, v116, s[10:11]
	v_cndmask_b32_e64 v203, 0, v117, s[10:11]
	v_cmp_lt_u32_e64 s[10:11], v207, v206
	s_and_b64 s[0:1], vcc, s[10:11]
	v_cndmask_b32_e64 v180, v180, 0, s[14:15]
	v_cndmask_b32_e64 v209, v203, 0, s[14:15]
	v_cndmask_b32_e64 v202, v202, 0, s[14:15]
	s_and_b64 s[14:15], s[0:1], s[12:13]
	v_cndmask_b32_e64 v207, 0, v197, s[14:15]
	v_cndmask_b32_e64 v203, 0, v196, s[14:15]
	s_and_b64 s[14:15], s[10:11], s[16:17]
	s_and_b64 s[10:11], s[10:11], s[8:9]
	v_cndmask_b32_e64 v213, 0, v123, s[10:11]
	v_cndmask_b32_e64 v214, 0, v122, s[10:11]
	v_cmp_le_u32_e64 s[10:11], v208, v206
	s_and_b64 s[0:1], vcc, s[10:11]
	s_and_b64 vcc, s[0:1], s[12:13]
	v_cndmask_b32_e32 v206, 0, v195, vcc
	v_cndmask_b32_e32 v208, 0, v194, vcc
	v_pk_fma_f32 v[194:195], v[96:97], v[198:199], 0 op_sel_hi:[1,1,0]
	v_lshlrev_b32_e32 v196, 16, v180
	v_and_b32_e32 v197, 0xffff0000, v180
	v_pk_fma_f32 v[194:195], v[80:81], v[196:197], v[194:195]
	v_lshlrev_b32_e32 v196, 16, v202
	v_and_b32_e32 v197, 0xffff0000, v202
	v_cndmask_b32_e64 v212, 0, v150, s[14:15]
	v_pk_fma_f32 v[194:195], v[72:73], v[196:197], v[194:195]
	v_lshlrev_b32_e32 v196, 16, v203
	v_and_b32_e32 v197, 0xffff0000, v203
	v_pk_fma_f32 v[194:195], v[84:85], v[196:197], v[194:195]
	v_lshlrev_b32_e32 v196, 16, v212
	v_and_b32_e32 v197, 0xffff0000, v212
	s_and_b64 vcc, s[10:11], s[16:17]
	v_pk_fma_f32 v[194:195], v[44:45], v[196:197], v[194:195]
	v_lshlrev_b32_e32 v196, 16, v214
	v_and_b32_e32 v197, 0xffff0000, v214
	v_cndmask_b32_e32 v216, 0, v148, vcc
	v_pk_fma_f32 v[194:195], v[32:33], v[196:197], v[194:195]
	v_lshlrev_b32_e32 v196, 16, v208
	v_and_b32_e32 v197, 0xffff0000, v208
	v_pk_fma_f32 v[194:195], v[24:25], v[196:197], v[194:195]
	v_lshlrev_b32_e32 v196, 16, v216
	v_and_b32_e32 v197, 0xffff0000, v216
	v_pk_fma_f32 v[202:203], v[36:37], v[196:197], v[194:195]
	v_pk_fma_f32 v[194:195], v[98:99], v[204:205], 0 op_sel_hi:[1,1,0]
	v_lshlrev_b32_e32 v196, 16, v210
	v_and_b32_e32 v197, 0xffff0000, v210
	v_pk_fma_f32 v[194:195], v[82:83], v[196:197], v[194:195]
	v_lshlrev_b32_e32 v196, 16, v209
	v_and_b32_e32 v197, 0xffff0000, v209
	v_cndmask_b32_e64 v211, 0, v151, s[14:15]
	v_pk_fma_f32 v[194:195], v[74:75], v[196:197], v[194:195]
	v_lshlrev_b32_e32 v196, 16, v207
	v_and_b32_e32 v197, 0xffff0000, v207
	v_pk_fma_f32 v[194:195], v[86:87], v[196:197], v[194:195]
	v_lshlrev_b32_e32 v196, 16, v211
	v_and_b32_e32 v197, 0xffff0000, v211
	v_pk_fma_f32 v[194:195], v[46:47], v[196:197], v[194:195]
	v_lshlrev_b32_e32 v196, 16, v213
	v_and_b32_e32 v197, 0xffff0000, v213
	v_cndmask_b32_e32 v215, 0, v149, vcc
	v_pk_fma_f32 v[194:195], v[34:35], v[196:197], v[194:195]
	v_lshlrev_b32_e32 v196, 16, v206
	v_and_b32_e32 v197, 0xffff0000, v206
	v_pk_fma_f32 v[194:195], v[26:27], v[196:197], v[194:195]
	v_lshlrev_b32_e32 v196, 16, v215
	v_and_b32_e32 v197, 0xffff0000, v215
	s_and_b64 vcc, s[10:11], s[8:9]
	v_pk_fma_f32 v[204:205], v[38:39], v[196:197], v[194:195]
	v_cndmask_b32_e32 v180, 0, v128, vcc
	v_cndmask_b32_e32 v212, 0, v129, vcc

.LBB0_641:
	s_or_b64 exec, exec, s[8:9]
	v_lshlrev_b32_e32 v194, 16, v212
	v_and_b32_e32 v195, 0xffff0000, v212
	v_pk_fma_f32 v[194:195], v[22:23], v[194:195], v[204:205]
	v_and_b32_e32 v199, 0xffff0000, v180
	v_mul_f32_e32 v196, 0xbfb8aa3b, v195
	v_exp_f32_e32 v196, v196
	v_mul_f32_e32 v197, 0xbfb8aa3b, v194
	v_exp_f32_e32 v198, v197
	v_add_u32_e32 v223, 1, v187
	v_add_f32_e32 v196, 1.0, v196
	v_rcp_f32_e32 v197, v196
	v_add_f32_e32 v196, 1.0, v198
	v_lshlrev_b32_e32 v198, 16, v180
	v_pk_fma_f32 v[198:199], v[20:21], v[198:199], v[202:203]
	v_rcp_f32_e32 v196, v196
	v_mul_f32_e32 v180, 0xbfb8aa3b, v199
	v_exp_f32_e32 v180, v180
	v_mul_f32_e32 v202, 0xbfb8aa3b, v198
	v_exp_f32_e32 v202, v202
	v_pk_mul_f32 v[194:195], v[194:195], v[196:197]
	v_add_f32_e32 v180, 1.0, v180
	v_rcp_f32_e32 v203, v180
	v_add_f32_e32 v180, 1.0, v202
	v_rcp_f32_e32 v202, v180
	v_cmp_lt_i32_e32 vcc, v223, v185
	s_waitcnt vmcnt(10)
	v_mov_b64_e32 v[214:215], v[130:131]
	s_waitcnt vmcnt(7)
	v_mov_b64_e32 v[210:211], v[136:137]
	v_pk_mul_f32 v[196:197], v[198:199], v[202:203]
	v_mov_b64_e32 v[216:217], v[134:135]
	v_cvt_pk_bf16_f32 v196, v196, v197
	v_cvt_pk_bf16_f32 v197, v194, v195
	global_store_dwordx2 v[200:201], v[196:197], off sc1
	s_waitcnt vmcnt(7)
	v_mov_b64_e32 v[212:213], v[142:143]
	v_mov_b64_e32 v[206:207], v[132:133]
	s_waitcnt vmcnt(6)
	v_mov_b64_e32 v[208:209], v[144:145]
	s_waitcnt vmcnt(3)
	v_mov_b64_e32 v[200:201], v[146:147]
	v_mov_b64_e32 v[202:203], v[140:141]
	v_mov_b64_e32 v[204:205], v[138:139]
	v_mov_b64_e32 v[230:231], v[128:129]
	v_mov_b64_e32 v[232:233], v[124:125]
	v_mov_b64_e32 v[234:235], v[126:127]
	v_mov_b64_e32 v[194:195], v[122:123]
	v_mov_b64_e32 v[218:219], v[118:119]
	v_mov_b64_e32 v[224:225], v[120:121]
	s_and_saveexec_b64 s[26:27], vcc
	s_cbranch_execz .LBB0_626
	v_add_u32_e32 v180, 3, v187
	v_mov_b32_e32 v224, v186
	v_cmp_lt_i32_e32 vcc, v180, v185
	v_mov_b64_e32 v[204:205], v[138:139]
	v_mov_b64_e32 v[202:203], v[140:141]
	v_mov_b64_e32 v[200:201], v[146:147]
	v_mov_b64_e32 v[208:209], v[144:145]
	v_mov_b64_e32 v[206:207], v[132:133]
	v_mov_b64_e32 v[212:213], v[142:143]
	v_mov_b64_e32 v[216:217], v[134:135]
	v_mov_b64_e32 v[210:211], v[136:137]
	v_mov_b64_e32 v[214:215], v[130:131]
	s_and_saveexec_b64 s[8:9], vcc
	s_cbranch_execz .LBB0_644
	v_subrev_u32_e32 v180, 60, v187
	v_med3_i32 v180, v180, 0, v253
	v_max_i32_e32 v198, -3, v223
	v_mov_b32_e32 v196, v186
	v_mul_u32_u24_e32 v180, 0xe00, v180
	v_add_u32_e32 v198, 3, v198
	v_lshl_add_u64 v[194:195], v[180:181], 1, s[20:21]
	v_lshlrev_b32_e32 v180, 3, v196
	v_min_u32_e32 v198, 0x87ff, v198
	v_and_b32_e32 v180, 0x1f8, v180
	v_mul_u32_u24_e32 v198, 0xe00, v198
	v_lshl_add_u64 v[194:195], v[194:195], 0, v[180:181]
	s_mov_b64 s[0:1], 0x1200
	v_lshlrev_b32_e32 v198, 1, v198
	v_mov_b32_e32 v199, v181
	v_lshl_add_u64 v[196:197], v[194:195], 0, s[0:1]
	v_add_co_u32_e32 v194, vcc, 0x1000, v194
	v_lshl_add_u64 v[198:199], s[20:21], 0, v[198:199]
	s_nop 0
	v_addc_co_u32_e32 v195, vcc, 0, v195, vcc
	v_lshl_add_u64 v[198:199], v[198:199], 0, v[180:181]
	v_lshl_add_u64 v[212:213], v[198:199], 0, s[0:1]
	global_load_dwordx2 v[200:201], v[194:195], off offset:512
	global_load_dwordx2 v[202:203], v[196:197], off offset:512
	global_load_dwordx2 v[206:207], v[212:213], off offset:512
	global_load_dwordx2 v[204:205], v[196:197], off offset:1024
	v_max_i32_e32 v196, 0xffffffbc, v187
	v_add_u32_e32 v196, 0x44, v196
	v_min_u32_e32 v196, 0x87ff, v196
	v_mul_u32_u24_e32 v196, 0xe00, v196
	v_lshlrev_b32_e32 v196, 1, v196
	v_mov_b32_e32 v197, v181
	v_add_co_u32_e32 v194, vcc, s83, v198
	v_lshl_add_u64 v[196:197], s[20:21], 0, v[196:197]
	s_nop 0
	v_addc_co_u32_e32 v195, vcc, 0, v199, vcc
	v_lshl_add_u64 v[196:197], v[196:197], 0, v[180:181]
	v_lshl_add_u64 v[198:199], v[196:197], 0, s[0:1]
	global_load_dwordx2 v[208:209], v[194:195], off offset:512
	global_load_dwordx2 v[210:211], v[198:199], off offset:512
	global_load_dwordx2 v[214:215], v[198:199], off offset:1024
	s_nop 0
	global_load_dwordx2 v[212:213], v[212:213], off offset:1024
	v_add_co_u32_e32 v194, vcc, 0x1000, v196
	s_nop 1
	v_addc_co_u32_e32 v195, vcc, 0, v197, vcc
	global_load_dwordx2 v[216:217], v[194:195], off offset:512

.LBB0_648:
	s_or_b64 exec, exec, s[8:9]
	v_lshlrev_b32_e32 v188, 16, v197
	v_and_b32_e32 v189, 0xffff0000, v197
	v_pk_fma_f32 v[188:189], v[10:11], v[188:189], v[198:199]
	v_lshlrev_b32_e32 v192, 16, v196
	v_mul_f32_e32 v180, 0xbfb8aa3b, v189
	v_exp_f32_e32 v180, v180
	v_mul_f32_e32 v190, 0xbfb8aa3b, v188
	v_exp_f32_e32 v190, v190
	v_and_b32_e32 v193, 0xffff0000, v196
	v_add_f32_e32 v180, 1.0, v180
	v_pk_fma_f32 v[192:193], v[8:9], v[192:193], v[194:195]
	v_rcp_f32_e32 v191, v180
	v_add_f32_e32 v180, 1.0, v190
	v_mul_f32_e32 v190, 0xbfb8aa3b, v193
	v_exp_f32_e32 v194, v190
	v_mul_f32_e32 v190, 0xbfb8aa3b, v192
	v_exp_f32_e32 v196, v190
	v_rcp_f32_e32 v190, v180
	v_add_f32_e32 v180, 1.0, v194
	v_rcp_f32_e32 v195, v180
	v_add_f32_e32 v180, 1.0, v196
	v_rcp_f32_e32 v194, v180
	v_pk_mul_f32 v[188:189], v[188:189], v[190:191]
	s_movk_i32 s0, 0x600
	v_pk_mul_f32 v[190:191], v[192:193], v[194:195]
	v_mov_b32_e32 v192, v188
	v_mov_b32_e32 v193, v190
	v_pk_mul_f32 v[192:193], v[192:193], v[192:193]
	v_mov_b32_e32 v194, v189
	v_mov_b32_e32 v195, v191
	v_pk_fma_f32 v[192:193], v[194:195], v[194:195], v[192:193]
	s_nop 0
	v_add_f32_e32 v180, v192, v193
	s_nop 1
	v_add_f32_dpp v180, v180, v180 quad_perm:[1,0,3,2] row_mask:0xf bank_mask:0xf bound_ctrl:1
	s_nop 1
	v_add_f32_dpp v180, v180, v180 quad_perm:[2,3,0,1] row_mask:0xf bank_mask:0xf bound_ctrl:1
	s_nop 1
	v_add_f32_dpp v180, v180, v180 row_half_mirror row_mask:0xf bank_mask:0xf bound_ctrl:1
	s_nop 1
	v_add_f32_dpp v180, v180, v180 row_mirror row_mask:0xf bank_mask:0xf bound_ctrl:1
	v_add_f32_e32 v180, 0x358637bd, v180
	v_rsq_f32_e32 v180, v180
	s_nop 0
	v_mul_f32_e32 v180, 0x3e000000, v180
	v_pk_mul_f32 v[188:189], v[188:189], v[180:181] op_sel_hi:[1,0]
	v_pk_mul_f32 v[190:191], v[190:191], v[180:181] op_sel_hi:[1,0]
	v_lshlrev_b32_e32 v180, 3, v224
	v_cvt_pk_bf16_f32 v190, v190, v191
	v_cvt_pk_bf16_f32 v191, v188, v189
	v_mov_b64_e32 v[188:189], s[22:23]
	v_mad_i64_i32 v[188:189], s[0:1], v223, s0, v[188:189]
	v_and_b32_e32 v180, 0x1f8, v180
	v_lshl_add_u64 v[188:189], v[188:189], 0, v[180:181]
	global_store_dwordx2 v[188:189], v[190:191], off sc1
	s_and_saveexec_b64 s[0:1], s[28:29]
	s_xor_b64 s[30:31], exec, s[0:1]
	s_cbranch_execz .LBB0_650
	v_cmp_le_u32_e64 s[10:11], v218, v187
	s_and_b64 s[0:1], vcc, s[10:11]
	v_cmp_le_u32_e64 s[12:13], v221, v220
	s_and_b64 s[8:9], s[0:1], s[12:13]
	v_cndmask_b32_e64 v179, 0, v179, s[8:9]
	v_cmp_eq_u32_e64 s[14:15], 0, v218
	v_cmp_lt_u32_e64 s[16:17], v221, v220
	v_cndmask_b32_e64 v178, 0, v178, s[8:9]
	v_cndmask_b32_e64 v180, v179, 0, s[14:15]
	s_and_b64 s[8:9], s[10:11], s[16:17]
	v_lshlrev_b32_e32 v192, 16, v180
	v_and_b32_e32 v193, 0xffff0000, v180
	v_cndmask_b32_e64 v180, 0, v114, s[8:9]
	v_cndmask_b32_e64 v190, 0, v115, s[8:9]
	v_cmp_le_u32_e64 s[8:9], v222, v220
	s_and_b64 s[10:11], s[10:11], s[8:9]
	v_cndmask_b32_e64 v194, v190, 0, s[14:15]
	v_cndmask_b32_e64 v190, 0, v140, s[10:11]
	v_cndmask_b32_e64 v191, 0, v141, s[10:11]
	v_cmp_lt_u32_e64 s[10:11], v218, v187
	s_and_b64 s[0:1], vcc, s[10:11]
	v_cndmask_b32_e64 v179, v178, 0, s[14:15]
	v_cndmask_b32_e64 v180, v180, 0, s[14:15]
	v_cndmask_b32_e64 v195, v191, 0, s[14:15]
	v_cndmask_b32_e64 v190, v190, 0, s[14:15]
	s_and_b64 s[14:15], s[0:1], s[12:13]
	v_cndmask_b32_e64 v196, 0, v177, s[14:15]
	v_cndmask_b32_e64 v191, 0, v176, s[14:15]
	s_and_b64 s[14:15], s[10:11], s[16:17]
	s_and_b64 s[10:11], s[10:11], s[8:9]
	v_cndmask_b32_e64 v199, 0, v133, s[10:11]
	v_cndmask_b32_e64 v223, 0, v132, s[10:11]
	v_cmp_le_u32_e64 s[10:11], v219, v187
	s_and_b64 s[0:1], vcc, s[10:11]
	v_lshlrev_b32_e32 v178, 16, v179
	v_and_b32_e32 v179, 0xffff0000, v179
	s_and_b64 s[12:13], s[0:1], s[12:13]
	v_cndmask_b32_e64 v224, 0, v175, s[12:13]
	v_cndmask_b32_e64 v225, 0, v174, s[12:13]
	v_pk_fma_f32 v[174:175], v[100:101], v[178:179], 0 op_sel_hi:[1,1,0]
	v_lshlrev_b32_e32 v176, 16, v180
	v_and_b32_e32 v177, 0xffff0000, v180
	v_pk_fma_f32 v[174:175], v[88:89], v[176:177], v[174:175]
	v_lshlrev_b32_e32 v176, 16, v190
	v_and_b32_e32 v177, 0xffff0000, v190
	v_cndmask_b32_e64 v198, 0, v118, s[14:15]
	v_pk_fma_f32 v[174:175], v[104:105], v[176:177], v[174:175]
	v_lshlrev_b32_e32 v176, 16, v191
	v_and_b32_e32 v177, 0xffff0000, v191
	v_pk_fma_f32 v[174:175], v[60:61], v[176:177], v[174:175]
	v_lshlrev_b32_e32 v176, 16, v198
	v_and_b32_e32 v177, 0xffff0000, v198
	s_and_b64 s[12:13], s[10:11], s[16:17]
	v_pk_fma_f32 v[174:175], v[48:49], v[176:177], v[174:175]
	v_lshlrev_b32_e32 v176, 16, v223
	v_and_b32_e32 v177, 0xffff0000, v223
	v_cndmask_b32_e64 v227, 0, v124, s[12:13]
	v_pk_fma_f32 v[174:175], v[40:41], v[176:177], v[174:175]
	v_lshlrev_b32_e32 v176, 16, v225
	v_and_b32_e32 v177, 0xffff0000, v225
	v_pk_fma_f32 v[174:175], v[52:53], v[176:177], v[174:175]
	v_lshlrev_b32_e32 v176, 16, v227
	v_and_b32_e32 v177, 0xffff0000, v227
	v_pk_fma_f32 v[190:191], v[12:13], v[176:177], v[174:175]
	v_pk_fma_f32 v[174:175], v[102:103], v[192:193], 0 op_sel_hi:[1,1,0]
	v_lshlrev_b32_e32 v176, 16, v194
	v_and_b32_e32 v177, 0xffff0000, v194
	v_pk_fma_f32 v[174:175], v[90:91], v[176:177], v[174:175]
	v_lshlrev_b32_e32 v176, 16, v195
	v_and_b32_e32 v177, 0xffff0000, v195
	v_cndmask_b32_e64 v197, 0, v119, s[14:15]
	v_pk_fma_f32 v[174:175], v[106:107], v[176:177], v[174:175]
	v_lshlrev_b32_e32 v176, 16, v196
	v_and_b32_e32 v177, 0xffff0000, v196
	v_pk_fma_f32 v[174:175], v[62:63], v[176:177], v[174:175]
	v_lshlrev_b32_e32 v176, 16, v197
	v_and_b32_e32 v177, 0xffff0000, v197
	v_pk_fma_f32 v[174:175], v[50:51], v[176:177], v[174:175]
	v_lshlrev_b32_e32 v176, 16, v199
	v_and_b32_e32 v177, 0xffff0000, v199
	v_cndmask_b32_e64 v226, 0, v125, s[12:13]
	v_pk_fma_f32 v[174:175], v[42:43], v[176:177], v[174:175]
	v_lshlrev_b32_e32 v176, 16, v224
	v_and_b32_e32 v177, 0xffff0000, v224
	v_pk_fma_f32 v[174:175], v[54:55], v[176:177], v[174:175]
	v_lshlrev_b32_e32 v176, 16, v226
	v_and_b32_e32 v177, 0xffff0000, v226
	s_and_b64 s[8:9], s[10:11], s[8:9]
	v_pk_fma_f32 v[194:195], v[14:15], v[176:177], v[174:175]
	v_cndmask_b32_e64 v193, 0, v137, s[8:9]
	v_cndmask_b32_e64 v192, 0, v136, s[8:9]

.LBB0_652:
	s_or_b64 exec, exec, s[8:9]
	v_lshlrev_b32_e32 v174, 16, v193
	v_and_b32_e32 v175, 0xffff0000, v193
	v_pk_fma_f32 v[174:175], v[6:7], v[174:175], v[194:195]
	v_and_b32_e32 v179, 0xffff0000, v192
	v_mul_f32_e32 v176, 0xbfb8aa3b, v175
	v_exp_f32_e32 v176, v176
	v_mul_f32_e32 v177, 0xbfb8aa3b, v174
	v_exp_f32_e32 v178, v177
	v_add_f32_e32 v176, 1.0, v176
	v_rcp_f32_e32 v177, v176
	v_add_f32_e32 v176, 1.0, v178
	v_lshlrev_b32_e32 v178, 16, v192
	v_pk_fma_f32 v[178:179], v[4:5], v[178:179], v[190:191]
	v_rcp_f32_e32 v176, v176
	v_mul_f32_e32 v180, 0xbfb8aa3b, v179
	v_exp_f32_e32 v180, v180
	v_mul_f32_e32 v190, 0xbfb8aa3b, v178
	v_exp_f32_e32 v190, v190
	v_pk_mul_f32 v[174:175], v[174:175], v[176:177]
	v_add_f32_e32 v180, 1.0, v180
	v_rcp_f32_e32 v191, v180
	v_add_f32_e32 v180, 1.0, v190
	v_rcp_f32_e32 v190, v180
	s_nop 0
	v_pk_mul_f32 v[176:177], v[178:179], v[190:191]
	v_mov_b32_e32 v178, v174
	v_mov_b32_e32 v179, v176
	v_pk_mul_f32 v[178:179], v[178:179], v[178:179]
	v_mov_b32_e32 v190, v175
	v_mov_b32_e32 v191, v177
	v_pk_fma_f32 v[178:179], v[190:191], v[190:191], v[178:179]
	s_nop 0
	v_add_f32_e32 v178, v178, v179
	s_nop 1
	v_add_f32_dpp v178, v178, v178 quad_perm:[1,0,3,2] row_mask:0xf bank_mask:0xf bound_ctrl:1
	s_nop 1
	v_add_f32_dpp v178, v178, v178 quad_perm:[2,3,0,1] row_mask:0xf bank_mask:0xf bound_ctrl:1
	s_nop 1
	v_add_f32_dpp v178, v178, v178 row_half_mirror row_mask:0xf bank_mask:0xf bound_ctrl:1
	s_nop 1
	v_add_f32_dpp v178, v178, v178 row_mirror row_mask:0xf bank_mask:0xf bound_ctrl:1
	v_add_f32_e32 v178, 0x358637bd, v178
	v_rsq_f32_e32 v178, v178
	s_nop 0
	v_pk_mul_f32 v[174:175], v[174:175], v[178:179] op_sel_hi:[1,0]
	v_pk_mul_f32 v[176:177], v[176:177], v[178:179] op_sel_hi:[1,0]
	s_nop 0
	v_cvt_pk_bf16_f32 v176, v176, v177
	v_cvt_pk_bf16_f32 v177, v174, v175
	global_store_dwordx2 v[188:189], v[176:177], off offset:512 sc1
	s_and_saveexec_b64 s[0:1], s[28:29]
	s_xor_b64 s[28:29], exec, s[0:1]
	s_cbranch_execz .LBB0_654
	v_cmp_le_u32_e64 s[10:11], v218, v187
	s_and_b64 s[0:1], vcc, s[10:11]
	v_cmp_le_u32_e64 s[12:13], v221, v220
	s_and_b64 s[8:9], s[0:1], s[12:13]
	v_cndmask_b32_e64 v155, 0, v155, s[8:9]
	v_cmp_eq_u32_e64 s[14:15], 0, v218
	v_cmp_lt_u32_e64 s[16:17], v221, v220
	v_cndmask_b32_e64 v154, 0, v154, s[8:9]
	v_cndmask_b32_e64 v174, v155, 0, s[14:15]
	s_and_b64 s[8:9], s[10:11], s[16:17]
	v_lshlrev_b32_e32 v176, 16, v174
	v_and_b32_e32 v177, 0xffff0000, v174
	v_cndmask_b32_e64 v174, 0, v116, s[8:9]
	v_cndmask_b32_e64 v175, 0, v117, s[8:9]
	v_cmp_le_u32_e64 s[8:9], v222, v220
	s_and_b64 s[10:11], s[10:11], s[8:9]
	v_cndmask_b32_e64 v178, v175, 0, s[14:15]
	v_cndmask_b32_e64 v175, 0, v138, s[10:11]
	v_cndmask_b32_e64 v179, 0, v139, s[10:11]
	v_cmp_lt_u32_e64 s[10:11], v218, v187
	s_and_b64 s[0:1], vcc, s[10:11]
	v_cndmask_b32_e64 v155, v154, 0, s[14:15]
	v_cndmask_b32_e64 v174, v174, 0, s[14:15]
	v_cndmask_b32_e64 v179, v179, 0, s[14:15]
	v_cndmask_b32_e64 v175, v175, 0, s[14:15]
	s_and_b64 s[14:15], s[0:1], s[12:13]
	v_cndmask_b32_e64 v180, 0, v151, s[14:15]
	v_cndmask_b32_e64 v190, 0, v150, s[14:15]
	s_and_b64 s[14:15], s[10:11], s[16:17]
	s_and_b64 s[10:11], s[10:11], s[8:9]
	v_cndmask_b32_e64 v193, 0, v143, s[10:11]
	v_cndmask_b32_e64 v194, 0, v142, s[10:11]
	v_cmp_le_u32_e64 s[10:11], v219, v187
	s_and_b64 s[0:1], vcc, s[10:11]
	v_lshlrev_b32_e32 v154, 16, v155
	v_and_b32_e32 v155, 0xffff0000, v155
	s_and_b64 vcc, s[0:1], s[12:13]
	v_cndmask_b32_e32 v187, 0, v149, vcc
	v_cndmask_b32_e32 v195, 0, v148, vcc
	v_pk_fma_f32 v[148:149], v[96:97], v[154:155], 0 op_sel_hi:[1,1,0]
	v_lshlrev_b32_e32 v150, 16, v174
	v_and_b32_e32 v151, 0xffff0000, v174
	v_pk_fma_f32 v[148:149], v[80:81], v[150:151], v[148:149]
	v_lshlrev_b32_e32 v150, 16, v175
	v_and_b32_e32 v151, 0xffff0000, v175
	v_cndmask_b32_e64 v192, 0, v122, s[14:15]
	v_pk_fma_f32 v[148:149], v[72:73], v[150:151], v[148:149]
	v_lshlrev_b32_e32 v150, 16, v190
	v_and_b32_e32 v151, 0xffff0000, v190
	v_pk_fma_f32 v[148:149], v[84:85], v[150:151], v[148:149]
	v_lshlrev_b32_e32 v150, 16, v192
	v_and_b32_e32 v151, 0xffff0000, v192
	s_and_b64 vcc, s[10:11], s[16:17]
	v_pk_fma_f32 v[148:149], v[44:45], v[150:151], v[148:149]
	v_lshlrev_b32_e32 v150, 16, v194
	v_and_b32_e32 v151, 0xffff0000, v194
	v_cndmask_b32_e32 v197, 0, v128, vcc
	v_pk_fma_f32 v[148:149], v[32:33], v[150:151], v[148:149]
	v_lshlrev_b32_e32 v150, 16, v195
	v_and_b32_e32 v151, 0xffff0000, v195
	v_pk_fma_f32 v[148:149], v[24:25], v[150:151], v[148:149]
	v_lshlrev_b32_e32 v150, 16, v197
	v_and_b32_e32 v151, 0xffff0000, v197
	v_pk_fma_f32 v[174:175], v[36:37], v[150:151], v[148:149]
	v_pk_fma_f32 v[148:149], v[98:99], v[176:177], 0 op_sel_hi:[1,1,0]
	v_lshlrev_b32_e32 v150, 16, v178
	v_and_b32_e32 v151, 0xffff0000, v178
	v_pk_fma_f32 v[148:149], v[82:83], v[150:151], v[148:149]
	v_lshlrev_b32_e32 v150, 16, v179
	v_and_b32_e32 v151, 0xffff0000, v179
	v_cndmask_b32_e64 v191, 0, v123, s[14:15]
	v_pk_fma_f32 v[148:149], v[74:75], v[150:151], v[148:149]
	v_lshlrev_b32_e32 v150, 16, v180
	v_and_b32_e32 v151, 0xffff0000, v180
	v_pk_fma_f32 v[148:149], v[86:87], v[150:151], v[148:149]
	v_lshlrev_b32_e32 v150, 16, v191
	v_and_b32_e32 v151, 0xffff0000, v191
	v_pk_fma_f32 v[148:149], v[46:47], v[150:151], v[148:149]
	v_lshlrev_b32_e32 v150, 16, v193
	v_and_b32_e32 v151, 0xffff0000, v193
	v_cndmask_b32_e32 v196, 0, v129, vcc
	v_pk_fma_f32 v[148:149], v[34:35], v[150:151], v[148:149]
	v_lshlrev_b32_e32 v150, 16, v187
	v_and_b32_e32 v151, 0xffff0000, v187
	v_pk_fma_f32 v[148:149], v[26:27], v[150:151], v[148:149]
	v_lshlrev_b32_e32 v150, 16, v196
	v_and_b32_e32 v151, 0xffff0000, v196
	s_and_b64 vcc, s[10:11], s[8:9]
	v_pk_fma_f32 v[178:179], v[38:39], v[150:151], v[148:149]
	v_cndmask_b32_e32 v177, 0, v131, vcc
	v_cndmask_b32_e32 v176, 0, v130, vcc

.LBB0_696:
	v_add_u32_e32 v124, s0, v144
	v_mov_b64_e32 v[126:127], s[12:13]
	v_ashrrev_i32_e32 v125, 31, v124
	v_mad_i64_i32 v[126:127], s[0:1], v162, s2, v[126:127]
	v_lshl_add_u64 v[126:127], v[124:125], 1, v[126:127]
	v_cvt_pk_bf16_f32 v128, v148, v149
	v_cvt_pk_bf16_f32 v129, v150, v151
	v_cvt_pk_bf16_f32 v130, v152, v153
	v_cvt_pk_bf16_f32 v131, v154, v155
	s_cmp_lt_i32 s19, 2
	s_mov_b64 s[28:29], -1
	global_store_dwordx4 v[126:127], v[128:131], off sc1
	s_cbranch_scc1 .LBB0_702
	s_cmp_gt_i32 s19, 2
	s_cbranch_scc0 .LBB0_699
	v_lshlrev_b32_e32 v180, 3, v161
	v_lshl_add_u64 v[128:129], s[14:15], 0, v[180:181]
	v_lshlrev_b32_e32 v180, 3, v159
	v_lshl_add_u64 v[128:129], v[128:129], 0, v[180:181]
	global_load_dwordx4 v[148:151], v[128:129], off offset:16
	s_nop 0
	global_load_dwordx4 v[128:131], v[128:129], off
	s_mov_b64 s[28:29], 0
	s_waitcnt vmcnt(0)
	v_pk_mul_f32 v[152:153], v[120:121], v[128:129] op_sel:[1,1] op_sel_hi:[1,0]
	s_nop 0
	v_pk_fma_f32 v[154:155], v[120:121], v[128:129], v[152:153] neg_lo:[0,0,1] neg_hi:[0,0,1]
	v_pk_fma_f32 v[128:129], v[120:121], v[128:129], v[152:153] op_sel_hi:[0,1,1]
	v_mov_b32_e32 v155, v129
	v_pk_mul_f32 v[128:129], v[146:147], v[154:155] op_sel_hi:[0,1]
	v_mul_f32_e32 v152, v123, v131
	v_mul_f32_e32 v154, v122, v131
	v_pk_fma_f32 v[152:153], v[122:123], v[130:131], v[152:153] op_sel_hi:[1,1,0] neg_lo:[0,0,1] neg_hi:[0,0,1]
	v_pk_fma_f32 v[130:131], v[122:123], v[130:131], v[154:155] op_sel:[0,1,0] op_sel_hi:[1,0,0]
	s_nop 0
	v_mov_b32_e32 v153, v131
	v_pk_mul_f32 v[130:131], v[146:147], v[152:153] op_sel_hi:[0,1]
	v_pk_mul_f32 v[152:153], v[116:117], v[148:149] op_sel:[1,1] op_sel_hi:[1,0]
	s_nop 0
	v_pk_fma_f32 v[154:155], v[116:117], v[148:149], v[152:153] neg_lo:[0,0,1] neg_hi:[0,0,1]
	v_pk_fma_f32 v[148:149], v[116:117], v[148:149], v[152:153] op_sel_hi:[0,1,1]
	v_mov_b32_e32 v155, v149
	v_pk_mul_f32 v[148:149], v[146:147], v[154:155] op_sel_hi:[0,1]
	v_mul_f32_e32 v152, v119, v151
	v_mul_f32_e32 v154, v118, v151
	v_pk_fma_f32 v[152:153], v[118:119], v[150:151], v[152:153] op_sel_hi:[1,1,0] neg_lo:[0,0,1] neg_hi:[0,0,1]
	v_pk_fma_f32 v[150:151], v[118:119], v[150:151], v[154:155] op_sel:[0,1,0] op_sel_hi:[1,0,0]
	s_nop 0
	v_mov_b32_e32 v153, v151
	v_pk_mul_f32 v[150:151], v[146:147], v[152:153] op_sel_hi:[0,1]

.LBB0_706:
	v_cvt_pk_bf16_f32 v116, v128, v129
	v_cvt_pk_bf16_f32 v117, v130, v131
	v_cvt_pk_bf16_f32 v118, v148, v149
	v_cvt_pk_bf16_f32 v119, v150, v151
	global_store_dwordx4 v[126:127], v[116:119], off offset:256 sc1
	s_cmp_lt_i32 s19, 2
	s_mov_b64 s[28:29], -1
	v_mov_b32_e32 v116, v160
	s_nop 0
	v_add3_u32 v127, v116, s4, 16
	v_bitop3_b32 v116, v127, s86, v254 bitop3:0x6c
	v_cmp_gt_i32_e32 vcc, s86, v127
	v_add_u32_e32 v116, 0x100, v116
	s_nop 0
	v_cndmask_b32_sdwa v116, v116, v127, vcc dst_sel:DWORD dst_unused:UNUSED_PAD src0_sel:DWORD src1_sel:BYTE_0
	v_lshlrev_b32_e32 v126, 5, v116
	s_cbranch_scc1 .LBB0_712
	s_cmp_gt_i32 s19, 2
	s_cbranch_scc0 .LBB0_709
	v_lshlrev_b32_e32 v180, 3, v126
	v_lshl_add_u64 v[116:117], s[14:15], 0, v[180:181]
	v_lshlrev_b32_e32 v180, 3, v159
	v_lshl_add_u64 v[116:117], v[116:117], 0, v[180:181]
	global_load_dwordx4 v[120:123], v[116:117], off offset:16
	s_nop 0
	global_load_dwordx4 v[116:119], v[116:117], off
	s_mov_b64 s[28:29], 0
	s_waitcnt vmcnt(0)
	v_pk_mul_f32 v[128:129], v[112:113], v[116:117] op_sel:[1,1] op_sel_hi:[1,0]
	s_nop 0
	v_pk_fma_f32 v[130:131], v[112:113], v[116:117], v[128:129] neg_lo:[0,0,1] neg_hi:[0,0,1]
	v_pk_fma_f32 v[116:117], v[112:113], v[116:117], v[128:129] op_sel_hi:[0,1,1]
	v_mov_b32_e32 v131, v117
	v_pk_mul_f32 v[116:117], v[146:147], v[130:131] op_sel_hi:[0,1]
	v_mul_f32_e32 v128, v115, v119
	v_mul_f32_e32 v130, v114, v119
	v_pk_fma_f32 v[128:129], v[114:115], v[118:119], v[128:129] op_sel_hi:[1,1,0] neg_lo:[0,0,1] neg_hi:[0,0,1]
	v_pk_fma_f32 v[118:119], v[114:115], v[118:119], v[130:131] op_sel:[0,1,0] op_sel_hi:[1,0,0]
	s_nop 0
	v_mov_b32_e32 v129, v119
	v_pk_mul_f32 v[118:119], v[146:147], v[128:129] op_sel_hi:[0,1]
	v_pk_mul_f32 v[128:129], v[108:109], v[120:121] op_sel:[1,1] op_sel_hi:[1,0]
	s_nop 0
	v_pk_fma_f32 v[130:131], v[108:109], v[120:121], v[128:129] neg_lo:[0,0,1] neg_hi:[0,0,1]
	v_pk_fma_f32 v[120:121], v[108:109], v[120:121], v[128:129] op_sel_hi:[0,1,1]
	v_mov_b32_e32 v131, v121
	v_pk_mul_f32 v[120:121], v[146:147], v[130:131] op_sel_hi:[0,1]
	v_mul_f32_e32 v128, v111, v123
	v_mul_f32_e32 v130, v110, v123
	v_pk_fma_f32 v[128:129], v[110:111], v[122:123], v[128:129] op_sel_hi:[1,1,0] neg_lo:[0,0,1] neg_hi:[0,0,1]
	v_pk_fma_f32 v[122:123], v[110:111], v[122:123], v[130:131] op_sel:[0,1,0] op_sel_hi:[1,0,0]
	s_nop 0
	v_mov_b32_e32 v129, v123
	v_pk_mul_f32 v[122:123], v[146:147], v[128:129] op_sel_hi:[0,1]

.LBB0_716:
	v_mov_b64_e32 v[108:109], s[12:13]
	v_mad_i64_i32 v[108:109], s[0:1], v127, s2, v[108:109]
	v_lshl_add_u64 v[108:109], v[124:125], 1, v[108:109]
	v_cvt_pk_bf16_f32 v110, v116, v117
	v_cvt_pk_bf16_f32 v111, v118, v119
	v_cvt_pk_bf16_f32 v112, v120, v121
	v_cvt_pk_bf16_f32 v113, v122, v123
	s_cmp_lt_i32 s19, 2
	s_mov_b64 s[28:29], -1
	global_store_dwordx4 v[108:109], v[110:113], off sc1
	s_cbranch_scc1 .LBB0_722
	s_cmp_gt_i32 s19, 2
	s_cbranch_scc0 .LBB0_719
	v_lshlrev_b32_e32 v180, 3, v126
	v_lshl_add_u64 v[110:111], s[14:15], 0, v[180:181]
	v_lshlrev_b32_e32 v180, 3, v159
	v_lshl_add_u64 v[110:111], v[110:111], 0, v[180:181]
	global_load_dwordx4 v[114:117], v[110:111], off offset:16
	s_nop 0
	global_load_dwordx4 v[110:113], v[110:111], off
	s_mov_b64 s[28:29], 0
	s_waitcnt vmcnt(0)
	v_pk_mul_f32 v[118:119], v[104:105], v[110:111] op_sel:[1,1] op_sel_hi:[1,0]
	s_nop 0
	v_pk_fma_f32 v[120:121], v[104:105], v[110:111], v[118:119] neg_lo:[0,0,1] neg_hi:[0,0,1]
	v_pk_fma_f32 v[110:111], v[104:105], v[110:111], v[118:119] op_sel_hi:[0,1,1]
	v_mov_b32_e32 v121, v111
	v_pk_mul_f32 v[110:111], v[146:147], v[120:121] op_sel_hi:[0,1]
	v_mul_f32_e32 v118, v107, v113
	v_mul_f32_e32 v120, v106, v113
	v_pk_fma_f32 v[118:119], v[106:107], v[112:113], v[118:119] op_sel_hi:[1,1,0] neg_lo:[0,0,1] neg_hi:[0,0,1]
	v_pk_fma_f32 v[112:113], v[106:107], v[112:113], v[120:121] op_sel:[0,1,0] op_sel_hi:[1,0,0]
	s_nop 0
	v_mov_b32_e32 v119, v113
	v_pk_mul_f32 v[112:113], v[146:147], v[118:119] op_sel_hi:[0,1]
	v_pk_mul_f32 v[118:119], v[100:101], v[114:115] op_sel:[1,1] op_sel_hi:[1,0]
	s_nop 0
	v_pk_fma_f32 v[120:121], v[100:101], v[114:115], v[118:119] neg_lo:[0,0,1] neg_hi:[0,0,1]
	v_pk_fma_f32 v[114:115], v[100:101], v[114:115], v[118:119] op_sel_hi:[0,1,1]
	v_mov_b32_e32 v121, v115
	v_pk_mul_f32 v[114:115], v[146:147], v[120:121] op_sel_hi:[0,1]
	v_mul_f32_e32 v118, v103, v117
	v_mul_f32_e32 v120, v102, v117
	v_pk_fma_f32 v[118:119], v[102:103], v[116:117], v[118:119] op_sel_hi:[1,1,0] neg_lo:[0,0,1] neg_hi:[0,0,1]
	v_pk_fma_f32 v[116:117], v[102:103], v[116:117], v[120:121] op_sel:[0,1,0] op_sel_hi:[1,0,0]
	s_nop 0
	v_mov_b32_e32 v119, v117
	v_pk_mul_f32 v[116:117], v[146:147], v[118:119] op_sel_hi:[0,1]

.LBB0_726:
	v_cvt_pk_bf16_f32 v100, v110, v111
	v_cvt_pk_bf16_f32 v101, v112, v113
	v_cvt_pk_bf16_f32 v102, v114, v115
	v_cvt_pk_bf16_f32 v103, v116, v117
	global_store_dwordx4 v[108:109], v[100:103], off offset:256 sc1
	s_cmp_lt_i32 s19, 2
	s_mov_b64 s[28:29], -1
	v_mov_b32_e32 v100, v160
	s_nop 0
	v_add3_u32 v109, v100, s4, 32
	v_bitop3_b32 v100, v109, s86, v254 bitop3:0x6c
	v_cmp_gt_i32_e32 vcc, s86, v109
	v_add_u32_e32 v100, 0x100, v100
	s_nop 0
	v_cndmask_b32_sdwa v100, v100, v109, vcc dst_sel:DWORD dst_unused:UNUSED_PAD src0_sel:DWORD src1_sel:BYTE_0
	v_lshlrev_b32_e32 v108, 5, v100
	s_cbranch_scc1 .LBB0_732
	s_cmp_gt_i32 s19, 2
	s_cbranch_scc0 .LBB0_729
	v_lshlrev_b32_e32 v180, 3, v108
	v_lshl_add_u64 v[100:101], s[14:15], 0, v[180:181]
	v_lshlrev_b32_e32 v180, 3, v159
	v_lshl_add_u64 v[100:101], v[100:101], 0, v[180:181]
	global_load_dwordx4 v[104:107], v[100:101], off offset:16
	s_nop 0
	global_load_dwordx4 v[100:103], v[100:101], off
	s_mov_b64 s[28:29], 0
	s_waitcnt vmcnt(0)
	v_pk_mul_f32 v[110:111], v[96:97], v[100:101] op_sel:[1,1] op_sel_hi:[1,0]
	s_nop 0
	v_pk_fma_f32 v[112:113], v[96:97], v[100:101], v[110:111] neg_lo:[0,0,1] neg_hi:[0,0,1]
	v_pk_fma_f32 v[100:101], v[96:97], v[100:101], v[110:111] op_sel_hi:[0,1,1]
	v_mov_b32_e32 v113, v101
	v_pk_mul_f32 v[100:101], v[146:147], v[112:113] op_sel_hi:[0,1]
	v_mul_f32_e32 v110, v99, v103
	v_mul_f32_e32 v112, v98, v103
	v_pk_fma_f32 v[110:111], v[98:99], v[102:103], v[110:111] op_sel_hi:[1,1,0] neg_lo:[0,0,1] neg_hi:[0,0,1]
	v_pk_fma_f32 v[102:103], v[98:99], v[102:103], v[112:113] op_sel:[0,1,0] op_sel_hi:[1,0,0]
	s_nop 0
	v_mov_b32_e32 v111, v103
	v_pk_mul_f32 v[102:103], v[146:147], v[110:111] op_sel_hi:[0,1]
	v_pk_mul_f32 v[110:111], v[92:93], v[104:105] op_sel:[1,1] op_sel_hi:[1,0]
	s_nop 0
	v_pk_fma_f32 v[112:113], v[92:93], v[104:105], v[110:111] neg_lo:[0,0,1] neg_hi:[0,0,1]
	v_pk_fma_f32 v[104:105], v[92:93], v[104:105], v[110:111] op_sel_hi:[0,1,1]
	v_mov_b32_e32 v113, v105
	v_pk_mul_f32 v[104:105], v[146:147], v[112:113] op_sel_hi:[0,1]
	v_mul_f32_e32 v110, v95, v107
	v_mul_f32_e32 v112, v94, v107
	v_pk_fma_f32 v[110:111], v[94:95], v[106:107], v[110:111] op_sel_hi:[1,1,0] neg_lo:[0,0,1] neg_hi:[0,0,1]
	v_pk_fma_f32 v[106:107], v[94:95], v[106:107], v[112:113] op_sel:[0,1,0] op_sel_hi:[1,0,0]
	s_nop 0
	v_mov_b32_e32 v111, v107
	v_pk_mul_f32 v[106:107], v[146:147], v[110:111] op_sel_hi:[0,1]

.LBB0_736:
	v_mov_b64_e32 v[92:93], s[12:13]
	v_mad_i64_i32 v[92:93], s[0:1], v109, s2, v[92:93]
	v_lshl_add_u64 v[92:93], v[124:125], 1, v[92:93]
	v_cvt_pk_bf16_f32 v94, v100, v101
	v_cvt_pk_bf16_f32 v95, v102, v103
	v_cvt_pk_bf16_f32 v96, v104, v105
	v_cvt_pk_bf16_f32 v97, v106, v107
	s_cmp_lt_i32 s19, 2
	s_mov_b64 s[28:29], -1
	global_store_dwordx4 v[92:93], v[94:97], off sc1
	s_cbranch_scc1 .LBB0_742
	s_cmp_gt_i32 s19, 2
	s_cbranch_scc0 .LBB0_739
	v_lshlrev_b32_e32 v180, 3, v108
	v_lshl_add_u64 v[94:95], s[14:15], 0, v[180:181]
	v_lshlrev_b32_e32 v180, 3, v159
	v_lshl_add_u64 v[94:95], v[94:95], 0, v[180:181]
	global_load_dwordx4 v[98:101], v[94:95], off offset:16
	s_nop 0
	global_load_dwordx4 v[94:97], v[94:95], off
	s_mov_b64 s[28:29], 0
	s_waitcnt vmcnt(0)
	v_pk_mul_f32 v[102:103], v[88:89], v[94:95] op_sel:[1,1] op_sel_hi:[1,0]
	s_nop 0
	v_pk_fma_f32 v[104:105], v[88:89], v[94:95], v[102:103] neg_lo:[0,0,1] neg_hi:[0,0,1]
	v_pk_fma_f32 v[94:95], v[88:89], v[94:95], v[102:103] op_sel_hi:[0,1,1]
	v_mov_b32_e32 v105, v95
	v_pk_mul_f32 v[94:95], v[146:147], v[104:105] op_sel_hi:[0,1]
	v_mul_f32_e32 v102, v91, v97
	v_mul_f32_e32 v104, v90, v97
	v_pk_fma_f32 v[102:103], v[90:91], v[96:97], v[102:103] op_sel_hi:[1,1,0] neg_lo:[0,0,1] neg_hi:[0,0,1]
	v_pk_fma_f32 v[96:97], v[90:91], v[96:97], v[104:105] op_sel:[0,1,0] op_sel_hi:[1,0,0]
	s_nop 0
	v_mov_b32_e32 v103, v97
	v_pk_mul_f32 v[96:97], v[146:147], v[102:103] op_sel_hi:[0,1]
	v_pk_mul_f32 v[102:103], v[84:85], v[98:99] op_sel:[1,1] op_sel_hi:[1,0]
	s_nop 0
	v_pk_fma_f32 v[104:105], v[84:85], v[98:99], v[102:103] neg_lo:[0,0,1] neg_hi:[0,0,1]
	v_pk_fma_f32 v[98:99], v[84:85], v[98:99], v[102:103] op_sel_hi:[0,1,1]
	v_mov_b32_e32 v105, v99
	v_pk_mul_f32 v[98:99], v[146:147], v[104:105] op_sel_hi:[0,1]
	v_mul_f32_e32 v102, v87, v101
	v_mul_f32_e32 v104, v86, v101
	v_pk_fma_f32 v[102:103], v[86:87], v[100:101], v[102:103] op_sel_hi:[1,1,0] neg_lo:[0,0,1] neg_hi:[0,0,1]
	v_pk_fma_f32 v[100:101], v[86:87], v[100:101], v[104:105] op_sel:[0,1,0] op_sel_hi:[1,0,0]
	s_nop 0
	v_mov_b32_e32 v103, v101
	v_pk_mul_f32 v[100:101], v[146:147], v[102:103] op_sel_hi:[0,1]

.LBB0_746:
	v_cvt_pk_bf16_f32 v84, v94, v95
	v_cvt_pk_bf16_f32 v85, v96, v97
	v_cvt_pk_bf16_f32 v86, v98, v99
	v_cvt_pk_bf16_f32 v87, v100, v101
	global_store_dwordx4 v[92:93], v[84:87], off offset:256 sc1
	s_cmp_lt_i32 s19, 2
	s_mov_b64 s[28:29], -1
	v_mov_b32_e32 v84, v160
	s_nop 0
	v_add3_u32 v84, v84, s4, 48
	v_bitop3_b32 v85, v84, s86, v254 bitop3:0x6c
	v_cmp_gt_i32_e32 vcc, s86, v84
	v_add_u32_e32 v85, 0x100, v85
	s_nop 0
	v_cndmask_b32_sdwa v85, v85, v84, vcc dst_sel:DWORD dst_unused:UNUSED_PAD src0_sel:DWORD src1_sel:BYTE_0
	v_lshlrev_b32_e32 v94, 5, v85
	s_cbranch_scc1 .LBB0_752
	s_cmp_gt_i32 s19, 2
	s_cbranch_scc0 .LBB0_749
	v_lshlrev_b32_e32 v180, 3, v94
	v_lshl_add_u64 v[86:87], s[14:15], 0, v[180:181]
	v_lshlrev_b32_e32 v180, 3, v159
	v_lshl_add_u64 v[86:87], v[86:87], 0, v[180:181]
	global_load_dwordx4 v[90:93], v[86:87], off offset:16
	s_nop 0
	global_load_dwordx4 v[86:89], v[86:87], off
	s_mov_b64 s[28:29], 0
	s_waitcnt vmcnt(0)
	v_pk_mul_f32 v[96:97], v[80:81], v[86:87] op_sel:[1,1] op_sel_hi:[1,0]
	s_nop 0
	v_pk_fma_f32 v[98:99], v[80:81], v[86:87], v[96:97] neg_lo:[0,0,1] neg_hi:[0,0,1]
	v_pk_fma_f32 v[86:87], v[80:81], v[86:87], v[96:97] op_sel_hi:[0,1,1]
	v_mov_b32_e32 v99, v87
	v_pk_mul_f32 v[86:87], v[146:147], v[98:99] op_sel_hi:[0,1]
	v_mul_f32_e32 v96, v83, v89
	v_mul_f32_e32 v98, v82, v89
	v_pk_fma_f32 v[96:97], v[82:83], v[88:89], v[96:97] op_sel_hi:[1,1,0] neg_lo:[0,0,1] neg_hi:[0,0,1]
	v_pk_fma_f32 v[88:89], v[82:83], v[88:89], v[98:99] op_sel:[0,1,0] op_sel_hi:[1,0,0]
	s_nop 0
	v_mov_b32_e32 v97, v89
	v_pk_mul_f32 v[88:89], v[146:147], v[96:97] op_sel_hi:[0,1]
	v_pk_mul_f32 v[96:97], v[76:77], v[90:91] op_sel:[1,1] op_sel_hi:[1,0]
	s_nop 0
	v_pk_fma_f32 v[98:99], v[76:77], v[90:91], v[96:97] neg_lo:[0,0,1] neg_hi:[0,0,1]
	v_pk_fma_f32 v[90:91], v[76:77], v[90:91], v[96:97] op_sel_hi:[0,1,1]
	v_mov_b32_e32 v99, v91
	v_pk_mul_f32 v[90:91], v[146:147], v[98:99] op_sel_hi:[0,1]
	v_mul_f32_e32 v96, v79, v93
	v_mul_f32_e32 v98, v78, v93
	v_pk_fma_f32 v[96:97], v[78:79], v[92:93], v[96:97] op_sel_hi:[1,1,0] neg_lo:[0,0,1] neg_hi:[0,0,1]
	v_pk_fma_f32 v[92:93], v[78:79], v[92:93], v[98:99] op_sel:[0,1,0] op_sel_hi:[1,0,0]
	s_nop 0
	v_mov_b32_e32 v97, v93
	v_pk_mul_f32 v[92:93], v[146:147], v[96:97] op_sel_hi:[0,1]

.LBB0_756:
	v_mov_b64_e32 v[76:77], s[12:13]
	v_mad_i64_i32 v[76:77], s[0:1], v84, s2, v[76:77]
	v_lshl_add_u64 v[84:85], v[124:125], 1, v[76:77]
	v_cvt_pk_bf16_f32 v76, v86, v87
	v_cvt_pk_bf16_f32 v77, v88, v89
	v_cvt_pk_bf16_f32 v78, v90, v91
	v_cvt_pk_bf16_f32 v79, v92, v93
	s_cmp_lt_i32 s19, 2
	s_mov_b64 s[28:29], -1
	global_store_dwordx4 v[84:85], v[76:79], off sc1
	s_cbranch_scc1 .LBB0_762
	s_cmp_gt_i32 s19, 2
	s_cbranch_scc0 .LBB0_759
	v_lshlrev_b32_e32 v180, 3, v94
	v_lshl_add_u64 v[76:77], s[14:15], 0, v[180:181]
	v_lshlrev_b32_e32 v180, 3, v159
	v_lshl_add_u64 v[76:77], v[76:77], 0, v[180:181]
	global_load_dwordx4 v[80:83], v[76:77], off offset:16
	s_nop 0
	global_load_dwordx4 v[76:79], v[76:77], off
	s_mov_b64 s[28:29], 0
	s_waitcnt vmcnt(0)
	v_pk_mul_f32 v[86:87], v[72:73], v[76:77] op_sel:[1,1] op_sel_hi:[1,0]
	s_nop 0
	v_pk_fma_f32 v[88:89], v[72:73], v[76:77], v[86:87] neg_lo:[0,0,1] neg_hi:[0,0,1]
	v_pk_fma_f32 v[76:77], v[72:73], v[76:77], v[86:87] op_sel_hi:[0,1,1]
	v_mov_b32_e32 v89, v77
	v_pk_mul_f32 v[76:77], v[146:147], v[88:89] op_sel_hi:[0,1]
	v_mul_f32_e32 v86, v75, v79
	v_mul_f32_e32 v88, v74, v79
	v_pk_fma_f32 v[86:87], v[74:75], v[78:79], v[86:87] op_sel_hi:[1,1,0] neg_lo:[0,0,1] neg_hi:[0,0,1]
	v_pk_fma_f32 v[78:79], v[74:75], v[78:79], v[88:89] op_sel:[0,1,0] op_sel_hi:[1,0,0]
	s_nop 0
	v_mov_b32_e32 v87, v79
	v_pk_mul_f32 v[78:79], v[146:147], v[86:87] op_sel_hi:[0,1]
	v_pk_mul_f32 v[86:87], v[68:69], v[80:81] op_sel:[1,1] op_sel_hi:[1,0]
	s_nop 0
	v_pk_fma_f32 v[88:89], v[68:69], v[80:81], v[86:87] neg_lo:[0,0,1] neg_hi:[0,0,1]
	v_pk_fma_f32 v[80:81], v[68:69], v[80:81], v[86:87] op_sel_hi:[0,1,1]
	v_mov_b32_e32 v89, v81
	v_pk_mul_f32 v[80:81], v[146:147], v[88:89] op_sel_hi:[0,1]
	v_mul_f32_e32 v86, v71, v83
	v_mul_f32_e32 v88, v70, v83
	v_pk_fma_f32 v[86:87], v[70:71], v[82:83], v[86:87] op_sel_hi:[1,1,0] neg_lo:[0,0,1] neg_hi:[0,0,1]
	v_pk_fma_f32 v[82:83], v[70:71], v[82:83], v[88:89] op_sel:[0,1,0] op_sel_hi:[1,0,0]
	s_nop 0
	v_mov_b32_e32 v87, v83
	v_pk_mul_f32 v[82:83], v[146:147], v[86:87] op_sel_hi:[0,1]

.LBB0_766:
	v_cvt_pk_bf16_f32 v68, v76, v77
	v_cvt_pk_bf16_f32 v69, v78, v79
	v_cvt_pk_bf16_f32 v70, v80, v81
	v_cvt_pk_bf16_f32 v71, v82, v83
	global_store_dwordx4 v[84:85], v[68:71], off offset:256 sc1
	s_add_i32 s0, s4, 0x80
	s_cmp_lt_i32 s19, 2
	v_mov_b32_e32 v68, v160
	s_mov_b64 s[28:29], -1
	v_add_u32_e32 v77, s0, v68
	v_bitop3_b32 v68, v77, s86, v254 bitop3:0x6c
	v_cmp_gt_i32_e32 vcc, s86, v77
	v_add_u32_e32 v68, 0x100, v68
	s_nop 0
	v_cndmask_b32_sdwa v68, v68, v77, vcc dst_sel:DWORD dst_unused:UNUSED_PAD src0_sel:DWORD src1_sel:BYTE_0
	v_lshlrev_b32_e32 v76, 5, v68
	s_cbranch_scc1 .LBB0_772
	s_cmp_gt_i32 s19, 2
	s_cbranch_scc0 .LBB0_769
	v_lshlrev_b32_e32 v180, 3, v76
	v_lshl_add_u64 v[68:69], s[14:15], 0, v[180:181]
	v_lshlrev_b32_e32 v180, 3, v159
	v_lshl_add_u64 v[68:69], v[68:69], 0, v[180:181]
	global_load_dwordx4 v[72:75], v[68:69], off offset:16
	s_nop 0
	global_load_dwordx4 v[68:71], v[68:69], off
	s_mov_b64 s[28:29], 0
	s_waitcnt vmcnt(0)
	v_pk_mul_f32 v[78:79], v[64:65], v[68:69] op_sel:[1,1] op_sel_hi:[1,0]
	s_nop 0
	v_pk_fma_f32 v[80:81], v[64:65], v[68:69], v[78:79] neg_lo:[0,0,1] neg_hi:[0,0,1]
	v_pk_fma_f32 v[68:69], v[64:65], v[68:69], v[78:79] op_sel_hi:[0,1,1]
	v_mov_b32_e32 v81, v69
	v_pk_mul_f32 v[68:69], v[146:147], v[80:81] op_sel_hi:[0,1]
	v_mul_f32_e32 v78, v67, v71
	v_mul_f32_e32 v80, v66, v71
	v_pk_fma_f32 v[78:79], v[66:67], v[70:71], v[78:79] op_sel_hi:[1,1,0] neg_lo:[0,0,1] neg_hi:[0,0,1]
	v_pk_fma_f32 v[70:71], v[66:67], v[70:71], v[80:81] op_sel:[0,1,0] op_sel_hi:[1,0,0]
	s_nop 0
	v_mov_b32_e32 v79, v71
	v_pk_mul_f32 v[70:71], v[146:147], v[78:79] op_sel_hi:[0,1]
	v_pk_mul_f32 v[78:79], v[60:61], v[72:73] op_sel:[1,1] op_sel_hi:[1,0]
	s_nop 0
	v_pk_fma_f32 v[80:81], v[60:61], v[72:73], v[78:79] neg_lo:[0,0,1] neg_hi:[0,0,1]
	v_pk_fma_f32 v[72:73], v[60:61], v[72:73], v[78:79] op_sel_hi:[0,1,1]
	v_mov_b32_e32 v81, v73
	v_pk_mul_f32 v[72:73], v[146:147], v[80:81] op_sel_hi:[0,1]
	v_mul_f32_e32 v78, v63, v75
	v_mul_f32_e32 v80, v62, v75
	v_pk_fma_f32 v[78:79], v[62:63], v[74:75], v[78:79] op_sel_hi:[1,1,0] neg_lo:[0,0,1] neg_hi:[0,0,1]
	v_pk_fma_f32 v[74:75], v[62:63], v[74:75], v[80:81] op_sel:[0,1,0] op_sel_hi:[1,0,0]
	s_nop 0
	v_mov_b32_e32 v79, v75
	v_pk_mul_f32 v[74:75], v[146:147], v[78:79] op_sel_hi:[0,1]

.LBB0_776:
	v_mov_b64_e32 v[60:61], s[12:13]
	v_mad_i64_i32 v[60:61], s[0:1], v77, s2, v[60:61]
	v_lshl_add_u64 v[60:61], v[124:125], 1, v[60:61]
	v_cvt_pk_bf16_f32 v62, v68, v69
	v_cvt_pk_bf16_f32 v63, v70, v71
	v_cvt_pk_bf16_f32 v64, v72, v73
	v_cvt_pk_bf16_f32 v65, v74, v75
	s_cmp_lt_i32 s19, 2
	s_mov_b64 s[28:29], -1
	global_store_dwordx4 v[60:61], v[62:65], off sc1
	s_cbranch_scc1 .LBB0_782
	s_cmp_gt_i32 s19, 2
	s_cbranch_scc0 .LBB0_779
	v_lshlrev_b32_e32 v180, 3, v76
	v_lshl_add_u64 v[62:63], s[14:15], 0, v[180:181]
	v_lshlrev_b32_e32 v180, 3, v159
	v_lshl_add_u64 v[62:63], v[62:63], 0, v[180:181]
	global_load_dwordx4 v[66:69], v[62:63], off offset:16
	s_nop 0
	global_load_dwordx4 v[62:65], v[62:63], off
	s_mov_b64 s[28:29], 0
	s_waitcnt vmcnt(0)
	v_pk_mul_f32 v[70:71], v[56:57], v[62:63] op_sel:[1,1] op_sel_hi:[1,0]
	s_nop 0
	v_pk_fma_f32 v[72:73], v[56:57], v[62:63], v[70:71] neg_lo:[0,0,1] neg_hi:[0,0,1]
	v_pk_fma_f32 v[62:63], v[56:57], v[62:63], v[70:71] op_sel_hi:[0,1,1]
	v_mov_b32_e32 v73, v63
	v_pk_mul_f32 v[62:63], v[146:147], v[72:73] op_sel_hi:[0,1]
	v_mul_f32_e32 v70, v59, v65
	v_mul_f32_e32 v72, v58, v65
	v_pk_fma_f32 v[70:71], v[58:59], v[64:65], v[70:71] op_sel_hi:[1,1,0] neg_lo:[0,0,1] neg_hi:[0,0,1]
	v_pk_fma_f32 v[64:65], v[58:59], v[64:65], v[72:73] op_sel:[0,1,0] op_sel_hi:[1,0,0]
	s_nop 0
	v_mov_b32_e32 v71, v65
	v_pk_mul_f32 v[64:65], v[146:147], v[70:71] op_sel_hi:[0,1]
	v_pk_mul_f32 v[70:71], v[52:53], v[66:67] op_sel:[1,1] op_sel_hi:[1,0]
	s_nop 0
	v_pk_fma_f32 v[72:73], v[52:53], v[66:67], v[70:71] neg_lo:[0,0,1] neg_hi:[0,0,1]
	v_pk_fma_f32 v[66:67], v[52:53], v[66:67], v[70:71] op_sel_hi:[0,1,1]
	v_mov_b32_e32 v73, v67
	v_pk_mul_f32 v[66:67], v[146:147], v[72:73] op_sel_hi:[0,1]
	v_mul_f32_e32 v70, v55, v69
	v_mul_f32_e32 v72, v54, v69
	v_pk_fma_f32 v[70:71], v[54:55], v[68:69], v[70:71] op_sel_hi:[1,1,0] neg_lo:[0,0,1] neg_hi:[0,0,1]
	v_pk_fma_f32 v[68:69], v[54:55], v[68:69], v[72:73] op_sel:[0,1,0] op_sel_hi:[1,0,0]
	s_nop 0
	v_mov_b32_e32 v71, v69
	v_pk_mul_f32 v[68:69], v[146:147], v[70:71] op_sel_hi:[0,1]

.LBB0_786:
	v_cvt_pk_bf16_f32 v52, v62, v63
	v_cvt_pk_bf16_f32 v53, v64, v65
	v_cvt_pk_bf16_f32 v54, v66, v67
	v_cvt_pk_bf16_f32 v55, v68, v69
	global_store_dwordx4 v[60:61], v[52:55], off offset:256 sc1
	s_add_i32 s0, s4, 0x90
	s_cmp_lt_i32 s19, 2
	v_mov_b32_e32 v52, v160
	s_mov_b64 s[28:29], -1
	v_add_u32_e32 v61, s0, v52
	v_bitop3_b32 v52, v61, s86, v254 bitop3:0x6c
	v_cmp_gt_i32_e32 vcc, s86, v61
	v_add_u32_e32 v52, 0x100, v52
	s_nop 0
	v_cndmask_b32_sdwa v52, v52, v61, vcc dst_sel:DWORD dst_unused:UNUSED_PAD src0_sel:DWORD src1_sel:BYTE_0
	v_lshlrev_b32_e32 v60, 5, v52
	s_cbranch_scc1 .LBB0_792
	s_cmp_gt_i32 s19, 2
	s_cbranch_scc0 .LBB0_789
	v_lshlrev_b32_e32 v180, 3, v60
	v_lshl_add_u64 v[52:53], s[14:15], 0, v[180:181]
	v_lshlrev_b32_e32 v180, 3, v159
	v_lshl_add_u64 v[52:53], v[52:53], 0, v[180:181]
	global_load_dwordx4 v[56:59], v[52:53], off offset:16
	s_nop 0
	global_load_dwordx4 v[52:55], v[52:53], off
	s_mov_b64 s[28:29], 0
	s_waitcnt vmcnt(0)
	v_pk_mul_f32 v[62:63], v[48:49], v[52:53] op_sel:[1,1] op_sel_hi:[1,0]
	s_nop 0
	v_pk_fma_f32 v[64:65], v[48:49], v[52:53], v[62:63] neg_lo:[0,0,1] neg_hi:[0,0,1]
	v_pk_fma_f32 v[52:53], v[48:49], v[52:53], v[62:63] op_sel_hi:[0,1,1]
	v_mov_b32_e32 v65, v53
	v_pk_mul_f32 v[52:53], v[146:147], v[64:65] op_sel_hi:[0,1]
	v_mul_f32_e32 v62, v51, v55
	v_mul_f32_e32 v64, v50, v55
	v_pk_fma_f32 v[62:63], v[50:51], v[54:55], v[62:63] op_sel_hi:[1,1,0] neg_lo:[0,0,1] neg_hi:[0,0,1]
	v_pk_fma_f32 v[54:55], v[50:51], v[54:55], v[64:65] op_sel:[0,1,0] op_sel_hi:[1,0,0]
	s_nop 0
	v_mov_b32_e32 v63, v55
	v_pk_mul_f32 v[54:55], v[146:147], v[62:63] op_sel_hi:[0,1]
	v_pk_mul_f32 v[62:63], v[44:45], v[56:57] op_sel:[1,1] op_sel_hi:[1,0]
	s_nop 0
	v_pk_fma_f32 v[64:65], v[44:45], v[56:57], v[62:63] neg_lo:[0,0,1] neg_hi:[0,0,1]
	v_pk_fma_f32 v[56:57], v[44:45], v[56:57], v[62:63] op_sel_hi:[0,1,1]
	v_mov_b32_e32 v65, v57
	v_pk_mul_f32 v[56:57], v[146:147], v[64:65] op_sel_hi:[0,1]
	v_mul_f32_e32 v62, v47, v59
	v_mul_f32_e32 v64, v46, v59
	v_pk_fma_f32 v[62:63], v[46:47], v[58:59], v[62:63] op_sel_hi:[1,1,0] neg_lo:[0,0,1] neg_hi:[0,0,1]
	v_pk_fma_f32 v[58:59], v[46:47], v[58:59], v[64:65] op_sel:[0,1,0] op_sel_hi:[1,0,0]
	s_nop 0
	v_mov_b32_e32 v63, v59
	v_pk_mul_f32 v[58:59], v[146:147], v[62:63] op_sel_hi:[0,1]

.LBB0_796:
	v_mov_b64_e32 v[44:45], s[12:13]
	v_mad_i64_i32 v[44:45], s[0:1], v61, s2, v[44:45]
	v_lshl_add_u64 v[44:45], v[124:125], 1, v[44:45]
	v_cvt_pk_bf16_f32 v46, v52, v53
	v_cvt_pk_bf16_f32 v47, v54, v55
	v_cvt_pk_bf16_f32 v48, v56, v57
	v_cvt_pk_bf16_f32 v49, v58, v59
	s_cmp_lt_i32 s19, 2
	s_mov_b64 s[28:29], -1
	global_store_dwordx4 v[44:45], v[46:49], off sc1
	s_cbranch_scc1 .LBB0_802
	s_cmp_gt_i32 s19, 2
	s_cbranch_scc0 .LBB0_799
	v_lshlrev_b32_e32 v180, 3, v60
	v_lshl_add_u64 v[46:47], s[14:15], 0, v[180:181]
	v_lshlrev_b32_e32 v180, 3, v159
	v_lshl_add_u64 v[46:47], v[46:47], 0, v[180:181]
	global_load_dwordx4 v[50:53], v[46:47], off offset:16
	s_nop 0
	global_load_dwordx4 v[46:49], v[46:47], off
	s_mov_b64 s[28:29], 0
	s_waitcnt vmcnt(0)
	v_pk_mul_f32 v[54:55], v[40:41], v[46:47] op_sel:[1,1] op_sel_hi:[1,0]
	s_nop 0
	v_pk_fma_f32 v[56:57], v[40:41], v[46:47], v[54:55] neg_lo:[0,0,1] neg_hi:[0,0,1]
	v_pk_fma_f32 v[46:47], v[40:41], v[46:47], v[54:55] op_sel_hi:[0,1,1]
	v_mov_b32_e32 v57, v47
	v_pk_mul_f32 v[46:47], v[146:147], v[56:57] op_sel_hi:[0,1]
	v_mul_f32_e32 v54, v43, v49
	v_mul_f32_e32 v56, v42, v49
	v_pk_fma_f32 v[54:55], v[42:43], v[48:49], v[54:55] op_sel_hi:[1,1,0] neg_lo:[0,0,1] neg_hi:[0,0,1]
	v_pk_fma_f32 v[48:49], v[42:43], v[48:49], v[56:57] op_sel:[0,1,0] op_sel_hi:[1,0,0]
	s_nop 0
	v_mov_b32_e32 v55, v49
	v_pk_mul_f32 v[48:49], v[146:147], v[54:55] op_sel_hi:[0,1]
	v_pk_mul_f32 v[54:55], v[36:37], v[50:51] op_sel:[1,1] op_sel_hi:[1,0]
	s_nop 0
	v_pk_fma_f32 v[56:57], v[36:37], v[50:51], v[54:55] neg_lo:[0,0,1] neg_hi:[0,0,1]
	v_pk_fma_f32 v[50:51], v[36:37], v[50:51], v[54:55] op_sel_hi:[0,1,1]
	v_mov_b32_e32 v57, v51
	v_pk_mul_f32 v[50:51], v[146:147], v[56:57] op_sel_hi:[0,1]
	v_mul_f32_e32 v54, v39, v53
	v_mul_f32_e32 v56, v38, v53
	v_pk_fma_f32 v[54:55], v[38:39], v[52:53], v[54:55] op_sel_hi:[1,1,0] neg_lo:[0,0,1] neg_hi:[0,0,1]
	v_pk_fma_f32 v[52:53], v[38:39], v[52:53], v[56:57] op_sel:[0,1,0] op_sel_hi:[1,0,0]
	s_nop 0
	v_mov_b32_e32 v55, v53
	v_pk_mul_f32 v[52:53], v[146:147], v[54:55] op_sel_hi:[0,1]

.LBB0_806:
	v_cvt_pk_bf16_f32 v36, v46, v47
	v_cvt_pk_bf16_f32 v37, v48, v49
	v_cvt_pk_bf16_f32 v38, v50, v51
	v_cvt_pk_bf16_f32 v39, v52, v53
	global_store_dwordx4 v[44:45], v[36:39], off offset:256 sc1
	s_add_i32 s0, s4, 0xa0
	s_cmp_lt_i32 s19, 2
	v_mov_b32_e32 v36, v160
	s_mov_b64 s[28:29], -1
	v_add_u32_e32 v45, s0, v36
	v_bitop3_b32 v36, v45, s86, v254 bitop3:0x6c
	v_cmp_gt_i32_e32 vcc, s86, v45
	v_add_u32_e32 v36, 0x100, v36
	s_nop 0
	v_cndmask_b32_sdwa v36, v36, v45, vcc dst_sel:DWORD dst_unused:UNUSED_PAD src0_sel:DWORD src1_sel:BYTE_0
	v_lshlrev_b32_e32 v44, 5, v36
	s_cbranch_scc1 .LBB0_812
	s_cmp_gt_i32 s19, 2
	s_cbranch_scc0 .LBB0_809
	v_lshlrev_b32_e32 v180, 3, v44
	v_lshl_add_u64 v[36:37], s[14:15], 0, v[180:181]
	v_lshlrev_b32_e32 v180, 3, v159
	v_lshl_add_u64 v[36:37], v[36:37], 0, v[180:181]
	global_load_dwordx4 v[40:43], v[36:37], off offset:16
	s_nop 0
	global_load_dwordx4 v[36:39], v[36:37], off
	s_mov_b64 s[28:29], 0
	s_waitcnt vmcnt(0)
	v_pk_mul_f32 v[46:47], v[32:33], v[36:37] op_sel:[1,1] op_sel_hi:[1,0]
	s_nop 0
	v_pk_fma_f32 v[48:49], v[32:33], v[36:37], v[46:47] neg_lo:[0,0,1] neg_hi:[0,0,1]
	v_pk_fma_f32 v[36:37], v[32:33], v[36:37], v[46:47] op_sel_hi:[0,1,1]
	v_mov_b32_e32 v49, v37
	v_pk_mul_f32 v[36:37], v[146:147], v[48:49] op_sel_hi:[0,1]
	v_mul_f32_e32 v46, v35, v39
	v_mul_f32_e32 v48, v34, v39
	v_pk_fma_f32 v[46:47], v[34:35], v[38:39], v[46:47] op_sel_hi:[1,1,0] neg_lo:[0,0,1] neg_hi:[0,0,1]
	v_pk_fma_f32 v[38:39], v[34:35], v[38:39], v[48:49] op_sel:[0,1,0] op_sel_hi:[1,0,0]
	s_nop 0
	v_mov_b32_e32 v47, v39
	v_pk_mul_f32 v[38:39], v[146:147], v[46:47] op_sel_hi:[0,1]
	v_pk_mul_f32 v[46:47], v[28:29], v[40:41] op_sel:[1,1] op_sel_hi:[1,0]
	s_nop 0
	v_pk_fma_f32 v[48:49], v[28:29], v[40:41], v[46:47] neg_lo:[0,0,1] neg_hi:[0,0,1]
	v_pk_fma_f32 v[40:41], v[28:29], v[40:41], v[46:47] op_sel_hi:[0,1,1]
	v_mov_b32_e32 v49, v41
	v_pk_mul_f32 v[40:41], v[146:147], v[48:49] op_sel_hi:[0,1]
	v_mul_f32_e32 v46, v31, v43
	v_mul_f32_e32 v48, v30, v43
	v_pk_fma_f32 v[46:47], v[30:31], v[42:43], v[46:47] op_sel_hi:[1,1,0] neg_lo:[0,0,1] neg_hi:[0,0,1]
	v_pk_fma_f32 v[42:43], v[30:31], v[42:43], v[48:49] op_sel:[0,1,0] op_sel_hi:[1,0,0]
	s_nop 0
	v_mov_b32_e32 v47, v43
	v_pk_mul_f32 v[42:43], v[146:147], v[46:47] op_sel_hi:[0,1]

.LBB0_816:
	v_mov_b64_e32 v[28:29], s[12:13]
	v_mad_i64_i32 v[28:29], s[0:1], v45, s2, v[28:29]
	v_lshl_add_u64 v[28:29], v[124:125], 1, v[28:29]
	v_cvt_pk_bf16_f32 v30, v36, v37
	v_cvt_pk_bf16_f32 v31, v38, v39
	v_cvt_pk_bf16_f32 v32, v40, v41
	v_cvt_pk_bf16_f32 v33, v42, v43
	s_cmp_lt_i32 s19, 2
	s_mov_b64 s[28:29], -1
	global_store_dwordx4 v[28:29], v[30:33], off sc1
	s_cbranch_scc1 .LBB0_822
	s_cmp_gt_i32 s19, 2
	s_cbranch_scc0 .LBB0_819
	v_lshlrev_b32_e32 v180, 3, v44
	v_lshl_add_u64 v[30:31], s[14:15], 0, v[180:181]
	v_lshlrev_b32_e32 v180, 3, v159
	v_lshl_add_u64 v[30:31], v[30:31], 0, v[180:181]
	global_load_dwordx4 v[34:37], v[30:31], off offset:16
	s_nop 0
	global_load_dwordx4 v[30:33], v[30:31], off
	s_mov_b64 s[28:29], 0
	s_waitcnt vmcnt(0)
	v_pk_mul_f32 v[38:39], v[24:25], v[30:31] op_sel:[1,1] op_sel_hi:[1,0]
	s_nop 0
	v_pk_fma_f32 v[40:41], v[24:25], v[30:31], v[38:39] neg_lo:[0,0,1] neg_hi:[0,0,1]
	v_pk_fma_f32 v[30:31], v[24:25], v[30:31], v[38:39] op_sel_hi:[0,1,1]
	v_mov_b32_e32 v41, v31
	v_pk_mul_f32 v[30:31], v[146:147], v[40:41] op_sel_hi:[0,1]
	v_mul_f32_e32 v38, v27, v33
	v_mul_f32_e32 v40, v26, v33
	v_pk_fma_f32 v[38:39], v[26:27], v[32:33], v[38:39] op_sel_hi:[1,1,0] neg_lo:[0,0,1] neg_hi:[0,0,1]
	v_pk_fma_f32 v[32:33], v[26:27], v[32:33], v[40:41] op_sel:[0,1,0] op_sel_hi:[1,0,0]
	s_nop 0
	v_mov_b32_e32 v39, v33
	v_pk_mul_f32 v[32:33], v[146:147], v[38:39] op_sel_hi:[0,1]
	v_pk_mul_f32 v[38:39], v[20:21], v[34:35] op_sel:[1,1] op_sel_hi:[1,0]
	s_nop 0
	v_pk_fma_f32 v[40:41], v[20:21], v[34:35], v[38:39] neg_lo:[0,0,1] neg_hi:[0,0,1]
	v_pk_fma_f32 v[34:35], v[20:21], v[34:35], v[38:39] op_sel_hi:[0,1,1]
	v_mov_b32_e32 v41, v35
	v_pk_mul_f32 v[34:35], v[146:147], v[40:41] op_sel_hi:[0,1]
	v_mul_f32_e32 v38, v23, v37
	v_mul_f32_e32 v40, v22, v37
	v_pk_fma_f32 v[38:39], v[22:23], v[36:37], v[38:39] op_sel_hi:[1,1,0] neg_lo:[0,0,1] neg_hi:[0,0,1]
	v_pk_fma_f32 v[36:37], v[22:23], v[36:37], v[40:41] op_sel:[0,1,0] op_sel_hi:[1,0,0]
	s_nop 0
	v_mov_b32_e32 v39, v37
	v_pk_mul_f32 v[36:37], v[146:147], v[38:39] op_sel_hi:[0,1]

.LBB0_826:
	v_cvt_pk_bf16_f32 v20, v30, v31
	v_cvt_pk_bf16_f32 v21, v32, v33
	v_cvt_pk_bf16_f32 v22, v34, v35
	v_cvt_pk_bf16_f32 v23, v36, v37
	global_store_dwordx4 v[28:29], v[20:23], off offset:256 sc1
	s_addk_i32 s4, 0xb0
	s_cmp_lt_i32 s19, 2
	v_add_u32_e32 v29, s4, v160
	v_bitop3_b32 v20, v29, s86, v254 bitop3:0x6c
	v_cmp_gt_i32_e32 vcc, s86, v29
	v_add_u32_e32 v20, 0x100, v20
	s_mov_b64 s[28:29], -1
	v_cndmask_b32_sdwa v20, v20, v29, vcc dst_sel:DWORD dst_unused:UNUSED_PAD src0_sel:DWORD src1_sel:BYTE_0
	v_lshlrev_b32_e32 v28, 5, v20
	s_cbranch_scc1 .LBB0_832
	s_cmp_gt_i32 s19, 2
	s_cbranch_scc0 .LBB0_829
	v_lshlrev_b32_e32 v180, 3, v28
	v_lshl_add_u64 v[20:21], s[14:15], 0, v[180:181]
	v_lshlrev_b32_e32 v180, 3, v159
	v_lshl_add_u64 v[20:21], v[20:21], 0, v[180:181]
	global_load_dwordx4 v[24:27], v[20:21], off offset:16
	s_nop 0
	global_load_dwordx4 v[20:23], v[20:21], off
	s_mov_b64 s[28:29], 0
	s_waitcnt vmcnt(0)
	v_pk_mul_f32 v[30:31], v[16:17], v[20:21] op_sel:[1,1] op_sel_hi:[1,0]
	s_nop 0
	v_pk_fma_f32 v[32:33], v[16:17], v[20:21], v[30:31] neg_lo:[0,0,1] neg_hi:[0,0,1]
	v_pk_fma_f32 v[20:21], v[16:17], v[20:21], v[30:31] op_sel_hi:[0,1,1]
	v_mov_b32_e32 v33, v21
	v_pk_mul_f32 v[20:21], v[146:147], v[32:33] op_sel_hi:[0,1]
	v_mul_f32_e32 v30, v19, v23
	v_mul_f32_e32 v32, v18, v23
	v_pk_fma_f32 v[30:31], v[18:19], v[22:23], v[30:31] op_sel_hi:[1,1,0] neg_lo:[0,0,1] neg_hi:[0,0,1]
	v_pk_fma_f32 v[22:23], v[18:19], v[22:23], v[32:33] op_sel:[0,1,0] op_sel_hi:[1,0,0]
	s_nop 0
	v_mov_b32_e32 v31, v23
	v_pk_mul_f32 v[22:23], v[146:147], v[30:31] op_sel_hi:[0,1]
	v_pk_mul_f32 v[30:31], v[12:13], v[24:25] op_sel:[1,1] op_sel_hi:[1,0]
	s_nop 0
	v_pk_fma_f32 v[32:33], v[12:13], v[24:25], v[30:31] neg_lo:[0,0,1] neg_hi:[0,0,1]
	v_pk_fma_f32 v[24:25], v[12:13], v[24:25], v[30:31] op_sel_hi:[0,1,1]
	v_mov_b32_e32 v33, v25
	v_pk_mul_f32 v[24:25], v[146:147], v[32:33] op_sel_hi:[0,1]
	v_mul_f32_e32 v30, v15, v27
	v_mul_f32_e32 v32, v14, v27
	v_pk_fma_f32 v[30:31], v[14:15], v[26:27], v[30:31] op_sel_hi:[1,1,0] neg_lo:[0,0,1] neg_hi:[0,0,1]
	v_pk_fma_f32 v[26:27], v[14:15], v[26:27], v[32:33] op_sel:[0,1,0] op_sel_hi:[1,0,0]
	s_nop 0
	v_mov_b32_e32 v31, v27
	v_pk_mul_f32 v[26:27], v[146:147], v[30:31] op_sel_hi:[0,1]

.LBB0_836:
	v_mov_b64_e32 v[12:13], s[12:13]
	v_mad_i64_i32 v[12:13], s[0:1], v29, s2, v[12:13]
	v_lshl_add_u64 v[12:13], v[124:125], 1, v[12:13]
	v_cvt_pk_bf16_f32 v14, v20, v21
	v_cvt_pk_bf16_f32 v15, v22, v23
	v_cvt_pk_bf16_f32 v16, v24, v25
	v_cvt_pk_bf16_f32 v17, v26, v27
	s_cmp_lt_i32 s19, 2
	s_mov_b64 s[28:29], -1
	global_store_dwordx4 v[12:13], v[14:17], off sc1
	s_cbranch_scc1 .LBB0_842
	s_cmp_gt_i32 s19, 2
	s_cbranch_scc0 .LBB0_839
	v_lshlrev_b32_e32 v180, 3, v28
	v_lshl_add_u64 v[14:15], s[14:15], 0, v[180:181]
	v_lshlrev_b32_e32 v180, 3, v159
	v_lshl_add_u64 v[14:15], v[14:15], 0, v[180:181]
	global_load_dwordx4 v[20:23], v[14:15], off offset:16
	s_nop 0
	global_load_dwordx4 v[14:17], v[14:15], off
	s_mov_b64 s[28:29], 0
	s_waitcnt vmcnt(0)
	v_pk_mul_f32 v[18:19], v[8:9], v[14:15] op_sel:[1,1] op_sel_hi:[1,0]
	s_nop 0
	v_pk_fma_f32 v[24:25], v[8:9], v[14:15], v[18:19] neg_lo:[0,0,1] neg_hi:[0,0,1]
	v_pk_fma_f32 v[14:15], v[8:9], v[14:15], v[18:19] op_sel_hi:[0,1,1]
	v_mov_b32_e32 v25, v15
	v_pk_mul_f32 v[14:15], v[146:147], v[24:25] op_sel_hi:[0,1]
	v_mul_f32_e32 v18, v11, v17
	v_mul_f32_e32 v24, v10, v17
	v_pk_fma_f32 v[18:19], v[10:11], v[16:17], v[18:19] op_sel_hi:[1,1,0] neg_lo:[0,0,1] neg_hi:[0,0,1]
	v_pk_fma_f32 v[16:17], v[10:11], v[16:17], v[24:25] op_sel:[0,1,0] op_sel_hi:[1,0,0]
	s_nop 0
	v_mov_b32_e32 v19, v17
	v_pk_mul_f32 v[16:17], v[4:5], v[20:21] op_sel:[1,1] op_sel_hi:[1,0]
	v_pk_mul_f32 v[18:19], v[146:147], v[18:19] op_sel_hi:[0,1]
	v_pk_fma_f32 v[24:25], v[4:5], v[20:21], v[16:17] neg_lo:[0,0,1] neg_hi:[0,0,1]
	v_pk_fma_f32 v[16:17], v[4:5], v[20:21], v[16:17] op_sel_hi:[0,1,1]
	v_mov_b32_e32 v25, v17
	v_pk_mul_f32 v[16:17], v[146:147], v[24:25] op_sel_hi:[0,1]
	v_mul_f32_e32 v20, v7, v23
	v_mul_f32_e32 v24, v6, v23
	v_pk_fma_f32 v[20:21], v[6:7], v[22:23], v[20:21] op_sel_hi:[1,1,0] neg_lo:[0,0,1] neg_hi:[0,0,1]
	v_pk_fma_f32 v[22:23], v[6:7], v[22:23], v[24:25] op_sel:[0,1,0] op_sel_hi:[1,0,0]
	s_nop 0
	v_mov_b32_e32 v21, v23
	v_pk_mul_f32 v[20:21], v[146:147], v[20:21] op_sel_hi:[0,1]

.LBB0_846:
	v_cvt_pk_bf16_f32 v4, v14, v15
	v_cvt_pk_bf16_f32 v5, v18, v19
	v_cvt_pk_bf16_f32 v6, v16, v17
	v_cvt_pk_bf16_f32 v7, v20, v21
	global_store_dwordx4 v[12:13], v[4:7], off offset:256 sc1
	s_andn2_b64 vcc, exec, s[6:7]
	s_mov_b64 s[4:5], -1
	s_cbranch_vccnz .LBB0_667
	s_andn2_b64 vcc, exec, s[10:11]
	s_cbranch_vccnz .LBB0_666
	s_barrier
	s_branch .LBB0_666

.LBB0_857:
	s_or_b64 exec, exec, s[6:7]
	v_lshlrev_b64 v[8:9], 6, v[12:13]
	v_add_u32_e32 v18, s2, v18
	s_movk_i32 s4, 0x87f
	v_lshl_add_u64 v[8:9], s[12:13], 0, v[8:9]
	v_lshlrev_b32_e32 v180, 2, v19
	v_cmp_lt_i32_e32 vcc, s4, v18
	v_lshl_add_u64 v[8:9], v[8:9], 0, v[180:181]
	s_or_b64 s[14:15], vcc, s[14:15]
	global_store_dwordx4 v[8:9], v[4:7], off sc1
	s_andn2_b64 exec, exec, s[14:15]
	s_cbranch_execz .LBB0_883

.LBB0_915:
	s_or_b64 exec, exec, s[20:21]
	v_lshlrev_b32_e32 v55, 16, v45
	v_lshlrev_b32_e32 v54, 16, v44
	v_and_b32_e32 v45, 0xffff0000, v45
	v_and_b32_e32 v44, 0xffff0000, v44
	v_lshlrev_b32_e32 v64, 16, v30
	v_and_b32_e32 v57, 0xffff0000, v30
	v_lshlrev_b32_e32 v66, 16, v31
	v_and_b32_e32 v67, 0xffff0000, v31
	v_pk_mul_f32 v[30:31], v[44:45], v[44:45]
	v_lshlrev_b32_e32 v59, 16, v43
	v_lshlrev_b32_e32 v58, 16, v42
	v_and_b32_e32 v43, 0xffff0000, v43
	v_and_b32_e32 v42, 0xffff0000, v42
	v_pk_fma_f32 v[30:31], v[54:55], v[54:55], v[30:31]
	v_lshlrev_b32_e32 v60, 16, v32
	v_and_b32_e32 v61, 0xffff0000, v32
	v_lshlrev_b32_e32 v62, 16, v33
	v_and_b32_e32 v63, 0xffff0000, v33
	v_pk_add_f32 v[30:31], v[30:31], v[30:31] op_sel_hi:[0,1]
	v_pk_mul_f32 v[32:33], v[42:43], v[42:43]
	v_mul_f32_e32 v65, v60, v60
	v_pk_fma_f32 v[32:33], v[58:59], v[58:59], v[32:33]
	v_mul_f32_e32 v69, v61, v61
	v_mul_f32_e32 v30, v62, v62
	v_mov_b32_e32 v68, v64
	v_pk_add_f32 v[32:33], v[32:33], v[32:33] op_sel_hi:[0,1]
	v_pk_fma_f32 v[70:71], v[62:63], v[62:63], v[30:31] op_sel_hi:[1,1,0]
	v_pk_add_f32 v[68:69], v[64:65], v[68:69]
	v_mul_f32_e32 v70, v57, v57
	v_mul_f32_e32 v30, v66, v66
	v_mul_f32_e32 v32, v67, v67
	v_mul_f32_e32 v72, v64, v64
	v_mov_b32_e32 v73, v69
	v_pk_add_f32 v[68:69], v[72:73], v[70:71]
	v_pk_add_f32 v[30:31], v[30:31], v[32:33]
	v_mov_b32_e32 v65, v57
	v_pk_add_f32 v[30:31], v[68:69], v[30:31]
	s_nop 0
	v_add_f32_e32 v29, v30, v31
	v_mov_b32_e32 v30, v181
	v_mov_b32_e32 v31, v44
	v_add_f32_dpp v29, v29, v29 row_shr:1 row_mask:0xf bank_mask:0xf bound_ctrl:1
	v_mov_b32_e32 v44, v55
	s_nop 0
	v_add_f32_dpp v29, v29, v29 row_shr:2 row_mask:0xf bank_mask:0xf bound_ctrl:1
	s_nop 1
	v_add_f32_dpp v29, v29, v29 row_shr:4 row_mask:0xf bank_mask:0xf bound_ctrl:1
	s_nop 1
	v_add_f32_dpp v29, v29, v29 row_shr:8 row_mask:0xf bank_mask:0xf bound_ctrl:1
	s_nop 1
	v_mov_b32_dpp v30, v29 row_bcast:15 row_mask:0xa bank_mask:0xf
	v_add_f32_e32 v29, v29, v30
	v_mov_b32_e32 v30, v181
	s_nop 1
	v_mov_b32_dpp v30, v29 row_bcast:31 row_mask:0xc bank_mask:0xf
	v_add_f32_e32 v29, v29, v30
	v_mov_b32_e32 v30, v54
	v_readlane_b32 s0, v29, 63
	s_nop 1
	v_fma_f32 v29, s0, v247, v237
	v_rsq_f32_e32 v68, v29
	v_ashrrev_i32_e32 v29, 31, v28
	v_lshlrev_b64 v[70:71], 12, v[28:29]
	v_pk_mul_f32 v[30:31], v[68:69], v[30:31] op_sel_hi:[0,1]
	v_pk_mul_f32 v[32:33], v[68:69], v[44:45] op_sel_hi:[0,1]
	v_pk_mul_f32 v[32:33], v[6:7], v[32:33]
	v_pk_mul_f32 v[30:31], v[4:5], v[30:31]
	v_lshl_add_u64 v[44:45], v[22:23], 0, v[70:71]
	global_store_dwordx4 v[44:45], v[30:33], off sc1
	s_nop 1
	v_mov_b32_e32 v30, v58
	v_mov_b32_e32 v31, v42
	v_mov_b32_e32 v42, v59
	v_pk_mul_f32 v[30:31], v[68:69], v[30:31] op_sel_hi:[0,1]
	v_pk_mul_f32 v[32:33], v[68:69], v[42:43] op_sel_hi:[0,1]
	v_pk_mul_f32 v[32:33], v[10:11], v[32:33]
	v_pk_mul_f32 v[30:31], v[8:9], v[30:31]
	global_store_dwordx4 v[44:45], v[30:33], off offset:1024 sc1
	s_waitcnt vmcnt(4)
	v_mov_b32_e32 v43, v49
	v_mov_b32_e32 v42, v48
	v_pk_mul_f32 v[30:31], v[68:69], v[60:61] op_sel_hi:[0,1]
	v_pk_mul_f32 v[32:33], v[68:69], v[62:63] op_sel_hi:[0,1]
	v_pk_mul_f32 v[32:33], v[14:15], v[32:33]
	v_pk_mul_f32 v[30:31], v[12:13], v[30:31]
	global_store_dwordx4 v[44:45], v[30:33], off offset:2048 sc1
	s_nop 1
	v_pk_mul_f32 v[30:31], v[68:69], v[64:65] op_sel_hi:[0,1]
	v_pk_mul_f32 v[32:33], v[68:69], v[66:67] op_sel_hi:[0,1]
	v_pk_mul_f32 v[32:33], v[18:19], v[32:33]
	v_pk_mul_f32 v[30:31], v[16:17], v[30:31]
	global_store_dwordx4 v[44:45], v[30:33], off offset:3072 sc1
	v_mov_b32_e32 v45, v47
	v_mov_b32_e32 v44, v46
	s_waitcnt vmcnt(4)
	v_mov_b32_e32 v31, v53
	v_mov_b32_e32 v30, v52
	v_mov_b32_e32 v33, v51
	v_mov_b32_e32 v32, v50

.LBB0_919:
	s_or_b64 exec, exec, s[4:5]
	v_lshlrev_b32_e32 v59, 16, v55
	v_lshlrev_b32_e32 v58, 16, v54
	v_and_b32_e32 v55, 0xffff0000, v55
	v_and_b32_e32 v54, 0xffff0000, v54
	v_lshlrev_b32_e32 v66, 16, v48
	v_and_b32_e32 v29, 0xffff0000, v48
	v_lshlrev_b32_e32 v68, 16, v49
	v_and_b32_e32 v69, 0xffff0000, v49
	v_pk_mul_f32 v[48:49], v[54:55], v[54:55]
	v_lshlrev_b32_e32 v61, 16, v53
	v_lshlrev_b32_e32 v60, 16, v52
	v_and_b32_e32 v53, 0xffff0000, v53
	v_and_b32_e32 v52, 0xffff0000, v52
	v_pk_fma_f32 v[48:49], v[58:59], v[58:59], v[48:49]
	v_lshlrev_b32_e32 v62, 16, v50
	v_and_b32_e32 v63, 0xffff0000, v50
	v_lshlrev_b32_e32 v64, 16, v51
	v_and_b32_e32 v65, 0xffff0000, v51
	v_pk_add_f32 v[48:49], v[48:49], v[48:49] op_sel_hi:[0,1]
	v_pk_mul_f32 v[50:51], v[52:53], v[52:53]
	v_mul_f32_e32 v67, v62, v62
	v_pk_fma_f32 v[50:51], v[60:61], v[60:61], v[50:51]
	v_mul_f32_e32 v71, v63, v63
	v_mul_f32_e32 v48, v64, v64
	v_mov_b32_e32 v70, v66
	v_pk_add_f32 v[50:51], v[50:51], v[50:51] op_sel_hi:[0,1]
	v_pk_fma_f32 v[72:73], v[64:65], v[64:65], v[48:49] op_sel_hi:[1,1,0]
	v_pk_add_f32 v[70:71], v[66:67], v[70:71]
	v_mul_f32_e32 v72, v29, v29
	v_mul_f32_e32 v48, v68, v68
	v_mul_f32_e32 v50, v69, v69
	v_mul_f32_e32 v74, v66, v66
	v_mov_b32_e32 v75, v71
	v_pk_add_f32 v[70:71], v[74:75], v[72:73]
	v_pk_add_f32 v[48:49], v[48:49], v[50:51]
	v_mov_b32_e32 v67, v29
	v_pk_add_f32 v[48:49], v[70:71], v[48:49]
	v_cmp_gt_i32_e64 s[6:7], s70, v28
	v_add_f32_e32 v47, v48, v49
	v_mov_b32_e32 v48, v181
	v_mov_b32_e32 v49, v54
	v_add_f32_dpp v47, v47, v47 row_shr:1 row_mask:0xf bank_mask:0xf bound_ctrl:1
	v_mov_b32_e32 v54, v59
	s_nop 0
	v_add_f32_dpp v47, v47, v47 row_shr:2 row_mask:0xf bank_mask:0xf bound_ctrl:1
	s_nop 1
	v_add_f32_dpp v47, v47, v47 row_shr:4 row_mask:0xf bank_mask:0xf bound_ctrl:1
	s_nop 1
	v_add_f32_dpp v47, v47, v47 row_shr:8 row_mask:0xf bank_mask:0xf bound_ctrl:1
	s_nop 1
	v_mov_b32_dpp v48, v47 row_bcast:15 row_mask:0xa bank_mask:0xf
	v_add_f32_e32 v47, v47, v48
	v_mov_b32_e32 v48, v181
	s_nop 1
	v_mov_b32_dpp v48, v47 row_bcast:31 row_mask:0xc bank_mask:0xf
	v_add_f32_e32 v47, v47, v48
	v_mov_b32_e32 v48, v58
	v_readlane_b32 s0, v47, 63
	s_nop 1
	v_fma_f32 v47, s0, v247, v237
	v_rsq_f32_e32 v70, v47
	s_nop 0
	v_pk_mul_f32 v[48:49], v[70:71], v[48:49] op_sel_hi:[0,1]
	v_pk_mul_f32 v[50:51], v[70:71], v[54:55] op_sel_hi:[0,1]
	v_pk_mul_f32 v[50:51], v[6:7], v[50:51]
	v_pk_mul_f32 v[48:49], v[4:5], v[48:49]
	v_lshl_add_u64 v[54:55], s[10:11], 0, v[26:27]
	global_store_dwordx4 v[54:55], v[48:51], off sc1
	s_nop 1
	v_mov_b32_e32 v48, v60
	v_mov_b32_e32 v49, v52
	v_mov_b32_e32 v52, v61
	v_pk_mul_f32 v[48:49], v[70:71], v[48:49] op_sel_hi:[0,1]
	v_pk_mul_f32 v[50:51], v[70:71], v[52:53] op_sel_hi:[0,1]
	v_pk_mul_f32 v[50:51], v[10:11], v[50:51]
	v_pk_mul_f32 v[48:49], v[8:9], v[48:49]
	global_store_dwordx4 v[54:55], v[48:51], off offset:1024 sc1
	s_nop 1
	v_pk_mul_f32 v[48:49], v[70:71], v[62:63] op_sel_hi:[0,1]
	v_pk_mul_f32 v[50:51], v[70:71], v[64:65] op_sel_hi:[0,1]
	v_pk_mul_f32 v[50:51], v[14:15], v[50:51]
	v_pk_mul_f32 v[48:49], v[12:13], v[48:49]
	global_store_dwordx4 v[54:55], v[48:51], off offset:2048 sc1
	s_nop 1
	v_pk_mul_f32 v[48:49], v[70:71], v[66:67] op_sel_hi:[0,1]
	v_pk_mul_f32 v[50:51], v[70:71], v[68:69] op_sel_hi:[0,1]
	v_pk_mul_f32 v[50:51], v[18:19], v[50:51]
	v_pk_mul_f32 v[48:49], v[16:17], v[48:49]
	global_store_dwordx4 v[54:55], v[48:51], off offset:3072 sc1
	s_and_saveexec_b64 s[18:19], s[6:7]
	s_cbranch_execz .LBB0_916
	s_mul_i32 s0, s75, 24
	v_add_u32_e32 v54, s0, v46
	v_cmp_gt_i32_e64 s[6:7], s70, v54
	v_mov_b32_e32 v46, v44
	v_mov_b32_e32 v47, v45
	v_mov_b32_e32 v48, v42
	v_mov_b32_e32 v49, v43
	v_mov_b32_e32 v50, v32
	v_mov_b32_e32 v51, v33
	v_mov_b32_e32 v52, v30
	v_mov_b32_e32 v53, v31
	s_and_saveexec_b64 s[20:21], s[6:7]
	s_cbranch_execz .LBB0_915
	v_ashrrev_i32_e32 v55, 31, v54
	v_lshlrev_b64 v[46:47], 12, v[54:55]
	v_lshl_add_u64 v[52:53], v[20:21], 0, v[46:47]
	global_load_dwordx2 v[46:47], v[52:53], off
	global_load_dwordx2 v[48:49], v[52:53], off offset:512
	global_load_dwordx2 v[50:51], v[52:53], off offset:1024
	s_nop 0
	global_load_dwordx2 v[52:53], v[52:53], off offset:1536
	s_branch .LBB0_915

.LBB0_927:
	v_mul_hi_i32 v6, v5, s77
	v_lshrrev_b32_e32 v7, 31, v6
	v_ashrrev_i32_e32 v6, 5, v6
	v_add_u32_e32 v14, v6, v7
	v_mov_b64_e32 v[6:7], s[78:79]
	v_mad_i64_i32 v[6:7], s[4:5], v14, s65, v[6:7]
	s_load_dwordx2 s[4:5], s[80:81], 0x40
	v_mul_i32_i24_e32 v11, 0xc90, v14
	v_sub_u32_e32 v10, v5, v11
	v_cmp_lt_i32_e32 vcc, s87, v10
	v_lshlrev_b32_e32 v180, 2, v12
	s_waitcnt lgkmcnt(0)
	v_mov_b64_e32 v[8:9], s[4:5]
	v_mad_i64_i32 v[14:15], s[4:5], v14, s54, v[8:9]
	v_add_u32_e32 v9, 0x410, v32
	v_add_u32_e32 v34, 0x418, v32
	v_add_u32_e32 v35, 0x820, v32
	v_add_u32_e32 v36, 0x828, v32
	v_add_u32_e32 v37, 0xc30, v32
	v_add_u32_e32 v38, 0xc38, v32
	v_add_u32_e32 v39, 0x1040, v32
	v_add_u32_e32 v40, 0x1048, v32
	v_add_u32_e32 v41, 0x1450, v32
	v_add_u32_e32 v42, 0x1458, v32
	v_add_u32_e32 v43, 0x1860, v32
	v_add_u32_e32 v44, 0x1868, v32
	v_add_u32_e32 v45, 0x1c70, v32
	v_add_u32_e32 v46, 0x1c78, v32
	v_add_u32_e32 v47, 0x2080, v32
	v_add_u32_e32 v48, 0x2088, v32
	v_add_u32_e32 v49, 0x2490, v32
	v_add_u32_e32 v50, 0x2498, v32
	v_add_u32_e32 v51, 0x28a0, v32
	v_add_u32_e32 v52, 0x28a8, v32
	v_add_u32_e32 v53, 0x2cb0, v32
	v_add_u32_e32 v54, 0x2cb8, v32
	v_add_u32_e32 v55, 0x30c0, v32
	v_add_u32_e32 v56, 0x30c8, v32
	v_add_u32_e32 v57, 0x34d0, v32
	v_add_u32_e32 v58, 0x34d8, v32
	v_add_u32_e32 v59, 0x38e0, v32
	v_add_u32_e32 v60, 0x38e8, v32
	v_add_u32_e32 v61, 0x3cf0, v32
	v_add_u32_e32 v62, 0x3cf8, v32
	v_lshlrev_b32_e32 v8, 1, v4
	v_add_u32_e32 v33, 0x400, v18
	s_and_saveexec_b64 s[4:5], vcc
	s_xor_b64 s[10:11], exec, s[4:5]
	s_cbranch_execz .LBB0_929
	v_lshlrev_b32_e32 v10, 4, v11
	v_sub_u32_e32 v10, v31, v10
	v_and_b32_e32 v63, 0xfc0, v10
	v_lshlrev_b32_e32 v10, 6, v11
	v_sub_u32_e32 v10, v30, v10
	v_and_b32_e32 v128, 0xc0, v10
	v_or_b32_e32 v10, v63, v16
	v_mul_u32_u24_e32 v10, 0xe10, v10
	v_lshlrev_b32_e32 v10, 2, v10
	v_mov_b32_e32 v11, v181
	v_lshl_add_u64 v[10:11], v[14:15], 0, v[10:11]
	v_lshlrev_b32_e32 v14, 2, v128
	v_mov_b32_e32 v15, v181
	v_lshl_add_u64 v[10:11], v[10:11], 0, v[14:15]
	v_lshl_add_u64 v[10:11], v[10:11], 0, v[180:181]
	v_add_co_u32_e32 v14, vcc, s84, v10
	s_mov_b32 s4, 0x11000
	s_nop 0
	v_addc_co_u32_e32 v15, vcc, 0, v11, vcc
	v_add_co_u32_e32 v68, vcc, s4, v10
	s_mov_b32 s4, 0x1f000
	s_nop 0
	v_addc_co_u32_e32 v69, vcc, 0, v11, vcc
	global_load_dwordx4 v[64:67], v[14:15], off offset:1088
	s_nop 0
	global_load_dwordx4 v[68:71], v[68:69], off offset:1344
	v_add_co_u32_e32 v14, vcc, s4, v10
	s_mov_b32 s4, 0x2d000
	s_nop 0
	v_addc_co_u32_e32 v15, vcc, 0, v11, vcc
	v_add_co_u32_e32 v76, vcc, s4, v10
	s_mov_b32 s4, 0x3b000
	s_nop 0
	v_addc_co_u32_e32 v77, vcc, 0, v11, vcc
	global_load_dwordx4 v[72:75], v[14:15], off offset:1600
	s_nop 0
	global_load_dwordx4 v[76:79], v[76:77], off offset:1856
	v_add_co_u32_e32 v14, vcc, s4, v10
	s_mov_b32 s4, 0x49000
	s_nop 0
	v_addc_co_u32_e32 v15, vcc, 0, v11, vcc
	v_add_co_u32_e32 v84, vcc, s4, v10
	s_mov_b32 s4, 0x57000
	s_nop 0
	v_addc_co_u32_e32 v85, vcc, 0, v11, vcc
	global_load_dwordx4 v[80:83], v[14:15], off offset:2112
	s_nop 0
	global_load_dwordx4 v[84:87], v[84:85], off offset:2368
	v_add_co_u32_e32 v14, vcc, s4, v10
	s_mov_b32 s4, 0x65000
	s_nop 0
	v_addc_co_u32_e32 v15, vcc, 0, v11, vcc
	v_add_co_u32_e32 v92, vcc, s4, v10
	s_mov_b32 s4, 0x73000
	s_nop 0
	v_addc_co_u32_e32 v93, vcc, 0, v11, vcc
	global_load_dwordx4 v[88:91], v[14:15], off offset:2624
	s_nop 0
	global_load_dwordx4 v[92:95], v[92:93], off offset:2880
	v_add_co_u32_e32 v14, vcc, s4, v10
	s_mov_b32 s4, 0x81000
	s_nop 0
	v_addc_co_u32_e32 v15, vcc, 0, v11, vcc
	v_add_co_u32_e32 v100, vcc, s4, v10
	s_mov_b32 s4, 0x8f000
	s_nop 0
	v_addc_co_u32_e32 v101, vcc, 0, v11, vcc
	global_load_dwordx4 v[96:99], v[14:15], off offset:3136
	s_nop 0
	global_load_dwordx4 v[100:103], v[100:101], off offset:3392
	v_add_co_u32_e32 v14, vcc, s4, v10
	s_mov_b32 s4, 0x9d000
	s_nop 0
	v_addc_co_u32_e32 v15, vcc, 0, v11, vcc
	v_add_co_u32_e32 v108, vcc, s4, v10
	s_mov_b32 s4, 0xac000
	s_nop 0
	v_addc_co_u32_e32 v109, vcc, 0, v11, vcc
	global_load_dwordx4 v[104:107], v[14:15], off offset:3648
	s_nop 0
	global_load_dwordx4 v[108:111], v[108:109], off offset:3904
	v_add_co_u32_e32 v14, vcc, s4, v10
	s_mov_b32 s4, 0xba000
	s_nop 0
	v_addc_co_u32_e32 v15, vcc, 0, v11, vcc
	v_add_co_u32_e32 v116, vcc, s4, v10
	s_mov_b32 s4, 0xc8000
	s_nop 0
	v_addc_co_u32_e32 v117, vcc, 0, v11, vcc
	global_load_dwordx4 v[112:115], v[14:15], off offset:64
	s_nop 0
	global_load_dwordx4 v[116:119], v[116:117], off offset:320
	v_add_co_u32_e32 v14, vcc, s4, v10
	s_mov_b32 s4, 0xd6000
	s_nop 0
	v_addc_co_u32_e32 v15, vcc, 0, v11, vcc
	global_load_dwordx4 v[120:123], v[14:15], off offset:576
	v_add_co_u32_e32 v10, vcc, s4, v10
	v_lshlrev_b32_e32 v180, 1, v63
	s_nop 0
	v_addc_co_u32_e32 v11, vcc, 0, v11, vcc
	global_load_dwordx4 v[124:127], v[10:11], off offset:832
	v_lshl_add_u64 v[6:7], v[6:7], 0, v[180:181]
	s_mov_b64 s[4:5], 0x680000
	s_waitcnt vmcnt(15)
	ds_write2_b32 v32, v64, v65 offset1:1
	ds_write2_b32 v32, v66, v67 offset0:2 offset1:3
	s_waitcnt vmcnt(14)
	ds_write2_b32 v9, v68, v69 offset1:1
	ds_write2_b32 v34, v70, v71 offset1:1
	s_waitcnt vmcnt(13)
	ds_write2_b32 v35, v72, v73 offset1:1
	ds_write2_b32 v36, v74, v75 offset1:1
	s_waitcnt vmcnt(12)
	ds_write2_b32 v37, v76, v77 offset1:1
	ds_write2_b32 v38, v78, v79 offset1:1
	s_waitcnt vmcnt(11)
	ds_write2_b32 v39, v80, v81 offset1:1
	ds_write2_b32 v40, v82, v83 offset1:1
	s_waitcnt vmcnt(10)
	ds_write2_b32 v41, v84, v85 offset1:1
	ds_write2_b32 v42, v86, v87 offset1:1
	s_waitcnt vmcnt(9)
	ds_write2_b32 v43, v88, v89 offset1:1
	ds_write2_b32 v44, v90, v91 offset1:1
	s_waitcnt vmcnt(8)
	ds_write2_b32 v45, v92, v93 offset1:1
	ds_write2_b32 v46, v94, v95 offset1:1
	s_waitcnt vmcnt(7)
	ds_write2_b32 v47, v96, v97 offset1:1
	ds_write2_b32 v48, v98, v99 offset1:1
	s_waitcnt vmcnt(6)
	ds_write2_b32 v49, v100, v101 offset1:1
	ds_write2_b32 v50, v102, v103 offset1:1
	s_waitcnt vmcnt(5)
	ds_write2_b32 v51, v104, v105 offset1:1
	ds_write2_b32 v52, v106, v107 offset1:1
	s_waitcnt vmcnt(4)
	ds_write2_b32 v53, v108, v109 offset1:1
	ds_write2_b32 v54, v110, v111 offset1:1
	s_waitcnt vmcnt(3)
	ds_write2_b32 v55, v112, v113 offset1:1
	ds_write2_b32 v56, v114, v115 offset1:1
	s_waitcnt vmcnt(2)
	ds_write2_b32 v57, v116, v117 offset1:1
	ds_write2_b32 v58, v118, v119 offset1:1
	s_waitcnt vmcnt(1)
	ds_write2_b32 v59, v120, v121 offset1:1
	ds_write2_b32 v60, v122, v123 offset1:1
	s_waitcnt vmcnt(0)
	ds_write2_b32 v61, v124, v125 offset1:1
	ds_write2_b32 v62, v126, v127 offset1:1
	s_waitcnt lgkmcnt(0)
	ds_read2_b32 v[10:11], v18 offset0:65 offset1:73
	ds_read2_b32 v[14:15], v18 offset1:8
	ds_read2_b32 v[34:35], v18 offset0:130 offset1:138
	ds_read2_b32 v[36:37], v18 offset0:195 offset1:203
	ds_read2_b32 v[38:39], v33 offset0:4 offset1:12
	ds_read2_b32 v[40:41], v33 offset0:69 offset1:77
	ds_read2_b32 v[42:43], v33 offset0:134 offset1:142
	ds_read2_b32 v[44:45], v33 offset0:199 offset1:207
	v_mov_b32_e32 v9, v181
	v_lshl_add_u64 v[6:7], v[6:7], 0, v[8:9]
	v_lshl_add_u64 v[46:47], v[6:7], 0, s[4:5]
	s_waitcnt lgkmcnt(6)
	v_cvt_pk_bf16_f32 v6, v14, v10
	v_or_b32_e32 v10, v128, v17
	v_lshlrev_b32_e32 v180, 11, v10
	s_waitcnt lgkmcnt(4)
	v_cvt_pk_bf16_f32 v7, v34, v36
	s_waitcnt lgkmcnt(2)
	v_cvt_pk_bf16_f32 v8, v38, v40
	s_waitcnt lgkmcnt(0)
	v_cvt_pk_bf16_f32 v9, v42, v44
	v_lshl_add_u64 v[48:49], v[46:47], 0, v[180:181]
	global_store_dwordx4 v[48:49], v[6:9], off sc1
	v_or_b32_e32 v10, v128, v19
	v_lshlrev_b32_e32 v180, 11, v10
	v_cvt_pk_bf16_f32 v6, v15, v11
	v_cvt_pk_bf16_f32 v7, v35, v37
	v_cvt_pk_bf16_f32 v8, v39, v41
	v_cvt_pk_bf16_f32 v9, v43, v45
	ds_read2_b32 v[14:15], v18 offset0:81 offset1:89
	ds_read2_b32 v[34:35], v18 offset0:16 offset1:24
	ds_read2_b32 v[36:37], v18 offset0:146 offset1:154
	ds_read2_b32 v[38:39], v18 offset0:211 offset1:219
	ds_read2_b32 v[40:41], v33 offset0:20 offset1:28
	ds_read2_b32 v[42:43], v33 offset0:85 offset1:93
	ds_read2_b32 v[44:45], v33 offset0:150 offset1:158
	ds_read2_b32 v[48:49], v33 offset0:215 offset1:223
	v_lshl_add_u64 v[10:11], v[46:47], 0, v[180:181]
	global_store_dwordx4 v[10:11], v[6:9], off sc1
	v_or_b32_e32 v10, v128, v20
	v_lshlrev_b32_e32 v180, 11, v10
	s_waitcnt lgkmcnt(6)
	v_cvt_pk_bf16_f32 v6, v34, v14
	s_waitcnt lgkmcnt(4)
	v_cvt_pk_bf16_f32 v7, v36, v38
	s_waitcnt lgkmcnt(2)
	v_cvt_pk_bf16_f32 v8, v40, v42
	s_waitcnt lgkmcnt(0)
	v_cvt_pk_bf16_f32 v9, v44, v48
	v_lshl_add_u64 v[10:11], v[46:47], 0, v[180:181]
	global_store_dwordx4 v[10:11], v[6:9], off sc1
	v_or_b32_e32 v10, v128, v21
	v_lshlrev_b32_e32 v180, 11, v10
	v_cvt_pk_bf16_f32 v6, v35, v15
	v_cvt_pk_bf16_f32 v7, v37, v39
	v_cvt_pk_bf16_f32 v8, v41, v43
	v_cvt_pk_bf16_f32 v9, v45, v49
	ds_read2_b32 v[14:15], v18 offset0:32 offset1:40
	ds_read2_b32 v[34:35], v18 offset0:97 offset1:105
	ds_read2_b32 v[36:37], v18 offset0:162 offset1:170
	ds_read2_b32 v[38:39], v18 offset0:227 offset1:235
	ds_read2_b32 v[40:41], v33 offset0:36 offset1:44
	ds_read2_b32 v[42:43], v33 offset0:101 offset1:109
	ds_read2_b32 v[44:45], v33 offset0:166 offset1:174
	ds_read2_b32 v[48:49], v33 offset0:231 offset1:239
	v_lshl_add_u64 v[10:11], v[46:47], 0, v[180:181]
	global_store_dwordx4 v[10:11], v[6:9], off sc1
	v_or_b32_e32 v10, v128, v22
	v_lshlrev_b32_e32 v180, 11, v10
	s_waitcnt lgkmcnt(6)
	v_cvt_pk_bf16_f32 v6, v14, v34
	s_waitcnt lgkmcnt(4)
	v_cvt_pk_bf16_f32 v7, v36, v38
	s_waitcnt lgkmcnt(2)
	v_cvt_pk_bf16_f32 v8, v40, v42
	s_waitcnt lgkmcnt(0)
	v_cvt_pk_bf16_f32 v9, v44, v48
	v_lshl_add_u64 v[10:11], v[46:47], 0, v[180:181]
	global_store_dwordx4 v[10:11], v[6:9], off sc1
	v_or_b32_e32 v10, v128, v23
	v_lshlrev_b32_e32 v180, 11, v10
	v_cvt_pk_bf16_f32 v6, v15, v35
	v_cvt_pk_bf16_f32 v7, v37, v39
	v_cvt_pk_bf16_f32 v8, v41, v43
	v_cvt_pk_bf16_f32 v9, v45, v49
	ds_read2_b32 v[14:15], v18 offset0:48 offset1:56
	ds_read2_b32 v[34:35], v18 offset0:113 offset1:121
	ds_read2_b32 v[36:37], v18 offset0:178 offset1:186
	ds_read2_b32 v[38:39], v18 offset0:243 offset1:251
	ds_read2_b32 v[40:41], v33 offset0:52 offset1:60
	ds_read2_b32 v[42:43], v33 offset0:117 offset1:125
	ds_read2_b32 v[44:45], v33 offset0:182 offset1:190
	ds_read2_b32 v[48:49], v33 offset0:247 offset1:255
	v_lshl_add_u64 v[10:11], v[46:47], 0, v[180:181]
	global_store_dwordx4 v[10:11], v[6:9], off sc1
	v_or_b32_e32 v10, v128, v24
	v_lshlrev_b32_e32 v180, 11, v10
	s_waitcnt lgkmcnt(6)
	v_cvt_pk_bf16_f32 v6, v14, v34
	s_waitcnt lgkmcnt(4)
	v_cvt_pk_bf16_f32 v7, v36, v38
	s_waitcnt lgkmcnt(2)
	v_cvt_pk_bf16_f32 v8, v40, v42
	s_waitcnt lgkmcnt(0)
	v_cvt_pk_bf16_f32 v9, v44, v48
	v_lshl_add_u64 v[10:11], v[46:47], 0, v[180:181]
	global_store_dwordx4 v[10:11], v[6:9], off sc1
	v_or_b32_e32 v10, v128, v25
	v_lshlrev_b32_e32 v180, 11, v10
	v_cvt_pk_bf16_f32 v6, v15, v35
	v_cvt_pk_bf16_f32 v7, v37, v39
	v_cvt_pk_bf16_f32 v8, v41, v43
	v_cvt_pk_bf16_f32 v9, v45, v49
	v_lshl_add_u64 v[10:11], v[46:47], 0, v[180:181]
	global_store_dwordx4 v[10:11], v[6:9], off sc1
	s_waitcnt lgkmcnt(0)
.LBB0_929:
	s_andn2_saveexec_b64 s[10:11], s[10:11]
	s_cbranch_execz .LBB0_926
	v_mul_i32_i24_e32 v11, 0x4ec5, v10
	v_lshrrev_b32_e32 v63, 31, v11
	v_ashrrev_i32_e32 v11, 20, v11
	v_add_u16_e32 v11, v11, v63
	v_lshlrev_b32_sdwa v128, v246, sext(v11) dst_sel:DWORD dst_unused:UNUSED_PAD src0_sel:DWORD src1_sel:WORD_0
	v_mul_lo_u16_e32 v63, 52, v11
	v_or_b32_e32 v11, v128, v16
	v_sub_u16_e32 v10, v10, v63
	v_mul_i32_i24_e32 v64, 0xe10, v11
	v_lshlrev_b32_sdwa v10, v246, sext(v10) dst_sel:DWORD dst_unused:UNUSED_PAD src0_sel:DWORD src1_sel:WORD_0
	v_ashrrev_i32_e32 v65, 31, v64
	v_lshl_add_u64 v[14:15], v[64:65], 2, v[14:15]
	v_ashrrev_i32_e32 v11, 31, v10
	v_lshl_add_u64 v[14:15], v[10:11], 2, v[14:15]
	v_lshl_add_u64 v[14:15], v[14:15], 0, v[180:181]
	v_add_co_u32_e32 v68, vcc, s73, v14
	s_mov_b32 s4, 0x2a000
	s_nop 0
	v_addc_co_u32_e32 v69, vcc, 0, v15, vcc
	v_add_co_u32_e32 v72, vcc, s71, v14
	global_load_dwordx4 v[64:67], v[14:15], off
	s_nop 0
	global_load_dwordx4 v[68:71], v[68:69], off offset:256
	v_addc_co_u32_e32 v73, vcc, 0, v15, vcc
	v_add_co_u32_e32 v76, vcc, s4, v14
	s_mov_b32 s4, 0x46000
	s_nop 0
	v_addc_co_u32_e32 v77, vcc, 0, v15, vcc
	v_add_co_u32_e32 v80, vcc, s85, v14
	global_load_dwordx4 v[72:75], v[72:73], off offset:512
	s_nop 0
	global_load_dwordx4 v[76:79], v[76:77], off offset:768
	v_addc_co_u32_e32 v81, vcc, 0, v15, vcc
	v_add_co_u32_e32 v84, vcc, s4, v14
	s_mov_b32 s4, 0x54000
	s_nop 0
	v_addc_co_u32_e32 v85, vcc, 0, v15, vcc
	v_add_co_u32_e32 v88, vcc, s4, v14
	s_mov_b32 s4, 0x62000
	s_nop 0
	v_addc_co_u32_e32 v89, vcc, 0, v15, vcc
	v_add_co_u32_e32 v92, vcc, s4, v14
	s_mov_b32 s4, 0x7e000
	s_nop 0
	v_addc_co_u32_e32 v93, vcc, 0, v15, vcc
	v_add_co_u32_e32 v96, vcc, s82, v14
	global_load_dwordx4 v[80:83], v[80:81], off offset:1024
	s_nop 0
	global_load_dwordx4 v[84:87], v[84:85], off offset:1280
	v_addc_co_u32_e32 v97, vcc, 0, v15, vcc
	v_add_co_u32_e32 v100, vcc, s4, v14
	s_mov_b32 s4, 0x8c000
	s_nop 0
	v_addc_co_u32_e32 v101, vcc, 0, v15, vcc
	v_add_co_u32_e32 v104, vcc, s4, v14
	s_mov_b32 s4, 0x9a000
	s_nop 0
	v_addc_co_u32_e32 v105, vcc, 0, v15, vcc
	v_add_co_u32_e32 v108, vcc, s4, v14
	s_mov_b32 s4, 0xa8000
	s_nop 0
	v_addc_co_u32_e32 v109, vcc, 0, v15, vcc
	v_add_co_u32_e32 v112, vcc, s4, v14
	s_mov_b32 s4, 0xb6000
	s_nop 0
	v_addc_co_u32_e32 v113, vcc, 0, v15, vcc
	v_add_co_u32_e32 v116, vcc, s4, v14
	global_load_dwordx4 v[88:91], v[88:89], off offset:1536
	s_nop 0
	global_load_dwordx4 v[92:95], v[92:93], off offset:1792
	v_addc_co_u32_e32 v117, vcc, 0, v15, vcc
	global_load_dwordx4 v[96:99], v[96:97], off offset:2048
	s_nop 0
	global_load_dwordx4 v[100:103], v[100:101], off offset:2304
	s_nop 0
	global_load_dwordx4 v[104:107], v[104:105], off offset:2560
	s_nop 0
	global_load_dwordx4 v[108:111], v[108:109], off offset:2816
	s_nop 0
	global_load_dwordx4 v[112:115], v[112:113], off offset:3072
	s_nop 0
	global_load_dwordx4 v[116:119], v[116:117], off offset:3328
	s_mov_b32 s4, 0xc4000
	v_add_co_u32_e32 v120, vcc, s4, v14
	s_mov_b32 s4, 0xd2000
	s_nop 0
	v_addc_co_u32_e32 v121, vcc, 0, v15, vcc
	global_load_dwordx4 v[120:123], v[120:121], off offset:3584
	v_add_co_u32_e32 v14, vcc, s4, v14
	v_ashrrev_i32_e32 v129, 31, v128
	s_nop 0
	v_addc_co_u32_e32 v15, vcc, 0, v15, vcc
	global_load_dwordx4 v[124:127], v[14:15], off offset:3840
	v_lshl_add_u64 v[6:7], v[128:129], 1, v[6:7]
	v_or_b32_e32 v11, v10, v17
	s_waitcnt vmcnt(15)
	ds_write2_b32 v32, v64, v65 offset1:1
	ds_write2_b32 v32, v66, v67 offset0:2 offset1:3
	s_waitcnt vmcnt(14)
	ds_write2_b32 v9, v68, v69 offset1:1
	ds_write2_b32 v34, v70, v71 offset1:1
	s_waitcnt vmcnt(13)
	ds_write2_b32 v35, v72, v73 offset1:1
	ds_write2_b32 v36, v74, v75 offset1:1
	s_waitcnt vmcnt(12)
	ds_write2_b32 v37, v76, v77 offset1:1
	ds_write2_b32 v38, v78, v79 offset1:1
	s_waitcnt vmcnt(11)
	ds_write2_b32 v39, v80, v81 offset1:1
	ds_write2_b32 v40, v82, v83 offset1:1
	s_waitcnt vmcnt(10)
	ds_write2_b32 v41, v84, v85 offset1:1
	ds_write2_b32 v42, v86, v87 offset1:1
	s_waitcnt vmcnt(9)
	ds_write2_b32 v43, v88, v89 offset1:1
	ds_write2_b32 v44, v90, v91 offset1:1
	s_waitcnt vmcnt(8)
	ds_write2_b32 v45, v92, v93 offset1:1
	ds_write2_b32 v46, v94, v95 offset1:1
	s_waitcnt vmcnt(7)
	ds_write2_b32 v47, v96, v97 offset1:1
	ds_write2_b32 v48, v98, v99 offset1:1
	s_waitcnt vmcnt(6)
	ds_write2_b32 v49, v100, v101 offset1:1
	ds_write2_b32 v50, v102, v103 offset1:1
	s_waitcnt vmcnt(5)
	ds_write2_b32 v51, v104, v105 offset1:1
	ds_write2_b32 v52, v106, v107 offset1:1
	s_waitcnt vmcnt(4)
	ds_write2_b32 v53, v108, v109 offset1:1
	ds_write2_b32 v54, v110, v111 offset1:1
	s_waitcnt vmcnt(3)
	ds_write2_b32 v55, v112, v113 offset1:1
	ds_write2_b32 v56, v114, v115 offset1:1
	s_waitcnt vmcnt(2)
	ds_write2_b32 v57, v116, v117 offset1:1
	ds_write2_b32 v58, v118, v119 offset1:1
	s_waitcnt vmcnt(1)
	ds_write2_b32 v59, v120, v121 offset1:1
	ds_write2_b32 v60, v122, v123 offset1:1
	s_waitcnt vmcnt(0)
	ds_write2_b32 v61, v124, v125 offset1:1
	ds_write2_b32 v62, v126, v127 offset1:1
	s_waitcnt lgkmcnt(0)
	v_mov_b32_e32 v9, v181
	ds_read2_b32 v[14:15], v18 offset0:65 offset1:73
	ds_read2_b32 v[34:35], v18 offset1:8
	ds_read2_b32 v[36:37], v18 offset0:130 offset1:138
	ds_read2_b32 v[38:39], v18 offset0:195 offset1:203
	ds_read2_b32 v[40:41], v33 offset0:4 offset1:12
	ds_read2_b32 v[42:43], v33 offset0:69 offset1:77
	ds_read2_b32 v[44:45], v33 offset0:134 offset1:142
	ds_read2_b32 v[46:47], v33 offset0:199 offset1:207
	v_lshl_add_u64 v[48:49], v[6:7], 0, v[8:9]
	s_waitcnt lgkmcnt(6)
	v_cvt_pk_bf16_f32 v6, v34, v14
	v_add_u32_e32 v14, 0xfffffb00, v10
	v_or_b32_e32 v52, v10, v26
	v_cmp_gt_u32_e32 vcc, s74, v14
	s_waitcnt lgkmcnt(4)
	v_cvt_pk_bf16_f32 v7, v36, v38
	s_waitcnt lgkmcnt(2)
	v_cvt_pk_bf16_f32 v8, v40, v42
	v_cndmask_b32_e32 v50, v11, v52, vcc
	v_ashrrev_i32_e32 v51, 31, v50
	v_lshlrev_b64 v[50:51], 11, v[50:51]
	v_cndmask_b32_e64 v11, 0, 1, vcc
	s_waitcnt lgkmcnt(0)
	v_cvt_pk_bf16_f32 v9, v44, v46
	v_lshl_add_u64 v[50:51], v[48:49], 0, v[50:51]
	v_lshl_or_b32 v14, v19, v11, v10
	global_store_dwordx4 v[50:51], v[6:9], off sc1
	s_nop 1
	v_cvt_pk_bf16_f32 v6, v35, v15
	v_ashrrev_i32_e32 v15, 31, v14
	v_cvt_pk_bf16_f32 v7, v37, v39
	v_cvt_pk_bf16_f32 v8, v41, v43
	v_cvt_pk_bf16_f32 v9, v45, v47
	v_lshlrev_b64 v[14:15], 11, v[14:15]
	ds_read2_b32 v[34:35], v18 offset0:81 offset1:89
	ds_read2_b32 v[36:37], v18 offset0:16 offset1:24
	ds_read2_b32 v[38:39], v18 offset0:146 offset1:154
	ds_read2_b32 v[40:41], v18 offset0:211 offset1:219
	ds_read2_b32 v[42:43], v33 offset0:20 offset1:28
	ds_read2_b32 v[44:45], v33 offset0:85 offset1:93
	ds_read2_b32 v[46:47], v33 offset0:150 offset1:158
	ds_read2_b32 v[50:51], v33 offset0:215 offset1:223
	v_lshl_add_u64 v[14:15], v[48:49], 0, v[14:15]
	global_store_dwordx4 v[14:15], v[6:9], off sc1
	v_lshl_or_b32 v14, v20, v11, v10
	v_ashrrev_i32_e32 v15, 31, v14
	v_lshlrev_b64 v[14:15], 11, v[14:15]
	s_waitcnt lgkmcnt(6)
	v_cvt_pk_bf16_f32 v6, v36, v34
	s_waitcnt lgkmcnt(4)
	v_cvt_pk_bf16_f32 v7, v38, v40
	s_waitcnt lgkmcnt(2)
	v_cvt_pk_bf16_f32 v8, v42, v44
	s_waitcnt lgkmcnt(0)
	v_cvt_pk_bf16_f32 v9, v46, v50
	v_lshl_add_u64 v[14:15], v[48:49], 0, v[14:15]
	global_store_dwordx4 v[14:15], v[6:9], off sc1
	v_lshl_or_b32 v14, v21, v11, v10
	v_ashrrev_i32_e32 v15, 31, v14
	v_lshlrev_b64 v[14:15], 11, v[14:15]
	v_cvt_pk_bf16_f32 v6, v37, v35
	v_cvt_pk_bf16_f32 v7, v39, v41
	v_cvt_pk_bf16_f32 v8, v43, v45
	v_cvt_pk_bf16_f32 v9, v47, v51
	v_lshl_add_u64 v[14:15], v[48:49], 0, v[14:15]
	ds_read2_b32 v[34:35], v18 offset0:32 offset1:40
	ds_read2_b32 v[36:37], v18 offset0:97 offset1:105
	ds_read2_b32 v[38:39], v18 offset0:162 offset1:170
	ds_read2_b32 v[40:41], v18 offset0:227 offset1:235
	ds_read2_b32 v[42:43], v33 offset0:36 offset1:44
	ds_read2_b32 v[44:45], v33 offset0:101 offset1:109
	ds_read2_b32 v[46:47], v33 offset0:166 offset1:174
	ds_read2_b32 v[50:51], v33 offset0:231 offset1:239
	global_store_dwordx4 v[14:15], v[6:9], off sc1
	v_or_b32_e32 v11, v10, v22
	v_or_b32_e32 v14, 1, v52
	v_cndmask_b32_e32 v14, v11, v14, vcc
	v_ashrrev_i32_e32 v15, 31, v14
	v_lshlrev_b64 v[14:15], 11, v[14:15]
	s_waitcnt lgkmcnt(6)
	v_cvt_pk_bf16_f32 v6, v34, v36
	s_waitcnt lgkmcnt(4)
	v_cvt_pk_bf16_f32 v7, v38, v40
	s_waitcnt lgkmcnt(2)
	v_cvt_pk_bf16_f32 v8, v42, v44
	s_waitcnt lgkmcnt(0)
	v_cvt_pk_bf16_f32 v9, v46, v50
	v_lshl_add_u64 v[14:15], v[48:49], 0, v[14:15]
	v_cndmask_b32_e32 v11, v23, v27, vcc
	global_store_dwordx4 v[14:15], v[6:9], off sc1
	v_or_b32_e32 v14, v11, v10
	v_ashrrev_i32_e32 v15, 31, v14
	v_cvt_pk_bf16_f32 v6, v35, v37
	v_cvt_pk_bf16_f32 v7, v39, v41
	v_cvt_pk_bf16_f32 v8, v43, v45
	v_cvt_pk_bf16_f32 v9, v47, v51
	v_lshlrev_b64 v[14:15], 11, v[14:15]
	ds_read2_b32 v[34:35], v18 offset0:48 offset1:56
	ds_read2_b32 v[36:37], v18 offset0:113 offset1:121
	ds_read2_b32 v[38:39], v18 offset0:178 offset1:186
	ds_read2_b32 v[40:41], v18 offset0:243 offset1:251
	ds_read2_b32 v[42:43], v33 offset0:52 offset1:60
	ds_read2_b32 v[44:45], v33 offset0:117 offset1:125
	ds_read2_b32 v[46:47], v33 offset0:182 offset1:190
	ds_read2_b32 v[50:51], v33 offset0:247 offset1:255
	v_lshl_add_u64 v[14:15], v[48:49], 0, v[14:15]
	v_cndmask_b32_e32 v11, v24, v28, vcc
	global_store_dwordx4 v[14:15], v[6:9], off sc1
	v_or_b32_e32 v14, v11, v10
	v_cndmask_b32_e32 v11, v25, v29, vcc
	v_ashrrev_i32_e32 v15, 31, v14
	v_or_b32_e32 v10, v11, v10
	v_lshlrev_b64 v[14:15], 11, v[14:15]
	v_ashrrev_i32_e32 v11, 31, v10
	s_waitcnt lgkmcnt(6)
	v_cvt_pk_bf16_f32 v6, v34, v36
	s_waitcnt lgkmcnt(4)
	v_cvt_pk_bf16_f32 v7, v38, v40
	s_waitcnt lgkmcnt(2)
	v_cvt_pk_bf16_f32 v8, v42, v44
	s_waitcnt lgkmcnt(0)
	v_cvt_pk_bf16_f32 v9, v46, v50
	v_lshl_add_u64 v[14:15], v[48:49], 0, v[14:15]
	v_lshlrev_b64 v[10:11], 11, v[10:11]
	global_store_dwordx4 v[14:15], v[6:9], off sc1
	v_lshl_add_u64 v[10:11], v[48:49], 0, v[10:11]
	s_nop 0
	v_cvt_pk_bf16_f32 v6, v35, v37
	v_cvt_pk_bf16_f32 v7, v39, v41
	v_cvt_pk_bf16_f32 v8, v43, v45
	v_cvt_pk_bf16_f32 v9, v47, v51
	global_store_dwordx4 v[10:11], v[6:9], off sc1
	s_waitcnt lgkmcnt(0)
	s_branch .LBB0_926

.LBB0_933:
	s_load_dwordx2 s[0:1], s[80:81], 0x40
	v_ashrrev_i32_e32 v8, 31, v5
	v_lshrrev_b32_e32 v9, 18, v8
	v_lshrrev_b32_e32 v8, 22, v8
	v_add_u32_e32 v9, v5, v9
	v_add_u32_e32 v8, v5, v8
	s_waitcnt lgkmcnt(0)
	v_mov_b64_e32 v[6:7], s[0:1]
	v_ashrrev_i32_e32 v15, 14, v9
	v_ashrrev_i32_e32 v10, 10, v8
	v_lshrrev_b32_e32 v8, 28, v10
	v_mad_i64_i32 v[6:7], s[0:1], v15, s54, v[6:7]
	v_mul_i32_i24_e32 v9, 0x400, v10
	v_add_u32_e32 v11, v10, v8
	s_movk_i32 s0, 0xf1f0
	v_mad_u64_u32 v[8:9], s[0:1], v9, s0, v[4:5]
	v_and_b32_e32 v11, -16, v11
	v_ashrrev_i32_e32 v9, 31, v8
	v_sub_u32_e32 v10, v10, v11
	v_lshl_add_u64 v[6:7], v[8:9], 2, v[6:7]
	v_ashrrev_i32_e32 v11, 31, v10
	v_lshl_add_u64 v[6:7], v[10:11], 2, v[6:7]
	v_add_co_u32_e32 v6, vcc, s84, v6
	v_mul_i32_i24_e32 v8, 0x4000, v15
	s_nop 0
	v_addc_co_u32_e32 v7, vcc, 0, v7, vcc
	global_load_dword v10, v[6:7], off offset:1024
	v_mov_b64_e32 v[6:7], s[78:79]
	v_sub_u32_e32 v8, v5, v8
	v_mad_i64_i32 v[6:7], s[0:1], v15, s65, v[6:7]
	v_add_u32_e32 v5, s20, v5
	v_ashrrev_i32_e32 v9, 31, v8
	v_cmp_lt_i32_e32 vcc, s2, v5
	v_lshl_add_u64 v[6:7], v[8:9], 2, v[6:7]
	s_mul_i32 s0, s20, 0xe10
	s_or_b64 s[8:9], vcc, s[8:9]
	v_add_co_u32_e32 v6, vcc, 0x1920000, v6
	v_add_u32_e32 v4, s0, v4
	s_nop 0
	v_addc_co_u32_e32 v7, vcc, 0, v7, vcc
	s_waitcnt vmcnt(0)
	global_store_dword v[6:7], v10, off sc1
	s_andn2_b64 exec, exec, s[8:9]
	s_cbranch_execnz .LBB0_933

.LBB0_936:
	s_or_b64 exec, exec, s[6:7]
	v_mul_f32_e32 v16, v10, v10
	v_fmamk_f32 v17, v16, 0xb94c1982, v240
	v_fmaak_f32 v17, v16, v17, 0xbe2aaa9d
	v_mul_f32_e32 v17, v16, v17
	v_fmac_f32_e32 v10, v10, v17
	v_fmamk_f32 v17, v16, 0x37d75334, v241
	v_fmaak_f32 v17, v16, v17, 0x3d2aabf7
	v_fmaak_f32 v17, v16, v17, 0xbf000004
	v_fma_f32 v16, v16, v17, 1.0
	v_lshlrev_b32_e32 v17, 30, v11
	v_and_b32_e32 v11, 1, v11
	v_cmp_eq_u32_e32 vcc, 0, v11
	v_xor_b32_e32 v9, v9, v8
	s_brev_b32 s0, 1
	v_cndmask_b32_e32 v11, v16, v10, vcc
	v_xor_b32_e32 v10, 0x80000000, v10
	v_cndmask_b32_e32 v10, v10, v16, vcc
	v_and_b32_e32 v18, 0x80000000, v17
	v_xor_b32_e32 v9, v9, v11
	v_bitop3_b32 v10, v10, v17, s0 bitop3:0x78
	s_movk_i32 s0, 0x1f8
	v_xor_b32_e32 v9, v9, v18
	v_cmp_class_f32_e64 vcc, v8, s0
	v_add_u32_e32 v7, s20, v7
	s_mov_b32 s0, 0x21fff
	v_cndmask_b32_e32 v8, v242, v10, vcc
	v_cndmask_b32_e32 v9, v242, v9, vcc
	v_cmp_lt_i32_e32 vcc, s0, v7
	global_store_dwordx2 v[4:5], v[8:9], off sc1
	s_or_b64 s[16:17], vcc, s[16:17]
	v_lshl_add_u64 v[4:5], v[4:5], 0, s[14:15]
	s_andn2_b64 exec, exec, s[16:17]
	s_cbranch_execz .LBB0_941

.LBB0_943:
	s_load_dwordx2 s[0:1], s[80:81], 0x48
	v_add_u32_e32 v6, s20, v6
	s_waitcnt lgkmcnt(0)
	v_lshl_add_u64 v[8:9], s[0:1], 0, v[4:5]
	global_load_dword v7, v[8:9], off
	s_nop 0
	global_load_dword v8, v[8:9], off offset:2048
	s_waitcnt vmcnt(1)
	v_max_f32_e32 v10, v7, v7
	s_waitcnt vmcnt(0)
	v_max_f32_e32 v9, v8, v8
	v_max_f32_e32 v9, v10, v9
	v_sub_f32_e32 v7, v7, v9
	v_mul_f32_e32 v10, 0x3fb8aa3b, v7
	v_fma_f32 v11, v7, s2, -v10
	v_rndne_f32_e32 v16, v10
	v_fmac_f32_e32 v11, 0x32a5705f, v7
	v_sub_f32_e32 v10, v10, v16
	v_add_f32_e32 v10, v10, v11
	v_exp_f32_e32 v10, v10
	v_cvt_i32_f32_e32 v11, v16
	v_cmp_ngt_f32_e32 vcc, s4, v7
	v_sub_f32_e32 v8, v8, v9
	v_mul_f32_e32 v9, 0x3fb8aa3b, v8
	v_ldexp_f32 v10, v10, v11
	v_cndmask_b32_e32 v10, 0, v10, vcc
	v_cmp_nlt_f32_e32 vcc, s5, v7
	v_rndne_f32_e32 v11, v9
	s_nop 0
	v_cndmask_b32_e32 v7, v249, v10, vcc
	v_fma_f32 v10, v8, s2, -v9
	v_fmac_f32_e32 v10, 0x32a5705f, v8
	v_sub_f32_e32 v9, v9, v11
	v_add_f32_e32 v9, v9, v10
	v_exp_f32_e32 v9, v9
	v_cvt_i32_f32_e32 v10, v11
	v_cmp_ngt_f32_e32 vcc, s4, v8
	v_ldexp_f32 v9, v9, v10
	s_nop 0
	v_cndmask_b32_e32 v9, 0, v9, vcc
	v_cmp_nlt_f32_e32 vcc, s5, v8
	s_nop 1
	v_cndmask_b32_e32 v10, v249, v9, vcc
	v_add_f32_e32 v7, v7, v10
	v_div_scale_f32 v11, s[0:1], v7, v7, v10
	v_rcp_f32_e32 v16, v11
	v_lshl_add_u64 v[8:9], s[78:79], 0, v[4:5]
	v_add_co_u32_e32 v8, vcc, 0x33dc000, v8
	v_fma_f32 v17, -v11, v16, 1.0
	s_nop 0
	v_addc_co_u32_e32 v9, vcc, 0, v9, vcc
	v_fmac_f32_e32 v16, v17, v16
	v_div_scale_f32 v17, vcc, v10, v7, v10
	v_mul_f32_e32 v18, v17, v16
	v_fma_f32 v19, -v11, v18, v17
	v_fmac_f32_e32 v18, v19, v16
	v_fma_f32 v11, -v11, v18, v17
	v_div_fmas_f32 v11, v11, v16, v18
	v_cmp_lt_i32_e32 vcc, s72, v6
	v_div_fixup_f32 v7, v11, v7, v10
	v_lshl_add_u64 v[4:5], v[4:5], 0, s[8:9]
	s_or_b64 s[10:11], vcc, s[10:11]
	global_store_dword v[8:9], v181, off sc1
	global_store_dword v[8:9], v7, off offset:2048 sc1
	s_andn2_b64 exec, exec, s[10:11]
	s_cbranch_execnz .LBB0_943

.LBB0_946:
	s_or_b64 exec, exec, s[6:7]
	s_waitcnt vmcnt(0)
	v_mul_f32_e32 v8, v20, v8
	v_mul_f32_e32 v11, 0x3fb8aa3b, v8
	s_mov_b32 s2, 0x3fb8aa3b
	v_fma_f32 v15, v8, s2, -v11
	v_rndne_f32_e32 v23, v11
	v_fmac_f32_e32 v15, 0x32a5705f, v8
	v_sub_f32_e32 v11, v11, v23
	v_add_f32_e32 v11, v11, v15
	v_exp_f32_e32 v11, v11
	v_cvt_i32_f32_e32 v15, v23
	s_mov_b32 s6, 0xc2ce8ed0
	v_cmp_ngt_f32_e32 vcc, s6, v8
	s_mov_b32 s7, 0x42b17218
	v_ldexp_f32 v11, v11, v15
	v_cndmask_b32_e32 v11, 0, v11, vcc
	v_cmp_nlt_f32_e32 vcc, s7, v8
	v_xor_b32_e32 v7, v7, v6
	s_brev_b32 s1, 1
	v_cndmask_b32_e32 v8, v249, v11, vcc
	v_mul_f32_e32 v11, v9, v9
	v_fmamk_f32 v15, v11, 0xb94c1982, v240
	v_fmaak_f32 v15, v11, v15, 0xbe2aaa9d
	v_mul_f32_e32 v15, v11, v15
	v_fmac_f32_e32 v9, v9, v15
	v_fmamk_f32 v15, v11, 0x37d75334, v241
	v_fmaak_f32 v15, v11, v15, 0x3d2aabf7
	v_fmaak_f32 v15, v11, v15, 0xbf000004
	v_fma_f32 v11, v11, v15, 1.0
	v_lshlrev_b32_e32 v15, 30, v10
	v_and_b32_e32 v10, 1, v10
	v_cmp_eq_u32_e32 vcc, 0, v10
	v_and_b32_e32 v23, 0x80000000, v15
	v_lshl_or_b32 v4, v5, 4, v4
	v_cndmask_b32_e32 v10, v11, v9, vcc
	v_xor_b32_e32 v9, 0x80000000, v9
	v_cndmask_b32_e32 v9, v9, v11, vcc
	v_xor_b32_e32 v7, v7, v10
	v_bitop3_b32 v9, v9, v15, s1 bitop3:0x78
	s_movk_i32 s1, 0x1f8
	v_xor_b32_e32 v7, v7, v23
	v_cmp_class_f32_e64 vcc, v6, s1
	v_ashrrev_i32_e32 v5, 31, v4
	v_lshlrev_b64 v[4:5], 12, v[4:5]
	v_cndmask_b32_e32 v7, v242, v7, vcc
	v_cndmask_b32_e32 v9, v242, v9, vcc
	v_mul_f32_e32 v49, v8, v7
	v_mul_f32_e32 v6, v8, v9
	v_mov_b32_e32 v7, v49
	global_store_dwordx2 v[16:17], v[6:7], off offset:-128 sc1
	s_load_dwordx2 s[4:5], s[80:81], 0xa0
	v_fma_f32 v48, v8, v9, -1.0
	v_and_b32_e32 v6, 0x3f0, v22
	v_pk_mul_f32 v[8:9], v[20:21], v[48:49]
	v_lshl_or_b32 v4, v6, 2, v4
	v_add_f32_e32 v15, v8, v9
	v_lshl_add_u64 v[8:9], s[18:19], 0, v[4:5]
	s_waitcnt lgkmcnt(0)
	v_lshl_add_u64 v[44:45], s[4:5], 0, v[4:5]
	global_load_dwordx4 v[4:7], v[8:9], off offset:48
	global_load_dwordx4 v[24:27], v[8:9], off offset:32
	global_load_dwordx4 v[28:31], v[8:9], off offset:16
	global_load_dwordx4 v[32:35], v[8:9], off
	s_nop 0
	global_load_dwordx4 v[8:11], v[44:45], off offset:48
	global_load_dwordx4 v[36:39], v[44:45], off offset:32
	global_load_dwordx4 v[40:43], v[44:45], off offset:16
	s_nop 0
	global_load_dwordx4 v[44:47], v[44:45], off
	v_mov_b32_e32 v50, v21
	v_mov_b32_e32 v52, v48
	v_mov_b32_e32 v53, v21
	v_mov_b32_e32 v48, v49
	v_mov_b32_e32 v49, v20
	v_pk_mul_f32 v[50:51], v[50:51], v[52:53] op_sel_hi:[0,1]
	v_pk_mul_f32 v[20:21], v[20:21], v[48:49] op_sel_hi:[0,1]
	v_add_f32_e32 v21, v21, v51
	v_div_scale_f32 v23, s[4:5], v21, v21, v15
	v_rcp_f32_e32 v48, v23
	v_add_u32_e32 v14, s20, v14
	s_movk_i32 s1, 0xfff
	v_fma_f32 v49, -v23, v48, 1.0
	v_fmac_f32_e32 v48, v49, v48
	v_div_scale_f32 v49, vcc, v15, v21, v15
	v_mul_f32_e32 v51, v49, v48
	v_fma_f32 v52, -v23, v51, v49
	v_fmac_f32_e32 v51, v52, v48
	v_fma_f32 v23, -v23, v51, v49
	v_div_fmas_f32 v23, v23, v48, v51
	v_div_fixup_f32 v52, v23, v21, v15
	v_sub_f32_e32 v15, v20, v50
	v_div_scale_f32 v20, s[4:5], v21, v21, v15
	v_rcp_f32_e32 v23, v20
	v_add_u32_e32 v22, s0, v22
	v_lshl_add_u64 v[18:19], v[18:19], 0, s[26:27]
	v_fma_f32 v48, -v20, v23, 1.0
	v_fmac_f32_e32 v23, v48, v23
	v_div_scale_f32 v48, vcc, v15, v21, v15
	v_mul_f32_e32 v49, v48, v23
	v_fma_f32 v50, -v20, v49, v48
	v_fmac_f32_e32 v49, v50, v23
	v_fma_f32 v20, -v20, v49, v48
	v_div_fmas_f32 v20, v20, v23, v49
	v_div_fixup_f32 v20, v20, v21, v15
	v_cmp_lt_i32_e32 vcc, s1, v14
	s_or_b64 s[28:29], vcc, s[28:29]
	s_waitcnt vmcnt(0)
	v_pk_mul_f32 v[48:49], v[44:45], v[20:21] op_sel_hi:[1,0]
	s_nop 0
	v_pk_fma_f32 v[48:49], v[32:33], v[52:53], v[48:49] op_sel_hi:[1,0,1] neg_lo:[0,0,1] neg_hi:[0,0,1]
	v_pk_mul_f32 v[32:33], v[32:33], v[20:21] op_sel_hi:[1,0]
	s_nop 0
	v_pk_fma_f32 v[32:33], v[44:45], v[52:53], v[32:33] op_sel_hi:[1,0,1]
	v_pk_mul_f32 v[44:45], v[46:47], v[20:21] op_sel_hi:[1,0]
	s_nop 0
	v_pk_fma_f32 v[50:51], v[34:35], v[52:53], v[44:45] op_sel_hi:[1,0,1] neg_lo:[0,0,1] neg_hi:[0,0,1]
	v_pk_mul_f32 v[34:35], v[34:35], v[20:21] op_sel_hi:[1,0]
	global_store_dwordx4 v[16:17], v[48:51], off offset:-120 sc1
	v_pk_fma_f32 v[34:35], v[46:47], v[52:53], v[34:35] op_sel_hi:[1,0,1]
	global_store_dwordx4 v[16:17], v[32:35], off offset:-56 sc1
	s_nop 1
	v_pk_mul_f32 v[32:33], v[40:41], v[20:21] op_sel_hi:[1,0]
	v_pk_mul_f32 v[34:35], v[42:43], v[20:21] op_sel_hi:[1,0]
	v_pk_fma_f32 v[32:33], v[28:29], v[52:53], v[32:33] op_sel_hi:[1,0,1] neg_lo:[0,0,1] neg_hi:[0,0,1]
	v_pk_mul_f32 v[28:29], v[28:29], v[20:21] op_sel_hi:[1,0]
	v_pk_fma_f32 v[34:35], v[30:31], v[52:53], v[34:35] op_sel_hi:[1,0,1] neg_lo:[0,0,1] neg_hi:[0,0,1]
	v_pk_mul_f32 v[30:31], v[30:31], v[20:21] op_sel_hi:[1,0]
	v_pk_fma_f32 v[28:29], v[40:41], v[52:53], v[28:29] op_sel_hi:[1,0,1]
	v_pk_fma_f32 v[30:31], v[42:43], v[52:53], v[30:31] op_sel_hi:[1,0,1]
	global_store_dwordx4 v[16:17], v[28:31], off offset:-40 sc1
	global_store_dwordx4 v[16:17], v[32:35], off offset:-104 sc1
	s_nop 0
	v_pk_mul_f32 v[28:29], v[36:37], v[20:21] op_sel_hi:[1,0]
	v_pk_mul_f32 v[30:31], v[38:39], v[20:21] op_sel_hi:[1,0]
	v_pk_fma_f32 v[28:29], v[24:25], v[52:53], v[28:29] op_sel_hi:[1,0,1] neg_lo:[0,0,1] neg_hi:[0,0,1]
	v_pk_mul_f32 v[24:25], v[24:25], v[20:21] op_sel_hi:[1,0]
	v_pk_fma_f32 v[30:31], v[26:27], v[52:53], v[30:31] op_sel_hi:[1,0,1] neg_lo:[0,0,1] neg_hi:[0,0,1]
	v_pk_mul_f32 v[26:27], v[26:27], v[20:21] op_sel_hi:[1,0]
	v_pk_fma_f32 v[24:25], v[36:37], v[52:53], v[24:25] op_sel_hi:[1,0,1]
	v_pk_fma_f32 v[26:27], v[38:39], v[52:53], v[26:27] op_sel_hi:[1,0,1]
	global_store_dwordx4 v[16:17], v[24:27], off offset:-24 sc1
	global_store_dwordx4 v[16:17], v[28:31], off offset:-88 sc1
	s_nop 0
	v_pk_mul_f32 v[24:25], v[8:9], v[20:21] op_sel_hi:[1,0]
	s_nop 0
	v_pk_fma_f32 v[24:25], v[4:5], v[52:53], v[24:25] op_sel_hi:[1,0,1] neg_lo:[0,0,1] neg_hi:[0,0,1]
	v_pk_mul_f32 v[4:5], v[4:5], v[20:21] op_sel_hi:[1,0]
	s_nop 0
	v_pk_fma_f32 v[4:5], v[8:9], v[52:53], v[4:5] op_sel_hi:[1,0,1]
	v_pk_mul_f32 v[8:9], v[10:11], v[20:21] op_sel_hi:[1,0]
	s_nop 0
	v_pk_fma_f32 v[26:27], v[6:7], v[52:53], v[8:9] op_sel_hi:[1,0,1] neg_lo:[0,0,1] neg_hi:[0,0,1]
	v_pk_mul_f32 v[6:7], v[6:7], v[20:21] op_sel_hi:[1,0]
	global_store_dwordx4 v[16:17], v[24:27], off offset:-72 sc1
	v_pk_fma_f32 v[6:7], v[10:11], v[52:53], v[6:7] op_sel_hi:[1,0,1]
	global_store_dwordx4 v[16:17], v[4:7], off offset:-8 sc1
	v_lshl_add_u64 v[16:17], v[16:17], 0, s[24:25]
	s_andn2_b64 exec, exec, s[28:29]
	s_cbranch_execz .LBB0_951

.LBB0_978:
	s_or_b64 exec, exec, s[10:11]
	v_pk_mul_f32 v[76:77], v[70:71], v[70:71]
	v_pk_mul_f32 v[78:79], v[68:69], v[68:69]
	v_pk_mul_f32 v[62:63], v[62:63], v[62:63]
	v_pk_mov_b32 v[122:123], v[78:79], v[76:77] op_sel:[1,0]
	v_mov_b32_e32 v79, v77
	v_pk_mul_f32 v[60:61], v[60:61], v[60:61]
	v_pk_add_f32 v[76:77], v[122:123], v[78:79]
	v_pk_mov_b32 v[78:79], v[60:61], v[62:63] op_sel:[1,0]
	v_mov_b32_e32 v61, v63
	v_pk_add_f32 v[60:61], v[78:79], v[60:61]
	v_pk_add_f32 v[76:77], v[76:77], v[76:77] op_sel_hi:[0,1]
	v_pk_add_f32 v[60:61], v[60:61], v[60:61] op_sel_hi:[0,1]
	v_mul_f32_e32 v60, v84, v84
	v_pk_fma_f32 v[62:63], v[84:85], v[84:85], v[60:61] op_sel_hi:[1,1,0]
	v_mul_f32_e32 v60, v86, v86
	v_pk_fma_f32 v[78:79], v[86:87], v[86:87], v[60:61] op_sel_hi:[1,1,0]
	v_mul_f32_e32 v62, v52, v52
	v_mul_f32_e32 v78, v53, v53
	v_mul_f32_e32 v60, v54, v54
	v_mul_f32_e32 v76, v55, v55
	v_pk_add_f32 v[62:63], v[62:63], v[78:79]
	v_pk_add_f32 v[60:61], v[60:61], v[76:77]
	v_lshlrev_b32_e32 v180, 3, v114
	v_pk_add_f32 v[60:61], v[62:63], v[60:61]
	v_lshl_add_u64 v[78:79], s[86:87], 0, v[110:111]
	v_add_f32_e32 v60, v60, v61
	v_mov_b32_e32 v61, v181
	v_mov_b32_e32 v126, v120
	v_add_f32_dpp v60, v60, v60 row_shr:1 row_mask:0xf bank_mask:0xf bound_ctrl:1
	s_nop 1
	v_add_f32_dpp v60, v60, v60 row_shr:2 row_mask:0xf bank_mask:0xf bound_ctrl:1
	s_nop 1
	v_add_f32_dpp v60, v60, v60 row_shr:4 row_mask:0xf bank_mask:0xf bound_ctrl:1
	s_nop 1
	v_add_f32_dpp v60, v60, v60 row_shr:8 row_mask:0xf bank_mask:0xf bound_ctrl:1
	s_nop 1
	v_mov_b32_dpp v61, v60 row_bcast:15 row_mask:0xa bank_mask:0xf
	v_add_f32_e32 v60, v60, v61
	v_mov_b32_e32 v61, v181
	s_nop 1
	v_mov_b32_dpp v61, v60 row_bcast:31 row_mask:0xc bank_mask:0xf
	v_add_f32_e32 v60, v60, v61
	s_nop 0
	v_readlane_b32 s0, v60, 63
	s_nop 1
	v_fma_f32 v60, s0, v247, v237
	v_rsq_f32_e32 v76, v60
	s_nop 0
	v_pk_mul_f32 v[60:61], v[68:69], v[76:77] op_sel_hi:[1,0]
	v_pk_mul_f32 v[62:63], v[70:71], v[76:77] op_sel_hi:[1,0]
	s_waitcnt lgkmcnt(0)
	v_pk_fma_f32 v[60:61], v[72:73], v[60:61], v[80:81]
	v_pk_fma_f32 v[62:63], v[74:75], v[62:63], v[82:83]
	v_cvt_pk_bf16_f32 v60, v60, v61
	v_cvt_pk_bf16_f32 v61, v62, v63
	v_lshl_add_u64 v[62:63], v[78:79], 0, v[180:181]
	global_store_dwordx2 v[62:63], v[60:61], off sc1
	v_lshl_add_u32 v60, v112, 4, v124
	v_pk_mul_f32 v[80:81], v[64:65], v[76:77] op_sel_hi:[1,0]
	v_pk_mul_f32 v[82:83], v[66:67], v[76:77] op_sel_hi:[1,0]
	ds_read_b128 v[60:63], v60 offset:40960
	ds_read_b128 v[64:67], v121 offset:46080
	v_lshl_add_u32 v68, v116, 4, v124
	v_lshl_add_u32 v72, v118, 4, v124
	ds_read_b128 v[68:71], v68 offset:40960
	ds_read_b128 v[72:75], v72 offset:40960
	s_waitcnt lgkmcnt(2)
	v_pk_fma_f32 v[62:63], v[62:63], v[82:83], v[66:67]
	v_pk_fma_f32 v[60:61], v[60:61], v[80:81], v[64:65]
	v_cvt_pk_bf16_f32 v65, v62, v63
	v_cvt_pk_bf16_f32 v64, v60, v61
	v_lshl_add_u64 v[66:67], v[112:113], 3, v[78:79]
	ds_read_b128 v[60:63], v121 offset:47104
	global_store_dwordx2 v[66:67], v[64:65], off sc1
	v_pk_mul_f32 v[64:65], v[56:57], v[76:77] op_sel_hi:[1,0]
	v_pk_mul_f32 v[66:67], v[58:59], v[76:77] op_sel_hi:[1,0]
	ds_read_b128 v[56:59], v121 offset:48128
	v_pk_mul_f32 v[52:53], v[52:53], v[76:77] op_sel_hi:[1,0]
	v_pk_mul_f32 v[54:55], v[54:55], v[76:77] op_sel_hi:[1,0]
	s_waitcnt lgkmcnt(1)
	v_pk_fma_f32 v[62:63], v[70:71], v[66:67], v[62:63]
	v_pk_fma_f32 v[60:61], v[68:69], v[64:65], v[60:61]
	s_waitcnt lgkmcnt(0)
	v_pk_fma_f32 v[54:55], v[54:55], v[74:75], v[58:59]
	v_pk_fma_f32 v[52:53], v[52:53], v[72:73], v[56:57]
	v_cvt_pk_bf16_f32 v60, v60, v61
	v_cvt_pk_bf16_f32 v61, v62, v63
	v_lshl_add_u64 v[62:63], v[116:117], 3, v[78:79]
	v_cvt_pk_bf16_f32 v52, v52, v53
	v_cvt_pk_bf16_f32 v53, v54, v55
	v_lshl_add_u64 v[54:55], v[118:119], 3, v[78:79]
	global_store_dwordx2 v[62:63], v[60:61], off sc1
	global_store_dwordx2 v[54:55], v[52:53], off sc1

.LBB0_988:
	s_or_b64 exec, exec, s[12:13]
	v_pk_mul_f32 v[116:117], v[58:59], v[58:59]
	v_pk_mul_f32 v[118:119], v[56:57], v[56:57]
	v_mul_f32_e32 v81, v64, v64
	v_pk_mov_b32 v[120:121], v[118:119], v[116:117] op_sel:[1,0]
	v_mov_b32_e32 v119, v117
	v_pk_add_f32 v[116:117], v[120:121], v[118:119]
	v_pk_mul_f32 v[118:119], v[54:55], v[54:55]
	v_pk_mul_f32 v[120:121], v[52:53], v[52:53]
	v_pk_add_f32 v[116:117], v[116:117], v[116:117] op_sel:[0,1] op_sel_hi:[1,0]
	v_pk_mov_b32 v[122:123], v[120:121], v[118:119] op_sel:[1,0]
	v_mov_b32_e32 v121, v119
	v_pk_add_f32 v[118:119], v[122:123], v[120:121]
	v_mul_f32_e32 v120, v65, v65
	v_pk_add_f32 v[118:119], v[118:119], v[118:119] op_sel:[0,1] op_sel_hi:[1,0]
	v_mov_b32_e32 v117, v81
	v_mov_b32_e32 v119, v120
	v_pk_add_f32 v[116:117], v[116:117], v[118:119]
	v_mul_f32_e32 v118, v61, v61
	v_mul_f32_e32 v121, v66, v66
	v_pk_fma_f32 v[118:119], v[60:61], v[60:61], v[118:119] op_sel_hi:[1,1,0]
	v_mul_f32_e32 v120, v63, v63
	v_mul_f32_e32 v122, v67, v67
	v_mov_b32_e32 v119, v121
	v_pk_fma_f32 v[120:121], v[62:63], v[62:63], v[120:121] op_sel_hi:[1,1,0]
	v_lshlrev_b32_e32 v180, 3, v80
	v_mov_b32_e32 v121, v122
	v_pk_add_f32 v[118:119], v[118:119], v[120:121]
	s_nop 0
	v_pk_add_f32 v[116:117], v[116:117], v[118:119]
	s_nop 0
	v_add_f32_e32 v81, v116, v117
	v_mov_b32_e32 v116, v181
	s_nop 0
	v_add_f32_dpp v81, v81, v81 row_shr:1 row_mask:0xf bank_mask:0xf bound_ctrl:1
	s_nop 1
	v_add_f32_dpp v81, v81, v81 row_shr:2 row_mask:0xf bank_mask:0xf bound_ctrl:1
	s_nop 1
	v_add_f32_dpp v81, v81, v81 row_shr:4 row_mask:0xf bank_mask:0xf bound_ctrl:1
	s_nop 1
	v_add_f32_dpp v81, v81, v81 row_shr:8 row_mask:0xf bank_mask:0xf bound_ctrl:1
	s_nop 1
	v_mov_b32_dpp v116, v81 row_bcast:15 row_mask:0xa bank_mask:0xf
	v_add_f32_e32 v81, v81, v116
	v_mov_b32_e32 v116, v181
	s_nop 1
	v_mov_b32_dpp v116, v81 row_bcast:31 row_mask:0xc bank_mask:0xf
	v_add_f32_e32 v81, v81, v116
	s_nop 0
	v_readlane_b32 s0, v81, 63
	s_nop 1
	v_fma_f32 v81, s0, v247, v237
	v_rsq_f32_e32 v116, v81
	s_nop 0
	v_pk_mul_f32 v[56:57], v[56:57], v[116:117] op_sel_hi:[1,0]
	v_pk_mul_f32 v[58:59], v[58:59], v[116:117] op_sel_hi:[1,0]
	s_waitcnt lgkmcnt(1)
	v_pk_fma_f32 v[56:57], v[68:69], v[56:57], v[72:73]
	v_pk_fma_f32 v[58:59], v[70:71], v[58:59], v[74:75]
	v_lshl_add_u64 v[68:69], s[86:87], 0, v[104:105]
	v_cvt_pk_bf16_f32 v56, v56, v57
	v_cvt_pk_bf16_f32 v57, v58, v59
	v_lshl_add_u64 v[58:59], v[68:69], 0, v[180:181]
	global_store_dwordx2 v[58:59], v[56:57], off sc1
	v_lshl_add_u32 v56, v82, 4, v124
	ds_read_b128 v[56:59], v56 offset:40960
	v_pk_mul_f32 v[70:71], v[52:53], v[116:117] op_sel_hi:[1,0]
	v_pk_mul_f32 v[72:73], v[54:55], v[116:117] op_sel_hi:[1,0]
	v_lshl_add_u32 v52, v84, 4, v124
	ds_read_b128 v[52:55], v52 offset:40960
	s_waitcnt lgkmcnt(1)
	v_pk_fma_f32 v[58:59], v[58:59], v[72:73], v[78:79]
	v_pk_fma_f32 v[56:57], v[56:57], v[70:71], v[76:77]
	v_pk_mul_f32 v[70:71], v[60:61], v[116:117] op_sel_hi:[1,0]
	v_cvt_pk_bf16_f32 v56, v56, v57
	v_cvt_pk_bf16_f32 v57, v58, v59
	v_lshl_add_u64 v[58:59], v[82:83], 3, v[68:69]
	global_store_dwordx2 v[58:59], v[56:57], off sc1
	ds_read_b128 v[56:59], v114 offset:47104
	v_pk_mul_f32 v[72:73], v[62:63], v[116:117] op_sel_hi:[1,0]
	v_lshl_add_u32 v60, v86, 4, v124
	ds_read_b128 v[60:63], v60 offset:40960
	s_waitcnt lgkmcnt(1)
	v_pk_fma_f32 v[54:55], v[54:55], v[72:73], v[58:59]
	v_pk_fma_f32 v[52:53], v[52:53], v[70:71], v[56:57]
	v_cvt_pk_bf16_f32 v57, v54, v55
	v_cvt_pk_bf16_f32 v56, v52, v53
	ds_read_b128 v[52:55], v114 offset:48128
	v_lshl_add_u64 v[58:59], v[84:85], 3, v[68:69]
	global_store_dwordx2 v[58:59], v[56:57], off sc1
	v_pk_mul_f32 v[56:57], v[64:65], v[116:117] op_sel_hi:[1,0]
	v_pk_mul_f32 v[58:59], v[66:67], v[116:117] op_sel_hi:[1,0]
	s_waitcnt lgkmcnt(0)
	v_pk_fma_f32 v[52:53], v[56:57], v[60:61], v[52:53]
	v_pk_fma_f32 v[54:55], v[58:59], v[62:63], v[54:55]
	v_cvt_pk_bf16_f32 v52, v52, v53
	v_cvt_pk_bf16_f32 v53, v54, v55
	v_lshl_add_u64 v[54:55], v[86:87], 3, v[68:69]
	global_store_dwordx2 v[54:55], v[52:53], off sc1
	v_add_u32_e32 v52, 3, v112
	v_cmp_lt_i32_e32 vcc, v52, v89
	s_and_saveexec_b64 s[12:13], vcc
	s_cbranch_execz .LBB0_990
	v_mov_b32_e32 v4, v186
	s_movk_i32 s0, 0x7fd
	v_and_b32_e32 v8, 63, v4
	v_add_u32_e32 v6, 0xfffff803, v112
	v_lshl_add_u64 v[4:5], v[102:103], 0, s[88:89]
	v_cmp_gt_i32_e32 vcc, s0, v112
	v_mov_b32_e32 v7, s31
	v_mov_b32_e32 v9, s30
	v_cndmask_b32_e32 v4, v6, v4, vcc
	v_mov_b32_e32 v6, s37
	v_cndmask_b32_e32 v5, 0, v5, vcc
	v_cndmask_b32_e32 v7, v6, v7, vcc
	v_mov_b32_e32 v6, s36
	v_lshlrev_b64 v[4:5], 12, v[4:5]
	v_cndmask_b32_e32 v6, v6, v9, vcc
	v_lshl_add_u64 v[4:5], v[6:7], 0, v[4:5]
	v_lshlrev_b32_e32 v180, 4, v8
	v_lshl_add_u64 v[16:17], v[4:5], 0, v[180:181]
	global_load_dwordx4 v[4:7], v[16:17], off
	global_load_dwordx4 v[8:11], v[16:17], off offset:1024
	global_load_dwordx4 v[12:15], v[16:17], off offset:2048
	s_nop 0
	global_load_dwordx4 v[16:19], v[16:17], off offset:3072

.LBB0_997:
	s_or_b64 exec, exec, s[12:13]
	v_pk_mul_f32 v[76:77], v[70:71], v[70:71]
	v_pk_mul_f32 v[78:79], v[68:69], v[68:69]
	v_pk_mul_f32 v[62:63], v[62:63], v[62:63]
	v_pk_mov_b32 v[130:131], v[78:79], v[76:77] op_sel:[1,0]
	v_mov_b32_e32 v79, v77
	v_pk_mul_f32 v[60:61], v[60:61], v[60:61]
	v_pk_add_f32 v[76:77], v[130:131], v[78:79]
	v_pk_mov_b32 v[78:79], v[60:61], v[62:63] op_sel:[1,0]
	v_mov_b32_e32 v61, v63
	v_pk_add_f32 v[60:61], v[78:79], v[60:61]
	v_pk_add_f32 v[76:77], v[76:77], v[76:77] op_sel_hi:[0,1]
	v_pk_add_f32 v[60:61], v[60:61], v[60:61] op_sel_hi:[0,1]
	v_mul_f32_e32 v60, v84, v84
	v_pk_fma_f32 v[62:63], v[84:85], v[84:85], v[60:61] op_sel_hi:[1,1,0]
	v_mul_f32_e32 v60, v86, v86
	v_pk_fma_f32 v[78:79], v[86:87], v[86:87], v[60:61] op_sel_hi:[1,1,0]
	v_mul_f32_e32 v62, v52, v52
	v_mul_f32_e32 v78, v53, v53
	v_mul_f32_e32 v60, v54, v54
	v_mul_f32_e32 v76, v55, v55
	v_pk_add_f32 v[62:63], v[62:63], v[78:79]
	v_pk_add_f32 v[60:61], v[60:61], v[76:77]
	v_lshlrev_b32_e32 v180, 3, v114
	v_pk_add_f32 v[60:61], v[62:63], v[60:61]
	v_mov_b32_e32 v126, v127
	v_add_f32_e32 v60, v60, v61
	v_mov_b32_e32 v61, v181
	s_nop 0
	v_add_f32_dpp v60, v60, v60 row_shr:1 row_mask:0xf bank_mask:0xf bound_ctrl:1
	s_nop 1
	v_add_f32_dpp v60, v60, v60 row_shr:2 row_mask:0xf bank_mask:0xf bound_ctrl:1
	s_nop 1
	v_add_f32_dpp v60, v60, v60 row_shr:4 row_mask:0xf bank_mask:0xf bound_ctrl:1
	s_nop 1
	v_add_f32_dpp v60, v60, v60 row_shr:8 row_mask:0xf bank_mask:0xf bound_ctrl:1
	s_nop 1
	v_mov_b32_dpp v61, v60 row_bcast:15 row_mask:0xa bank_mask:0xf
	v_add_f32_e32 v60, v60, v61
	v_mov_b32_e32 v61, v181
	s_nop 1
	v_mov_b32_dpp v61, v60 row_bcast:31 row_mask:0xc bank_mask:0xf
	v_add_f32_e32 v60, v60, v61
	s_nop 0
	v_readlane_b32 s0, v60, 63
	s_nop 1
	v_fma_f32 v60, s0, v247, v237
	v_rsq_f32_e32 v76, v60
	v_lshlrev_b64 v[60:61], 11, v[116:117]
	v_lshl_add_u64 v[78:79], s[26:27], 0, v[60:61]
	v_lshl_add_u64 v[60:61], v[78:79], 0, v[180:181]
	v_pk_mul_f32 v[62:63], v[68:69], v[76:77] op_sel_hi:[1,0]
	v_pk_mul_f32 v[68:69], v[70:71], v[76:77] op_sel_hi:[1,0]
	s_waitcnt lgkmcnt(0)
	v_pk_fma_f32 v[62:63], v[72:73], v[62:63], v[80:81]
	v_pk_fma_f32 v[68:69], v[74:75], v[68:69], v[82:83]
	v_cvt_pk_bf16_f32 v62, v62, v63
	v_cvt_pk_bf16_f32 v63, v68, v69
	global_store_dwordx2 v[60:61], v[62:63], off sc1
	v_lshl_add_u32 v60, v118, 4, v124
	v_pk_mul_f32 v[80:81], v[64:65], v[76:77] op_sel_hi:[1,0]
	v_pk_mul_f32 v[82:83], v[66:67], v[76:77] op_sel_hi:[1,0]
	ds_read_b128 v[60:63], v60 offset:40960
	ds_read_b128 v[64:67], v128 offset:46080
	v_lshl_add_u32 v68, v120, 4, v124
	v_lshl_add_u32 v72, v122, 4, v124
	ds_read_b128 v[68:71], v68 offset:40960
	ds_read_b128 v[72:75], v72 offset:40960
	s_waitcnt lgkmcnt(2)
	v_pk_fma_f32 v[62:63], v[62:63], v[82:83], v[66:67]
	v_pk_fma_f32 v[60:61], v[60:61], v[80:81], v[64:65]
	v_cvt_pk_bf16_f32 v65, v62, v63
	v_cvt_pk_bf16_f32 v64, v60, v61
	v_lshl_add_u64 v[66:67], v[118:119], 3, v[78:79]
	ds_read_b128 v[60:63], v128 offset:47104
	global_store_dwordx2 v[66:67], v[64:65], off sc1
	v_pk_mul_f32 v[64:65], v[56:57], v[76:77] op_sel_hi:[1,0]
	v_pk_mul_f32 v[66:67], v[58:59], v[76:77] op_sel_hi:[1,0]
	ds_read_b128 v[56:59], v128 offset:48128
	v_pk_mul_f32 v[52:53], v[52:53], v[76:77] op_sel_hi:[1,0]
	v_pk_mul_f32 v[54:55], v[54:55], v[76:77] op_sel_hi:[1,0]
	s_waitcnt lgkmcnt(1)
	v_pk_fma_f32 v[62:63], v[70:71], v[66:67], v[62:63]
	v_pk_fma_f32 v[60:61], v[68:69], v[64:65], v[60:61]
	s_waitcnt lgkmcnt(0)
	v_pk_fma_f32 v[54:55], v[54:55], v[74:75], v[58:59]
	v_pk_fma_f32 v[52:53], v[52:53], v[72:73], v[56:57]
	v_cvt_pk_bf16_f32 v60, v60, v61
	v_cvt_pk_bf16_f32 v61, v62, v63
	v_lshl_add_u64 v[62:63], v[120:121], 3, v[78:79]
	v_cvt_pk_bf16_f32 v52, v52, v53
	v_cvt_pk_bf16_f32 v53, v54, v55
	v_lshl_add_u64 v[54:55], v[122:123], 3, v[78:79]
	global_store_dwordx2 v[62:63], v[60:61], off sc1
	global_store_dwordx2 v[54:55], v[52:53], off sc1

.LBB0_1015:
	s_or_b64 exec, exec, s[12:13]
	v_pk_mul_f32 v[62:63], v[52:53], v[52:53]
	v_pk_mul_f32 v[64:65], v[50:51], v[50:51]
	v_lshlrev_b32_e32 v180, 3, v54
	v_pk_mov_b32 v[68:69], v[64:65], v[62:63] op_sel:[1,0]
	v_mov_b32_e32 v65, v63
	v_pk_add_f32 v[62:63], v[68:69], v[64:65]
	v_pk_mul_f32 v[64:65], v[46:47], v[46:47]
	v_pk_add_f32 v[62:63], v[62:63], v[62:63] op_sel_hi:[0,1]
	v_pk_mul_f32 v[68:69], v[48:49], v[48:49]
	v_mul_f32_e32 v62, v42, v42
	v_pk_mov_b32 v[70:71], v[68:69], v[64:65] op_sel:[1,0]
	v_mov_b32_e32 v69, v65
	v_pk_add_f32 v[64:65], v[70:71], v[68:69]
	v_pk_fma_f32 v[68:69], v[42:43], v[42:43], v[62:63] op_sel_hi:[1,1,0]
	v_mul_f32_e32 v62, v44, v44
	v_pk_add_f32 v[64:65], v[64:65], v[64:65] op_sel_hi:[0,1]
	v_pk_fma_f32 v[70:71], v[44:45], v[44:45], v[62:63] op_sel_hi:[1,1,0]
	v_mul_f32_e32 v68, v38, v38
	v_mul_f32_e32 v70, v39, v39
	v_mul_f32_e32 v62, v40, v40
	v_mul_f32_e32 v64, v41, v41
	v_pk_add_f32 v[68:69], v[68:69], v[70:71]
	v_pk_add_f32 v[62:63], v[62:63], v[64:65]
	v_lshl_add_u64 v[64:65], s[40:41], 0, v[96:97]
	v_pk_add_f32 v[62:63], v[68:69], v[62:63]
	v_mov_b32_e32 v67, v55
	v_add_f32_e32 v62, v62, v63
	v_mov_b32_e32 v63, v181
	s_nop 0
	v_add_f32_dpp v62, v62, v62 row_shr:1 row_mask:0xf bank_mask:0xf bound_ctrl:1
	s_nop 1
	v_add_f32_dpp v62, v62, v62 row_shr:2 row_mask:0xf bank_mask:0xf bound_ctrl:1
	s_nop 1
	v_add_f32_dpp v62, v62, v62 row_shr:4 row_mask:0xf bank_mask:0xf bound_ctrl:1
	s_nop 1
	v_add_f32_dpp v62, v62, v62 row_shr:8 row_mask:0xf bank_mask:0xf bound_ctrl:1
	s_nop 1
	v_mov_b32_dpp v63, v62 row_bcast:15 row_mask:0xa bank_mask:0xf
	v_add_f32_e32 v62, v62, v63
	v_mov_b32_e32 v63, v181
	s_nop 1
	v_mov_b32_dpp v63, v62 row_bcast:31 row_mask:0xc bank_mask:0xf
	v_add_f32_e32 v62, v62, v63
	s_nop 0
	v_readlane_b32 s0, v62, 63
	s_nop 1
	v_fma_f32 v62, s0, v247, v237
	v_rsq_f32_e32 v62, v62
	s_nop 0
	v_pk_mul_f32 v[50:51], v[62:63], v[50:51] op_sel_hi:[0,1]
	v_pk_mul_f32 v[52:53], v[62:63], v[52:53] op_sel_hi:[0,1]
	s_waitcnt lgkmcnt(0)
	v_pk_fma_f32 v[6:7], v[6:7], v[52:53], v[10:11]
	v_pk_fma_f32 v[4:5], v[4:5], v[50:51], v[8:9]
	v_pk_mul_f32 v[68:69], v[48:49], v[62:63] op_sel_hi:[1,0]
	v_cvt_pk_bf16_f32 v4, v4, v5
	v_cvt_pk_bf16_f32 v5, v6, v7
	v_lshl_add_u64 v[6:7], v[64:65], 0, v[180:181]
	global_store_dwordx2 v[6:7], v[4:5], off sc1
	v_lshl_add_u32 v4, v56, 4, v124
	ds_read_b128 v[4:7], v4 offset:40960
	ds_read_b128 v[8:11], v57 offset:46080
	v_pk_mul_f32 v[70:71], v[46:47], v[62:63] op_sel_hi:[1,0]
	v_lshl_add_u32 v46, v36, 4, v124
	ds_read_b128 v[46:49], v46 offset:40960
	v_lshl_add_u32 v50, v58, 4, v124
	s_waitcnt lgkmcnt(1)
	v_pk_fma_f32 v[6:7], v[6:7], v[70:71], v[10:11]
	v_pk_fma_f32 v[4:5], v[4:5], v[68:69], v[8:9]
	v_cvt_pk_bf16_f32 v9, v6, v7
	v_cvt_pk_bf16_f32 v8, v4, v5
	ds_read_b128 v[4:7], v57 offset:47104
	v_lshl_add_u64 v[10:11], v[60:61], 3, v[64:65]
	ds_read_b128 v[50:53], v50 offset:40960
	global_store_dwordx2 v[10:11], v[8:9], off sc1
	ds_read_b128 v[8:11], v57 offset:48128
	v_pk_mul_f32 v[42:43], v[42:43], v[62:63] op_sel_hi:[1,0]
	v_pk_mul_f32 v[44:45], v[44:45], v[62:63] op_sel_hi:[1,0]
	s_waitcnt lgkmcnt(2)
	v_pk_fma_f32 v[4:5], v[46:47], v[42:43], v[4:5]
	v_pk_fma_f32 v[6:7], v[48:49], v[44:45], v[6:7]
	v_cvt_pk_bf16_f32 v4, v4, v5
	v_cvt_pk_bf16_f32 v5, v6, v7
	v_lshl_add_u64 v[6:7], v[36:37], 3, v[64:65]
	global_store_dwordx2 v[6:7], v[4:5], off sc1
	v_pk_mul_f32 v[4:5], v[38:39], v[62:63] op_sel_hi:[1,0]
	v_pk_mul_f32 v[6:7], v[40:41], v[62:63] op_sel_hi:[1,0]
	s_waitcnt lgkmcnt(0)
	v_pk_fma_f32 v[4:5], v[4:5], v[50:51], v[8:9]
	v_pk_fma_f32 v[6:7], v[6:7], v[52:53], v[10:11]
	v_cvt_pk_bf16_f32 v4, v4, v5
	v_cvt_pk_bf16_f32 v5, v6, v7
	v_lshl_add_u64 v[6:7], v[58:59], 3, v[64:65]
	global_store_dwordx2 v[6:7], v[4:5], off sc1

.LBB0_1023:
	s_or_b64 exec, exec, s[10:11]
	s_waitcnt vmcnt(1)
	v_and_b32_e32 v51, 0xffff0000, v13
	v_and_b32_e32 v50, 0xffff0000, v12
	v_and_b32_e32 v55, 0xffff0000, v15
	v_and_b32_e32 v54, 0xffff0000, v14
	v_lshlrev_b32_e32 v49, 16, v13
	v_lshlrev_b32_e32 v48, 16, v12
	v_lshlrev_b32_e32 v53, 16, v15
	v_lshlrev_b32_e32 v52, 16, v14
	s_waitcnt vmcnt(0)
	v_lshlrev_b32_e32 v58, 16, v16
	v_and_b32_e32 v59, 0xffff0000, v16
	v_lshlrev_b32_e32 v60, 16, v17
	v_lshlrev_b32_e32 v62, 16, v18
	v_pk_mul_f32 v[68:69], v[50:51], v[50:51]
	v_pk_mul_f32 v[70:71], v[54:55], v[54:55]
	v_and_b32_e32 v61, 0xffff0000, v17
	v_pk_fma_f32 v[68:69], v[48:49], v[48:49], v[68:69]
	v_pk_fma_f32 v[70:71], v[52:53], v[52:53], v[70:71]
	v_mul_f32_e32 v63, v58, v58
	v_mul_f32_e32 v73, v59, v59
	v_mul_f32_e32 v56, v60, v60
	v_mov_b32_e32 v72, v62
	v_and_b32_e32 v66, 0xffff0000, v18
	v_lshlrev_b32_e32 v64, 16, v19
	v_and_b32_e32 v65, 0xffff0000, v19
	v_pk_add_f32 v[68:69], v[68:69], v[68:69] op_sel_hi:[0,1]
	v_pk_add_f32 v[70:71], v[70:71], v[70:71] op_sel_hi:[0,1]
	v_pk_fma_f32 v[74:75], v[60:61], v[60:61], v[56:57] op_sel_hi:[1,1,0]
	v_pk_add_f32 v[72:73], v[62:63], v[72:73]
	v_mul_f32_e32 v74, v66, v66
	v_mul_f32_e32 v70, v64, v64
	v_mul_f32_e32 v68, v65, v65
	v_mul_f32_e32 v76, v62, v62
	v_mov_b32_e32 v77, v73
	v_pk_add_f32 v[72:73], v[76:77], v[74:75]
	v_pk_add_f32 v[68:69], v[70:71], v[68:69]
	v_mov_b32_e32 v43, 0
	v_pk_add_f32 v[68:69], v[72:73], v[68:69]
	v_lshlrev_b32_e32 v180, 3, v38
	v_add_f32_e32 v39, v68, v69
	v_mov_b32_e32 v68, v48
	v_mov_b32_e32 v69, v50
	v_add_f32_dpp v39, v39, v39 row_shr:1 row_mask:0xf bank_mask:0xf bound_ctrl:1
	v_mov_b32_e32 v50, v49
	v_mov_b32_e32 v63, v66
	v_add_f32_dpp v39, v39, v39 row_shr:2 row_mask:0xf bank_mask:0xf bound_ctrl:1
	v_add_u32_e32 v66, 3, v57
	v_cmp_lt_i32_e64 s[12:13], v66, v125
	v_add_f32_dpp v39, v39, v39 row_shr:4 row_mask:0xf bank_mask:0xf bound_ctrl:1
	v_cmp_ge_i32_e64 s[10:11], v66, v125
	s_nop 0
	v_add_f32_dpp v39, v39, v39 row_shr:8 row_mask:0xf bank_mask:0xf bound_ctrl:1
	s_nop 1
	v_mov_b32_dpp v43, v39 row_bcast:15 row_mask:0xa bank_mask:0xf
	v_add_f32_e32 v39, v39, v43
	v_mov_b32_e32 v43, 0
	s_nop 1
	v_mov_b32_dpp v43, v39 row_bcast:31 row_mask:0xc bank_mask:0xf
	v_add_f32_e32 v39, v39, v43
	s_nop 0
	v_readlane_b32 s0, v39, 63
	s_nop 1
	v_fma_f32 v39, s0, v247, v237
	v_rsq_f32_e32 v56, v39
	v_lshl_add_u64 v[38:39], s[40:41], 0, v[94:95]
	v_pk_mul_f32 v[68:69], v[56:57], v[68:69] op_sel_hi:[0,1]
	v_pk_mul_f32 v[48:49], v[56:57], v[50:51] op_sel_hi:[0,1]
	s_waitcnt lgkmcnt(0)
	v_pk_fma_f32 v[6:7], v[6:7], v[48:49], v[10:11]
	v_pk_fma_f32 v[4:5], v[4:5], v[68:69], v[8:9]
	s_nop 0
	v_cvt_pk_bf16_f32 v4, v4, v5
	v_cvt_pk_bf16_f32 v5, v6, v7
	v_lshl_add_u64 v[6:7], v[38:39], 0, v[180:181]
	global_store_dwordx2 v[6:7], v[4:5], off sc1
	v_mov_b32_e32 v4, v52
	v_mov_b32_e32 v5, v54
	v_pk_mul_f32 v[68:69], v[56:57], v[4:5] op_sel_hi:[0,1]
	v_lshl_add_u32 v4, v42, 4, v124
	ds_read_b128 v[4:7], v4 offset:40960
	ds_read_b128 v[8:11], v37 offset:46080
	v_mov_b32_e32 v54, v53
	v_pk_mul_f32 v[70:71], v[56:57], v[54:55] op_sel_hi:[0,1]
	v_lshl_add_u32 v42, v40, 4, v124
	ds_read_b128 v[48:51], v42 offset:40960
	s_waitcnt lgkmcnt(1)
	v_pk_fma_f32 v[6:7], v[6:7], v[70:71], v[10:11]
	v_pk_fma_f32 v[4:5], v[4:5], v[68:69], v[8:9]
	v_cvt_pk_bf16_f32 v9, v6, v7
	v_cvt_pk_bf16_f32 v8, v4, v5
	ds_read_b128 v[4:7], v37 offset:47104
	v_lshl_add_u32 v42, v44, 4, v124
	v_lshl_add_u64 v[10:11], v[46:47], 3, v[38:39]
	ds_read_b128 v[52:55], v42 offset:40960
	global_store_dwordx2 v[10:11], v[8:9], off sc1
	ds_read_b128 v[8:11], v37 offset:48128
	v_pk_mul_f32 v[42:43], v[56:57], v[58:59] op_sel_hi:[0,1]
	v_pk_mul_f32 v[46:47], v[56:57], v[60:61] op_sel_hi:[0,1]
	s_waitcnt lgkmcnt(2)
	v_pk_fma_f32 v[6:7], v[50:51], v[46:47], v[6:7]
	v_pk_fma_f32 v[4:5], v[48:49], v[42:43], v[4:5]
	s_nop 0
	v_cvt_pk_bf16_f32 v4, v4, v5
	v_cvt_pk_bf16_f32 v5, v6, v7
	v_lshl_add_u64 v[6:7], v[40:41], 3, v[38:39]
	global_store_dwordx2 v[6:7], v[4:5], off sc1
	v_pk_mul_f32 v[4:5], v[56:57], v[62:63] op_sel_hi:[0,1]
	v_pk_mul_f32 v[6:7], v[56:57], v[64:65] op_sel_hi:[0,1]
	s_waitcnt lgkmcnt(0)
	v_pk_fma_f32 v[6:7], v[6:7], v[54:55], v[10:11]
	v_pk_fma_f32 v[4:5], v[4:5], v[52:53], v[8:9]
	s_nop 0
	v_cvt_pk_bf16_f32 v4, v4, v5
	v_cvt_pk_bf16_f32 v5, v6, v7
	v_lshl_add_u64 v[6:7], v[44:45], 3, v[38:39]
	global_store_dwordx2 v[6:7], v[4:5], off sc1
	s_and_saveexec_b64 s[4:5], s[12:13]
	s_cbranch_execz .LBB0_1025
	v_mov_b32_e32 v4, v186
	s_nop 0
	v_and_b32_e32 v6, 63, v4
	v_add_u32_e32 v4, 0xfffff803, v57
	v_ashrrev_i32_e32 v5, 31, v4
	v_lshlrev_b64 v[4:5], 12, v[4:5]
	v_lshl_add_u64 v[4:5], s[30:31], 0, v[4:5]
	v_lshlrev_b32_e32 v180, 3, v6
	v_lshl_add_u64 v[4:5], v[4:5], 0, v[180:181]
	global_load_dwordx2 v[12:13], v[4:5], off
	global_load_dwordx2 v[14:15], v[4:5], off offset:512
	global_load_dwordx2 v[16:17], v[4:5], off offset:1024
	global_load_dwordx2 v[18:19], v[4:5], off offset:1536

.LBB0_1030:
	s_or_b64 exec, exec, s[12:13]
	v_pk_mul_f32 v[68:69], v[54:55], v[54:55]
	v_pk_mul_f32 v[70:71], v[52:53], v[52:53]
	v_mov_b32_e32 v67, v181
	v_pk_mov_b32 v[72:73], v[70:71], v[68:69] op_sel:[1,0]
	v_mov_b32_e32 v71, v69
	v_pk_add_f32 v[68:69], v[72:73], v[70:71]
	v_pk_mul_f32 v[70:71], v[46:47], v[46:47]
	v_pk_add_f32 v[68:69], v[68:69], v[68:69] op_sel_hi:[0,1]
	v_pk_mul_f32 v[72:73], v[48:49], v[48:49]
	v_mul_f32_e32 v68, v42, v42
	v_pk_mov_b32 v[74:75], v[72:73], v[70:71] op_sel:[1,0]
	v_mov_b32_e32 v73, v71
	v_pk_add_f32 v[70:71], v[74:75], v[72:73]
	v_pk_fma_f32 v[72:73], v[42:43], v[42:43], v[68:69] op_sel_hi:[1,1,0]
	v_mul_f32_e32 v68, v44, v44
	v_pk_add_f32 v[70:71], v[70:71], v[70:71] op_sel_hi:[0,1]
	v_pk_fma_f32 v[74:75], v[44:45], v[44:45], v[68:69] op_sel_hi:[1,1,0]
	v_mul_f32_e32 v72, v38, v38
	v_mul_f32_e32 v74, v39, v39
	v_mul_f32_e32 v68, v40, v40
	v_mul_f32_e32 v70, v41, v41
	v_pk_add_f32 v[72:73], v[72:73], v[74:75]
	v_pk_add_f32 v[68:69], v[68:69], v[70:71]
	v_lshlrev_b32_e32 v180, 3, v56
	v_pk_add_f32 v[68:69], v[72:73], v[68:69]
	s_nop 0
	v_add_f32_e32 v51, v68, v69
	s_nop 1
	v_add_f32_dpp v51, v51, v51 row_shr:1 row_mask:0xf bank_mask:0xf bound_ctrl:1
	s_nop 1
	v_add_f32_dpp v51, v51, v51 row_shr:2 row_mask:0xf bank_mask:0xf bound_ctrl:1
	s_nop 1
	v_add_f32_dpp v51, v51, v51 row_shr:4 row_mask:0xf bank_mask:0xf bound_ctrl:1
	s_nop 1
	v_add_f32_dpp v51, v51, v51 row_shr:8 row_mask:0xf bank_mask:0xf bound_ctrl:1
	s_nop 1
	v_mov_b32_dpp v67, v51 row_bcast:15 row_mask:0xa bank_mask:0xf
	v_add_f32_e32 v51, v51, v67
	v_mov_b32_e32 v67, v181
	s_nop 1
	v_mov_b32_dpp v67, v51 row_bcast:31 row_mask:0xc bank_mask:0xf
	v_add_f32_e32 v51, v51, v67
	v_mov_b32_e32 v67, v37
	v_readlane_b32 s0, v51, 63
	s_nop 1
	v_fma_f32 v51, s0, v247, v237
	v_rsq_f32_e32 v68, v51
	v_ashrrev_i32_e32 v51, 31, v50
	v_lshlrev_b64 v[50:51], 11, v[50:51]
	v_pk_mul_f32 v[52:53], v[68:69], v[52:53] op_sel_hi:[0,1]
	v_pk_mul_f32 v[54:55], v[68:69], v[54:55] op_sel_hi:[0,1]
	s_waitcnt lgkmcnt(0)
	v_pk_fma_f32 v[6:7], v[6:7], v[54:55], v[10:11]
	v_pk_fma_f32 v[4:5], v[4:5], v[52:53], v[8:9]
	v_lshl_add_u64 v[54:55], s[26:27], 0, v[50:51]
	v_cvt_pk_bf16_f32 v4, v4, v5
	v_cvt_pk_bf16_f32 v5, v6, v7
	v_lshl_add_u64 v[6:7], v[54:55], 0, v[180:181]
	global_store_dwordx2 v[6:7], v[4:5], off sc1
	v_lshl_add_u32 v4, v60, 4, v124
	ds_read_b128 v[4:7], v4 offset:40960
	ds_read_b128 v[8:11], v61 offset:46080
	v_pk_mul_f32 v[70:71], v[48:49], v[68:69] op_sel_hi:[1,0]
	v_pk_mul_f32 v[72:73], v[46:47], v[68:69] op_sel_hi:[1,0]
	v_lshl_add_u32 v46, v58, 4, v124
	ds_read_b128 v[46:49], v46 offset:40960
	s_waitcnt lgkmcnt(1)
	v_pk_fma_f32 v[6:7], v[6:7], v[72:73], v[10:11]
	v_pk_fma_f32 v[4:5], v[4:5], v[70:71], v[8:9]
	v_cvt_pk_bf16_f32 v9, v6, v7
	v_cvt_pk_bf16_f32 v8, v4, v5
	ds_read_b128 v[4:7], v61 offset:47104
	v_lshl_add_u32 v50, v62, 4, v124
	v_lshl_add_u64 v[10:11], v[64:65], 3, v[54:55]
	ds_read_b128 v[50:53], v50 offset:40960
	global_store_dwordx2 v[10:11], v[8:9], off sc1
	ds_read_b128 v[8:11], v61 offset:48128
	v_pk_mul_f32 v[42:43], v[42:43], v[68:69] op_sel_hi:[1,0]
	v_pk_mul_f32 v[44:45], v[44:45], v[68:69] op_sel_hi:[1,0]
	s_waitcnt lgkmcnt(2)
	v_pk_fma_f32 v[4:5], v[46:47], v[42:43], v[4:5]
	v_pk_fma_f32 v[6:7], v[48:49], v[44:45], v[6:7]
	v_cvt_pk_bf16_f32 v4, v4, v5
	v_cvt_pk_bf16_f32 v5, v6, v7
	v_lshl_add_u64 v[6:7], v[58:59], 3, v[54:55]
	global_store_dwordx2 v[6:7], v[4:5], off sc1
	v_pk_mul_f32 v[4:5], v[38:39], v[68:69] op_sel_hi:[1,0]
	v_pk_mul_f32 v[6:7], v[40:41], v[68:69] op_sel_hi:[1,0]
	s_waitcnt lgkmcnt(0)
	v_pk_fma_f32 v[4:5], v[4:5], v[50:51], v[8:9]
	v_pk_fma_f32 v[6:7], v[6:7], v[52:53], v[10:11]
	v_cvt_pk_bf16_f32 v4, v4, v5
	v_cvt_pk_bf16_f32 v5, v6, v7
	v_lshl_add_u64 v[6:7], v[62:63], 3, v[54:55]
	global_store_dwordx2 v[6:7], v[4:5], off sc1
